# all flat_load/flat_store (generic-pointer ops on global memory) rewritten as global_load/global_store; on top of merge+gates epilogues
# speedup vs baseline: 1.0078x; 1.0078x over previous
; template <bool FFN_PERM = false>
; __device__ __forceinline__ void transpose_item(const float* W, int ldw, int K, bf16_t* WT, int nblk, int item, LAS float* scr, int lane) {
;     const int kb = item / nblk, nb = item % nblk, k0 = 64 * kb, n0 = 32 * nb;
;     const int d0 = FFN_PERM ? ((n0 < DFF) ? ((n0 >> 7) * 256 + (n0 & 127)) : ((((n0 - DFF) >> 7) * 256) + 128 + ((n0 - DFF) & 127))) : n0;
; #pragma unroll 8
;     for (int i = 0; i < 32; ++i) { const int kk = 2 * i + (lane >> 5); scr[kk * 33 + (lane & 31)] = W[(size_t)(k0 + kk) * ldw + n0 + (lane & 31)]; }
.LBB0_25:
	s_lshl_b32 s16, s6, 1
	s_lshl_b32 s17, s7, 1
	v_mov_b32_e32 v59, v0
	v_or_b32_e32 v58, s17, v50
	s_add_i32 s18, s16, 4
	s_add_i32 s19, s17, 4
	s_add_i32 s20, s16, 8
	s_add_i32 s21, s17, 8
	s_add_i32 s22, s16, 12
	s_add_i32 s23, s17, 12
	s_add_i32 s24, s16, 16
	s_add_i32 s25, s17, 16
	s_add_i32 s26, s16, 20
	s_add_i32 s27, s17, 20
	s_add_i32 s28, s16, 24
	s_add_i32 s29, s17, 24
	s_add_i32 s30, s16, 28
	s_add_i32 s31, s17, 28
	v_mov_b32_e32 v61, v0
	v_mov_b32_e32 v63, v0
	v_mov_b32_e32 v65, v0
	v_mov_b32_e32 v67, v0
	v_mov_b32_e32 v69, v0
	v_mov_b32_e32 v71, v0
	v_mov_b32_e32 v73, v0
	v_mov_b32_e32 v75, v0
	v_mov_b32_e32 v77, v0
	v_mov_b32_e32 v79, v0
	v_mov_b32_e32 v81, v0
	v_mov_b32_e32 v83, v0
	v_mov_b32_e32 v85, v0
	v_mov_b32_e32 v87, v0
	v_mov_b32_e32 v89, v0
	v_or_b32_e32 v60, s16, v3
	v_lshlrev_b64 v[58:59], 9, v[58:59]
	v_or_b32_e32 v64, s18, v3
	v_or_b32_e32 v62, s19, v50
	v_or_b32_e32 v68, s20, v3
	v_or_b32_e32 v66, s21, v50
	v_or_b32_e32 v72, s22, v3
	v_or_b32_e32 v70, s23, v50
	v_or_b32_e32 v76, s24, v3
	v_or_b32_e32 v74, s25, v50
	v_or_b32_e32 v80, s26, v3
	v_or_b32_e32 v78, s27, v50
	v_or_b32_e32 v84, s28, v3
	v_or_b32_e32 v82, s29, v50
	v_or_b32_e32 v88, s30, v3
	v_or_b32_e32 v86, s31, v50
	v_lshlrev_b64 v[60:61], 9, v[60:61]
	v_lshl_add_u64 v[58:59], v[52:53], 0, v[58:59]
	v_lshlrev_b64 v[64:65], 9, v[64:65]
	v_lshlrev_b64 v[62:63], 9, v[62:63]
	v_lshlrev_b64 v[68:69], 9, v[68:69]
	v_lshlrev_b64 v[66:67], 9, v[66:67]
	v_lshlrev_b64 v[72:73], 9, v[72:73]
	v_lshlrev_b64 v[70:71], 9, v[70:71]
	v_lshlrev_b64 v[76:77], 9, v[76:77]
	v_lshlrev_b64 v[74:75], 9, v[74:75]
	v_lshlrev_b64 v[80:81], 9, v[80:81]
	v_lshlrev_b64 v[78:79], 9, v[78:79]
	v_lshlrev_b64 v[84:85], 9, v[84:85]
	v_lshlrev_b64 v[82:83], 9, v[82:83]
	v_lshlrev_b64 v[88:89], 9, v[88:89]
	v_lshlrev_b64 v[86:87], 9, v[86:87]
	v_lshl_add_u64 v[60:61], v[52:53], 0, v[60:61]
	v_lshl_add_u64 v[62:63], v[52:53], 0, v[62:63]
	v_lshl_add_u64 v[64:65], v[52:53], 0, v[64:65]
	v_lshl_add_u64 v[66:67], v[52:53], 0, v[66:67]
	v_lshl_add_u64 v[68:69], v[52:53], 0, v[68:69]
	v_lshl_add_u64 v[70:71], v[52:53], 0, v[70:71]
	v_lshl_add_u64 v[72:73], v[52:53], 0, v[72:73]
	v_lshl_add_u64 v[74:75], v[52:53], 0, v[74:75]
	v_lshl_add_u64 v[76:77], v[52:53], 0, v[76:77]
	v_lshl_add_u64 v[78:79], v[52:53], 0, v[78:79]
	v_lshl_add_u64 v[80:81], v[52:53], 0, v[80:81]
	v_lshl_add_u64 v[82:83], v[52:53], 0, v[82:83]
	v_lshl_add_u64 v[84:85], v[52:53], 0, v[84:85]
	v_lshl_add_u64 v[86:87], v[52:53], 0, v[86:87]
	v_lshl_add_u64 v[88:89], v[52:53], 0, v[88:89]
	global_load_dword v51, v[58:59], off
	global_load_dword v90, v[60:61], off
	global_load_dword v91, v[62:63], off
	global_load_dword v92, v[64:65], off
	global_load_dword v93, v[66:67], off
	global_load_dword v94, v[68:69], off
	global_load_dword v95, v[70:71], off
	global_load_dword v96, v[72:73], off
	global_load_dword v97, v[74:75], off
	global_load_dword v98, v[76:77], off
	global_load_dword v99, v[78:79], off
	global_load_dword v100, v[80:81], off
	global_load_dword v101, v[82:83], off
	global_load_dword v102, v[84:85], off
	global_load_dword v103, v[86:87], off
	global_load_dword v104, v[88:89], off
	v_or_b32_e32 v60, s16, v1
	v_or_b32_e32 v58, s17, v2
	s_add_i32 s7, s7, 16
	s_add_i32 s6, s6, 16
	s_add_i32 s9, s9, -16
	v_mad_u64_u32 v[58:59], s[16:17], v58, s63, v[4:5]
	v_mad_u64_u32 v[60:61], s[16:17], v60, s63, v[4:5]
	v_or_b32_e32 v59, s18, v1
	v_or_b32_e32 v61, s19, v2
	v_or_b32_e32 v68, s20, v1
	v_or_b32_e32 v66, s21, v2
	v_or_b32_e32 v72, s22, v1
	v_or_b32_e32 v70, s23, v2
	v_or_b32_e32 v76, s24, v1
	v_or_b32_e32 v74, s25, v2
	v_or_b32_e32 v80, s26, v1
	v_or_b32_e32 v78, s27, v2
	v_or_b32_e32 v84, s28, v1
	v_or_b32_e32 v82, s29, v2
	v_or_b32_e32 v88, s30, v1
	v_or_b32_e32 v86, s31, v2
	s_cmp_lg_u32 s9, 0
	v_mad_u64_u32 v[62:63], s[16:17], v61, s63, v[4:5]
	v_mad_u64_u32 v[64:65], s[16:17], v59, s63, v[4:5]
	v_mad_u64_u32 v[66:67], s[16:17], v66, s63, v[4:5]
	v_mad_u64_u32 v[68:69], s[16:17], v68, s63, v[4:5]
	v_mad_u64_u32 v[70:71], s[16:17], v70, s63, v[4:5]
	v_mad_u64_u32 v[72:73], s[16:17], v72, s63, v[4:5]
	v_mad_u64_u32 v[74:75], s[16:17], v74, s63, v[4:5]
	v_mad_u64_u32 v[76:77], s[16:17], v76, s63, v[4:5]
	v_mad_u64_u32 v[78:79], s[16:17], v78, s63, v[4:5]
	v_mad_u64_u32 v[80:81], s[16:17], v80, s63, v[4:5]
	v_mad_u64_u32 v[82:83], s[16:17], v82, s63, v[4:5]
	v_mad_u64_u32 v[84:85], s[16:17], v84, s63, v[4:5]
	v_mad_u64_u32 v[86:87], s[16:17], v86, s63, v[4:5]
	v_mad_u64_u32 v[88:89], s[16:17], v88, s63, v[4:5]
	s_waitcnt vmcnt(0)
	ds_write_b32 v58, v51
	s_waitcnt vmcnt(14)
	ds_write_b32 v60, v90
	s_waitcnt vmcnt(13)
	ds_write_b32 v62, v91
	s_waitcnt vmcnt(12)
	ds_write_b32 v64, v92
	s_waitcnt vmcnt(11)
	ds_write_b32 v66, v93
	s_waitcnt vmcnt(10)
	ds_write_b32 v68, v94
	s_waitcnt vmcnt(9)
	ds_write_b32 v70, v95
	s_waitcnt vmcnt(8)
	ds_write_b32 v72, v96
	s_waitcnt vmcnt(7)
	ds_write_b32 v74, v97
	s_waitcnt vmcnt(6)
	ds_write_b32 v76, v98
	s_waitcnt vmcnt(5)
	ds_write_b32 v78, v99
	s_waitcnt vmcnt(4)
	ds_write_b32 v80, v100
	s_waitcnt vmcnt(3)
	ds_write_b32 v82, v101
	s_waitcnt vmcnt(2)
	ds_write_b32 v84, v102
	s_waitcnt vmcnt(1)
	ds_write_b32 v86, v103
	s_waitcnt vmcnt(0)
	ds_write_b32 v88, v104
	s_cbranch_scc1 .LBB0_25
; #define LAS __attribute__((address_space(3)))
; __device__ __forceinline__ unsigned pk2(float lo, float hi) { return f2bf(lo) | (f2bf(hi) << 16); }
; template <bool FFN_PERM = false>
; __device__ __forceinline__ void transpose_item(const float* W, int ldw, int K, bf16_t* WT, int nblk, int item, LAS float* scr, int lane) {
;     ...
;     const int c = lane & 7;
; #pragma unroll
;     for (int j = 0; j < 4; ++j) { const int n = (lane >> 3) + 8 * j; const LAS float* s = scr + (8 * c) * 33 + n;
;         u32x4 o; o.x = pk2(s[0 * 33], s[1 * 33]); o.y = pk2(s[2 * 33], s[3 * 33]); o.z = pk2(s[4 * 33], s[5 * 33]); o.w = pk2(s[6 * 33], s[7 * 33]);
;         *(u32x4*)(WT + (size_t)(d0 + n) * K + k0 + 8 * c) = o; }
;     asm volatile("s_waitcnt lgkmcnt(0)" ::: "memory");
	s_waitcnt lgkmcnt(0)
	ds_read_b32 v51, v54
	ds_read_b32 v58, v54 offset:132
	ds_read_b32 v59, v54 offset:264
	ds_read_b32 v60, v54 offset:396
	ds_read_b32 v61, v54 offset:528
	ds_read_b32 v62, v54 offset:660
	ds_read_b32 v63, v54 offset:792
	ds_read_b32 v64, v54 offset:924
	s_waitcnt lgkmcnt(7)
	v_bfe_u32 v65, v51, 16, 1
	v_add3_u32 v51, v51, v65, s60
	s_waitcnt lgkmcnt(6)
	v_bfe_u32 v65, v58, 16, 1
	v_lshrrev_b32_e32 v51, 16, v51
	v_add3_u32 v58, v58, v65, s60
	v_and_or_b32 v58, v58, s61, v51
	s_waitcnt lgkmcnt(5)
	v_bfe_u32 v51, v59, 16, 1
	v_add3_u32 v51, v59, v51, s60
	s_waitcnt lgkmcnt(4)
	v_bfe_u32 v59, v60, 16, 1
	v_lshrrev_b32_e32 v51, 16, v51
	v_add3_u32 v59, v60, v59, s60
	s_lshl_b32 s6, s96, 1
	v_and_or_b32 v59, v59, s61, v51
	s_waitcnt lgkmcnt(3)
	v_bfe_u32 v51, v61, 16, 1
	s_add_u32 s6, s12, s6
	v_add3_u32 v51, v61, v51, s60
	s_waitcnt lgkmcnt(2)
	v_bfe_u32 v60, v62, 16, 1
	s_addc_u32 s7, s13, 0
	s_lshl_b32 s9, s3, 1
	v_lshrrev_b32_e32 v51, 16, v51
	v_add3_u32 v60, v62, v60, s60
	s_add_u32 s6, s6, s9
	v_and_or_b32 v60, v60, s61, v51
	s_waitcnt lgkmcnt(1)
	v_bfe_u32 v51, v63, 16, 1
	s_addc_u32 s7, s7, 0
	v_lshlrev_b32_e32 v52, 1, v6
	v_mov_b32_e32 v53, v0
	v_add3_u32 v51, v63, v51, s60
	s_waitcnt lgkmcnt(0)
	v_bfe_u32 v61, v64, 16, 1
	v_lshl_add_u64 v[52:53], s[6:7], 0, v[52:53]
	v_lshrrev_b32_e32 v51, 16, v51
	v_add3_u32 v61, v64, v61, s60
	v_and_or_b32 v61, v61, s61, v51
	v_lshl_add_u64 v[62:63], v[52:53], 0, v[38:39]
	global_store_dwordx4 v[62:63], v[58:61], off
	ds_read_b32 v51, v54 offset:32
	ds_read_b32 v58, v54 offset:164
	ds_read_b32 v59, v54 offset:296
	ds_read_b32 v60, v54 offset:428
	ds_read_b32 v61, v54 offset:560
	ds_read_b32 v62, v54 offset:692
	ds_read_b32 v63, v54 offset:824
	ds_read_b32 v64, v54 offset:956
	s_waitcnt lgkmcnt(0)
	v_bfe_u32 v65, v51, 16, 1
	v_add3_u32 v51, v51, v65, s60
	v_bfe_u32 v65, v58, 16, 1
	v_lshrrev_b32_e32 v51, 16, v51
	v_add3_u32 v58, v58, v65, s60
	v_and_or_b32 v58, v58, s61, v51
	v_bfe_u32 v51, v59, 16, 1
	v_add3_u32 v51, v59, v51, s60
	v_bfe_u32 v59, v60, 16, 1
	v_lshrrev_b32_e32 v51, 16, v51
	v_add3_u32 v59, v60, v59, s60
	v_and_or_b32 v59, v59, s61, v51
	v_bfe_u32 v51, v61, 16, 1
	v_add3_u32 v51, v61, v51, s60
	v_bfe_u32 v60, v62, 16, 1
	v_lshrrev_b32_e32 v51, 16, v51
	v_add3_u32 v60, v62, v60, s60
	v_and_or_b32 v60, v60, s61, v51
	v_bfe_u32 v51, v63, 16, 1
	v_add3_u32 v51, v63, v51, s60
	v_bfe_u32 v61, v64, 16, 1
	v_lshrrev_b32_e32 v51, 16, v51
	v_add3_u32 v61, v64, v61, s60
	v_and_or_b32 v61, v61, s61, v51
	v_lshl_add_u64 v[62:63], v[52:53], 0, v[40:41]
	global_store_dwordx4 v[62:63], v[58:61], off
	ds_read_b32 v51, v54 offset:64
	ds_read_b32 v58, v54 offset:196
	ds_read_b32 v59, v54 offset:328
	ds_read_b32 v60, v54 offset:460
	ds_read_b32 v61, v54 offset:592
	ds_read_b32 v62, v54 offset:724
	ds_read_b32 v63, v54 offset:856
	ds_read_b32 v64, v54 offset:988
	s_waitcnt lgkmcnt(0)
	v_bfe_u32 v65, v51, 16, 1
	v_add3_u32 v51, v51, v65, s60
	v_bfe_u32 v65, v58, 16, 1
	v_lshrrev_b32_e32 v51, 16, v51
	v_add3_u32 v58, v58, v65, s60
	v_and_or_b32 v58, v58, s61, v51
	v_bfe_u32 v51, v59, 16, 1
	v_add3_u32 v51, v59, v51, s60
	v_bfe_u32 v59, v60, 16, 1
	v_lshrrev_b32_e32 v51, 16, v51
	v_add3_u32 v59, v60, v59, s60
	v_and_or_b32 v59, v59, s61, v51
	v_bfe_u32 v51, v61, 16, 1
	v_add3_u32 v51, v61, v51, s60
	v_bfe_u32 v60, v62, 16, 1
	v_lshrrev_b32_e32 v51, 16, v51
	v_add3_u32 v60, v62, v60, s60
	v_and_or_b32 v60, v60, s61, v51
	v_bfe_u32 v51, v63, 16, 1
	v_add3_u32 v51, v63, v51, s60
	v_bfe_u32 v61, v64, 16, 1
	v_lshrrev_b32_e32 v51, 16, v51
	v_add3_u32 v61, v64, v61, s60
	v_and_or_b32 v61, v61, s61, v51
	v_lshl_add_u64 v[62:63], v[52:53], 0, v[42:43]
	global_store_dwordx4 v[62:63], v[58:61], off
	ds_read_b32 v51, v54 offset:96
	ds_read_b32 v58, v54 offset:228
	ds_read_b32 v59, v54 offset:360
	ds_read_b32 v60, v54 offset:492
	ds_read_b32 v61, v54 offset:624
	ds_read_b32 v62, v54 offset:756
	ds_read_b32 v63, v54 offset:888
	ds_read_b32 v64, v54 offset:1020
	s_waitcnt lgkmcnt(0)
	v_bfe_u32 v65, v51, 16, 1
	v_add3_u32 v51, v51, v65, s60
	v_bfe_u32 v65, v58, 16, 1
	v_lshrrev_b32_e32 v51, 16, v51
	v_add3_u32 v58, v58, v65, s60
	v_and_or_b32 v58, v58, s61, v51
	v_bfe_u32 v51, v59, 16, 1
	v_add3_u32 v51, v59, v51, s60
	v_bfe_u32 v59, v60, 16, 1
	v_lshrrev_b32_e32 v51, 16, v51
	v_add3_u32 v59, v60, v59, s60
	v_and_or_b32 v59, v59, s61, v51
	v_bfe_u32 v51, v61, 16, 1
	v_add3_u32 v51, v61, v51, s60
	v_bfe_u32 v60, v62, 16, 1
	v_lshrrev_b32_e32 v51, 16, v51
	v_add3_u32 v60, v62, v60, s60
	v_and_or_b32 v60, v60, s61, v51
	v_bfe_u32 v51, v63, 16, 1
	v_add3_u32 v51, v63, v51, s60
	v_bfe_u32 v61, v64, 16, 1
	v_lshrrev_b32_e32 v51, 16, v51
	v_add3_u32 v61, v64, v61, s60
	v_and_or_b32 v61, v61, s61, v51
	v_lshl_add_u64 v[52:53], v[52:53], 0, v[44:45]
	global_store_dwordx4 v[52:53], v[58:61], off
	s_waitcnt lgkmcnt(0)
	s_mov_b64 s[6:7], 0

; template <bool FFN_PERM = false>
; __device__ __forceinline__ void transpose_item(const float* W, int ldw, int K, bf16_t* WT, int nblk, int item, LAS float* scr, int lane) {
;     const int kb = item / nblk, nb = item % nblk, k0 = 64 * kb, n0 = 32 * nb;
;     const int d0 = FFN_PERM ? ((n0 < DFF) ? ((n0 >> 7) * 256 + (n0 & 127)) : ((((n0 - DFF) >> 7) * 256) + 128 + ((n0 - DFF) & 127))) : n0;
; #pragma unroll 8
;     for (int i = 0; i < 32; ++i) { const int kk = 2 * i + (lane >> 5); scr[kk * 33 + (lane & 31)] = W[(size_t)(k0 + kk) * ldw + n0 + (lane & 31)]; }
.LBB0_29:
	s_lshl_b32 s9, s6, 1
	s_lshl_b32 s16, s7, 1
	v_mov_b32_e32 v59, v0
	v_or_b32_e32 v58, s16, v50
	s_add_i32 s18, s9, 4
	s_add_i32 s19, s16, 4
	s_add_i32 s20, s9, 8
	s_add_i32 s21, s16, 8
	s_add_i32 s22, s9, 12
	s_add_i32 s23, s16, 12
	s_add_i32 s24, s9, 16
	s_add_i32 s25, s16, 16
	s_add_i32 s26, s9, 20
	s_add_i32 s27, s16, 20
	s_add_i32 s28, s9, 24
	s_add_i32 s29, s16, 24
	s_add_i32 s30, s9, 28
	s_add_i32 s31, s16, 28
	v_mov_b32_e32 v61, v0
	v_mov_b32_e32 v63, v0
	v_mov_b32_e32 v65, v0
	v_mov_b32_e32 v67, v0
	v_mov_b32_e32 v69, v0
	v_mov_b32_e32 v71, v0
	v_mov_b32_e32 v73, v0
	v_mov_b32_e32 v75, v0
	v_mov_b32_e32 v77, v0
	v_mov_b32_e32 v79, v0
	v_mov_b32_e32 v81, v0
	v_mov_b32_e32 v83, v0
	v_mov_b32_e32 v85, v0
	v_mov_b32_e32 v87, v0
	v_mov_b32_e32 v89, v0
	v_or_b32_e32 v60, s9, v3
	v_lshlrev_b64 v[58:59], 9, v[58:59]
	v_or_b32_e32 v64, s18, v3
	v_or_b32_e32 v62, s19, v50
	v_or_b32_e32 v68, s20, v3
	v_or_b32_e32 v66, s21, v50
	v_or_b32_e32 v72, s22, v3
	v_or_b32_e32 v70, s23, v50
	v_or_b32_e32 v76, s24, v3
	v_or_b32_e32 v74, s25, v50
	v_or_b32_e32 v80, s26, v3
	v_or_b32_e32 v78, s27, v50
	v_or_b32_e32 v84, s28, v3
	v_or_b32_e32 v82, s29, v50
	v_or_b32_e32 v88, s30, v3
	v_or_b32_e32 v86, s31, v50
	v_lshlrev_b64 v[60:61], 9, v[60:61]
	v_lshl_add_u64 v[58:59], v[52:53], 0, v[58:59]
	v_lshlrev_b64 v[64:65], 9, v[64:65]
	v_lshlrev_b64 v[62:63], 9, v[62:63]
	v_lshlrev_b64 v[68:69], 9, v[68:69]
	v_lshlrev_b64 v[66:67], 9, v[66:67]
	v_lshlrev_b64 v[72:73], 9, v[72:73]
	v_lshlrev_b64 v[70:71], 9, v[70:71]
	v_lshlrev_b64 v[76:77], 9, v[76:77]
	v_lshlrev_b64 v[74:75], 9, v[74:75]
	v_lshlrev_b64 v[80:81], 9, v[80:81]
	v_lshlrev_b64 v[78:79], 9, v[78:79]
	v_lshlrev_b64 v[84:85], 9, v[84:85]
	v_lshlrev_b64 v[82:83], 9, v[82:83]
	v_lshlrev_b64 v[88:89], 9, v[88:89]
	v_lshlrev_b64 v[86:87], 9, v[86:87]
	v_lshl_add_u64 v[60:61], v[52:53], 0, v[60:61]
	v_lshl_add_u64 v[62:63], v[52:53], 0, v[62:63]
	v_lshl_add_u64 v[64:65], v[52:53], 0, v[64:65]
	v_lshl_add_u64 v[66:67], v[52:53], 0, v[66:67]
	v_lshl_add_u64 v[68:69], v[52:53], 0, v[68:69]
	v_lshl_add_u64 v[70:71], v[52:53], 0, v[70:71]
	v_lshl_add_u64 v[72:73], v[52:53], 0, v[72:73]
	v_lshl_add_u64 v[74:75], v[52:53], 0, v[74:75]
	v_lshl_add_u64 v[76:77], v[52:53], 0, v[76:77]
	v_lshl_add_u64 v[78:79], v[52:53], 0, v[78:79]
	v_lshl_add_u64 v[80:81], v[52:53], 0, v[80:81]
	v_lshl_add_u64 v[82:83], v[52:53], 0, v[82:83]
	v_lshl_add_u64 v[84:85], v[52:53], 0, v[84:85]
	v_lshl_add_u64 v[86:87], v[52:53], 0, v[86:87]
	v_lshl_add_u64 v[88:89], v[52:53], 0, v[88:89]
	global_load_dword v51, v[58:59], off
	global_load_dword v90, v[60:61], off
	global_load_dword v91, v[62:63], off
	global_load_dword v92, v[64:65], off
	global_load_dword v93, v[66:67], off
	global_load_dword v94, v[68:69], off
	global_load_dword v95, v[70:71], off
	global_load_dword v96, v[72:73], off
	global_load_dword v97, v[74:75], off
	global_load_dword v98, v[76:77], off
	global_load_dword v99, v[78:79], off
	global_load_dword v100, v[80:81], off
	global_load_dword v101, v[82:83], off
	global_load_dword v102, v[84:85], off
	global_load_dword v103, v[86:87], off
	global_load_dword v104, v[88:89], off
	v_or_b32_e32 v60, s9, v1
	v_or_b32_e32 v58, s16, v2
	s_add_i32 s7, s7, 16
	s_add_i32 s6, s6, 16
	s_add_i32 s8, s8, -16
	v_mad_u64_u32 v[58:59], s[16:17], v58, s63, v[4:5]
	v_mad_u64_u32 v[60:61], s[16:17], v60, s63, v[4:5]
	v_or_b32_e32 v59, s18, v1
	v_or_b32_e32 v61, s19, v2
	v_or_b32_e32 v68, s20, v1
	v_or_b32_e32 v66, s21, v2
	v_or_b32_e32 v72, s22, v1
	v_or_b32_e32 v70, s23, v2
	v_or_b32_e32 v76, s24, v1
	v_or_b32_e32 v74, s25, v2
	v_or_b32_e32 v80, s26, v1
	v_or_b32_e32 v78, s27, v2
	v_or_b32_e32 v84, s28, v1
	v_or_b32_e32 v82, s29, v2
	v_or_b32_e32 v88, s30, v1
	v_or_b32_e32 v86, s31, v2
	s_cmp_lg_u32 s8, 0
	v_mad_u64_u32 v[62:63], s[16:17], v61, s63, v[4:5]
	v_mad_u64_u32 v[64:65], s[16:17], v59, s63, v[4:5]
	v_mad_u64_u32 v[66:67], s[16:17], v66, s63, v[4:5]
	v_mad_u64_u32 v[68:69], s[16:17], v68, s63, v[4:5]
	v_mad_u64_u32 v[70:71], s[16:17], v70, s63, v[4:5]
	v_mad_u64_u32 v[72:73], s[16:17], v72, s63, v[4:5]
	v_mad_u64_u32 v[74:75], s[16:17], v74, s63, v[4:5]
	v_mad_u64_u32 v[76:77], s[16:17], v76, s63, v[4:5]
	v_mad_u64_u32 v[78:79], s[16:17], v78, s63, v[4:5]
	v_mad_u64_u32 v[80:81], s[16:17], v80, s63, v[4:5]
	v_mad_u64_u32 v[82:83], s[16:17], v82, s63, v[4:5]
	v_mad_u64_u32 v[84:85], s[16:17], v84, s63, v[4:5]
	v_mad_u64_u32 v[86:87], s[16:17], v86, s63, v[4:5]
	v_mad_u64_u32 v[88:89], s[16:17], v88, s63, v[4:5]
	s_waitcnt vmcnt(0)
	ds_write_b32 v58, v51
	ds_write_b32 v60, v90
	ds_write_b32 v62, v91
	ds_write_b32 v64, v92
	ds_write_b32 v66, v93
	ds_write_b32 v68, v94
	ds_write_b32 v70, v95
	ds_write_b32 v72, v96
	ds_write_b32 v74, v97
	ds_write_b32 v76, v98
	ds_write_b32 v78, v99
	ds_write_b32 v80, v100
	ds_write_b32 v82, v101
	ds_write_b32 v84, v102
	ds_write_b32 v86, v103
	ds_write_b32 v88, v104
	s_cbranch_scc1 .LBB0_29
; #define LAS __attribute__((address_space(3)))
; __device__ __forceinline__ unsigned pk2(float lo, float hi) { return f2bf(lo) | (f2bf(hi) << 16); }
; template <bool FFN_PERM = false>
; __device__ __forceinline__ void transpose_item(const float* W, int ldw, int K, bf16_t* WT, int nblk, int item, LAS float* scr, int lane) {
;     ...
;     const int c = lane & 7;
; #pragma unroll
;     for (int j = 0; j < 4; ++j) { const int n = (lane >> 3) + 8 * j; const LAS float* s = scr + (8 * c) * 33 + n;
;         u32x4 o; o.x = pk2(s[0 * 33], s[1 * 33]); o.y = pk2(s[2 * 33], s[3 * 33]); o.z = pk2(s[4 * 33], s[5 * 33]); o.w = pk2(s[6 * 33], s[7 * 33]);
;         *(u32x4*)(WT + (size_t)(d0 + n) * K + k0 + 8 * c) = o; }
;     asm volatile("s_waitcnt lgkmcnt(0)" ::: "memory");
	s_lshl_b32 s6, s96, 1
	s_add_u32 s6, s14, s6
	s_addc_u32 s7, s15, 0
	s_lshl_b32 s3, s3, 1
	s_add_u32 s6, s6, s3
	s_waitcnt lgkmcnt(0)
	s_addc_u32 s7, s7, 0
	v_lshlrev_b32_e32 v50, 1, v6
	v_mov_b32_e32 v51, v0
	v_lshl_add_u64 v[58:59], s[6:7], 0, v[50:51]
	ds_read_b32 v3, v54
	ds_read_b32 v50, v54 offset:132
	ds_read_b32 v51, v54 offset:264
	ds_read_b32 v52, v54 offset:396
	ds_read_b32 v53, v54 offset:528
	ds_read_b32 v60, v54 offset:660
	ds_read_b32 v61, v54 offset:792
	ds_read_b32 v62, v54 offset:924
	s_waitcnt lgkmcnt(0)
	v_bfe_u32 v63, v3, 16, 1
	v_add3_u32 v3, v3, v63, s60
	v_bfe_u32 v63, v50, 16, 1
	v_lshrrev_b32_e32 v3, 16, v3
	v_add3_u32 v50, v50, v63, s60
	v_and_or_b32 v50, v50, s61, v3
	v_bfe_u32 v3, v51, 16, 1
	v_add3_u32 v3, v51, v3, s60
	v_bfe_u32 v51, v52, 16, 1
	v_lshrrev_b32_e32 v3, 16, v3
	v_add3_u32 v51, v52, v51, s60
	v_and_or_b32 v51, v51, s61, v3
	v_bfe_u32 v3, v53, 16, 1
	v_add3_u32 v3, v53, v3, s60
	v_bfe_u32 v52, v60, 16, 1
	v_lshrrev_b32_e32 v3, 16, v3
	v_add3_u32 v52, v60, v52, s60
	v_and_or_b32 v52, v52, s61, v3
	v_bfe_u32 v3, v61, 16, 1
	v_add3_u32 v3, v61, v3, s60
	v_bfe_u32 v53, v62, 16, 1
	v_lshrrev_b32_e32 v3, 16, v3
	v_add3_u32 v53, v62, v53, s60
	v_and_or_b32 v53, v53, s61, v3
	v_lshl_add_u64 v[60:61], v[58:59], 0, v[38:39]
	global_store_dwordx4 v[60:61], v[50:53], off
	ds_read_b32 v3, v54 offset:32
	ds_read_b32 v50, v54 offset:164
	ds_read_b32 v51, v54 offset:296
	ds_read_b32 v52, v54 offset:428
	ds_read_b32 v53, v54 offset:560
	ds_read_b32 v60, v54 offset:692
	ds_read_b32 v61, v54 offset:824
	ds_read_b32 v62, v54 offset:956
	s_waitcnt lgkmcnt(0)
	v_bfe_u32 v63, v3, 16, 1
	v_add3_u32 v3, v3, v63, s60
	v_bfe_u32 v63, v50, 16, 1
	v_lshrrev_b32_e32 v3, 16, v3
	v_add3_u32 v50, v50, v63, s60
	v_and_or_b32 v50, v50, s61, v3
	v_bfe_u32 v3, v51, 16, 1
	v_add3_u32 v3, v51, v3, s60
	v_bfe_u32 v51, v52, 16, 1
	v_lshrrev_b32_e32 v3, 16, v3
	v_add3_u32 v51, v52, v51, s60
	v_and_or_b32 v51, v51, s61, v3
	v_bfe_u32 v3, v53, 16, 1
	v_add3_u32 v3, v53, v3, s60
	v_bfe_u32 v52, v60, 16, 1
	v_lshrrev_b32_e32 v3, 16, v3
	v_add3_u32 v52, v60, v52, s60
	v_and_or_b32 v52, v52, s61, v3
	v_bfe_u32 v3, v61, 16, 1
	v_add3_u32 v3, v61, v3, s60
	v_bfe_u32 v53, v62, 16, 1
	v_lshrrev_b32_e32 v3, 16, v3
	v_add3_u32 v53, v62, v53, s60
	v_and_or_b32 v53, v53, s61, v3
	v_lshl_add_u64 v[60:61], v[58:59], 0, v[40:41]
	global_store_dwordx4 v[60:61], v[50:53], off
	ds_read_b32 v3, v54 offset:64
	ds_read_b32 v50, v54 offset:196
	ds_read_b32 v51, v54 offset:328
	ds_read_b32 v52, v54 offset:460
	ds_read_b32 v53, v54 offset:592
	ds_read_b32 v60, v54 offset:724
	ds_read_b32 v61, v54 offset:856
	ds_read_b32 v62, v54 offset:988
	s_waitcnt lgkmcnt(0)
	v_bfe_u32 v63, v3, 16, 1
	v_add3_u32 v3, v3, v63, s60
	v_bfe_u32 v63, v50, 16, 1
	v_lshrrev_b32_e32 v3, 16, v3
	v_add3_u32 v50, v50, v63, s60
	v_and_or_b32 v50, v50, s61, v3
	v_bfe_u32 v3, v51, 16, 1
	v_add3_u32 v3, v51, v3, s60
	v_bfe_u32 v51, v52, 16, 1
	v_lshrrev_b32_e32 v3, 16, v3
	v_add3_u32 v51, v52, v51, s60
	v_and_or_b32 v51, v51, s61, v3
	v_bfe_u32 v3, v53, 16, 1
	v_add3_u32 v3, v53, v3, s60
	v_bfe_u32 v52, v60, 16, 1
	v_lshrrev_b32_e32 v3, 16, v3
	v_add3_u32 v52, v60, v52, s60
	v_and_or_b32 v52, v52, s61, v3
	v_bfe_u32 v3, v61, 16, 1
	v_add3_u32 v3, v61, v3, s60
	v_bfe_u32 v53, v62, 16, 1
	v_lshrrev_b32_e32 v3, 16, v3
	v_add3_u32 v53, v62, v53, s60
	v_and_or_b32 v53, v53, s61, v3
	v_lshl_add_u64 v[60:61], v[58:59], 0, v[42:43]
	global_store_dwordx4 v[60:61], v[50:53], off
	ds_read_b32 v3, v54 offset:96
	ds_read_b32 v50, v54 offset:228
	ds_read_b32 v51, v54 offset:360
	ds_read_b32 v52, v54 offset:492
	ds_read_b32 v53, v54 offset:624
	ds_read_b32 v60, v54 offset:756
	ds_read_b32 v61, v54 offset:888
	ds_read_b32 v62, v54 offset:1020
	s_waitcnt lgkmcnt(0)
	v_bfe_u32 v63, v3, 16, 1
	v_add3_u32 v3, v3, v63, s60
	v_bfe_u32 v63, v50, 16, 1
	v_lshrrev_b32_e32 v3, 16, v3
	v_add3_u32 v50, v50, v63, s60
	v_and_or_b32 v50, v50, s61, v3
	v_bfe_u32 v3, v51, 16, 1
	v_add3_u32 v3, v51, v3, s60
	v_bfe_u32 v51, v52, 16, 1
	v_lshrrev_b32_e32 v3, 16, v3
	v_add3_u32 v51, v52, v51, s60
	v_and_or_b32 v51, v51, s61, v3
	v_bfe_u32 v3, v53, 16, 1
	v_add3_u32 v3, v53, v3, s60
	v_bfe_u32 v52, v60, 16, 1
	v_lshrrev_b32_e32 v3, 16, v3
	v_add3_u32 v52, v60, v52, s60
	v_and_or_b32 v52, v52, s61, v3
	v_bfe_u32 v3, v61, 16, 1
	v_add3_u32 v3, v61, v3, s60
	v_bfe_u32 v53, v62, 16, 1
	v_lshrrev_b32_e32 v3, 16, v3
	v_add3_u32 v53, v62, v53, s60
	v_and_or_b32 v53, v53, s61, v3
	v_lshl_add_u64 v[58:59], v[58:59], 0, v[44:45]
	global_store_dwordx4 v[58:59], v[50:53], off
	s_waitcnt lgkmcnt(0)

; template <bool FFN_PERM = false>
; __device__ __forceinline__ void transpose_item(const float* W, int ldw, int K, bf16_t* WT, int nblk, int item, LAS float* scr, int lane) {
;     const int kb = item / nblk, nb = item % nblk, k0 = 64 * kb, n0 = 32 * nb;
;     const int d0 = FFN_PERM ? ((n0 < DFF) ? ((n0 >> 7) * 256 + (n0 & 127)) : ((((n0 - DFF) >> 7) * 256) + 128 + ((n0 - DFF) & 127))) : n0;
; #pragma unroll 8
;     for (int i = 0; i < 32; ++i) { const int kk = 2 * i + (lane >> 5); scr[kk * 33 + (lane & 31)] = W[(size_t)(k0 + kk) * ldw + n0 + (lane & 31)]; }
.LBB0_34:
	s_lshl_b32 s16, s6, 1
	s_lshl_b32 s17, s8, 1
	v_mov_b32_e32 v59, v0
	v_or_b32_e32 v58, s17, v52
	s_add_i32 s18, s16, 4
	s_add_i32 s19, s17, 4
	s_add_i32 s20, s16, 8
	s_add_i32 s21, s17, 8
	s_add_i32 s22, s16, 12
	s_add_i32 s23, s17, 12
	s_add_i32 s24, s16, 16
	s_add_i32 s25, s17, 16
	s_add_i32 s26, s16, 20
	s_add_i32 s27, s17, 20
	s_add_i32 s28, s16, 24
	s_add_i32 s29, s17, 24
	s_add_i32 s30, s16, 28
	s_add_i32 s31, s17, 28
	v_mov_b32_e32 v61, v0
	v_mov_b32_e32 v63, v0
	v_mov_b32_e32 v65, v0
	v_mov_b32_e32 v67, v0
	v_mov_b32_e32 v69, v0
	v_mov_b32_e32 v71, v0
	v_mov_b32_e32 v73, v0
	v_mov_b32_e32 v75, v0
	v_mov_b32_e32 v77, v0
	v_mov_b32_e32 v79, v0
	v_mov_b32_e32 v81, v0
	v_mov_b32_e32 v83, v0
	v_mov_b32_e32 v85, v0
	v_mov_b32_e32 v87, v0
	v_mov_b32_e32 v89, v0
	v_or_b32_e32 v60, s16, v3
	v_lshlrev_b64 v[58:59], 12, v[58:59]
	v_or_b32_e32 v64, s18, v3
	v_or_b32_e32 v62, s19, v52
	v_or_b32_e32 v68, s20, v3
	v_or_b32_e32 v66, s21, v52
	v_or_b32_e32 v72, s22, v3
	v_or_b32_e32 v70, s23, v52
	v_or_b32_e32 v76, s24, v3
	v_or_b32_e32 v74, s25, v52
	v_or_b32_e32 v80, s26, v3
	v_or_b32_e32 v78, s27, v52
	v_or_b32_e32 v84, s28, v3
	v_or_b32_e32 v82, s29, v52
	v_or_b32_e32 v88, s30, v3
	v_or_b32_e32 v86, s31, v52
	v_lshlrev_b64 v[60:61], 12, v[60:61]
	v_lshl_add_u64 v[58:59], v[50:51], 0, v[58:59]
	v_lshlrev_b64 v[64:65], 12, v[64:65]
	v_lshlrev_b64 v[62:63], 12, v[62:63]
	v_lshlrev_b64 v[68:69], 12, v[68:69]
	v_lshlrev_b64 v[66:67], 12, v[66:67]
	v_lshlrev_b64 v[72:73], 12, v[72:73]
	v_lshlrev_b64 v[70:71], 12, v[70:71]
	v_lshlrev_b64 v[76:77], 12, v[76:77]
	v_lshlrev_b64 v[74:75], 12, v[74:75]
	v_lshlrev_b64 v[80:81], 12, v[80:81]
	v_lshlrev_b64 v[78:79], 12, v[78:79]
	v_lshlrev_b64 v[84:85], 12, v[84:85]
	v_lshlrev_b64 v[82:83], 12, v[82:83]
	v_lshlrev_b64 v[88:89], 12, v[88:89]
	v_lshlrev_b64 v[86:87], 12, v[86:87]
	v_lshl_add_u64 v[60:61], v[50:51], 0, v[60:61]
	v_lshl_add_u64 v[62:63], v[50:51], 0, v[62:63]
	v_lshl_add_u64 v[64:65], v[50:51], 0, v[64:65]
	v_lshl_add_u64 v[66:67], v[50:51], 0, v[66:67]
	v_lshl_add_u64 v[68:69], v[50:51], 0, v[68:69]
	v_lshl_add_u64 v[70:71], v[50:51], 0, v[70:71]
	v_lshl_add_u64 v[72:73], v[50:51], 0, v[72:73]
	v_lshl_add_u64 v[74:75], v[50:51], 0, v[74:75]
	v_lshl_add_u64 v[76:77], v[50:51], 0, v[76:77]
	v_lshl_add_u64 v[78:79], v[50:51], 0, v[78:79]
	v_lshl_add_u64 v[80:81], v[50:51], 0, v[80:81]
	v_lshl_add_u64 v[82:83], v[50:51], 0, v[82:83]
	v_lshl_add_u64 v[84:85], v[50:51], 0, v[84:85]
	v_lshl_add_u64 v[86:87], v[50:51], 0, v[86:87]
	v_lshl_add_u64 v[88:89], v[50:51], 0, v[88:89]
	global_load_dword v53, v[58:59], off
	global_load_dword v90, v[60:61], off
	global_load_dword v91, v[62:63], off
	global_load_dword v92, v[64:65], off
	global_load_dword v93, v[66:67], off
	global_load_dword v94, v[68:69], off
	global_load_dword v95, v[70:71], off
	global_load_dword v96, v[72:73], off
	global_load_dword v97, v[74:75], off
	global_load_dword v98, v[76:77], off
	global_load_dword v99, v[78:79], off
	global_load_dword v100, v[80:81], off
	global_load_dword v101, v[82:83], off
	global_load_dword v102, v[84:85], off
	global_load_dword v103, v[86:87], off
	global_load_dword v104, v[88:89], off
	v_or_b32_e32 v60, s16, v1
	v_or_b32_e32 v58, s17, v2
	s_add_i32 s8, s8, 16
	s_add_i32 s6, s6, 16
	s_add_i32 s9, s9, -16
	v_mad_u64_u32 v[58:59], s[16:17], v58, s63, v[4:5]
	v_mad_u64_u32 v[60:61], s[16:17], v60, s63, v[4:5]
	v_or_b32_e32 v59, s18, v1
	v_or_b32_e32 v61, s19, v2
	v_or_b32_e32 v68, s20, v1
	v_or_b32_e32 v66, s21, v2
	v_or_b32_e32 v72, s22, v1
	v_or_b32_e32 v70, s23, v2
	v_or_b32_e32 v76, s24, v1
	v_or_b32_e32 v74, s25, v2
	v_or_b32_e32 v80, s26, v1
	v_or_b32_e32 v78, s27, v2
	v_or_b32_e32 v84, s28, v1
	v_or_b32_e32 v82, s29, v2
	v_or_b32_e32 v88, s30, v1
	v_or_b32_e32 v86, s31, v2
	s_cmp_lg_u32 s9, 0
	v_mad_u64_u32 v[62:63], s[16:17], v61, s63, v[4:5]
	v_mad_u64_u32 v[64:65], s[16:17], v59, s63, v[4:5]
	v_mad_u64_u32 v[66:67], s[16:17], v66, s63, v[4:5]
	v_mad_u64_u32 v[68:69], s[16:17], v68, s63, v[4:5]
	v_mad_u64_u32 v[70:71], s[16:17], v70, s63, v[4:5]
	v_mad_u64_u32 v[72:73], s[16:17], v72, s63, v[4:5]
	v_mad_u64_u32 v[74:75], s[16:17], v74, s63, v[4:5]
	v_mad_u64_u32 v[76:77], s[16:17], v76, s63, v[4:5]
	v_mad_u64_u32 v[78:79], s[16:17], v78, s63, v[4:5]
	v_mad_u64_u32 v[80:81], s[16:17], v80, s63, v[4:5]
	v_mad_u64_u32 v[82:83], s[16:17], v82, s63, v[4:5]
	v_mad_u64_u32 v[84:85], s[16:17], v84, s63, v[4:5]
	v_mad_u64_u32 v[86:87], s[16:17], v86, s63, v[4:5]
	v_mad_u64_u32 v[88:89], s[16:17], v88, s63, v[4:5]
	s_waitcnt vmcnt(0)
	ds_write_b32 v58, v53
	ds_write_b32 v60, v90
	ds_write_b32 v62, v91
	ds_write_b32 v64, v92
	ds_write_b32 v66, v93
	ds_write_b32 v68, v94
	ds_write_b32 v70, v95
	ds_write_b32 v72, v96
	ds_write_b32 v74, v97
	ds_write_b32 v76, v98
	ds_write_b32 v78, v99
	ds_write_b32 v80, v100
	ds_write_b32 v82, v101
	ds_write_b32 v84, v102
	ds_write_b32 v86, v103
	ds_write_b32 v88, v104
	s_cbranch_scc1 .LBB0_34
; #define LAS __attribute__((address_space(3)))
; __device__ __forceinline__ unsigned pk2(float lo, float hi) { return f2bf(lo) | (f2bf(hi) << 16); }
; template <bool FFN_PERM = false>
; __device__ __forceinline__ void transpose_item(const float* W, int ldw, int K, bf16_t* WT, int nblk, int item, LAS float* scr, int lane) {
;     ...
;     const int c = lane & 7;
; #pragma unroll
;     for (int j = 0; j < 4; ++j) { const int n = (lane >> 3) + 8 * j; const LAS float* s = scr + (8 * c) * 33 + n;
;         u32x4 o; o.x = pk2(s[0 * 33], s[1 * 33]); o.y = pk2(s[2 * 33], s[3 * 33]); o.z = pk2(s[4 * 33], s[5 * 33]); o.w = pk2(s[6 * 33], s[7 * 33]);
;         *(u32x4*)(WT + (size_t)(d0 + n) * K + k0 + 8 * c) = o; }
;     asm volatile("s_waitcnt lgkmcnt(0)" ::: "memory");
	s_waitcnt lgkmcnt(0)
	ds_read_b32 v3, v54
	ds_read_b32 v50, v54 offset:132
	ds_read_b32 v51, v54 offset:264
	ds_read_b32 v52, v54 offset:396
	ds_read_b32 v53, v54 offset:528
	ds_read_b32 v60, v54 offset:660
	ds_read_b32 v61, v54 offset:792
	ds_read_b32 v62, v54 offset:924
	s_waitcnt lgkmcnt(0)
	v_bfe_u32 v63, v3, 16, 1
	v_add3_u32 v3, v3, v63, s60
	v_bfe_u32 v63, v50, 16, 1
	v_lshrrev_b32_e32 v3, 16, v3
	v_add3_u32 v50, v50, v63, s60
	v_and_or_b32 v50, v50, s61, v3
	v_bfe_u32 v3, v51, 16, 1
	v_add3_u32 v3, v51, v3, s60
	v_bfe_u32 v51, v52, 16, 1
	v_lshrrev_b32_e32 v3, 16, v3
	v_add3_u32 v51, v52, v51, s60
	v_and_or_b32 v51, v51, s61, v3
	v_bfe_u32 v3, v53, 16, 1
	v_add3_u32 v3, v53, v3, s60
	v_bfe_u32 v52, v60, 16, 1
	v_lshrrev_b32_e32 v3, 16, v3
	v_add3_u32 v52, v60, v52, s60
	v_and_or_b32 v52, v52, s61, v3
	v_bfe_u32 v3, v61, 16, 1
	v_add3_u32 v3, v61, v3, s60
	v_bfe_u32 v53, v62, 16, 1
	v_lshrrev_b32_e32 v3, 16, v3
	v_add3_u32 v53, v62, v53, s60
	v_and_or_b32 v53, v53, s61, v3
	v_or_b32_e32 v3, s3, v7
	s_lshl_b32 s96, s7, 1
	v_mul_u32_u24_e32 v3, 0xb00, v3
	v_lshl_add_u64 v[58:59], v[8:9], 0, s[96:97]
	v_lshlrev_b32_e32 v60, 1, v3
	v_mov_b32_e32 v61, v0
	v_lshl_add_u64 v[60:61], v[58:59], 0, v[60:61]
	global_store_dwordx4 v[60:61], v[50:53], off
	ds_read_b32 v3, v54 offset:32
	ds_read_b32 v50, v54 offset:164
	ds_read_b32 v51, v54 offset:296
	ds_read_b32 v52, v54 offset:428
	ds_read_b32 v53, v54 offset:560
	ds_read_b32 v60, v54 offset:692
	ds_read_b32 v61, v54 offset:824
	ds_read_b32 v62, v54 offset:956
	s_waitcnt lgkmcnt(0)
	v_bfe_u32 v63, v3, 16, 1
	v_add3_u32 v3, v3, v63, s60
	v_bfe_u32 v63, v50, 16, 1
	v_lshrrev_b32_e32 v3, 16, v3
	v_add3_u32 v50, v50, v63, s60
	v_and_or_b32 v50, v50, s61, v3
	v_bfe_u32 v3, v51, 16, 1
	v_add3_u32 v3, v51, v3, s60
	v_bfe_u32 v51, v52, 16, 1
	v_lshrrev_b32_e32 v3, 16, v3
	v_add3_u32 v51, v52, v51, s60
	v_and_or_b32 v51, v51, s61, v3
	v_bfe_u32 v3, v53, 16, 1
	v_add3_u32 v3, v53, v3, s60
	v_bfe_u32 v52, v60, 16, 1
	v_lshrrev_b32_e32 v3, 16, v3
	v_add3_u32 v52, v60, v52, s60
	v_and_or_b32 v52, v52, s61, v3
	v_bfe_u32 v3, v61, 16, 1
	v_add3_u32 v3, v61, v3, s60
	v_bfe_u32 v53, v62, 16, 1
	v_lshrrev_b32_e32 v3, 16, v3
	v_add3_u32 v53, v62, v53, s60
	v_and_or_b32 v53, v53, s61, v3
	v_or_b32_e32 v3, s3, v55
	v_mul_u32_u24_e32 v3, 0xb00, v3
	v_lshlrev_b32_e32 v60, 1, v3
	v_mov_b32_e32 v61, v0
	v_lshl_add_u64 v[60:61], v[58:59], 0, v[60:61]
	global_store_dwordx4 v[60:61], v[50:53], off
	ds_read_b32 v3, v54 offset:64
	ds_read_b32 v50, v54 offset:196
	ds_read_b32 v51, v54 offset:328
	ds_read_b32 v52, v54 offset:460
	ds_read_b32 v53, v54 offset:592
	ds_read_b32 v60, v54 offset:724
	ds_read_b32 v61, v54 offset:856
	ds_read_b32 v62, v54 offset:988
	s_waitcnt lgkmcnt(0)
	v_bfe_u32 v63, v3, 16, 1
	v_add3_u32 v3, v3, v63, s60
	v_bfe_u32 v63, v50, 16, 1
	v_lshrrev_b32_e32 v3, 16, v3
	v_add3_u32 v50, v50, v63, s60
	v_and_or_b32 v50, v50, s61, v3
	v_bfe_u32 v3, v51, 16, 1
	v_add3_u32 v3, v51, v3, s60
	v_bfe_u32 v51, v52, 16, 1
	v_lshrrev_b32_e32 v3, 16, v3
	v_add3_u32 v51, v52, v51, s60
	v_and_or_b32 v51, v51, s61, v3
	v_bfe_u32 v3, v53, 16, 1
	v_add3_u32 v3, v53, v3, s60
	v_bfe_u32 v52, v60, 16, 1
	v_lshrrev_b32_e32 v3, 16, v3
	v_add3_u32 v52, v60, v52, s60
	v_and_or_b32 v52, v52, s61, v3
	v_bfe_u32 v3, v61, 16, 1
	v_add3_u32 v3, v61, v3, s60
	v_bfe_u32 v53, v62, 16, 1
	v_lshrrev_b32_e32 v3, 16, v3
	v_add3_u32 v53, v62, v53, s60
	v_and_or_b32 v53, v53, s61, v3
	v_or_b32_e32 v3, s3, v56
	v_mul_u32_u24_e32 v3, 0xb00, v3
	v_lshlrev_b32_e32 v60, 1, v3
	v_mov_b32_e32 v61, v0
	v_lshl_add_u64 v[60:61], v[58:59], 0, v[60:61]
	global_store_dwordx4 v[60:61], v[50:53], off
	ds_read_b32 v3, v54 offset:96
	ds_read_b32 v50, v54 offset:228
	ds_read_b32 v51, v54 offset:360
	ds_read_b32 v52, v54 offset:492
	ds_read_b32 v53, v54 offset:624
	ds_read_b32 v60, v54 offset:756
	ds_read_b32 v61, v54 offset:888
	ds_read_b32 v62, v54 offset:1020
	s_waitcnt lgkmcnt(0)
	v_bfe_u32 v63, v3, 16, 1
	v_add3_u32 v3, v3, v63, s60
	v_bfe_u32 v63, v50, 16, 1
	v_lshrrev_b32_e32 v3, 16, v3
	v_add3_u32 v50, v50, v63, s60
	v_and_or_b32 v50, v50, s61, v3
	v_bfe_u32 v3, v51, 16, 1
	v_add3_u32 v3, v51, v3, s60
	v_bfe_u32 v51, v52, 16, 1
	v_lshrrev_b32_e32 v3, 16, v3
	v_add3_u32 v51, v52, v51, s60
	v_and_or_b32 v51, v51, s61, v3
	v_bfe_u32 v3, v53, 16, 1
	v_add3_u32 v3, v53, v3, s60
	v_bfe_u32 v52, v60, 16, 1
	v_lshrrev_b32_e32 v3, 16, v3
	v_add3_u32 v52, v60, v52, s60
	v_and_or_b32 v52, v52, s61, v3
	v_bfe_u32 v3, v61, 16, 1
	v_add3_u32 v3, v61, v3, s60
	v_bfe_u32 v53, v62, 16, 1
	v_lshrrev_b32_e32 v3, 16, v3
	v_add3_u32 v53, v62, v53, s60
	v_and_or_b32 v53, v53, s61, v3
	v_or_b32_e32 v3, s3, v57
	v_mul_u32_u24_e32 v3, 0xb00, v3
	v_lshlrev_b32_e32 v60, 1, v3
	v_mov_b32_e32 v61, v0
	v_lshl_add_u64 v[58:59], v[58:59], 0, v[60:61]
	global_store_dwordx4 v[58:59], v[50:53], off
	s_waitcnt lgkmcnt(0)

; template <bool FFN_PERM = false>
; __device__ __forceinline__ void transpose_item(const float* W, int ldw, int K, bf16_t* WT, int nblk, int item, LAS float* scr, int lane) {
;     const int kb = item / nblk, nb = item % nblk, k0 = 64 * kb, n0 = 32 * nb;
;     const int d0 = FFN_PERM ? ((n0 < DFF) ? ((n0 >> 7) * 256 + (n0 & 127)) : ((((n0 - DFF) >> 7) * 256) + 128 + ((n0 - DFF) & 127))) : n0;
; #pragma unroll 8
;     for (int i = 0; i < 32; ++i) { const int kk = 2 * i + (lane >> 5); scr[kk * 33 + (lane & 31)] = W[(size_t)(k0 + kk) * ldw + n0 + (lane & 31)]; }
.LBB0_43:
	s_lshl_b32 s18, s9, 1
	s_lshl_b32 s17, s8, 1
	v_or_b32_e32 v51, s18, v2
	v_or_b32_e32 v3, s17, v1
	v_add_u32_e32 v58, s6, v51
	v_add_u32_e32 v52, s7, v3
	v_mad_u64_u32 v[58:59], s[20:21], v58, s22, v[50:51]
	v_mad_u64_u32 v[52:53], s[20:21], v52, s22, v[50:51]
	v_mov_b32_e32 v59, v0
	v_lshl_add_u64 v[58:59], v[58:59], 2, s[4:5]
	v_mov_b32_e32 v53, v0
	v_lshl_add_u64 v[52:53], v[52:53], 2, s[4:5]
	global_load_dword v60, v[58:59], off
	global_load_dword v61, v[52:53], off
	v_mad_u64_u32 v[52:53], s[20:21], v51, s63, v[4:5]
	v_mad_u64_u32 v[58:59], s[20:21], v3, s63, v[4:5]
	s_add_i32 s20, s18, 4
	s_add_i32 s19, s17, 4
	v_or_b32_e32 v51, s20, v2
	v_or_b32_e32 v3, s19, v1
	s_add_i32 s19, s17, 8
	s_add_i32 s9, s9, 16
	s_add_i32 s8, s8, 16
	s_add_i32 s16, s16, -16
	s_waitcnt vmcnt(0)
	ds_write_b32 v52, v60
	ds_write_b32 v58, v61
	v_add_u32_e32 v58, s6, v51
	v_add_u32_e32 v52, s7, v3
	v_mad_u64_u32 v[58:59], s[20:21], v58, s22, v[50:51]
	v_mad_u64_u32 v[52:53], s[20:21], v52, s22, v[50:51]
	v_mov_b32_e32 v59, v0
	v_lshl_add_u64 v[58:59], v[58:59], 2, s[4:5]
	v_mov_b32_e32 v53, v0
	v_lshl_add_u64 v[52:53], v[52:53], 2, s[4:5]
	global_load_dword v60, v[58:59], off
	global_load_dword v61, v[52:53], off
	v_mad_u64_u32 v[52:53], s[20:21], v51, s63, v[4:5]
	v_mad_u64_u32 v[58:59], s[20:21], v3, s63, v[4:5]
	s_add_i32 s20, s18, 8
	s_nop 0
	v_or_b32_e32 v51, s20, v2
	v_or_b32_e32 v3, s19, v1
	s_add_i32 s19, s17, 12
	s_waitcnt vmcnt(0)
	ds_write_b32 v52, v60
	ds_write_b32 v58, v61
	v_add_u32_e32 v58, s6, v51
	v_add_u32_e32 v52, s7, v3
	v_mad_u64_u32 v[58:59], s[20:21], v58, s22, v[50:51]
	v_mad_u64_u32 v[52:53], s[20:21], v52, s22, v[50:51]
	v_mov_b32_e32 v59, v0
	v_lshl_add_u64 v[58:59], v[58:59], 2, s[4:5]
	v_mov_b32_e32 v53, v0
	v_lshl_add_u64 v[52:53], v[52:53], 2, s[4:5]
	global_load_dword v60, v[58:59], off
	global_load_dword v61, v[52:53], off
	v_mad_u64_u32 v[52:53], s[20:21], v51, s63, v[4:5]
	v_mad_u64_u32 v[58:59], s[20:21], v3, s63, v[4:5]
	s_add_i32 s20, s18, 12
	s_nop 0
	v_or_b32_e32 v51, s20, v2
	v_or_b32_e32 v3, s19, v1
	s_add_i32 s19, s17, 16
	s_waitcnt vmcnt(0)
	ds_write_b32 v52, v60
	ds_write_b32 v58, v61
	v_add_u32_e32 v58, s6, v51
	v_add_u32_e32 v52, s7, v3
	v_mad_u64_u32 v[58:59], s[20:21], v58, s22, v[50:51]
	v_mad_u64_u32 v[52:53], s[20:21], v52, s22, v[50:51]
	v_mov_b32_e32 v59, v0
	v_lshl_add_u64 v[58:59], v[58:59], 2, s[4:5]
	v_mov_b32_e32 v53, v0
	v_lshl_add_u64 v[52:53], v[52:53], 2, s[4:5]
	global_load_dword v60, v[58:59], off
	global_load_dword v61, v[52:53], off
	v_mad_u64_u32 v[52:53], s[20:21], v51, s63, v[4:5]
	v_mad_u64_u32 v[58:59], s[20:21], v3, s63, v[4:5]
	s_add_i32 s20, s18, 16
	s_nop 0
	v_or_b32_e32 v51, s20, v2
	v_or_b32_e32 v3, s19, v1
	s_add_i32 s19, s17, 20
	s_waitcnt vmcnt(0)
	ds_write_b32 v52, v60
	ds_write_b32 v58, v61
	v_add_u32_e32 v58, s6, v51
	v_add_u32_e32 v52, s7, v3
	v_mad_u64_u32 v[58:59], s[20:21], v58, s22, v[50:51]
	v_mad_u64_u32 v[52:53], s[20:21], v52, s22, v[50:51]
	v_mov_b32_e32 v59, v0
	v_lshl_add_u64 v[58:59], v[58:59], 2, s[4:5]
	v_mov_b32_e32 v53, v0
	v_lshl_add_u64 v[52:53], v[52:53], 2, s[4:5]
	global_load_dword v60, v[58:59], off
	global_load_dword v61, v[52:53], off
	v_mad_u64_u32 v[52:53], s[20:21], v51, s63, v[4:5]
	v_mad_u64_u32 v[58:59], s[20:21], v3, s63, v[4:5]
	s_add_i32 s20, s18, 20
	s_nop 0
	v_or_b32_e32 v51, s20, v2
	v_or_b32_e32 v3, s19, v1
	s_add_i32 s19, s17, 24
	s_add_i32 s17, s17, 28
	s_waitcnt vmcnt(0)
	ds_write_b32 v52, v60
	ds_write_b32 v58, v61
	v_add_u32_e32 v58, s6, v51
	v_add_u32_e32 v52, s7, v3
	v_mad_u64_u32 v[58:59], s[20:21], v58, s22, v[50:51]
	v_mad_u64_u32 v[52:53], s[20:21], v52, s22, v[50:51]
	v_mov_b32_e32 v59, v0
	v_lshl_add_u64 v[58:59], v[58:59], 2, s[4:5]
	v_mov_b32_e32 v53, v0
	v_lshl_add_u64 v[52:53], v[52:53], 2, s[4:5]
	global_load_dword v60, v[58:59], off
	global_load_dword v61, v[52:53], off
	v_mad_u64_u32 v[52:53], s[20:21], v51, s63, v[4:5]
	v_mad_u64_u32 v[58:59], s[20:21], v3, s63, v[4:5]
	s_add_i32 s20, s18, 24
	s_nop 0
	v_or_b32_e32 v51, s20, v2
	v_or_b32_e32 v3, s19, v1
	s_add_i32 s18, s18, 28
	s_cmp_lg_u32 s16, 0
	s_waitcnt vmcnt(0)
	ds_write_b32 v52, v60
	ds_write_b32 v58, v61
	v_add_u32_e32 v58, s6, v51
	v_add_u32_e32 v52, s7, v3
	v_mad_u64_u32 v[58:59], s[20:21], v58, s22, v[50:51]
	v_mad_u64_u32 v[52:53], s[20:21], v52, s22, v[50:51]
	v_mov_b32_e32 v59, v0
	v_lshl_add_u64 v[58:59], v[58:59], 2, s[4:5]
	v_mov_b32_e32 v53, v0
	v_lshl_add_u64 v[52:53], v[52:53], 2, s[4:5]
	global_load_dword v60, v[58:59], off
	global_load_dword v61, v[52:53], off
	v_mad_u64_u32 v[52:53], s[20:21], v51, s63, v[4:5]
	v_mad_u64_u32 v[58:59], s[20:21], v3, s63, v[4:5]
	v_or_b32_e32 v51, s18, v2
	v_or_b32_e32 v3, s17, v1
	s_waitcnt vmcnt(0)
	ds_write_b32 v52, v60
	ds_write_b32 v58, v61
	v_add_u32_e32 v58, s6, v51
	v_add_u32_e32 v52, s7, v3
	v_mad_u64_u32 v[58:59], s[18:19], v58, s22, v[50:51]
	v_mad_u64_u32 v[52:53], s[18:19], v52, s22, v[50:51]
	v_mov_b32_e32 v59, v0
	v_lshl_add_u64 v[58:59], v[58:59], 2, s[4:5]
	v_mov_b32_e32 v53, v0
	v_lshl_add_u64 v[52:53], v[52:53], 2, s[4:5]
	global_load_dword v60, v[58:59], off
	global_load_dword v61, v[52:53], off
	v_mad_u64_u32 v[52:53], s[18:19], v51, s63, v[4:5]
	v_mad_u64_u32 v[58:59], s[18:19], v3, s63, v[4:5]
	s_waitcnt vmcnt(0)
	ds_write_b32 v52, v60
	ds_write_b32 v58, v61
	s_cbranch_scc1 .LBB0_43
; #define LAS __attribute__((address_space(3)))
; __device__ __forceinline__ unsigned pk2(float lo, float hi) { return f2bf(lo) | (f2bf(hi) << 16); }
; template <bool FFN_PERM = false>
; __device__ __forceinline__ void transpose_item(const float* W, int ldw, int K, bf16_t* WT, int nblk, int item, LAS float* scr, int lane) {
;     ...
;     const int c = lane & 7;
; #pragma unroll
;     for (int j = 0; j < 4; ++j) { const int n = (lane >> 3) + 8 * j; const LAS float* s = scr + (8 * c) * 33 + n;
;         u32x4 o; o.x = pk2(s[0 * 33], s[1 * 33]); o.y = pk2(s[2 * 33], s[3 * 33]); o.z = pk2(s[4 * 33], s[5 * 33]); o.w = pk2(s[6 * 33], s[7 * 33]);
;         *(u32x4*)(WT + (size_t)(d0 + n) * K + k0 + 8 * c) = o; }
;     asm volatile("s_waitcnt lgkmcnt(0)" ::: "memory");
	s_waitcnt lgkmcnt(0)
	ds_read_b32 v3, v54
	ds_read_b32 v50, v54 offset:132
	ds_read_b32 v51, v54 offset:264
	ds_read_b32 v52, v54 offset:396
	ds_read_b32 v53, v54 offset:528
	ds_read_b32 v60, v54 offset:660
	ds_read_b32 v61, v54 offset:792
	ds_read_b32 v62, v54 offset:924
	s_waitcnt lgkmcnt(0)
	v_bfe_u32 v63, v3, 16, 1
	v_add3_u32 v3, v3, v63, s60
	v_bfe_u32 v63, v50, 16, 1
	v_lshrrev_b32_e32 v3, 16, v3
	v_add3_u32 v50, v50, v63, s60
	v_and_or_b32 v50, v50, s61, v3
	v_bfe_u32 v3, v51, 16, 1
	v_add3_u32 v3, v51, v3, s60
	v_bfe_u32 v51, v52, 16, 1
	v_lshrrev_b32_e32 v3, 16, v3
	v_add3_u32 v51, v52, v51, s60
	v_and_or_b32 v51, v51, s61, v3
	v_bfe_u32 v3, v53, 16, 1
	v_add3_u32 v3, v53, v3, s60
	v_bfe_u32 v52, v60, 16, 1
	v_lshrrev_b32_e32 v3, 16, v3
	v_add3_u32 v52, v60, v52, s60
	v_and_or_b32 v52, v52, s61, v3
	v_bfe_u32 v3, v61, 16, 1
	s_lshl_b32 s96, s6, 1
	v_add3_u32 v3, v61, v3, s60
	v_bfe_u32 v53, v62, 16, 1
	v_add_u32_e32 v60, s3, v7
	v_mov_b32_e32 v61, v0
	v_lshl_add_u64 v[58:59], v[10:11], 0, s[96:97]
	v_lshrrev_b32_e32 v3, 16, v3
	v_add3_u32 v53, v62, v53, s60
	v_lshlrev_b64 v[60:61], 11, v[60:61]
	v_and_or_b32 v53, v53, s61, v3
	v_lshl_add_u64 v[60:61], v[58:59], 0, v[60:61]
	global_store_dwordx4 v[60:61], v[50:53], off
	ds_read_b32 v3, v54 offset:32
	ds_read_b32 v50, v54 offset:164
	ds_read_b32 v51, v54 offset:296
	ds_read_b32 v52, v54 offset:428
	ds_read_b32 v53, v54 offset:560
	ds_read_b32 v60, v54 offset:692
	ds_read_b32 v61, v54 offset:824
	ds_read_b32 v62, v54 offset:956
	s_waitcnt lgkmcnt(0)
	v_bfe_u32 v63, v3, 16, 1
	v_add3_u32 v3, v3, v63, s60
	v_bfe_u32 v63, v50, 16, 1
	v_lshrrev_b32_e32 v3, 16, v3
	v_add3_u32 v50, v50, v63, s60
	v_and_or_b32 v50, v50, s61, v3
	v_bfe_u32 v3, v51, 16, 1
	v_add3_u32 v3, v51, v3, s60
	v_bfe_u32 v51, v52, 16, 1
	v_lshrrev_b32_e32 v3, 16, v3
	v_add3_u32 v51, v52, v51, s60
	v_and_or_b32 v51, v51, s61, v3
	v_bfe_u32 v3, v53, 16, 1
	v_add3_u32 v3, v53, v3, s60
	v_bfe_u32 v52, v60, 16, 1
	v_lshrrev_b32_e32 v3, 16, v3
	v_add3_u32 v52, v60, v52, s60
	v_and_or_b32 v52, v52, s61, v3
	v_bfe_u32 v3, v61, 16, 1
	v_add3_u32 v3, v61, v3, s60
	v_bfe_u32 v53, v62, 16, 1
	v_add_u32_e32 v60, s3, v55
	v_mov_b32_e32 v61, v0
	v_lshrrev_b32_e32 v3, 16, v3
	v_add3_u32 v53, v62, v53, s60
	v_lshlrev_b64 v[60:61], 11, v[60:61]
	v_and_or_b32 v53, v53, s61, v3
	v_lshl_add_u64 v[60:61], v[58:59], 0, v[60:61]
	global_store_dwordx4 v[60:61], v[50:53], off
	ds_read_b32 v3, v54 offset:64
	ds_read_b32 v50, v54 offset:196
	ds_read_b32 v51, v54 offset:328
	ds_read_b32 v52, v54 offset:460
	ds_read_b32 v53, v54 offset:592
	ds_read_b32 v60, v54 offset:724
	ds_read_b32 v61, v54 offset:856
	ds_read_b32 v62, v54 offset:988
	s_waitcnt lgkmcnt(0)
	v_bfe_u32 v63, v3, 16, 1
	v_add3_u32 v3, v3, v63, s60
	v_bfe_u32 v63, v50, 16, 1
	v_lshrrev_b32_e32 v3, 16, v3
	v_add3_u32 v50, v50, v63, s60
	v_and_or_b32 v50, v50, s61, v3
	v_bfe_u32 v3, v51, 16, 1
	v_add3_u32 v3, v51, v3, s60
	v_bfe_u32 v51, v52, 16, 1
	v_lshrrev_b32_e32 v3, 16, v3
	v_add3_u32 v51, v52, v51, s60
	v_and_or_b32 v51, v51, s61, v3
	v_bfe_u32 v3, v53, 16, 1
	v_add3_u32 v3, v53, v3, s60
	v_bfe_u32 v52, v60, 16, 1
	v_lshrrev_b32_e32 v3, 16, v3
	v_add3_u32 v52, v60, v52, s60
	v_and_or_b32 v52, v52, s61, v3
	v_bfe_u32 v3, v61, 16, 1
	v_add3_u32 v3, v61, v3, s60
	v_bfe_u32 v53, v62, 16, 1
	v_add_u32_e32 v60, s3, v56
	v_mov_b32_e32 v61, v0
	v_lshrrev_b32_e32 v3, 16, v3
	v_add3_u32 v53, v62, v53, s60
	v_lshlrev_b64 v[60:61], 11, v[60:61]
	v_and_or_b32 v53, v53, s61, v3
	v_lshl_add_u64 v[60:61], v[58:59], 0, v[60:61]
	global_store_dwordx4 v[60:61], v[50:53], off
	ds_read_b32 v3, v54 offset:96
	ds_read_b32 v50, v54 offset:228
	ds_read_b32 v51, v54 offset:360
	ds_read_b32 v52, v54 offset:492
	ds_read_b32 v53, v54 offset:624
	ds_read_b32 v60, v54 offset:756
	ds_read_b32 v61, v54 offset:888
	ds_read_b32 v62, v54 offset:1020
	s_waitcnt lgkmcnt(0)
	v_bfe_u32 v63, v3, 16, 1
	v_add3_u32 v3, v3, v63, s60
	v_bfe_u32 v63, v50, 16, 1
	v_lshrrev_b32_e32 v3, 16, v3
	v_add3_u32 v50, v50, v63, s60
	v_and_or_b32 v50, v50, s61, v3
	v_bfe_u32 v3, v51, 16, 1
	v_add3_u32 v3, v51, v3, s60
	v_bfe_u32 v51, v52, 16, 1
	v_lshrrev_b32_e32 v3, 16, v3
	v_add3_u32 v51, v52, v51, s60
	v_and_or_b32 v51, v51, s61, v3
	v_bfe_u32 v3, v53, 16, 1
	v_add3_u32 v3, v53, v3, s60
	v_bfe_u32 v52, v60, 16, 1
	v_lshrrev_b32_e32 v3, 16, v3
	v_add3_u32 v52, v60, v52, s60
	v_and_or_b32 v52, v52, s61, v3
	v_bfe_u32 v3, v61, 16, 1
	v_add3_u32 v3, v61, v3, s60
	v_bfe_u32 v53, v62, 16, 1
	v_add_u32_e32 v60, s3, v57
	v_mov_b32_e32 v61, v0
	v_lshrrev_b32_e32 v3, 16, v3
	v_add3_u32 v53, v62, v53, s60
	v_lshlrev_b64 v[60:61], 11, v[60:61]
	v_and_or_b32 v53, v53, s61, v3
	v_lshl_add_u64 v[58:59], v[58:59], 0, v[60:61]
	global_store_dwordx4 v[58:59], v[50:53], off
	s_waitcnt lgkmcnt(0)

; template <bool FFN_PERM = false>
; __device__ __forceinline__ void transpose_item(const float* W, int ldw, int K, bf16_t* WT, int nblk, int item, LAS float* scr, int lane) {
;     const int kb = item / nblk, nb = item % nblk, k0 = 64 * kb, n0 = 32 * nb;
;     const int d0 = FFN_PERM ? ((n0 < DFF) ? ((n0 >> 7) * 256 + (n0 & 127)) : ((((n0 - DFF) >> 7) * 256) + 128 + ((n0 - DFF) & 127))) : n0;
; #pragma unroll 8
;     for (int i = 0; i < 32; ++i) { const int kk = 2 * i + (lane >> 5); scr[kk * 33 + (lane & 31)] = W[(size_t)(k0 + kk) * ldw + n0 + (lane & 31)]; }
.LBB0_48:
	s_lshl_b32 s16, s6, 1
	s_lshl_b32 s17, s8, 1
	v_mov_b32_e32 v59, v0
	v_or_b32_e32 v58, s17, v52
	s_add_i32 s18, s16, 4
	s_add_i32 s19, s17, 4
	s_add_i32 s20, s16, 8
	s_add_i32 s21, s17, 8
	s_add_i32 s22, s16, 12
	s_add_i32 s23, s17, 12
	s_add_i32 s24, s16, 16
	s_add_i32 s25, s17, 16
	s_add_i32 s26, s16, 20
	s_add_i32 s27, s17, 20
	s_add_i32 s28, s16, 24
	s_add_i32 s29, s17, 24
	s_add_i32 s30, s16, 28
	s_add_i32 s31, s17, 28
	v_mov_b32_e32 v61, v0
	v_mov_b32_e32 v63, v0
	v_mov_b32_e32 v65, v0
	v_mov_b32_e32 v67, v0
	v_mov_b32_e32 v69, v0
	v_mov_b32_e32 v71, v0
	v_mov_b32_e32 v73, v0
	v_mov_b32_e32 v75, v0
	v_mov_b32_e32 v77, v0
	v_mov_b32_e32 v79, v0
	v_mov_b32_e32 v81, v0
	v_mov_b32_e32 v83, v0
	v_mov_b32_e32 v85, v0
	v_mov_b32_e32 v87, v0
	v_mov_b32_e32 v89, v0
	v_or_b32_e32 v60, s16, v3
	v_lshlrev_b64 v[58:59], 12, v[58:59]
	v_or_b32_e32 v64, s18, v3
	v_or_b32_e32 v62, s19, v52
	v_or_b32_e32 v68, s20, v3
	v_or_b32_e32 v66, s21, v52
	v_or_b32_e32 v72, s22, v3
	v_or_b32_e32 v70, s23, v52
	v_or_b32_e32 v76, s24, v3
	v_or_b32_e32 v74, s25, v52
	v_or_b32_e32 v80, s26, v3
	v_or_b32_e32 v78, s27, v52
	v_or_b32_e32 v84, s28, v3
	v_or_b32_e32 v82, s29, v52
	v_or_b32_e32 v88, s30, v3
	v_or_b32_e32 v86, s31, v52
	v_lshlrev_b64 v[60:61], 12, v[60:61]
	v_lshl_add_u64 v[58:59], v[50:51], 0, v[58:59]
	v_lshlrev_b64 v[64:65], 12, v[64:65]
	v_lshlrev_b64 v[62:63], 12, v[62:63]
	v_lshlrev_b64 v[68:69], 12, v[68:69]
	v_lshlrev_b64 v[66:67], 12, v[66:67]
	v_lshlrev_b64 v[72:73], 12, v[72:73]
	v_lshlrev_b64 v[70:71], 12, v[70:71]
	v_lshlrev_b64 v[76:77], 12, v[76:77]
	v_lshlrev_b64 v[74:75], 12, v[74:75]
	v_lshlrev_b64 v[80:81], 12, v[80:81]
	v_lshlrev_b64 v[78:79], 12, v[78:79]
	v_lshlrev_b64 v[84:85], 12, v[84:85]
	v_lshlrev_b64 v[82:83], 12, v[82:83]
	v_lshlrev_b64 v[88:89], 12, v[88:89]
	v_lshlrev_b64 v[86:87], 12, v[86:87]
	v_lshl_add_u64 v[60:61], v[50:51], 0, v[60:61]
	v_lshl_add_u64 v[62:63], v[50:51], 0, v[62:63]
	v_lshl_add_u64 v[64:65], v[50:51], 0, v[64:65]
	v_lshl_add_u64 v[66:67], v[50:51], 0, v[66:67]
	v_lshl_add_u64 v[68:69], v[50:51], 0, v[68:69]
	v_lshl_add_u64 v[70:71], v[50:51], 0, v[70:71]
	v_lshl_add_u64 v[72:73], v[50:51], 0, v[72:73]
	v_lshl_add_u64 v[74:75], v[50:51], 0, v[74:75]
	v_lshl_add_u64 v[76:77], v[50:51], 0, v[76:77]
	v_lshl_add_u64 v[78:79], v[50:51], 0, v[78:79]
	v_lshl_add_u64 v[80:81], v[50:51], 0, v[80:81]
	v_lshl_add_u64 v[82:83], v[50:51], 0, v[82:83]
	v_lshl_add_u64 v[84:85], v[50:51], 0, v[84:85]
	v_lshl_add_u64 v[86:87], v[50:51], 0, v[86:87]
	v_lshl_add_u64 v[88:89], v[50:51], 0, v[88:89]
	global_load_dword v53, v[58:59], off
	global_load_dword v90, v[60:61], off
	global_load_dword v91, v[62:63], off
	global_load_dword v92, v[64:65], off
	global_load_dword v93, v[66:67], off
	global_load_dword v94, v[68:69], off
	global_load_dword v95, v[70:71], off
	global_load_dword v96, v[72:73], off
	global_load_dword v97, v[74:75], off
	global_load_dword v98, v[76:77], off
	global_load_dword v99, v[78:79], off
	global_load_dword v100, v[80:81], off
	global_load_dword v101, v[82:83], off
	global_load_dword v102, v[84:85], off
	global_load_dword v103, v[86:87], off
	global_load_dword v104, v[88:89], off
	v_or_b32_e32 v60, s16, v1
	v_or_b32_e32 v58, s17, v2
	s_add_i32 s8, s8, 16
	s_add_i32 s6, s6, 16
	s_add_i32 s9, s9, -16
	v_mad_u64_u32 v[58:59], s[16:17], v58, s63, v[4:5]
	v_mad_u64_u32 v[60:61], s[16:17], v60, s63, v[4:5]
	v_or_b32_e32 v59, s18, v1
	v_or_b32_e32 v61, s19, v2
	v_or_b32_e32 v68, s20, v1
	v_or_b32_e32 v66, s21, v2
	v_or_b32_e32 v72, s22, v1
	v_or_b32_e32 v70, s23, v2
	v_or_b32_e32 v76, s24, v1
	v_or_b32_e32 v74, s25, v2
	v_or_b32_e32 v80, s26, v1
	v_or_b32_e32 v78, s27, v2
	v_or_b32_e32 v84, s28, v1
	v_or_b32_e32 v82, s29, v2
	v_or_b32_e32 v88, s30, v1
	v_or_b32_e32 v86, s31, v2
	s_cmp_lg_u32 s9, 0
	v_mad_u64_u32 v[62:63], s[16:17], v61, s63, v[4:5]
	v_mad_u64_u32 v[64:65], s[16:17], v59, s63, v[4:5]
	v_mad_u64_u32 v[66:67], s[16:17], v66, s63, v[4:5]
	v_mad_u64_u32 v[68:69], s[16:17], v68, s63, v[4:5]
	v_mad_u64_u32 v[70:71], s[16:17], v70, s63, v[4:5]
	v_mad_u64_u32 v[72:73], s[16:17], v72, s63, v[4:5]
	v_mad_u64_u32 v[74:75], s[16:17], v74, s63, v[4:5]
	v_mad_u64_u32 v[76:77], s[16:17], v76, s63, v[4:5]
	v_mad_u64_u32 v[78:79], s[16:17], v78, s63, v[4:5]
	v_mad_u64_u32 v[80:81], s[16:17], v80, s63, v[4:5]
	v_mad_u64_u32 v[82:83], s[16:17], v82, s63, v[4:5]
	v_mad_u64_u32 v[84:85], s[16:17], v84, s63, v[4:5]
	v_mad_u64_u32 v[86:87], s[16:17], v86, s63, v[4:5]
	v_mad_u64_u32 v[88:89], s[16:17], v88, s63, v[4:5]
	s_waitcnt vmcnt(0)
	ds_write_b32 v58, v53
	ds_write_b32 v60, v90
	ds_write_b32 v62, v91
	ds_write_b32 v64, v92
	ds_write_b32 v66, v93
	ds_write_b32 v68, v94
	ds_write_b32 v70, v95
	ds_write_b32 v72, v96
	ds_write_b32 v74, v97
	ds_write_b32 v76, v98
	ds_write_b32 v78, v99
	ds_write_b32 v80, v100
	ds_write_b32 v82, v101
	ds_write_b32 v84, v102
	ds_write_b32 v86, v103
	ds_write_b32 v88, v104
	s_cbranch_scc1 .LBB0_48
; #define LAS __attribute__((address_space(3)))
; __device__ __forceinline__ unsigned pk2(float lo, float hi) { return f2bf(lo) | (f2bf(hi) << 16); }
; template <bool FFN_PERM = false>
; __device__ __forceinline__ void transpose_item(const float* W, int ldw, int K, bf16_t* WT, int nblk, int item, LAS float* scr, int lane) {
;     ...
;     const int c = lane & 7;
; #pragma unroll
;     for (int j = 0; j < 4; ++j) { const int n = (lane >> 3) + 8 * j; const LAS float* s = scr + (8 * c) * 33 + n;
;         u32x4 o; o.x = pk2(s[0 * 33], s[1 * 33]); o.y = pk2(s[2 * 33], s[3 * 33]); o.z = pk2(s[4 * 33], s[5 * 33]); o.w = pk2(s[6 * 33], s[7 * 33]);
;         *(u32x4*)(WT + (size_t)(d0 + n) * K + k0 + 8 * c) = o; }
;     asm volatile("s_waitcnt lgkmcnt(0)" ::: "memory");
	s_waitcnt lgkmcnt(0)
	ds_read_b32 v3, v54
	ds_read_b32 v50, v54 offset:132
	ds_read_b32 v51, v54 offset:264
	ds_read_b32 v52, v54 offset:396
	ds_read_b32 v53, v54 offset:528
	ds_read_b32 v60, v54 offset:660
	ds_read_b32 v61, v54 offset:792
	ds_read_b32 v62, v54 offset:924
	s_waitcnt lgkmcnt(0)
	v_bfe_u32 v63, v3, 16, 1
	v_add3_u32 v3, v3, v63, s60
	v_bfe_u32 v63, v50, 16, 1
	v_lshrrev_b32_e32 v3, 16, v3
	v_add3_u32 v50, v50, v63, s60
	v_and_or_b32 v50, v50, s61, v3
	v_bfe_u32 v3, v51, 16, 1
	v_add3_u32 v3, v51, v3, s60
	v_bfe_u32 v51, v52, 16, 1
	v_lshrrev_b32_e32 v3, 16, v3
	v_add3_u32 v51, v52, v51, s60
	v_and_or_b32 v51, v51, s61, v3
	v_bfe_u32 v3, v53, 16, 1
	v_add3_u32 v3, v53, v3, s60
	v_bfe_u32 v52, v60, 16, 1
	v_lshrrev_b32_e32 v3, 16, v3
	v_add3_u32 v52, v60, v52, s60
	v_and_or_b32 v52, v52, s61, v3
	v_bfe_u32 v3, v61, 16, 1
	v_add3_u32 v3, v61, v3, s60
	v_bfe_u32 v53, v62, 16, 1
	v_lshrrev_b32_e32 v3, 16, v3
	v_add3_u32 v53, v62, v53, s60
	s_lshl_b32 s96, s7, 1
	v_and_or_b32 v53, v53, s61, v3
	v_or_b32_e32 v3, s3, v7
	v_lshl_add_u64 v[58:59], v[12:13], 0, s[96:97]
	v_lshlrev_b32_e32 v60, 11, v3
	v_mov_b32_e32 v61, v0
	v_lshl_add_u64 v[60:61], v[58:59], 0, v[60:61]
	global_store_dwordx4 v[60:61], v[50:53], off
	ds_read_b32 v3, v54 offset:32
	ds_read_b32 v50, v54 offset:164
	ds_read_b32 v51, v54 offset:296
	ds_read_b32 v52, v54 offset:428
	ds_read_b32 v53, v54 offset:560
	ds_read_b32 v60, v54 offset:692
	ds_read_b32 v61, v54 offset:824
	ds_read_b32 v62, v54 offset:956
	s_waitcnt lgkmcnt(0)
	v_bfe_u32 v63, v3, 16, 1
	v_add3_u32 v3, v3, v63, s60
	v_bfe_u32 v63, v50, 16, 1
	v_lshrrev_b32_e32 v3, 16, v3
	v_add3_u32 v50, v50, v63, s60
	v_and_or_b32 v50, v50, s61, v3
	v_bfe_u32 v3, v51, 16, 1
	v_add3_u32 v3, v51, v3, s60
	v_bfe_u32 v51, v52, 16, 1
	v_lshrrev_b32_e32 v3, 16, v3
	v_add3_u32 v51, v52, v51, s60
	v_and_or_b32 v51, v51, s61, v3
	v_bfe_u32 v3, v53, 16, 1
	v_add3_u32 v3, v53, v3, s60
	v_bfe_u32 v52, v60, 16, 1
	v_lshrrev_b32_e32 v3, 16, v3
	v_add3_u32 v52, v60, v52, s60
	v_and_or_b32 v52, v52, s61, v3
	v_bfe_u32 v3, v61, 16, 1
	v_add3_u32 v3, v61, v3, s60
	v_bfe_u32 v53, v62, 16, 1
	v_lshrrev_b32_e32 v3, 16, v3
	v_add3_u32 v53, v62, v53, s60
	v_and_or_b32 v53, v53, s61, v3
	v_or_b32_e32 v3, s3, v55
	v_lshlrev_b32_e32 v60, 11, v3
	v_mov_b32_e32 v61, v0
	v_lshl_add_u64 v[60:61], v[58:59], 0, v[60:61]
	global_store_dwordx4 v[60:61], v[50:53], off
	ds_read_b32 v3, v54 offset:64
	ds_read_b32 v50, v54 offset:196
	ds_read_b32 v51, v54 offset:328
	ds_read_b32 v52, v54 offset:460
	ds_read_b32 v53, v54 offset:592
	ds_read_b32 v60, v54 offset:724
	ds_read_b32 v61, v54 offset:856
	ds_read_b32 v62, v54 offset:988
	s_waitcnt lgkmcnt(0)
	v_bfe_u32 v63, v3, 16, 1
	v_add3_u32 v3, v3, v63, s60
	v_bfe_u32 v63, v50, 16, 1
	v_lshrrev_b32_e32 v3, 16, v3
	v_add3_u32 v50, v50, v63, s60
	v_and_or_b32 v50, v50, s61, v3
	v_bfe_u32 v3, v51, 16, 1
	v_add3_u32 v3, v51, v3, s60
	v_bfe_u32 v51, v52, 16, 1
	v_lshrrev_b32_e32 v3, 16, v3
	v_add3_u32 v51, v52, v51, s60
	v_and_or_b32 v51, v51, s61, v3
	v_bfe_u32 v3, v53, 16, 1
	v_add3_u32 v3, v53, v3, s60
	v_bfe_u32 v52, v60, 16, 1
	v_lshrrev_b32_e32 v3, 16, v3
	v_add3_u32 v52, v60, v52, s60
	v_and_or_b32 v52, v52, s61, v3
	v_bfe_u32 v3, v61, 16, 1
	v_add3_u32 v3, v61, v3, s60
	v_bfe_u32 v53, v62, 16, 1
	v_lshrrev_b32_e32 v3, 16, v3
	v_add3_u32 v53, v62, v53, s60
	v_and_or_b32 v53, v53, s61, v3
	v_or_b32_e32 v3, s3, v56
	v_lshlrev_b32_e32 v60, 11, v3
	v_mov_b32_e32 v61, v0
	v_lshl_add_u64 v[60:61], v[58:59], 0, v[60:61]
	global_store_dwordx4 v[60:61], v[50:53], off
	ds_read_b32 v3, v54 offset:96
	ds_read_b32 v50, v54 offset:228
	ds_read_b32 v51, v54 offset:360
	ds_read_b32 v52, v54 offset:492
	ds_read_b32 v53, v54 offset:624
	ds_read_b32 v60, v54 offset:756
	ds_read_b32 v61, v54 offset:888
	ds_read_b32 v62, v54 offset:1020
	s_waitcnt lgkmcnt(0)
	v_bfe_u32 v63, v3, 16, 1
	v_add3_u32 v3, v3, v63, s60
	v_bfe_u32 v63, v50, 16, 1
	v_lshrrev_b32_e32 v3, 16, v3
	v_add3_u32 v50, v50, v63, s60
	v_and_or_b32 v50, v50, s61, v3
	v_bfe_u32 v3, v51, 16, 1
	v_add3_u32 v3, v51, v3, s60
	v_bfe_u32 v51, v52, 16, 1
	v_lshrrev_b32_e32 v3, 16, v3
	v_add3_u32 v51, v52, v51, s60
	v_and_or_b32 v51, v51, s61, v3
	v_bfe_u32 v3, v53, 16, 1
	v_add3_u32 v3, v53, v3, s60
	v_bfe_u32 v52, v60, 16, 1
	v_lshrrev_b32_e32 v3, 16, v3
	v_add3_u32 v52, v60, v52, s60
	v_and_or_b32 v52, v52, s61, v3
	v_bfe_u32 v3, v61, 16, 1
	v_add3_u32 v3, v61, v3, s60
	v_bfe_u32 v53, v62, 16, 1
	v_lshrrev_b32_e32 v3, 16, v3
	v_add3_u32 v53, v62, v53, s60
	v_and_or_b32 v53, v53, s61, v3
	v_or_b32_e32 v3, s3, v57
	v_lshlrev_b32_e32 v60, 11, v3
	v_mov_b32_e32 v61, v0
	v_lshl_add_u64 v[58:59], v[58:59], 0, v[60:61]
	global_store_dwordx4 v[58:59], v[50:53], off
	s_waitcnt lgkmcnt(0)

; template <bool FFN_PERM = false>
; __device__ __forceinline__ void transpose_item(const float* W, int ldw, int K, bf16_t* WT, int nblk, int item, LAS float* scr, int lane) {
;     const int kb = item / nblk, nb = item % nblk, k0 = 64 * kb, n0 = 32 * nb;
;     const int d0 = FFN_PERM ? ((n0 < DFF) ? ((n0 >> 7) * 256 + (n0 & 127)) : ((((n0 - DFF) >> 7) * 256) + 128 + ((n0 - DFF) & 127))) : n0;
; #pragma unroll 8
;     for (int i = 0; i < 32; ++i) { const int kk = 2 * i + (lane >> 5); scr[kk * 33 + (lane & 31)] = W[(size_t)(k0 + kk) * ldw + n0 + (lane & 31)]; }
.LBB0_53:
	s_lshl_b32 s16, s7, 1
	s_lshl_b32 s17, s8, 1
	v_mov_b32_e32 v59, v0
	v_or_b32_e32 v58, s17, v52
	s_add_i32 s18, s16, 4
	s_add_i32 s19, s17, 4
	s_add_i32 s20, s16, 8
	s_add_i32 s21, s17, 8
	s_add_i32 s22, s16, 12
	s_add_i32 s23, s17, 12
	s_add_i32 s24, s16, 16
	s_add_i32 s25, s17, 16
	s_add_i32 s26, s16, 20
	s_add_i32 s27, s17, 20
	s_add_i32 s28, s16, 24
	s_add_i32 s29, s17, 24
	s_add_i32 s30, s16, 28
	s_add_i32 s31, s17, 28
	v_mov_b32_e32 v61, v0
	v_mov_b32_e32 v63, v0
	v_mov_b32_e32 v65, v0
	v_mov_b32_e32 v67, v0
	v_mov_b32_e32 v69, v0
	v_mov_b32_e32 v71, v0
	v_mov_b32_e32 v73, v0
	v_mov_b32_e32 v75, v0
	v_mov_b32_e32 v77, v0
	v_mov_b32_e32 v79, v0
	v_mov_b32_e32 v81, v0
	v_mov_b32_e32 v83, v0
	v_mov_b32_e32 v85, v0
	v_mov_b32_e32 v87, v0
	v_mov_b32_e32 v89, v0
	v_or_b32_e32 v60, s16, v3
	v_lshlrev_b64 v[58:59], 12, v[58:59]
	v_or_b32_e32 v64, s18, v3
	v_or_b32_e32 v62, s19, v52
	v_or_b32_e32 v68, s20, v3
	v_or_b32_e32 v66, s21, v52
	v_or_b32_e32 v72, s22, v3
	v_or_b32_e32 v70, s23, v52
	v_or_b32_e32 v76, s24, v3
	v_or_b32_e32 v74, s25, v52
	v_or_b32_e32 v80, s26, v3
	v_or_b32_e32 v78, s27, v52
	v_or_b32_e32 v84, s28, v3
	v_or_b32_e32 v82, s29, v52
	v_or_b32_e32 v88, s30, v3
	v_or_b32_e32 v86, s31, v52
	v_lshlrev_b64 v[60:61], 12, v[60:61]
	v_lshl_add_u64 v[58:59], v[50:51], 0, v[58:59]
	v_lshlrev_b64 v[64:65], 12, v[64:65]
	v_lshlrev_b64 v[62:63], 12, v[62:63]
	v_lshlrev_b64 v[68:69], 12, v[68:69]
	v_lshlrev_b64 v[66:67], 12, v[66:67]
	v_lshlrev_b64 v[72:73], 12, v[72:73]
	v_lshlrev_b64 v[70:71], 12, v[70:71]
	v_lshlrev_b64 v[76:77], 12, v[76:77]
	v_lshlrev_b64 v[74:75], 12, v[74:75]
	v_lshlrev_b64 v[80:81], 12, v[80:81]
	v_lshlrev_b64 v[78:79], 12, v[78:79]
	v_lshlrev_b64 v[84:85], 12, v[84:85]
	v_lshlrev_b64 v[82:83], 12, v[82:83]
	v_lshlrev_b64 v[88:89], 12, v[88:89]
	v_lshlrev_b64 v[86:87], 12, v[86:87]
	v_lshl_add_u64 v[60:61], v[50:51], 0, v[60:61]
	v_lshl_add_u64 v[62:63], v[50:51], 0, v[62:63]
	v_lshl_add_u64 v[64:65], v[50:51], 0, v[64:65]
	v_lshl_add_u64 v[66:67], v[50:51], 0, v[66:67]
	v_lshl_add_u64 v[68:69], v[50:51], 0, v[68:69]
	v_lshl_add_u64 v[70:71], v[50:51], 0, v[70:71]
	v_lshl_add_u64 v[72:73], v[50:51], 0, v[72:73]
	v_lshl_add_u64 v[74:75], v[50:51], 0, v[74:75]
	v_lshl_add_u64 v[76:77], v[50:51], 0, v[76:77]
	v_lshl_add_u64 v[78:79], v[50:51], 0, v[78:79]
	v_lshl_add_u64 v[80:81], v[50:51], 0, v[80:81]
	v_lshl_add_u64 v[82:83], v[50:51], 0, v[82:83]
	v_lshl_add_u64 v[84:85], v[50:51], 0, v[84:85]
	v_lshl_add_u64 v[86:87], v[50:51], 0, v[86:87]
	v_lshl_add_u64 v[88:89], v[50:51], 0, v[88:89]
	global_load_dword v53, v[58:59], off
	global_load_dword v90, v[60:61], off
	global_load_dword v91, v[62:63], off
	global_load_dword v92, v[64:65], off
	global_load_dword v93, v[66:67], off
	global_load_dword v94, v[68:69], off
	global_load_dword v95, v[70:71], off
	global_load_dword v96, v[72:73], off
	global_load_dword v97, v[74:75], off
	global_load_dword v98, v[76:77], off
	global_load_dword v99, v[78:79], off
	global_load_dword v100, v[80:81], off
	global_load_dword v101, v[82:83], off
	global_load_dword v102, v[84:85], off
	global_load_dword v103, v[86:87], off
	global_load_dword v104, v[88:89], off
	v_or_b32_e32 v60, s16, v1
	v_or_b32_e32 v58, s17, v2
	s_add_i32 s8, s8, 16
	s_add_i32 s7, s7, 16
	s_add_i32 s9, s9, -16
	v_mad_u64_u32 v[58:59], s[16:17], v58, s63, v[4:5]
	v_mad_u64_u32 v[60:61], s[16:17], v60, s63, v[4:5]
	v_or_b32_e32 v59, s18, v1
	v_or_b32_e32 v61, s19, v2
	v_or_b32_e32 v68, s20, v1
	v_or_b32_e32 v66, s21, v2
	v_or_b32_e32 v72, s22, v1
	v_or_b32_e32 v70, s23, v2
	v_or_b32_e32 v76, s24, v1
	v_or_b32_e32 v74, s25, v2
	v_or_b32_e32 v80, s26, v1
	v_or_b32_e32 v78, s27, v2
	v_or_b32_e32 v84, s28, v1
	v_or_b32_e32 v82, s29, v2
	v_or_b32_e32 v88, s30, v1
	v_or_b32_e32 v86, s31, v2
	s_cmp_lg_u32 s9, 0
	v_mad_u64_u32 v[62:63], s[16:17], v61, s63, v[4:5]
	v_mad_u64_u32 v[64:65], s[16:17], v59, s63, v[4:5]
	v_mad_u64_u32 v[66:67], s[16:17], v66, s63, v[4:5]
	v_mad_u64_u32 v[68:69], s[16:17], v68, s63, v[4:5]
	v_mad_u64_u32 v[70:71], s[16:17], v70, s63, v[4:5]
	v_mad_u64_u32 v[72:73], s[16:17], v72, s63, v[4:5]
	v_mad_u64_u32 v[74:75], s[16:17], v74, s63, v[4:5]
	v_mad_u64_u32 v[76:77], s[16:17], v76, s63, v[4:5]
	v_mad_u64_u32 v[78:79], s[16:17], v78, s63, v[4:5]
	v_mad_u64_u32 v[80:81], s[16:17], v80, s63, v[4:5]
	v_mad_u64_u32 v[82:83], s[16:17], v82, s63, v[4:5]
	v_mad_u64_u32 v[84:85], s[16:17], v84, s63, v[4:5]
	v_mad_u64_u32 v[86:87], s[16:17], v86, s63, v[4:5]
	v_mad_u64_u32 v[88:89], s[16:17], v88, s63, v[4:5]
	s_waitcnt vmcnt(0)
	ds_write_b32 v58, v53
	ds_write_b32 v60, v90
	ds_write_b32 v62, v91
	ds_write_b32 v64, v92
	ds_write_b32 v66, v93
	ds_write_b32 v68, v94
	ds_write_b32 v70, v95
	ds_write_b32 v72, v96
	ds_write_b32 v74, v97
	ds_write_b32 v76, v98
	ds_write_b32 v78, v99
	ds_write_b32 v80, v100
	ds_write_b32 v82, v101
	ds_write_b32 v84, v102
	ds_write_b32 v86, v103
	ds_write_b32 v88, v104
	s_cbranch_scc1 .LBB0_53
; #define LAS __attribute__((address_space(3)))
; __device__ __forceinline__ unsigned pk2(float lo, float hi) { return f2bf(lo) | (f2bf(hi) << 16); }
; template <bool FFN_PERM = false>
; __device__ __forceinline__ void transpose_item(const float* W, int ldw, int K, bf16_t* WT, int nblk, int item, LAS float* scr, int lane) {
;     ...
;     const int c = lane & 7;
; #pragma unroll
;     for (int j = 0; j < 4; ++j) { const int n = (lane >> 3) + 8 * j; const LAS float* s = scr + (8 * c) * 33 + n;
;         u32x4 o; o.x = pk2(s[0 * 33], s[1 * 33]); o.y = pk2(s[2 * 33], s[3 * 33]); o.z = pk2(s[4 * 33], s[5 * 33]); o.w = pk2(s[6 * 33], s[7 * 33]);
;         *(u32x4*)(WT + (size_t)(d0 + n) * K + k0 + 8 * c) = o; }
;     asm volatile("s_waitcnt lgkmcnt(0)" ::: "memory");
	s_waitcnt lgkmcnt(0)
	ds_read_b32 v3, v54
	ds_read_b32 v50, v54 offset:132
	ds_read_b32 v51, v54 offset:264
	ds_read_b32 v52, v54 offset:396
	ds_read_b32 v53, v54 offset:528
	ds_read_b32 v60, v54 offset:660
	ds_read_b32 v61, v54 offset:792
	ds_read_b32 v62, v54 offset:924
	s_waitcnt lgkmcnt(0)
	v_bfe_u32 v63, v3, 16, 1
	v_add3_u32 v3, v3, v63, s60
	v_bfe_u32 v63, v50, 16, 1
	v_lshrrev_b32_e32 v3, 16, v3
	v_add3_u32 v50, v50, v63, s60
	v_and_or_b32 v50, v50, s61, v3
	v_bfe_u32 v3, v51, 16, 1
	v_add3_u32 v3, v51, v3, s60
	v_bfe_u32 v51, v52, 16, 1
	v_lshrrev_b32_e32 v3, 16, v3
	v_add3_u32 v51, v52, v51, s60
	v_and_or_b32 v51, v51, s61, v3
	v_bfe_u32 v3, v53, 16, 1
	v_add3_u32 v3, v53, v3, s60
	v_bfe_u32 v52, v60, 16, 1
	v_lshrrev_b32_e32 v3, 16, v3
	v_add3_u32 v52, v60, v52, s60
	v_and_or_b32 v52, v52, s61, v3
	v_bfe_u32 v3, v61, 16, 1
	v_add3_u32 v3, v61, v3, s60
	v_bfe_u32 v53, v62, 16, 1
	v_lshrrev_b32_e32 v3, 16, v3
	v_add3_u32 v53, v62, v53, s60
	s_lshl_b32 s96, s6, 1
	v_and_or_b32 v53, v53, s61, v3
	v_or_b32_e32 v3, s3, v7
	v_lshl_add_u64 v[58:59], v[14:15], 0, s[96:97]
	v_lshlrev_b32_e32 v60, 11, v3
	v_mov_b32_e32 v61, v0
	v_lshl_add_u64 v[60:61], v[58:59], 0, v[60:61]
	global_store_dwordx4 v[60:61], v[50:53], off
	ds_read_b32 v3, v54 offset:32
	ds_read_b32 v50, v54 offset:164
	ds_read_b32 v51, v54 offset:296
	ds_read_b32 v52, v54 offset:428
	ds_read_b32 v53, v54 offset:560
	ds_read_b32 v60, v54 offset:692
	ds_read_b32 v61, v54 offset:824
	ds_read_b32 v62, v54 offset:956
	s_waitcnt lgkmcnt(0)
	v_bfe_u32 v63, v3, 16, 1
	v_add3_u32 v3, v3, v63, s60
	v_bfe_u32 v63, v50, 16, 1
	v_lshrrev_b32_e32 v3, 16, v3
	v_add3_u32 v50, v50, v63, s60
	v_and_or_b32 v50, v50, s61, v3
	v_bfe_u32 v3, v51, 16, 1
	v_add3_u32 v3, v51, v3, s60
	v_bfe_u32 v51, v52, 16, 1
	v_lshrrev_b32_e32 v3, 16, v3
	v_add3_u32 v51, v52, v51, s60
	v_and_or_b32 v51, v51, s61, v3
	v_bfe_u32 v3, v53, 16, 1
	v_add3_u32 v3, v53, v3, s60
	v_bfe_u32 v52, v60, 16, 1
	v_lshrrev_b32_e32 v3, 16, v3
	v_add3_u32 v52, v60, v52, s60
	v_and_or_b32 v52, v52, s61, v3
	v_bfe_u32 v3, v61, 16, 1
	v_add3_u32 v3, v61, v3, s60
	v_bfe_u32 v53, v62, 16, 1
	v_lshrrev_b32_e32 v3, 16, v3
	v_add3_u32 v53, v62, v53, s60
	v_and_or_b32 v53, v53, s61, v3
	v_or_b32_e32 v3, s3, v55
	v_lshlrev_b32_e32 v60, 11, v3
	v_mov_b32_e32 v61, v0
	v_lshl_add_u64 v[60:61], v[58:59], 0, v[60:61]
	global_store_dwordx4 v[60:61], v[50:53], off
	ds_read_b32 v3, v54 offset:64
	ds_read_b32 v50, v54 offset:196
	ds_read_b32 v51, v54 offset:328
	ds_read_b32 v52, v54 offset:460
	ds_read_b32 v53, v54 offset:592
	ds_read_b32 v60, v54 offset:724
	ds_read_b32 v61, v54 offset:856
	ds_read_b32 v62, v54 offset:988
	s_waitcnt lgkmcnt(0)
	v_bfe_u32 v63, v3, 16, 1
	v_add3_u32 v3, v3, v63, s60
	v_bfe_u32 v63, v50, 16, 1
	v_lshrrev_b32_e32 v3, 16, v3
	v_add3_u32 v50, v50, v63, s60
	v_and_or_b32 v50, v50, s61, v3
	v_bfe_u32 v3, v51, 16, 1
	v_add3_u32 v3, v51, v3, s60
	v_bfe_u32 v51, v52, 16, 1
	v_lshrrev_b32_e32 v3, 16, v3
	v_add3_u32 v51, v52, v51, s60
	v_and_or_b32 v51, v51, s61, v3
	v_bfe_u32 v3, v53, 16, 1
	v_add3_u32 v3, v53, v3, s60
	v_bfe_u32 v52, v60, 16, 1
	v_lshrrev_b32_e32 v3, 16, v3
	v_add3_u32 v52, v60, v52, s60
	v_and_or_b32 v52, v52, s61, v3
	v_bfe_u32 v3, v61, 16, 1
	v_add3_u32 v3, v61, v3, s60
	v_bfe_u32 v53, v62, 16, 1
	v_lshrrev_b32_e32 v3, 16, v3
	v_add3_u32 v53, v62, v53, s60
	v_and_or_b32 v53, v53, s61, v3
	v_or_b32_e32 v3, s3, v56
	v_lshlrev_b32_e32 v60, 11, v3
	v_mov_b32_e32 v61, v0
	v_lshl_add_u64 v[60:61], v[58:59], 0, v[60:61]
	global_store_dwordx4 v[60:61], v[50:53], off
	ds_read_b32 v3, v54 offset:96
	ds_read_b32 v50, v54 offset:228
	ds_read_b32 v51, v54 offset:360
	ds_read_b32 v52, v54 offset:492
	ds_read_b32 v53, v54 offset:624
	ds_read_b32 v60, v54 offset:756
	ds_read_b32 v61, v54 offset:888
	ds_read_b32 v62, v54 offset:1020
	s_waitcnt lgkmcnt(0)
	v_bfe_u32 v63, v3, 16, 1
	v_add3_u32 v3, v3, v63, s60
	v_bfe_u32 v63, v50, 16, 1
	v_lshrrev_b32_e32 v3, 16, v3
	v_add3_u32 v50, v50, v63, s60
	v_and_or_b32 v50, v50, s61, v3
	v_bfe_u32 v3, v51, 16, 1
	v_add3_u32 v3, v51, v3, s60
	v_bfe_u32 v51, v52, 16, 1
	v_lshrrev_b32_e32 v3, 16, v3
	v_add3_u32 v51, v52, v51, s60
	v_and_or_b32 v51, v51, s61, v3
	v_bfe_u32 v3, v53, 16, 1
	v_add3_u32 v3, v53, v3, s60
	v_bfe_u32 v52, v60, 16, 1
	v_lshrrev_b32_e32 v3, 16, v3
	v_add3_u32 v52, v60, v52, s60
	v_and_or_b32 v52, v52, s61, v3
	v_bfe_u32 v3, v61, 16, 1
	v_add3_u32 v3, v61, v3, s60
	v_bfe_u32 v53, v62, 16, 1
	v_lshrrev_b32_e32 v3, 16, v3
	v_add3_u32 v53, v62, v53, s60
	v_and_or_b32 v53, v53, s61, v3
	v_or_b32_e32 v3, s3, v57
	v_lshlrev_b32_e32 v60, 11, v3
	v_mov_b32_e32 v61, v0
	v_lshl_add_u64 v[58:59], v[58:59], 0, v[60:61]
	global_store_dwordx4 v[58:59], v[50:53], off
	s_waitcnt lgkmcnt(0)

; template <bool FFN_PERM = false>
; __device__ __forceinline__ void transpose_item(const float* W, int ldw, int K, bf16_t* WT, int nblk, int item, LAS float* scr, int lane) {
;     const int kb = item / nblk, nb = item % nblk, k0 = 64 * kb, n0 = 32 * nb;
;     const int d0 = FFN_PERM ? ((n0 < DFF) ? ((n0 >> 7) * 256 + (n0 & 127)) : ((((n0 - DFF) >> 7) * 256) + 128 + ((n0 - DFF) & 127))) : n0;
; #pragma unroll 8
;     for (int i = 0; i < 32; ++i) { const int kk = 2 * i + (lane >> 5); scr[kk * 33 + (lane & 31)] = W[(size_t)(k0 + kk) * ldw + n0 + (lane & 31)]; }
.LBB0_58:
	s_lshl_b32 s16, s7, 1
	s_lshl_b32 s17, s8, 1
	v_mov_b32_e32 v59, v0
	v_or_b32_e32 v58, s17, v52
	s_add_i32 s18, s16, 4
	s_add_i32 s19, s17, 4
	s_add_i32 s20, s16, 8
	s_add_i32 s21, s17, 8
	s_add_i32 s22, s16, 12
	s_add_i32 s23, s17, 12
	s_add_i32 s24, s16, 16
	s_add_i32 s25, s17, 16
	s_add_i32 s26, s16, 20
	s_add_i32 s27, s17, 20
	s_add_i32 s28, s16, 24
	s_add_i32 s29, s17, 24
	s_add_i32 s30, s16, 28
	s_add_i32 s31, s17, 28
	v_mov_b32_e32 v61, v0
	v_mov_b32_e32 v63, v0
	v_mov_b32_e32 v65, v0
	v_mov_b32_e32 v67, v0
	v_mov_b32_e32 v69, v0
	v_mov_b32_e32 v71, v0
	v_mov_b32_e32 v73, v0
	v_mov_b32_e32 v75, v0
	v_mov_b32_e32 v77, v0
	v_mov_b32_e32 v79, v0
	v_mov_b32_e32 v81, v0
	v_mov_b32_e32 v83, v0
	v_mov_b32_e32 v85, v0
	v_mov_b32_e32 v87, v0
	v_mov_b32_e32 v89, v0
	v_or_b32_e32 v60, s16, v3
	v_lshlrev_b64 v[58:59], 12, v[58:59]
	v_or_b32_e32 v64, s18, v3
	v_or_b32_e32 v62, s19, v52
	v_or_b32_e32 v68, s20, v3
	v_or_b32_e32 v66, s21, v52
	v_or_b32_e32 v72, s22, v3
	v_or_b32_e32 v70, s23, v52
	v_or_b32_e32 v76, s24, v3
	v_or_b32_e32 v74, s25, v52
	v_or_b32_e32 v80, s26, v3
	v_or_b32_e32 v78, s27, v52
	v_or_b32_e32 v84, s28, v3
	v_or_b32_e32 v82, s29, v52
	v_or_b32_e32 v88, s30, v3
	v_or_b32_e32 v86, s31, v52
	v_lshlrev_b64 v[60:61], 12, v[60:61]
	v_lshl_add_u64 v[58:59], v[50:51], 0, v[58:59]
	v_lshlrev_b64 v[64:65], 12, v[64:65]
	v_lshlrev_b64 v[62:63], 12, v[62:63]
	v_lshlrev_b64 v[68:69], 12, v[68:69]
	v_lshlrev_b64 v[66:67], 12, v[66:67]
	v_lshlrev_b64 v[72:73], 12, v[72:73]
	v_lshlrev_b64 v[70:71], 12, v[70:71]
	v_lshlrev_b64 v[76:77], 12, v[76:77]
	v_lshlrev_b64 v[74:75], 12, v[74:75]
	v_lshlrev_b64 v[80:81], 12, v[80:81]
	v_lshlrev_b64 v[78:79], 12, v[78:79]
	v_lshlrev_b64 v[84:85], 12, v[84:85]
	v_lshlrev_b64 v[82:83], 12, v[82:83]
	v_lshlrev_b64 v[88:89], 12, v[88:89]
	v_lshlrev_b64 v[86:87], 12, v[86:87]
	v_lshl_add_u64 v[60:61], v[50:51], 0, v[60:61]
	v_lshl_add_u64 v[62:63], v[50:51], 0, v[62:63]
	v_lshl_add_u64 v[64:65], v[50:51], 0, v[64:65]
	v_lshl_add_u64 v[66:67], v[50:51], 0, v[66:67]
	v_lshl_add_u64 v[68:69], v[50:51], 0, v[68:69]
	v_lshl_add_u64 v[70:71], v[50:51], 0, v[70:71]
	v_lshl_add_u64 v[72:73], v[50:51], 0, v[72:73]
	v_lshl_add_u64 v[74:75], v[50:51], 0, v[74:75]
	v_lshl_add_u64 v[76:77], v[50:51], 0, v[76:77]
	v_lshl_add_u64 v[78:79], v[50:51], 0, v[78:79]
	v_lshl_add_u64 v[80:81], v[50:51], 0, v[80:81]
	v_lshl_add_u64 v[82:83], v[50:51], 0, v[82:83]
	v_lshl_add_u64 v[84:85], v[50:51], 0, v[84:85]
	v_lshl_add_u64 v[86:87], v[50:51], 0, v[86:87]
	v_lshl_add_u64 v[88:89], v[50:51], 0, v[88:89]
	global_load_dword v53, v[58:59], off
	global_load_dword v90, v[60:61], off
	global_load_dword v91, v[62:63], off
	global_load_dword v92, v[64:65], off
	global_load_dword v93, v[66:67], off
	global_load_dword v94, v[68:69], off
	global_load_dword v95, v[70:71], off
	global_load_dword v96, v[72:73], off
	global_load_dword v97, v[74:75], off
	global_load_dword v98, v[76:77], off
	global_load_dword v99, v[78:79], off
	global_load_dword v100, v[80:81], off
	global_load_dword v101, v[82:83], off
	global_load_dword v102, v[84:85], off
	global_load_dword v103, v[86:87], off
	global_load_dword v104, v[88:89], off
	v_or_b32_e32 v60, s16, v1
	v_or_b32_e32 v58, s17, v2
	s_add_i32 s8, s8, 16
	s_add_i32 s7, s7, 16
	s_add_i32 s9, s9, -16
	v_mad_u64_u32 v[58:59], s[16:17], v58, s63, v[4:5]
	v_mad_u64_u32 v[60:61], s[16:17], v60, s63, v[4:5]
	v_or_b32_e32 v59, s18, v1
	v_or_b32_e32 v61, s19, v2
	v_or_b32_e32 v68, s20, v1
	v_or_b32_e32 v66, s21, v2
	v_or_b32_e32 v72, s22, v1
	v_or_b32_e32 v70, s23, v2
	v_or_b32_e32 v76, s24, v1
	v_or_b32_e32 v74, s25, v2
	v_or_b32_e32 v80, s26, v1
	v_or_b32_e32 v78, s27, v2
	v_or_b32_e32 v84, s28, v1
	v_or_b32_e32 v82, s29, v2
	v_or_b32_e32 v88, s30, v1
	v_or_b32_e32 v86, s31, v2
	s_cmp_lg_u32 s9, 0
	v_mad_u64_u32 v[62:63], s[16:17], v61, s63, v[4:5]
	v_mad_u64_u32 v[64:65], s[16:17], v59, s63, v[4:5]
	v_mad_u64_u32 v[66:67], s[16:17], v66, s63, v[4:5]
	v_mad_u64_u32 v[68:69], s[16:17], v68, s63, v[4:5]
	v_mad_u64_u32 v[70:71], s[16:17], v70, s63, v[4:5]
	v_mad_u64_u32 v[72:73], s[16:17], v72, s63, v[4:5]
	v_mad_u64_u32 v[74:75], s[16:17], v74, s63, v[4:5]
	v_mad_u64_u32 v[76:77], s[16:17], v76, s63, v[4:5]
	v_mad_u64_u32 v[78:79], s[16:17], v78, s63, v[4:5]
	v_mad_u64_u32 v[80:81], s[16:17], v80, s63, v[4:5]
	v_mad_u64_u32 v[82:83], s[16:17], v82, s63, v[4:5]
	v_mad_u64_u32 v[84:85], s[16:17], v84, s63, v[4:5]
	v_mad_u64_u32 v[86:87], s[16:17], v86, s63, v[4:5]
	v_mad_u64_u32 v[88:89], s[16:17], v88, s63, v[4:5]
	s_waitcnt vmcnt(0)
	ds_write_b32 v58, v53
	ds_write_b32 v60, v90
	ds_write_b32 v62, v91
	ds_write_b32 v64, v92
	ds_write_b32 v66, v93
	ds_write_b32 v68, v94
	ds_write_b32 v70, v95
	ds_write_b32 v72, v96
	ds_write_b32 v74, v97
	ds_write_b32 v76, v98
	ds_write_b32 v78, v99
	ds_write_b32 v80, v100
	ds_write_b32 v82, v101
	ds_write_b32 v84, v102
	ds_write_b32 v86, v103
	ds_write_b32 v88, v104
	s_cbranch_scc1 .LBB0_58
; #define LAS __attribute__((address_space(3)))
; __device__ __forceinline__ unsigned pk2(float lo, float hi) { return f2bf(lo) | (f2bf(hi) << 16); }
; template <bool FFN_PERM = false>
; __device__ __forceinline__ void transpose_item(const float* W, int ldw, int K, bf16_t* WT, int nblk, int item, LAS float* scr, int lane) {
;     ...
;     const int c = lane & 7;
; #pragma unroll
;     for (int j = 0; j < 4; ++j) { const int n = (lane >> 3) + 8 * j; const LAS float* s = scr + (8 * c) * 33 + n;
;         u32x4 o; o.x = pk2(s[0 * 33], s[1 * 33]); o.y = pk2(s[2 * 33], s[3 * 33]); o.z = pk2(s[4 * 33], s[5 * 33]); o.w = pk2(s[6 * 33], s[7 * 33]);
;         *(u32x4*)(WT + (size_t)(d0 + n) * K + k0 + 8 * c) = o; }
;     asm volatile("s_waitcnt lgkmcnt(0)" ::: "memory");
	s_waitcnt lgkmcnt(0)
	ds_read_b32 v3, v54
	ds_read_b32 v50, v54 offset:132
	ds_read_b32 v51, v54 offset:264
	ds_read_b32 v52, v54 offset:396
	ds_read_b32 v53, v54 offset:528
	ds_read_b32 v60, v54 offset:660
	ds_read_b32 v61, v54 offset:792
	ds_read_b32 v62, v54 offset:924
	s_waitcnt lgkmcnt(0)
	v_bfe_u32 v63, v3, 16, 1
	v_add3_u32 v3, v3, v63, s60
	v_bfe_u32 v63, v50, 16, 1
	v_lshrrev_b32_e32 v3, 16, v3
	v_add3_u32 v50, v50, v63, s60
	v_and_or_b32 v50, v50, s61, v3
	v_bfe_u32 v3, v51, 16, 1
	v_add3_u32 v3, v51, v3, s60
	v_bfe_u32 v51, v52, 16, 1
	v_lshrrev_b32_e32 v3, 16, v3
	v_add3_u32 v51, v52, v51, s60
	v_and_or_b32 v51, v51, s61, v3
	v_bfe_u32 v3, v53, 16, 1
	v_add3_u32 v3, v53, v3, s60
	v_bfe_u32 v52, v60, 16, 1
	v_lshrrev_b32_e32 v3, 16, v3
	v_add3_u32 v52, v60, v52, s60
	v_and_or_b32 v52, v52, s61, v3
	v_bfe_u32 v3, v61, 16, 1
	v_add3_u32 v3, v61, v3, s60
	v_bfe_u32 v53, v62, 16, 1
	v_lshrrev_b32_e32 v3, 16, v3
	v_add3_u32 v53, v62, v53, s60
	s_lshl_b32 s96, s6, 1
	v_and_or_b32 v53, v53, s61, v3
	v_or_b32_e32 v3, s3, v7
	v_lshl_add_u64 v[58:59], v[16:17], 0, s[96:97]
	v_lshlrev_b32_e32 v60, 11, v3
	v_mov_b32_e32 v61, v0
	v_lshl_add_u64 v[60:61], v[58:59], 0, v[60:61]
	global_store_dwordx4 v[60:61], v[50:53], off
	ds_read_b32 v3, v54 offset:32
	ds_read_b32 v50, v54 offset:164
	ds_read_b32 v51, v54 offset:296
	ds_read_b32 v52, v54 offset:428
	ds_read_b32 v53, v54 offset:560
	ds_read_b32 v60, v54 offset:692
	ds_read_b32 v61, v54 offset:824
	ds_read_b32 v62, v54 offset:956
	s_waitcnt lgkmcnt(0)
	v_bfe_u32 v63, v3, 16, 1
	v_add3_u32 v3, v3, v63, s60
	v_bfe_u32 v63, v50, 16, 1
	v_lshrrev_b32_e32 v3, 16, v3
	v_add3_u32 v50, v50, v63, s60
	v_and_or_b32 v50, v50, s61, v3
	v_bfe_u32 v3, v51, 16, 1
	v_add3_u32 v3, v51, v3, s60
	v_bfe_u32 v51, v52, 16, 1
	v_lshrrev_b32_e32 v3, 16, v3
	v_add3_u32 v51, v52, v51, s60
	v_and_or_b32 v51, v51, s61, v3
	v_bfe_u32 v3, v53, 16, 1
	v_add3_u32 v3, v53, v3, s60
	v_bfe_u32 v52, v60, 16, 1
	v_lshrrev_b32_e32 v3, 16, v3
	v_add3_u32 v52, v60, v52, s60
	v_and_or_b32 v52, v52, s61, v3
	v_bfe_u32 v3, v61, 16, 1
	v_add3_u32 v3, v61, v3, s60
	v_bfe_u32 v53, v62, 16, 1
	v_lshrrev_b32_e32 v3, 16, v3
	v_add3_u32 v53, v62, v53, s60
	v_and_or_b32 v53, v53, s61, v3
	v_or_b32_e32 v3, s3, v55
	v_lshlrev_b32_e32 v60, 11, v3
	v_mov_b32_e32 v61, v0
	v_lshl_add_u64 v[60:61], v[58:59], 0, v[60:61]
	global_store_dwordx4 v[60:61], v[50:53], off
	ds_read_b32 v3, v54 offset:64
	ds_read_b32 v50, v54 offset:196
	ds_read_b32 v51, v54 offset:328
	ds_read_b32 v52, v54 offset:460
	ds_read_b32 v53, v54 offset:592
	ds_read_b32 v60, v54 offset:724
	ds_read_b32 v61, v54 offset:856
	ds_read_b32 v62, v54 offset:988
	s_waitcnt lgkmcnt(0)
	v_bfe_u32 v63, v3, 16, 1
	v_add3_u32 v3, v3, v63, s60
	v_bfe_u32 v63, v50, 16, 1
	v_lshrrev_b32_e32 v3, 16, v3
	v_add3_u32 v50, v50, v63, s60
	v_and_or_b32 v50, v50, s61, v3
	v_bfe_u32 v3, v51, 16, 1
	v_add3_u32 v3, v51, v3, s60
	v_bfe_u32 v51, v52, 16, 1
	v_lshrrev_b32_e32 v3, 16, v3
	v_add3_u32 v51, v52, v51, s60
	v_and_or_b32 v51, v51, s61, v3
	v_bfe_u32 v3, v53, 16, 1
	v_add3_u32 v3, v53, v3, s60
	v_bfe_u32 v52, v60, 16, 1
	v_lshrrev_b32_e32 v3, 16, v3
	v_add3_u32 v52, v60, v52, s60
	v_and_or_b32 v52, v52, s61, v3
	v_bfe_u32 v3, v61, 16, 1
	v_add3_u32 v3, v61, v3, s60
	v_bfe_u32 v53, v62, 16, 1
	v_lshrrev_b32_e32 v3, 16, v3
	v_add3_u32 v53, v62, v53, s60
	v_and_or_b32 v53, v53, s61, v3
	v_or_b32_e32 v3, s3, v56
	v_lshlrev_b32_e32 v60, 11, v3
	v_mov_b32_e32 v61, v0
	v_lshl_add_u64 v[60:61], v[58:59], 0, v[60:61]
	global_store_dwordx4 v[60:61], v[50:53], off
	ds_read_b32 v3, v54 offset:96
	ds_read_b32 v50, v54 offset:228
	ds_read_b32 v51, v54 offset:360
	ds_read_b32 v52, v54 offset:492
	ds_read_b32 v53, v54 offset:624
	ds_read_b32 v60, v54 offset:756
	ds_read_b32 v61, v54 offset:888
	ds_read_b32 v62, v54 offset:1020
	s_waitcnt lgkmcnt(0)
	v_bfe_u32 v63, v3, 16, 1
	v_add3_u32 v3, v3, v63, s60
	v_bfe_u32 v63, v50, 16, 1
	v_lshrrev_b32_e32 v3, 16, v3
	v_add3_u32 v50, v50, v63, s60
	v_and_or_b32 v50, v50, s61, v3
	v_bfe_u32 v3, v51, 16, 1
	v_add3_u32 v3, v51, v3, s60
	v_bfe_u32 v51, v52, 16, 1
	v_lshrrev_b32_e32 v3, 16, v3
	v_add3_u32 v51, v52, v51, s60
	v_and_or_b32 v51, v51, s61, v3
	v_bfe_u32 v3, v53, 16, 1
	v_add3_u32 v3, v53, v3, s60
	v_bfe_u32 v52, v60, 16, 1
	v_lshrrev_b32_e32 v3, 16, v3
	v_add3_u32 v52, v60, v52, s60
	v_and_or_b32 v52, v52, s61, v3
	v_bfe_u32 v3, v61, 16, 1
	v_add3_u32 v3, v61, v3, s60
	v_bfe_u32 v53, v62, 16, 1
	v_lshrrev_b32_e32 v3, 16, v3
	v_add3_u32 v53, v62, v53, s60
	v_and_or_b32 v53, v53, s61, v3
	v_or_b32_e32 v3, s3, v57
	v_lshlrev_b32_e32 v60, 11, v3
	v_mov_b32_e32 v61, v0
	v_lshl_add_u64 v[58:59], v[58:59], 0, v[60:61]
	global_store_dwordx4 v[58:59], v[50:53], off
	s_waitcnt lgkmcnt(0)

; template <bool FFN_PERM = false>
; __device__ __forceinline__ void transpose_item(const float* W, int ldw, int K, bf16_t* WT, int nblk, int item, LAS float* scr, int lane) {
;     const int kb = item / nblk, nb = item % nblk, k0 = 64 * kb, n0 = 32 * nb;
;     const int d0 = FFN_PERM ? ((n0 < DFF) ? ((n0 >> 7) * 256 + (n0 & 127)) : ((((n0 - DFF) >> 7) * 256) + 128 + ((n0 - DFF) & 127))) : n0;
; #pragma unroll 8
;     for (int i = 0; i < 32; ++i) { const int kk = 2 * i + (lane >> 5); scr[kk * 33 + (lane & 31)] = W[(size_t)(k0 + kk) * ldw + n0 + (lane & 31)]; }
.LBB0_63:
	s_lshl_b32 s16, s6, 1
	s_lshl_b32 s17, s8, 1
	v_mov_b32_e32 v59, v0
	v_or_b32_e32 v58, s17, v52
	s_add_i32 s18, s16, 4
	s_add_i32 s19, s17, 4
	s_add_i32 s20, s16, 8
	s_add_i32 s21, s17, 8
	s_add_i32 s22, s16, 12
	s_add_i32 s23, s17, 12
	s_add_i32 s24, s16, 16
	s_add_i32 s25, s17, 16
	s_add_i32 s26, s16, 20
	s_add_i32 s27, s17, 20
	s_add_i32 s28, s16, 24
	s_add_i32 s29, s17, 24
	s_add_i32 s30, s16, 28
	s_add_i32 s31, s17, 28
	v_mov_b32_e32 v61, v0
	v_mov_b32_e32 v63, v0
	v_mov_b32_e32 v65, v0
	v_mov_b32_e32 v67, v0
	v_mov_b32_e32 v69, v0
	v_mov_b32_e32 v71, v0
	v_mov_b32_e32 v73, v0
	v_mov_b32_e32 v75, v0
	v_mov_b32_e32 v77, v0
	v_mov_b32_e32 v79, v0
	v_mov_b32_e32 v81, v0
	v_mov_b32_e32 v83, v0
	v_mov_b32_e32 v85, v0
	v_mov_b32_e32 v87, v0
	v_mov_b32_e32 v89, v0
	v_or_b32_e32 v60, s16, v3
	v_lshlrev_b64 v[58:59], 12, v[58:59]
	v_or_b32_e32 v64, s18, v3
	v_or_b32_e32 v62, s19, v52
	v_or_b32_e32 v68, s20, v3
	v_or_b32_e32 v66, s21, v52
	v_or_b32_e32 v72, s22, v3
	v_or_b32_e32 v70, s23, v52
	v_or_b32_e32 v76, s24, v3
	v_or_b32_e32 v74, s25, v52
	v_or_b32_e32 v80, s26, v3
	v_or_b32_e32 v78, s27, v52
	v_or_b32_e32 v84, s28, v3
	v_or_b32_e32 v82, s29, v52
	v_or_b32_e32 v88, s30, v3
	v_or_b32_e32 v86, s31, v52
	v_lshlrev_b64 v[60:61], 12, v[60:61]
	v_lshl_add_u64 v[58:59], v[50:51], 0, v[58:59]
	v_lshlrev_b64 v[64:65], 12, v[64:65]
	v_lshlrev_b64 v[62:63], 12, v[62:63]
	v_lshlrev_b64 v[68:69], 12, v[68:69]
	v_lshlrev_b64 v[66:67], 12, v[66:67]
	v_lshlrev_b64 v[72:73], 12, v[72:73]
	v_lshlrev_b64 v[70:71], 12, v[70:71]
	v_lshlrev_b64 v[76:77], 12, v[76:77]
	v_lshlrev_b64 v[74:75], 12, v[74:75]
	v_lshlrev_b64 v[80:81], 12, v[80:81]
	v_lshlrev_b64 v[78:79], 12, v[78:79]
	v_lshlrev_b64 v[84:85], 12, v[84:85]
	v_lshlrev_b64 v[82:83], 12, v[82:83]
	v_lshlrev_b64 v[88:89], 12, v[88:89]
	v_lshlrev_b64 v[86:87], 12, v[86:87]
	v_lshl_add_u64 v[60:61], v[50:51], 0, v[60:61]
	v_lshl_add_u64 v[62:63], v[50:51], 0, v[62:63]
	v_lshl_add_u64 v[64:65], v[50:51], 0, v[64:65]
	v_lshl_add_u64 v[66:67], v[50:51], 0, v[66:67]
	v_lshl_add_u64 v[68:69], v[50:51], 0, v[68:69]
	v_lshl_add_u64 v[70:71], v[50:51], 0, v[70:71]
	v_lshl_add_u64 v[72:73], v[50:51], 0, v[72:73]
	v_lshl_add_u64 v[74:75], v[50:51], 0, v[74:75]
	v_lshl_add_u64 v[76:77], v[50:51], 0, v[76:77]
	v_lshl_add_u64 v[78:79], v[50:51], 0, v[78:79]
	v_lshl_add_u64 v[80:81], v[50:51], 0, v[80:81]
	v_lshl_add_u64 v[82:83], v[50:51], 0, v[82:83]
	v_lshl_add_u64 v[84:85], v[50:51], 0, v[84:85]
	v_lshl_add_u64 v[86:87], v[50:51], 0, v[86:87]
	v_lshl_add_u64 v[88:89], v[50:51], 0, v[88:89]
	global_load_dword v53, v[58:59], off
	global_load_dword v90, v[60:61], off
	global_load_dword v91, v[62:63], off
	global_load_dword v92, v[64:65], off
	global_load_dword v93, v[66:67], off
	global_load_dword v94, v[68:69], off
	global_load_dword v95, v[70:71], off
	global_load_dword v96, v[72:73], off
	global_load_dword v97, v[74:75], off
	global_load_dword v98, v[76:77], off
	global_load_dword v99, v[78:79], off
	global_load_dword v100, v[80:81], off
	global_load_dword v101, v[82:83], off
	global_load_dword v102, v[84:85], off
	global_load_dword v103, v[86:87], off
	global_load_dword v104, v[88:89], off
	v_or_b32_e32 v60, s16, v1
	v_or_b32_e32 v58, s17, v2
	s_add_i32 s8, s8, 16
	s_add_i32 s6, s6, 16
	s_add_i32 s9, s9, -16
	v_mad_u64_u32 v[58:59], s[16:17], v58, s63, v[4:5]
	v_mad_u64_u32 v[60:61], s[16:17], v60, s63, v[4:5]
	v_or_b32_e32 v59, s18, v1
	v_or_b32_e32 v61, s19, v2
	v_or_b32_e32 v68, s20, v1
	v_or_b32_e32 v66, s21, v2
	v_or_b32_e32 v72, s22, v1
	v_or_b32_e32 v70, s23, v2
	v_or_b32_e32 v76, s24, v1
	v_or_b32_e32 v74, s25, v2
	v_or_b32_e32 v80, s26, v1
	v_or_b32_e32 v78, s27, v2
	v_or_b32_e32 v84, s28, v1
	v_or_b32_e32 v82, s29, v2
	v_or_b32_e32 v88, s30, v1
	v_or_b32_e32 v86, s31, v2
	s_cmp_lg_u32 s9, 0
	v_mad_u64_u32 v[62:63], s[16:17], v61, s63, v[4:5]
	v_mad_u64_u32 v[64:65], s[16:17], v59, s63, v[4:5]
	v_mad_u64_u32 v[66:67], s[16:17], v66, s63, v[4:5]
	v_mad_u64_u32 v[68:69], s[16:17], v68, s63, v[4:5]
	v_mad_u64_u32 v[70:71], s[16:17], v70, s63, v[4:5]
	v_mad_u64_u32 v[72:73], s[16:17], v72, s63, v[4:5]
	v_mad_u64_u32 v[74:75], s[16:17], v74, s63, v[4:5]
	v_mad_u64_u32 v[76:77], s[16:17], v76, s63, v[4:5]
	v_mad_u64_u32 v[78:79], s[16:17], v78, s63, v[4:5]
	v_mad_u64_u32 v[80:81], s[16:17], v80, s63, v[4:5]
	v_mad_u64_u32 v[82:83], s[16:17], v82, s63, v[4:5]
	v_mad_u64_u32 v[84:85], s[16:17], v84, s63, v[4:5]
	v_mad_u64_u32 v[86:87], s[16:17], v86, s63, v[4:5]
	v_mad_u64_u32 v[88:89], s[16:17], v88, s63, v[4:5]
	s_waitcnt vmcnt(0)
	ds_write_b32 v58, v53
	ds_write_b32 v60, v90
	ds_write_b32 v62, v91
	ds_write_b32 v64, v92
	ds_write_b32 v66, v93
	ds_write_b32 v68, v94
	ds_write_b32 v70, v95
	ds_write_b32 v72, v96
	ds_write_b32 v74, v97
	ds_write_b32 v76, v98
	ds_write_b32 v78, v99
	ds_write_b32 v80, v100
	ds_write_b32 v82, v101
	ds_write_b32 v84, v102
	ds_write_b32 v86, v103
	ds_write_b32 v88, v104
	s_cbranch_scc1 .LBB0_63
; #define LAS __attribute__((address_space(3)))
; __device__ __forceinline__ unsigned pk2(float lo, float hi) { return f2bf(lo) | (f2bf(hi) << 16); }
; template <bool FFN_PERM = false>
; __device__ __forceinline__ void transpose_item(const float* W, int ldw, int K, bf16_t* WT, int nblk, int item, LAS float* scr, int lane) {
;     ...
;     const int c = lane & 7;
; #pragma unroll
;     for (int j = 0; j < 4; ++j) { const int n = (lane >> 3) + 8 * j; const LAS float* s = scr + (8 * c) * 33 + n;
;         u32x4 o; o.x = pk2(s[0 * 33], s[1 * 33]); o.y = pk2(s[2 * 33], s[3 * 33]); o.z = pk2(s[4 * 33], s[5 * 33]); o.w = pk2(s[6 * 33], s[7 * 33]);
;         *(u32x4*)(WT + (size_t)(d0 + n) * K + k0 + 8 * c) = o; }
;     asm volatile("s_waitcnt lgkmcnt(0)" ::: "memory");
	s_waitcnt lgkmcnt(0)
	ds_read_b32 v3, v54
	ds_read_b32 v50, v54 offset:132
	ds_read_b32 v51, v54 offset:264
	ds_read_b32 v52, v54 offset:396
	ds_read_b32 v53, v54 offset:528
	ds_read_b32 v60, v54 offset:660
	ds_read_b32 v61, v54 offset:792
	ds_read_b32 v62, v54 offset:924
	s_waitcnt lgkmcnt(0)
	v_bfe_u32 v63, v3, 16, 1
	v_add3_u32 v3, v3, v63, s60
	v_bfe_u32 v63, v50, 16, 1
	v_lshrrev_b32_e32 v3, 16, v3
	v_add3_u32 v50, v50, v63, s60
	v_and_or_b32 v50, v50, s61, v3
	v_bfe_u32 v3, v51, 16, 1
	v_add3_u32 v3, v51, v3, s60
	v_bfe_u32 v51, v52, 16, 1
	v_lshrrev_b32_e32 v3, 16, v3
	v_add3_u32 v51, v52, v51, s60
	v_and_or_b32 v51, v51, s61, v3
	v_bfe_u32 v3, v53, 16, 1
	v_add3_u32 v3, v53, v3, s60
	v_bfe_u32 v52, v60, 16, 1
	v_lshrrev_b32_e32 v3, 16, v3
	v_add3_u32 v52, v60, v52, s60
	v_and_or_b32 v52, v52, s61, v3
	v_bfe_u32 v3, v61, 16, 1
	v_add3_u32 v3, v61, v3, s60
	v_bfe_u32 v53, v62, 16, 1
	v_lshrrev_b32_e32 v3, 16, v3
	v_add3_u32 v53, v62, v53, s60
	s_lshl_b32 s96, s7, 1
	v_and_or_b32 v53, v53, s61, v3
	v_or_b32_e32 v3, s3, v7
	v_lshl_add_u64 v[58:59], v[18:19], 0, s[96:97]
	v_lshlrev_b32_e32 v60, 11, v3
	v_mov_b32_e32 v61, v0
	v_lshl_add_u64 v[60:61], v[58:59], 0, v[60:61]
	global_store_dwordx4 v[60:61], v[50:53], off
	ds_read_b32 v3, v54 offset:32
	ds_read_b32 v50, v54 offset:164
	ds_read_b32 v51, v54 offset:296
	ds_read_b32 v52, v54 offset:428
	ds_read_b32 v53, v54 offset:560
	ds_read_b32 v60, v54 offset:692
	ds_read_b32 v61, v54 offset:824
	ds_read_b32 v62, v54 offset:956
	s_waitcnt lgkmcnt(0)
	v_bfe_u32 v63, v3, 16, 1
	v_add3_u32 v3, v3, v63, s60
	v_bfe_u32 v63, v50, 16, 1
	v_lshrrev_b32_e32 v3, 16, v3
	v_add3_u32 v50, v50, v63, s60
	v_and_or_b32 v50, v50, s61, v3
	v_bfe_u32 v3, v51, 16, 1
	v_add3_u32 v3, v51, v3, s60
	v_bfe_u32 v51, v52, 16, 1
	v_lshrrev_b32_e32 v3, 16, v3
	v_add3_u32 v51, v52, v51, s60
	v_and_or_b32 v51, v51, s61, v3
	v_bfe_u32 v3, v53, 16, 1
	v_add3_u32 v3, v53, v3, s60
	v_bfe_u32 v52, v60, 16, 1
	v_lshrrev_b32_e32 v3, 16, v3
	v_add3_u32 v52, v60, v52, s60
	v_and_or_b32 v52, v52, s61, v3
	v_bfe_u32 v3, v61, 16, 1
	v_add3_u32 v3, v61, v3, s60
	v_bfe_u32 v53, v62, 16, 1
	v_lshrrev_b32_e32 v3, 16, v3
	v_add3_u32 v53, v62, v53, s60
	v_and_or_b32 v53, v53, s61, v3
	v_or_b32_e32 v3, s3, v55
	v_lshlrev_b32_e32 v60, 11, v3
	v_mov_b32_e32 v61, v0
	v_lshl_add_u64 v[60:61], v[58:59], 0, v[60:61]
	global_store_dwordx4 v[60:61], v[50:53], off
	ds_read_b32 v3, v54 offset:64
	ds_read_b32 v50, v54 offset:196
	ds_read_b32 v51, v54 offset:328
	ds_read_b32 v52, v54 offset:460
	ds_read_b32 v53, v54 offset:592
	ds_read_b32 v60, v54 offset:724
	ds_read_b32 v61, v54 offset:856
	ds_read_b32 v62, v54 offset:988
	s_waitcnt lgkmcnt(0)
	v_bfe_u32 v63, v3, 16, 1
	v_add3_u32 v3, v3, v63, s60
	v_bfe_u32 v63, v50, 16, 1
	v_lshrrev_b32_e32 v3, 16, v3
	v_add3_u32 v50, v50, v63, s60
	v_and_or_b32 v50, v50, s61, v3
	v_bfe_u32 v3, v51, 16, 1
	v_add3_u32 v3, v51, v3, s60
	v_bfe_u32 v51, v52, 16, 1
	v_lshrrev_b32_e32 v3, 16, v3
	v_add3_u32 v51, v52, v51, s60
	v_and_or_b32 v51, v51, s61, v3
	v_bfe_u32 v3, v53, 16, 1
	v_add3_u32 v3, v53, v3, s60
	v_bfe_u32 v52, v60, 16, 1
	v_lshrrev_b32_e32 v3, 16, v3
	v_add3_u32 v52, v60, v52, s60
	v_and_or_b32 v52, v52, s61, v3
	v_bfe_u32 v3, v61, 16, 1
	v_add3_u32 v3, v61, v3, s60
	v_bfe_u32 v53, v62, 16, 1
	v_lshrrev_b32_e32 v3, 16, v3
	v_add3_u32 v53, v62, v53, s60
	v_and_or_b32 v53, v53, s61, v3
	v_or_b32_e32 v3, s3, v56
	v_lshlrev_b32_e32 v60, 11, v3
	v_mov_b32_e32 v61, v0
	v_lshl_add_u64 v[60:61], v[58:59], 0, v[60:61]
	global_store_dwordx4 v[60:61], v[50:53], off
	ds_read_b32 v3, v54 offset:96
	ds_read_b32 v50, v54 offset:228
	ds_read_b32 v51, v54 offset:360
	ds_read_b32 v52, v54 offset:492
	ds_read_b32 v53, v54 offset:624
	ds_read_b32 v60, v54 offset:756
	ds_read_b32 v61, v54 offset:888
	ds_read_b32 v62, v54 offset:1020
	s_waitcnt lgkmcnt(0)
	v_bfe_u32 v63, v3, 16, 1
	v_add3_u32 v3, v3, v63, s60
	v_bfe_u32 v63, v50, 16, 1
	v_lshrrev_b32_e32 v3, 16, v3
	v_add3_u32 v50, v50, v63, s60
	v_and_or_b32 v50, v50, s61, v3
	v_bfe_u32 v3, v51, 16, 1
	v_add3_u32 v3, v51, v3, s60
	v_bfe_u32 v51, v52, 16, 1
	v_lshrrev_b32_e32 v3, 16, v3
	v_add3_u32 v51, v52, v51, s60
	v_and_or_b32 v51, v51, s61, v3
	v_bfe_u32 v3, v53, 16, 1
	v_add3_u32 v3, v53, v3, s60
	v_bfe_u32 v52, v60, 16, 1
	v_lshrrev_b32_e32 v3, 16, v3
	v_add3_u32 v52, v60, v52, s60
	v_and_or_b32 v52, v52, s61, v3
	v_bfe_u32 v3, v61, 16, 1
	v_add3_u32 v3, v61, v3, s60
	v_bfe_u32 v53, v62, 16, 1
	v_lshrrev_b32_e32 v3, 16, v3
	v_add3_u32 v53, v62, v53, s60
	v_and_or_b32 v53, v53, s61, v3
	v_or_b32_e32 v3, s3, v57
	v_lshlrev_b32_e32 v60, 11, v3
	v_mov_b32_e32 v61, v0
	v_lshl_add_u64 v[58:59], v[58:59], 0, v[60:61]
	global_store_dwordx4 v[58:59], v[50:53], off
	s_waitcnt lgkmcnt(0)

; template <bool FFN_PERM = false>
; __device__ __forceinline__ void transpose_item(const float* W, int ldw, int K, bf16_t* WT, int nblk, int item, LAS float* scr, int lane) {
;     const int kb = item / nblk, nb = item % nblk, k0 = 64 * kb, n0 = 32 * nb;
;     const int d0 = FFN_PERM ? ((n0 < DFF) ? ((n0 >> 7) * 256 + (n0 & 127)) : ((((n0 - DFF) >> 7) * 256) + 128 + ((n0 - DFF) & 127))) : n0;
; #pragma unroll 8
;     for (int i = 0; i < 32; ++i) { const int kk = 2 * i + (lane >> 5); scr[kk * 33 + (lane & 31)] = W[(size_t)(k0 + kk) * ldw + n0 + (lane & 31)]; }
.LBB0_68:
	s_lshl_b32 s18, s7, 1
	s_lshl_b32 s19, s8, 1
	v_or_b32_e32 v53, s18, v3
	v_or_b32_e32 v58, s19, v52
	s_add_i32 s20, s18, 4
	s_add_i32 s21, s19, 4
	s_add_i32 s22, s18, 8
	s_add_i32 s23, s19, 8
	s_add_i32 s24, s18, 12
	s_add_i32 s25, s19, 12
	s_add_i32 s26, s18, 16
	s_add_i32 s27, s19, 16
	s_add_i32 s28, s18, 20
	s_add_i32 s29, s19, 20
	s_add_i32 s30, s18, 24
	s_add_i32 s31, s19, 24
	s_add_i32 s34, s18, 28
	s_add_i32 s35, s19, 28
	v_mad_u64_u32 v[58:59], s[16:17], v58, s33, v[50:51]
	v_mad_u64_u32 v[60:61], s[16:17], v53, s33, v[50:51]
	v_or_b32_e32 v53, s20, v3
	v_or_b32_e32 v62, s21, v52
	v_or_b32_e32 v68, s22, v3
	v_or_b32_e32 v66, s23, v52
	v_or_b32_e32 v72, s24, v3
	v_or_b32_e32 v70, s25, v52
	v_or_b32_e32 v76, s26, v3
	v_or_b32_e32 v74, s27, v52
	v_or_b32_e32 v80, s28, v3
	v_or_b32_e32 v78, s29, v52
	v_or_b32_e32 v84, s30, v3
	v_or_b32_e32 v82, s31, v52
	v_or_b32_e32 v88, s34, v3
	v_or_b32_e32 v86, s35, v52
	v_mad_u64_u32 v[62:63], s[16:17], v62, s33, v[50:51]
	v_mad_u64_u32 v[64:65], s[16:17], v53, s33, v[50:51]
	v_mad_u64_u32 v[66:67], s[16:17], v66, s33, v[50:51]
	v_mad_u64_u32 v[68:69], s[16:17], v68, s33, v[50:51]
	v_mad_u64_u32 v[70:71], s[16:17], v70, s33, v[50:51]
	v_mad_u64_u32 v[72:73], s[16:17], v72, s33, v[50:51]
	v_mad_u64_u32 v[74:75], s[16:17], v74, s33, v[50:51]
	v_mad_u64_u32 v[76:77], s[16:17], v76, s33, v[50:51]
	v_mad_u64_u32 v[78:79], s[16:17], v78, s33, v[50:51]
	v_mad_u64_u32 v[80:81], s[16:17], v80, s33, v[50:51]
	v_mad_u64_u32 v[82:83], s[16:17], v82, s33, v[50:51]
	v_mad_u64_u32 v[84:85], s[16:17], v84, s33, v[50:51]
	v_mad_u64_u32 v[86:87], s[16:17], v86, s33, v[50:51]
	v_mad_u64_u32 v[88:89], s[16:17], v88, s33, v[50:51]
	global_load_dword v53, v[58:59], off
	global_load_dword v90, v[60:61], off
	global_load_dword v91, v[62:63], off
	global_load_dword v92, v[64:65], off
	global_load_dword v93, v[66:67], off
	global_load_dword v94, v[68:69], off
	global_load_dword v95, v[70:71], off
	global_load_dword v96, v[72:73], off
	global_load_dword v97, v[74:75], off
	global_load_dword v98, v[76:77], off
	global_load_dword v99, v[78:79], off
	global_load_dword v100, v[80:81], off
	global_load_dword v101, v[82:83], off
	global_load_dword v102, v[84:85], off
	global_load_dword v103, v[86:87], off
	global_load_dword v104, v[88:89], off
	v_or_b32_e32 v60, s18, v1
	v_or_b32_e32 v58, s19, v2
	s_add_i32 s8, s8, 16
	s_add_i32 s7, s7, 16
	s_add_i32 s9, s9, -16
	v_mad_u64_u32 v[58:59], s[16:17], v58, s63, v[4:5]
	v_mad_u64_u32 v[60:61], s[16:17], v60, s63, v[4:5]
	v_or_b32_e32 v59, s20, v1
	v_or_b32_e32 v61, s21, v2
	v_or_b32_e32 v68, s22, v1
	v_or_b32_e32 v66, s23, v2
	v_or_b32_e32 v72, s24, v1
	v_or_b32_e32 v70, s25, v2
	v_or_b32_e32 v76, s26, v1
	v_or_b32_e32 v74, s27, v2
	v_or_b32_e32 v80, s28, v1
	v_or_b32_e32 v78, s29, v2
	v_or_b32_e32 v84, s30, v1
	v_or_b32_e32 v82, s31, v2
	v_or_b32_e32 v88, s34, v1
	v_or_b32_e32 v86, s35, v2
	s_cmp_lg_u32 s9, 0
	v_mad_u64_u32 v[62:63], s[16:17], v61, s63, v[4:5]
	v_mad_u64_u32 v[64:65], s[16:17], v59, s63, v[4:5]
	v_mad_u64_u32 v[66:67], s[16:17], v66, s63, v[4:5]
	v_mad_u64_u32 v[68:69], s[16:17], v68, s63, v[4:5]
	v_mad_u64_u32 v[70:71], s[16:17], v70, s63, v[4:5]
	v_mad_u64_u32 v[72:73], s[16:17], v72, s63, v[4:5]
	v_mad_u64_u32 v[74:75], s[16:17], v74, s63, v[4:5]
	v_mad_u64_u32 v[76:77], s[16:17], v76, s63, v[4:5]
	v_mad_u64_u32 v[78:79], s[16:17], v78, s63, v[4:5]
	v_mad_u64_u32 v[80:81], s[16:17], v80, s63, v[4:5]
	v_mad_u64_u32 v[82:83], s[16:17], v82, s63, v[4:5]
	v_mad_u64_u32 v[84:85], s[16:17], v84, s63, v[4:5]
	v_mad_u64_u32 v[86:87], s[16:17], v86, s63, v[4:5]
	v_mad_u64_u32 v[88:89], s[16:17], v88, s63, v[4:5]
	s_waitcnt vmcnt(0)
	ds_write_b32 v58, v53
	ds_write_b32 v60, v90
	ds_write_b32 v62, v91
	ds_write_b32 v64, v92
	ds_write_b32 v66, v93
	ds_write_b32 v68, v94
	ds_write_b32 v70, v95
	ds_write_b32 v72, v96
	ds_write_b32 v74, v97
	ds_write_b32 v76, v98
	ds_write_b32 v78, v99
	ds_write_b32 v80, v100
	ds_write_b32 v82, v101
	ds_write_b32 v84, v102
	ds_write_b32 v86, v103
	ds_write_b32 v88, v104
	s_cbranch_scc1 .LBB0_68
; #define LAS __attribute__((address_space(3)))
; __device__ __forceinline__ unsigned pk2(float lo, float hi) { return f2bf(lo) | (f2bf(hi) << 16); }
; template <bool FFN_PERM = false>
; __device__ __forceinline__ void transpose_item(const float* W, int ldw, int K, bf16_t* WT, int nblk, int item, LAS float* scr, int lane) {
;     ...
;     const int c = lane & 7;
; #pragma unroll
;     for (int j = 0; j < 4; ++j) { const int n = (lane >> 3) + 8 * j; const LAS float* s = scr + (8 * c) * 33 + n;
;         u32x4 o; o.x = pk2(s[0 * 33], s[1 * 33]); o.y = pk2(s[2 * 33], s[3 * 33]); o.z = pk2(s[4 * 33], s[5 * 33]); o.w = pk2(s[6 * 33], s[7 * 33]);
;         *(u32x4*)(WT + (size_t)(d0 + n) * K + k0 + 8 * c) = o; }
;     asm volatile("s_waitcnt lgkmcnt(0)" ::: "memory");
	s_waitcnt lgkmcnt(0)
	ds_read_b32 v3, v54
	ds_read_b32 v50, v54 offset:132
	ds_read_b32 v51, v54 offset:264
	ds_read_b32 v52, v54 offset:396
	ds_read_b32 v53, v54 offset:528
	ds_read_b32 v60, v54 offset:660
	ds_read_b32 v61, v54 offset:792
	ds_read_b32 v62, v54 offset:924
	s_waitcnt lgkmcnt(0)
	v_bfe_u32 v63, v3, 16, 1
	v_add3_u32 v3, v3, v63, s60
	v_bfe_u32 v63, v50, 16, 1
	v_lshrrev_b32_e32 v3, 16, v3
	v_add3_u32 v50, v50, v63, s60
	v_and_or_b32 v50, v50, s61, v3
	v_bfe_u32 v3, v51, 16, 1
	v_add3_u32 v3, v51, v3, s60
	v_bfe_u32 v51, v52, 16, 1
	v_lshrrev_b32_e32 v3, 16, v3
	v_add3_u32 v51, v52, v51, s60
	v_and_or_b32 v51, v51, s61, v3
	v_bfe_u32 v3, v53, 16, 1
	v_add3_u32 v3, v53, v3, s60
	v_bfe_u32 v52, v60, 16, 1
	v_lshrrev_b32_e32 v3, 16, v3
	v_add3_u32 v52, v60, v52, s60
	v_and_or_b32 v52, v52, s61, v3
	v_bfe_u32 v3, v61, 16, 1
	v_add3_u32 v3, v61, v3, s60
	v_bfe_u32 v53, v62, 16, 1
	s_and_b32 s3, 0xffff, s3
	s_and_b32 s6, 0xffff, s6
	v_lshrrev_b32_e32 v3, 16, v3
	v_add3_u32 v53, v62, v53, s60
	s_lshl_b32 s96, s6, 1
	v_and_or_b32 v53, v53, s61, v3
	v_or_b32_e32 v3, s3, v7
	v_lshl_add_u64 v[58:59], v[20:21], 0, s[96:97]
	v_lshlrev_b32_e32 v60, 11, v3
	v_mov_b32_e32 v61, v0
	v_lshl_add_u64 v[60:61], v[58:59], 0, v[60:61]
	global_store_dwordx4 v[60:61], v[50:53], off
	ds_read_b32 v3, v54 offset:32
	ds_read_b32 v50, v54 offset:164
	ds_read_b32 v51, v54 offset:296
	ds_read_b32 v52, v54 offset:428
	ds_read_b32 v53, v54 offset:560
	ds_read_b32 v60, v54 offset:692
	ds_read_b32 v61, v54 offset:824
	ds_read_b32 v62, v54 offset:956
	s_waitcnt lgkmcnt(0)
	v_bfe_u32 v63, v3, 16, 1
	v_add3_u32 v3, v3, v63, s60
	v_bfe_u32 v63, v50, 16, 1
	v_lshrrev_b32_e32 v3, 16, v3
	v_add3_u32 v50, v50, v63, s60
	v_and_or_b32 v50, v50, s61, v3
	v_bfe_u32 v3, v51, 16, 1
	v_add3_u32 v3, v51, v3, s60
	v_bfe_u32 v51, v52, 16, 1
	v_lshrrev_b32_e32 v3, 16, v3
	v_add3_u32 v51, v52, v51, s60
	v_and_or_b32 v51, v51, s61, v3
	v_bfe_u32 v3, v53, 16, 1
	v_add3_u32 v3, v53, v3, s60
	v_bfe_u32 v52, v60, 16, 1
	v_lshrrev_b32_e32 v3, 16, v3
	v_add3_u32 v52, v60, v52, s60
	v_and_or_b32 v52, v52, s61, v3
	v_bfe_u32 v3, v61, 16, 1
	v_add3_u32 v3, v61, v3, s60
	v_bfe_u32 v53, v62, 16, 1
	v_lshrrev_b32_e32 v3, 16, v3
	v_add3_u32 v53, v62, v53, s60
	v_and_or_b32 v53, v53, s61, v3
	v_or_b32_e32 v3, s3, v55
	v_lshlrev_b32_e32 v60, 11, v3
	v_mov_b32_e32 v61, v0
	v_lshl_add_u64 v[60:61], v[58:59], 0, v[60:61]
	global_store_dwordx4 v[60:61], v[50:53], off
	ds_read_b32 v3, v54 offset:64
	ds_read_b32 v50, v54 offset:196
	ds_read_b32 v51, v54 offset:328
	ds_read_b32 v52, v54 offset:460
	ds_read_b32 v53, v54 offset:592
	ds_read_b32 v60, v54 offset:724
	ds_read_b32 v61, v54 offset:856
	ds_read_b32 v62, v54 offset:988
	s_waitcnt lgkmcnt(0)
	v_bfe_u32 v63, v3, 16, 1
	v_add3_u32 v3, v3, v63, s60
	v_bfe_u32 v63, v50, 16, 1
	v_lshrrev_b32_e32 v3, 16, v3
	v_add3_u32 v50, v50, v63, s60
	v_and_or_b32 v50, v50, s61, v3
	v_bfe_u32 v3, v51, 16, 1
	v_add3_u32 v3, v51, v3, s60
	v_bfe_u32 v51, v52, 16, 1
	v_lshrrev_b32_e32 v3, 16, v3
	v_add3_u32 v51, v52, v51, s60
	v_and_or_b32 v51, v51, s61, v3
	v_bfe_u32 v3, v53, 16, 1
	v_add3_u32 v3, v53, v3, s60
	v_bfe_u32 v52, v60, 16, 1
	v_lshrrev_b32_e32 v3, 16, v3
	v_add3_u32 v52, v60, v52, s60
	v_and_or_b32 v52, v52, s61, v3
	v_bfe_u32 v3, v61, 16, 1
	v_add3_u32 v3, v61, v3, s60
	v_bfe_u32 v53, v62, 16, 1
	v_lshrrev_b32_e32 v3, 16, v3
	v_add3_u32 v53, v62, v53, s60
	v_and_or_b32 v53, v53, s61, v3
	v_or_b32_e32 v3, s3, v56
	v_lshlrev_b32_e32 v60, 11, v3
	v_mov_b32_e32 v61, v0
	v_lshl_add_u64 v[60:61], v[58:59], 0, v[60:61]
	global_store_dwordx4 v[60:61], v[50:53], off
	ds_read_b32 v3, v54 offset:96
	ds_read_b32 v50, v54 offset:228
	ds_read_b32 v51, v54 offset:360
	ds_read_b32 v52, v54 offset:492
	ds_read_b32 v53, v54 offset:624
	ds_read_b32 v60, v54 offset:756
	ds_read_b32 v61, v54 offset:888
	ds_read_b32 v62, v54 offset:1020
	s_waitcnt lgkmcnt(0)
	v_bfe_u32 v63, v3, 16, 1
	v_add3_u32 v3, v3, v63, s60
	v_bfe_u32 v63, v50, 16, 1
	v_lshrrev_b32_e32 v3, 16, v3
	v_add3_u32 v50, v50, v63, s60
	v_and_or_b32 v50, v50, s61, v3
	v_bfe_u32 v3, v51, 16, 1
	v_add3_u32 v3, v51, v3, s60
	v_bfe_u32 v51, v52, 16, 1
	v_lshrrev_b32_e32 v3, 16, v3
	v_add3_u32 v51, v52, v51, s60
	v_and_or_b32 v51, v51, s61, v3
	v_bfe_u32 v3, v53, 16, 1
	v_add3_u32 v3, v53, v3, s60
	v_bfe_u32 v52, v60, 16, 1
	v_lshrrev_b32_e32 v3, 16, v3
	v_add3_u32 v52, v60, v52, s60
	v_and_or_b32 v52, v52, s61, v3
	v_bfe_u32 v3, v61, 16, 1
	v_add3_u32 v3, v61, v3, s60
	v_bfe_u32 v53, v62, 16, 1
	v_lshrrev_b32_e32 v3, 16, v3
	v_add3_u32 v53, v62, v53, s60
	v_and_or_b32 v53, v53, s61, v3
	v_or_b32_e32 v3, s3, v57
	v_lshlrev_b32_e32 v60, 11, v3
	v_mov_b32_e32 v61, v0
	v_lshl_add_u64 v[58:59], v[58:59], 0, v[60:61]
	global_store_dwordx4 v[58:59], v[50:53], off
	s_waitcnt lgkmcnt(0)

; template <bool FFN_PERM = false>
; __device__ __forceinline__ void transpose_item(const float* W, int ldw, int K, bf16_t* WT, int nblk, int item, LAS float* scr, int lane) {
;     const int kb = item / nblk, nb = item % nblk, k0 = 64 * kb, n0 = 32 * nb;
;     const int d0 = FFN_PERM ? ((n0 < DFF) ? ((n0 >> 7) * 256 + (n0 & 127)) : ((((n0 - DFF) >> 7) * 256) + 128 + ((n0 - DFF) & 127))) : n0;
; #pragma unroll 8
;     for (int i = 0; i < 32; ++i) { const int kk = 2 * i + (lane >> 5); scr[kk * 33 + (lane & 31)] = W[(size_t)(k0 + kk) * ldw + n0 + (lane & 31)]; }
.LBB0_73:
	s_lshl_b32 s18, s3, 1
	s_lshl_b32 s19, s7, 1
	v_or_b32_e32 v53, s18, v3
	v_or_b32_e32 v58, s19, v52
	s_add_i32 s20, s18, 4
	s_add_i32 s21, s19, 4
	s_add_i32 s22, s18, 8
	s_add_i32 s23, s19, 8
	s_add_i32 s24, s18, 12
	s_add_i32 s25, s19, 12
	s_add_i32 s26, s18, 16
	s_add_i32 s27, s19, 16
	s_add_i32 s28, s18, 20
	s_add_i32 s29, s19, 20
	s_add_i32 s30, s18, 24
	s_add_i32 s31, s19, 24
	s_add_i32 s34, s18, 28
	s_add_i32 s35, s19, 28
	v_mad_i64_i32 v[58:59], s[16:17], v58, s33, v[50:51]
	v_mad_i64_i32 v[60:61], s[16:17], v53, s33, v[50:51]
	v_or_b32_e32 v53, s20, v3
	v_or_b32_e32 v62, s21, v52
	v_or_b32_e32 v68, s22, v3
	v_or_b32_e32 v66, s23, v52
	v_or_b32_e32 v72, s24, v3
	v_or_b32_e32 v70, s25, v52
	v_or_b32_e32 v76, s26, v3
	v_or_b32_e32 v74, s27, v52
	v_or_b32_e32 v80, s28, v3
	v_or_b32_e32 v78, s29, v52
	v_or_b32_e32 v84, s30, v3
	v_or_b32_e32 v82, s31, v52
	v_or_b32_e32 v88, s34, v3
	v_or_b32_e32 v86, s35, v52
	v_mad_i64_i32 v[62:63], s[16:17], v62, s33, v[50:51]
	v_mad_i64_i32 v[64:65], s[16:17], v53, s33, v[50:51]
	v_mad_i64_i32 v[66:67], s[16:17], v66, s33, v[50:51]
	v_mad_i64_i32 v[68:69], s[16:17], v68, s33, v[50:51]
	v_mad_i64_i32 v[70:71], s[16:17], v70, s33, v[50:51]
	v_mad_i64_i32 v[72:73], s[16:17], v72, s33, v[50:51]
	v_mad_i64_i32 v[74:75], s[16:17], v74, s33, v[50:51]
	v_mad_i64_i32 v[76:77], s[16:17], v76, s33, v[50:51]
	v_mad_i64_i32 v[78:79], s[16:17], v78, s33, v[50:51]
	v_mad_i64_i32 v[80:81], s[16:17], v80, s33, v[50:51]
	v_mad_i64_i32 v[82:83], s[16:17], v82, s33, v[50:51]
	v_mad_i64_i32 v[84:85], s[16:17], v84, s33, v[50:51]
	v_mad_i64_i32 v[86:87], s[16:17], v86, s33, v[50:51]
	v_mad_i64_i32 v[88:89], s[16:17], v88, s33, v[50:51]
	global_load_dword v53, v[58:59], off
	global_load_dword v90, v[60:61], off
	global_load_dword v91, v[62:63], off
	global_load_dword v92, v[64:65], off
	global_load_dword v93, v[66:67], off
	global_load_dword v94, v[68:69], off
	global_load_dword v95, v[70:71], off
	global_load_dword v96, v[72:73], off
	global_load_dword v97, v[74:75], off
	global_load_dword v98, v[76:77], off
	global_load_dword v99, v[78:79], off
	global_load_dword v100, v[80:81], off
	global_load_dword v101, v[82:83], off
	global_load_dword v102, v[84:85], off
	global_load_dword v103, v[86:87], off
	global_load_dword v104, v[88:89], off
	v_or_b32_e32 v60, s18, v1
	v_or_b32_e32 v58, s19, v2
	s_add_i32 s7, s7, 16
	s_add_i32 s3, s3, 16
	s_add_i32 s9, s9, -16
	v_mad_u64_u32 v[58:59], s[16:17], v58, s63, v[4:5]
	v_mad_u64_u32 v[60:61], s[16:17], v60, s63, v[4:5]
	v_or_b32_e32 v59, s20, v1
	v_or_b32_e32 v61, s21, v2
	v_or_b32_e32 v68, s22, v1
	v_or_b32_e32 v66, s23, v2
	v_or_b32_e32 v72, s24, v1
	v_or_b32_e32 v70, s25, v2
	v_or_b32_e32 v76, s26, v1
	v_or_b32_e32 v74, s27, v2
	v_or_b32_e32 v80, s28, v1
	v_or_b32_e32 v78, s29, v2
	v_or_b32_e32 v84, s30, v1
	v_or_b32_e32 v82, s31, v2
	v_or_b32_e32 v88, s34, v1
	v_or_b32_e32 v86, s35, v2
	s_cmp_lg_u32 s9, 0
	v_mad_u64_u32 v[62:63], s[16:17], v61, s63, v[4:5]
	v_mad_u64_u32 v[64:65], s[16:17], v59, s63, v[4:5]
	v_mad_u64_u32 v[66:67], s[16:17], v66, s63, v[4:5]
	v_mad_u64_u32 v[68:69], s[16:17], v68, s63, v[4:5]
	v_mad_u64_u32 v[70:71], s[16:17], v70, s63, v[4:5]
	v_mad_u64_u32 v[72:73], s[16:17], v72, s63, v[4:5]
	v_mad_u64_u32 v[74:75], s[16:17], v74, s63, v[4:5]
	v_mad_u64_u32 v[76:77], s[16:17], v76, s63, v[4:5]
	v_mad_u64_u32 v[78:79], s[16:17], v78, s63, v[4:5]
	v_mad_u64_u32 v[80:81], s[16:17], v80, s63, v[4:5]
	v_mad_u64_u32 v[82:83], s[16:17], v82, s63, v[4:5]
	v_mad_u64_u32 v[84:85], s[16:17], v84, s63, v[4:5]
	v_mad_u64_u32 v[86:87], s[16:17], v86, s63, v[4:5]
	v_mad_u64_u32 v[88:89], s[16:17], v88, s63, v[4:5]
	s_waitcnt vmcnt(0)
	ds_write_b32 v58, v53
	ds_write_b32 v60, v90
	ds_write_b32 v62, v91
	ds_write_b32 v64, v92
	ds_write_b32 v66, v93
	ds_write_b32 v68, v94
	ds_write_b32 v70, v95
	ds_write_b32 v72, v96
	ds_write_b32 v74, v97
	ds_write_b32 v76, v98
	ds_write_b32 v78, v99
	ds_write_b32 v80, v100
	ds_write_b32 v82, v101
	ds_write_b32 v84, v102
	ds_write_b32 v86, v103
	ds_write_b32 v88, v104
	s_cbranch_scc1 .LBB0_73
; #define LAS __attribute__((address_space(3)))
; __device__ __forceinline__ unsigned pk2(float lo, float hi) { return f2bf(lo) | (f2bf(hi) << 16); }
; template <bool FFN_PERM = false>
; __device__ __forceinline__ void transpose_item(const float* W, int ldw, int K, bf16_t* WT, int nblk, int item, LAS float* scr, int lane) {
;     ...
;     const int d0 = FFN_PERM ? ((n0 < DFF) ? ((n0 >> 7) * 256 + (n0 & 127)) : ((((n0 - DFF) >> 7) * 256) + 128 + ((n0 - DFF) & 127))) : n0;
;     ...
;     const int c = lane & 7;
; #pragma unroll
;     for (int j = 0; j < 4; ++j) { const int n = (lane >> 3) + 8 * j; const LAS float* s = scr + (8 * c) * 33 + n;
;         u32x4 o; o.x = pk2(s[0 * 33], s[1 * 33]); o.y = pk2(s[2 * 33], s[3 * 33]); o.z = pk2(s[4 * 33], s[5 * 33]); o.w = pk2(s[6 * 33], s[7 * 33]);
;         *(u32x4*)(WT + (size_t)(d0 + n) * K + k0 + 8 * c) = o; }
;     asm volatile("s_waitcnt lgkmcnt(0)" ::: "memory");
	s_waitcnt lgkmcnt(0)
	ds_read_b32 v3, v54
	ds_read_b32 v50, v54 offset:132
	ds_read_b32 v51, v54 offset:264
	ds_read_b32 v52, v54 offset:396
	ds_read_b32 v53, v54 offset:528
	ds_read_b32 v60, v54 offset:660
	ds_read_b32 v61, v54 offset:792
	ds_read_b32 v62, v54 offset:924
	s_waitcnt lgkmcnt(0)
	v_bfe_u32 v63, v3, 16, 1
	v_add3_u32 v3, v3, v63, s60
	v_bfe_u32 v63, v50, 16, 1
	v_lshrrev_b32_e32 v3, 16, v3
	v_add3_u32 v50, v50, v63, s60
	v_and_or_b32 v50, v50, s61, v3
	v_bfe_u32 v3, v51, 16, 1
	v_add3_u32 v3, v51, v3, s60
	v_bfe_u32 v51, v52, 16, 1
	v_lshrrev_b32_e32 v3, 16, v3
	v_add3_u32 v51, v52, v51, s60
	v_and_or_b32 v51, v51, s61, v3
	v_bfe_u32 v3, v53, 16, 1
	v_add3_u32 v3, v53, v3, s60
	v_bfe_u32 v52, v60, 16, 1
	v_lshrrev_b32_e32 v3, 16, v3
	v_add3_u32 v52, v60, v52, s60
	v_and_or_b32 v52, v52, s61, v3
	v_bfe_u32 v3, v61, 16, 1
	v_or_b32_e32 v60, s6, v7
	s_ashr_i32 s9, s8, 31
	v_add3_u32 v3, v61, v3, s60
	v_bfe_u32 v53, v62, 16, 1
	v_ashrrev_i32_e32 v61, 31, v60
	v_lshl_add_u64 v[58:59], s[8:9], 1, v[22:23]
	v_lshrrev_b32_e32 v3, 16, v3
	v_add3_u32 v53, v62, v53, s60
	v_lshlrev_b64 v[60:61], 11, v[60:61]
	v_and_or_b32 v53, v53, s61, v3
	v_lshl_add_u64 v[60:61], v[58:59], 0, v[60:61]
	global_store_dwordx4 v[60:61], v[50:53], off
	ds_read_b32 v3, v54 offset:32
	ds_read_b32 v50, v54 offset:164
	ds_read_b32 v51, v54 offset:296
	ds_read_b32 v52, v54 offset:428
	ds_read_b32 v53, v54 offset:560
	ds_read_b32 v60, v54 offset:692
	ds_read_b32 v61, v54 offset:824
	ds_read_b32 v62, v54 offset:956
	s_waitcnt lgkmcnt(0)
	v_bfe_u32 v63, v3, 16, 1
	v_add3_u32 v3, v3, v63, s60
	v_bfe_u32 v63, v50, 16, 1
	v_lshrrev_b32_e32 v3, 16, v3
	v_add3_u32 v50, v50, v63, s60
	v_and_or_b32 v50, v50, s61, v3
	v_bfe_u32 v3, v51, 16, 1
	v_add3_u32 v3, v51, v3, s60
	v_bfe_u32 v51, v52, 16, 1
	v_lshrrev_b32_e32 v3, 16, v3
	v_add3_u32 v51, v52, v51, s60
	v_and_or_b32 v51, v51, s61, v3
	v_bfe_u32 v3, v53, 16, 1
	v_add3_u32 v3, v53, v3, s60
	v_bfe_u32 v52, v60, 16, 1
	v_lshrrev_b32_e32 v3, 16, v3
	v_add3_u32 v52, v60, v52, s60
	v_and_or_b32 v52, v52, s61, v3
	v_bfe_u32 v3, v61, 16, 1
	v_or_b32_e32 v60, s6, v55
	v_add3_u32 v3, v61, v3, s60
	v_bfe_u32 v53, v62, 16, 1
	v_ashrrev_i32_e32 v61, 31, v60
	v_lshrrev_b32_e32 v3, 16, v3
	v_add3_u32 v53, v62, v53, s60
	v_lshlrev_b64 v[60:61], 11, v[60:61]
	v_and_or_b32 v53, v53, s61, v3
	v_lshl_add_u64 v[60:61], v[58:59], 0, v[60:61]
	global_store_dwordx4 v[60:61], v[50:53], off
	ds_read_b32 v3, v54 offset:64
	ds_read_b32 v50, v54 offset:196
	ds_read_b32 v51, v54 offset:328
	ds_read_b32 v52, v54 offset:460
	ds_read_b32 v53, v54 offset:592
	ds_read_b32 v60, v54 offset:724
	ds_read_b32 v61, v54 offset:856
	ds_read_b32 v62, v54 offset:988
	s_waitcnt lgkmcnt(0)
	v_bfe_u32 v63, v3, 16, 1
	v_add3_u32 v3, v3, v63, s60
	v_bfe_u32 v63, v50, 16, 1
	v_lshrrev_b32_e32 v3, 16, v3
	v_add3_u32 v50, v50, v63, s60
	v_and_or_b32 v50, v50, s61, v3
	v_bfe_u32 v3, v51, 16, 1
	v_add3_u32 v3, v51, v3, s60
	v_bfe_u32 v51, v52, 16, 1
	v_lshrrev_b32_e32 v3, 16, v3
	v_add3_u32 v51, v52, v51, s60
	v_and_or_b32 v51, v51, s61, v3
	v_bfe_u32 v3, v53, 16, 1
	v_add3_u32 v3, v53, v3, s60
	v_bfe_u32 v52, v60, 16, 1
	v_lshrrev_b32_e32 v3, 16, v3
	v_add3_u32 v52, v60, v52, s60
	v_and_or_b32 v52, v52, s61, v3
	v_bfe_u32 v3, v61, 16, 1
	v_or_b32_e32 v60, s6, v56
	v_add3_u32 v3, v61, v3, s60
	v_bfe_u32 v53, v62, 16, 1
	v_ashrrev_i32_e32 v61, 31, v60
	v_lshrrev_b32_e32 v3, 16, v3
	v_add3_u32 v53, v62, v53, s60
	v_lshlrev_b64 v[60:61], 11, v[60:61]
	v_and_or_b32 v53, v53, s61, v3
	v_lshl_add_u64 v[60:61], v[58:59], 0, v[60:61]
	global_store_dwordx4 v[60:61], v[50:53], off
	ds_read_b32 v3, v54 offset:96
	ds_read_b32 v50, v54 offset:228
	ds_read_b32 v51, v54 offset:360
	ds_read_b32 v52, v54 offset:492
	ds_read_b32 v53, v54 offset:624
	ds_read_b32 v60, v54 offset:756
	ds_read_b32 v61, v54 offset:888
	ds_read_b32 v62, v54 offset:1020
	s_waitcnt lgkmcnt(0)
	v_bfe_u32 v63, v3, 16, 1
	v_add3_u32 v3, v3, v63, s60
	v_bfe_u32 v63, v50, 16, 1
	v_lshrrev_b32_e32 v3, 16, v3
	v_add3_u32 v50, v50, v63, s60
	v_and_or_b32 v50, v50, s61, v3
	v_bfe_u32 v3, v51, 16, 1
	v_add3_u32 v3, v51, v3, s60
	v_bfe_u32 v51, v52, 16, 1
	v_lshrrev_b32_e32 v3, 16, v3
	v_add3_u32 v51, v52, v51, s60
	v_and_or_b32 v51, v51, s61, v3
	v_bfe_u32 v3, v53, 16, 1
	v_add3_u32 v3, v53, v3, s60
	v_bfe_u32 v52, v60, 16, 1
	v_lshrrev_b32_e32 v3, 16, v3
	v_add3_u32 v52, v60, v52, s60
	v_and_or_b32 v52, v52, s61, v3
	v_bfe_u32 v3, v61, 16, 1
	v_or_b32_e32 v60, s6, v57
	v_add3_u32 v3, v61, v3, s60
	v_bfe_u32 v53, v62, 16, 1
	v_ashrrev_i32_e32 v61, 31, v60
	v_lshrrev_b32_e32 v3, 16, v3
	v_add3_u32 v53, v62, v53, s60
	v_lshlrev_b64 v[60:61], 11, v[60:61]
	v_and_or_b32 v53, v53, s61, v3
	v_lshl_add_u64 v[58:59], v[58:59], 0, v[60:61]
	global_store_dwordx4 v[58:59], v[50:53], off
	s_waitcnt lgkmcnt(0)
	s_branch .LBB0_14

; __device__ __forceinline__ float fast_exp2(float x) { return __builtin_amdgcn_exp2f(x); }
; __device__ __forceinline__ float log1p_small(float e) { return e < 0.01f ? e * (1.0f - e * (0.5f - e * 0.33333334f)) : fast_log2(1.0f + e) * 0.6931471806f; }
; template <class T> __device__ __forceinline__ T* launder_ptr(T* p) { asm volatile("" : "+s"(p)); return p; }
; template <bool WITH_F>
; __device__ __forceinline__ void rmsnorm_rows(const float* x, const float* g, bf16_t* hout, const Params& P, int l, LAS unsigned char* lds, int gw, int NGW, int lane) {
;     ...
;             if (lane < 8) { const float z = mine * rstd + bfv; const float lf = -(fmaxf(-z, 0.f) + log1p_small(fast_exp2(-fabsf(z) * LOG2E)));
;                 ((float*)(launder_ptr(P.ws) + WS_LOGF))[(size_t)m * 8 + lane] = lf; }
.LBB0_89:
	s_or_b64 exec, exec, s[22:23]
	v_max_f32_e64 v18, -v18, -v18
	v_max_f32_e32 v18, 0, v18
	v_add_f32_e32 v18, v18, v19
	s_mov_b64 s[22:23], s[94:95]
	v_xor_b32_e32 v20, 0x80000000, v18
	s_nop 0
	v_lshl_add_u64 v[18:19], s[22:23], 0, v[34:35]
	global_store_dword v[18:19], v20, off

; __device__ __forceinline__ unsigned pk2(float lo, float hi) { return f2bf(lo) | (f2bf(hi) << 16); }
; __device__ __forceinline__ float fast_rsq(float x) { return __builtin_amdgcn_rsqf(x); }
; template <bool WITH_F>
; __device__ __forceinline__ void rmsnorm_rows(const float* x, const float* g, bf16_t* hout, const Params& P, int l, LAS unsigned char* lds, int gw, int NGW, int lane) {
;     ...
;     for (int m = gw; m < MTOK; m += NGW) {
;         const f32x4* xr = (const f32x4*)(x + (size_t)m * DM) + lane;
;         f32x4 v[4]; float ss = 0.f;
; #pragma unroll
;         for (int j = 0; j < 4; ++j) { v[j] = xr[64 * j]; ss += (v[j].x * v[j].x + v[j].y * v[j].y) + (v[j].z * v[j].z + v[j].w * v[j].w); }
;         const float rstd = fast_rsq(wave_sum(ss) * (1.0f / DM) + EPS);
;         unsigned long long* o8 = (unsigned long long*)(hout + (size_t)m * DM) + lane;
; #pragma unroll
;         for (int j = 0; j < 4; ++j) { const f32x4 hv = v[j] * rstd * gv[j];
;             o8[64 * j] = (unsigned long long)pk2(hv.x, hv.y) | ((unsigned long long)pk2(hv.z, hv.w) << 32); }
;         if (WITH_F) {
;             float a[8];
; #pragma unroll
;             for (int q = 0; q < 8; ++q) a[q] = 0.f;
; #pragma unroll
;             for (int j = 0; j < 4; ++j)
; #pragma unroll
;                 for (int e = 0; e < 4; ++e) { const f32x4 w0 = wf[((j * 4 + e) * 2 + 0) * 64 + lane], w1 = wf[((j * 4 + e) * 2 + 1) * 64 + lane]; const float xv = v[j][e];
;                     a[0] += xv * w0.x; a[1] += xv * w0.y; a[2] += xv * w0.z; a[3] += xv * w0.w; a[4] += xv * w1.x; a[5] += xv * w1.y; a[6] += xv * w1.z; a[7] += xv * w1.w; }
.LBB0_91:
	s_waitcnt lgkmcnt(0)
	global_load_dwordx4 v[30:33], v[38:39], off
	global_load_dwordx4 v[26:29], v[38:39], off offset:1024
	global_load_dwordx4 v[18:21], v[38:39], off offset:3072
	global_load_dwordx4 v[22:25], v[38:39], off offset:2048
	s_waitcnt vmcnt(0) lgkmcnt(0)
	v_pk_mul_f32 v[48:49], v[32:33], v[32:33]
	v_pk_mul_f32 v[50:51], v[30:31], v[30:31]
	v_pk_mul_f32 v[52:53], v[28:29], v[28:29]
	v_pk_mul_f32 v[54:55], v[26:27], v[26:27]
	v_pk_mov_b32 v[58:59], v[50:51], v[48:49] op_sel:[1,0]
	v_mov_b32_e32 v51, v49
	v_pk_mov_b32 v[48:49], v[54:55], v[52:53] op_sel:[1,0]
	v_mov_b32_e32 v55, v53
	v_mul_f32_e32 v40, v23, v23
	v_mul_f32_e32 v56, v25, v25
	v_pk_add_f32 v[50:51], v[58:59], v[50:51]
	v_pk_add_f32 v[48:49], v[48:49], v[54:55]
	v_mul_f32_e32 v60, v18, v18
	v_mul_f32_e32 v61, v19, v19
	v_mul_f32_e32 v62, v20, v20
	v_mul_f32_e32 v63, v21, v21
	v_pk_fma_f32 v[52:53], v[22:23], v[22:23], v[40:41] op_sel_hi:[1,1,0]
	v_pk_fma_f32 v[56:57], v[24:25], v[24:25], v[56:57] op_sel_hi:[1,1,0]
	v_pk_add_f32 v[50:51], v[50:51], v[50:51] op_sel:[0,1] op_sel_hi:[1,0]
	v_pk_add_f32 v[48:49], v[48:49], v[48:49] op_sel:[0,1] op_sel_hi:[1,0]
	v_mov_b32_e32 v53, v62
	v_mov_b32_e32 v57, v63
	v_mov_b32_e32 v51, v60
	v_mov_b32_e32 v49, v61
	v_pk_add_f32 v[52:53], v[52:53], v[56:57]
	v_pk_add_f32 v[48:49], v[50:51], v[48:49]
	s_nop 0
	v_pk_add_f32 v[48:49], v[48:49], v[52:53]
	s_nop 0
	v_add_f32_e32 v40, v48, v49
	ds_bpermute_b32 v48, v41, v40
	s_waitcnt lgkmcnt(0)
	v_add_f32_e32 v40, v40, v48
	ds_bpermute_b32 v48, v42, v40
	s_waitcnt lgkmcnt(0)
	v_add_f32_e32 v40, v40, v48
	ds_bpermute_b32 v48, v43, v40
	s_waitcnt lgkmcnt(0)
	v_add_f32_e32 v40, v40, v48
	ds_bpermute_b32 v48, v44, v40
	s_waitcnt lgkmcnt(0)
	v_add_f32_e32 v40, v40, v48
	ds_bpermute_b32 v48, v45, v40
	s_waitcnt lgkmcnt(0)
	v_add_f32_e32 v40, v40, v48
	ds_bpermute_b32 v48, v46, v40
	s_waitcnt lgkmcnt(0)
	v_add_f32_e32 v40, v40, v48
	v_fmamk_f32 v40, v40, 0x3a800000, v216
	v_rsq_f32_e32 v40, v40
	s_nop 0
	v_pk_mul_f32 v[48:49], v[30:31], v[40:41] op_sel_hi:[1,0]
	v_pk_mul_f32 v[50:51], v[32:33], v[40:41] op_sel_hi:[1,0]
	v_pk_mul_f32 v[52:53], v[26:27], v[40:41] op_sel_hi:[1,0]
	v_pk_mul_f32 v[54:55], v[28:29], v[40:41] op_sel_hi:[1,0]
	v_pk_mul_f32 v[56:57], v[22:23], v[40:41] op_sel_hi:[1,0]
	v_pk_mul_f32 v[58:59], v[24:25], v[40:41] op_sel_hi:[1,0]
	v_pk_mul_f32 v[60:61], v[18:19], v[40:41] op_sel_hi:[1,0]
	v_pk_mul_f32 v[62:63], v[20:21], v[40:41] op_sel_hi:[1,0]
	v_pk_mul_f32 v[50:51], v[4:5], v[50:51]
	v_pk_mul_f32 v[48:49], v[2:3], v[48:49]
	v_pk_mul_f32 v[54:55], v[8:9], v[54:55]
	v_pk_mul_f32 v[52:53], v[6:7], v[52:53]
	v_pk_mul_f32 v[58:59], v[12:13], v[58:59]
	v_pk_mul_f32 v[56:57], v[10:11], v[56:57]
	v_pk_mul_f32 v[62:63], v[16:17], v[62:63]
	v_pk_mul_f32 v[60:61], v[14:15], v[60:61]
	v_bfe_u32 v64, v48, 16, 1
	v_bfe_u32 v66, v50, 16, 1
	v_bfe_u32 v65, v49, 16, 1
	v_bfe_u32 v67, v51, 16, 1
	v_bfe_u32 v68, v52, 16, 1
	v_bfe_u32 v70, v54, 16, 1
	v_bfe_u32 v72, v56, 16, 1
	v_bfe_u32 v74, v58, 16, 1
	v_bfe_u32 v76, v60, 16, 1
	v_bfe_u32 v78, v62, 16, 1
	v_add3_u32 v48, v48, v64, s60
	v_add3_u32 v50, v50, v66, s60
	v_bfe_u32 v69, v53, 16, 1
	v_bfe_u32 v71, v55, 16, 1
	v_bfe_u32 v73, v57, 16, 1
	v_bfe_u32 v75, v59, 16, 1
	v_bfe_u32 v77, v61, 16, 1
	v_bfe_u32 v79, v63, 16, 1
	v_add3_u32 v49, v49, v65, s60
	v_add3_u32 v51, v51, v67, s60
	v_add3_u32 v52, v52, v68, s60
	v_add3_u32 v54, v54, v70, s60
	v_add3_u32 v56, v56, v72, s60
	v_add3_u32 v58, v58, v74, s60
	v_add3_u32 v60, v60, v76, s60
	v_add3_u32 v62, v62, v78, s60
	v_lshrrev_b32_e32 v48, 16, v48
	v_lshrrev_b32_e32 v50, 16, v50
	v_add3_u32 v53, v53, v69, s60
	v_add3_u32 v55, v55, v71, s60
	v_add3_u32 v57, v57, v73, s60
	v_add3_u32 v59, v59, v75, s60
	v_add3_u32 v61, v61, v77, s60
	v_add3_u32 v63, v63, v79, s60
	v_lshrrev_b32_e32 v52, 16, v52
	v_lshrrev_b32_e32 v54, 16, v54
	v_lshrrev_b32_e32 v56, 16, v56
	v_lshrrev_b32_e32 v58, 16, v58
	v_lshrrev_b32_e32 v60, 16, v60
	v_lshrrev_b32_e32 v62, 16, v62
	v_and_or_b32 v48, v49, s61, v48
	v_and_or_b32 v49, v51, s61, v50
	v_and_or_b32 v50, v53, s61, v52
	v_and_or_b32 v51, v55, s61, v54
	v_and_or_b32 v52, v57, s61, v56
	v_and_or_b32 v53, v59, s61, v58
	v_and_or_b32 v54, v61, s61, v60
	v_and_or_b32 v55, v63, s61, v62
	global_store_dwordx2 v[36:37], v[48:49], off
	global_store_dwordx2 v[36:37], v[50:51], off offset:512
	global_store_dwordx2 v[36:37], v[52:53], off offset:1024
	global_store_dwordx2 v[36:37], v[54:55], off offset:1536
	ds_read_b128 v[48:51], v47
	ds_read_b128 v[52:55], v47 offset:1024
	ds_read_b128 v[56:59], v47 offset:2048
	ds_read_b128 v[60:63], v47 offset:3072
	ds_read_b128 v[64:67], v47 offset:4096
	ds_read_b128 v[68:71], v47 offset:5120
	ds_read_b128 v[72:75], v47 offset:6144
	s_waitcnt lgkmcnt(0)
	v_fma_f32 v76, v30, v48, 0
	v_fma_f32 v77, v30, v49, 0
	v_fma_f32 v78, v30, v50, 0
	v_fma_f32 v79, v30, v51, 0
	ds_read_b128 v[48:51], v47 offset:7168
	v_fma_f32 v80, v30, v52, 0
	v_fma_f32 v81, v30, v53, 0
	v_fma_f32 v82, v30, v54, 0
	v_fma_f32 v83, v30, v55, 0
	v_fmac_f32_e32 v76, v31, v56
	v_fmac_f32_e32 v77, v31, v57
	v_fmac_f32_e32 v78, v31, v58
	v_fmac_f32_e32 v79, v31, v59
	v_fmac_f32_e32 v80, v31, v60
	v_fmac_f32_e32 v81, v31, v61
	v_fmac_f32_e32 v82, v31, v62
	v_fmac_f32_e32 v83, v31, v63
	v_fmac_f32_e32 v76, v32, v64
	v_fmac_f32_e32 v77, v32, v65
	v_fmac_f32_e32 v78, v32, v66
	v_fmac_f32_e32 v79, v32, v67
	v_fmac_f32_e32 v80, v32, v68
	v_fmac_f32_e32 v81, v32, v69
	v_fmac_f32_e32 v82, v32, v70
	v_fmac_f32_e32 v83, v32, v71
	v_fmac_f32_e32 v76, v33, v72
	v_fmac_f32_e32 v77, v33, v73
	v_fmac_f32_e32 v78, v33, v74
	v_fmac_f32_e32 v79, v33, v75
	ds_read_b128 v[52:55], v47 offset:8192
	s_waitcnt lgkmcnt(0)
; template <bool WITH_F>
; __device__ __forceinline__ void rmsnorm_rows(const float* x, const float* g, bf16_t* hout, const Params& P, int l, LAS unsigned char* lds, int gw, int NGW, int lane) {
;     ...
;             for (int j = 0; j < 4; ++j)
; #pragma unroll
;                 for (int e = 0; e < 4; ++e) { const f32x4 w0 = wf[((j * 4 + e) * 2 + 0) * 64 + lane], w1 = wf[((j * 4 + e) * 2 + 1) * 64 + lane]; const float xv = v[j][e];
;                     a[0] += xv * w0.x; a[1] += xv * w0.y; a[2] += xv * w0.z; a[3] += xv * w0.w; a[4] += xv * w1.x; a[5] += xv * w1.y; a[6] += xv * w1.z; a[7] += xv * w1.w; }
	v_fmac_f32_e32 v80, v33, v48
	v_fmac_f32_e32 v81, v33, v49
	v_fmac_f32_e32 v82, v33, v50
	v_fmac_f32_e32 v83, v33, v51
	ds_read_b128 v[30:33], v47 offset:9216
	ds_read_b128 v[48:51], v47 offset:10240
	v_fmac_f32_e32 v76, v26, v52
	v_fmac_f32_e32 v77, v26, v53
	v_fmac_f32_e32 v78, v26, v54
	s_waitcnt lgkmcnt(0)
	v_fmac_f32_e32 v80, v26, v30
	v_fmac_f32_e32 v81, v26, v31
	v_fmac_f32_e32 v82, v26, v32
	v_fmac_f32_e32 v83, v26, v33
	ds_read_b128 v[30:33], v47 offset:11264
	v_fmac_f32_e32 v79, v26, v55
	v_fmac_f32_e32 v76, v27, v48
	v_fmac_f32_e32 v77, v27, v49
	v_fmac_f32_e32 v78, v27, v50
	v_fmac_f32_e32 v79, v27, v51
	ds_read_b128 v[48:51], v47 offset:12288
	s_waitcnt lgkmcnt(0)
	v_fmac_f32_e32 v80, v27, v30
	v_fmac_f32_e32 v81, v27, v31
	v_fmac_f32_e32 v82, v27, v32
	v_fmac_f32_e32 v83, v27, v33
	ds_read_b128 v[30:33], v47 offset:13312
	v_fmac_f32_e32 v76, v28, v48
	v_fmac_f32_e32 v77, v28, v49
	v_fmac_f32_e32 v78, v28, v50
	v_fmac_f32_e32 v79, v28, v51
	ds_read_b128 v[48:51], v47 offset:14336
	s_waitcnt lgkmcnt(0)
	v_fmac_f32_e32 v80, v28, v30
	v_fmac_f32_e32 v81, v28, v31
	v_fmac_f32_e32 v82, v28, v32
	v_fmac_f32_e32 v83, v28, v33
	ds_read_b128 v[30:33], v47 offset:15360
	v_fmac_f32_e32 v76, v29, v48
	v_fmac_f32_e32 v77, v29, v49
	v_fmac_f32_e32 v78, v29, v50
	v_fmac_f32_e32 v79, v29, v51
	ds_read_b128 v[48:51], v47 offset:16384
	s_waitcnt lgkmcnt(0)
	v_fmac_f32_e32 v80, v29, v30
	v_fmac_f32_e32 v81, v29, v31
	v_fmac_f32_e32 v82, v29, v32
	v_fmac_f32_e32 v83, v29, v33
	ds_read_b128 v[26:29], v47 offset:17408
	ds_read_b128 v[30:33], v47 offset:18432
	v_fmac_f32_e32 v76, v22, v48
	v_fmac_f32_e32 v77, v22, v49
	v_fmac_f32_e32 v78, v22, v50
	s_waitcnt lgkmcnt(0)
	v_fmac_f32_e32 v80, v22, v26
	v_fmac_f32_e32 v81, v22, v27
	v_fmac_f32_e32 v82, v22, v28
	v_fmac_f32_e32 v83, v22, v29
	ds_read_b128 v[26:29], v47 offset:19456
	v_fmac_f32_e32 v79, v22, v51
	v_fmac_f32_e32 v76, v23, v30
	v_fmac_f32_e32 v77, v23, v31
	v_fmac_f32_e32 v78, v23, v32
	v_fmac_f32_e32 v79, v23, v33
	ds_read_b128 v[30:33], v47 offset:20480
	s_waitcnt lgkmcnt(0)
	v_fmac_f32_e32 v80, v23, v26
	v_fmac_f32_e32 v81, v23, v27
	v_fmac_f32_e32 v82, v23, v28
	v_fmac_f32_e32 v83, v23, v29
	ds_read_b128 v[26:29], v47 offset:21504
	v_fmac_f32_e32 v76, v24, v30
	v_fmac_f32_e32 v77, v24, v31
	v_fmac_f32_e32 v78, v24, v32
	v_fmac_f32_e32 v79, v24, v33
	ds_read_b128 v[30:33], v47 offset:22528
	s_waitcnt lgkmcnt(0)
	v_fmac_f32_e32 v80, v24, v26
	v_fmac_f32_e32 v81, v24, v27
	v_fmac_f32_e32 v82, v24, v28
	v_fmac_f32_e32 v83, v24, v29
	ds_read_b128 v[26:29], v47 offset:23552
	v_fmac_f32_e32 v76, v25, v30
	v_fmac_f32_e32 v77, v25, v31
	v_fmac_f32_e32 v78, v25, v32
	v_fmac_f32_e32 v79, v25, v33
	ds_read_b128 v[30:33], v47 offset:24576
	s_waitcnt lgkmcnt(0)
	v_fmac_f32_e32 v80, v25, v26
	v_fmac_f32_e32 v81, v25, v27
	v_fmac_f32_e32 v82, v25, v28
	v_fmac_f32_e32 v83, v25, v29
	ds_read_b128 v[22:25], v47 offset:25600
	ds_read_b128 v[26:29], v47 offset:26624
	v_fmac_f32_e32 v76, v18, v30
	v_fmac_f32_e32 v77, v18, v31
	v_fmac_f32_e32 v78, v18, v32
	s_waitcnt lgkmcnt(0)
	v_fmac_f32_e32 v80, v18, v22
	v_fmac_f32_e32 v81, v18, v23
	v_fmac_f32_e32 v82, v18, v24
	v_fmac_f32_e32 v83, v18, v25
	ds_read_b128 v[22:25], v47 offset:27648
	v_fmac_f32_e32 v79, v18, v33
	v_fmac_f32_e32 v76, v19, v26
	v_fmac_f32_e32 v77, v19, v27
	v_fmac_f32_e32 v78, v19, v28
	v_fmac_f32_e32 v79, v19, v29
	ds_read_b128 v[26:29], v47 offset:28672
	s_waitcnt lgkmcnt(0)
	v_fmac_f32_e32 v80, v19, v22
	v_fmac_f32_e32 v81, v19, v23
	v_fmac_f32_e32 v82, v19, v24
	v_fmac_f32_e32 v83, v19, v25
	ds_read_b128 v[22:25], v47 offset:29696
	ds_read_b128 v[30:33], v47 offset:30720
	v_fmac_f32_e32 v77, v20, v27
	v_fmac_f32_e32 v76, v20, v26
	v_fmac_f32_e32 v78, v20, v28
	v_fmac_f32_e32 v79, v20, v29
	s_waitcnt lgkmcnt(0)
	v_fmac_f32_e32 v77, v21, v31
	v_fmac_f32_e32 v80, v20, v22
	v_fmac_f32_e32 v81, v20, v23
	v_fmac_f32_e32 v82, v20, v24
	v_fmac_f32_e32 v83, v20, v25
	ds_bpermute_b32 v20, v41, v77
	ds_read_b128 v[26:29], v47 offset:31744
	v_fmac_f32_e32 v78, v21, v32
	v_fmac_f32_e32 v76, v21, v30
	v_fmac_f32_e32 v79, v21, v33
	s_waitcnt lgkmcnt(0)
; __device__ __forceinline__ float fast_exp2(float x) { return __builtin_amdgcn_exp2f(x); }
; __device__ __forceinline__ float fast_log2(float x) { return __builtin_amdgcn_logf(x); }
; __device__ __forceinline__ float log1p_small(float e) { return e < 0.01f ? e * (1.0f - e * (0.5f - e * 0.33333334f)) : fast_log2(1.0f + e) * 0.6931471806f; }
; template <bool WITH_F>
; __device__ __forceinline__ void rmsnorm_rows(const float* x, const float* g, bf16_t* hout, const Params& P, int l, LAS unsigned char* lds, int gw, int NGW, int lane) {
;     ...
;             float mine = 0.f;
; #pragma unroll
;             for (int q = 0; q < 8; ++q) { const float s = wave_sum(a[q]); if ((lane & 7) == q) mine = s; }
;             if (lane < 8) { const float z = mine * rstd + bfv; const float lf = -(fmaxf(-z, 0.f) + log1p_small(fast_exp2(-fabsf(z) * LOG2E)));
	v_add_f32_e32 v20, v77, v20
	ds_bpermute_b32 v22, v42, v20
	v_fmac_f32_e32 v80, v21, v26
	v_fmac_f32_e32 v81, v21, v27
	v_fmac_f32_e32 v82, v21, v28
	v_fmac_f32_e32 v83, v21, v29
	s_waitcnt lgkmcnt(0)
	v_add_f32_e32 v20, v20, v22
	ds_bpermute_b32 v21, v41, v78
	ds_bpermute_b32 v22, v43, v20
	ds_bpermute_b32 v24, v41, v80
	ds_bpermute_b32 v18, v41, v76
	ds_bpermute_b32 v30, v41, v83
	s_waitcnt lgkmcnt(0)
	v_add_f32_e32 v21, v78, v21
	v_add_f32_e32 v20, v20, v22
	ds_bpermute_b32 v23, v42, v21
	ds_bpermute_b32 v22, v44, v20
	v_add_f32_e32 v18, v76, v18
	v_add_f32_e32 v30, v83, v30
	ds_bpermute_b32 v19, v42, v18
	s_waitcnt lgkmcnt(0)
	v_add_f32_e32 v21, v21, v23
	v_add_f32_e32 v20, v20, v22
	ds_bpermute_b32 v22, v41, v79
	ds_bpermute_b32 v23, v43, v21
	ds_bpermute_b32 v25, v45, v20
	ds_bpermute_b32 v33, v42, v30
	v_add_f32_e32 v18, v18, v19
	s_waitcnt lgkmcnt(0)
	v_add_f32_e32 v22, v79, v22
	v_add_f32_e32 v21, v21, v23
	v_add_f32_e32 v23, v80, v24
	ds_bpermute_b32 v26, v42, v22
	ds_bpermute_b32 v24, v42, v23
	ds_bpermute_b32 v27, v44, v21
	v_add_f32_e32 v20, v20, v25
	v_add_f32_e32 v30, v30, v33
	s_waitcnt lgkmcnt(0)
	v_add_f32_e32 v22, v22, v26
	v_add_f32_e32 v23, v23, v24
	ds_bpermute_b32 v26, v43, v22
	ds_bpermute_b32 v24, v43, v23
	v_add_f32_e32 v25, v21, v27
	ds_bpermute_b32 v27, v45, v25
	ds_bpermute_b32 v19, v43, v18
	s_waitcnt lgkmcnt(0)
	v_add_f32_e32 v22, v22, v26
	v_add_f32_e32 v23, v23, v24
	ds_bpermute_b32 v26, v44, v22
	ds_bpermute_b32 v24, v44, v23
	ds_bpermute_b32 v33, v43, v30
	v_add_f32_e32 v18, v18, v19
	ds_bpermute_b32 v19, v44, v18
	s_waitcnt lgkmcnt(0)
	v_add_f32_e32 v26, v22, v26
	v_add_f32_e32 v22, v25, v27
	v_add_f32_e32 v27, v23, v24
	ds_bpermute_b32 v28, v45, v26
	ds_bpermute_b32 v29, v45, v27
	v_add_f32_e32 v30, v30, v33
	ds_bpermute_b32 v33, v44, v30
	v_add_f32_e32 v18, v18, v19
	s_waitcnt lgkmcnt(0)
	v_add_f32_e32 v24, v26, v28
	ds_bpermute_b32 v28, v41, v81
	v_add_f32_e32 v26, v27, v29
	ds_bpermute_b32 v29, v41, v82
	v_add_f32_e32 v33, v30, v33
	ds_bpermute_b32 v19, v45, v18
	s_waitcnt lgkmcnt(0)
	v_add_f32_e32 v28, v81, v28
	ds_bpermute_b32 v31, v42, v28
	v_add_f32_e32 v29, v82, v29
	ds_bpermute_b32 v32, v42, v29
	ds_bpermute_b32 v49, v45, v33
	v_add_f32_e32 v18, v18, v19
	s_waitcnt lgkmcnt(0)
	v_add_f32_e32 v28, v28, v31
	ds_bpermute_b32 v31, v43, v28
	v_add_f32_e32 v29, v29, v32
	ds_bpermute_b32 v32, v43, v29
	ds_bpermute_b32 v19, v46, v18
	ds_bpermute_b32 v21, v46, v20
	s_waitcnt lgkmcnt(0)
	v_add_f32_e32 v28, v28, v31
	ds_bpermute_b32 v31, v44, v28
	v_add_f32_e32 v29, v29, v32
	ds_bpermute_b32 v32, v44, v29
	ds_bpermute_b32 v23, v46, v22
	ds_bpermute_b32 v25, v46, v24
	s_waitcnt lgkmcnt(0)
	v_add_f32_e32 v28, v28, v31
	ds_bpermute_b32 v31, v45, v28
	v_add_f32_e32 v32, v29, v32
	ds_bpermute_b32 v48, v45, v32
	ds_bpermute_b32 v27, v46, v26
	s_waitcnt lgkmcnt(0)
	v_add_f32_e32 v28, v28, v31
	ds_bpermute_b32 v29, v46, v28
	v_add_f32_e32 v30, v32, v48
	v_add_f32_e32 v32, v33, v49
	ds_bpermute_b32 v31, v46, v30
	ds_bpermute_b32 v33, v46, v32
	s_and_saveexec_b64 s[34:35], vcc
	s_cbranch_execz .LBB0_90
	v_add_f32_e32 v18, v18, v19
	v_add_f32_e32 v20, v20, v21
	v_cndmask_b32_e64 v18, 0, v18, s[20:21]
	v_add_f32_e32 v22, v22, v23
	v_cndmask_b32_e64 v18, v18, v20, s[18:19]
	v_add_f32_e32 v24, v24, v25
	v_cndmask_b32_e64 v18, v18, v22, s[16:17]
	v_add_f32_e32 v26, v26, v27
	v_cndmask_b32_e64 v18, v18, v24, s[14:15]
	s_waitcnt lgkmcnt(0)
	v_add_f32_e32 v28, v28, v29
	v_cndmask_b32_e64 v18, v18, v26, s[12:13]
	v_add_f32_e32 v30, v30, v31
	v_cndmask_b32_e64 v18, v18, v28, s[10:11]
	v_add_f32_e32 v32, v32, v33
	v_cndmask_b32_e64 v18, v18, v30, s[8:9]
	v_cndmask_b32_e64 v18, v18, v32, s[6:7]
	v_fma_f32 v18, v40, v18, v1
	s_mov_b32 s3, 0xbfb8aa3b
	v_mul_f32_e64 v19, |v18|, s3
	v_exp_f32_e32 v20, v19
	s_mov_b32 s3, 0x3c23d70a
	v_cmp_ngt_f32_e64 s[22:23], s3, v20
	s_and_saveexec_b64 s[36:37], s[22:23]
	s_xor_b64 s[22:23], exec, s[36:37]
	v_add_f32_e32 v19, 1.0, v20
	v_log_f32_e32 v19, v19
	s_nop 0
	v_mul_f32_e32 v19, 0x3f317218, v19
	s_andn2_saveexec_b64 s[22:23], s[22:23]
	s_cbranch_execz .LBB0_89
	s_mov_b32 s3, 0xbeaaaaab
	v_fma_f32 v19, v20, s3, 0.5
	v_fma_f32 v19, -v20, v19, 1.0
	v_mul_f32_e32 v19, v20, v19
	s_branch .LBB0_89

; __device__ __forceinline__ unsigned xb_ld(unsigned* p)              { return __hip_atomic_load(p, __ATOMIC_RELAXED, __HIP_MEMORY_SCOPE_AGENT); }
; __device__ __forceinline__ void xcd_barrier_complete(unsigned* bar, unsigned x, unsigned& nloc, unsigned& nx) {
;     ...
;     for (;;) {
;         sum = 0u; cnt = 0u; mine = 0u;
; #pragma unroll
;         for (unsigned j = 0; j < 16; ++j) { const unsigned c = xb_ld(&bar[XB_XCNT(j)]); sum += c; cnt += (c > 0u) ? 1u : 0u; mine = (j == x) ? c : mine; }
;         if (sum == G) break;
;         __builtin_amdgcn_s_sleep(1);
;         if ((++sp & 255u) == 0u) { if (xb_ld(&bar[XB_TMO])) break; if (sp > XB_SPIN_CAP) { atomicAdd(&bar[XB_TMO], 1u); break; } }
.LBB0_102:
	v_mov_b64_e32 v[14:15], s[38:39]
	global_load_dword v12, v[14:15], off offset:1024 sc1
	global_load_dword v1, v[14:15], off offset:1280 sc1
	s_waitcnt lgkmcnt(0)
	global_load_dword v2, v[14:15], off offset:1536 sc1
	global_load_dword v3, v[14:15], off offset:1792 sc1
	global_load_dword v4, v[14:15], off offset:2048 sc1
	global_load_dword v5, v[14:15], off offset:2304 sc1
	global_load_dword v6, v[14:15], off offset:2560 sc1
	global_load_dword v7, v[14:15], off offset:2816 sc1
	global_load_dword v8, v[14:15], off offset:3072 sc1
	global_load_dword v9, v[14:15], off offset:3328 sc1
	global_load_dword v10, v[14:15], off offset:3584 sc1
	global_load_dword v11, v[14:15], off offset:3840 sc1
	v_mov_b64_e32 v[14:15], s[6:7]
	global_load_dword v13, v[14:15], off sc1
	v_mov_b64_e32 v[14:15], s[8:9]
	global_load_dword v14, v[14:15], off sc1
	v_mov_b64_e32 v[16:17], s[10:11]
	global_load_dword v15, v[16:17], off sc1
	v_mov_b64_e32 v[16:17], s[12:13]
	global_load_dword v16, v[16:17], off sc1
	s_or_b64 s[20:21], s[20:21], exec
	s_or_b64 s[18:19], s[18:19], exec
	s_waitcnt vmcnt(0)
	v_add_u32_e32 v17, v1, v12
	s_waitcnt lgkmcnt(0)
	v_add_u32_e32 v17, v17, v2
	v_add_u32_e32 v17, v17, v3
	v_add_u32_e32 v17, v17, v4
	v_add_u32_e32 v17, v17, v5
	v_add_u32_e32 v17, v17, v6
	v_add_u32_e32 v17, v17, v7
	v_add_u32_e32 v17, v17, v8
	v_add_u32_e32 v17, v17, v9
	v_add_u32_e32 v17, v17, v10
	v_add_u32_e32 v17, v17, v11
	v_add_u32_e32 v17, v17, v13
	v_add_u32_e32 v17, v17, v14
	v_add_u32_e32 v17, v17, v15
	v_add_u32_e32 v17, v17, v16
	v_cmp_ne_u32_e32 vcc, s59, v17
	s_and_saveexec_b64 s[22:23], vcc
	s_cbranch_execz .LBB0_101
	s_and_b32 s26, s34, 0xff
	s_mov_b64 s[24:25], -1
	s_cmp_eq_u32 s26, 0
	s_mov_b64 s[28:29], -1
	s_mov_b64 s[26:27], -1
	s_sleep 1
	s_cbranch_scc1 .LBB0_105
	s_and_saveexec_b64 s[30:31], s[28:29]
	s_cbranch_execz .LBB0_100
	s_branch .LBB0_108
.LBB0_105:
	v_mov_b64_e32 v[18:19], s[38:39]
	global_load_dword v17, v[18:19], off offset:512 sc1
	s_mov_b64 s[28:29], 0
	s_waitcnt vmcnt(0) lgkmcnt(0)
	v_cmp_eq_u32_e32 vcc, 0, v17
	s_and_saveexec_b64 s[30:31], vcc
	s_cmp_lt_u32 s34, 0x400001
	s_cselect_b64 s[28:29], -1, 0
	s_xor_b64 s[26:27], exec, -1
	s_and_b64 s[28:29], s[28:29], exec
	s_or_b64 exec, exec, s[30:31]
	s_and_saveexec_b64 s[30:31], s[28:29]
	s_cbranch_execz .LBB0_100

; __device__ __forceinline__ unsigned xb_ld(unsigned* p)              { return __hip_atomic_load(p, __ATOMIC_RELAXED, __HIP_MEMORY_SCOPE_AGENT); }
; __device__ __forceinline__ unsigned xb_add(unsigned* p, unsigned v) { return __hip_atomic_fetch_add(p, v, __ATOMIC_RELAXED, __HIP_MEMORY_SCOPE_AGENT); }
; #define XB_SPIN(cond, bar) do { unsigned _sp = 0; while (cond) { __builtin_amdgcn_s_sleep(1); \
;     if ((++_sp & 255u) == 0u) { if (xb_ld(&(bar)[XB_TMO])) break; if (_sp > XB_SPIN_CAP) { atomicAdd(&(bar)[XB_TMO], 1u); break; } } } } while (0)
; __device__ __forceinline__ void xcd_barrier(const XcdBarrier& b) {
;     ...
;         const unsigned old = xb_add(&bar[XB_XSUB(b.x)], 1u);
;         const unsigned gen = old / nloc;
;         if (old + 1u == (gen + 1u) * nloc) {
;     ...
;             XB_SPIN(xb_ld(&bar[XB_XGEN(b.x)]) == gen, bar);
.LBB0_112:
	s_lshl_b32 s5, s5, 8
	s_add_u32 s26, s38, s5
	s_addc_u32 s5, s39, 0
	v_mov_b32_e32 v1, s26
	v_add_co_u32_e32 v6, vcc, 0x1000, v1
	v_mov_b32_e32 v1, s5
	s_nop 0
	v_addc_co_u32_e32 v7, vcc, 0, v1, vcc
	flat_atomic_add v1, v[6:7], v217 offset:1024 sc0
	v_cvt_f32_u32_e32 v3, v4
	v_sub_u32_e32 v5, 0, v4
	v_rcp_iflag_f32_e32 v3, v3
	s_nop 0
	v_mul_f32_e32 v3, 0x4f7ffffe, v3
	v_cvt_u32_f32_e32 v3, v3
	v_mul_lo_u32 v5, v5, v3
	v_mul_hi_u32 v5, v3, v5
	v_add_u32_e32 v3, v3, v5
	s_waitcnt vmcnt(0) lgkmcnt(0)
	v_mul_hi_u32 v3, v1, v3
	v_mul_lo_u32 v5, v3, v4
	v_add_u32_e32 v6, 1, v1
	v_sub_u32_e32 v1, v1, v5
	v_add_u32_e32 v7, 1, v3
	v_cmp_ge_u32_e32 vcc, v1, v4
	v_sub_u32_e32 v5, v1, v4
	s_nop 0
	v_cndmask_b32_e32 v3, v3, v7, vcc
	v_cndmask_b32_e32 v1, v1, v5, vcc
	v_add_u32_e32 v5, 1, v3
	v_cmp_ge_u32_e32 vcc, v1, v4
	s_nop 1
	v_cndmask_b32_e32 v1, v3, v5, vcc
	v_mad_u64_u32 v[4:5], s[6:7], v4, v1, v[4:5]
	v_cmp_ne_u32_e32 vcc, v6, v4
	s_and_saveexec_b64 s[6:7], vcc
	s_xor_b64 s[6:7], exec, s[6:7]
	s_cbranch_execz .LBB0_125
	v_mov_b32_e32 v2, s26
	v_add_co_u32_e32 v2, vcc, 0x2000, v2
	v_mov_b32_e32 v3, s5
	s_nop 0
	v_addc_co_u32_e32 v3, vcc, 0, v3, vcc
	global_load_dword v2, v[2:3], off offset:1024 sc1
	s_add_u32 s10, s26, 0x2400
	s_addc_u32 s11, s5, 0
	s_waitcnt vmcnt(0) lgkmcnt(0)
	v_cmp_eq_u32_e32 vcc, v2, v1
	s_and_saveexec_b64 s[8:9], vcc
	s_cbranch_execz .LBB0_124
	s_mov_b32 s27, 1
	s_mov_b64 s[12:13], 0
	s_branch .LBB0_116

; __device__ __forceinline__ unsigned xb_ld(unsigned* p)              { return __hip_atomic_load(p, __ATOMIC_RELAXED, __HIP_MEMORY_SCOPE_AGENT); }
; #define XB_SPIN(cond, bar) do { unsigned _sp = 0; while (cond) { __builtin_amdgcn_s_sleep(1); \
;     if ((++_sp & 255u) == 0u) { if (xb_ld(&(bar)[XB_TMO])) break; if (_sp > XB_SPIN_CAP) { atomicAdd(&(bar)[XB_TMO], 1u); break; } } } } while (0)
; __device__ __forceinline__ void xcd_barrier(const XcdBarrier& b) {
;     ...
;             XB_SPIN(xb_ld(&bar[XB_XGEN(b.x)]) == gen, bar);
.LBB0_116:
	s_and_b32 s20, s27, 0xff
	s_mov_b64 s[18:19], -1
	s_cmp_lg_u32 s20, 0
	s_mov_b64 s[20:21], -1
	s_sleep 1
	s_cbranch_scc1 .LBB0_120
	v_mov_b64_e32 v[2:3], s[38:39]
	global_load_dword v2, v[2:3], off offset:512 sc1
	s_mov_b64 s[20:21], 0
	s_mov_b64 s[22:23], -1
	s_waitcnt vmcnt(0) lgkmcnt(0)
	v_cmp_eq_u32_e32 vcc, 0, v2
	s_and_saveexec_b64 s[24:25], vcc
	s_cmp_lt_u32 s27, 0x400001
	s_cselect_b64 s[20:21], -1, 0
	s_xor_b64 s[22:23], exec, -1
	s_and_b64 s[20:21], s[20:21], exec
	s_or_b64 exec, exec, s[24:25]
.LBB0_120:
	s_andn2_b64 s[16:17], s[16:17], exec
	s_and_b64 s[22:23], s[22:23], exec
	s_or_b64 s[16:17], s[16:17], s[22:23]
	s_and_saveexec_b64 s[22:23], s[20:21]
	s_cbranch_execz .LBB0_115
	v_mov_b64_e32 v[2:3], s[10:11]
	global_load_dword v2, v[2:3], off sc1
	s_add_i32 s27, s27, 1
	s_or_b64 s[16:17], s[16:17], exec
	s_waitcnt vmcnt(0) lgkmcnt(0)
	v_cmp_ne_u32_e32 vcc, v2, v1
	s_orn2_b64 s[18:19], vcc, exec
	s_branch .LBB0_115

; __device__ __forceinline__ unsigned xb_ld(unsigned* p)              { return __hip_atomic_load(p, __ATOMIC_RELAXED, __HIP_MEMORY_SCOPE_AGENT); }
; __device__ __forceinline__ unsigned xb_add(unsigned* p, unsigned v) { return __hip_atomic_fetch_add(p, v, __ATOMIC_RELAXED, __HIP_MEMORY_SCOPE_AGENT); }
; #define XB_SPIN(cond, bar) do { unsigned _sp = 0; while (cond) { __builtin_amdgcn_s_sleep(1); \
;     if ((++_sp & 255u) == 0u) { if (xb_ld(&(bar)[XB_TMO])) break; if (_sp > XB_SPIN_CAP) { atomicAdd(&(bar)[XB_TMO], 1u); break; } } } } while (0)
; __device__ __forceinline__ void xcd_barrier(const XcdBarrier& b) {
;     ...
;             __builtin_amdgcn_fence(__ATOMIC_RELEASE, "agent");
;             asm volatile("s_waitcnt vmcnt(0)" ::: "memory");
;             const unsigned og = xb_add(&bar[XB_TOP], 1u);
;             const unsigned tg = og / nx;
;             if (og + 1u == (tg + 1u) * nx) xb_add(&bar[XB_TOPGEN], 1u);
;             else XB_SPIN(xb_ld(&bar[XB_TOPGEN]) == tg, bar);
.LBB0_125:
	s_andn2_saveexec_b64 s[6:7], s[6:7]
	s_cbranch_execz .LBB0_141
	v_mov_b32_e32 v1, s38
	v_add_co_u32_e32 v4, vcc, 0x3000, v1
	v_mov_b32_e32 v1, s39
	buffer_wbl2 sc1
	s_waitcnt vmcnt(0)
	v_addc_co_u32_e32 v5, vcc, 0, v1, vcc
	flat_atomic_add v1, v[4:5], v217 offset:1024 sc0
	v_cvt_f32_u32_e32 v3, v2
	v_sub_u32_e32 v4, 0, v2
	s_add_u32 s6, s38, 0x3500
	s_addc_u32 s7, s39, 0
	v_rcp_iflag_f32_e32 v3, v3
	s_mov_b64 s[10:11], -1
	v_mul_f32_e32 v3, 0x4f7ffffe, v3
	v_cvt_u32_f32_e32 v3, v3
	v_mul_lo_u32 v4, v4, v3
	v_mul_hi_u32 v4, v3, v4
	v_add_u32_e32 v3, v3, v4
	s_waitcnt vmcnt(0) lgkmcnt(0)
	v_mul_hi_u32 v3, v1, v3
	v_mul_lo_u32 v5, v3, v2
	v_add_u32_e32 v4, 1, v1
	v_sub_u32_e32 v1, v1, v5
	v_add_u32_e32 v6, 1, v3
	v_cmp_ge_u32_e32 vcc, v1, v2
	v_sub_u32_e32 v5, v1, v2
	s_nop 0
	v_cndmask_b32_e32 v3, v3, v6, vcc
	v_cndmask_b32_e32 v1, v1, v5, vcc
	v_add_u32_e32 v5, 1, v3
	v_cmp_ge_u32_e32 vcc, v1, v2
	s_nop 1
	v_cndmask_b32_e32 v1, v3, v5, vcc
	v_mad_u64_u32 v[2:3], s[8:9], v2, v1, v[2:3]
	v_cmp_ne_u32_e32 vcc, v4, v2
	v_mov_b64_e32 v[2:3], s[6:7]
	s_and_saveexec_b64 s[8:9], vcc
	s_cbranch_execz .LBB0_138
	v_mov_b64_e32 v[2:3], s[6:7]
	global_load_dword v2, v[2:3], off sc1
	s_mov_b64 s[14:15], 0
	s_waitcnt vmcnt(0) lgkmcnt(0)
	v_cmp_eq_u32_e32 vcc, v2, v1
	s_and_saveexec_b64 s[12:13], vcc
	s_cbranch_execz .LBB0_137
	s_add_u32 s10, s38, 0x200
	s_addc_u32 s11, s39, 0
	s_mov_b32 s27, 1
	s_branch .LBB0_130

; __device__ __forceinline__ unsigned xb_ld(unsigned* p)              { return __hip_atomic_load(p, __ATOMIC_RELAXED, __HIP_MEMORY_SCOPE_AGENT); }
; #define XB_SPIN(cond, bar) do { unsigned _sp = 0; while (cond) { __builtin_amdgcn_s_sleep(1); \
;     if ((++_sp & 255u) == 0u) { if (xb_ld(&(bar)[XB_TMO])) break; if (_sp > XB_SPIN_CAP) { atomicAdd(&(bar)[XB_TMO], 1u); break; } } } } while (0)
; __device__ __forceinline__ void xcd_barrier(const XcdBarrier& b) {
;     ...
;             else XB_SPIN(xb_ld(&bar[XB_TOPGEN]) == tg, bar);
.LBB0_132:
	v_mov_b64_e32 v[2:3], s[10:11]
	global_load_dword v2, v[2:3], off sc1
	s_mov_b64 s[22:23], 0
	s_mov_b64 s[20:21], -1
	s_waitcnt vmcnt(0) lgkmcnt(0)
	v_cmp_eq_u32_e32 vcc, 0, v2
	s_and_saveexec_b64 s[24:25], vcc
	s_cmp_lt_u32 s27, 0x400001
	s_cselect_b64 s[22:23], -1, 0
	s_xor_b64 s[20:21], exec, -1
	s_and_b64 s[22:23], s[22:23], exec
	s_or_b64 exec, exec, s[24:25]
	s_and_saveexec_b64 s[24:25], s[22:23]
	s_cbranch_execz .LBB0_129
.LBB0_135:
	v_mov_b64_e32 v[2:3], s[6:7]
	global_load_dword v2, v[2:3], off sc1
	s_add_i32 s27, s27, 1
	s_or_b64 s[20:21], s[20:21], exec
	s_waitcnt vmcnt(0) lgkmcnt(0)
	v_cmp_ne_u32_e32 vcc, v2, v1
	s_orn2_b64 s[18:19], vcc, exec
	s_branch .LBB0_129

; __device__ __forceinline__ void cumsum_logf(const Params& P, int b, int wid, int lane) {
;     ...
;     float v[32]; float s = 0.f;
; #pragma unroll
;     for (int i = 0; i < 32; ++i) { s += lf[(size_t)(lane * 32 + i) * 8]; v[i] = s; }
;     float inc = s;
; #pragma unroll
;     for (int o = 1; o < 64; o <<= 1) { const float t = __shfl_up(inc, o); if (lane >= o) inc += t; }
.LBB0_160:
	v_and_b32_e32 v4, 64, v220
	v_add_u32_e32 v5, -1, v220
	v_add_u32_e32 v6, -2, v220
	v_cmp_lt_i32_e32 vcc, v5, v4
	v_add_u32_e32 v7, -4, v220
	v_add_u32_e32 v8, -8, v220
	v_cndmask_b32_e32 v11, v5, v220, vcc
	v_cmp_lt_i32_e32 vcc, v6, v4
	v_add_u32_e32 v9, -16, v220
	s_mov_b64 s[24:25], s[94:95]
	v_cndmask_b32_e32 v6, v6, v220, vcc
	v_cmp_lt_i32_e32 vcc, v7, v4
	v_subrev_u32_e32 v10, 32, v220
	v_lshlrev_b32_e32 v12, 2, v6
	v_cndmask_b32_e32 v7, v7, v220, vcc
	v_cmp_lt_i32_e32 vcc, v8, v4
	v_lshlrev_b32_e32 v13, 2, v7
	v_lshlrev_b32_e32 v11, 2, v11
	v_cndmask_b32_e32 v8, v8, v220, vcc
	v_cmp_lt_i32_e32 vcc, v9, v4
	v_lshlrev_b32_e32 v8, 2, v8
	s_add_i32 s18, s18, s2
	v_cndmask_b32_e32 v9, v9, v220, vcc
	v_cmp_lt_i32_e32 vcc, v10, v4
	v_lshl_add_u64 v[4:5], s[24:25], 0, v[2:3]
	v_lshlrev_b32_e32 v9, 2, v9
	v_cndmask_b32_e32 v10, v10, v220, vcc
	v_add_co_u32_e32 v6, vcc, 0x100000, v4
	v_lshlrev_b32_e32 v10, 2, v10
	s_nop 0
	v_addc_co_u32_e32 v7, vcc, 0, v5, vcc
	global_load_dword v14, v[6:7], off
	global_load_dword v15, v[6:7], off offset:32
	global_load_dword v16, v[6:7], off offset:64
	global_load_dword v17, v[6:7], off offset:96
	global_load_dword v18, v[6:7], off offset:128
	global_load_dword v19, v[6:7], off offset:160
	global_load_dword v20, v[6:7], off offset:192
	global_load_dword v21, v[6:7], off offset:224
	global_load_dword v22, v[6:7], off offset:256
	global_load_dword v23, v[6:7], off offset:288
	global_load_dword v24, v[6:7], off offset:320
	global_load_dword v25, v[6:7], off offset:352
	global_load_dword v26, v[6:7], off offset:384
	global_load_dword v27, v[6:7], off offset:416
	global_load_dword v28, v[6:7], off offset:448
	global_load_dword v29, v[6:7], off offset:480
	global_load_dword v30, v[6:7], off offset:512
	global_load_dword v31, v[6:7], off offset:544
	global_load_dword v32, v[6:7], off offset:576
	global_load_dword v33, v[6:7], off offset:608
	global_load_dword v34, v[6:7], off offset:640
	global_load_dword v35, v[6:7], off offset:672
	global_load_dword v36, v[6:7], off offset:704
	global_load_dword v37, v[6:7], off offset:736
	global_load_dword v38, v[6:7], off offset:768
	global_load_dword v39, v[6:7], off offset:800
	global_load_dword v40, v[6:7], off offset:832
	global_load_dword v41, v[6:7], off offset:864
	global_load_dword v42, v[6:7], off offset:896
	global_load_dword v43, v[6:7], off offset:928
	global_load_dword v44, v[6:7], off offset:960
	s_nop 0
	global_load_dword v6, v[6:7], off offset:992
	s_cmp_gt_i32 s18, 15
	v_lshl_add_u64 v[2:3], v[2:3], 0, s[22:23]
	s_waitcnt vmcnt(0) lgkmcnt(0)
	v_add_f32_e32 v7, 0, v14
	v_add_f32_e32 v14, v7, v15
	v_add_f32_e32 v15, v14, v16
	v_add_f32_e32 v16, v15, v17
	v_add_f32_e32 v17, v16, v18
	v_add_f32_e32 v18, v17, v19
	v_add_f32_e32 v19, v18, v20
	v_add_f32_e32 v20, v19, v21
	v_add_f32_e32 v21, v20, v22
	v_add_f32_e32 v22, v21, v23
	v_add_f32_e32 v23, v22, v24
	v_add_f32_e32 v24, v23, v25
	v_add_f32_e32 v25, v24, v26
	v_add_f32_e32 v26, v25, v27
	v_add_f32_e32 v27, v26, v28
	v_add_f32_e32 v28, v27, v29
	v_add_f32_e32 v29, v28, v30
	v_add_f32_e32 v30, v29, v31
	v_add_f32_e32 v31, v30, v32
	v_add_f32_e32 v32, v31, v33
	v_add_f32_e32 v33, v32, v34
	v_add_f32_e32 v34, v33, v35
	v_add_f32_e32 v35, v34, v36
	v_add_f32_e32 v36, v35, v37
	v_add_f32_e32 v37, v36, v38
	v_add_f32_e32 v38, v37, v39
	v_add_f32_e32 v39, v38, v40
	v_add_f32_e32 v40, v39, v41
	v_add_f32_e32 v41, v40, v42
	v_add_f32_e32 v42, v41, v43
	v_add_f32_e32 v43, v42, v44
	v_add_f32_e32 v6, v43, v6
	ds_bpermute_b32 v11, v11, v6
	s_waitcnt lgkmcnt(0)
	v_add_f32_e32 v11, v6, v11
	v_cndmask_b32_e64 v11, v11, v6, s[6:7]
	ds_bpermute_b32 v12, v12, v11
	s_waitcnt lgkmcnt(0)
	v_add_f32_e32 v12, v11, v12
	v_cndmask_b32_e64 v11, v12, v11, s[8:9]
	ds_bpermute_b32 v12, v13, v11
	s_waitcnt lgkmcnt(0)
	v_add_f32_e32 v12, v11, v12
	v_cndmask_b32_e64 v11, v12, v11, s[10:11]
	ds_bpermute_b32 v8, v8, v11
	s_waitcnt lgkmcnt(0)
; __device__ __forceinline__ void cumsum_logf(const Params& P, int b, int wid, int lane) {
;     ...
;     for (int o = 1; o < 64; o <<= 1) { const float t = __shfl_up(inc, o); if (lane >= o) inc += t; }
;     const float excl = inc - s;
; #pragma unroll
;     for (int i = 0; i < 32; ++i) c[(size_t)(lane * 32 + i) * 8] = (excl + v[i]) * LOG2E;
	v_add_f32_e32 v8, v11, v8
	v_cndmask_b32_e64 v8, v8, v11, s[12:13]
	ds_bpermute_b32 v9, v9, v8
	s_waitcnt lgkmcnt(0)
	v_add_f32_e32 v9, v8, v9
	v_cndmask_b32_e64 v8, v9, v8, s[14:15]
	ds_bpermute_b32 v9, v10, v8
	s_waitcnt lgkmcnt(0)
	v_add_f32_e32 v9, v8, v9
	v_cndmask_b32_e64 v8, v9, v8, s[16:17]
	v_sub_f32_e32 v8, v8, v6
	v_add_f32_e32 v7, v7, v8
	v_add_f32_e32 v9, v14, v8
	v_add_f32_e32 v10, v15, v8
	v_add_f32_e32 v11, v16, v8
	v_add_f32_e32 v12, v17, v8
	v_add_f32_e32 v13, v18, v8
	v_add_f32_e32 v14, v19, v8
	v_add_f32_e32 v15, v20, v8
	v_add_f32_e32 v16, v21, v8
	v_add_f32_e32 v17, v22, v8
	v_add_f32_e32 v18, v23, v8
	v_add_f32_e32 v19, v24, v8
	v_add_f32_e32 v20, v25, v8
	v_add_f32_e32 v21, v26, v8
	v_add_f32_e32 v22, v27, v8
	v_add_f32_e32 v23, v28, v8
	v_add_f32_e32 v24, v29, v8
	v_add_f32_e32 v25, v30, v8
	v_add_f32_e32 v26, v31, v8
	v_add_f32_e32 v27, v32, v8
	v_add_f32_e32 v28, v33, v8
	v_add_f32_e32 v29, v34, v8
	v_add_f32_e32 v30, v35, v8
	v_add_f32_e32 v31, v36, v8
	v_add_f32_e32 v32, v37, v8
	v_add_f32_e32 v33, v38, v8
	v_add_f32_e32 v34, v39, v8
	v_add_f32_e32 v35, v40, v8
	v_add_f32_e32 v36, v41, v8
	v_add_f32_e32 v37, v42, v8
	v_add_f32_e32 v38, v43, v8
	v_add_f32_e32 v6, v6, v8
	v_mul_f32_e32 v7, 0x3fb8aa3b, v7
	v_mul_f32_e32 v8, 0x3fb8aa3b, v9
	v_mul_f32_e32 v9, 0x3fb8aa3b, v10
	v_mul_f32_e32 v10, 0x3fb8aa3b, v11
	v_mul_f32_e32 v11, 0x3fb8aa3b, v12
	v_mul_f32_e32 v12, 0x3fb8aa3b, v13
	v_mul_f32_e32 v13, 0x3fb8aa3b, v14
	v_mul_f32_e32 v14, 0x3fb8aa3b, v15
	v_mul_f32_e32 v15, 0x3fb8aa3b, v16
	v_mul_f32_e32 v16, 0x3fb8aa3b, v17
	v_mul_f32_e32 v17, 0x3fb8aa3b, v18
	v_mul_f32_e32 v18, 0x3fb8aa3b, v19
	v_mul_f32_e32 v19, 0x3fb8aa3b, v20
	v_mul_f32_e32 v20, 0x3fb8aa3b, v21
	v_mul_f32_e32 v21, 0x3fb8aa3b, v22
	v_mul_f32_e32 v22, 0x3fb8aa3b, v23
	v_mul_f32_e32 v23, 0x3fb8aa3b, v24
	v_mul_f32_e32 v24, 0x3fb8aa3b, v25
	v_mul_f32_e32 v25, 0x3fb8aa3b, v26
	v_mul_f32_e32 v26, 0x3fb8aa3b, v27
	v_mul_f32_e32 v27, 0x3fb8aa3b, v28
	v_mul_f32_e32 v28, 0x3fb8aa3b, v29
	v_mul_f32_e32 v29, 0x3fb8aa3b, v30
	v_mul_f32_e32 v30, 0x3fb8aa3b, v31
	v_mul_f32_e32 v31, 0x3fb8aa3b, v32
	v_mul_f32_e32 v32, 0x3fb8aa3b, v33
	v_mul_f32_e32 v33, 0x3fb8aa3b, v34
	v_mul_f32_e32 v34, 0x3fb8aa3b, v35
	v_mul_f32_e32 v35, 0x3fb8aa3b, v36
	v_mul_f32_e32 v36, 0x3fb8aa3b, v37
	v_mul_f32_e32 v37, 0x3fb8aa3b, v38
	v_mul_f32_e32 v6, 0x3fb8aa3b, v6
	global_store_dword v[4:5], v7, off
	global_store_dword v[4:5], v8, off offset:32
	global_store_dword v[4:5], v9, off offset:64
	global_store_dword v[4:5], v10, off offset:96
	global_store_dword v[4:5], v11, off offset:128
	global_store_dword v[4:5], v12, off offset:160
	global_store_dword v[4:5], v13, off offset:192
	global_store_dword v[4:5], v14, off offset:224
	global_store_dword v[4:5], v15, off offset:256
	global_store_dword v[4:5], v16, off offset:288
	global_store_dword v[4:5], v17, off offset:320
	global_store_dword v[4:5], v18, off offset:352
	global_store_dword v[4:5], v19, off offset:384
	global_store_dword v[4:5], v20, off offset:416
	global_store_dword v[4:5], v21, off offset:448
	global_store_dword v[4:5], v22, off offset:480
	global_store_dword v[4:5], v23, off offset:512
	global_store_dword v[4:5], v24, off offset:544
	global_store_dword v[4:5], v25, off offset:576
	global_store_dword v[4:5], v26, off offset:608
	global_store_dword v[4:5], v27, off offset:640
	global_store_dword v[4:5], v28, off offset:672
	global_store_dword v[4:5], v29, off offset:704
	global_store_dword v[4:5], v30, off offset:736
	global_store_dword v[4:5], v31, off offset:768
	global_store_dword v[4:5], v32, off offset:800
	global_store_dword v[4:5], v33, off offset:832
	global_store_dword v[4:5], v34, off offset:864
	global_store_dword v[4:5], v35, off offset:896
	global_store_dword v[4:5], v36, off offset:928
	global_store_dword v[4:5], v37, off offset:960
	global_store_dword v[4:5], v6, off offset:992
	s_cbranch_scc0 .LBB0_160

; __global__ void __launch_bounds__(512, 2) fwd_megakernel(Params P) {
;     ...
;         for (int i = vcu * 512 + tid; i < MTOK; i += G * 512) ((float*)(ws + WS_SUMSQ))[i] = 0.f;
.LBB0_164:
	v_add_u32_e32 v7, -2, v7
	v_ashrrev_i32_e32 v9, 31, v5
	v_mov_b32_e32 v8, v5
	v_ashrrev_i32_e32 v11, 31, v4
	v_mov_b32_e32 v10, v4
	v_cmp_eq_u32_e32 vcc, 0, v7
	v_add_u32_e32 v5, s9, v5
	v_add_u32_e32 v4, s5, v4
	v_lshl_add_u64 v[10:11], v[10:11], 2, s[10:11]
	v_lshl_add_u64 v[8:9], v[8:9], 2, s[10:11]
	s_or_b64 s[2:3], vcc, s[2:3]
	global_store_dword v[10:11], v0, off
	global_store_dword v[8:9], v0, off
	s_andn2_b64 exec, exec, s[2:3]
	s_cbranch_execnz .LBB0_164
	s_or_b64 exec, exec, s[2:3]
	v_cmp_ne_u32_e32 vcc, v1, v6
	v_mad_u64_u32 v[2:3], s[2:3], v6, s8, v[2:3]
	s_orn2_b64 s[14:15], vcc, exec

; __global__ void __launch_bounds__(512, 2) fwd_megakernel(Params P) {
;     ...
;         for (int i = vcu * 512 + tid; i < MTOK; i += G * 512) ((float*)(ws + WS_SUMSQ))[i] = 0.f;
.LBB0_168:
	v_add_u32_e32 v2, s8, v2
	v_cmp_lt_i32_e32 vcc, s60, v2
	global_store_dword v[4:5], v0, off
	s_or_b64 s[10:11], vcc, s[10:11]
	v_lshl_add_u64 v[4:5], v[4:5], 0, s[2:3]
	s_andn2_b64 exec, exec, s[10:11]
	s_cbranch_execnz .LBB0_168

; __device__ __forceinline__ float gelu_tanh(float x) { const float t = x + 0.044715f * x * x * x; return x * fast_rcp(1.0f + fast_exp2(-2.3022082f * t)); }
; __device__ __forceinline__ u32x4 pack8(f32x4 v0, f32x4 v1) { u32x4 w; w.x = cvt_pk_bf16(v0[0], v0[1]); w.y = cvt_pk_bf16(v0[2], v0[3]); w.z = cvt_pk_bf16(v1[0], v1[1]); w.w = cvt_pk_bf16(v1[2], v1[3]); return w; }
;     __device__ __forceinline__ void operator()(f32x4 (&acc)[2][2][4][2], const Unit& u, int wr, int wc, int fr, int fq) const {
;     ...
;         bf16_t* dst = (pn < 8) ? O + (size_t)(pn >> 2) * (MT * XP) + (pn & 3) * 256 : O + O_DQ + (size_t)(q_ >> 1) * (MT * QP) + (q_ & 1) * 256;
;         EPI_LOOP_BEGIN
;             if (mode == 1) {
; #pragma unroll
;                 for (int e = 0; e < 4; ++e) { v0[e] = gelu_tanh(v0[e]); v1[e] = gelu_tanh(v1[e]); }
;             } else if (mode == 2) { v0 = v0 * qs; v1 = v1 * qs; }
;             *(u32x4*)(dst + (size_t)row * pitch + (col - u.pn * BM)) = pack8(v0, v1);
.LBB0_202:
	s_lshl_b32 s13, s13, 1
	s_lshl_b32 s19, s20, 9
	s_and_b32 s13, s19, s13
	v_lshl_add_u32 v152, s22, 8, v1
	s_add_u32 s20, s24, s13
	v_ashrrev_i32_e32 v153, 31, v152
	s_addc_u32 s21, s25, 0
	v_lshlrev_b64 v[122:123], s18, v[152:153]
	v_lshl_add_u64 v[126:127], v[122:123], 1, s[20:21]
	v_mov_b32_e32 v151, v0
	v_cvt_pk_bf16_f32 v122, v130, v131
	v_cvt_pk_bf16_f32 v123, v132, v133
	v_cvt_pk_bf16_f32 v124, v134, v135
	v_cvt_pk_bf16_f32 v125, v136, v137
	v_lshl_add_u64 v[130:131], v[126:127], 0, v[150:151]
	s_cmp_gt_i32 s11, 1
	s_mov_b64 s[22:23], -1
	global_store_dwordx4 v[130:131], v[122:125], off
	s_cbranch_scc0 .LBB0_204
	s_mov_b32 s22, 0x3e38aa3b
	v_pk_mul_f32 v[124:125], v[120:121], s[22:23] op_sel_hi:[1,0]
	v_pk_mul_f32 v[122:123], v[118:119], s[22:23] op_sel_hi:[1,0]
	v_pk_mul_f32 v[128:129], v[116:117], s[22:23] op_sel_hi:[1,0]
	v_pk_mul_f32 v[126:127], v[114:115], s[22:23] op_sel_hi:[1,0]
	s_mov_b64 s[22:23], 0

; __device__ __forceinline__ float gelu_tanh(float x) { const float t = x + 0.044715f * x * x * x; return x * fast_rcp(1.0f + fast_exp2(-2.3022082f * t)); }
; __device__ __forceinline__ u32x4 pack8(f32x4 v0, f32x4 v1) { u32x4 w; w.x = cvt_pk_bf16(v0[0], v0[1]); w.y = cvt_pk_bf16(v0[2], v0[3]); w.z = cvt_pk_bf16(v1[0], v1[1]); w.w = cvt_pk_bf16(v1[2], v1[3]); return w; }
;     __device__ __forceinline__ void operator()(f32x4 (&acc)[2][2][4][2], const Unit& u, int wr, int wc, int fr, int fq) const {
;     ...
;         bf16_t* dst = (pn < 8) ? O + (size_t)(pn >> 2) * (MT * XP) + (pn & 3) * 256 : O + O_DQ + (size_t)(q_ >> 1) * (MT * QP) + (q_ & 1) * 256;
;         EPI_LOOP_BEGIN
;             if (mode == 1) {
; #pragma unroll
;                 for (int e = 0; e < 4; ++e) { v0[e] = gelu_tanh(v0[e]); v1[e] = gelu_tanh(v1[e]); }
;             } else if (mode == 2) { v0 = v0 * qs; v1 = v1 * qs; }
;             *(u32x4*)(dst + (size_t)row * pitch + (col - u.pn * BM)) = pack8(v0, v1);
.LBB0_208:
	v_cvt_pk_bf16_f32 v114, v122, v123
	v_cvt_pk_bf16_f32 v115, v124, v125
	v_cvt_pk_bf16_f32 v116, v126, v127
	v_cvt_pk_bf16_f32 v117, v128, v129
	s_cmp_gt_i32 s11, 1
	s_mov_b64 s[22:23], -1
	global_store_dwordx4 v[130:131], v[114:117], off offset:256
	s_cbranch_scc0 .LBB0_210
	s_mov_b32 s22, 0x3e38aa3b
	v_pk_mul_f32 v[116:117], v[112:113], s[22:23] op_sel_hi:[1,0]
	v_pk_mul_f32 v[114:115], v[110:111], s[22:23] op_sel_hi:[1,0]
	v_pk_mul_f32 v[120:121], v[108:109], s[22:23] op_sel_hi:[1,0]
	v_pk_mul_f32 v[118:119], v[106:107], s[22:23] op_sel_hi:[1,0]
	s_mov_b64 s[22:23], 0

; __device__ __forceinline__ float gelu_tanh(float x) { const float t = x + 0.044715f * x * x * x; return x * fast_rcp(1.0f + fast_exp2(-2.3022082f * t)); }
; __device__ __forceinline__ u32x4 pack8(f32x4 v0, f32x4 v1) { u32x4 w; w.x = cvt_pk_bf16(v0[0], v0[1]); w.y = cvt_pk_bf16(v0[2], v0[3]); w.z = cvt_pk_bf16(v1[0], v1[1]); w.w = cvt_pk_bf16(v1[2], v1[3]); return w; }
;     __device__ __forceinline__ void operator()(f32x4 (&acc)[2][2][4][2], const Unit& u, int wr, int wc, int fr, int fq) const {
;     ...
;         bf16_t* dst = (pn < 8) ? O + (size_t)(pn >> 2) * (MT * XP) + (pn & 3) * 256 : O + O_DQ + (size_t)(q_ >> 1) * (MT * QP) + (q_ & 1) * 256;
;         EPI_LOOP_BEGIN
;             if (mode == 1) {
; #pragma unroll
;                 for (int e = 0; e < 4; ++e) { v0[e] = gelu_tanh(v0[e]); v1[e] = gelu_tanh(v1[e]); }
;             } else if (mode == 2) { v0 = v0 * qs; v1 = v1 * qs; }
;             *(u32x4*)(dst + (size_t)row * pitch + (col - u.pn * BM)) = pack8(v0, v1);
.LBB0_214:
	v_or_b32_e32 v106, 16, v152
	v_ashrrev_i32_e32 v107, 31, v106
	v_lshlrev_b64 v[106:107], s18, v[106:107]
	v_lshl_add_u64 v[110:111], v[106:107], 1, s[20:21]
	v_mov_b32_e32 v151, v0
	v_cvt_pk_bf16_f32 v106, v114, v115
	v_cvt_pk_bf16_f32 v107, v116, v117
	v_cvt_pk_bf16_f32 v108, v118, v119
	v_cvt_pk_bf16_f32 v109, v120, v121
	v_lshl_add_u64 v[114:115], v[110:111], 0, v[150:151]
	s_cmp_gt_i32 s11, 1
	s_mov_b64 s[22:23], -1
	global_store_dwordx4 v[114:115], v[106:109], off
	s_cbranch_scc0 .LBB0_216
	s_mov_b32 s22, 0x3e38aa3b
	v_pk_mul_f32 v[108:109], v[104:105], s[22:23] op_sel_hi:[1,0]
	v_pk_mul_f32 v[106:107], v[102:103], s[22:23] op_sel_hi:[1,0]
	v_pk_mul_f32 v[112:113], v[100:101], s[22:23] op_sel_hi:[1,0]
	v_pk_mul_f32 v[110:111], v[98:99], s[22:23] op_sel_hi:[1,0]
	s_mov_b64 s[22:23], 0

; __device__ __forceinline__ float gelu_tanh(float x) { const float t = x + 0.044715f * x * x * x; return x * fast_rcp(1.0f + fast_exp2(-2.3022082f * t)); }
; __device__ __forceinline__ u32x4 pack8(f32x4 v0, f32x4 v1) { u32x4 w; w.x = cvt_pk_bf16(v0[0], v0[1]); w.y = cvt_pk_bf16(v0[2], v0[3]); w.z = cvt_pk_bf16(v1[0], v1[1]); w.w = cvt_pk_bf16(v1[2], v1[3]); return w; }
;     __device__ __forceinline__ void operator()(f32x4 (&acc)[2][2][4][2], const Unit& u, int wr, int wc, int fr, int fq) const {
;     ...
;         bf16_t* dst = (pn < 8) ? O + (size_t)(pn >> 2) * (MT * XP) + (pn & 3) * 256 : O + O_DQ + (size_t)(q_ >> 1) * (MT * QP) + (q_ & 1) * 256;
;         EPI_LOOP_BEGIN
;             if (mode == 1) {
; #pragma unroll
;                 for (int e = 0; e < 4; ++e) { v0[e] = gelu_tanh(v0[e]); v1[e] = gelu_tanh(v1[e]); }
;             } else if (mode == 2) { v0 = v0 * qs; v1 = v1 * qs; }
;             *(u32x4*)(dst + (size_t)row * pitch + (col - u.pn * BM)) = pack8(v0, v1);
.LBB0_220:
	v_cvt_pk_bf16_f32 v98, v106, v107
	v_cvt_pk_bf16_f32 v99, v108, v109
	v_cvt_pk_bf16_f32 v100, v110, v111
	v_cvt_pk_bf16_f32 v101, v112, v113
	s_cmp_gt_i32 s11, 1
	s_mov_b64 s[22:23], -1
	global_store_dwordx4 v[114:115], v[98:101], off offset:256
	s_cbranch_scc0 .LBB0_222
	s_mov_b32 s22, 0x3e38aa3b
	v_pk_mul_f32 v[100:101], v[96:97], s[22:23] op_sel_hi:[1,0]
	v_pk_mul_f32 v[98:99], v[94:95], s[22:23] op_sel_hi:[1,0]
	v_pk_mul_f32 v[104:105], v[92:93], s[22:23] op_sel_hi:[1,0]
	v_pk_mul_f32 v[102:103], v[90:91], s[22:23] op_sel_hi:[1,0]
	s_mov_b64 s[22:23], 0

; __device__ __forceinline__ float gelu_tanh(float x) { const float t = x + 0.044715f * x * x * x; return x * fast_rcp(1.0f + fast_exp2(-2.3022082f * t)); }
; __device__ __forceinline__ u32x4 pack8(f32x4 v0, f32x4 v1) { u32x4 w; w.x = cvt_pk_bf16(v0[0], v0[1]); w.y = cvt_pk_bf16(v0[2], v0[3]); w.z = cvt_pk_bf16(v1[0], v1[1]); w.w = cvt_pk_bf16(v1[2], v1[3]); return w; }
;     __device__ __forceinline__ void operator()(f32x4 (&acc)[2][2][4][2], const Unit& u, int wr, int wc, int fr, int fq) const {
;     ...
;         bf16_t* dst = (pn < 8) ? O + (size_t)(pn >> 2) * (MT * XP) + (pn & 3) * 256 : O + O_DQ + (size_t)(q_ >> 1) * (MT * QP) + (q_ & 1) * 256;
;         EPI_LOOP_BEGIN
;             if (mode == 1) {
; #pragma unroll
;                 for (int e = 0; e < 4; ++e) { v0[e] = gelu_tanh(v0[e]); v1[e] = gelu_tanh(v1[e]); }
;             } else if (mode == 2) { v0 = v0 * qs; v1 = v1 * qs; }
;             *(u32x4*)(dst + (size_t)row * pitch + (col - u.pn * BM)) = pack8(v0, v1);
.LBB0_226:
	v_or_b32_e32 v90, 32, v152
	v_ashrrev_i32_e32 v91, 31, v90
	v_lshlrev_b64 v[90:91], s18, v[90:91]
	v_lshl_add_u64 v[94:95], v[90:91], 1, s[20:21]
	v_mov_b32_e32 v151, v0
	v_cvt_pk_bf16_f32 v90, v98, v99
	v_cvt_pk_bf16_f32 v91, v100, v101
	v_cvt_pk_bf16_f32 v92, v102, v103
	v_cvt_pk_bf16_f32 v93, v104, v105
	v_lshl_add_u64 v[98:99], v[94:95], 0, v[150:151]
	s_cmp_gt_i32 s11, 1
	s_mov_b64 s[22:23], -1
	global_store_dwordx4 v[98:99], v[90:93], off
	s_cbranch_scc0 .LBB0_228
	s_mov_b32 s22, 0x3e38aa3b
	v_pk_mul_f32 v[92:93], v[88:89], s[22:23] op_sel_hi:[1,0]
	v_pk_mul_f32 v[90:91], v[86:87], s[22:23] op_sel_hi:[1,0]
	v_pk_mul_f32 v[96:97], v[84:85], s[22:23] op_sel_hi:[1,0]
	v_pk_mul_f32 v[94:95], v[82:83], s[22:23] op_sel_hi:[1,0]
	s_mov_b64 s[22:23], 0

; __device__ __forceinline__ float gelu_tanh(float x) { const float t = x + 0.044715f * x * x * x; return x * fast_rcp(1.0f + fast_exp2(-2.3022082f * t)); }
; __device__ __forceinline__ u32x4 pack8(f32x4 v0, f32x4 v1) { u32x4 w; w.x = cvt_pk_bf16(v0[0], v0[1]); w.y = cvt_pk_bf16(v0[2], v0[3]); w.z = cvt_pk_bf16(v1[0], v1[1]); w.w = cvt_pk_bf16(v1[2], v1[3]); return w; }
;     __device__ __forceinline__ void operator()(f32x4 (&acc)[2][2][4][2], const Unit& u, int wr, int wc, int fr, int fq) const {
;     ...
;         bf16_t* dst = (pn < 8) ? O + (size_t)(pn >> 2) * (MT * XP) + (pn & 3) * 256 : O + O_DQ + (size_t)(q_ >> 1) * (MT * QP) + (q_ & 1) * 256;
;         EPI_LOOP_BEGIN
;             if (mode == 1) {
; #pragma unroll
;                 for (int e = 0; e < 4; ++e) { v0[e] = gelu_tanh(v0[e]); v1[e] = gelu_tanh(v1[e]); }
;             } else if (mode == 2) { v0 = v0 * qs; v1 = v1 * qs; }
;             *(u32x4*)(dst + (size_t)row * pitch + (col - u.pn * BM)) = pack8(v0, v1);
.LBB0_232:
	v_cvt_pk_bf16_f32 v82, v90, v91
	v_cvt_pk_bf16_f32 v83, v92, v93
	v_cvt_pk_bf16_f32 v84, v94, v95
	v_cvt_pk_bf16_f32 v85, v96, v97
	s_cmp_gt_i32 s11, 1
	s_mov_b64 s[22:23], -1
	global_store_dwordx4 v[98:99], v[82:85], off offset:256
	s_cbranch_scc0 .LBB0_234
	s_mov_b32 s22, 0x3e38aa3b
	v_pk_mul_f32 v[84:85], v[80:81], s[22:23] op_sel_hi:[1,0]
	v_pk_mul_f32 v[82:83], v[78:79], s[22:23] op_sel_hi:[1,0]
	v_pk_mul_f32 v[88:89], v[76:77], s[22:23] op_sel_hi:[1,0]
	v_pk_mul_f32 v[86:87], v[74:75], s[22:23] op_sel_hi:[1,0]
	s_mov_b64 s[22:23], 0

; __device__ __forceinline__ float gelu_tanh(float x) { const float t = x + 0.044715f * x * x * x; return x * fast_rcp(1.0f + fast_exp2(-2.3022082f * t)); }
; __device__ __forceinline__ u32x4 pack8(f32x4 v0, f32x4 v1) { u32x4 w; w.x = cvt_pk_bf16(v0[0], v0[1]); w.y = cvt_pk_bf16(v0[2], v0[3]); w.z = cvt_pk_bf16(v1[0], v1[1]); w.w = cvt_pk_bf16(v1[2], v1[3]); return w; }
;     __device__ __forceinline__ void operator()(f32x4 (&acc)[2][2][4][2], const Unit& u, int wr, int wc, int fr, int fq) const {
;     ...
;         bf16_t* dst = (pn < 8) ? O + (size_t)(pn >> 2) * (MT * XP) + (pn & 3) * 256 : O + O_DQ + (size_t)(q_ >> 1) * (MT * QP) + (q_ & 1) * 256;
;         EPI_LOOP_BEGIN
;             if (mode == 1) {
; #pragma unroll
;                 for (int e = 0; e < 4; ++e) { v0[e] = gelu_tanh(v0[e]); v1[e] = gelu_tanh(v1[e]); }
;             } else if (mode == 2) { v0 = v0 * qs; v1 = v1 * qs; }
;             *(u32x4*)(dst + (size_t)row * pitch + (col - u.pn * BM)) = pack8(v0, v1);
.LBB0_238:
	v_or_b32_e32 v74, 48, v152
	v_ashrrev_i32_e32 v75, 31, v74
	v_lshlrev_b64 v[74:75], s18, v[74:75]
	v_lshl_add_u64 v[78:79], v[74:75], 1, s[20:21]
	v_mov_b32_e32 v151, v0
	v_cvt_pk_bf16_f32 v74, v82, v83
	v_cvt_pk_bf16_f32 v75, v84, v85
	v_cvt_pk_bf16_f32 v76, v86, v87
	v_cvt_pk_bf16_f32 v77, v88, v89
	v_lshl_add_u64 v[82:83], v[78:79], 0, v[150:151]
	s_cmp_gt_i32 s11, 1
	s_mov_b64 s[22:23], -1
	global_store_dwordx4 v[82:83], v[74:77], off
	s_cbranch_scc0 .LBB0_240
	s_mov_b32 s22, 0x3e38aa3b
	v_pk_mul_f32 v[76:77], v[72:73], s[22:23] op_sel_hi:[1,0]
	v_pk_mul_f32 v[74:75], v[70:71], s[22:23] op_sel_hi:[1,0]
	v_pk_mul_f32 v[80:81], v[68:69], s[22:23] op_sel_hi:[1,0]
	v_pk_mul_f32 v[78:79], v[66:67], s[22:23] op_sel_hi:[1,0]
	s_mov_b64 s[22:23], 0

; __device__ __forceinline__ float gelu_tanh(float x) { const float t = x + 0.044715f * x * x * x; return x * fast_rcp(1.0f + fast_exp2(-2.3022082f * t)); }
; __device__ __forceinline__ u32x4 pack8(f32x4 v0, f32x4 v1) { u32x4 w; w.x = cvt_pk_bf16(v0[0], v0[1]); w.y = cvt_pk_bf16(v0[2], v0[3]); w.z = cvt_pk_bf16(v1[0], v1[1]); w.w = cvt_pk_bf16(v1[2], v1[3]); return w; }
;     __device__ __forceinline__ void operator()(f32x4 (&acc)[2][2][4][2], const Unit& u, int wr, int wc, int fr, int fq) const {
;     ...
;         bf16_t* dst = (pn < 8) ? O + (size_t)(pn >> 2) * (MT * XP) + (pn & 3) * 256 : O + O_DQ + (size_t)(q_ >> 1) * (MT * QP) + (q_ & 1) * 256;
;         EPI_LOOP_BEGIN
;             if (mode == 1) {
; #pragma unroll
;                 for (int e = 0; e < 4; ++e) { v0[e] = gelu_tanh(v0[e]); v1[e] = gelu_tanh(v1[e]); }
;             } else if (mode == 2) { v0 = v0 * qs; v1 = v1 * qs; }
;             *(u32x4*)(dst + (size_t)row * pitch + (col - u.pn * BM)) = pack8(v0, v1);
.LBB0_244:
	v_cvt_pk_bf16_f32 v66, v74, v75
	v_cvt_pk_bf16_f32 v67, v76, v77
	v_cvt_pk_bf16_f32 v68, v78, v79
	v_cvt_pk_bf16_f32 v69, v80, v81
	global_store_dwordx4 v[82:83], v[66:69], off offset:256
	s_cmp_gt_i32 s11, 1
	s_mov_b64 s[22:23], -1
	s_cbranch_scc0 .LBB0_246
	s_mov_b32 s22, 0x3e38aa3b
	v_pk_mul_f32 v[68:69], v[64:65], s[22:23] op_sel_hi:[1,0]
	v_pk_mul_f32 v[66:67], v[62:63], s[22:23] op_sel_hi:[1,0]
	v_pk_mul_f32 v[72:73], v[60:61], s[22:23] op_sel_hi:[1,0]
	v_pk_mul_f32 v[70:71], v[58:59], s[22:23] op_sel_hi:[1,0]
	s_mov_b64 s[22:23], 0

; __device__ __forceinline__ float gelu_tanh(float x) { const float t = x + 0.044715f * x * x * x; return x * fast_rcp(1.0f + fast_exp2(-2.3022082f * t)); }
; __device__ __forceinline__ u32x4 pack8(f32x4 v0, f32x4 v1) { u32x4 w; w.x = cvt_pk_bf16(v0[0], v0[1]); w.y = cvt_pk_bf16(v0[2], v0[3]); w.z = cvt_pk_bf16(v1[0], v1[1]); w.w = cvt_pk_bf16(v1[2], v1[3]); return w; }
;     __device__ __forceinline__ void operator()(f32x4 (&acc)[2][2][4][2], const Unit& u, int wr, int wc, int fr, int fq) const {
;     ...
;         bf16_t* dst = (pn < 8) ? O + (size_t)(pn >> 2) * (MT * XP) + (pn & 3) * 256 : O + O_DQ + (size_t)(q_ >> 1) * (MT * QP) + (q_ & 1) * 256;
;         EPI_LOOP_BEGIN
;             if (mode == 1) {
; #pragma unroll
;                 for (int e = 0; e < 4; ++e) { v0[e] = gelu_tanh(v0[e]); v1[e] = gelu_tanh(v1[e]); }
;             } else if (mode == 2) { v0 = v0 * qs; v1 = v1 * qs; }
;             *(u32x4*)(dst + (size_t)row * pitch + (col - u.pn * BM)) = pack8(v0, v1);
.LBB0_250:
	v_add_u32_e32 v58, 0x80, v152
	v_ashrrev_i32_e32 v59, 31, v58
	v_lshlrev_b64 v[58:59], s18, v[58:59]
	v_lshl_add_u64 v[62:63], v[58:59], 1, s[20:21]
	v_mov_b32_e32 v151, v0
	v_cvt_pk_bf16_f32 v58, v66, v67
	v_cvt_pk_bf16_f32 v59, v68, v69
	v_cvt_pk_bf16_f32 v60, v70, v71
	v_cvt_pk_bf16_f32 v61, v72, v73
	v_lshl_add_u64 v[66:67], v[62:63], 0, v[150:151]
	s_cmp_gt_i32 s11, 1
	s_mov_b64 s[22:23], -1
	global_store_dwordx4 v[66:67], v[58:61], off
	s_cbranch_scc0 .LBB0_252
	s_mov_b32 s22, 0x3e38aa3b
	v_pk_mul_f32 v[60:61], v[56:57], s[22:23] op_sel_hi:[1,0]
	v_pk_mul_f32 v[58:59], v[54:55], s[22:23] op_sel_hi:[1,0]
	v_pk_mul_f32 v[64:65], v[52:53], s[22:23] op_sel_hi:[1,0]
	v_pk_mul_f32 v[62:63], v[50:51], s[22:23] op_sel_hi:[1,0]
	s_mov_b64 s[22:23], 0

; __device__ __forceinline__ float gelu_tanh(float x) { const float t = x + 0.044715f * x * x * x; return x * fast_rcp(1.0f + fast_exp2(-2.3022082f * t)); }
; __device__ __forceinline__ u32x4 pack8(f32x4 v0, f32x4 v1) { u32x4 w; w.x = cvt_pk_bf16(v0[0], v0[1]); w.y = cvt_pk_bf16(v0[2], v0[3]); w.z = cvt_pk_bf16(v1[0], v1[1]); w.w = cvt_pk_bf16(v1[2], v1[3]); return w; }
;     __device__ __forceinline__ void operator()(f32x4 (&acc)[2][2][4][2], const Unit& u, int wr, int wc, int fr, int fq) const {
;     ...
;         bf16_t* dst = (pn < 8) ? O + (size_t)(pn >> 2) * (MT * XP) + (pn & 3) * 256 : O + O_DQ + (size_t)(q_ >> 1) * (MT * QP) + (q_ & 1) * 256;
;         EPI_LOOP_BEGIN
;             if (mode == 1) {
; #pragma unroll
;                 for (int e = 0; e < 4; ++e) { v0[e] = gelu_tanh(v0[e]); v1[e] = gelu_tanh(v1[e]); }
;             } else if (mode == 2) { v0 = v0 * qs; v1 = v1 * qs; }
;             *(u32x4*)(dst + (size_t)row * pitch + (col - u.pn * BM)) = pack8(v0, v1);
.LBB0_256:
	v_cvt_pk_bf16_f32 v50, v58, v59
	v_cvt_pk_bf16_f32 v51, v60, v61
	v_cvt_pk_bf16_f32 v52, v62, v63
	v_cvt_pk_bf16_f32 v53, v64, v65
	s_cmp_gt_i32 s11, 1
	s_mov_b64 s[22:23], -1
	global_store_dwordx4 v[66:67], v[50:53], off offset:256
	s_cbranch_scc0 .LBB0_258
	s_mov_b32 s22, 0x3e38aa3b
	v_pk_mul_f32 v[52:53], v[48:49], s[22:23] op_sel_hi:[1,0]
	v_pk_mul_f32 v[50:51], v[46:47], s[22:23] op_sel_hi:[1,0]
	v_pk_mul_f32 v[56:57], v[44:45], s[22:23] op_sel_hi:[1,0]
	v_pk_mul_f32 v[54:55], v[42:43], s[22:23] op_sel_hi:[1,0]
	s_mov_b64 s[22:23], 0

; __device__ __forceinline__ float gelu_tanh(float x) { const float t = x + 0.044715f * x * x * x; return x * fast_rcp(1.0f + fast_exp2(-2.3022082f * t)); }
; __device__ __forceinline__ u32x4 pack8(f32x4 v0, f32x4 v1) { u32x4 w; w.x = cvt_pk_bf16(v0[0], v0[1]); w.y = cvt_pk_bf16(v0[2], v0[3]); w.z = cvt_pk_bf16(v1[0], v1[1]); w.w = cvt_pk_bf16(v1[2], v1[3]); return w; }
;     __device__ __forceinline__ void operator()(f32x4 (&acc)[2][2][4][2], const Unit& u, int wr, int wc, int fr, int fq) const {
;     ...
;         bf16_t* dst = (pn < 8) ? O + (size_t)(pn >> 2) * (MT * XP) + (pn & 3) * 256 : O + O_DQ + (size_t)(q_ >> 1) * (MT * QP) + (q_ & 1) * 256;
;         EPI_LOOP_BEGIN
;             if (mode == 1) {
; #pragma unroll
;                 for (int e = 0; e < 4; ++e) { v0[e] = gelu_tanh(v0[e]); v1[e] = gelu_tanh(v1[e]); }
;             } else if (mode == 2) { v0 = v0 * qs; v1 = v1 * qs; }
;             *(u32x4*)(dst + (size_t)row * pitch + (col - u.pn * BM)) = pack8(v0, v1);
.LBB0_262:
	v_add_u32_e32 v42, 0x90, v152
	v_ashrrev_i32_e32 v43, 31, v42
	v_lshlrev_b64 v[42:43], s18, v[42:43]
	v_lshl_add_u64 v[46:47], v[42:43], 1, s[20:21]
	v_mov_b32_e32 v151, v0
	v_cvt_pk_bf16_f32 v42, v50, v51
	v_cvt_pk_bf16_f32 v43, v52, v53
	v_cvt_pk_bf16_f32 v44, v54, v55
	v_cvt_pk_bf16_f32 v45, v56, v57
	v_lshl_add_u64 v[50:51], v[46:47], 0, v[150:151]
	s_cmp_gt_i32 s11, 1
	s_mov_b64 s[22:23], -1
	global_store_dwordx4 v[50:51], v[42:45], off
	s_cbranch_scc0 .LBB0_264
	s_mov_b32 s22, 0x3e38aa3b
	v_pk_mul_f32 v[44:45], v[40:41], s[22:23] op_sel_hi:[1,0]
	v_pk_mul_f32 v[42:43], v[38:39], s[22:23] op_sel_hi:[1,0]
	v_pk_mul_f32 v[48:49], v[36:37], s[22:23] op_sel_hi:[1,0]
	v_pk_mul_f32 v[46:47], v[34:35], s[22:23] op_sel_hi:[1,0]
	s_mov_b64 s[22:23], 0

; __device__ __forceinline__ float gelu_tanh(float x) { const float t = x + 0.044715f * x * x * x; return x * fast_rcp(1.0f + fast_exp2(-2.3022082f * t)); }
; __device__ __forceinline__ u32x4 pack8(f32x4 v0, f32x4 v1) { u32x4 w; w.x = cvt_pk_bf16(v0[0], v0[1]); w.y = cvt_pk_bf16(v0[2], v0[3]); w.z = cvt_pk_bf16(v1[0], v1[1]); w.w = cvt_pk_bf16(v1[2], v1[3]); return w; }
;     __device__ __forceinline__ void operator()(f32x4 (&acc)[2][2][4][2], const Unit& u, int wr, int wc, int fr, int fq) const {
;     ...
;         bf16_t* dst = (pn < 8) ? O + (size_t)(pn >> 2) * (MT * XP) + (pn & 3) * 256 : O + O_DQ + (size_t)(q_ >> 1) * (MT * QP) + (q_ & 1) * 256;
;         EPI_LOOP_BEGIN
;             if (mode == 1) {
; #pragma unroll
;                 for (int e = 0; e < 4; ++e) { v0[e] = gelu_tanh(v0[e]); v1[e] = gelu_tanh(v1[e]); }
;             } else if (mode == 2) { v0 = v0 * qs; v1 = v1 * qs; }
;             *(u32x4*)(dst + (size_t)row * pitch + (col - u.pn * BM)) = pack8(v0, v1);
.LBB0_268:
	v_cvt_pk_bf16_f32 v34, v42, v43
	v_cvt_pk_bf16_f32 v35, v44, v45
	v_cvt_pk_bf16_f32 v36, v46, v47
	v_cvt_pk_bf16_f32 v37, v48, v49
	s_cmp_gt_i32 s11, 1
	s_mov_b64 s[22:23], -1
	global_store_dwordx4 v[50:51], v[34:37], off offset:256
	s_cbranch_scc0 .LBB0_270
	s_mov_b32 s22, 0x3e38aa3b
	v_pk_mul_f32 v[36:37], v[32:33], s[22:23] op_sel_hi:[1,0]
	v_pk_mul_f32 v[34:35], v[30:31], s[22:23] op_sel_hi:[1,0]
	v_pk_mul_f32 v[40:41], v[28:29], s[22:23] op_sel_hi:[1,0]
	v_pk_mul_f32 v[38:39], v[26:27], s[22:23] op_sel_hi:[1,0]
	s_mov_b64 s[22:23], 0

; __device__ __forceinline__ float gelu_tanh(float x) { const float t = x + 0.044715f * x * x * x; return x * fast_rcp(1.0f + fast_exp2(-2.3022082f * t)); }
; __device__ __forceinline__ u32x4 pack8(f32x4 v0, f32x4 v1) { u32x4 w; w.x = cvt_pk_bf16(v0[0], v0[1]); w.y = cvt_pk_bf16(v0[2], v0[3]); w.z = cvt_pk_bf16(v1[0], v1[1]); w.w = cvt_pk_bf16(v1[2], v1[3]); return w; }
;     __device__ __forceinline__ void operator()(f32x4 (&acc)[2][2][4][2], const Unit& u, int wr, int wc, int fr, int fq) const {
;     ...
;         bf16_t* dst = (pn < 8) ? O + (size_t)(pn >> 2) * (MT * XP) + (pn & 3) * 256 : O + O_DQ + (size_t)(q_ >> 1) * (MT * QP) + (q_ & 1) * 256;
;         EPI_LOOP_BEGIN
;             if (mode == 1) {
; #pragma unroll
;                 for (int e = 0; e < 4; ++e) { v0[e] = gelu_tanh(v0[e]); v1[e] = gelu_tanh(v1[e]); }
;             } else if (mode == 2) { v0 = v0 * qs; v1 = v1 * qs; }
;             *(u32x4*)(dst + (size_t)row * pitch + (col - u.pn * BM)) = pack8(v0, v1);
.LBB0_274:
	v_add_u32_e32 v26, 0xa0, v152
	v_ashrrev_i32_e32 v27, 31, v26
	v_lshlrev_b64 v[26:27], s18, v[26:27]
	v_lshl_add_u64 v[30:31], v[26:27], 1, s[20:21]
	v_mov_b32_e32 v151, v0
	v_cvt_pk_bf16_f32 v26, v34, v35
	v_cvt_pk_bf16_f32 v27, v36, v37
	v_cvt_pk_bf16_f32 v28, v38, v39
	v_cvt_pk_bf16_f32 v29, v40, v41
	v_lshl_add_u64 v[34:35], v[30:31], 0, v[150:151]
	s_cmp_gt_i32 s11, 1
	s_mov_b64 s[22:23], -1
	global_store_dwordx4 v[34:35], v[26:29], off
	s_cbranch_scc0 .LBB0_276
	s_mov_b32 s22, 0x3e38aa3b
	v_pk_mul_f32 v[28:29], v[24:25], s[22:23] op_sel_hi:[1,0]
	v_pk_mul_f32 v[26:27], v[22:23], s[22:23] op_sel_hi:[1,0]
	v_pk_mul_f32 v[32:33], v[20:21], s[22:23] op_sel_hi:[1,0]
	v_pk_mul_f32 v[30:31], v[18:19], s[22:23] op_sel_hi:[1,0]
	s_mov_b64 s[22:23], 0

; __device__ __forceinline__ float gelu_tanh(float x) { const float t = x + 0.044715f * x * x * x; return x * fast_rcp(1.0f + fast_exp2(-2.3022082f * t)); }
; __device__ __forceinline__ u32x4 pack8(f32x4 v0, f32x4 v1) { u32x4 w; w.x = cvt_pk_bf16(v0[0], v0[1]); w.y = cvt_pk_bf16(v0[2], v0[3]); w.z = cvt_pk_bf16(v1[0], v1[1]); w.w = cvt_pk_bf16(v1[2], v1[3]); return w; }
;     __device__ __forceinline__ void operator()(f32x4 (&acc)[2][2][4][2], const Unit& u, int wr, int wc, int fr, int fq) const {
;     ...
;         bf16_t* dst = (pn < 8) ? O + (size_t)(pn >> 2) * (MT * XP) + (pn & 3) * 256 : O + O_DQ + (size_t)(q_ >> 1) * (MT * QP) + (q_ & 1) * 256;
;         EPI_LOOP_BEGIN
;             if (mode == 1) {
; #pragma unroll
;                 for (int e = 0; e < 4; ++e) { v0[e] = gelu_tanh(v0[e]); v1[e] = gelu_tanh(v1[e]); }
;             } else if (mode == 2) { v0 = v0 * qs; v1 = v1 * qs; }
;             *(u32x4*)(dst + (size_t)row * pitch + (col - u.pn * BM)) = pack8(v0, v1);
.LBB0_280:
	v_cvt_pk_bf16_f32 v18, v26, v27
	v_cvt_pk_bf16_f32 v19, v28, v29
	v_cvt_pk_bf16_f32 v20, v30, v31
	v_cvt_pk_bf16_f32 v21, v32, v33
	s_cmp_gt_i32 s11, 1
	s_mov_b64 s[22:23], -1
	global_store_dwordx4 v[34:35], v[18:21], off offset:256
	s_cbranch_scc0 .LBB0_282
	s_mov_b32 s22, 0x3e38aa3b
	v_pk_mul_f32 v[20:21], v[16:17], s[22:23] op_sel_hi:[1,0]
	v_pk_mul_f32 v[18:19], v[14:15], s[22:23] op_sel_hi:[1,0]
	v_pk_mul_f32 v[24:25], v[12:13], s[22:23] op_sel_hi:[1,0]
	v_pk_mul_f32 v[22:23], v[10:11], s[22:23] op_sel_hi:[1,0]
	s_mov_b64 s[22:23], 0

; __device__ __forceinline__ float gelu_tanh(float x) { const float t = x + 0.044715f * x * x * x; return x * fast_rcp(1.0f + fast_exp2(-2.3022082f * t)); }
; __device__ __forceinline__ u32x4 pack8(f32x4 v0, f32x4 v1) { u32x4 w; w.x = cvt_pk_bf16(v0[0], v0[1]); w.y = cvt_pk_bf16(v0[2], v0[3]); w.z = cvt_pk_bf16(v1[0], v1[1]); w.w = cvt_pk_bf16(v1[2], v1[3]); return w; }
;     __device__ __forceinline__ void operator()(f32x4 (&acc)[2][2][4][2], const Unit& u, int wr, int wc, int fr, int fq) const {
;     ...
;         bf16_t* dst = (pn < 8) ? O + (size_t)(pn >> 2) * (MT * XP) + (pn & 3) * 256 : O + O_DQ + (size_t)(q_ >> 1) * (MT * QP) + (q_ & 1) * 256;
;         EPI_LOOP_BEGIN
;             if (mode == 1) {
; #pragma unroll
;                 for (int e = 0; e < 4; ++e) { v0[e] = gelu_tanh(v0[e]); v1[e] = gelu_tanh(v1[e]); }
;             } else if (mode == 2) { v0 = v0 * qs; v1 = v1 * qs; }
;             *(u32x4*)(dst + (size_t)row * pitch + (col - u.pn * BM)) = pack8(v0, v1);
.LBB0_286:
	v_add_u32_e32 v10, 0xb0, v152
	v_ashrrev_i32_e32 v11, 31, v10
	v_lshlrev_b64 v[10:11], s18, v[10:11]
	v_lshl_add_u64 v[14:15], v[10:11], 1, s[20:21]
	v_mov_b32_e32 v151, v0
	v_cvt_pk_bf16_f32 v10, v18, v19
	v_cvt_pk_bf16_f32 v11, v20, v21
	v_cvt_pk_bf16_f32 v12, v22, v23
	v_cvt_pk_bf16_f32 v13, v24, v25
	v_lshl_add_u64 v[18:19], v[14:15], 0, v[150:151]
	s_cmp_gt_i32 s11, 1
	s_mov_b64 s[18:19], -1
	global_store_dwordx4 v[18:19], v[10:13], off
	s_cbranch_scc0 .LBB0_288
	s_mov_b32 s18, 0x3e38aa3b
	v_pk_mul_f32 v[12:13], v[8:9], s[18:19] op_sel_hi:[1,0]
	v_pk_mul_f32 v[10:11], v[6:7], s[18:19] op_sel_hi:[1,0]
	v_pk_mul_f32 v[16:17], v[4:5], s[18:19] op_sel_hi:[1,0]
	v_pk_mul_f32 v[14:15], v[2:3], s[18:19] op_sel_hi:[1,0]
	s_mov_b64 s[18:19], 0

; __device__ __forceinline__ float gelu_tanh(float x) { const float t = x + 0.044715f * x * x * x; return x * fast_rcp(1.0f + fast_exp2(-2.3022082f * t)); }
; __device__ __forceinline__ u32x4 pack8(f32x4 v0, f32x4 v1) { u32x4 w; w.x = cvt_pk_bf16(v0[0], v0[1]); w.y = cvt_pk_bf16(v0[2], v0[3]); w.z = cvt_pk_bf16(v1[0], v1[1]); w.w = cvt_pk_bf16(v1[2], v1[3]); return w; }
;     __device__ __forceinline__ void operator()(f32x4 (&acc)[2][2][4][2], const Unit& u, int wr, int wc, int fr, int fq) const {
;     ...
;         bf16_t* dst = (pn < 8) ? O + (size_t)(pn >> 2) * (MT * XP) + (pn & 3) * 256 : O + O_DQ + (size_t)(q_ >> 1) * (MT * QP) + (q_ & 1) * 256;
;         EPI_LOOP_BEGIN
;             if (mode == 1) {
; #pragma unroll
;                 for (int e = 0; e < 4; ++e) { v0[e] = gelu_tanh(v0[e]); v1[e] = gelu_tanh(v1[e]); }
;             } else if (mode == 2) { v0 = v0 * qs; v1 = v1 * qs; }
;             *(u32x4*)(dst + (size_t)row * pitch + (col - u.pn * BM)) = pack8(v0, v1);
.LBB0_292:
	v_cvt_pk_bf16_f32 v2, v10, v11
	v_cvt_pk_bf16_f32 v3, v12, v13
	v_cvt_pk_bf16_f32 v4, v14, v15
	v_cvt_pk_bf16_f32 v5, v16, v17
	global_store_dwordx4 v[18:19], v[2:5], off offset:256
	s_andn2_b64 vcc, exec, s[6:7]
	s_mov_b64 s[6:7], -1
	s_cbranch_vccnz .LBB0_178
	s_andn2_b64 vcc, exec, s[2:3]
	s_cbranch_vccnz .LBB0_177
	s_barrier
	s_branch .LBB0_177

; __device__ __forceinline__ unsigned xb_ld(unsigned* p)              { return __hip_atomic_load(p, __ATOMIC_RELAXED, __HIP_MEMORY_SCOPE_AGENT); }
; __device__ __forceinline__ void xcd_barrier_complete(unsigned* bar, unsigned x, unsigned& nloc, unsigned& nx) {
;     ...
;     for (;;) {
;         sum = 0u; cnt = 0u; mine = 0u;
; #pragma unroll
;         for (unsigned j = 0; j < 16; ++j) { const unsigned c = xb_ld(&bar[XB_XCNT(j)]); sum += c; cnt += (c > 0u) ? 1u : 0u; mine = (j == x) ? c : mine; }
;         if (sum == G) break;
;         __builtin_amdgcn_s_sleep(1);
;         if ((++sp & 255u) == 0u) { if (xb_ld(&bar[XB_TMO])) break; if (sp > XB_SPIN_CAP) { atomicAdd(&bar[XB_TMO], 1u); break; } }
;     }
.LBB0_301:
	v_mov_b64_e32 v[12:13], s[38:39]
	s_waitcnt lgkmcnt(0)
	global_load_dword v2, v[12:13], off offset:1024 sc1
	global_load_dword v1, v[12:13], off offset:1280 sc1
	global_load_dword v3, v[12:13], off offset:1536 sc1
	s_or_b64 s[20:21], s[20:21], exec
	s_or_b64 s[18:19], s[18:19], exec
	s_waitcnt vmcnt(0) lgkmcnt(0)
	v_add_u32_e32 v4, v1, v2
	v_add_u32_e32 v5, v4, v3
	global_load_dword v4, v[12:13], off offset:1792 sc1
	s_waitcnt vmcnt(0) lgkmcnt(0)
	v_add_u32_e32 v6, v5, v4
	global_load_dword v5, v[12:13], off offset:2048 sc1
	s_waitcnt vmcnt(0) lgkmcnt(0)
	v_add_u32_e32 v7, v6, v5
	global_load_dword v6, v[12:13], off offset:2304 sc1
	s_waitcnt vmcnt(0) lgkmcnt(0)
	v_add_u32_e32 v8, v7, v6
	global_load_dword v7, v[12:13], off offset:2560 sc1
	s_waitcnt vmcnt(0) lgkmcnt(0)
	v_add_u32_e32 v9, v8, v7
	global_load_dword v8, v[12:13], off offset:2816 sc1
	s_waitcnt vmcnt(0) lgkmcnt(0)
	v_add_u32_e32 v10, v9, v8
	global_load_dword v9, v[12:13], off offset:3072 sc1
	s_waitcnt vmcnt(0) lgkmcnt(0)
	v_add_u32_e32 v11, v10, v9
	global_load_dword v10, v[12:13], off offset:3328 sc1
	s_waitcnt vmcnt(0) lgkmcnt(0)
	v_add_u32_e32 v14, v11, v10
	global_load_dword v11, v[12:13], off offset:3584 sc1
	s_waitcnt vmcnt(0) lgkmcnt(0)
	v_add_u32_e32 v14, v14, v11
	global_load_dword v12, v[12:13], off offset:3840 sc1
	s_waitcnt vmcnt(0) lgkmcnt(0)
	v_add_u32_e32 v16, v14, v12
	v_mov_b64_e32 v[14:15], s[6:7]
	global_load_dword v13, v[14:15], off sc1
	v_mov_b64_e32 v[14:15], s[8:9]
	global_load_dword v14, v[14:15], off sc1
	s_waitcnt vmcnt(0) lgkmcnt(0)
	v_add_u32_e32 v16, v16, v13
	v_add_u32_e32 v18, v16, v14
	v_mov_b64_e32 v[16:17], s[10:11]
	global_load_dword v15, v[16:17], off sc1
	v_mov_b64_e32 v[16:17], s[12:13]
	global_load_dword v16, v[16:17], off sc1
	s_waitcnt vmcnt(0) lgkmcnt(0)
	v_add_u32_e32 v18, v18, v15
	v_add_u32_e32 v17, v18, v16
	v_cmp_ne_u32_e32 vcc, s59, v17
	s_and_saveexec_b64 s[22:23], vcc
	s_cbranch_execz .LBB0_300
	s_and_b32 s26, s34, 0xff
	s_mov_b64 s[24:25], -1
	s_cmp_eq_u32 s26, 0
	s_mov_b64 s[28:29], -1
	s_mov_b64 s[26:27], -1
	s_sleep 1
	s_cbranch_scc1 .LBB0_304
	s_and_saveexec_b64 s[30:31], s[28:29]
	s_cbranch_execz .LBB0_299
	s_branch .LBB0_307

; __device__ __forceinline__ unsigned xb_ld(unsigned* p)              { return __hip_atomic_load(p, __ATOMIC_RELAXED, __HIP_MEMORY_SCOPE_AGENT); }
; __device__ __forceinline__ unsigned xb_add(unsigned* p, unsigned v) { return __hip_atomic_fetch_add(p, v, __ATOMIC_RELAXED, __HIP_MEMORY_SCOPE_AGENT); }
; #define XB_SPIN(cond, bar) do { unsigned _sp = 0; while (cond) { __builtin_amdgcn_s_sleep(1); \
;     if ((++_sp & 255u) == 0u) { if (xb_ld(&(bar)[XB_TMO])) break; if (_sp > XB_SPIN_CAP) { atomicAdd(&(bar)[XB_TMO], 1u); break; } } } } while (0)
; __device__ __forceinline__ void xcd_barrier(const XcdBarrier& b) {
;     ...
;         const unsigned old = xb_add(&bar[XB_XSUB(b.x)], 1u);
;         const unsigned gen = old / nloc;
;         if (old + 1u == (gen + 1u) * nloc) {
;             __builtin_amdgcn_fence(__ATOMIC_RELEASE, "agent");
;             asm volatile("s_waitcnt vmcnt(0)" ::: "memory");
;             const unsigned og = xb_add(&bar[XB_TOP], 1u);
;             const unsigned tg = og / nx;
;             if (og + 1u == (tg + 1u) * nx) xb_add(&bar[XB_TOPGEN], 1u);
;             else XB_SPIN(xb_ld(&bar[XB_TOPGEN]) == tg, bar);
;             __builtin_amdgcn_fence(__ATOMIC_ACQUIRE, "agent");
;             xb_add(&bar[XB_XGEN(b.x)], 1u);
;             asm volatile("s_waitcnt vmcnt(0)" ::: "memory");
;         } else {
;             XB_SPIN(xb_ld(&bar[XB_XGEN(b.x)]) == gen, bar);
.LBB0_311:
	s_lshl_b32 s5, s5, 8
	s_add_u32 s26, s38, s5
	s_addc_u32 s5, s39, 0
	v_mov_b32_e32 v1, s26
	v_add_co_u32_e32 v6, vcc, 0x1000, v1
	v_mov_b32_e32 v1, s5
	s_nop 0
	v_addc_co_u32_e32 v7, vcc, 0, v1, vcc
	flat_atomic_add v3, v[6:7], v217 offset:1024 sc0
	v_cvt_f32_u32_e32 v1, v4
	v_sub_u32_e32 v5, 0, v4
	v_rcp_iflag_f32_e32 v1, v1
	s_nop 0
	v_mul_f32_e32 v1, 0x4f7ffffe, v1
	v_cvt_u32_f32_e32 v1, v1
	v_mul_lo_u32 v5, v5, v1
	v_mul_hi_u32 v5, v1, v5
	v_add_u32_e32 v1, v1, v5
	s_waitcnt vmcnt(0) lgkmcnt(0)
	v_mul_hi_u32 v1, v3, v1
	v_mul_lo_u32 v5, v1, v4
	v_sub_u32_e32 v5, v3, v5
	v_cmp_ge_u32_e32 vcc, v5, v4
	v_add_u32_e32 v6, 1, v1
	v_add_u32_e32 v3, 1, v3
	v_cndmask_b32_e32 v1, v1, v6, vcc
	v_sub_u32_e32 v6, v5, v4
	v_cndmask_b32_e32 v5, v5, v6, vcc
	v_cmp_ge_u32_e32 vcc, v5, v4
	v_add_u32_e32 v5, 1, v1
	s_nop 0
	v_cndmask_b32_e32 v1, v1, v5, vcc
	v_mad_u64_u32 v[4:5], s[6:7], v4, v1, v[4:5]
	v_cmp_ne_u32_e32 vcc, v3, v4
	s_and_saveexec_b64 s[6:7], vcc
	s_xor_b64 s[6:7], exec, s[6:7]
	s_cbranch_execz .LBB0_324
	v_mov_b32_e32 v2, s26
	v_add_co_u32_e32 v2, vcc, 0x2000, v2
	v_mov_b32_e32 v3, s5
	s_nop 0
	v_addc_co_u32_e32 v3, vcc, 0, v3, vcc
	global_load_dword v2, v[2:3], off offset:1024 sc1
	s_add_u32 s10, s26, 0x2400
	s_addc_u32 s11, s5, 0
	s_waitcnt vmcnt(0) lgkmcnt(0)
	v_cmp_eq_u32_e32 vcc, v2, v1
	s_and_saveexec_b64 s[8:9], vcc
	s_cbranch_execz .LBB0_323
	s_mov_b32 s27, 1
	s_mov_b64 s[12:13], 0
	s_branch .LBB0_315

; __device__ __forceinline__ unsigned xb_ld(unsigned* p)              { return __hip_atomic_load(p, __ATOMIC_RELAXED, __HIP_MEMORY_SCOPE_AGENT); }
; __device__ __forceinline__ unsigned xb_add(unsigned* p, unsigned v) { return __hip_atomic_fetch_add(p, v, __ATOMIC_RELAXED, __HIP_MEMORY_SCOPE_AGENT); }
; #define XB_SPIN(cond, bar) do { unsigned _sp = 0; while (cond) { __builtin_amdgcn_s_sleep(1); \
;     if ((++_sp & 255u) == 0u) { if (xb_ld(&(bar)[XB_TMO])) break; if (_sp > XB_SPIN_CAP) { atomicAdd(&(bar)[XB_TMO], 1u); break; } } } } while (0)
; __device__ __forceinline__ void xcd_barrier(const XcdBarrier& b) {
;     ...
;         if (old + 1u == (gen + 1u) * nloc) {
;             __builtin_amdgcn_fence(__ATOMIC_RELEASE, "agent");
;             asm volatile("s_waitcnt vmcnt(0)" ::: "memory");
;             const unsigned og = xb_add(&bar[XB_TOP], 1u);
;             const unsigned tg = og / nx;
;             if (og + 1u == (tg + 1u) * nx) xb_add(&bar[XB_TOPGEN], 1u);
;             else XB_SPIN(xb_ld(&bar[XB_TOPGEN]) == tg, bar);
.LBB0_324:
	s_andn2_saveexec_b64 s[6:7], s[6:7]
	s_cbranch_execz .LBB0_340
	v_mov_b32_e32 v1, s38
	v_add_co_u32_e32 v4, vcc, 0x3000, v1
	v_mov_b32_e32 v1, s39
	buffer_wbl2 sc1
	s_waitcnt vmcnt(0)
	v_addc_co_u32_e32 v5, vcc, 0, v1, vcc
	flat_atomic_add v3, v[4:5], v217 offset:1024 sc0
	v_cvt_f32_u32_e32 v1, v2
	v_sub_u32_e32 v4, 0, v2
	s_mov_b64 s[10:11], -1
	v_rcp_iflag_f32_e32 v1, v1
	s_nop 0
	v_mul_f32_e32 v1, 0x4f7ffffe, v1
	v_cvt_u32_f32_e32 v1, v1
	v_mul_lo_u32 v4, v4, v1
	v_mul_hi_u32 v4, v1, v4
	v_add_u32_e32 v1, v1, v4
	s_waitcnt vmcnt(0) lgkmcnt(0)
	v_mul_hi_u32 v1, v3, v1
	v_mul_lo_u32 v4, v1, v2
	v_sub_u32_e32 v4, v3, v4
	v_cmp_ge_u32_e32 vcc, v4, v2
	v_add_u32_e32 v5, 1, v1
	s_nop 0
	v_cndmask_b32_e32 v1, v1, v5, vcc
	v_sub_u32_e32 v5, v4, v2
	v_cndmask_b32_e32 v4, v4, v5, vcc
	v_cmp_ge_u32_e32 vcc, v4, v2
	v_add_u32_e32 v4, 1, v1
	s_nop 0
	v_cndmask_b32_e32 v1, v1, v4, vcc
	v_add_u32_e32 v4, 1, v3
	v_mad_u64_u32 v[2:3], s[6:7], v2, v1, v[2:3]
	s_add_u32 s6, s38, 0x3500
	s_addc_u32 s7, s39, 0
	v_cmp_ne_u32_e32 vcc, v4, v2
	v_mov_b64_e32 v[2:3], s[6:7]
	s_and_saveexec_b64 s[8:9], vcc
	s_cbranch_execz .LBB0_337
	v_mov_b64_e32 v[2:3], s[6:7]
	global_load_dword v2, v[2:3], off sc1
	s_mov_b64 s[14:15], 0
	s_waitcnt vmcnt(0) lgkmcnt(0)
	v_cmp_eq_u32_e32 vcc, v2, v1
	s_and_saveexec_b64 s[12:13], vcc
	s_cbranch_execz .LBB0_336
	s_add_u32 s10, s38, 0x200
	s_addc_u32 s11, s39, 0
	s_mov_b32 s27, 1
	s_branch .LBB0_329

; #define LAS __attribute__((address_space(3)))
; __device__ __forceinline__ float fast_exp2(float x) { return __builtin_amdgcn_exp2f(x); }
; __device__ __forceinline__ float log1p_small(float e) { return e < 0.01f ? e * (1.0f - e * (0.5f - e * 0.33333334f)) : fast_log2(1.0f + e) * 0.6931471806f; }
; #define RG_XLOAD(T0) do { _Pragma("unroll") for (int k = 0; k < 7; ++k) { const int t = (T0) + 4 * rg - 3 + k; xw[k] = (u32x4){0u, 0u, 0u, 0u}; \
;         if (t >= 0) xw[k] = *(const u32x4*)(proj + O_XR + (rowb + t) * XP + 128 * n + 8 * cc); } } while (0)
; __device__ __forceinline__ void rglru_unit(const Params& P, int l, int unit, LAS unsigned char* lds, bool dry = false) {
;     ...
;     {
; #pragma unroll
;       for (int i = 0; i < 4; ++i) { const int idx = tid + 512 * i, gate = idx >> 10, rem = idx & 1023, d = rem >> 4, ch = rem & 15;
;           const bf16_t* srcw = (const bf16_t*)(ws_ + (gate ? WS_RGI : WS_RGR)) + n * 16384 + (64 * j + d) * 128 + ch * 8;
;           *(LAS u32x4*)(WB + (gate * 64 + d) * 272 + ch * 16) = *(const u32x4*)srcw; } }
;     const float br = P.in[I_RGBR][l * DM + dglob], bi = P.in[I_RGBI][l * DM + dglob];
;     const float ap_ = P.in[I_RGA][l * DM + dglob]; const float sp8 = 8.0f * (fmaxf(-ap_, 0.f) + log1p_small(fast_exp2(-fabsf(ap_) * LOG2E)));
;     const int cc = tid & 15, rg = tid >> 4;
;     float cw[4][8], cbias[8];
; #pragma unroll
;     for (int e = 0; e < 8; ++e) { cbias[e] = P.in[I_RCB][l * DM + 128 * n + 8 * cc + e];
; #pragma unroll
;         for (int k = 0; k < 4; ++k) cw[k][e] = P.in[I_RCW][(l * 4 + k) * DM + 128 * n + 8 * cc + e]; }
;     LAS unsigned char* xc = lds;
;     LAS float* Ab = (LAS float*)(lds + 34816);
;     LAS float* Ub = (LAS float*)(lds + 67584);
;     LAS f32x2* seg = (LAS f32x2*)(lds + 100352);
;     float carry = 0.f;
;     const size_t rowb = (size_t)b * SEQ;
;     u32x4 xw[7];
;     ...
;     RG_XLOAD(0);
.LBB0_347:
	v_mov_b32_e32 v11, v180
	s_lshl_b32 s3, s26, 6
	v_readfirstlane_b32 s8, v11
	s_ashr_i32 s9, s8, 3
	s_bfe_u32 s2, s26, 0x30001
	s_and_b32 s10, s3, 64
	s_andn2_b32 s9, s9, 31
	s_mov_b64 s[20:21], s[94:95]
	s_add_i32 s7, s9, s10
	s_lshl_b32 s6, s2, 7
	s_lshl_b32 s2, s2, 15
	s_movk_i32 s14, 0x400
	s_add_u32 s2, s20, s2
	v_bfe_u32 v3, v11, 4, 6
	v_cmp_gt_u32_e32 vcc, s14, v11
	s_addc_u32 s3, s21, 0
	v_mov_b32_e32 v7, v0
	v_cndmask_b32_e32 v6, v221, v222, vcc
	v_or_b32_e32 v5, s10, v3
	v_and_b32_e32 v1, 15, v11
	v_lshl_add_u64 v[6:7], s[2:3], 0, v[6:7]
	v_lshlrev_b32_e32 v14, 8, v5
	v_mov_b32_e32 v15, v0
	v_lshlrev_b32_e32 v4, 4, v1
	v_lshl_add_u64 v[6:7], v[6:7], 0, v[14:15]
	v_mov_b32_e32 v5, v0
	v_lshl_add_u64 v[6:7], v[6:7], 0, v[4:5]
	global_load_dwordx4 v[6:9], v[6:7], off
	v_readlane_b32 s11, v255, 5
	v_ashrrev_i32_e32 v12, 4, v11
	s_mov_b32 s15, 0xfffffc0
	v_add_u32_e32 v2, s11, v4
	v_and_or_b32 v13, v12, s15, v3
	s_movk_i32 s16, 0x110
	v_mad_u64_u32 v[16:17], s[12:13], v13, s16, v[2:3]
	s_movk_i32 s11, 0xfbff
	v_and_b32_e32 v10, 31, v11
	v_readlane_b32 s36, v254, 13
	v_readlane_b32 s37, v254, 14
	v_readlane_b32 s38, v254, 15
	v_readlane_b32 s39, v254, 16
	v_readlane_b32 s40, v254, 17
	v_readlane_b32 s41, v254, 18
	v_readlane_b32 s42, v254, 19
	v_readlane_b32 s43, v254, 20
	v_readlane_b32 s44, v254, 21
	v_readlane_b32 s45, v254, 22
	v_readlane_b32 s46, v254, 23
	v_readlane_b32 s47, v254, 24
	v_readlane_b32 s48, v254, 25
	v_readlane_b32 s49, v254, 26
	v_readlane_b32 s50, v254, 27
	v_readlane_b32 s51, v254, 28
	s_waitcnt vmcnt(0) lgkmcnt(0)
	ds_write_b128 v16, v[6:9]
	v_add_u32_e32 v6, 0x200, v11
	v_lshrrev_b32_e32 v13, 4, v6
	v_cmp_gt_u32_e32 vcc, s14, v6
	v_mov_b32_e32 v7, v0
	v_and_or_b32 v8, v13, 63, s10
	v_cndmask_b32_e32 v6, v221, v222, vcc
	v_lshl_add_u64 v[6:7], s[2:3], 0, v[6:7]
	v_lshlrev_b32_e32 v8, 8, v8
	v_mov_b32_e32 v9, v0
	v_lshl_add_u64 v[6:7], v[6:7], 0, v[8:9]
	v_lshl_add_u64 v[6:7], v[6:7], 0, v[4:5]
	global_load_dwordx4 v[6:9], v[6:7], off
	v_mad_u64_u32 v[16:17], s[12:13], v13, s16, v[2:3]
	v_cmp_lt_u32_e32 vcc, s11, v11
	v_add_u32_e32 v13, 0x400, v11
	v_lshrrev_b32_e32 v13, 4, v13
	v_and_or_b32 v3, v13, s15, v3
	s_waitcnt vmcnt(0) lgkmcnt(0)
	ds_write_b128 v16, v[6:9]
	v_cndmask_b32_e32 v6, v221, v222, vcc
	v_mov_b32_e32 v7, v0
	v_lshl_add_u64 v[6:7], s[2:3], 0, v[6:7]
	v_lshl_add_u64 v[6:7], v[6:7], 0, v[14:15]
	v_lshl_add_u64 v[6:7], v[6:7], 0, v[4:5]
	global_load_dwordx4 v[6:9], v[6:7], off
	v_mad_u64_u32 v[14:15], s[12:13], v3, s16, v[2:3]
	v_add_u32_e32 v3, 0x600, v11
	v_lshrrev_b32_e32 v13, 4, v3
	v_cmp_gt_u32_e32 vcc, s14, v3
	v_and_or_b32 v3, v13, 63, s10
	s_waitcnt vmcnt(0) lgkmcnt(0)
	ds_write_b128 v14, v[6:9]
	v_cndmask_b32_e32 v6, v221, v222, vcc
	v_mov_b32_e32 v7, v0
	v_lshl_add_u64 v[6:7], s[2:3], 0, v[6:7]
	v_lshlrev_b32_e32 v8, 8, v3
	v_mov_b32_e32 v9, v0
	v_lshl_add_u64 v[6:7], v[6:7], 0, v[8:9]
	v_lshl_add_u64 v[6:7], v[6:7], 0, v[4:5]
	global_load_dwordx4 v[6:9], v[6:7], off
	v_mad_u64_u32 v[2:3], s[2:3], v13, s16, v[2:3]
	v_or_b32_e32 v5, s7, v10
	s_or_b32 s7, s6, s4
	s_mov_b32 s2, 0xbfb8aa3b
	s_waitcnt vmcnt(0) lgkmcnt(0)
	ds_write_b128 v2, v[6:9]
	v_add_u32_e32 v2, s7, v5
	v_ashrrev_i32_e32 v3, 31, v2
	v_lshlrev_b64 v[2:3], 2, v[2:3]
	v_lshl_add_u64 v[6:7], s[48:49], 0, v[2:3]
	v_readlane_b32 s36, v254, 29
	v_readlane_b32 s37, v254, 30
	v_readlane_b32 s38, v254, 31
	v_readlane_b32 s39, v254, 32
	global_load_dword v128, v[6:7], off
	v_lshl_add_u64 v[6:7], s[36:37], 0, v[2:3]
	v_lshl_add_u64 v[2:3], s[38:39], 0, v[2:3]
	global_load_dword v13, v[2:3], off
	global_load_dword v129, v[6:7], off
	v_readlane_b32 s40, v254, 33
	v_readlane_b32 s41, v254, 34
	v_readlane_b32 s42, v254, 35
	v_readlane_b32 s43, v254, 36
	v_readlane_b32 s44, v254, 37
	v_readlane_b32 s45, v254, 38
	v_readlane_b32 s46, v254, 39
	v_readlane_b32 s47, v254, 40
	v_readlane_b32 s48, v254, 41
	v_readlane_b32 s49, v254, 42
	v_readlane_b32 s50, v254, 43
	v_readlane_b32 s51, v254, 44
	s_waitcnt vmcnt(1)
	v_mul_f32_e64 v2, |v13|, s2
	v_exp_f32_e32 v2, v2
	s_mov_b32 s2, 0x3c23d70a
	v_cmp_ngt_f32_e32 vcc, s2, v2
	s_and_saveexec_b64 s[2:3], vcc
	s_xor_b64 s[2:3], exec, s[2:3]
	v_add_f32_e32 v2, 1.0, v2
	v_log_f32_e32 v2, v2
	s_nop 0
	v_mul_f32_e32 v14, 0x3f317218, v2
	s_andn2_saveexec_b64 s[2:3], s[2:3]
	s_mov_b32 s10, 0xbeaaaaab
	v_fma_f32 v3, v2, s10, 0.5
	v_fma_f32 v3, -v2, v3, 1.0
	v_mul_f32_e32 v14, v2, v3
	s_or_b64 exec, exec, s[2:3]
	v_lshlrev_b32_e32 v1, 3, v1
	s_or_b32 s2, s6, s27
	v_readlane_b32 s36, v254, 13
	v_or_b32_e32 v6, s2, v1
	v_readlane_b32 s42, v254, 19
	v_readlane_b32 s43, v254, 20
	v_mov_b32_e32 v7, v0
	v_or_b32_e32 v2, s7, v1
	v_mov_b32_e32 v3, v0
	v_readlane_b32 s44, v254, 21
	v_readlane_b32 s45, v254, 22
	v_lshl_add_u64 v[6:7], v[6:7], 2, s[42:43]
	s_mov_b64 s[2:3], 0x1000
	v_lshl_add_u64 v[2:3], v[2:3], 2, s[44:45]
	v_lshl_add_u64 v[8:9], v[6:7], 0, s[2:3]
	s_mov_b64 s[2:3], 0x2000
	v_lshl_add_u64 v[16:17], v[6:7], 0, s[2:3]
	s_mov_b64 s[2:3], 0x3000
	global_load_dwordx4 v[34:37], v[2:3], off offset:16
	global_load_dwordx4 v[38:41], v[2:3], off
	global_load_dwordx4 v[42:45], v[6:7], off offset:16
	global_load_dwordx4 v[46:49], v[6:7], off
	v_add_co_u32_e32 v2, vcc, s77, v6
	v_lshl_add_u64 v[18:19], v[6:7], 0, s[2:3]
	s_nop 0
	v_addc_co_u32_e32 v3, vcc, 0, v7, vcc
	s_movk_i32 s2, 0x3000
	global_load_dwordx4 v[50:53], v[2:3], off offset:-4096
	global_load_dwordx4 v[54:57], v[2:3], off
	global_load_dwordx4 v[58:61], v[8:9], off offset:16
	global_load_dwordx4 v[62:65], v[16:17], off offset:16
	v_add_co_u32_e32 v2, vcc, s2, v6
	s_ashr_i32 s22, s26, 4
	s_nop 0
	v_addc_co_u32_e32 v3, vcc, 0, v7, vcc
	global_load_dwordx4 v[66:69], v[2:3], off
	global_load_dwordx4 v[70:73], v[18:19], off offset:16
	s_ashr_i32 s23, s22, 31
	s_lshl_b64 s[2:3], s[22:23], 11
	s_lshl_b32 s6, s6, 1
	s_add_u32 s6, s20, s6
	s_addc_u32 s7, s21, 0
	v_lshlrev_b32_e32 v2, 1, v1
	v_mov_b32_e32 v3, v0
	v_lshl_add_u64 v[2:3], s[6:7], 0, v[2:3]
	s_mov_b64 s[6:7], 0x6e00000
	v_lshl_add_u64 v[106:107], v[2:3], 0, s[6:7]
	v_mov_b32_e32 v2, v0
	v_mov_b32_e32 v3, v0
	v_mov_b32_e32 v1, v0
	v_mov_b64_e32 v[76:77], v[2:3]
	v_lshlrev_b32_e32 v6, 2, v12
	v_cmp_lt_i32_e32 vcc, 0, v12
	v_mov_b64_e32 v[74:75], v[0:1]
	v_readlane_b32 s37, v254, 14
	v_readlane_b32 s38, v254, 15
	v_readlane_b32 s39, v254, 16
	v_readlane_b32 s40, v254, 17
	v_readlane_b32 s41, v254, 18
	v_readlane_b32 s46, v254, 23
	v_readlane_b32 s47, v254, 24
	v_readlane_b32 s48, v254, 25
	v_readlane_b32 s49, v254, 26
	v_readlane_b32 s50, v254, 27
	v_readlane_b32 s51, v254, 28
	s_and_saveexec_b64 s[6:7], vcc
	s_cbranch_execz .LBB0_353
	v_add_u32_e32 v8, -3, v6
	v_mov_b32_e32 v9, v0
	v_lshl_add_u64 v[8:9], s[2:3], 0, v[8:9]
	v_lshlrev_b64 v[8:9], 11, v[8:9]
	v_lshl_add_u64 v[8:9], v[106:107], 0, v[8:9]
	global_load_dwordx4 v[74:77], v[8:9], off
; #define RG_XLOAD(T0) do { _Pragma("unroll") for (int k = 0; k < 7; ++k) { const int t = (T0) + 4 * rg - 3 + k; xw[k] = (u32x4){0u, 0u, 0u, 0u}; \
;         if (t >= 0) xw[k] = *(const u32x4*)(proj + O_XR + (rowb + t) * XP + 128 * n + 8 * cc); } } while (0)
; __device__ __forceinline__ void rglru_unit(const Params& P, int l, int unit, LAS unsigned char* lds, bool dry = false) {
;     ...
;     RG_XLOAD(0);
.LBB0_353:
	s_or_b64 exec, exec, s[6:7]
	v_mov_b64_e32 v[80:81], v[2:3]
	v_mov_b64_e32 v[78:79], v[0:1]
	s_and_saveexec_b64 s[6:7], vcc
	s_cbranch_execz .LBB0_355
	v_add_u32_e32 v2, -2, v6
	v_mov_b32_e32 v3, v0
	v_lshl_add_u64 v[2:3], s[2:3], 0, v[2:3]
	v_lshlrev_b64 v[2:3], 11, v[2:3]
	v_lshl_add_u64 v[2:3], v[106:107], 0, v[2:3]
	global_load_dwordx4 v[78:81], v[2:3], off
.LBB0_355:
	s_or_b64 exec, exec, s[6:7]
	v_mov_b32_e32 v2, v0
	v_mov_b32_e32 v3, v0
	v_mov_b32_e32 v1, v0
	v_mov_b64_e32 v[84:85], v[2:3]
	v_mov_b64_e32 v[82:83], v[0:1]
	s_and_saveexec_b64 s[6:7], vcc
	s_cbranch_execz .LBB0_357
	v_add_u32_e32 v8, -1, v6
	v_mov_b32_e32 v9, v0
	v_lshl_add_u64 v[8:9], s[2:3], 0, v[8:9]
	v_lshlrev_b64 v[8:9], 11, v[8:9]
	v_lshl_add_u64 v[8:9], v[106:107], 0, v[8:9]
	global_load_dwordx4 v[82:85], v[8:9], off
.LBB0_357:
	s_or_b64 exec, exec, s[6:7]
	v_mov_b64_e32 v[92:93], v[2:3]
	v_cmp_lt_i32_e32 vcc, -1, v12
	v_mov_b64_e32 v[90:91], v[0:1]
	s_and_saveexec_b64 s[6:7], vcc
	s_cbranch_execz .LBB0_359
	v_mov_b32_e32 v7, v0
	v_lshl_add_u64 v[2:3], s[2:3], 0, v[6:7]
	v_lshlrev_b64 v[2:3], 11, v[2:3]
	v_lshl_add_u64 v[2:3], v[106:107], 0, v[2:3]
	global_load_dwordx4 v[90:93], v[2:3], off
.LBB0_359:
	s_or_b64 exec, exec, s[6:7]
	v_mov_b32_e32 v2, v0
	v_mov_b32_e32 v3, v0
	v_mov_b32_e32 v1, v0
	v_mov_b64_e32 v[96:97], v[2:3]
	v_or_b32_e32 v8, 1, v6
	v_mov_b64_e32 v[94:95], v[0:1]
	s_and_saveexec_b64 s[6:7], vcc
	s_cbranch_execz .LBB0_361
	v_mov_b32_e32 v9, v0
	v_lshl_add_u64 v[16:17], s[2:3], 0, v[8:9]
	v_lshlrev_b64 v[16:17], 11, v[16:17]
	v_lshl_add_u64 v[16:17], v[106:107], 0, v[16:17]
	global_load_dwordx4 v[94:97], v[16:17], off
.LBB0_361:
	s_or_b64 exec, exec, s[6:7]
	v_mov_b64_e32 v[100:101], v[2:3]
	v_mov_b64_e32 v[98:99], v[0:1]
	s_and_saveexec_b64 s[6:7], vcc
	s_cbranch_execz .LBB0_363
	v_or_b32_e32 v2, 2, v6
	v_mov_b32_e32 v3, v0
	v_lshl_add_u64 v[2:3], s[2:3], 0, v[2:3]
	v_lshlrev_b64 v[2:3], 11, v[2:3]
	v_lshl_add_u64 v[2:3], v[106:107], 0, v[2:3]
	global_load_dwordx4 v[98:101], v[2:3], off
.LBB0_363:
	s_or_b64 exec, exec, s[6:7]
	v_mov_b32_e32 v89, 0
	v_mov_b32_e32 v102, 0
	v_mov_b32_e32 v103, 0
	v_mov_b32_e32 v104, 0
	v_mov_b32_e32 v105, 0
	s_and_saveexec_b64 s[6:7], vcc
	s_cbranch_execz .LBB0_365
	v_or_b32_e32 v2, 3, v6
	v_mov_b32_e32 v3, v0
	v_lshl_add_u64 v[2:3], s[2:3], 0, v[2:3]
	v_lshlrev_b64 v[2:3], 11, v[2:3]
	v_lshl_add_u64 v[2:3], v[106:107], 0, v[2:3]
	global_load_dwordx4 v[102:105], v[2:3], off

; #define LAS __attribute__((address_space(3)))
; __device__ __forceinline__ float fast_exp2(float x) { return __builtin_amdgcn_exp2f(x); }
; __device__ __forceinline__ float sigmoidf_(float x) { return fast_rcp(1.0f + fast_exp2(-x * LOG2E)); }
; __device__ __forceinline__ int crow(int r, int hi) { return (r & 3) + 8 * (r >> 2) + 4 * hi; }
; __device__ __forceinline__ void rglru_unit(const Params& P, int l, int unit, LAS unsigned char* lds, bool dry = false) {
;     ...
;         const int sc = lane, ss = wid;
;         bf16_t* gp = proj + O_GR + (rowb + t0 + 16 * ss) * XP + 128 * n + 64 * j + sc;
;         unsigned short gq[16];
; #pragma unroll
;         for (int k = 0; k < 16; ++k) gq[k] = gp[(size_t)k * XP];
;         __syncthreads();
;         f32x16 accr = {}, acci = {};
; #pragma unroll
;         for (int s = 0; s < 8; ++s) { const bf16x8 a = *(const LAS bf16x8*)(xc + (32 * tb + r32) * 272 + (16 * s + 8 * hi) * 2);
;             const bf16x8 wr_ = *(const LAS bf16x8*)(WB + (32 * cb + r32) * 272 + (16 * s + 8 * hi) * 2), wi_ = *(const LAS bf16x8*)(WB + (64 + 32 * cb + r32) * 272 + (16 * s + 8 * hi) * 2);
;             accr = __builtin_amdgcn_mfma_f32_32x32x16_bf16(a, wr_, accr, 0, 0, 0); acci = __builtin_amdgcn_mfma_f32_32x32x16_bf16(a, wi_, acci, 0, 0, 0); }
; #pragma unroll
;         for (int r = 0; r < 16; ++r) { const int tok = 32 * tb + crow(r, hi);
;             const float rr = sigmoidf_(accr[r] + br), ii = sigmoidf_(acci[r] + bi);
;             const float la = -rr * sp8; const float a = fast_exp2(la * LOG2E);
;             const float x2 = 2.0f * la;
;             const float em = -x2 * (1.0f + x2 * (0.5f + x2 * (0.16666667f + x2 * (0.041666668f + x2 * (0.0083333338f + x2 * 0.0013888889f)))));
;             const float mult = __builtin_sqrtf(fmaxf(em, 0.f));
;             const float xcv = bf2f(*(const LAS unsigned short*)(xc + tok * 272 + dch * 2));
;             Ab[tok * 64 + 32 * cb + r32] = a; Ub[tok * 64 + 32 * cb + r32] = mult * ii * xcv; }
.LBB0_367:
	v_lshl_add_u64 v[2:3], v[108:109], 0, s[22:23]
	v_add_co_u32_e32 v126, vcc, 0xae00000, v2
	s_add_u32 s22, s22, 0x40000
	s_nop 0
	v_addc_co_u32_e32 v127, vcc, 0, v3, vcc
	v_add_co_u32_e32 v124, vcc, 0xae01000, v2
	s_addc_u32 s23, s23, 0
	s_nop 0
	v_addc_co_u32_e32 v125, vcc, 0, v3, vcc
	v_add_co_u32_e32 v122, vcc, 0xae02000, v2
	s_cmp_lg_u32 s22, 0x400000
	s_nop 0
	v_addc_co_u32_e32 v123, vcc, 0, v3, vcc
	v_add_co_u32_e32 v120, vcc, 0xae03000, v2
	v_add_u32_e32 v110, 0x80, v110
	s_nop 0
	v_addc_co_u32_e32 v121, vcc, 0, v3, vcc
	v_add_co_u32_e32 v118, vcc, 0xae04000, v2
	global_load_ushort v207, v[126:127], off
	global_load_ushort v206, v[126:127], off offset:2048
	global_load_ushort v205, v[124:125], off
	global_load_ushort v204, v[124:125], off offset:2048
	global_load_ushort v203, v[122:123], off
	global_load_ushort v202, v[122:123], off offset:2048
	global_load_ushort v201, v[120:121], off
	global_load_ushort v200, v[120:121], off offset:2048
	v_addc_co_u32_e32 v119, vcc, 0, v3, vcc
	v_add_co_u32_e32 v116, vcc, 0xae05000, v2
	s_nop 1
	v_addc_co_u32_e32 v117, vcc, 0, v3, vcc
	v_add_co_u32_e32 v114, vcc, 0xae06000, v2
	s_nop 1
	v_addc_co_u32_e32 v115, vcc, 0, v3, vcc
	v_add_co_u32_e32 v112, vcc, 0xae07000, v2
	s_nop 1
	v_addc_co_u32_e32 v113, vcc, 0, v3, vcc
	global_load_ushort v199, v[118:119], off
	global_load_ushort v198, v[118:119], off offset:2048
	global_load_ushort v197, v[116:117], off
	global_load_ushort v196, v[116:117], off offset:2048
	global_load_ushort v195, v[114:115], off
	global_load_ushort v194, v[114:115], off offset:2048
	global_load_ushort v111, v[112:113], off
	global_load_ushort v1, v[112:113], off offset:2048
	s_waitcnt lgkmcnt(0)
	s_barrier
	ds_read_b128 v[2:5], v190
	ds_read_b128 v[6:9], v191
	s_waitcnt lgkmcnt(0)
	v_mfma_f32_32x32x16_bf16 v[18:33], v[2:5], v[6:9], 0
	ds_read_b128 v[6:9], v192
	ds_read_b128 v[208:211], v190 offset:32
	ds_read_b128 v[212:215], v191 offset:32
	s_waitcnt vmcnt(0)
	v_lshlrev_b32_e32 v1, 16, v1
	s_waitcnt lgkmcnt(2)
	v_mfma_f32_32x32x16_bf16 v[2:17], v[2:5], v[6:9], 0
	s_waitcnt lgkmcnt(0)
	v_mfma_f32_32x32x16_bf16 v[18:33], v[208:211], v[212:215], v[18:33]
	ds_read_b128 v[212:215], v192 offset:32
	s_waitcnt lgkmcnt(0)
	v_mfma_f32_32x32x16_bf16 v[2:17], v[208:211], v[212:215], v[2:17]
	ds_read_b128 v[208:211], v190 offset:64
	ds_read_b128 v[212:215], v191 offset:64
	s_waitcnt lgkmcnt(0)
	v_mfma_f32_32x32x16_bf16 v[18:33], v[208:211], v[212:215], v[18:33]
	ds_read_b128 v[212:215], v192 offset:64
	s_waitcnt lgkmcnt(0)
	v_mfma_f32_32x32x16_bf16 v[2:17], v[208:211], v[212:215], v[2:17]
	ds_read_b128 v[208:211], v190 offset:96
	ds_read_b128 v[212:215], v191 offset:96
	s_waitcnt lgkmcnt(0)
	v_mfma_f32_32x32x16_bf16 v[18:33], v[208:211], v[212:215], v[18:33]
	ds_read_b128 v[212:215], v192 offset:96
	s_waitcnt lgkmcnt(0)
	v_mfma_f32_32x32x16_bf16 v[2:17], v[208:211], v[212:215], v[2:17]
	ds_read_b128 v[208:211], v190 offset:128
	ds_read_b128 v[212:215], v191 offset:128
	s_waitcnt lgkmcnt(0)
	v_mfma_f32_32x32x16_bf16 v[18:33], v[208:211], v[212:215], v[18:33]
	ds_read_b128 v[212:215], v192 offset:128
	s_waitcnt lgkmcnt(0)
	v_mfma_f32_32x32x16_bf16 v[2:17], v[208:211], v[212:215], v[2:17]
	ds_read_b128 v[208:211], v190 offset:160
	ds_read_b128 v[212:215], v191 offset:160
	s_waitcnt lgkmcnt(0)
	v_mfma_f32_32x32x16_bf16 v[18:33], v[208:211], v[212:215], v[18:33]
	ds_read_b128 v[212:215], v192 offset:160
	s_waitcnt lgkmcnt(0)
	v_mfma_f32_32x32x16_bf16 v[2:17], v[208:211], v[212:215], v[2:17]
	ds_read_b128 v[208:211], v190 offset:192
	ds_read_b128 v[212:215], v191 offset:192
	s_waitcnt lgkmcnt(0)
	v_mfma_f32_32x32x16_bf16 v[18:33], v[208:211], v[212:215], v[18:33]
	ds_read_b128 v[212:215], v192 offset:192
	s_waitcnt lgkmcnt(0)
	v_mfma_f32_32x32x16_bf16 v[2:17], v[208:211], v[212:215], v[2:17]
	ds_read_b128 v[208:211], v190 offset:224
	ds_read_b128 v[212:215], v191 offset:224
	ds_read_b128 v[226:229], v192 offset:224
	s_waitcnt lgkmcnt(1)
	v_mfma_f32_32x32x16_bf16 v[18:33], v[208:211], v[212:215], v[18:33]
	s_waitcnt lgkmcnt(0)
	v_mfma_f32_32x32x16_bf16 v[2:17], v[208:211], v[226:229], v[2:17]
	s_nop 9
	v_add_f32_e32 v18, v128, v18
	v_mul_f32_e32 v18, 0xbfb8aa3b, v18
	v_exp_f32_e32 v18, v18
	v_add_f32_e32 v19, v128, v19
	v_mul_f32_e32 v19, 0xbfb8aa3b, v19
	v_exp_f32_e32 v19, v19
	v_add_f32_e32 v18, 1.0, v18
	v_rcp_f32_e64 v18, -v18
	v_add_f32_e32 v2, v129, v2
	v_mul_f32_e32 v2, 0xbfb8aa3b, v2
	v_exp_f32_e32 v2, v2
	v_mul_f32_e32 v18, v130, v18
	v_add_f32_e32 v86, v18, v18
	v_fmamk_f32 v87, v86, 0x3ab60b61, v218
	v_fmaak_f32 v87, v86, v87, 0x3d2aaaab
	v_fmaak_f32 v87, v86, v87, 0x3e2aaaab
	v_fma_f32 v87, v86, v87, 0.5
	v_fma_f32 v87, v86, v87, 1.0
	v_mul_f32_e64 v86, v87, -v86
	v_max_f32_e32 v86, 0, v86
	v_mul_f32_e32 v87, 0x4f800000, v86
	v_cmp_gt_f32_e32 vcc, s0, v86
	v_mul_f32_e32 v18, 0x3fb8aa3b, v18
	v_exp_f32_e32 v18, v18
	v_cndmask_b32_e32 v86, v86, v87, vcc
	v_sqrt_f32_e32 v87, v86
	v_add_f32_e32 v2, 1.0, v2
	v_rcp_f32_e32 v2, v2
	v_add_f32_e32 v3, v129, v3
	v_add_u32_e32 v88, -1, v87
	v_fma_f32 v182, -v88, v87, v86
	v_cmp_ge_f32_e64 s[20:21], 0, v182
	v_add_u32_e32 v182, 1, v87
	v_mul_f32_e32 v3, 0xbfb8aa3b, v3
	v_cndmask_b32_e64 v88, v87, v88, s[20:21]
	v_fma_f32 v87, -v182, v87, v86
	v_cmp_lt_f32_e64 s[20:21], 0, v87
	v_exp_f32_e32 v3, v3
	v_add_f32_e32 v4, v129, v4
	v_cndmask_b32_e64 v87, v88, v182, s[20:21]
	v_mul_f32_e32 v88, 0x37800000, v87
	v_cndmask_b32_e32 v87, v87, v88, vcc
	v_cmp_class_f32_e32 vcc, v86, v219
	v_mul_f32_e32 v4, 0xbfb8aa3b, v4
	v_exp_f32_e32 v4, v4
	v_cndmask_b32_e32 v86, v87, v86, vcc
	ds_read_u16 v87, v193
	ds_read_u16 v88, v193 offset:272
	ds_read_u16 v182, v193 offset:544
	ds_read_u16 v183, v193 offset:816
	ds_read_u16 v184, v193 offset:2176
	ds_read_u16 v185, v193 offset:2448
	ds_read_u16 v208, v193 offset:2720
	ds_read_u16 v209, v193 offset:2992
	ds_write_b32 v134, v18 offset:34816
	v_add_f32_e32 v18, 1.0, v19
	v_rcp_f32_e64 v18, -v18
	s_waitcnt lgkmcnt(8)
; #define LAS __attribute__((address_space(3)))
; __device__ __forceinline__ float fast_exp2(float x) { return __builtin_amdgcn_exp2f(x); }
; __device__ __forceinline__ float sigmoidf_(float x) { return fast_rcp(1.0f + fast_exp2(-x * LOG2E)); }
; __device__ __forceinline__ int crow(int r, int hi) { return (r & 3) + 8 * (r >> 2) + 4 * hi; }
; __device__ __forceinline__ void rglru_unit(const Params& P, int l, int unit, LAS unsigned char* lds, bool dry = false) {
;     ...
;         for (int r = 0; r < 16; ++r) { const int tok = 32 * tb + crow(r, hi);
;             const float rr = sigmoidf_(accr[r] + br), ii = sigmoidf_(acci[r] + bi);
;             const float la = -rr * sp8; const float a = fast_exp2(la * LOG2E);
;             const float x2 = 2.0f * la;
;             const float em = -x2 * (1.0f + x2 * (0.5f + x2 * (0.16666667f + x2 * (0.041666668f + x2 * (0.0083333338f + x2 * 0.0013888889f)))));
;             const float mult = __builtin_sqrtf(fmaxf(em, 0.f));
;             const float xcv = bf2f(*(const LAS unsigned short*)(xc + tok * 272 + dch * 2));
;             Ab[tok * 64 + 32 * cb + r32] = a; Ub[tok * 64 + 32 * cb + r32] = mult * ii * xcv; }
	v_lshlrev_b32_e32 v87, 16, v87
	v_mul_f32_e32 v2, v2, v86
	v_mul_f32_e32 v2, v2, v87
	ds_write_b32 v135, v2
	v_add_f32_e32 v2, 1.0, v3
	v_mul_f32_e32 v3, v130, v18
	v_add_f32_e32 v18, v3, v3
	v_fmamk_f32 v19, v18, 0x3ab60b61, v218
	v_fmaak_f32 v19, v18, v19, 0x3d2aaaab
	v_fmaak_f32 v19, v18, v19, 0x3e2aaaab
	v_fma_f32 v19, v18, v19, 0.5
	v_fma_f32 v19, v18, v19, 1.0
	v_mul_f32_e64 v18, v19, -v18
	v_max_f32_e32 v18, 0, v18
	v_mul_f32_e32 v19, 0x4f800000, v18
	v_cmp_gt_f32_e32 vcc, s0, v18
	v_mul_f32_e32 v3, 0x3fb8aa3b, v3
	v_exp_f32_e32 v3, v3
	v_cndmask_b32_e32 v18, v18, v19, vcc
	v_sqrt_f32_e32 v19, v18
	v_rcp_f32_e32 v2, v2
	ds_write_b32 v136, v3 offset:34816
	v_add_u32_e32 v86, -1, v19
	v_fma_f32 v87, -v86, v19, v18
	v_cmp_ge_f32_e64 s[20:21], 0, v87
	v_add_u32_e32 v87, 1, v19
	s_nop 0
	v_cndmask_b32_e64 v86, v19, v86, s[20:21]
	v_fma_f32 v19, -v87, v19, v18
	v_cmp_lt_f32_e64 s[20:21], 0, v19
	s_nop 1
	v_cndmask_b32_e64 v19, v86, v87, s[20:21]
	v_mul_f32_e32 v86, 0x37800000, v19
	v_cndmask_b32_e32 v19, v19, v86, vcc
	v_cmp_class_f32_e32 vcc, v18, v219
	s_nop 1
	v_cndmask_b32_e32 v18, v19, v18, vcc
	v_add_f32_e32 v19, v128, v20
	v_mul_f32_e32 v19, 0xbfb8aa3b, v19
	v_exp_f32_e32 v19, v19
	s_waitcnt lgkmcnt(9)
	v_lshlrev_b32_e32 v20, 16, v88
	v_mul_f32_e32 v2, v2, v18
	v_mul_f32_e32 v2, v2, v20
	v_add_f32_e32 v3, 1.0, v19
	v_rcp_f32_e64 v3, -v3
	ds_write_b32 v137, v2
	v_add_f32_e32 v2, 1.0, v4
	v_rcp_f32_e32 v2, v2
	v_mul_f32_e32 v3, v130, v3
	v_add_f32_e32 v4, v3, v3
	v_fmamk_f32 v18, v4, 0x3ab60b61, v218
	v_fmaak_f32 v18, v4, v18, 0x3d2aaaab
	v_fmaak_f32 v18, v4, v18, 0x3e2aaaab
	v_fma_f32 v18, v4, v18, 0.5
	v_fma_f32 v18, v4, v18, 1.0
	v_mul_f32_e64 v4, v18, -v4
	v_max_f32_e32 v4, 0, v4
	v_mul_f32_e32 v18, 0x4f800000, v4
	v_cmp_gt_f32_e32 vcc, s0, v4
	v_mul_f32_e32 v3, 0x3fb8aa3b, v3
	v_exp_f32_e32 v3, v3
	v_cndmask_b32_e32 v4, v4, v18, vcc
	v_sqrt_f32_e32 v18, v4
	ds_write_b32 v138, v3 offset:34816
	v_add_u32_e32 v19, -1, v18
	v_fma_f32 v20, -v19, v18, v4
	v_cmp_ge_f32_e64 s[20:21], 0, v20
	v_add_u32_e32 v20, 1, v18
	s_nop 0
	v_cndmask_b32_e64 v19, v18, v19, s[20:21]
	v_fma_f32 v18, -v20, v18, v4
	v_cmp_lt_f32_e64 s[20:21], 0, v18
	s_nop 1
	v_cndmask_b32_e64 v18, v19, v20, s[20:21]
	v_mul_f32_e32 v19, 0x37800000, v18
	v_cndmask_b32_e32 v18, v18, v19, vcc
	v_cmp_class_f32_e32 vcc, v4, v219
	s_waitcnt lgkmcnt(10)
	v_lshlrev_b32_e32 v19, 16, v182
	v_cndmask_b32_e32 v4, v18, v4, vcc
	v_add_f32_e32 v18, v128, v21
	v_mul_f32_e32 v18, 0xbfb8aa3b, v18
	v_exp_f32_e32 v18, v18
	v_mul_f32_e32 v2, v2, v4
	v_add_f32_e32 v4, v129, v5
	v_mul_f32_e32 v4, 0xbfb8aa3b, v4
	v_add_f32_e32 v3, 1.0, v18
	v_rcp_f32_e64 v3, -v3
	v_exp_f32_e32 v4, v4
	v_mul_f32_e32 v2, v2, v19
	ds_write_b32 v139, v2
	v_mul_f32_e32 v3, v130, v3
	v_add_f32_e32 v2, 1.0, v4
	v_add_f32_e32 v4, v3, v3
	v_fmamk_f32 v5, v4, 0x3ab60b61, v218
	v_fmaak_f32 v5, v4, v5, 0x3d2aaaab
	v_fmaak_f32 v5, v4, v5, 0x3e2aaaab
	v_fma_f32 v5, v4, v5, 0.5
	v_fma_f32 v5, v4, v5, 1.0
	v_mul_f32_e64 v4, v5, -v4
	v_max_f32_e32 v4, 0, v4
	v_mul_f32_e32 v5, 0x4f800000, v4
	v_cmp_gt_f32_e32 vcc, s0, v4
	v_mul_f32_e32 v3, 0x3fb8aa3b, v3
	v_rcp_f32_e32 v2, v2
	v_cndmask_b32_e32 v4, v4, v5, vcc
	v_sqrt_f32_e32 v5, v4
	v_exp_f32_e32 v3, v3
	v_add_u32_e32 v18, -1, v5
	v_fma_f32 v19, -v18, v5, v4
	v_cmp_ge_f32_e64 s[20:21], 0, v19
	v_add_u32_e32 v19, 1, v5
	ds_write_b32 v140, v3 offset:34816
	v_cndmask_b32_e64 v18, v5, v18, s[20:21]
	v_fma_f32 v5, -v19, v5, v4
	v_cmp_lt_f32_e64 s[20:21], 0, v5
	s_nop 1
	v_cndmask_b32_e64 v5, v18, v19, s[20:21]
	v_mul_f32_e32 v18, 0x37800000, v5
	v_cndmask_b32_e32 v5, v5, v18, vcc
	v_cmp_class_f32_e32 vcc, v4, v219
	s_waitcnt lgkmcnt(11)
	v_lshlrev_b32_e32 v18, 16, v183
	v_cndmask_b32_e32 v4, v5, v4, vcc
	v_add_f32_e32 v5, v128, v22
	v_mul_f32_e32 v5, 0xbfb8aa3b, v5
	v_exp_f32_e32 v5, v5
	v_mul_f32_e32 v2, v2, v4
	v_add_f32_e32 v4, v129, v6
	v_mul_f32_e32 v4, 0xbfb8aa3b, v4
	v_add_f32_e32 v3, 1.0, v5
	v_rcp_f32_e64 v3, -v3
	v_exp_f32_e32 v4, v4
	v_mul_f32_e32 v2, v2, v18
	ds_write_b32 v141, v2
	v_mul_f32_e32 v3, v130, v3
	v_add_f32_e32 v2, 1.0, v4
	v_add_f32_e32 v4, v3, v3
	v_fmamk_f32 v5, v4, 0x3ab60b61, v218
	v_fmaak_f32 v5, v4, v5, 0x3d2aaaab
	v_fmaak_f32 v5, v4, v5, 0x3e2aaaab
	v_fma_f32 v5, v4, v5, 0.5
	v_fma_f32 v5, v4, v5, 1.0
	v_mul_f32_e64 v4, v5, -v4
	v_max_f32_e32 v4, 0, v4
	v_mul_f32_e32 v5, 0x4f800000, v4
	v_cmp_gt_f32_e32 vcc, s0, v4
	v_mul_f32_e32 v3, 0x3fb8aa3b, v3
	v_rcp_f32_e32 v2, v2
	v_cndmask_b32_e32 v4, v4, v5, vcc
	v_sqrt_f32_e32 v5, v4
	v_exp_f32_e32 v3, v3
	v_add_u32_e32 v6, -1, v5
	v_fma_f32 v18, -v6, v5, v4
	v_cmp_ge_f32_e64 s[20:21], 0, v18
	v_add_u32_e32 v18, 1, v5
	ds_write_b32 v142, v3 offset:34816
	v_cndmask_b32_e64 v6, v5, v6, s[20:21]
	v_fma_f32 v5, -v18, v5, v4
	v_cmp_lt_f32_e64 s[20:21], 0, v5
	s_nop 1
	v_cndmask_b32_e64 v5, v6, v18, s[20:21]
	v_mul_f32_e32 v6, 0x37800000, v5
	v_cndmask_b32_e32 v5, v5, v6, vcc
	v_cmp_class_f32_e32 vcc, v4, v219
	s_waitcnt lgkmcnt(12)
	v_lshlrev_b32_e32 v6, 16, v184
	v_cndmask_b32_e32 v4, v5, v4, vcc
	v_add_f32_e32 v5, v128, v23
	v_mul_f32_e32 v5, 0xbfb8aa3b, v5
	v_exp_f32_e32 v5, v5
	v_mul_f32_e32 v2, v2, v4
	v_add_f32_e32 v4, v129, v7
	v_mul_f32_e32 v4, 0xbfb8aa3b, v4
	v_add_f32_e32 v3, 1.0, v5
	v_rcp_f32_e64 v3, -v3
	v_exp_f32_e32 v4, v4
	v_mul_f32_e32 v2, v2, v6
	ds_write_b32 v143, v2
	v_mul_f32_e32 v3, v130, v3
	v_add_f32_e32 v2, 1.0, v4
	v_add_f32_e32 v4, v3, v3
	v_fmamk_f32 v5, v4, 0x3ab60b61, v218
	v_fmaak_f32 v5, v4, v5, 0x3d2aaaab
	v_fmaak_f32 v5, v4, v5, 0x3e2aaaab
	v_fma_f32 v5, v4, v5, 0.5
	v_fma_f32 v5, v4, v5, 1.0
	v_mul_f32_e64 v4, v5, -v4
	v_max_f32_e32 v4, 0, v4
	v_mul_f32_e32 v5, 0x4f800000, v4
	v_cmp_gt_f32_e32 vcc, s0, v4
	v_mul_f32_e32 v3, 0x3fb8aa3b, v3
	v_rcp_f32_e32 v2, v2
	v_cndmask_b32_e32 v4, v4, v5, vcc
	v_sqrt_f32_e32 v5, v4
	v_exp_f32_e32 v3, v3
	v_add_u32_e32 v6, -1, v5
	v_fma_f32 v7, -v6, v5, v4
	v_cmp_ge_f32_e64 s[20:21], 0, v7
	v_add_u32_e32 v7, 1, v5
	ds_write_b32 v144, v3 offset:34816
	v_cndmask_b32_e64 v6, v5, v6, s[20:21]
	v_fma_f32 v5, -v7, v5, v4
	v_cmp_lt_f32_e64 s[20:21], 0, v5
	s_nop 1
	v_cndmask_b32_e64 v5, v6, v7, s[20:21]
	v_mul_f32_e32 v6, 0x37800000, v5
	v_cndmask_b32_e32 v5, v5, v6, vcc
	v_cmp_class_f32_e32 vcc, v4, v219
	s_waitcnt lgkmcnt(13)
; #define LAS __attribute__((address_space(3)))
; __device__ __forceinline__ float fast_exp2(float x) { return __builtin_amdgcn_exp2f(x); }
; __device__ __forceinline__ float sigmoidf_(float x) { return fast_rcp(1.0f + fast_exp2(-x * LOG2E)); }
; __device__ __forceinline__ int crow(int r, int hi) { return (r & 3) + 8 * (r >> 2) + 4 * hi; }
; __device__ __forceinline__ void rglru_unit(const Params& P, int l, int unit, LAS unsigned char* lds, bool dry = false) {
;     ...
;         for (int r = 0; r < 16; ++r) { const int tok = 32 * tb + crow(r, hi);
;             const float rr = sigmoidf_(accr[r] + br), ii = sigmoidf_(acci[r] + bi);
;             const float la = -rr * sp8; const float a = fast_exp2(la * LOG2E);
;             const float x2 = 2.0f * la;
;             const float em = -x2 * (1.0f + x2 * (0.5f + x2 * (0.16666667f + x2 * (0.041666668f + x2 * (0.0083333338f + x2 * 0.0013888889f)))));
;             const float mult = __builtin_sqrtf(fmaxf(em, 0.f));
;             const float xcv = bf2f(*(const LAS unsigned short*)(xc + tok * 272 + dch * 2));
;             Ab[tok * 64 + 32 * cb + r32] = a; Ub[tok * 64 + 32 * cb + r32] = mult * ii * xcv; }
	v_lshlrev_b32_e32 v6, 16, v185
	v_cndmask_b32_e32 v4, v5, v4, vcc
	v_add_f32_e32 v5, v128, v24
	v_mul_f32_e32 v5, 0xbfb8aa3b, v5
	v_exp_f32_e32 v5, v5
	v_mul_f32_e32 v2, v2, v4
	v_add_f32_e32 v4, v129, v8
	v_mul_f32_e32 v4, 0xbfb8aa3b, v4
	v_add_f32_e32 v3, 1.0, v5
	v_rcp_f32_e64 v3, -v3
	v_exp_f32_e32 v4, v4
	v_mul_f32_e32 v2, v2, v6
	ds_write_b32 v145, v2
	v_mul_f32_e32 v3, v130, v3
	v_add_f32_e32 v2, 1.0, v4
	v_add_f32_e32 v4, v3, v3
	v_fmamk_f32 v5, v4, 0x3ab60b61, v218
	v_fmaak_f32 v5, v4, v5, 0x3d2aaaab
	v_fmaak_f32 v5, v4, v5, 0x3e2aaaab
	v_fma_f32 v5, v4, v5, 0.5
	v_fma_f32 v5, v4, v5, 1.0
	v_mul_f32_e64 v4, v5, -v4
	v_max_f32_e32 v4, 0, v4
	v_mul_f32_e32 v5, 0x4f800000, v4
	v_cmp_gt_f32_e32 vcc, s0, v4
	v_mul_f32_e32 v3, 0x3fb8aa3b, v3
	v_rcp_f32_e32 v2, v2
	v_cndmask_b32_e32 v4, v4, v5, vcc
	v_sqrt_f32_e32 v5, v4
	v_exp_f32_e32 v3, v3
	v_add_u32_e32 v6, -1, v5
	v_fma_f32 v7, -v6, v5, v4
	v_cmp_ge_f32_e64 s[20:21], 0, v7
	v_add_u32_e32 v7, 1, v5
	ds_write_b32 v146, v3 offset:34816
	v_cndmask_b32_e64 v6, v5, v6, s[20:21]
	v_fma_f32 v5, -v7, v5, v4
	v_cmp_lt_f32_e64 s[20:21], 0, v5
	s_nop 1
	v_cndmask_b32_e64 v5, v6, v7, s[20:21]
	v_mul_f32_e32 v6, 0x37800000, v5
	v_cndmask_b32_e32 v5, v5, v6, vcc
	v_cmp_class_f32_e32 vcc, v4, v219
	s_waitcnt lgkmcnt(14)
	v_lshlrev_b32_e32 v6, 16, v208
	v_cndmask_b32_e32 v4, v5, v4, vcc
	v_add_f32_e32 v5, v128, v25
	v_mul_f32_e32 v5, 0xbfb8aa3b, v5
	v_exp_f32_e32 v5, v5
	v_mul_f32_e32 v2, v2, v4
	v_add_f32_e32 v4, v129, v9
	v_mul_f32_e32 v4, 0xbfb8aa3b, v4
	v_add_f32_e32 v3, 1.0, v5
	v_rcp_f32_e64 v3, -v3
	v_exp_f32_e32 v4, v4
	v_mul_f32_e32 v2, v2, v6
	ds_write_b32 v147, v2
	v_mul_f32_e32 v3, v130, v3
	v_add_f32_e32 v2, 1.0, v4
	v_add_f32_e32 v4, v3, v3
	v_fmamk_f32 v5, v4, 0x3ab60b61, v218
	v_fmaak_f32 v5, v4, v5, 0x3d2aaaab
	v_fmaak_f32 v5, v4, v5, 0x3e2aaaab
	v_fma_f32 v5, v4, v5, 0.5
	v_fma_f32 v5, v4, v5, 1.0
	v_mul_f32_e64 v4, v5, -v4
	v_max_f32_e32 v4, 0, v4
	v_mul_f32_e32 v5, 0x4f800000, v4
	v_cmp_gt_f32_e32 vcc, s0, v4
	v_mul_f32_e32 v3, 0x3fb8aa3b, v3
	v_rcp_f32_e32 v2, v2
	v_cndmask_b32_e32 v4, v4, v5, vcc
	v_sqrt_f32_e32 v5, v4
	v_exp_f32_e32 v3, v3
	v_add_u32_e32 v6, -1, v5
	v_fma_f32 v7, -v6, v5, v4
	v_cmp_ge_f32_e64 s[20:21], 0, v7
	v_add_u32_e32 v7, 1, v5
	ds_write_b32 v148, v3 offset:34816
	v_cndmask_b32_e64 v6, v5, v6, s[20:21]
	v_fma_f32 v5, -v7, v5, v4
	v_cmp_lt_f32_e64 s[20:21], 0, v5
	s_nop 1
	v_cndmask_b32_e64 v5, v6, v7, s[20:21]
	v_mul_f32_e32 v6, 0x37800000, v5
	v_cndmask_b32_e32 v5, v5, v6, vcc
	v_cmp_class_f32_e32 vcc, v4, v219
	s_waitcnt lgkmcnt(14)
	v_lshlrev_b32_e32 v6, 16, v209
	v_cndmask_b32_e32 v4, v5, v4, vcc
	v_add_f32_e32 v5, v128, v26
	v_mul_f32_e32 v5, 0xbfb8aa3b, v5
	v_exp_f32_e32 v5, v5
	v_mul_f32_e32 v2, v2, v4
	v_add_f32_e32 v4, v129, v10
	v_mul_f32_e32 v4, 0xbfb8aa3b, v4
	v_add_f32_e32 v3, 1.0, v5
	v_rcp_f32_e64 v3, -v3
	v_exp_f32_e32 v4, v4
	v_mul_f32_e32 v2, v2, v6
	ds_write_b32 v149, v2
	v_mul_f32_e32 v3, v130, v3
	v_add_f32_e32 v2, 1.0, v4
	v_add_f32_e32 v4, v3, v3
	v_fmamk_f32 v5, v4, 0x3ab60b61, v218
	v_fmaak_f32 v5, v4, v5, 0x3d2aaaab
	v_fmaak_f32 v5, v4, v5, 0x3e2aaaab
	v_fma_f32 v5, v4, v5, 0.5
	v_fma_f32 v5, v4, v5, 1.0
	v_mul_f32_e64 v4, v5, -v4
	v_max_f32_e32 v4, 0, v4
	v_mul_f32_e32 v5, 0x4f800000, v4
	v_cmp_gt_f32_e32 vcc, s0, v4
	v_mul_f32_e32 v3, 0x3fb8aa3b, v3
	v_rcp_f32_e32 v2, v2
	v_cndmask_b32_e32 v4, v4, v5, vcc
	v_sqrt_f32_e32 v5, v4
	v_exp_f32_e32 v3, v3
	v_add_u32_e32 v6, -1, v5
	v_fma_f32 v7, -v6, v5, v4
	v_cmp_ge_f32_e64 s[20:21], 0, v7
	v_add_u32_e32 v7, 1, v5
	s_nop 0
	v_cndmask_b32_e64 v6, v5, v6, s[20:21]
	v_fma_f32 v5, -v7, v5, v4
	v_cmp_lt_f32_e64 s[20:21], 0, v5
	s_nop 1
	v_cndmask_b32_e64 v5, v6, v7, s[20:21]
	v_mul_f32_e32 v6, 0x37800000, v5
	v_cndmask_b32_e32 v5, v5, v6, vcc
	v_cmp_class_f32_e32 vcc, v4, v219
	ds_read_u16 v6, v193 offset:4352
	ds_read_u16 v7, v193 offset:4624
	ds_read_u16 v8, v193 offset:4896
	ds_read_u16 v9, v193 offset:5168
	ds_read_u16 v10, v193 offset:6528
	ds_read_u16 v18, v193 offset:6800
	ds_read_u16 v19, v193 offset:7072
	ds_read_u16 v20, v193 offset:7344
	v_cndmask_b32_e32 v4, v5, v4, vcc
	v_add_f32_e32 v5, v128, v27
	v_mul_f32_e32 v5, 0xbfb8aa3b, v5
	v_exp_f32_e32 v5, v5
	ds_write_b32 v150, v3 offset:34816
	v_mul_f32_e32 v2, v2, v4
	v_add_f32_e32 v4, v129, v11
	v_add_f32_e32 v3, 1.0, v5
	v_mul_f32_e32 v4, 0xbfb8aa3b, v4
	v_rcp_f32_e64 v3, -v3
	v_exp_f32_e32 v4, v4
	s_waitcnt lgkmcnt(8)
	v_lshlrev_b32_e32 v6, 16, v6
	v_mul_f32_e32 v2, v2, v6
	v_mul_f32_e32 v3, v130, v3
	ds_write_b32 v151, v2
	v_add_f32_e32 v2, 1.0, v4
	v_add_f32_e32 v4, v3, v3
	v_fmamk_f32 v5, v4, 0x3ab60b61, v218
	v_fmaak_f32 v5, v4, v5, 0x3d2aaaab
	v_fmaak_f32 v5, v4, v5, 0x3e2aaaab
	v_fma_f32 v5, v4, v5, 0.5
	v_fma_f32 v5, v4, v5, 1.0
	v_mul_f32_e64 v4, v5, -v4
	v_max_f32_e32 v4, 0, v4
	v_mul_f32_e32 v5, 0x4f800000, v4
	v_cmp_gt_f32_e32 vcc, s0, v4
	v_mul_f32_e32 v3, 0x3fb8aa3b, v3
	v_rcp_f32_e32 v2, v2
	v_cndmask_b32_e32 v4, v4, v5, vcc
	v_sqrt_f32_e32 v5, v4
	v_exp_f32_e32 v3, v3
	v_add_u32_e32 v6, -1, v5
	v_fma_f32 v11, -v6, v5, v4
	v_cmp_ge_f32_e64 s[20:21], 0, v11
	v_add_u32_e32 v11, 1, v5
	ds_write_b32 v152, v3 offset:34816
	v_cndmask_b32_e64 v6, v5, v6, s[20:21]
	v_fma_f32 v5, -v11, v5, v4
	v_cmp_lt_f32_e64 s[20:21], 0, v5
	s_nop 1
	v_cndmask_b32_e64 v5, v6, v11, s[20:21]
	v_mul_f32_e32 v6, 0x37800000, v5
	v_cndmask_b32_e32 v5, v5, v6, vcc
	v_cmp_class_f32_e32 vcc, v4, v219
	s_waitcnt lgkmcnt(9)
; #define LAS __attribute__((address_space(3)))
; __device__ __forceinline__ float fast_exp2(float x) { return __builtin_amdgcn_exp2f(x); }
; __device__ __forceinline__ float sigmoidf_(float x) { return fast_rcp(1.0f + fast_exp2(-x * LOG2E)); }
; __device__ __forceinline__ int crow(int r, int hi) { return (r & 3) + 8 * (r >> 2) + 4 * hi; }
; __device__ __forceinline__ void rglru_unit(const Params& P, int l, int unit, LAS unsigned char* lds, bool dry = false) {
;     ...
;         for (int r = 0; r < 16; ++r) { const int tok = 32 * tb + crow(r, hi);
;             const float rr = sigmoidf_(accr[r] + br), ii = sigmoidf_(acci[r] + bi);
;             const float la = -rr * sp8; const float a = fast_exp2(la * LOG2E);
;             const float x2 = 2.0f * la;
;             const float em = -x2 * (1.0f + x2 * (0.5f + x2 * (0.16666667f + x2 * (0.041666668f + x2 * (0.0083333338f + x2 * 0.0013888889f)))));
;             const float mult = __builtin_sqrtf(fmaxf(em, 0.f));
;             const float xcv = bf2f(*(const LAS unsigned short*)(xc + tok * 272 + dch * 2));
;             Ab[tok * 64 + 32 * cb + r32] = a; Ub[tok * 64 + 32 * cb + r32] = mult * ii * xcv; }
	v_lshlrev_b32_e32 v6, 16, v7
	v_cndmask_b32_e32 v4, v5, v4, vcc
	v_add_f32_e32 v5, v128, v28
	v_mul_f32_e32 v5, 0xbfb8aa3b, v5
	v_exp_f32_e32 v5, v5
	v_mul_f32_e32 v2, v2, v4
	v_add_f32_e32 v4, v129, v12
	v_mul_f32_e32 v4, 0xbfb8aa3b, v4
	v_add_f32_e32 v3, 1.0, v5
	v_rcp_f32_e64 v3, -v3
	v_exp_f32_e32 v4, v4
	v_mul_f32_e32 v2, v2, v6
	ds_write_b32 v153, v2
	v_mul_f32_e32 v3, v130, v3
	v_add_f32_e32 v2, 1.0, v4
	v_add_f32_e32 v4, v3, v3
	v_fmamk_f32 v5, v4, 0x3ab60b61, v218
	v_fmaak_f32 v5, v4, v5, 0x3d2aaaab
	v_fmaak_f32 v5, v4, v5, 0x3e2aaaab
	v_fma_f32 v5, v4, v5, 0.5
	v_fma_f32 v5, v4, v5, 1.0
	v_mul_f32_e64 v4, v5, -v4
	v_max_f32_e32 v4, 0, v4
	v_mul_f32_e32 v5, 0x4f800000, v4
	v_cmp_gt_f32_e32 vcc, s0, v4
	v_mul_f32_e32 v3, 0x3fb8aa3b, v3
	v_rcp_f32_e32 v2, v2
	v_cndmask_b32_e32 v4, v4, v5, vcc
	v_sqrt_f32_e32 v5, v4
	v_exp_f32_e32 v3, v3
	v_add_u32_e32 v6, -1, v5
	v_fma_f32 v7, -v6, v5, v4
	v_cmp_ge_f32_e64 s[20:21], 0, v7
	v_add_u32_e32 v7, 1, v5
	ds_write_b32 v154, v3 offset:34816
	v_cndmask_b32_e64 v6, v5, v6, s[20:21]
	v_fma_f32 v5, -v7, v5, v4
	v_cmp_lt_f32_e64 s[20:21], 0, v5
	s_nop 1
	v_cndmask_b32_e64 v5, v6, v7, s[20:21]
	v_mul_f32_e32 v6, 0x37800000, v5
	v_cndmask_b32_e32 v5, v5, v6, vcc
	v_cmp_class_f32_e32 vcc, v4, v219
	s_waitcnt lgkmcnt(10)
	v_lshlrev_b32_e32 v6, 16, v8
	v_cndmask_b32_e32 v4, v5, v4, vcc
	v_add_f32_e32 v5, v128, v29
	v_mul_f32_e32 v5, 0xbfb8aa3b, v5
	v_exp_f32_e32 v5, v5
	v_mul_f32_e32 v2, v2, v4
	v_add_f32_e32 v4, v129, v13
	v_mul_f32_e32 v4, 0xbfb8aa3b, v4
	v_add_f32_e32 v3, 1.0, v5
	v_rcp_f32_e64 v3, -v3
	v_exp_f32_e32 v4, v4
	v_mul_f32_e32 v2, v2, v6
	ds_write_b32 v155, v2
	v_mul_f32_e32 v3, v130, v3
	v_add_f32_e32 v2, 1.0, v4
	v_add_f32_e32 v4, v3, v3
	v_fmamk_f32 v5, v4, 0x3ab60b61, v218
	v_fmaak_f32 v5, v4, v5, 0x3d2aaaab
	v_fmaak_f32 v5, v4, v5, 0x3e2aaaab
	v_fma_f32 v5, v4, v5, 0.5
	v_fma_f32 v5, v4, v5, 1.0
	v_mul_f32_e64 v4, v5, -v4
	v_max_f32_e32 v4, 0, v4
	v_mul_f32_e32 v5, 0x4f800000, v4
	v_cmp_gt_f32_e32 vcc, s0, v4
	v_mul_f32_e32 v3, 0x3fb8aa3b, v3
	v_rcp_f32_e32 v2, v2
	v_cndmask_b32_e32 v4, v4, v5, vcc
	v_sqrt_f32_e32 v5, v4
	v_exp_f32_e32 v3, v3
	v_add_u32_e32 v6, -1, v5
	v_fma_f32 v7, -v6, v5, v4
	v_cmp_ge_f32_e64 s[20:21], 0, v7
	v_add_u32_e32 v7, 1, v5
	ds_write_b32 v156, v3 offset:34816
	v_cndmask_b32_e64 v6, v5, v6, s[20:21]
	v_fma_f32 v5, -v7, v5, v4
	v_cmp_lt_f32_e64 s[20:21], 0, v5
	s_nop 1
	v_cndmask_b32_e64 v5, v6, v7, s[20:21]
	v_mul_f32_e32 v6, 0x37800000, v5
	v_cndmask_b32_e32 v5, v5, v6, vcc
	v_cmp_class_f32_e32 vcc, v4, v219
	s_waitcnt lgkmcnt(11)
	v_lshlrev_b32_e32 v6, 16, v9
	v_cndmask_b32_e32 v4, v5, v4, vcc
	v_add_f32_e32 v5, v128, v30
	v_mul_f32_e32 v5, 0xbfb8aa3b, v5
	v_exp_f32_e32 v5, v5
	v_mul_f32_e32 v2, v2, v4
	v_add_f32_e32 v4, v129, v14
	v_mul_f32_e32 v4, 0xbfb8aa3b, v4
	v_add_f32_e32 v3, 1.0, v5
	v_rcp_f32_e64 v3, -v3
	v_exp_f32_e32 v4, v4
	v_mul_f32_e32 v2, v2, v6
	ds_write_b32 v157, v2
	v_mul_f32_e32 v3, v130, v3
	v_add_f32_e32 v2, 1.0, v4
	v_add_f32_e32 v4, v3, v3
	v_fmamk_f32 v5, v4, 0x3ab60b61, v218
	v_fmaak_f32 v5, v4, v5, 0x3d2aaaab
	v_fmaak_f32 v5, v4, v5, 0x3e2aaaab
	v_fma_f32 v5, v4, v5, 0.5
	v_fma_f32 v5, v4, v5, 1.0
	v_mul_f32_e64 v4, v5, -v4
	v_max_f32_e32 v4, 0, v4
	v_mul_f32_e32 v5, 0x4f800000, v4
	v_cmp_gt_f32_e32 vcc, s0, v4
	v_mul_f32_e32 v3, 0x3fb8aa3b, v3
	v_rcp_f32_e32 v2, v2
	v_cndmask_b32_e32 v4, v4, v5, vcc
	v_sqrt_f32_e32 v5, v4
	v_exp_f32_e32 v3, v3
	v_add_u32_e32 v6, -1, v5
	v_fma_f32 v7, -v6, v5, v4
	v_cmp_ge_f32_e64 s[20:21], 0, v7
	v_add_u32_e32 v7, 1, v5
	ds_write_b32 v158, v3 offset:34816
	v_cndmask_b32_e64 v6, v5, v6, s[20:21]
	v_fma_f32 v5, -v7, v5, v4
	v_cmp_lt_f32_e64 s[20:21], 0, v5
	s_nop 1
	v_cndmask_b32_e64 v5, v6, v7, s[20:21]
	v_mul_f32_e32 v6, 0x37800000, v5
	v_cndmask_b32_e32 v5, v5, v6, vcc
	v_cmp_class_f32_e32 vcc, v4, v219
	s_waitcnt lgkmcnt(12)
	v_lshlrev_b32_e32 v6, 16, v10
	v_cndmask_b32_e32 v4, v5, v4, vcc
	v_add_f32_e32 v5, v128, v31
	v_mul_f32_e32 v5, 0xbfb8aa3b, v5
	v_exp_f32_e32 v5, v5
	v_mul_f32_e32 v2, v2, v4
	v_add_f32_e32 v4, v129, v15
	v_mul_f32_e32 v4, 0xbfb8aa3b, v4
	v_add_f32_e32 v3, 1.0, v5
	v_rcp_f32_e64 v3, -v3
	v_exp_f32_e32 v4, v4
	v_mul_f32_e32 v2, v2, v6
	ds_write_b32 v159, v2
	v_mul_f32_e32 v3, v130, v3
	v_add_f32_e32 v2, 1.0, v4
	v_add_f32_e32 v4, v3, v3
	v_fmamk_f32 v5, v4, 0x3ab60b61, v218
	v_fmaak_f32 v5, v4, v5, 0x3d2aaaab
	v_fmaak_f32 v5, v4, v5, 0x3e2aaaab
	v_fma_f32 v5, v4, v5, 0.5
	v_fma_f32 v5, v4, v5, 1.0
	v_mul_f32_e64 v4, v5, -v4
	v_max_f32_e32 v4, 0, v4
	v_mul_f32_e32 v5, 0x4f800000, v4
	v_cmp_gt_f32_e32 vcc, s0, v4
	v_mul_f32_e32 v3, 0x3fb8aa3b, v3
	v_rcp_f32_e32 v2, v2
	v_cndmask_b32_e32 v4, v4, v5, vcc
	v_sqrt_f32_e32 v5, v4
	v_exp_f32_e32 v3, v3
	v_add_u32_e32 v6, -1, v5
	v_fma_f32 v7, -v6, v5, v4
	v_cmp_ge_f32_e64 s[20:21], 0, v7
	v_add_u32_e32 v7, 1, v5
	ds_write_b32 v160, v3 offset:34816
	v_cndmask_b32_e64 v6, v5, v6, s[20:21]
	v_fma_f32 v5, -v7, v5, v4
	v_cmp_lt_f32_e64 s[20:21], 0, v5
	s_nop 1
	v_cndmask_b32_e64 v5, v6, v7, s[20:21]
	v_mul_f32_e32 v6, 0x37800000, v5
	v_cndmask_b32_e32 v5, v5, v6, vcc
	v_cmp_class_f32_e32 vcc, v4, v219
	s_waitcnt lgkmcnt(13)
; #define LAS __attribute__((address_space(3)))
; __device__ __forceinline__ float fast_exp2(float x) { return __builtin_amdgcn_exp2f(x); }
; __device__ __forceinline__ float sigmoidf_(float x) { return fast_rcp(1.0f + fast_exp2(-x * LOG2E)); }
; __device__ __forceinline__ int crow(int r, int hi) { return (r & 3) + 8 * (r >> 2) + 4 * hi; }
; __device__ __forceinline__ void rglru_unit(const Params& P, int l, int unit, LAS unsigned char* lds, bool dry = false) {
;     ...
;         for (int r = 0; r < 16; ++r) { const int tok = 32 * tb + crow(r, hi);
;             const float rr = sigmoidf_(accr[r] + br), ii = sigmoidf_(acci[r] + bi);
;             const float la = -rr * sp8; const float a = fast_exp2(la * LOG2E);
;             const float x2 = 2.0f * la;
;             const float em = -x2 * (1.0f + x2 * (0.5f + x2 * (0.16666667f + x2 * (0.041666668f + x2 * (0.0083333338f + x2 * 0.0013888889f)))));
;             const float mult = __builtin_sqrtf(fmaxf(em, 0.f));
;             const float xcv = bf2f(*(const LAS unsigned short*)(xc + tok * 272 + dch * 2));
;             Ab[tok * 64 + 32 * cb + r32] = a; Ub[tok * 64 + 32 * cb + r32] = mult * ii * xcv; }
;         __syncthreads();
;         { const int c = sc, s = ss;
;           float As = 1.f, Hs = 0.f;
; #pragma unroll
;           for (int k = 0; k < 16; ++k) { const float a = Ab[(16 * s + k) * 64 + c], u = Ub[(16 * s + k) * 64 + c]; Hs = a * Hs + u; As *= a; }
;           seg[s * 64 + c] = (f32x2){As, Hs};
;           __syncthreads();
	v_lshlrev_b32_e32 v6, 16, v18
	v_cndmask_b32_e32 v4, v5, v4, vcc
	v_add_f32_e32 v5, v128, v32
	v_mul_f32_e32 v5, 0xbfb8aa3b, v5
	v_exp_f32_e32 v5, v5
	v_mul_f32_e32 v2, v2, v4
	v_add_f32_e32 v4, v129, v16
	v_mul_f32_e32 v4, 0xbfb8aa3b, v4
	v_add_f32_e32 v3, 1.0, v5
	v_rcp_f32_e64 v3, -v3
	v_exp_f32_e32 v4, v4
	v_mul_f32_e32 v2, v2, v6
	ds_write_b32 v161, v2
	v_mul_f32_e32 v3, v130, v3
	v_add_f32_e32 v2, 1.0, v4
	v_add_f32_e32 v4, v3, v3
	v_fmamk_f32 v5, v4, 0x3ab60b61, v218
	v_fmaak_f32 v5, v4, v5, 0x3d2aaaab
	v_fmaak_f32 v5, v4, v5, 0x3e2aaaab
	v_fma_f32 v5, v4, v5, 0.5
	v_fma_f32 v5, v4, v5, 1.0
	v_mul_f32_e64 v4, v5, -v4
	v_max_f32_e32 v4, 0, v4
	v_mul_f32_e32 v5, 0x4f800000, v4
	v_cmp_gt_f32_e32 vcc, s0, v4
	v_mul_f32_e32 v3, 0x3fb8aa3b, v3
	v_rcp_f32_e32 v2, v2
	v_cndmask_b32_e32 v4, v4, v5, vcc
	v_sqrt_f32_e32 v5, v4
	v_exp_f32_e32 v3, v3
	v_add_u32_e32 v6, -1, v5
	v_fma_f32 v7, -v6, v5, v4
	v_cmp_ge_f32_e64 s[20:21], 0, v7
	v_add_u32_e32 v7, 1, v5
	ds_write_b32 v162, v3 offset:34816
	v_cndmask_b32_e64 v6, v5, v6, s[20:21]
	v_fma_f32 v5, -v7, v5, v4
	v_cmp_lt_f32_e64 s[20:21], 0, v5
	s_nop 1
	v_cndmask_b32_e64 v5, v6, v7, s[20:21]
	v_mul_f32_e32 v6, 0x37800000, v5
	v_cndmask_b32_e32 v5, v5, v6, vcc
	v_cmp_class_f32_e32 vcc, v4, v219
	s_waitcnt lgkmcnt(14)
	v_lshlrev_b32_e32 v6, 16, v19
	v_cndmask_b32_e32 v4, v5, v4, vcc
	v_add_f32_e32 v5, v128, v33
	v_mul_f32_e32 v5, 0xbfb8aa3b, v5
	v_exp_f32_e32 v5, v5
	v_mul_f32_e32 v2, v2, v4
	v_add_f32_e32 v4, v129, v17
	v_mul_f32_e32 v4, 0xbfb8aa3b, v4
	v_add_f32_e32 v3, 1.0, v5
	v_rcp_f32_e64 v3, -v3
	v_exp_f32_e32 v4, v4
	v_mul_f32_e32 v2, v2, v6
	ds_write_b32 v163, v2
	v_mul_f32_e32 v3, v130, v3
	v_add_f32_e32 v2, 1.0, v4
	v_add_f32_e32 v4, v3, v3
	v_fmamk_f32 v5, v4, 0x3ab60b61, v218
	v_fmaak_f32 v5, v4, v5, 0x3d2aaaab
	v_fmaak_f32 v5, v4, v5, 0x3e2aaaab
	v_fma_f32 v5, v4, v5, 0.5
	v_fma_f32 v5, v4, v5, 1.0
	v_mul_f32_e64 v4, v5, -v4
	v_max_f32_e32 v4, 0, v4
	v_mul_f32_e32 v5, 0x4f800000, v4
	v_cmp_gt_f32_e32 vcc, s0, v4
	v_rcp_f32_e32 v2, v2
	v_mul_f32_e32 v3, 0x3fb8aa3b, v3
	v_cndmask_b32_e32 v4, v4, v5, vcc
	v_sqrt_f32_e32 v5, v4
	v_exp_f32_e32 v3, v3
	v_add_u32_e32 v6, -1, v5
	v_fma_f32 v7, -v6, v5, v4
	v_cmp_ge_f32_e64 s[20:21], 0, v7
	v_add_u32_e32 v7, 1, v5
	ds_write_b32 v164, v3 offset:34816
	v_cndmask_b32_e64 v6, v5, v6, s[20:21]
	v_fma_f32 v5, -v7, v5, v4
	v_cmp_lt_f32_e64 s[20:21], 0, v5
	s_nop 1
	v_cndmask_b32_e64 v5, v6, v7, s[20:21]
	v_mul_f32_e32 v6, 0x37800000, v5
	v_cndmask_b32_e32 v5, v5, v6, vcc
	v_cmp_class_f32_e32 vcc, v4, v219
	s_nop 1
	v_cndmask_b32_e32 v4, v5, v4, vcc
	s_waitcnt lgkmcnt(14)
	v_lshlrev_b32_e32 v5, 16, v20
	v_mul_f32_e32 v2, v2, v4
	v_mul_f32_e32 v2, v2, v5
	ds_write_b32 v165, v2
	s_waitcnt lgkmcnt(0)
	s_barrier
	ds_read2st64_b32 v[2:3], v133 offset0:136 offset1:137
	ds_read2st64_b32 v[4:5], v133 offset0:138 offset1:139
	ds_read2st64_b32 v[6:7], v133 offset0:140 offset1:141
	ds_read2st64_b32 v[8:9], v133 offset0:142 offset1:143
	ds_read_b32 v10, v166
	ds_read_b32 v11, v167
	ds_read_b32 v12, v168
	ds_read_b32 v13, v169
	ds_read_b32 v14, v170
	ds_read_b32 v15, v171
	ds_read_b32 v16, v172
	ds_read_b32 v18, v173
	s_waitcnt lgkmcnt(7)
	v_fmac_f32_e32 v10, 0, v2
	s_waitcnt lgkmcnt(6)
	v_fmac_f32_e32 v11, v10, v3
	s_waitcnt lgkmcnt(5)
	v_fmac_f32_e32 v12, v11, v4
	s_waitcnt lgkmcnt(4)
	v_fmac_f32_e32 v13, v12, v5
	s_waitcnt lgkmcnt(3)
	v_fmac_f32_e32 v14, v13, v6
	s_waitcnt lgkmcnt(2)
	v_fmac_f32_e32 v15, v14, v7
	s_waitcnt lgkmcnt(1)
	v_fmac_f32_e32 v16, v15, v8
	v_mul_f32_e32 v2, v2, v3
	s_waitcnt lgkmcnt(0)
	v_fmac_f32_e32 v18, v16, v9
	ds_read2st64_b32 v[10:11], v133 offset0:144 offset1:145
	ds_read2st64_b32 v[12:13], v133 offset0:146 offset1:147
	ds_read2st64_b32 v[14:15], v133 offset0:148 offset1:149
	ds_read2st64_b32 v[16:17], v133 offset0:150 offset1:151
	ds_read_b32 v3, v174
	ds_read_b32 v19, v175
	ds_read_b32 v21, v176
	ds_read_b32 v23, v177
	ds_read_b32 v25, v178
	ds_read_b32 v27, v179
	ds_read_b32 v29, v186
	ds_read_b32 v31, v187
	s_waitcnt lgkmcnt(7)
	v_fmac_f32_e32 v3, v18, v10
	v_mov_b32_e32 v32, v4
	v_mov_b32_e32 v33, v11
	v_mov_b32_e32 v18, v5
	v_mul_f32_e32 v4, v2, v4
	s_waitcnt lgkmcnt(6)
	v_pk_fma_f32 v[2:3], v[2:3], v[32:33], v[18:19]
	v_mul_f32_e32 v4, v4, v5
	v_mov_b32_e32 v5, v3
	v_mov_b32_e32 v2, v6
	v_mov_b32_e32 v3, v12
	v_pk_mul_f32 v[18:19], v[4:5], v[2:3]
	v_mov_b32_e32 v6, v7
	v_mov_b32_e32 v20, v7
	v_pk_mul_f32 v[6:7], v[18:19], v[6:7]
	s_waitcnt lgkmcnt(5)
	v_pk_fma_f32 v[2:3], v[4:5], v[2:3], v[20:21]
	v_mov_b32_e32 v4, v8
	v_mov_b32_e32 v2, v6
	v_mov_b32_e32 v5, v13
	v_pk_mul_f32 v[6:7], v[6:7], v[8:9]
	v_mov_b32_e32 v8, v9
	v_mov_b32_e32 v22, v9
	v_pk_mul_f32 v[6:7], v[6:7], v[8:9]
	s_waitcnt lgkmcnt(4)
	v_pk_fma_f32 v[2:3], v[2:3], v[4:5], v[22:23]
	v_mov_b32_e32 v8, v11
	v_mov_b32_e32 v7, v3
	v_mov_b32_e32 v2, v10
	v_mov_b32_e32 v3, v14
	v_pk_mul_f32 v[4:5], v[6:7], v[2:3]
	v_mov_b32_e32 v24, v11
	v_pk_mul_f32 v[4:5], v[4:5], v[8:9]
	s_waitcnt lgkmcnt(3)
	v_pk_fma_f32 v[2:3], v[6:7], v[2:3], v[24:25]
	v_mov_b32_e32 v6, v12
	v_mov_b32_e32 v2, v4
	v_mov_b32_e32 v7, v15
	v_pk_mul_f32 v[4:5], v[4:5], v[12:13]
	v_mov_b32_e32 v8, v13
	v_mov_b32_e32 v26, v13
	v_pk_mul_f32 v[4:5], v[4:5], v[8:9]
	s_waitcnt lgkmcnt(2)
	v_pk_fma_f32 v[2:3], v[2:3], v[6:7], v[26:27]
	v_mov_b32_e32 v8, v15
	v_mov_b32_e32 v5, v3
	v_mov_b32_e32 v2, v14
	v_mov_b32_e32 v3, v16
	v_pk_mul_f32 v[6:7], v[4:5], v[2:3]
	v_mov_b32_e32 v28, v15
	v_pk_mul_f32 v[6:7], v[6:7], v[8:9]
	s_waitcnt lgkmcnt(1)
	v_pk_fma_f32 v[2:3], v[4:5], v[2:3], v[28:29]
	v_pk_mul_f32 v[4:5], v[6:7], v[16:17]
	v_mov_b32_e32 v2, v6
	v_mov_b32_e32 v6, v17
	v_mov_b32_e32 v30, v17
	v_pk_mul_f32 v[4:5], v[4:5], v[6:7]
	s_waitcnt lgkmcnt(0)
	v_pk_fma_f32 v[2:3], v[2:3], v[16:17], v[30:31]
	s_nop 0
	v_mov_b32_e32 v5, v3
	ds_write_b64 v131, v[4:5]
	s_waitcnt lgkmcnt(0)
	s_barrier
; __device__ __forceinline__ unsigned f2bf(float f) { unsigned u = __builtin_bit_cast(unsigned, f); return (u + 0x7fffu + ((u >> 16) & 1u)) >> 16; }
; __device__ __forceinline__ void rglru_unit(const Params& P, int l, int unit, LAS unsigned char* lds, bool dry = false) {
;     ...
;           float hin = carry, hn = carry;
; #pragma unroll
;           for (int s2 = 0; s2 < 8; ++s2) { if (s2 == s) hin = hn; const f32x2 sg = seg[s2 * 64 + c]; hn = sg.x * hn + sg.y; }
;           carry = hn;
;           float h = hin;
; #pragma unroll
;           for (int k = 0; k < 16; ++k) { const float a = Ab[(16 * s + k) * 64 + c], u = Ub[(16 * s + k) * 64 + c]; h = a * h + u;
;               const float gg = bf2f(gq[k]); gp[(size_t)k * XP] = (bf16_t)f2bf(dry ? gg : gg * h); }
	ds_read2st64_b64 v[2:5], v132 offset1:1
	ds_read2st64_b64 v[6:9], v132 offset0:2 offset1:3
	s_waitcnt lgkmcnt(1)
	v_fma_f32 v2, v89, v2, v3
	v_cndmask_b32_e64 v3, v89, v2, s[6:7]
	v_fmac_f32_e32 v5, v4, v2
	v_cndmask_b32_e64 v10, v3, v5, s[8:9]
	s_waitcnt lgkmcnt(0)
	v_fma_f32 v6, v6, v5, v7
	ds_read2st64_b64 v[2:5], v132 offset0:4 offset1:5
	ds_read2st64_b64 v[86:89], v132 offset0:6 offset1:7
	v_cndmask_b32_e64 v7, v10, v6, s[10:11]
	v_fmac_f32_e32 v9, v8, v6
	v_cndmask_b32_e64 v6, v7, v9, s[12:13]
	s_waitcnt lgkmcnt(1)
	v_fma_f32 v2, v2, v9, v3
	v_cndmask_b32_e64 v3, v6, v2, s[14:15]
	v_fmac_f32_e32 v5, v4, v2
	v_cndmask_b32_e64 v2, v3, v5, s[16:17]
	s_waitcnt lgkmcnt(0)
	v_fma_f32 v10, v86, v5, v87
	v_cndmask_b32_e64 v11, v2, v10, s[18:19]
	ds_read2st64_b32 v[2:3], v133 offset0:136 offset1:137
	ds_read2st64_b32 v[4:5], v133 offset0:138 offset1:139
	ds_read2st64_b32 v[6:7], v133 offset0:140 offset1:141
	ds_read2st64_b32 v[8:9], v133 offset0:142 offset1:143
	ds_read_b32 v12, v166
	ds_read_b32 v13, v167
	ds_read_b32 v14, v168
	ds_read_b32 v15, v169
	ds_read_b32 v16, v170
	ds_read_b32 v17, v171
	ds_read_b32 v18, v172
	ds_read_b32 v19, v173
	s_waitcnt lgkmcnt(7)
	v_fmac_f32_e32 v12, v2, v11
	v_lshlrev_b32_e32 v2, 16, v207
	v_mul_f32_e32 v2, v12, v2
	v_bfe_u32 v11, v2, 16, 1
	v_add3_u32 v2, v2, v11, s60
	global_store_short_d16_hi v[126:127], v2, off
	s_waitcnt lgkmcnt(0)
	v_fmac_f32_e32 v13, v3, v12
	v_lshlrev_b32_e32 v2, 16, v206
	v_mul_f32_e32 v2, v13, v2
	v_bfe_u32 v3, v2, 16, 1
	v_add3_u32 v2, v2, v3, s60
	global_store_short_d16_hi v[126:127], v2, off offset:2048
	v_fmac_f32_e32 v14, v4, v13
	v_lshlrev_b32_e32 v2, 16, v205
	v_mul_f32_e32 v2, v14, v2
	v_bfe_u32 v3, v2, 16, 1
	v_add3_u32 v2, v2, v3, s60
	global_store_short_d16_hi v[124:125], v2, off
	v_fmac_f32_e32 v15, v5, v14
	v_lshlrev_b32_e32 v2, 16, v204
	v_mul_f32_e32 v2, v15, v2
	v_bfe_u32 v3, v2, 16, 1
	v_add3_u32 v2, v2, v3, s60
	global_store_short_d16_hi v[124:125], v2, off offset:2048
	v_fmac_f32_e32 v16, v6, v15
	v_lshlrev_b32_e32 v2, 16, v203
	v_mul_f32_e32 v2, v16, v2
	v_bfe_u32 v3, v2, 16, 1
	v_add3_u32 v2, v2, v3, s60
	global_store_short_d16_hi v[122:123], v2, off
	v_fmac_f32_e32 v17, v7, v16
	v_lshlrev_b32_e32 v2, 16, v202
	v_mul_f32_e32 v2, v17, v2
	v_bfe_u32 v3, v2, 16, 1
	v_add3_u32 v2, v2, v3, s60
	global_store_short_d16_hi v[122:123], v2, off offset:2048
	v_fmac_f32_e32 v18, v8, v17
	v_lshlrev_b32_e32 v2, 16, v201
	v_mul_f32_e32 v2, v18, v2
	v_bfe_u32 v3, v2, 16, 1
	v_add3_u32 v2, v2, v3, s60
	global_store_short_d16_hi v[120:121], v2, off
	v_fmac_f32_e32 v19, v9, v18
	v_lshlrev_b32_e32 v2, 16, v200
	v_mul_f32_e32 v2, v19, v2
	v_bfe_u32 v3, v2, 16, 1
	v_add3_u32 v2, v2, v3, s60
	global_store_short_d16_hi v[120:121], v2, off offset:2048
	ds_read2st64_b32 v[2:3], v133 offset0:144 offset1:145
	ds_read2st64_b32 v[4:5], v133 offset0:146 offset1:147
	ds_read2st64_b32 v[6:7], v133 offset0:148 offset1:149
	ds_read2st64_b32 v[8:9], v133 offset0:150 offset1:151
	ds_read_b32 v11, v174
	ds_read_b32 v12, v175
	ds_read_b32 v13, v176
	ds_read_b32 v14, v177
	ds_read_b32 v15, v178
	ds_read_b32 v16, v179
	ds_read_b32 v17, v186
	ds_read_b32 v18, v187
	s_waitcnt lgkmcnt(0)
	v_fmac_f32_e32 v11, v19, v2
	v_lshlrev_b32_e32 v2, 16, v199
	v_mul_f32_e32 v2, v11, v2
	v_bfe_u32 v19, v2, 16, 1
	v_add3_u32 v2, v2, v19, s60
	global_store_short_d16_hi v[118:119], v2, off
	v_fmac_f32_e32 v12, v11, v3
	v_lshlrev_b32_e32 v2, 16, v198
	v_mul_f32_e32 v2, v12, v2
	v_bfe_u32 v3, v2, 16, 1
	v_add3_u32 v2, v2, v3, s60
	global_store_short_d16_hi v[118:119], v2, off offset:2048
	v_fmac_f32_e32 v13, v12, v4
	v_lshlrev_b32_e32 v2, 16, v197
	v_mul_f32_e32 v2, v13, v2
	v_bfe_u32 v3, v2, 16, 1
	v_add3_u32 v2, v2, v3, s60
	global_store_short_d16_hi v[116:117], v2, off
	v_fmac_f32_e32 v14, v13, v5
	v_lshlrev_b32_e32 v2, 16, v196
	v_mul_f32_e32 v2, v14, v2
	v_bfe_u32 v3, v2, 16, 1
	v_add3_u32 v2, v2, v3, s60
	global_store_short_d16_hi v[116:117], v2, off offset:2048
	v_fmac_f32_e32 v15, v14, v6
	v_lshlrev_b32_e32 v2, 16, v195
	v_mul_f32_e32 v2, v15, v2
	v_bfe_u32 v3, v2, 16, 1
	v_add3_u32 v2, v2, v3, s60
	global_store_short_d16_hi v[114:115], v2, off
	v_fmac_f32_e32 v16, v15, v7
	v_lshlrev_b32_e32 v2, 16, v194
	v_mul_f32_e32 v2, v16, v2
	v_bfe_u32 v3, v2, 16, 1
	v_add3_u32 v2, v2, v3, s60
	global_store_short_d16_hi v[114:115], v2, off offset:2048
	v_fmac_f32_e32 v17, v16, v8
	v_lshlrev_b32_e32 v2, 16, v111
	v_mul_f32_e32 v2, v17, v2
	v_bfe_u32 v3, v2, 16, 1
	v_fmac_f32_e32 v18, v17, v9
	v_add3_u32 v2, v2, v3, s60
	v_mul_f32_e32 v1, v18, v1
	global_store_short_d16_hi v[112:113], v2, off
	v_bfe_u32 v2, v1, 16, 1
	v_add3_u32 v1, v1, v2, s60
	v_fmac_f32_e32 v89, v88, v10
	global_store_short_d16_hi v[112:113], v1, off offset:2048
	s_cbranch_scc0 .LBB0_346
; #define LAS __attribute__((address_space(3)))
; __device__ __forceinline__ unsigned pk2(float lo, float hi) { return f2bf(lo) | (f2bf(hi) << 16); }
; __device__ __forceinline__ void rglru_unit(const Params& P, int l, int unit, LAS unsigned char* lds, bool dry = false) {
;     ...
;             float xv[7][8];
; #pragma unroll
;             for (int k = 0; k < 7; ++k) { const u32x4 w = xw[k];
;                 xv[k][0] = bflo(w.x); xv[k][1] = bfhi(w.x); xv[k][2] = bflo(w.y); xv[k][3] = bfhi(w.y); xv[k][4] = bflo(w.z); xv[k][5] = bfhi(w.z); xv[k][6] = bflo(w.w); xv[k][7] = bfhi(w.w); }
; #pragma unroll
;             for (int i = 0; i < 4; ++i) { float o[8];
; #pragma unroll
;                 for (int e = 0; e < 8; ++e) o[e] = cbias[e] + cw[0][e] * xv[i][e] + cw[1][e] * xv[i + 1][e] + cw[2][e] * xv[i + 2][e] + cw[3][e] * xv[i + 3][e];
;                 u32x4 w; w.x = pk2(o[0], o[1]); w.y = pk2(o[2], o[3]); w.z = pk2(o[4], o[5]); w.w = pk2(o[6], o[7]);
;                 *(LAS u32x4*)(xc + (4 * rg + i) * 272 + cc * 16) = w; }
.LBB0_368:
	s_waitcnt lgkmcnt(0)
	v_and_b32_e32 v4, 0xffff0000, v74
	v_and_b32_e32 v5, 0xffff0000, v75
	v_and_b32_e32 v8, 0xffff0000, v76
	v_and_b32_e32 v9, 0xffff0000, v77
	v_lshlrev_b32_e32 v2, 16, v74
	v_lshlrev_b32_e32 v3, 16, v75
	v_lshlrev_b32_e32 v6, 16, v76
	v_lshlrev_b32_e32 v7, 16, v77
	v_and_b32_e32 v13, 0xffff0000, v79
	v_and_b32_e32 v12, 0xffff0000, v78
	v_pk_fma_f32 v[4:5], v[48:49], v[4:5], v[40:41]
	v_and_b32_e32 v25, 0xffff0000, v81
	v_and_b32_e32 v24, 0xffff0000, v80
	v_pk_fma_f32 v[8:9], v[44:45], v[8:9], v[36:37]
	v_lshlrev_b32_e32 v11, 16, v79
	v_lshlrev_b32_e32 v10, 16, v78
	v_and_b32_e32 v17, 0xffff0000, v83
	v_and_b32_e32 v16, 0xffff0000, v82
	v_pk_fma_f32 v[2:3], v[46:47], v[2:3], v[38:39]
	v_pk_fma_f32 v[4:5], v[52:53], v[12:13], v[4:5]
	v_lshlrev_b32_e32 v23, 16, v81
	v_lshlrev_b32_e32 v22, 16, v80
	v_and_b32_e32 v29, 0xffff0000, v85
	v_and_b32_e32 v28, 0xffff0000, v84
	v_pk_fma_f32 v[6:7], v[42:43], v[6:7], v[34:35]
	v_pk_fma_f32 v[8:9], v[60:61], v[24:25], v[8:9]
	v_lshlrev_b32_e32 v15, 16, v83
	v_lshlrev_b32_e32 v14, 16, v82
	v_and_b32_e32 v21, 0xffff0000, v91
	v_and_b32_e32 v20, 0xffff0000, v90
	v_pk_fma_f32 v[2:3], v[50:51], v[10:11], v[2:3]
	v_pk_fma_f32 v[4:5], v[56:57], v[16:17], v[4:5]
	v_lshlrev_b32_e32 v27, 16, v85
	v_lshlrev_b32_e32 v26, 16, v84
	v_and_b32_e32 v33, 0xffff0000, v93
	v_and_b32_e32 v32, 0xffff0000, v92
	v_pk_fma_f32 v[6:7], v[58:59], v[22:23], v[6:7]
	v_pk_fma_f32 v[8:9], v[64:65], v[28:29], v[8:9]
	v_lshlrev_b32_e32 v19, 16, v91
	v_lshlrev_b32_e32 v18, 16, v90
	v_pk_fma_f32 v[2:3], v[54:55], v[14:15], v[2:3]
	v_pk_fma_f32 v[4:5], v[68:69], v[20:21], v[4:5]
	v_lshlrev_b32_e32 v31, 16, v93
	v_lshlrev_b32_e32 v30, 16, v92
	v_pk_fma_f32 v[6:7], v[62:63], v[26:27], v[6:7]
	v_pk_fma_f32 v[8:9], v[72:73], v[32:33], v[8:9]
	v_pk_fma_f32 v[2:3], v[66:67], v[18:19], v[2:3]
	v_pk_fma_f32 v[6:7], v[70:71], v[30:31], v[6:7]
	v_bfe_u32 v1, v9, 16, 1
	v_bfe_u32 v86, v8, 16, 1
	v_bfe_u32 v87, v5, 16, 1
	v_bfe_u32 v88, v4, 16, 1
	v_add3_u32 v88, v4, v88, s60
	v_add3_u32 v87, v5, v87, s60
	v_add3_u32 v4, v8, v86, s60
	v_add3_u32 v1, v9, v1, s60
	v_bfe_u32 v5, v2, 16, 1
	v_bfe_u32 v8, v3, 16, 1
	v_bfe_u32 v9, v6, 16, 1
	v_bfe_u32 v86, v7, 16, 1
	v_add3_u32 v7, v7, v86, s60
	v_add3_u32 v6, v6, v9, s60
	v_add3_u32 v3, v3, v8, s60
	v_add3_u32 v2, v2, v5, s60
	v_lshrrev_b32_e32 v2, 16, v2
	v_lshrrev_b32_e32 v3, 16, v3
	v_lshrrev_b32_e32 v6, 16, v6
	v_lshrrev_b32_e32 v5, 16, v7
	v_and_or_b32 v5, v1, s61, v5
	v_and_or_b32 v4, v4, s61, v6
	v_and_or_b32 v3, v87, s61, v3
	v_and_or_b32 v2, v88, s61, v2
	ds_write_b128 v188, v[2:5]
	v_pk_fma_f32 v[4:5], v[48:49], v[12:13], v[40:41]
	v_pk_fma_f32 v[24:25], v[44:45], v[24:25], v[36:37]
	v_pk_fma_f32 v[2:3], v[46:47], v[10:11], v[38:39]
	v_pk_fma_f32 v[4:5], v[52:53], v[16:17], v[4:5]
	v_pk_fma_f32 v[22:23], v[42:43], v[22:23], v[34:35]
	v_pk_fma_f32 v[24:25], v[60:61], v[28:29], v[24:25]
	v_and_b32_e32 v9, 0xffff0000, v95
	v_and_b32_e32 v8, 0xffff0000, v94
	v_pk_fma_f32 v[2:3], v[50:51], v[14:15], v[2:3]
	v_pk_fma_f32 v[4:5], v[56:57], v[20:21], v[4:5]
	v_and_b32_e32 v13, 0xffff0000, v97
	v_and_b32_e32 v12, 0xffff0000, v96
	v_pk_fma_f32 v[22:23], v[58:59], v[26:27], v[22:23]
	v_pk_fma_f32 v[24:25], v[64:65], v[32:33], v[24:25]
	v_lshlrev_b32_e32 v7, 16, v95
	v_lshlrev_b32_e32 v6, 16, v94
	v_pk_fma_f32 v[2:3], v[54:55], v[18:19], v[2:3]
	v_pk_fma_f32 v[4:5], v[68:69], v[8:9], v[4:5]
	v_lshlrev_b32_e32 v11, 16, v97
	v_lshlrev_b32_e32 v10, 16, v96
	v_pk_fma_f32 v[22:23], v[62:63], v[30:31], v[22:23]
	v_pk_fma_f32 v[24:25], v[72:73], v[12:13], v[24:25]
	v_pk_fma_f32 v[2:3], v[66:67], v[6:7], v[2:3]
	v_pk_fma_f32 v[22:23], v[70:71], v[10:11], v[22:23]
	v_bfe_u32 v1, v25, 16, 1
	v_bfe_u32 v86, v24, 16, 1
	v_bfe_u32 v87, v5, 16, 1
	v_bfe_u32 v88, v4, 16, 1
	v_add3_u32 v88, v4, v88, s60
	v_add3_u32 v87, v5, v87, s60
	v_add3_u32 v4, v24, v86, s60
	v_add3_u32 v1, v25, v1, s60
	v_bfe_u32 v5, v2, 16, 1
	v_bfe_u32 v24, v3, 16, 1
	v_bfe_u32 v25, v22, 16, 1
	v_bfe_u32 v86, v23, 16, 1
	v_add3_u32 v23, v23, v86, s60
	v_add3_u32 v22, v22, v25, s60
	v_add3_u32 v3, v3, v24, s60
	v_add3_u32 v2, v2, v5, s60
	v_lshrrev_b32_e32 v2, 16, v2
	v_lshrrev_b32_e32 v3, 16, v3
	v_lshrrev_b32_e32 v22, 16, v22
	v_lshrrev_b32_e32 v5, 16, v23
	v_and_or_b32 v5, v1, s61, v5
	v_and_or_b32 v4, v4, s61, v22
	v_and_or_b32 v3, v87, s61, v3
	v_and_or_b32 v2, v88, s61, v2
	ds_write_b128 v189, v[2:5]
	v_pk_fma_f32 v[4:5], v[48:49], v[16:17], v[40:41]
	v_pk_fma_f32 v[28:29], v[44:45], v[28:29], v[36:37]
	v_pk_fma_f32 v[2:3], v[46:47], v[14:15], v[38:39]
	v_pk_fma_f32 v[4:5], v[52:53], v[20:21], v[4:5]
	v_pk_fma_f32 v[26:27], v[42:43], v[26:27], v[34:35]
	v_pk_fma_f32 v[28:29], v[60:61], v[32:33], v[28:29]
	v_and_b32_e32 v25, 0xffff0000, v99
	v_and_b32_e32 v24, 0xffff0000, v98
	v_pk_fma_f32 v[2:3], v[50:51], v[18:19], v[2:3]
	v_pk_fma_f32 v[4:5], v[56:57], v[8:9], v[4:5]
	v_and_b32_e32 v17, 0xffff0000, v101
	v_and_b32_e32 v16, 0xffff0000, v100
	v_pk_fma_f32 v[26:27], v[58:59], v[30:31], v[26:27]
	v_pk_fma_f32 v[28:29], v[64:65], v[12:13], v[28:29]
	v_lshlrev_b32_e32 v23, 16, v99
	v_lshlrev_b32_e32 v22, 16, v98
	v_pk_fma_f32 v[2:3], v[54:55], v[6:7], v[2:3]
	v_pk_fma_f32 v[4:5], v[68:69], v[24:25], v[4:5]
	v_lshlrev_b32_e32 v15, 16, v101
	v_lshlrev_b32_e32 v14, 16, v100
	v_pk_fma_f32 v[26:27], v[62:63], v[10:11], v[26:27]
	v_pk_fma_f32 v[28:29], v[72:73], v[16:17], v[28:29]
	v_pk_fma_f32 v[2:3], v[66:67], v[22:23], v[2:3]
	v_pk_fma_f32 v[26:27], v[70:71], v[14:15], v[26:27]
	v_bfe_u32 v1, v29, 16, 1
	v_bfe_u32 v86, v28, 16, 1
; #define LAS __attribute__((address_space(3)))
; __device__ __forceinline__ unsigned pk2(float lo, float hi) { return f2bf(lo) | (f2bf(hi) << 16); }
; #define RG_XLOAD(T0) do { _Pragma("unroll") for (int k = 0; k < 7; ++k) { const int t = (T0) + 4 * rg - 3 + k; xw[k] = (u32x4){0u, 0u, 0u, 0u}; \
;         if (t >= 0) xw[k] = *(const u32x4*)(proj + O_XR + (rowb + t) * XP + 128 * n + 8 * cc); } } while (0)
; __device__ __forceinline__ void rglru_unit(const Params& P, int l, int unit, LAS unsigned char* lds, bool dry = false) {
;     ...
;             for (int i = 0; i < 4; ++i) { float o[8];
; #pragma unroll
;                 for (int e = 0; e < 8; ++e) o[e] = cbias[e] + cw[0][e] * xv[i][e] + cw[1][e] * xv[i + 1][e] + cw[2][e] * xv[i + 2][e] + cw[3][e] * xv[i + 3][e];
;                 u32x4 w; w.x = pk2(o[0], o[1]); w.y = pk2(o[2], o[3]); w.z = pk2(o[4], o[5]); w.w = pk2(o[6], o[7]);
;                 *(LAS u32x4*)(xc + (4 * rg + i) * 272 + cc * 16) = w; }
;         }
;         if (tile + 1 < SEQ / 128) RG_XLOAD(t0 + 128);
	v_bfe_u32 v87, v5, 16, 1
	v_bfe_u32 v88, v4, 16, 1
	v_add3_u32 v88, v4, v88, s60
	v_add3_u32 v87, v5, v87, s60
	v_add3_u32 v4, v28, v86, s60
	v_add3_u32 v1, v29, v1, s60
	v_bfe_u32 v5, v2, 16, 1
	v_bfe_u32 v28, v3, 16, 1
	v_bfe_u32 v29, v26, 16, 1
	v_bfe_u32 v86, v27, 16, 1
	v_add3_u32 v27, v27, v86, s60
	v_add3_u32 v26, v26, v29, s60
	v_add3_u32 v3, v3, v28, s60
	v_add3_u32 v2, v2, v5, s60
	v_lshrrev_b32_e32 v2, 16, v2
	v_lshrrev_b32_e32 v3, 16, v3
	v_lshrrev_b32_e32 v26, 16, v26
	v_lshrrev_b32_e32 v5, 16, v27
	v_pk_fma_f32 v[18:19], v[46:47], v[18:19], v[38:39]
	v_and_or_b32 v5, v1, s61, v5
	v_and_or_b32 v4, v4, s61, v26
	v_and_or_b32 v3, v87, s61, v3
	v_and_or_b32 v2, v88, s61, v2
	v_pk_fma_f32 v[6:7], v[50:51], v[6:7], v[18:19]
	ds_write_b128 v189, v[2:5] offset:272
	v_lshlrev_b32_e32 v3, 16, v103
	v_lshlrev_b32_e32 v2, 16, v102
	v_pk_fma_f32 v[6:7], v[54:55], v[22:23], v[6:7]
	v_pk_fma_f32 v[18:19], v[42:43], v[30:31], v[34:35]
	v_pk_fma_f32 v[2:3], v[66:67], v[2:3], v[6:7]
	v_pk_fma_f32 v[6:7], v[48:49], v[20:21], v[40:41]
	v_and_b32_e32 v5, 0xffff0000, v103
	v_pk_fma_f32 v[6:7], v[52:53], v[8:9], v[6:7]
	v_and_b32_e32 v4, 0xffff0000, v102
	v_pk_fma_f32 v[6:7], v[56:57], v[24:25], v[6:7]
	v_pk_fma_f32 v[10:11], v[58:59], v[10:11], v[18:19]
	v_pk_fma_f32 v[4:5], v[68:69], v[4:5], v[6:7]
	v_lshlrev_b32_e32 v7, 16, v105
	v_lshlrev_b32_e32 v6, 16, v104
	v_pk_fma_f32 v[10:11], v[62:63], v[14:15], v[10:11]
	v_and_b32_e32 v9, 0xffff0000, v105
	v_pk_fma_f32 v[6:7], v[70:71], v[6:7], v[10:11]
	v_pk_fma_f32 v[10:11], v[44:45], v[32:33], v[36:37]
	v_and_b32_e32 v8, 0xffff0000, v104
	v_pk_fma_f32 v[10:11], v[60:61], v[12:13], v[10:11]
	v_bfe_u32 v12, v4, 16, 1
	v_pk_fma_f32 v[10:11], v[64:65], v[16:17], v[10:11]
	v_add3_u32 v12, v4, v12, s60
	v_pk_fma_f32 v[8:9], v[72:73], v[8:9], v[10:11]
	v_bfe_u32 v11, v5, 16, 1
	v_bfe_u32 v1, v9, 16, 1
	v_bfe_u32 v10, v8, 16, 1
	v_add3_u32 v11, v5, v11, s60
	v_add3_u32 v4, v8, v10, s60
	v_add3_u32 v1, v9, v1, s60
	v_bfe_u32 v5, v2, 16, 1
	v_bfe_u32 v8, v3, 16, 1
	v_bfe_u32 v9, v6, 16, 1
	v_bfe_u32 v10, v7, 16, 1
	v_add3_u32 v7, v7, v10, s60
	v_add3_u32 v6, v6, v9, s60
	v_add3_u32 v3, v3, v8, s60
	v_add3_u32 v2, v2, v5, s60
	v_lshrrev_b32_e32 v2, 16, v2
	v_lshrrev_b32_e32 v3, 16, v3
	v_lshrrev_b32_e32 v6, 16, v6
	v_lshrrev_b32_e32 v5, 16, v7
	v_and_or_b32 v5, v1, s61, v5
	v_and_or_b32 v4, v4, s61, v6
	v_and_or_b32 v3, v11, s61, v3
	v_and_or_b32 v2, v12, s61, v2
	s_cmp_eq_u32 s22, 0x3c0000
	ds_write_b128 v189, v[2:5] offset:544
	s_cbranch_scc1 .LBB0_367
	v_mov_b32_e32 v78, v0
	v_mov_b32_e32 v79, v0
	v_add_u32_e32 v4, -6, v110
	v_mov_b32_e32 v80, v0
	v_mov_b32_e32 v81, v0
	v_mov_b64_e32 v[74:75], v[78:79]
	v_cmp_lt_i32_e32 vcc, -1, v4
	v_mov_b64_e32 v[76:77], v[80:81]
	s_and_saveexec_b64 s[20:21], vcc
	s_cbranch_execz .LBB0_371
	v_mov_b32_e32 v5, v0
	v_lshl_add_u64 v[2:3], s[2:3], 0, v[4:5]
	v_lshlrev_b64 v[2:3], 11, v[2:3]
	v_lshl_add_u64 v[2:3], v[106:107], 0, v[2:3]
	global_load_dwordx4 v[74:77], v[2:3], off
.LBB0_371:
	s_or_b64 exec, exec, s[20:21]
	v_cmp_lt_i32_e64 s[20:21], -2, v4
	s_and_saveexec_b64 s[24:25], s[20:21]
	s_cbranch_execz .LBB0_373
	v_add_u32_e32 v2, -5, v110
	v_mov_b32_e32 v3, v0
	v_lshl_add_u64 v[2:3], s[2:3], 0, v[2:3]
	v_lshlrev_b64 v[2:3], 11, v[2:3]
	v_lshl_add_u64 v[2:3], v[106:107], 0, v[2:3]
	global_load_dwordx4 v[78:81], v[2:3], off
.LBB0_373:
	s_or_b64 exec, exec, s[24:25]
	v_mov_b32_e32 v2, v0
	v_mov_b32_e32 v3, v0
	v_mov_b32_e32 v1, v0
	v_mov_b64_e32 v[84:85], v[2:3]
	v_mov_b64_e32 v[82:83], v[0:1]
	s_and_saveexec_b64 s[20:21], vcc
	s_cbranch_execz .LBB0_375
	v_add_u32_e32 v6, -4, v110
	v_mov_b32_e32 v7, v0
	v_lshl_add_u64 v[6:7], s[2:3], 0, v[6:7]
	v_lshlrev_b64 v[6:7], 11, v[6:7]
	v_lshl_add_u64 v[6:7], v[106:107], 0, v[6:7]
	global_load_dwordx4 v[82:85], v[6:7], off
.LBB0_375:
	s_or_b64 exec, exec, s[20:21]
	v_mov_b64_e32 v[92:93], v[2:3]
	v_cmp_lt_i32_e32 vcc, -4, v4
	v_mov_b64_e32 v[90:91], v[0:1]
	s_and_saveexec_b64 s[20:21], vcc
	s_cbranch_execz .LBB0_377
	v_add_u32_e32 v2, -3, v110
	v_mov_b32_e32 v3, v0
	v_lshl_add_u64 v[2:3], s[2:3], 0, v[2:3]
	v_lshlrev_b64 v[2:3], 11, v[2:3]
	v_lshl_add_u64 v[2:3], v[106:107], 0, v[2:3]
	global_load_dwordx4 v[90:93], v[2:3], off
.LBB0_377:
	s_or_b64 exec, exec, s[20:21]
	v_mov_b32_e32 v2, v0
	v_mov_b32_e32 v3, v0
	v_mov_b32_e32 v1, v0
	v_mov_b64_e32 v[96:97], v[2:3]
	v_cmp_lt_i32_e32 vcc, -5, v4
	v_mov_b64_e32 v[94:95], v[0:1]
	s_and_saveexec_b64 s[20:21], vcc
	s_cbranch_execz .LBB0_379
	v_add_u32_e32 v6, -2, v110
	v_mov_b32_e32 v7, v0
	v_lshl_add_u64 v[6:7], s[2:3], 0, v[6:7]
	v_lshlrev_b64 v[6:7], 11, v[6:7]
	v_lshl_add_u64 v[6:7], v[106:107], 0, v[6:7]
	global_load_dwordx4 v[94:97], v[6:7], off
.LBB0_379:
	s_or_b64 exec, exec, s[20:21]
	v_mov_b64_e32 v[100:101], v[2:3]
	v_cmp_lt_i32_e32 vcc, -6, v4
	v_mov_b64_e32 v[98:99], v[0:1]
	s_and_saveexec_b64 s[20:21], vcc
	s_cbranch_execz .LBB0_381
	v_add_u32_e32 v2, -1, v110
	v_mov_b32_e32 v3, v0
	v_lshl_add_u64 v[2:3], s[2:3], 0, v[2:3]
	v_lshlrev_b64 v[2:3], 11, v[2:3]
	v_lshl_add_u64 v[2:3], v[106:107], 0, v[2:3]
	global_load_dwordx4 v[98:101], v[2:3], off
.LBB0_381:
	s_or_b64 exec, exec, s[20:21]
	v_cmp_lt_i32_e32 vcc, -7, v4
	v_mov_b32_e32 v105, 0
	v_mov_b32_e32 v104, 0
	v_mov_b32_e32 v103, 0
	v_mov_b32_e32 v102, 0
	s_and_saveexec_b64 s[20:21], vcc
	s_cbranch_execz .LBB0_366
	v_mov_b32_e32 v111, v0
	v_lshl_add_u64 v[2:3], s[2:3], 0, v[110:111]
	v_lshlrev_b64 v[2:3], 11, v[2:3]
	v_lshl_add_u64 v[2:3], v[106:107], 0, v[2:3]
	global_load_dwordx4 v[102:105], v[2:3], off
	s_branch .LBB0_366

; #define LAS __attribute__((address_space(3)))
; #define DIFF_GLOADK(t) do { _Pragma("unroll") for (int i = 0; i < 2; ++i) kreg[i] = *(const u32x4*)(sbase + O_DK + (size_t)(64 * (t) + 32 * i) * QP); } while (0)
; #define DIFF_GLOADV(t) do { _Pragma("unroll") for (int i = 0; i < 2; ++i) vreg[i] = *(const u32x4*)(sbase + O_DV + (size_t)(64 * (t) + 32 * i) * QP); } while (0)
; #define DIFF_LSTOREK(buf) do { _Pragma("unroll") for (int i = 0; i < 2; ++i) *(LAS u32x4*)(lds + (buf) * BUFB + KOFF + (srow + 32 * i) * 272 + sch * 16) = kreg[i]; } while (0)
; #define DIFF_LSTOREV(buf) do { _Pragma("unroll") for (int i = 0; i < 2; ++i) *(LAS u32x4*)(lds + (buf) * BUFB + VOFF + (srow + 32 * i) * DVS + sch * 16) = vreg[i]; } while (0)
; __device__ __forceinline__ void diff_unit(const Params& P, int l, int b, int h, int qb, float lam, float lam_init, LAS unsigned char* lds, bool dry = false) {
;     ...
;     LAS unsigned char* qlds = lds + 79872 + wid * 4608 + r32 * 144 + hi * 16;
;     { const bf16_t* Qw = proj + O_DQ + (rowb + q0 + wq * 32 + r32) * QP + h * 128 + map * 64;
; #pragma unroll
;       for (int d0 = 0; d0 < 4; ++d0) *(LAS bf16x8*)(qlds + d0 * 32) = *(const bf16x8*)(Qw + d0 * 16 + hi * 8); }
;     ...
;     f32x16 o[4];
; #pragma unroll
;     for (int d = 0; d < 4; ++d) o[d] = f32x16{};
;     float mref = 0.f, lrun = 0.f;
;     const int NT = 2 * (qb + 1);
;     u32x4 kreg[2], vreg[2];
;     const int srow = tid >> 4, sch = tid & 15;
;     const bf16_t* sbase = proj + (rowb + srow) * QP + h * 128 + sch * 8;
;     ...
;     const int qme = q0 + wq * 32 + r32;
;     ...
;     DIFF_GLOADK(0); DIFF_GLOADV(0); DIFF_LSTOREK(0); DIFF_LSTOREV(0);
;     DIFF_GLOADK(1); DIFF_LSTOREK(1);
;     __syncthreads();
;     const float b31 = bt[127];
.LBB0_392:
	s_or_b64 exec, exec, s[4:5]
	s_ashr_i32 s6, s73, 6
	s_ashr_i32 s48, s57, 5
	s_and_b32 s74, s6, 3
	s_mulk_i32 s6, 0x1200
	s_and_b32 s71, s57, 7
	s_ashr_i32 s49, s48, 31
	s_add_i32 s6, s6, 0
	s_ashr_i32 s78, s73, 8
	s_lshl_b64 s[4:5], s[48:49], 11
	s_lshl_b32 s7, s71, 7
	s_add_i32 s6, s6, 0x13800
	s_add_u32 s90, s2, 0xee00000
	s_addc_u32 s91, s3, 0
	s_lshl_b32 s81, s74, 5
	s_or_b32 s52, s81, s7
	s_waitcnt vmcnt(0)
	v_and_b32_e32 v167, 31, v160
	s_or_b32 s50, s4, s52
	v_or_b32_e32 v2, s50, v167
	v_mov_b32_e32 v3, s5
	v_mov_b32_e32 v1, s6
	s_movk_i32 s6, 0x90
	v_lshlrev_b64 v[2:3], 10, v[2:3]
	v_mad_u32_u24 v1, v167, s6, v1
	v_lshl_add_u64 v[2:3], s[90:91], 0, v[2:3]
	s_lshl_b32 s96, s70, 8
	s_lshl_b32 s6, s78, 6
	v_bfe_u32 v166, v160, 5, 1
	v_lshl_add_u64 v[2:3], v[2:3], 0, s[96:97]
	s_ashr_i32 s7, s6, 31
	v_lshlrev_b32_e32 v156, 4, v166
	v_lshl_add_u64 v[2:3], s[6:7], 1, v[2:3]
	v_mov_b32_e32 v157, v0
	v_lshl_add_u64 v[6:7], v[2:3], 0, v[156:157]
	global_load_dwordx4 v[2:5], v[6:7], off
	v_add_u32_e32 v35, v1, v156
	v_ashrrev_i32_e32 v162, 4, v160
	v_ashrrev_i32_e32 v163, 31, v162
	v_lshlrev_b32_e32 v1, 4, v160
	v_and_b32_e32 v158, 0xf0, v1
	v_mov_b32_e32 v159, v0
	s_mov_b32 s6, 0x10e00000
	v_add_u32_e32 v175, 0, v158
	v_or_b32_e32 v168, s52, v167
	s_cmpk_lt_u32 s52, 0xb0
	v_lshlrev_b32_e32 v157, 2, v166
	s_waitcnt vmcnt(0) lgkmcnt(0)
	ds_write_b128 v35, v[2:5]
	global_load_dwordx4 v[2:5], v[6:7], off offset:32
	s_waitcnt vmcnt(0) lgkmcnt(0)
	ds_write_b128 v35, v[2:5] offset:32
	global_load_dwordx4 v[2:5], v[6:7], off offset:64
	s_waitcnt vmcnt(0) lgkmcnt(0)
	ds_write_b128 v35, v[2:5] offset:64
	global_load_dwordx4 v[2:5], v[6:7], off offset:96
	s_waitcnt vmcnt(0) lgkmcnt(0)
	ds_write_b128 v35, v[2:5] offset:96
	v_lshl_add_u64 v[2:3], s[4:5], 0, v[162:163]
	v_lshlrev_b64 v[2:3], 10, v[2:3]
	v_lshl_add_u64 v[2:3], s[2:3], 0, v[2:3]
	v_lshl_add_u64 v[2:3], v[2:3], 0, s[96:97]
	v_lshl_add_u64 v[14:15], v[2:3], 0, v[158:159]
	v_add_co_u32_e32 v2, vcc, s6, v14
	s_mov_b32 s6, 0x10e08000
	s_nop 0
	v_addc_co_u32_e32 v3, vcc, 0, v15, vcc
	v_add_co_u32_e32 v6, vcc, s6, v14
	s_mov_b32 s6, 0x12e00000
	s_nop 0
	v_addc_co_u32_e32 v7, vcc, 0, v15, vcc
	v_add_co_u32_e32 v10, vcc, s6, v14
	s_mov_b32 s6, 0x12e08000
	s_nop 0
	v_addc_co_u32_e32 v11, vcc, 0, v15, vcc
	v_add_co_u32_e32 v16, vcc, s6, v14
	global_load_dwordx4 v[2:5], v[2:3], off
	s_nop 0
	v_addc_co_u32_e32 v17, vcc, 0, v15, vcc
	global_load_dwordx4 v[6:9], v[6:7], off
	s_movk_i32 s6, 0x110
	global_load_dwordx4 v[10:13], v[10:11], off
	v_mul_lo_u32 v159, v162, s6
	global_load_dwordx4 v[16:19], v[16:17], off
	s_movk_i32 s6, 0x140
	v_mul_lo_u32 v174, v162, s6
	v_add_u32_e32 v176, v175, v159
	v_add_u32_e32 v1, 0x2800, v174
	s_mov_b32 s6, 0x10e10000
	v_add_u32_e32 v177, v175, v174
	v_add_u32_e32 v178, v175, v1
	s_waitcnt vmcnt(0) lgkmcnt(0)
	ds_write_b128 v176, v[2:5]
	ds_write_b128 v176, v[6:9] offset:8704
	v_add_co_u32_e32 v2, vcc, s6, v14
	ds_write_b128 v177, v[10:13] offset:17408
	s_nop 0
	v_addc_co_u32_e32 v3, vcc, 0, v15, vcc
	ds_write_b128 v178, v[16:19] offset:17408
	global_load_dwordx4 v[148:151], v[2:3], off
	v_add_co_u32_e32 v2, vcc, 0x10e18000, v14
	v_readlane_b32 s6, v255, 8
	s_nop 0
	v_addc_co_u32_e32 v3, vcc, 0, v15, vcc
	global_load_dwordx4 v[152:155], v[2:3], off
	v_mov_b32_e32 v1, s6
	s_waitcnt vmcnt(0) lgkmcnt(0)
	ds_write_b128 v176, v[148:151] offset:37888
	ds_write_b128 v176, v[152:155] offset:46592
	s_waitcnt lgkmcnt(0)
	s_barrier
	ds_read_b32 v34, v1
	s_cbranch_scc0 .LBB0_394
	v_or_b32_e32 v5, 2, v157
	v_or_b32_e32 v7, 3, v157
	v_sub_u32_e32 v1, v168, v157
	v_xad_u32 v3, v157, -1, v168
	v_sub_u32_e32 v5, v168, v5
	v_sub_u32_e32 v7, v168, v7
	v_med3_i32 v2, v1, 0, v223
	v_max_i32_e32 v1, 32, v1
	v_med3_i32 v4, v3, 0, v223
	v_max_i32_e32 v3, 32, v3
	v_med3_i32 v6, v5, 0, v223
	v_max_i32_e32 v5, 32, v5
	v_med3_i32 v8, v7, 0, v223
	v_max_i32_e32 v7, 32, v7
	v_subrev_u32_e32 v1, 32, v1
	v_subrev_u32_e32 v3, 32, v3
	v_subrev_u32_e32 v5, 32, v5
	v_subrev_u32_e32 v7, 32, v7
	s_add_i32 s6, 0, 0x13000
	v_min_u32_e32 v1, 0x7f, v1
	v_min_u32_e32 v3, 0x7f, v3
	v_min_u32_e32 v5, 0x7f, v5
	v_min_u32_e32 v7, 0x7f, v7
	v_lshl_add_u32 v2, v2, 2, s6
	v_lshl_add_u32 v1, v1, 2, s6
	v_lshl_add_u32 v3, v3, 2, s6
	v_lshl_add_u32 v5, v5, 2, s6
	v_lshl_add_u32 v7, v7, 2, s6
	v_lshl_add_u32 v4, v4, 2, s6
	v_lshl_add_u32 v6, v6, 2, s6
	v_lshl_add_u32 v8, v8, 2, s6
	ds_read_b32 v36, v2
	ds_read_b32 v16, v1
	ds_read_b32 v37, v4
	ds_read_b32 v17, v3
	ds_read_b32 v38, v6
	ds_read_b32 v18, v5
	ds_read_b32 v39, v8
	ds_read_b32 v19, v7
	v_or_b32_e32 v1, 8, v157
	v_or_b32_e32 v3, 9, v157
	v_or_b32_e32 v5, 10, v157
	v_or_b32_e32 v7, 11, v157
	v_sub_u32_e32 v1, v168, v1
	v_sub_u32_e32 v3, v168, v3
	v_sub_u32_e32 v5, v168, v5
	v_sub_u32_e32 v7, v168, v7
	v_med3_i32 v2, v1, 0, v223
	v_max_i32_e32 v1, 32, v1
	v_med3_i32 v4, v3, 0, v223
	v_max_i32_e32 v3, 32, v3
	v_med3_i32 v6, v5, 0, v223
	v_max_i32_e32 v5, 32, v5
	v_med3_i32 v8, v7, 0, v223
	v_max_i32_e32 v7, 32, v7
	v_subrev_u32_e32 v1, 32, v1
	v_subrev_u32_e32 v3, 32, v3
	v_subrev_u32_e32 v5, 32, v5
	v_subrev_u32_e32 v7, 32, v7
	v_min_u32_e32 v1, 0x7f, v1
	v_min_u32_e32 v3, 0x7f, v3
	v_min_u32_e32 v5, 0x7f, v5
	v_min_u32_e32 v7, 0x7f, v7
	v_lshl_add_u32 v2, v2, 2, s6
	v_lshl_add_u32 v1, v1, 2, s6
	v_lshl_add_u32 v3, v3, 2, s6
	v_lshl_add_u32 v5, v5, 2, s6
	v_lshl_add_u32 v7, v7, 2, s6
	v_lshl_add_u32 v4, v4, 2, s6
	v_lshl_add_u32 v6, v6, 2, s6
	v_lshl_add_u32 v8, v8, 2, s6
	ds_read_b32 v40, v2
	ds_read_b32 v20, v1
	ds_read_b32 v41, v4
	ds_read_b32 v21, v3
	ds_read_b32 v42, v6
	ds_read_b32 v22, v5
	ds_read_b32 v43, v8
	ds_read_b32 v23, v7
	v_or_b32_e32 v1, 16, v157
	v_or_b32_e32 v3, 17, v157
	v_or_b32_e32 v5, 18, v157
	v_or_b32_e32 v7, 19, v157
	v_sub_u32_e32 v1, v168, v1
	v_sub_u32_e32 v3, v168, v3
	v_sub_u32_e32 v5, v168, v5
	v_sub_u32_e32 v7, v168, v7
	v_med3_i32 v2, v1, 0, v223
	v_max_i32_e32 v1, 32, v1
	v_med3_i32 v4, v3, 0, v223
	v_max_i32_e32 v3, 32, v3
	v_med3_i32 v6, v5, 0, v223
	v_max_i32_e32 v5, 32, v5
	v_med3_i32 v8, v7, 0, v223
	v_max_i32_e32 v7, 32, v7
	v_subrev_u32_e32 v1, 32, v1
	v_subrev_u32_e32 v3, 32, v3
	v_subrev_u32_e32 v5, 32, v5
	v_subrev_u32_e32 v7, 32, v7
	v_min_u32_e32 v1, 0x7f, v1
	v_min_u32_e32 v3, 0x7f, v3
	v_min_u32_e32 v5, 0x7f, v5
	v_min_u32_e32 v7, 0x7f, v7
	v_lshl_add_u32 v2, v2, 2, s6
	v_lshl_add_u32 v1, v1, 2, s6
	v_lshl_add_u32 v3, v3, 2, s6
	v_lshl_add_u32 v5, v5, 2, s6
	v_lshl_add_u32 v7, v7, 2, s6
	v_lshl_add_u32 v4, v4, 2, s6
	v_lshl_add_u32 v6, v6, 2, s6
	v_lshl_add_u32 v8, v8, 2, s6
	ds_read_b32 v44, v2
	ds_read_b32 v24, v1
	ds_read_b32 v45, v4
	ds_read_b32 v25, v3
	ds_read_b32 v46, v6
	ds_read_b32 v26, v5
	ds_read_b32 v47, v8
	ds_read_b32 v27, v7
	v_or_b32_e32 v1, 24, v157
	v_or_b32_e32 v3, 25, v157
	v_or_b32_e32 v5, 26, v157
	v_or_b32_e32 v7, 27, v157
	v_sub_u32_e32 v1, v168, v1
	v_sub_u32_e32 v3, v168, v3
	v_sub_u32_e32 v5, v168, v5
	v_sub_u32_e32 v7, v168, v7
	v_med3_i32 v2, v1, 0, v223
	v_max_i32_e32 v1, 32, v1
	v_med3_i32 v4, v3, 0, v223
	v_max_i32_e32 v3, 32, v3
	v_med3_i32 v6, v5, 0, v223
	v_max_i32_e32 v5, 32, v5
	v_med3_i32 v8, v7, 0, v223
	v_max_i32_e32 v7, 32, v7
	v_subrev_u32_e32 v1, 32, v1
	v_subrev_u32_e32 v3, 32, v3
	v_subrev_u32_e32 v5, 32, v5
	v_subrev_u32_e32 v7, 32, v7
	v_lshl_add_u32 v2, v2, 2, s6
	v_min_u32_e32 v1, 0x7f, v1
	v_min_u32_e32 v3, 0x7f, v3
	v_min_u32_e32 v5, 0x7f, v5
	v_min_u32_e32 v7, 0x7f, v7
	v_lshl_add_u32 v1, v1, 2, s6
	v_lshl_add_u32 v4, v4, 2, s6
	v_lshl_add_u32 v3, v3, 2, s6
	v_lshl_add_u32 v6, v6, 2, s6
	v_lshl_add_u32 v5, v5, 2, s6
	v_lshl_add_u32 v8, v8, 2, s6
	v_lshl_add_u32 v7, v7, 2, s6
	ds_read_b32 v48, v2
	ds_read_b32 v28, v1
	ds_read_b32 v49, v4
	ds_read_b32 v29, v3
	ds_read_b32 v50, v6
	ds_read_b32 v30, v5
	ds_read_b32 v51, v8
	ds_read_b32 v31, v7
	s_cbranch_execz .LBB0_395
	s_branch .LBB0_396

; #define DIFF_QK(P0, P1, kt) do { bf16x8 qf[4]; _Pragma("unroll") for (int d0 = 0; d0 < 4; ++d0) qf[d0] = *(const LAS bf16x8*)(qlds + d0 * 32); attn_qk(P0, P1, kt, 272, qf, r32, hi); } while (0)
; __device__ __forceinline__ void diff_unit(const Params& P, int l, int b, int h, int qb, float lam, float lam_init, LAS unsigned char* lds, bool dry = false) {
;     ...
;     DIFF_INIT(s0, s1, 0); DIFF_QK(s0, s1, lds + KOFF + map * 128);
.LBB0_396:
	s_lshl_b32 s6, s78, 7
	s_add_i32 s53, s6, 0
	v_mov_b32_e32 v1, s53
	s_movk_i32 s6, 0x110
	v_mad_u32_u24 v1, v167, s6, v1
	v_add_u32_e32 v179, v1, v156
	ds_read_b128 v[2:5], v179
	ds_read_b128 v[10:13], v35
	s_mov_b64 s[6:7], 0x6e00000
	s_cmp_eq_u32 s71, 0
	v_lshl_add_u64 v[14:15], v[14:15], 0, s[6:7]
	s_waitcnt lgkmcnt(0)
	v_mfma_f32_32x32x16_bf16 v[36:51], v[2:5], v[10:13], v[36:51]
	ds_read_b128 v[2:5], v179 offset:8704
	s_cselect_b64 s[6:7], -1, 0
	s_cmp_lg_u32 s71, 0
	s_cselect_b64 s[40:41], -1, 0
	s_and_b64 vcc, exec, s[6:7]
	s_waitcnt lgkmcnt(0)
	v_mfma_f32_32x32x16_bf16 v[16:31], v[2:5], v[10:13], v[16:31]
	ds_read_b128 v[6:9], v179 offset:32
	ds_read_b128 v[2:5], v35 offset:32
	s_waitcnt lgkmcnt(0)
	v_mfma_f32_32x32x16_bf16 v[36:51], v[6:9], v[2:5], v[36:51]
	ds_read_b128 v[6:9], v179 offset:8736
	s_waitcnt lgkmcnt(0)
	v_mfma_f32_32x32x16_bf16 v[16:31], v[6:9], v[2:5], v[16:31]
	ds_read_b128 v[6:9], v179 offset:64
	ds_read_b128 v[52:55], v35 offset:64
	s_waitcnt lgkmcnt(0)
	v_mfma_f32_32x32x16_bf16 v[36:51], v[6:9], v[52:55], v[36:51]
	ds_read_b128 v[6:9], v179 offset:8768
	s_waitcnt lgkmcnt(0)
	v_mfma_f32_32x32x16_bf16 v[16:31], v[6:9], v[52:55], v[16:31]
	ds_read_b128 v[56:59], v179 offset:96
	ds_read_b128 v[6:9], v35 offset:96
	s_waitcnt lgkmcnt(0)
	v_mfma_f32_32x32x16_bf16 v[36:51], v[56:59], v[6:9], v[36:51]
	ds_read_b128 v[56:59], v179 offset:8800
	s_waitcnt lgkmcnt(0)
	v_mfma_f32_32x32x16_bf16 v[16:31], v[56:59], v[6:9], v[16:31]
	s_cbranch_vccnz .LBB0_398
	v_add_co_u32_e32 v32, vcc, 0xa020000, v14
	s_nop 1
	v_addc_co_u32_e32 v33, vcc, 0, v15, vcc
	v_add_co_u32_e32 v56, vcc, 0xa028000, v14
	s_nop 1
	v_addc_co_u32_e32 v57, vcc, 0, v15, vcc
	global_load_dwordx4 v[148:151], v[32:33], off
	global_load_dwordx4 v[152:155], v[56:57], off
.LBB0_398:
	v_add_co_u32_e32 v32, vcc, 0xc010000, v14
	s_lshl_b32 s80, s71, 1
	s_nop 0
	v_addc_co_u32_e32 v33, vcc, 0, v15, vcc
	v_add_co_u32_e32 v14, vcc, 0xc018000, v14
	s_lshr_b32 s83, s74, 1
	s_nop 0
	v_addc_co_u32_e32 v15, vcc, 0, v15, vcc
	global_load_dwordx4 v[132:135], v[32:33], off
	global_load_dwordx4 v[136:139], v[14:15], off
	s_sub_i32 s8, 1, s80
	s_cmp_gt_i32 s8, s83
	s_cselect_b64 s[8:9], -1, 0
	s_and_b64 s[8:9], s[6:7], s[8:9]
	s_and_b64 vcc, exec, s[8:9]
	s_cbranch_vccnz .LBB0_401
	s_cmpk_lt_u32 s52, 0xf0
	s_cbranch_scc0 .LBB0_402
	v_subrev_u32_e32 v1, 64, v168
	v_or_b32_e32 v56, 2, v157
	v_or_b32_e32 v58, 3, v157
	v_sub_u32_e32 v14, v1, v157
	v_xad_u32 v32, v157, -1, v1
	v_sub_u32_e32 v56, v1, v56
	v_sub_u32_e32 v58, v1, v58
	v_med3_i32 v15, v14, 0, v223
	v_max_i32_e32 v14, 32, v14
	v_med3_i32 v33, v32, 0, v223
	v_max_i32_e32 v32, 32, v32
	v_med3_i32 v57, v56, 0, v223
	v_max_i32_e32 v56, 32, v56
	v_med3_i32 v59, v58, 0, v223
	v_max_i32_e32 v58, 32, v58
	v_subrev_u32_e32 v14, 32, v14
	v_subrev_u32_e32 v32, 32, v32
	v_subrev_u32_e32 v56, 32, v56
	v_subrev_u32_e32 v58, 32, v58
	s_add_i32 s10, 0, 0x13000
	v_min_u32_e32 v14, 0x7f, v14
	v_min_u32_e32 v32, 0x7f, v32
	v_min_u32_e32 v56, 0x7f, v56
	v_min_u32_e32 v58, 0x7f, v58
	v_lshl_add_u32 v15, v15, 2, s10
	v_lshl_add_u32 v14, v14, 2, s10
	v_lshl_add_u32 v32, v32, 2, s10
	v_lshl_add_u32 v56, v56, 2, s10
	v_lshl_add_u32 v58, v58, 2, s10
	v_lshl_add_u32 v33, v33, 2, s10
	v_lshl_add_u32 v57, v57, 2, s10
	v_lshl_add_u32 v59, v59, 2, s10
	ds_read_b32 v84, v15
	ds_read_b32 v68, v14
	ds_read_b32 v85, v33
	ds_read_b32 v69, v32
	ds_read_b32 v86, v57
	ds_read_b32 v70, v56
	ds_read_b32 v87, v59
	ds_read_b32 v71, v58
	v_or_b32_e32 v14, 8, v157
	v_or_b32_e32 v32, 9, v157
	v_or_b32_e32 v56, 10, v157
	v_or_b32_e32 v58, 11, v157
	v_sub_u32_e32 v14, v1, v14
	v_sub_u32_e32 v32, v1, v32
	v_sub_u32_e32 v56, v1, v56
	v_sub_u32_e32 v58, v1, v58
	v_med3_i32 v15, v14, 0, v223
	v_max_i32_e32 v14, 32, v14
	v_med3_i32 v33, v32, 0, v223
	v_max_i32_e32 v32, 32, v32
	v_med3_i32 v57, v56, 0, v223
	v_max_i32_e32 v56, 32, v56
	v_med3_i32 v59, v58, 0, v223
	v_max_i32_e32 v58, 32, v58
	v_subrev_u32_e32 v14, 32, v14
	v_subrev_u32_e32 v32, 32, v32
	v_subrev_u32_e32 v56, 32, v56
	v_subrev_u32_e32 v58, 32, v58
	v_min_u32_e32 v14, 0x7f, v14
	v_min_u32_e32 v32, 0x7f, v32
	v_min_u32_e32 v56, 0x7f, v56
	v_min_u32_e32 v58, 0x7f, v58
	v_lshl_add_u32 v15, v15, 2, s10
	v_lshl_add_u32 v14, v14, 2, s10
	v_lshl_add_u32 v32, v32, 2, s10
	v_lshl_add_u32 v56, v56, 2, s10
	v_lshl_add_u32 v58, v58, 2, s10
	v_lshl_add_u32 v33, v33, 2, s10
	v_lshl_add_u32 v57, v57, 2, s10
	v_lshl_add_u32 v59, v59, 2, s10
	ds_read_b32 v88, v15
	ds_read_b32 v72, v14
	ds_read_b32 v89, v33
	ds_read_b32 v73, v32
	ds_read_b32 v90, v57
	ds_read_b32 v74, v56
	ds_read_b32 v91, v59
	ds_read_b32 v75, v58
	v_or_b32_e32 v14, 16, v157
	v_or_b32_e32 v32, 17, v157
	v_or_b32_e32 v56, 18, v157
	v_or_b32_e32 v58, 19, v157
	v_sub_u32_e32 v14, v1, v14
	v_sub_u32_e32 v32, v1, v32
	v_sub_u32_e32 v56, v1, v56
	v_sub_u32_e32 v58, v1, v58
	v_med3_i32 v15, v14, 0, v223
	v_max_i32_e32 v14, 32, v14
	v_med3_i32 v33, v32, 0, v223
	v_max_i32_e32 v32, 32, v32
	v_med3_i32 v57, v56, 0, v223
	v_max_i32_e32 v56, 32, v56
	v_med3_i32 v59, v58, 0, v223
	v_max_i32_e32 v58, 32, v58
	v_subrev_u32_e32 v14, 32, v14
	v_subrev_u32_e32 v32, 32, v32
	v_subrev_u32_e32 v56, 32, v56
	v_subrev_u32_e32 v58, 32, v58
	v_min_u32_e32 v14, 0x7f, v14
	v_min_u32_e32 v32, 0x7f, v32
	v_min_u32_e32 v56, 0x7f, v56
	v_min_u32_e32 v58, 0x7f, v58
	v_lshl_add_u32 v15, v15, 2, s10
	v_lshl_add_u32 v14, v14, 2, s10
	v_lshl_add_u32 v32, v32, 2, s10
	v_lshl_add_u32 v56, v56, 2, s10
	v_lshl_add_u32 v58, v58, 2, s10
	v_lshl_add_u32 v33, v33, 2, s10
	v_lshl_add_u32 v57, v57, 2, s10
	v_lshl_add_u32 v59, v59, 2, s10
	ds_read_b32 v92, v15
	ds_read_b32 v76, v14
	ds_read_b32 v93, v33
	ds_read_b32 v77, v32
	ds_read_b32 v94, v57
	ds_read_b32 v78, v56
	ds_read_b32 v95, v59
	ds_read_b32 v79, v58
	v_or_b32_e32 v14, 24, v157
	v_or_b32_e32 v32, 25, v157
	v_or_b32_e32 v56, 26, v157
	v_or_b32_e32 v58, 27, v157
	v_sub_u32_e32 v14, v1, v14
	v_sub_u32_e32 v32, v1, v32
	v_sub_u32_e32 v56, v1, v56
	v_sub_u32_e32 v1, v1, v58
	v_med3_i32 v15, v14, 0, v223
	v_max_i32_e32 v14, 32, v14
	v_med3_i32 v33, v32, 0, v223
	v_max_i32_e32 v32, 32, v32
	v_med3_i32 v57, v56, 0, v223
	v_max_i32_e32 v56, 32, v56
	v_med3_i32 v58, v1, 0, v223
	v_max_i32_e32 v1, 32, v1
	v_subrev_u32_e32 v14, 32, v14
	v_subrev_u32_e32 v32, 32, v32
	v_subrev_u32_e32 v56, 32, v56
	v_subrev_u32_e32 v1, 32, v1
	v_lshl_add_u32 v15, v15, 2, s10
	v_min_u32_e32 v14, 0x7f, v14
	v_min_u32_e32 v32, 0x7f, v32
	v_min_u32_e32 v56, 0x7f, v56
	v_min_u32_e32 v1, 0x7f, v1
	v_lshl_add_u32 v14, v14, 2, s10
	v_lshl_add_u32 v33, v33, 2, s10
	v_lshl_add_u32 v32, v32, 2, s10
	v_lshl_add_u32 v57, v57, 2, s10
	v_lshl_add_u32 v56, v56, 2, s10
	v_lshl_add_u32 v58, v58, 2, s10
	v_lshl_add_u32 v1, v1, 2, s10
	ds_read_b32 v96, v15
	ds_read_b32 v80, v14
	ds_read_b32 v97, v33
	ds_read_b32 v81, v32
	ds_read_b32 v98, v57
	ds_read_b32 v82, v56
	ds_read_b32 v99, v58
	ds_read_b32 v83, v1
	s_cbranch_execz .LBB0_403
	s_branch .LBB0_404

; #define SBAR_() __builtin_amdgcn_sched_barrier(0)
; __device__ __forceinline__ void diff_steady_step(f32x16& s0, f32x16& s1, f32x16& n0, f32x16& n1, const LAS unsigned char* kb, const LAS unsigned char* Vt, const LAS unsigned char* qlds, ...
;     ...
;     bf16x8 ka[3], kc[3], va[4];
;     ...
;     DKF_(ka, 0); DKF_(kc, 1);
;     { const float v_ = b31 - mref;
; #pragma unroll
;       for (int r = 0; r < 16; ++r) { n0[r] = v_; n1[r] = v_; } }
;     SBAR_();
;     float rs = 0.f; u32x4 w0, w1, w2, w3;
;     ...
;     MF_(n0, ka[0], ka[2]); EXPN_(s0, 0, 2); SBAR_();
;     MF_(n1, ka[1], ka[2]); DKF_(ka, 2); EXPN_(s0, 2, 2); w0.x = cvt_pk_bf16(s0[0], s0[1]); SBAR_();
;     MF_(n0, kc[0], kc[2]); EXPN_(s0, 4, 2); w0.y = cvt_pk_bf16(s0[2], s0[3]); SBAR_();
;     MF_(n1, kc[1], kc[2]); DKF_(kc, 3); EXPN_(s0, 6, 2); w0.z = cvt_pk_bf16(s0[4], s0[5]); SBAR_();
;     MF_(n0, ka[0], ka[2]); EXPN_(s0, 8, 2); w0.w = cvt_pk_bf16(s0[6], s0[7]); SBAR_();
;     MF_(n1, ka[1], ka[2]); EXPN_(s0, 10, 2); w1.x = cvt_pk_bf16(s0[8], s0[9]); SBAR_();
; #pragma unroll
;     for (int d = 0; d < 4; ++d) va[d] = DVF_(0, d);
;     MF_(n0, kc[0], kc[2]); EXPN_(s0, 12, 2); w1.y = cvt_pk_bf16(s0[10], s0[11]); SBAR_();
;     MF_(n1, kc[1], kc[2]); EXPN_(s0, 14, 2); w1.z = cvt_pk_bf16(s0[12], s0[13]); w1.w = cvt_pk_bf16(s0[14], s0[15]); SBAR_();
;     vreg[0] = *(const u32x4*)vsrc; vreg[1] = *(const u32x4*)(vsrc + vstep);
;     const bf16x8 pa0 = __builtin_bit_cast(bf16x8, w0), pa1 = __builtin_bit_cast(bf16x8, w1);
;     SBAR_();
;     MF_(o[0], pa0, va[0]); EXPN_(s1, 0, 2); SBAR_();
;     MF_(o[1], pa0, va[1]); va[0] = DVF_(1, 0); va[1] = DVF_(1, 1); EXPN_(s1, 2, 2); w2.x = cvt_pk_bf16(s1[0], s1[1]); SBAR_();
;     MF_(o[2], pa0, va[2]); va[2] = DVF_(1, 2); EXPN_(s1, 4, 2); w2.y = cvt_pk_bf16(s1[2], s1[3]); SBAR_();
;     MF_(o[3], pa0, va[3]); va[3] = DVF_(1, 3); EXPN_(s1, 6, 2); w2.z = cvt_pk_bf16(s1[4], s1[5]); w2.w = cvt_pk_bf16(s1[6], s1[7]); SBAR_();
;     MF_(o[0], pa1, va[0]); EXPN_(s1, 8, 2); SBAR_();
;     MF_(o[1], pa1, va[1]); va[0] = DVF_(2, 0); va[1] = DVF_(2, 1); EXPN_(s1, 10, 2); w3.x = cvt_pk_bf16(s1[8], s1[9]); SBAR_();
;     MF_(o[2], pa1, va[2]); va[2] = DVF_(2, 2); EXPN_(s1, 12, 2); w3.y = cvt_pk_bf16(s1[10], s1[11]); SBAR_();
;     MF_(o[3], pa1, va[3]); va[3] = DVF_(2, 3); EXPN_(s1, 14, 2); w3.z = cvt_pk_bf16(s1[12], s1[13]); w3.w = cvt_pk_bf16(s1[14], s1[15]); SBAR_();
.LBB0_416:
	ds_read_b128 v[68:71], v179 offset:37888
	ds_read_b128 v[72:75], v179 offset:37920
	ds_read_b128 v[76:79], v179 offset:46592
	ds_read_b128 v[80:83], v179 offset:46624
	ds_read_b128 v[188:191], v35
	ds_read_b128 v[196:199], v35 offset:32
	v_mov_b32_e32 v133, v132
	v_mov_b32_e32 v134, v132
	v_mov_b32_e32 v135, v132
	v_mov_b32_e32 v136, v132
	v_mov_b32_e32 v137, v132
	v_mov_b32_e32 v138, v132
	v_mov_b32_e32 v139, v132
	v_mov_b32_e32 v140, v132
	v_mov_b32_e32 v141, v132
	v_mov_b32_e32 v142, v132
	v_mov_b32_e32 v143, v132
	v_mov_b32_e32 v144, v132
	v_mov_b32_e32 v145, v132
	v_mov_b32_e32 v146, v132
	v_mov_b32_e32 v147, v132
	s_waitcnt lgkmcnt(0)
	s_nop 0
	v_mfma_f32_32x32x16_bf16 v[84:99], v[68:71], v[188:191], v[132:147]
	v_exp_f32_e32 v100, v100
	v_exp_f32_e32 v101, v101
	v_add_f32_e32 v68, 0, v100
	v_add_f32_e32 v172, v101, v68
	v_mfma_f32_32x32x16_bf16 v[132:147], v[76:79], v[188:191], v[132:147]
	ds_read_b128 v[68:71], v179 offset:37952
	ds_read_b128 v[76:79], v179 offset:46656
	ds_read_b128 v[188:191], v35 offset:64
	v_exp_f32_e32 v102, v102
	v_exp_f32_e32 v103, v103
	v_cvt_pk_bf16_f32 v200, v100, v101
	v_add_f32_e32 v172, v102, v172
	v_add_f32_e32 v172, v103, v172
	v_mfma_f32_32x32x16_bf16 v[84:99], v[72:75], v[196:199], v[84:99]
	v_exp_f32_e32 v104, v104
	v_exp_f32_e32 v105, v105
	v_cvt_pk_bf16_f32 v201, v102, v103
	v_add_f32_e32 v72, v104, v172
	v_add_f32_e32 v172, v105, v72
	v_mfma_f32_32x32x16_bf16 v[132:147], v[80:83], v[196:199], v[132:147]
	ds_read_b128 v[72:75], v179 offset:37984
	ds_read_b128 v[196:199], v179 offset:46688
	ds_read_b128 v[204:207], v35 offset:96
	v_exp_f32_e32 v106, v106
	v_exp_f32_e32 v107, v107
	v_cvt_pk_bf16_f32 v202, v104, v105
	v_add_f32_e32 v80, v106, v172
	v_add_f32_e32 v80, v107, v80
	s_waitcnt lgkmcnt(0)
	v_mfma_f32_32x32x16_bf16 v[84:99], v[68:71], v[188:191], v[84:99]
	v_exp_f32_e32 v108, v108
	v_exp_f32_e32 v109, v109
	v_cvt_pk_bf16_f32 v203, v106, v107
	v_add_f32_e32 v68, v108, v80
	v_add_f32_e32 v68, v109, v68
	v_mfma_f32_32x32x16_bf16 v[132:147], v[76:79], v[188:191], v[132:147]
	v_exp_f32_e32 v110, v110
	v_exp_f32_e32 v111, v111
	v_cvt_pk_bf16_f32 v188, v108, v109
	ds_read_b64_tr_b16 v[208:209], v169 offset:17408
	ds_read_b64_tr_b16 v[232:233], v169 offset:17472
	ds_read_b64_tr_b16 v[236:237], v169 offset:17536
	ds_read_b64_tr_b16 v[240:241], v169 offset:17600
	ds_read_b64_tr_b16 v[210:211], v169 offset:19968
	ds_read_b64_tr_b16 v[234:235], v169 offset:20032
	ds_read_b64_tr_b16 v[238:239], v169 offset:20096
	ds_read_b64_tr_b16 v[242:243], v169 offset:20160
	v_mfma_f32_32x32x16_bf16 v[84:99], v[72:75], v[204:207], v[84:99]
	v_exp_f32_e32 v112, v112
	v_exp_f32_e32 v113, v113
	v_add_f32_e32 v172, v110, v68
	v_cvt_pk_bf16_f32 v189, v110, v111
	v_mov_b64_e32 v[68:69], v[132:133]
	v_mov_b64_e32 v[70:71], v[134:135]
	v_mov_b64_e32 v[72:73], v[136:137]
	v_mov_b64_e32 v[74:75], v[138:139]
	v_mov_b64_e32 v[76:77], v[140:141]
	v_mov_b64_e32 v[78:79], v[142:143]
	v_mov_b64_e32 v[80:81], v[144:145]
	v_mov_b64_e32 v[82:83], v[146:147]
	v_exp_f32_e32 v114, v114
	v_exp_f32_e32 v115, v115
	v_mfma_f32_32x32x16_bf16 v[68:83], v[196:199], v[204:207], v[68:83]
	v_cvt_pk_bf16_f32 v190, v112, v113
	v_cvt_pk_bf16_f32 v191, v114, v115
	v_add_co_u32_e32 v132, vcc, s58, v164
	s_nop 1
	v_addc_co_u32_e32 v133, vcc, -1, v165, vcc
	global_load_dwordx4 v[132:135], v[132:133], off
	s_nop 0
	global_load_dwordx4 v[136:139], v[164:165], off
	s_waitcnt lgkmcnt(0)
	v_mfma_f32_32x32x16_bf16 v[52:67], v[200:203], v[208:211], v[52:67]
	v_exp_f32_e32 v116, v116
	v_exp_f32_e32 v117, v117
	v_mfma_f32_32x32x16_bf16 v[36:51], v[200:203], v[232:235], v[36:51]
	ds_read_b64_tr_b16 v[140:141], v169 offset:22528
	ds_read_b64_tr_b16 v[142:143], v169 offset:25088
	ds_read_b64_tr_b16 v[144:145], v169 offset:22592
	ds_read_b64_tr_b16 v[146:147], v169 offset:25152
	v_exp_f32_e32 v118, v118
	v_exp_f32_e32 v119, v119
	v_mfma_f32_32x32x16_bf16 v[18:33], v[200:203], v[236:239], v[18:33]
	ds_read_b64_tr_b16 v[196:197], v169 offset:22656
	ds_read_b64_tr_b16 v[198:199], v169 offset:25216
	v_exp_f32_e32 v120, v120
	v_exp_f32_e32 v121, v121
	v_mfma_f32_32x32x16_bf16 v[2:17], v[200:203], v[240:243], v[2:17]
	ds_read_b64_tr_b16 v[200:201], v169 offset:22720
	ds_read_b64_tr_b16 v[202:203], v169 offset:25280
	v_exp_f32_e32 v122, v122
	v_exp_f32_e32 v123, v123
	s_waitcnt lgkmcnt(0)
	v_mfma_f32_32x32x16_bf16 v[52:67], v[188:191], v[140:143], v[52:67]
	v_exp_f32_e32 v124, v124
	v_exp_f32_e32 v125, v125
	v_mfma_f32_32x32x16_bf16 v[36:51], v[188:191], v[144:147], v[36:51]
	ds_read_b64_tr_b16 v[140:141], v169 offset:27648
	ds_read_b64_tr_b16 v[142:143], v169 offset:30208
	ds_read_b64_tr_b16 v[144:145], v169 offset:27712
	ds_read_b64_tr_b16 v[146:147], v169 offset:30272
	v_exp_f32_e32 v126, v126
	v_exp_f32_e32 v127, v127
	v_mfma_f32_32x32x16_bf16 v[18:33], v[188:191], v[196:199], v[18:33]
	ds_read_b64_tr_b16 v[196:197], v169 offset:27776
	ds_read_b64_tr_b16 v[198:199], v169 offset:30336
	v_exp_f32_e32 v128, v128
	v_exp_f32_e32 v129, v129
	v_mfma_f32_32x32x16_bf16 v[2:17], v[188:191], v[200:203], v[2:17]
	ds_read_b64_tr_b16 v[188:189], v169 offset:27840
	ds_read_b64_tr_b16 v[190:191], v169 offset:30400
	v_exp_f32_e32 v130, v130
	v_exp_f32_e32 v131, v131
	v_cvt_pk_bf16_f32 v201, v126, v127
	v_cvt_pk_bf16_f32 v200, v124, v125
	v_cvt_pk_bf16_f32 v207, v122, v123
	v_cvt_pk_bf16_f32 v206, v120, v121
	v_cvt_pk_bf16_f32 v205, v118, v119
	v_cvt_pk_bf16_f32 v204, v116, v117
	v_cvt_pk_bf16_f32 v202, v128, v129
	v_cvt_pk_bf16_f32 v203, v130, v131
	s_waitcnt lgkmcnt(0)
; #define LAS __attribute__((address_space(3)))
; __device__ __forceinline__ float fast_exp2(float x) { return __builtin_amdgcn_exp2f(x); }
; __device__ __forceinline__ float half_max(float v) { auto rr = __builtin_amdgcn_permlane32_swap(__float_as_uint(v), __float_as_uint(v), false, false); return fmaxf(__uint_as_float(rr[0]), __uint_as_float(rr[1])); }
; __device__ __forceinline__ void diff_steady_step(f32x16& s0, f32x16& s1, f32x16& n0, f32x16& n1, const LAS unsigned char* kb, const LAS unsigned char* Vt, const LAS unsigned char* qlds, ...
;     const float rm = rmc;
;     if (__any(rm > 8.0f)) {
;         const float dl = fmaxf(rm, 0.f);
;         mref += dl;
; #pragma unroll
;         for (int r = 0; r < 16; ++r) { s0[r] -= dl; s1[r] -= dl; }
;         const float alpha = fast_exp2(-dl);
;         lrun *= alpha;
;         if (hi == 0) wsf[r32] = alpha;
;         asm volatile("s_waitcnt lgkmcnt(0)" ::: "memory");
; #pragma unroll
;         for (int jj = 0; jj < 4; ++jj) { const f32x4 al = *(const LAS f32x4*)(wsf + 8 * jj + 4 * hi);
; #pragma unroll
;             for (int d = 0; d < 4; ++d) { o[d][4 * jj + 0] *= al.x; o[d][4 * jj + 1] *= al.y; o[d][4 * jj + 2] *= al.z; o[d][4 * jj + 3] *= al.w; } }
;         asm volatile("s_waitcnt lgkmcnt(0)" ::: "memory");
;     ...
;     lrun += rs;
;     const bf16x8 pa2 = __builtin_bit_cast(bf16x8, w2), pa3 = __builtin_bit_cast(bf16x8, w3);
;     float ra = fmaxf(fmaxf(n0[0], n0[1]), n1[0]), rb = fmaxf(fmaxf(n0[2], n0[3]), n1[1]);
;     MF_(o[0], pa2, va[0]); ra = fmaxf(fmaxf(ra, n1[2]), n1[3]); rb = fmaxf(fmaxf(rb, n0[4]), n0[5]); SBAR_();
;     MF_(o[1], pa2, va[1]); va[0] = DVF_(3, 0); va[1] = DVF_(3, 1); ra = fmaxf(fmaxf(ra, n0[6]), n0[7]); rb = fmaxf(fmaxf(rb, n1[4]), n1[5]); SBAR_();
;     MF_(o[2], pa2, va[2]); va[2] = DVF_(3, 2); ra = fmaxf(fmaxf(ra, n1[6]), n1[7]); rb = fmaxf(fmaxf(rb, n0[8]), n0[9]); SBAR_();
;     MF_(o[3], pa2, va[3]); va[3] = DVF_(3, 3); ra = fmaxf(fmaxf(ra, n0[10]), n0[11]); rb = fmaxf(fmaxf(rb, n1[8]), n1[9]); SBAR_();
;     MF_(o[0], pa3, va[0]); ra = fmaxf(fmaxf(ra, n1[10]), n1[11]); rb = fmaxf(fmaxf(rb, n0[12]), n0[13]); SBAR_();
;     MF_(o[1], pa3, va[1]); ra = fmaxf(fmaxf(ra, n0[14]), n0[15]); rb = fmaxf(fmaxf(rb, n1[12]), n1[13]); SBAR_();
;     MF_(o[2], pa3, va[2]); ra = fmaxf(fmaxf(ra, n1[14]), n1[15]); SBAR_();
;     MF_(o[3], pa3, va[3]);
;     ...
;     rmc = half_max(fmaxf(ra, rb));
; }
	v_mfma_f32_32x32x16_bf16 v[52:67], v[204:207], v[140:143], v[52:67]
	v_max_f32_e32 v182, v85, v85
	v_max_f32_e32 v183, v84, v84
	v_max_f32_e32 v182, v183, v182
	v_max3_f32 v183, v86, v87, v69
	v_max3_f32 v182, v182, v68, v70
	v_max3_f32 v183, v183, v88, v89
	v_mfma_f32_32x32x16_bf16 v[36:51], v[204:207], v[144:147], v[36:51]
	ds_read_b64_tr_b16 v[140:141], v169 offset:32768
	ds_read_b64_tr_b16 v[142:143], v169 offset:35328
	ds_read_b64_tr_b16 v[144:145], v169 offset:32832
	ds_read_b64_tr_b16 v[146:147], v169 offset:35392
	v_max3_f32 v182, v182, v71, v90
	v_max3_f32 v183, v183, v72, v73
	v_mfma_f32_32x32x16_bf16 v[18:33], v[204:207], v[196:199], v[18:33]
	ds_read_b64_tr_b16 v[196:197], v169 offset:32896
	ds_read_b64_tr_b16 v[198:199], v169 offset:35456
	v_max3_f32 v182, v182, v91, v74
	v_max3_f32 v183, v183, v92, v93
	v_mfma_f32_32x32x16_bf16 v[2:17], v[204:207], v[188:191], v[2:17]
	ds_read_b64_tr_b16 v[188:189], v169 offset:32960
	ds_read_b64_tr_b16 v[190:191], v169 offset:35520
	v_max3_f32 v182, v182, v75, v94
	v_max3_f32 v183, v183, v76, v77
	s_waitcnt lgkmcnt(0)
	v_mfma_f32_32x32x16_bf16 v[52:67], v[200:203], v[140:143], v[52:67]
	v_max3_f32 v140, v182, v95, v78
	v_max3_f32 v141, v183, v96, v97
	v_mfma_f32_32x32x16_bf16 v[36:51], v[200:203], v[144:147], v[36:51]
	v_max3_f32 v140, v140, v79, v98
	v_max3_f32 v141, v141, v80, v81
	v_mfma_f32_32x32x16_bf16 v[18:33], v[200:203], v[196:199], v[18:33]
	v_max3_f32 v140, v140, v99, v82
	v_add_f32_e32 v142, v111, v172
	v_add_f32_e32 v142, v112, v142
	v_add_f32_e32 v142, v113, v142
	v_add_f32_e32 v142, v114, v142
	v_add_f32_e32 v142, v115, v142
	v_add_f32_e32 v142, v116, v142
	v_add_f32_e32 v142, v117, v142
	v_add_f32_e32 v142, v118, v142
	v_add_f32_e32 v142, v119, v142
	v_add_f32_e32 v142, v120, v142
	v_add_f32_e32 v142, v121, v142
	v_add_f32_e32 v142, v122, v142
	v_add_f32_e32 v142, v123, v142
	v_add_f32_e32 v142, v124, v142
	v_mfma_f32_32x32x16_bf16 v[2:17], v[200:203], v[188:191], v[2:17]
	v_add_f32_e32 v142, v125, v142
	v_add_f32_e32 v142, v126, v142
	v_add_f32_e32 v142, v127, v142
	v_max3_f32 v140, v140, v83, v141
	v_add_f32_e32 v142, v128, v142
	v_mov_b32_e32 v141, v140
	v_add_f32_e32 v142, v129, v142
	s_nop 0
	v_permlane32_swap_b32_e32 v140, v141
	v_add_f32_e32 v142, v130, v142
	s_waitcnt vmcnt(0)
	ds_write_b128 v176, v[148:151]
	ds_write_b128 v176, v[152:155] offset:8704
	v_add_f32_e32 v142, v131, v142
	ds_write_b128 v177, v[132:135] offset:55296
	ds_write_b128 v178, v[136:139] offset:55296
	v_max_f32_e32 v132, v141, v141
	v_max_f32_e32 v133, v140, v140
	s_add_i32 s96, s96, 2
	v_add_f32_e32 v172, v161, v142
	v_max_f32_e32 v132, v133, v132
	v_lshl_add_u64 v[164:165], v[164:165], 0, s[88:89]
	s_cmp_ge_i32 s96, s10
	s_waitcnt lgkmcnt(0)
	s_barrier
	s_cbranch_scc1 .LBB0_425
.LBB0_417:
	v_add_co_u32_e32 v100, vcc, 0xfdff8000, v164
	s_nop 1
	v_addc_co_u32_e32 v101, vcc, -1, v165, vcc
	v_add_co_u32_e32 v102, vcc, 0xfe000000, v164
	s_nop 1
	v_addc_co_u32_e32 v103, vcc, -1, v165, vcc
	global_load_dwordx4 v[148:151], v[100:101], off
	global_load_dwordx4 v[152:155], v[102:103], off
	v_cmp_lt_f32_e32 vcc, s67, v132
	s_cbranch_vccz .LBB0_421
	v_max_f32_e32 v100, v132, v132
	v_max_f32_e32 v100, 0, v100
	v_exp_f32_e64 v101, -v100
	s_and_saveexec_b64 s[8:9], s[6:7]
	ds_write_b32 v170, v101
	s_or_b64 exec, exec, s[8:9]
	s_waitcnt lgkmcnt(0)
	v_add_u32_e32 v112, s75, v156
	v_add_f32_e32 v173, v100, v173
	v_sub_f32_e32 v99, v99, v100
	v_sub_f32_e32 v98, v98, v100
	v_sub_f32_e32 v97, v97, v100
	v_sub_f32_e32 v96, v96, v100
	v_sub_f32_e32 v95, v95, v100
	v_sub_f32_e32 v94, v94, v100
	v_sub_f32_e32 v93, v93, v100
	v_sub_f32_e32 v92, v92, v100
	v_sub_f32_e32 v91, v91, v100
	v_sub_f32_e32 v90, v90, v100
	v_sub_f32_e32 v89, v89, v100
	v_sub_f32_e32 v88, v88, v100
	v_sub_f32_e32 v87, v87, v100
	v_sub_f32_e32 v86, v86, v100
	v_sub_f32_e32 v85, v85, v100
	v_sub_f32_e32 v84, v84, v100
	v_sub_f32_e32 v83, v83, v100
	v_sub_f32_e32 v82, v82, v100
	v_sub_f32_e32 v81, v81, v100
	v_sub_f32_e32 v80, v80, v100
	v_sub_f32_e32 v79, v79, v100
	v_sub_f32_e32 v78, v78, v100
	v_sub_f32_e32 v77, v77, v100
	v_sub_f32_e32 v76, v76, v100
	v_sub_f32_e32 v75, v75, v100
	v_sub_f32_e32 v74, v74, v100
	v_sub_f32_e32 v73, v73, v100
	v_sub_f32_e32 v72, v72, v100
	v_sub_f32_e32 v71, v71, v100
	v_sub_f32_e32 v70, v70, v100
	v_sub_f32_e32 v69, v69, v100
	v_sub_f32_e32 v68, v68, v100
	v_mul_f32_e32 v172, v172, v101
	ds_read_b128 v[100:103], v112
	ds_read_b128 v[104:107], v112 offset:32
	ds_read_b128 v[108:111], v112 offset:64
	ds_read_b128 v[112:115], v112 offset:96
	s_waitcnt lgkmcnt(0)
	s_waitcnt lgkmcnt(0)
	v_pk_mul_f32 v[54:55], v[54:55], v[102:103]
	v_pk_mul_f32 v[56:57], v[56:57], v[104:105]
	v_pk_mul_f32 v[60:61], v[60:61], v[108:109]
	v_pk_mul_f32 v[64:65], v[64:65], v[112:113]
	v_pk_mul_f32 v[66:67], v[66:67], v[114:115]
	v_pk_mul_f32 v[62:63], v[62:63], v[110:111]
	v_pk_mul_f32 v[58:59], v[58:59], v[106:107]
	v_pk_mul_f32 v[52:53], v[52:53], v[100:101]
	v_pk_mul_f32 v[48:49], v[48:49], v[112:113]
	v_pk_mul_f32 v[44:45], v[44:45], v[108:109]
	v_pk_mul_f32 v[40:41], v[40:41], v[104:105]
	v_pk_mul_f32 v[50:51], v[50:51], v[114:115]
	v_pk_mul_f32 v[46:47], v[46:47], v[110:111]
	v_pk_mul_f32 v[42:43], v[42:43], v[106:107]
	v_pk_mul_f32 v[38:39], v[38:39], v[102:103]
	v_pk_mul_f32 v[36:37], v[36:37], v[100:101]
	v_pk_mul_f32 v[30:31], v[30:31], v[112:113]
	v_pk_mul_f32 v[26:27], v[26:27], v[108:109]
	v_pk_mul_f32 v[22:23], v[22:23], v[104:105]
	v_pk_mul_f32 v[32:33], v[32:33], v[114:115]
	v_pk_mul_f32 v[28:29], v[28:29], v[110:111]
	v_pk_mul_f32 v[24:25], v[24:25], v[106:107]
	v_pk_mul_f32 v[20:21], v[20:21], v[102:103]
	v_pk_mul_f32 v[18:19], v[18:19], v[100:101]
	v_pk_mul_f32 v[14:15], v[14:15], v[112:113]
	v_pk_mul_f32 v[10:11], v[10:11], v[108:109]
	v_pk_mul_f32 v[6:7], v[6:7], v[104:105]
	v_pk_mul_f32 v[16:17], v[16:17], v[114:115]
	v_pk_mul_f32 v[12:13], v[12:13], v[110:111]
	v_pk_mul_f32 v[8:9], v[8:9], v[106:107]
	v_pk_mul_f32 v[4:5], v[4:5], v[102:103]
	v_pk_mul_f32 v[2:3], v[2:3], v[100:101]
; #define SBAR_() __builtin_amdgcn_sched_barrier(0)
; __device__ __forceinline__ void diff_steady_step(f32x16& s0, f32x16& s1, f32x16& n0, f32x16& n1, const LAS unsigned char* kb, const LAS unsigned char* Vt, const LAS unsigned char* qlds, ...
;     ...
;     bf16x8 ka[3], kc[3], va[4];
;     ...
;     DKF_(ka, 0); DKF_(kc, 1);
;     { const float v_ = b31 - mref;
; #pragma unroll
;       for (int r = 0; r < 16; ++r) { n0[r] = v_; n1[r] = v_; } }
;     SBAR_();
;     float rs = 0.f; u32x4 w0, w1, w2, w3;
;     ...
;     MF_(n0, ka[0], ka[2]); EXPN_(s0, 0, 2); SBAR_();
;     MF_(n1, ka[1], ka[2]); DKF_(ka, 2); EXPN_(s0, 2, 2); w0.x = cvt_pk_bf16(s0[0], s0[1]); SBAR_();
;     MF_(n0, kc[0], kc[2]); EXPN_(s0, 4, 2); w0.y = cvt_pk_bf16(s0[2], s0[3]); SBAR_();
;     MF_(n1, kc[1], kc[2]); DKF_(kc, 3); EXPN_(s0, 6, 2); w0.z = cvt_pk_bf16(s0[4], s0[5]); SBAR_();
;     MF_(n0, ka[0], ka[2]); EXPN_(s0, 8, 2); w0.w = cvt_pk_bf16(s0[6], s0[7]); SBAR_();
;     MF_(n1, ka[1], ka[2]); EXPN_(s0, 10, 2); w1.x = cvt_pk_bf16(s0[8], s0[9]); SBAR_();
; #pragma unroll
;     for (int d = 0; d < 4; ++d) va[d] = DVF_(0, d);
;     MF_(n0, kc[0], kc[2]); EXPN_(s0, 12, 2); w1.y = cvt_pk_bf16(s0[10], s0[11]); SBAR_();
;     MF_(n1, kc[1], kc[2]); EXPN_(s0, 14, 2); w1.z = cvt_pk_bf16(s0[12], s0[13]); w1.w = cvt_pk_bf16(s0[14], s0[15]); SBAR_();
;     vreg[0] = *(const u32x4*)vsrc; vreg[1] = *(const u32x4*)(vsrc + vstep);
;     const bf16x8 pa0 = __builtin_bit_cast(bf16x8, w0), pa1 = __builtin_bit_cast(bf16x8, w1);
;     SBAR_();
;     MF_(o[0], pa0, va[0]); EXPN_(s1, 0, 2); SBAR_();
;     MF_(o[1], pa0, va[1]); va[0] = DVF_(1, 0); va[1] = DVF_(1, 1); EXPN_(s1, 2, 2); w2.x = cvt_pk_bf16(s1[0], s1[1]); SBAR_();
;     MF_(o[2], pa0, va[2]); va[2] = DVF_(1, 2); EXPN_(s1, 4, 2); w2.y = cvt_pk_bf16(s1[2], s1[3]); SBAR_();
;     MF_(o[3], pa0, va[3]); va[3] = DVF_(1, 3); EXPN_(s1, 6, 2); w2.z = cvt_pk_bf16(s1[4], s1[5]); w2.w = cvt_pk_bf16(s1[6], s1[7]); SBAR_();
;     MF_(o[0], pa1, va[0]); EXPN_(s1, 8, 2); SBAR_();
;     MF_(o[1], pa1, va[1]); va[0] = DVF_(2, 0); va[1] = DVF_(2, 1); EXPN_(s1, 10, 2); w3.x = cvt_pk_bf16(s1[8], s1[9]); SBAR_();
;     MF_(o[2], pa1, va[2]); va[2] = DVF_(2, 2); EXPN_(s1, 12, 2); w3.y = cvt_pk_bf16(s1[10], s1[11]); SBAR_();
;     MF_(o[3], pa1, va[3]); va[3] = DVF_(2, 3); EXPN_(s1, 14, 2); w3.z = cvt_pk_bf16(s1[12], s1[13]); w3.w = cvt_pk_bf16(s1[14], s1[15]); SBAR_();
.LBB0_421:
	ds_read_b128 v[116:119], v179
	ds_read_b128 v[188:191], v179 offset:32
	ds_read_b128 v[196:199], v179 offset:8704
	ds_read_b128 v[200:203], v179 offset:8736
	ds_read_b128 v[204:207], v35
	ds_read_b128 v[208:211], v35 offset:32
	v_sub_f32_e32 v132, v34, v173
	v_mov_b32_e32 v133, v132
	v_mov_b32_e32 v134, v132
	v_mov_b32_e32 v135, v132
	v_mov_b32_e32 v136, v132
	v_mov_b32_e32 v137, v132
	v_mov_b32_e32 v138, v132
	v_mov_b32_e32 v139, v132
	v_mov_b32_e32 v140, v132
	v_mov_b32_e32 v141, v132
	v_mov_b32_e32 v142, v132
	v_mov_b32_e32 v143, v132
	v_mov_b32_e32 v144, v132
	v_mov_b32_e32 v145, v132
	v_mov_b32_e32 v146, v132
	v_mov_b32_e32 v147, v132
	s_waitcnt lgkmcnt(0)
	s_nop 0
	v_mfma_f32_32x32x16_bf16 v[100:115], v[116:119], v[204:207], v[132:147]
	v_exp_f32_e32 v84, v84
	v_exp_f32_e32 v85, v85
	v_add_f32_e32 v116, 0, v84
	v_add_f32_e32 v161, v85, v116
	v_mov_b64_e32 v[116:117], v[132:133]
	v_mov_b64_e32 v[118:119], v[134:135]
	v_mov_b64_e32 v[120:121], v[136:137]
	v_mov_b64_e32 v[122:123], v[138:139]
	v_mov_b64_e32 v[124:125], v[140:141]
	v_mov_b64_e32 v[126:127], v[142:143]
	v_mov_b64_e32 v[128:129], v[144:145]
	v_mov_b64_e32 v[130:131], v[146:147]
	ds_read_b128 v[134:137], v179 offset:64
	ds_read_b128 v[138:141], v179 offset:8768
	ds_read_b128 v[142:145], v35 offset:64
	v_mfma_f32_32x32x16_bf16 v[116:131], v[196:199], v[204:207], v[116:131]
	v_exp_f32_e32 v86, v86
	v_exp_f32_e32 v87, v87
	v_cvt_pk_bf16_f32 v196, v84, v85
	v_add_f32_e32 v133, v86, v161
	v_add_f32_e32 v133, v87, v133
	v_mfma_f32_32x32x16_bf16 v[100:115], v[188:191], v[208:211], v[100:115]
	v_exp_f32_e32 v88, v88
	v_exp_f32_e32 v89, v89
	v_cvt_pk_bf16_f32 v197, v86, v87
	v_add_f32_e32 v84, v88, v133
	v_add_f32_e32 v133, v89, v84
	v_mfma_f32_32x32x16_bf16 v[116:131], v[200:203], v[208:211], v[116:131]
	ds_read_b128 v[84:87], v179 offset:96
	ds_read_b128 v[188:191], v179 offset:8800
	ds_read_b128 v[200:203], v35 offset:96
	v_exp_f32_e32 v90, v90
	v_exp_f32_e32 v91, v91
	v_cvt_pk_bf16_f32 v198, v88, v89
	v_add_f32_e32 v133, v90, v133
	v_add_f32_e32 v133, v91, v133
	s_waitcnt lgkmcnt(0)
	v_mfma_f32_32x32x16_bf16 v[100:115], v[134:137], v[142:145], v[100:115]
	v_exp_f32_e32 v88, v92
	v_exp_f32_e32 v92, v93
	v_cvt_pk_bf16_f32 v199, v90, v91
	v_add_f32_e32 v89, v88, v133
	v_add_f32_e32 v89, v92, v89
	v_mfma_f32_32x32x16_bf16 v[116:131], v[138:141], v[142:145], v[116:131]
	v_exp_f32_e32 v90, v94
	v_exp_f32_e32 v133, v95
	v_cvt_pk_bf16_f32 v92, v88, v92
	ds_read_b64_tr_b16 v[134:135], v169 offset:55296
	ds_read_b64_tr_b16 v[138:139], v169 offset:55360
	ds_read_b64_tr_b16 v[142:143], v169 offset:55424
	ds_read_b64_tr_b16 v[204:205], v169 offset:55488
	ds_read_b64_tr_b16 v[136:137], v169 offset:57856
	ds_read_b64_tr_b16 v[140:141], v169 offset:57920
	ds_read_b64_tr_b16 v[144:145], v169 offset:57984
	ds_read_b64_tr_b16 v[206:207], v169 offset:58048
	v_mfma_f32_32x32x16_bf16 v[100:115], v[84:87], v[200:203], v[100:115]
	v_exp_f32_e32 v161, v97
	v_add_f32_e32 v146, v90, v89
	v_exp_f32_e32 v147, v96
	v_cvt_pk_bf16_f32 v93, v90, v133
	v_mfma_f32_32x32x16_bf16 v[116:131], v[188:191], v[200:203], v[116:131]
	v_exp_f32_e32 v182, v98
	v_exp_f32_e32 v183, v99
	v_cvt_pk_bf16_f32 v94, v147, v161
	v_cvt_pk_bf16_f32 v95, v182, v183
	v_add_co_u32_e32 v84, vcc, s1, v164
	s_nop 1
	v_addc_co_u32_e32 v85, vcc, -1, v165, vcc
	v_add_co_u32_e32 v88, vcc, s61, v164
	s_nop 1
	v_addc_co_u32_e32 v89, vcc, -1, v165, vcc
	global_load_dwordx4 v[84:87], v[84:85], off
	s_nop 0
	global_load_dwordx4 v[88:91], v[88:89], off
	s_waitcnt lgkmcnt(0)
	v_mfma_f32_32x32x16_bf16 v[52:67], v[196:199], v[134:137], v[52:67]
	v_exp_f32_e32 v184, v68
	v_exp_f32_e32 v185, v69
	v_mfma_f32_32x32x16_bf16 v[36:51], v[196:199], v[138:141], v[36:51]
	ds_read_b64_tr_b16 v[96:97], v169 offset:60416
	ds_read_b64_tr_b16 v[98:99], v169 offset:62976
	ds_read_b64_tr_b16 v[134:135], v169 offset:60480
	ds_read_b64_tr_b16 v[136:137], v169 offset:63040
	v_exp_f32_e32 v186, v70
	v_exp_f32_e32 v188, v71
	v_mfma_f32_32x32x16_bf16 v[18:33], v[196:199], v[142:145], v[18:33]
	ds_read_b64_tr_b16 v[68:69], v169 offset:60544
	ds_read_b64_tr_b16 v[70:71], v169 offset:63104
	v_exp_f32_e32 v142, v72
	v_exp_f32_e32 v143, v73
	v_mfma_f32_32x32x16_bf16 v[2:17], v[196:199], v[204:207], v[2:17]
	ds_read_b64_tr_b16 v[138:139], v169 offset:60608
	ds_read_b64_tr_b16 v[140:141], v169 offset:63168
	v_exp_f32_e32 v144, v74
	v_exp_f32_e32 v145, v75
	s_waitcnt lgkmcnt(0)
; __device__ __forceinline__ float half_max(float v) { auto rr = __builtin_amdgcn_permlane32_swap(__float_as_uint(v), __float_as_uint(v), false, false); return fmaxf(__uint_as_float(rr[0]), __uint_as_float(rr[1])); }
; #define SBAR_() __builtin_amdgcn_sched_barrier(0)
; #define MF_(dst, a_, b_) dst = __builtin_amdgcn_mfma_f32_32x32x16_bf16(a_, b_, dst, 0, 0, 0)
; __device__ __forceinline__ void diff_steady_step(f32x16& s0, f32x16& s1, f32x16& n0, f32x16& n1, const LAS unsigned char* kb, const LAS unsigned char* Vt, const LAS unsigned char* qlds, ...
;     ...
;     lrun += rs;
;     const bf16x8 pa2 = __builtin_bit_cast(bf16x8, w2), pa3 = __builtin_bit_cast(bf16x8, w3);
;     float ra = fmaxf(fmaxf(n0[0], n0[1]), n1[0]), rb = fmaxf(fmaxf(n0[2], n0[3]), n1[1]);
;     MF_(o[0], pa2, va[0]); ra = fmaxf(fmaxf(ra, n1[2]), n1[3]); rb = fmaxf(fmaxf(rb, n0[4]), n0[5]); SBAR_();
;     MF_(o[1], pa2, va[1]); va[0] = DVF_(3, 0); va[1] = DVF_(3, 1); ra = fmaxf(fmaxf(ra, n0[6]), n0[7]); rb = fmaxf(fmaxf(rb, n1[4]), n1[5]); SBAR_();
;     MF_(o[2], pa2, va[2]); va[2] = DVF_(3, 2); ra = fmaxf(fmaxf(ra, n1[6]), n1[7]); rb = fmaxf(fmaxf(rb, n0[8]), n0[9]); SBAR_();
;     MF_(o[3], pa2, va[3]); va[3] = DVF_(3, 3); ra = fmaxf(fmaxf(ra, n0[10]), n0[11]); rb = fmaxf(fmaxf(rb, n1[8]), n1[9]); SBAR_();
;     MF_(o[0], pa3, va[0]); ra = fmaxf(fmaxf(ra, n1[10]), n1[11]); rb = fmaxf(fmaxf(rb, n0[12]), n0[13]); SBAR_();
;     MF_(o[1], pa3, va[1]); ra = fmaxf(fmaxf(ra, n0[14]), n0[15]); rb = fmaxf(fmaxf(rb, n1[12]), n1[13]); SBAR_();
;     MF_(o[2], pa3, va[2]); ra = fmaxf(fmaxf(ra, n1[14]), n1[15]); SBAR_();
;     MF_(o[3], pa3, va[3]);
;     ...
;     rmc = half_max(fmaxf(ra, rb));
; }
	v_mfma_f32_32x32x16_bf16 v[52:67], v[92:95], v[96:99], v[52:67]
	v_exp_f32_e32 v189, v76
	v_exp_f32_e32 v190, v77
	v_mfma_f32_32x32x16_bf16 v[36:51], v[92:95], v[134:137], v[36:51]
	ds_read_b64_tr_b16 v[72:73], v171 offset:10240
	ds_read_b64_tr_b16 v[74:75], v171 offset:12800
	ds_read_b64_tr_b16 v[96:97], v171 offset:10304
	ds_read_b64_tr_b16 v[98:99], v171 offset:12864
	v_exp_f32_e32 v134, v78
	v_exp_f32_e32 v135, v79
	v_mfma_f32_32x32x16_bf16 v[18:33], v[92:95], v[68:71], v[18:33]
	ds_read_b64_tr_b16 v[68:69], v171 offset:10368
	ds_read_b64_tr_b16 v[70:71], v171 offset:12928
	v_exp_f32_e32 v136, v80
	v_exp_f32_e32 v137, v81
	v_mfma_f32_32x32x16_bf16 v[2:17], v[92:95], v[138:141], v[2:17]
	ds_read_b64_tr_b16 v[76:77], v171 offset:10432
	ds_read_b64_tr_b16 v[78:79], v171 offset:12992
	v_exp_f32_e32 v138, v82
	v_exp_f32_e32 v139, v83
	v_cvt_pk_bf16_f32 v81, v134, v135
	v_cvt_pk_bf16_f32 v80, v189, v190
	v_cvt_pk_bf16_f32 v95, v144, v145
	v_cvt_pk_bf16_f32 v94, v142, v143
	v_cvt_pk_bf16_f32 v93, v186, v188
	v_cvt_pk_bf16_f32 v92, v184, v185
	v_cvt_pk_bf16_f32 v82, v136, v137
	v_cvt_pk_bf16_f32 v83, v138, v139
	s_waitcnt lgkmcnt(0)
	v_mfma_f32_32x32x16_bf16 v[52:67], v[92:95], v[72:75], v[52:67]
	v_max_f32_e32 v140, v101, v101
	v_max_f32_e32 v141, v100, v100
	v_max_f32_e32 v140, v141, v140
	v_max3_f32 v141, v102, v103, v117
	v_max3_f32 v140, v140, v116, v118
	v_max3_f32 v141, v141, v104, v105
	v_mfma_f32_32x32x16_bf16 v[36:51], v[92:95], v[96:99], v[36:51]
	ds_read_b64_tr_b16 v[72:73], v171 offset:15360
	ds_read_b64_tr_b16 v[74:75], v171 offset:17920
	ds_read_b64_tr_b16 v[96:97], v171 offset:15424
	ds_read_b64_tr_b16 v[98:99], v171 offset:17984
	v_max3_f32 v140, v140, v119, v106
	v_max3_f32 v141, v141, v120, v121
	v_mfma_f32_32x32x16_bf16 v[18:33], v[92:95], v[68:71], v[18:33]
	ds_read_b64_tr_b16 v[68:69], v171 offset:15488
	ds_read_b64_tr_b16 v[70:71], v171 offset:18048
	v_max3_f32 v140, v140, v107, v122
	v_max3_f32 v141, v141, v108, v109
	v_mfma_f32_32x32x16_bf16 v[2:17], v[92:95], v[76:79], v[2:17]
	ds_read_b64_tr_b16 v[76:77], v171 offset:15552
	ds_read_b64_tr_b16 v[78:79], v171 offset:18112
	v_max3_f32 v92, v140, v123, v110
	v_max3_f32 v93, v141, v124, v125
	s_waitcnt lgkmcnt(0)
	v_mfma_f32_32x32x16_bf16 v[52:67], v[80:83], v[72:75], v[52:67]
	v_max3_f32 v72, v92, v111, v126
	v_max3_f32 v73, v93, v112, v113
	v_mfma_f32_32x32x16_bf16 v[36:51], v[80:83], v[96:99], v[36:51]
	v_max3_f32 v72, v72, v127, v114
	v_max3_f32 v73, v73, v128, v129
	v_mfma_f32_32x32x16_bf16 v[18:33], v[80:83], v[68:71], v[18:33]
	v_max3_f32 v72, v72, v115, v130
	v_add_co_u32_e32 v68, vcc, 0xfe008000, v164
	s_waitcnt vmcnt(0)
	ds_write_b128 v176, v[148:151] offset:37888
	ds_write_b128 v176, v[152:155] offset:46592
	ds_write_b128 v177, v[84:87] offset:17408
	ds_write_b128 v177, v[88:91] offset:27648
	v_addc_co_u32_e32 v69, vcc, -1, v165, vcc
	v_add_co_u32_e32 v70, vcc, 0xfe010000, v164
	s_waitcnt lgkmcnt(0)
	s_barrier
	v_addc_co_u32_e32 v71, vcc, -1, v165, vcc
	global_load_dwordx4 v[148:151], v[68:69], off
	global_load_dwordx4 v[152:155], v[70:71], off
	v_add_f32_e32 v70, v133, v146
	v_add_f32_e32 v70, v147, v70
	v_add_f32_e32 v70, v161, v70
	v_add_f32_e32 v70, v182, v70
	v_add_f32_e32 v70, v183, v70
	v_add_f32_e32 v70, v184, v70
	v_add_f32_e32 v70, v185, v70
	v_add_f32_e32 v70, v186, v70
	v_add_f32_e32 v70, v188, v70
	v_add_f32_e32 v70, v142, v70
	v_add_f32_e32 v70, v143, v70
	v_add_f32_e32 v70, v144, v70
	v_add_f32_e32 v70, v145, v70
	v_add_f32_e32 v70, v189, v70
	v_mfma_f32_32x32x16_bf16 v[2:17], v[80:83], v[76:79], v[2:17]
	v_add_f32_e32 v70, v190, v70
	v_add_f32_e32 v70, v134, v70
	v_max3_f32 v68, v72, v131, v73
	v_add_f32_e32 v70, v135, v70
	v_mov_b32_e32 v69, v68
	v_add_f32_e32 v70, v136, v70
	s_nop 0
	v_permlane32_swap_b32_e32 v68, v69
	v_add_f32_e32 v70, v137, v70
	v_add_f32_e32 v70, v138, v70
	v_max_f32_e32 v69, v69, v69
	v_max_f32_e32 v68, v68, v68
	v_add_f32_e32 v70, v139, v70
	v_max_f32_e32 v68, v68, v69
	v_add_f32_e32 v161, v172, v70
	v_cmp_lt_f32_e32 vcc, s67, v68
	s_cbranch_vccz .LBB0_416
	v_max_f32_e32 v68, v68, v68
	v_max_f32_e32 v68, 0, v68
	v_exp_f32_e64 v69, -v68
	s_and_saveexec_b64 s[8:9], s[6:7]
	s_cbranch_execz .LBB0_415
	ds_write_b32 v170, v69
	s_branch .LBB0_415

; #define DIFF_QK(P0, P1, kt) do { bf16x8 qf[4]; _Pragma("unroll") for (int d0 = 0; d0 < 4; ++d0) qf[d0] = *(const LAS bf16x8*)(qlds + d0 * 32); attn_qk(P0, P1, kt, 272, qf, r32, hi); } while (0)
; #define DIFF_GLOADK(t) do { _Pragma("unroll") for (int i = 0; i < 2; ++i) kreg[i] = *(const u32x4*)(sbase + O_DK + (size_t)(64 * (t) + 32 * i) * QP); } while (0)
; #define DIFF_GLOADV(t) do { _Pragma("unroll") for (int i = 0; i < 2; ++i) vreg[i] = *(const u32x4*)(sbase + O_DV + (size_t)(64 * (t) + 32 * i) * QP); } while (0)
; #define DIFF_LSTOREK(buf) do { _Pragma("unroll") for (int i = 0; i < 2; ++i) *(LAS u32x4*)(lds + (buf) * BUFB + KOFF + (srow + 32 * i) * 272 + sch * 16) = kreg[i]; } while (0)
; #define DIFF_LSTOREV(buf) do { _Pragma("unroll") for (int i = 0; i < 2; ++i) *(LAS u32x4*)(lds + (buf) * BUFB + VOFF + (srow + 32 * i) * DVS + sch * 16) = vreg[i]; } while (0)
; __device__ __forceinline__ void diff_unit(const Params& P, int l, int b, int h, int qb, float lam, float lam_init, LAS unsigned char* lds, bool dry = false) {
;     ...
;     const int qme = q0 + wq * 32 + r32;
;     ...
;     DIFF_GLOADK(0); DIFF_GLOADV(0); DIFF_LSTOREK(0); DIFF_LSTOREV(0);
;     DIFF_GLOADK(1); DIFF_LSTOREK(1);
;     __syncthreads();
;     const float b31 = bt[127];
;     f32x16 s0, s1, n0 = {}, n1 = {};
;     DIFF_INIT(s0, s1, 0); DIFF_QK(s0, s1, lds + KOFF + map * 128);
.LBB0_428:
	s_add_i32 s8, s67, -3
	s_cmp_lt_u32 s8, s80
	s_cselect_b64 s[2:3], -1, 0
	s_cmp_ge_u32 s8, s80
	s_cbranch_scc1 .LBB0_430
	s_waitcnt vmcnt(0)
	v_add_co_u32_e32 v132, vcc, 0x8000, v140
	s_nop 1
	v_addc_co_u32_e32 v133, vcc, 0, v141, vcc
	global_load_dwordx4 v[148:151], v[140:141], off
	global_load_dwordx4 v[152:155], v[132:133], off
.LBB0_430:
	s_waitcnt vmcnt(0)
	v_add_co_u32_e32 v132, vcc, 0x1ff0000, v140
	s_add_i32 s46, s62, s67
	s_nop 0
	v_addc_co_u32_e32 v133, vcc, 0, v141, vcc
	v_add_co_u32_e32 v136, vcc, 0x1ff8000, v140
	s_add_i32 s10, s46, -3
	s_nop 0
	v_addc_co_u32_e32 v137, vcc, 0, v141, vcc
	global_load_dwordx4 v[132:135], v[132:133], off
	s_nop 0
	global_load_dwordx4 v[136:139], v[136:137], off
	s_cmp_lt_i32 s10, s83
	s_cselect_b64 s[42:43], -1, 0
	s_cmp_ge_i32 s10, s83
	s_cbranch_scc1 .LBB0_450
	s_add_i32 s8, s66, 64
	s_cmp_lt_i32 s8, s76
	s_mov_b64 s[8:9], -1
	s_cbranch_scc1 .LBB0_433
	v_add_u32_e32 v100, v175, v212
	v_subrev_u32_e32 v101, 64, v100
	v_add_u32_e32 v103, 0xffffffbf, v100
	v_med3_i32 v102, v101, 0, v223
	v_max_i32_e32 v101, 32, v101
	v_med3_i32 v104, v103, 0, v223
	v_max_i32_e32 v103, 32, v103
	v_add_u32_e32 v105, 0xffffffbe, v100
	v_add_u32_e32 v107, 0xffffffbd, v100
	v_subrev_u32_e32 v101, 32, v101
	v_subrev_u32_e32 v103, 32, v103
	v_med3_i32 v106, v105, 0, v223
	v_max_i32_e32 v105, 32, v105
	v_med3_i32 v108, v107, 0, v223
	v_max_i32_e32 v107, 32, v107
	s_add_i32 s8, 0, 0x13000
	v_min_u32_e32 v101, 0x7f, v101
	v_min_u32_e32 v103, 0x7f, v103
	v_subrev_u32_e32 v105, 32, v105
	v_subrev_u32_e32 v107, 32, v107
	v_lshl_add_u32 v102, v102, 2, s8
	v_lshl_add_u32 v101, v101, 2, s8
	v_lshl_add_u32 v104, v104, 2, s8
	v_lshl_add_u32 v103, v103, 2, s8
	v_lshl_add_u32 v106, v106, 2, s8
	v_min_u32_e32 v105, 0x7f, v105
	v_lshl_add_u32 v108, v108, 2, s8
	v_min_u32_e32 v107, 0x7f, v107
	v_lshl_add_u32 v105, v105, 2, s8
	v_lshl_add_u32 v107, v107, 2, s8
	ds_read_b32 v116, v102
	ds_read_b32 v142, v101
	ds_read_b32 v101, v104
	ds_read_b32 v117, v103
	ds_read_b32 v102, v106
	ds_read_b32 v118, v105
	ds_read_b32 v103, v108
	ds_read_b32 v119, v107
	v_add_u32_e32 v104, 0xffffffb8, v100
	v_add_u32_e32 v106, 0xffffffb7, v100
	v_add_u32_e32 v108, 0xffffffb6, v100
	v_add_u32_e32 v110, 0xffffffb5, v100
	v_med3_i32 v105, v104, 0, v223
	v_max_i32_e32 v104, 32, v104
	v_med3_i32 v107, v106, 0, v223
	v_max_i32_e32 v106, 32, v106
	v_med3_i32 v109, v108, 0, v223
	v_max_i32_e32 v108, 32, v108
	v_med3_i32 v111, v110, 0, v223
	v_max_i32_e32 v110, 32, v110
	v_subrev_u32_e32 v104, 32, v104
	v_subrev_u32_e32 v106, 32, v106
	v_subrev_u32_e32 v108, 32, v108
	v_subrev_u32_e32 v110, 32, v110
	v_min_u32_e32 v104, 0x7f, v104
	v_min_u32_e32 v106, 0x7f, v106
	v_min_u32_e32 v108, 0x7f, v108
	v_min_u32_e32 v110, 0x7f, v110
	v_lshl_add_u32 v105, v105, 2, s8
	v_lshl_add_u32 v104, v104, 2, s8
	v_lshl_add_u32 v107, v107, 2, s8
	v_lshl_add_u32 v106, v106, 2, s8
	v_lshl_add_u32 v108, v108, 2, s8
	v_lshl_add_u32 v110, v110, 2, s8
	v_lshl_add_u32 v109, v109, 2, s8
	v_lshl_add_u32 v111, v111, 2, s8
	ds_read_b32 v105, v105
	ds_read_b32 v120, v104
	ds_read_b32 v107, v107
	ds_read_b32 v121, v106
	ds_read_b32 v106, v109
	ds_read_b32 v122, v108
	ds_read_b32 v108, v111
	ds_read_b32 v123, v110
	v_add_u32_e32 v104, 0xffffffb0, v100
	v_add_u32_e32 v110, 0xffffffaf, v100
	v_add_u32_e32 v112, 0xffffffae, v100
	v_med3_i32 v109, v104, 0, v223
	v_max_i32_e32 v104, 32, v104
	v_med3_i32 v111, v110, 0, v223
	v_max_i32_e32 v110, 32, v110
	v_med3_i32 v113, v112, 0, v223
	v_max_i32_e32 v112, 32, v112
	v_add_u32_e32 v114, 0xffffffad, v100
	v_subrev_u32_e32 v104, 32, v104
	v_subrev_u32_e32 v110, 32, v110
	v_subrev_u32_e32 v112, 32, v112
	v_med3_i32 v115, v114, 0, v223
	v_max_i32_e32 v114, 32, v114
	v_min_u32_e32 v104, 0x7f, v104
	v_min_u32_e32 v110, 0x7f, v110
	v_min_u32_e32 v112, 0x7f, v112
	v_subrev_u32_e32 v114, 32, v114
	v_lshl_add_u32 v109, v109, 2, s8
	v_lshl_add_u32 v104, v104, 2, s8
	v_lshl_add_u32 v111, v111, 2, s8
	v_lshl_add_u32 v110, v110, 2, s8
	v_lshl_add_u32 v112, v112, 2, s8
	v_min_u32_e32 v114, 0x7f, v114
	v_lshl_add_u32 v113, v113, 2, s8
	v_lshl_add_u32 v115, v115, 2, s8
	v_lshl_add_u32 v114, v114, 2, s8
	ds_read_b32 v109, v109
	ds_read_b32 v124, v104
	ds_read_b32 v111, v111
	ds_read_b32 v125, v110
	ds_read_b32 v110, v113
	ds_read_b32 v126, v112
	ds_read_b32 v112, v115
	ds_read_b32 v127, v114
	v_add_u32_e32 v104, 0xffffffa8, v100
	v_med3_i32 v113, v104, 0, v223
	v_max_i32_e32 v104, 32, v104
	v_subrev_u32_e32 v104, 32, v104
	v_min_u32_e32 v104, 0x7f, v104
	v_lshl_add_u32 v114, v104, 2, s8
	v_add_u32_e32 v104, 0xffffffa7, v100
	v_med3_i32 v115, v104, 0, v223
	v_max_i32_e32 v104, 32, v104
	v_subrev_u32_e32 v104, 32, v104
	v_min_u32_e32 v104, 0x7f, v104
	v_lshl_add_u32 v128, v104, 2, s8
	v_add_u32_e32 v104, 0xffffffa6, v100
	v_med3_i32 v129, v104, 0, v223
	v_max_i32_e32 v104, 32, v104
	v_subrev_u32_e32 v104, 32, v104
	v_min_u32_e32 v104, 0x7f, v104
	v_add_u32_e32 v100, 0xffffffa5, v100
	v_lshl_add_u32 v130, v104, 2, s8
	v_med3_i32 v104, v100, 0, v223
	v_max_i32_e32 v100, 32, v100
	v_subrev_u32_e32 v100, 32, v100
	v_lshl_add_u32 v113, v113, 2, s8
	v_lshl_add_u32 v115, v115, 2, s8
	v_lshl_add_u32 v131, v104, 2, s8
	v_min_u32_e32 v100, 0x7f, v100
	v_lshl_add_u32 v129, v129, 2, s8
	s_waitcnt lgkmcnt(0)
	v_sub_f32_e32 v104, v105, v173
	v_sub_f32_e32 v105, v107, v173
	v_sub_f32_e32 v107, v108, v173
	v_sub_f32_e32 v108, v109, v173
	v_sub_f32_e32 v109, v111, v173
	v_sub_f32_e32 v111, v112, v173
	v_lshl_add_u32 v100, v100, 2, s8
	ds_read_b32 v112, v113
	ds_read_b32 v143, v114
	ds_read_b32 v113, v115
	ds_read_b32 v144, v128
	ds_read_b32 v114, v129
	ds_read_b32 v130, v130
	ds_read_b32 v115, v131
	ds_read_b32 v131, v100
	v_sub_f32_e32 v101, v101, v173
	v_sub_f32_e32 v102, v102, v173
	v_sub_f32_e32 v103, v103, v173
	v_sub_f32_e32 v106, v106, v173
	v_sub_f32_e32 v110, v110, v173
	s_waitcnt lgkmcnt(0)
	v_sub_f32_e32 v112, v112, v173
	v_sub_f32_e32 v113, v113, v173
	v_sub_f32_e32 v114, v114, v173
	v_sub_f32_e32 v115, v115, v173
	v_sub_f32_e32 v100, v116, v173
	v_sub_f32_e32 v117, v117, v173
	v_sub_f32_e32 v118, v118, v173
	v_sub_f32_e32 v119, v119, v173
	v_sub_f32_e32 v120, v120, v173
	v_sub_f32_e32 v121, v121, v173
	v_sub_f32_e32 v122, v122, v173
	v_sub_f32_e32 v123, v123, v173
	v_sub_f32_e32 v124, v124, v173
	v_sub_f32_e32 v125, v125, v173
	v_sub_f32_e32 v126, v126, v173
	v_sub_f32_e32 v127, v127, v173
	v_sub_f32_e32 v128, v143, v173
	v_sub_f32_e32 v129, v144, v173
	v_sub_f32_e32 v130, v130, v173
	v_sub_f32_e32 v131, v131, v173
	v_sub_f32_e32 v116, v142, v173
	s_mov_b64 s[8:9], 0

.LBB0_438:
	s_cmp_lt_u32 s67, s58
	s_cselect_b64 s[54:55], -1, 0
	s_cmp_ge_u32 s67, s58
	s_cselect_b64 s[52:53], -1, 0
	s_and_b64 vcc, exec, s[52:53]
	s_waitcnt vmcnt(0) lgkmcnt(0)
	ds_write_b128 v163, v[132:135] offset:17408
	ds_write_b128 v163, v[136:139] offset:27648
	s_waitcnt lgkmcnt(0)
	s_barrier
	s_cbranch_vccnz .LBB0_440
	v_add_co_u32_e32 v142, vcc, 0x10000, v140
	s_nop 1
	v_addc_co_u32_e32 v143, vcc, 0, v141, vcc
	v_add_co_u32_e32 v144, vcc, 0x18000, v140
	s_nop 1
	v_addc_co_u32_e32 v145, vcc, 0, v141, vcc
	global_load_dwordx4 v[148:151], v[142:143], off
	global_load_dwordx4 v[152:155], v[144:145], off
.LBB0_440:
	s_and_b64 vcc, exec, s[8:9]
	s_cbranch_vccnz .LBB0_442
	v_add_co_u32_e32 v132, vcc, 0x2000000, v140
	s_nop 1
	v_addc_co_u32_e32 v133, vcc, 0, v141, vcc
	v_add_co_u32_e32 v136, vcc, 0x2008000, v140
	s_nop 1
	v_addc_co_u32_e32 v137, vcc, 0, v141, vcc
	global_load_dwordx4 v[132:135], v[132:133], off
	s_nop 0
	global_load_dwordx4 v[136:139], v[136:137], off

; __device__ __forceinline__ void diff_unit(const Params& P, int l, int b, int h, int qb, float lam, float lam_init, LAS unsigned char* lds, bool dry = false) {
;     ...
;     if (map == 0) {
;         float ssq[16];
; #pragma unroll
;         for (int r = 0; r < 16; ++r) ssq[r] = 0.f;
; #pragma unroll
;         for (int d = 0; d < 4; ++d)
; #pragma unroll
;             for (int r = 0; r < 16; ++r) { const float v = o[d][r] * il[r] - xch[((wq * 4 + d) * 16 + r) * 64 + lane]; o[d][r] = v; ssq[r] += v * v; }
.LBB0_491:
	s_cmpk_gt_u32 s73, 0xff
	s_waitcnt lgkmcnt(0)
	s_barrier
	s_cbranch_scc1 .LBB0_493
	s_add_i32 s2, 0, 0x13800
	v_lshl_add_u32 v105, v1, 2, s2
	s_lshl_b32 s2, s73, 8
	s_and_b32 s3, s2, 0xc000
	v_add_u32_e32 v106, s3, v105
	ds_read2st64_b32 v[34:35], v106 offset1:1
	s_or_b32 s2, s2, 0x3f00
	v_readlane_b32 s8, v254, 29
	v_readlane_b32 s20, v254, 41
	v_readlane_b32 s21, v254, 42
	s_waitcnt lgkmcnt(0)
	v_fma_f32 v89, v52, v80, -v34
	v_fma_f32 v88, v53, v81, -v35
	ds_read2st64_b32 v[34:35], v106 offset0:2 offset1:3
	v_readlane_b32 s9, v254, 30
	v_readlane_b32 s10, v254, 31
	v_readlane_b32 s11, v254, 32
	v_readlane_b32 s12, v254, 33
	s_waitcnt lgkmcnt(0)
	v_fma_f32 v87, v54, v82, -v34
	v_fma_f32 v86, v55, v83, -v35
	ds_read2st64_b32 v[34:35], v106 offset0:4 offset1:5
	v_readlane_b32 s13, v254, 34
	v_readlane_b32 s14, v254, 35
	v_readlane_b32 s15, v254, 36
	v_readlane_b32 s16, v254, 37
	s_waitcnt lgkmcnt(0)
	v_fma_f32 v85, v56, v76, -v34
	v_fma_f32 v84, v57, v77, -v35
	ds_read2st64_b32 v[34:35], v106 offset0:6 offset1:7
	v_readlane_b32 s17, v254, 38
	v_readlane_b32 s18, v254, 39
	v_readlane_b32 s19, v254, 40
	v_readlane_b32 s22, v254, 43
	s_waitcnt lgkmcnt(0)
	v_fma_f32 v58, v58, v78, -v34
	v_fma_f32 v57, v59, v79, -v35
	ds_read2st64_b32 v[34:35], v106 offset0:8 offset1:9
	v_readlane_b32 s23, v254, 44
	s_waitcnt lgkmcnt(0)
	v_fma_f32 v56, v60, v72, -v34
	v_fma_f32 v55, v61, v73, -v35
	ds_read2st64_b32 v[34:35], v106 offset0:10 offset1:11
	ds_read2st64_b32 v[60:61], v106 offset0:14 offset1:15
	s_waitcnt lgkmcnt(0)
	v_fma_f32 v54, v62, v74, -v34
	v_fma_f32 v53, v63, v75, -v35
	ds_read2st64_b32 v[34:35], v106 offset0:12 offset1:13
	v_fma_f32 v1, v67, v71, -v61
	s_waitcnt lgkmcnt(0)
	v_fma_f32 v52, v64, v68, -v34
	v_fma_f32 v34, v66, v70, -v60
	ds_read2st64_b32 v[60:61], v106 offset0:16 offset1:17
	v_fma_f32 v35, v65, v69, -v35
	s_waitcnt lgkmcnt(0)
	v_fma_f32 v66, v36, v80, -v60
	v_fma_f32 v65, v37, v81, -v61
	ds_read2st64_b32 v[36:37], v106 offset0:18 offset1:19
	v_mul_f32_e32 v107, v66, v66
	v_fmac_f32_e32 v107, v89, v89
	v_mul_f32_e32 v104, v65, v65
	v_fmac_f32_e32 v104, v88, v88
	s_waitcnt lgkmcnt(0)
	v_fma_f32 v64, v38, v82, -v36
	v_fma_f32 v63, v39, v83, -v37
	ds_read2st64_b32 v[36:37], v106 offset0:20 offset1:21
	v_mul_f32_e32 v103, v64, v64
	v_fmac_f32_e32 v103, v87, v87
	v_mul_f32_e32 v102, v63, v63
	v_fmac_f32_e32 v102, v86, v86
	s_waitcnt lgkmcnt(0)
	v_fma_f32 v61, v40, v76, -v36
	v_fma_f32 v59, v41, v77, -v37
	ds_read2st64_b32 v[36:37], v106 offset0:22 offset1:23
	v_mul_f32_e32 v101, v61, v61
	v_fmac_f32_e32 v101, v85, v85
	v_mul_f32_e32 v99, v59, v59
	v_fmac_f32_e32 v99, v84, v84
	s_waitcnt lgkmcnt(0)
	v_fma_f32 v62, v42, v78, -v36
	v_fma_f32 v60, v43, v79, -v37
	ds_read2st64_b32 v[36:37], v106 offset0:24 offset1:25
	v_mul_f32_e32 v100, v62, v62
	v_fmac_f32_e32 v100, v58, v58
	v_mul_f32_e32 v96, v60, v60
	v_fmac_f32_e32 v96, v57, v57
	s_waitcnt lgkmcnt(0)
	v_fma_f32 v43, v44, v72, -v36
	v_fma_f32 v42, v45, v73, -v37
	ds_read2st64_b32 v[36:37], v106 offset0:26 offset1:27
	ds_read2st64_b32 v[44:45], v106 offset0:30 offset1:31
	v_mul_f32_e32 v95, v43, v43
	v_fmac_f32_e32 v95, v56, v56
	v_mul_f32_e32 v90, v42, v42
	s_waitcnt lgkmcnt(0)
	v_fma_f32 v41, v46, v74, -v36
	v_fma_f32 v40, v47, v75, -v37
	ds_read2st64_b32 v[36:37], v106 offset0:28 offset1:29
	v_fma_f32 v39, v50, v70, -v44
	v_fmac_f32_e32 v90, v55, v55
	v_mul_f32_e32 v92, v41, v41
	v_fmac_f32_e32 v92, v54, v54
	s_waitcnt lgkmcnt(0)
	v_fma_f32 v38, v48, v68, -v36
	v_fma_f32 v36, v49, v69, -v37
	v_fma_f32 v37, v51, v71, -v45
	ds_read2st64_b32 v[44:45], v106 offset0:32 offset1:33
	v_mul_f32_e32 v91, v40, v40
	v_fmac_f32_e32 v91, v53, v53
	v_mul_f32_e32 v94, v38, v38
	v_fmac_f32_e32 v94, v52, v52
	s_waitcnt lgkmcnt(0)
	v_fma_f32 v51, v18, v80, -v44
	v_fma_f32 v50, v19, v81, -v45
	ds_read2st64_b32 v[18:19], v106 offset0:34 offset1:35
	v_fmac_f32_e32 v107, v51, v51
	v_fmac_f32_e32 v104, v50, v50
	v_mul_f32_e32 v93, v36, v36
	v_fmac_f32_e32 v93, v35, v35
	s_waitcnt lgkmcnt(0)
	v_fma_f32 v49, v20, v82, -v18
	v_fma_f32 v48, v21, v83, -v19
	ds_read2st64_b32 v[18:19], v106 offset0:36 offset1:37
	v_fmac_f32_e32 v103, v49, v49
	v_fmac_f32_e32 v102, v48, v48
	v_mul_f32_e32 v98, v39, v39
	v_fmac_f32_e32 v98, v34, v34
	s_waitcnt lgkmcnt(0)
	v_fma_f32 v47, v22, v76, -v18
	v_fma_f32 v45, v23, v77, -v19
	ds_read2st64_b32 v[18:19], v106 offset0:38 offset1:39
	v_fmac_f32_e32 v101, v47, v47
	v_fmac_f32_e32 v99, v45, v45
	v_mul_f32_e32 v97, v37, v37
	v_fmac_f32_e32 v97, v1, v1
	s_waitcnt lgkmcnt(0)
	v_fma_f32 v46, v24, v78, -v18
	v_fma_f32 v44, v25, v79, -v19
	ds_read2st64_b32 v[18:19], v106 offset0:40 offset1:41
	v_fmac_f32_e32 v100, v46, v46
	v_fmac_f32_e32 v96, v44, v44
	s_waitcnt lgkmcnt(0)
	v_fma_f32 v25, v26, v72, -v18
	v_fma_f32 v24, v27, v73, -v19
	ds_read2st64_b32 v[18:19], v106 offset0:42 offset1:43
	ds_read2st64_b32 v[26:27], v106 offset0:46 offset1:47
	v_fmac_f32_e32 v95, v25, v25
	v_fmac_f32_e32 v90, v24, v24
	s_waitcnt lgkmcnt(0)
	v_fma_f32 v23, v28, v74, -v18
	v_fma_f32 v22, v29, v75, -v19
	ds_read2st64_b32 v[18:19], v106 offset0:44 offset1:45
	v_fma_f32 v20, v32, v70, -v26
	v_fmac_f32_e32 v92, v23, v23
	v_fmac_f32_e32 v91, v22, v22
	v_fmac_f32_e32 v98, v20, v20
	s_waitcnt lgkmcnt(0)
	v_fma_f32 v21, v30, v68, -v18
	v_fma_f32 v18, v33, v71, -v27
	ds_read2st64_b32 v[26:27], v106 offset0:48 offset1:49
	v_fma_f32 v19, v31, v69, -v19
	v_fmac_f32_e32 v94, v21, v21
	v_fmac_f32_e32 v93, v19, v19
	v_fmac_f32_e32 v97, v18, v18
	s_waitcnt lgkmcnt(0)
	v_fma_f32 v67, v2, v80, -v26
	v_fma_f32 v33, v3, v81, -v27
	ds_read2st64_b32 v[2:3], v106 offset0:50 offset1:51
	v_fmac_f32_e32 v107, v67, v67
	v_fmac_f32_e32 v104, v33, v33
	s_waitcnt lgkmcnt(0)
; __device__ __forceinline__ float fast_rsq(float x) { return __builtin_amdgcn_rsqf(x); }
; __device__ __forceinline__ int crow(int r, int hi) { return (r & 3) + 8 * (r >> 2) + 4 * hi; }
; __device__ __forceinline__ void diff_unit(const Params& P, int l, int b, int h, int qb, float lam, float lam_init, LAS unsigned char* lds, bool dry = false) {
;     ...
;             for (int r = 0; r < 16; ++r) { const float v = o[d][r] * il[r] - xch[((wq * 4 + d) * 16 + r) * 64 + lane]; o[d][r] = v; ssq[r] += v * v; }
; #pragma unroll
;         for (int r = 0; r < 16; ++r) {
; #pragma unroll
;             for (int s = 1; s < 32; s <<= 1) ssq[r] += __shfl_xor(ssq[r], s);
;         }
;         const float post = 1.0f - lam_init;
;         float gsub[4];
; #pragma unroll
;         for (int d = 0; d < 4; ++d) gsub[d] = P.in[I_SUBG][l * 128 + 32 * d + r32] * post;
;         bf16_t* Ow = proj + O_DQ + (rowb + q0 + wq * 32) * QP + h * 128;
; #pragma unroll
;         for (int r = 0; r < 16; ++r) { const int q = crow(r, hi); const float rstd = fast_rsq(ssq[r] * (1.0f / 128.0f) + EPS);
	v_fma_f32 v32, v4, v82, -v2
	v_fma_f32 v31, v5, v83, -v3
	ds_read2st64_b32 v[2:3], v106 offset0:52 offset1:53
	v_fmac_f32_e32 v103, v32, v32
	v_fmac_f32_e32 v102, v31, v31
	s_waitcnt lgkmcnt(0)
	v_fma_f32 v30, v6, v76, -v2
	v_fma_f32 v28, v7, v77, -v3
	ds_read2st64_b32 v[2:3], v106 offset0:54 offset1:55
	v_fmac_f32_e32 v101, v30, v30
	v_fmac_f32_e32 v99, v28, v28
	v_or_b32_e32 v76, s64, v167
	v_mov_b32_e32 v77, v0
	s_waitcnt lgkmcnt(0)
	v_fma_f32 v29, v8, v78, -v2
	v_fma_f32 v27, v9, v79, -v3
	ds_read2st64_b32 v[2:3], v106 offset0:56 offset1:57
	v_fmac_f32_e32 v100, v29, v29
	v_fmac_f32_e32 v96, v27, v27
	v_lshl_add_u64 v[80:81], v[76:77], 2, s[20:21]
	s_waitcnt lgkmcnt(0)
	v_fma_f32 v26, v10, v72, -v2
	v_fma_f32 v10, v11, v73, -v3
	ds_read2st64_b32 v[2:3], v106 offset0:58 offset1:59
	v_fmac_f32_e32 v95, v26, v26
	v_fmac_f32_e32 v90, v10, v10
	s_waitcnt lgkmcnt(0)
	v_fma_f32 v9, v12, v74, -v2
	v_fma_f32 v8, v13, v75, -v3
	ds_read2st64_b32 v[2:3], v106 offset0:60 offset1:61
	v_fmac_f32_e32 v92, v9, v9
	v_fmac_f32_e32 v91, v8, v8
	s_waitcnt lgkmcnt(0)
	v_fma_f32 v7, v14, v68, -v2
	ds_read_b32 v2, v106 offset:15872
	v_fma_f32 v6, v15, v69, -v3
	v_fmac_f32_e32 v94, v7, v7
	v_fmac_f32_e32 v93, v6, v6
	s_waitcnt lgkmcnt(0)
	v_fma_f32 v5, v16, v70, -v2
	v_add_u32_e32 v2, s2, v105
	ds_read_b32 v2, v2
	v_fmac_f32_e32 v98, v5, v5
	s_lshl_b64 s[2:3], s[50:51], 10
	s_add_u32 s2, s90, s2
	s_addc_u32 s3, s91, s3
	s_waitcnt lgkmcnt(0)
	v_fma_f32 v4, v17, v71, -v2
	ds_bpermute_b32 v2, v225, v107
	v_fmac_f32_e32 v97, v4, v4
	s_lshl_b32 s6, s82, 1
	s_add_u32 s2, s2, s6
	s_addc_u32 s3, s3, 0
	s_waitcnt lgkmcnt(0)
	v_add_f32_e32 v2, v107, v2
	ds_bpermute_b32 v3, v221, v2
	s_waitcnt lgkmcnt(0)
	v_add_f32_e32 v2, v2, v3
	ds_bpermute_b32 v3, v222, v2
	s_waitcnt lgkmcnt(0)
	v_add_f32_e32 v2, v2, v3
	ds_bpermute_b32 v3, v252, v2
	s_waitcnt lgkmcnt(0)
	v_add_f32_e32 v2, v2, v3
	ds_bpermute_b32 v3, v253, v2
	s_waitcnt lgkmcnt(0)
	v_add_f32_e32 v2, v2, v3
	ds_bpermute_b32 v3, v225, v104
	v_fmamk_f32 v2, v2, 0x3c000000, v216
	v_rsq_f32_e32 v82, v2
	v_lshlrev_b32_e32 v2, 12, v166
	s_waitcnt lgkmcnt(0)
	v_add_f32_e32 v3, v104, v3
	ds_bpermute_b32 v11, v221, v3
	v_mul_f32_e32 v66, v66, v82
	v_mul_f32_e32 v51, v51, v82
	s_waitcnt lgkmcnt(0)
	v_add_f32_e32 v3, v3, v11
	ds_bpermute_b32 v11, v222, v3
	s_waitcnt lgkmcnt(0)
	v_add_f32_e32 v3, v3, v11
	ds_bpermute_b32 v11, v252, v3
	s_waitcnt lgkmcnt(0)
	v_add_f32_e32 v3, v3, v11
	ds_bpermute_b32 v11, v253, v3
	s_waitcnt lgkmcnt(0)
	v_add_f32_e32 v15, v3, v11
	ds_bpermute_b32 v3, v225, v103
	v_fmamk_f32 v15, v15, 0x3c000000, v216
	v_rsq_f32_e32 v15, v15
	s_waitcnt lgkmcnt(0)
	v_add_f32_e32 v3, v103, v3
	ds_bpermute_b32 v11, v221, v3
	v_mul_f32_e32 v50, v50, v15
	s_waitcnt lgkmcnt(0)
	v_add_f32_e32 v3, v3, v11
	ds_bpermute_b32 v11, v222, v3
	s_waitcnt lgkmcnt(0)
	v_add_f32_e32 v3, v3, v11
	ds_bpermute_b32 v11, v252, v3
	s_waitcnt lgkmcnt(0)
	v_add_f32_e32 v3, v3, v11
	ds_bpermute_b32 v11, v253, v3
	s_waitcnt lgkmcnt(0)
	v_add_f32_e32 v16, v3, v11
	ds_bpermute_b32 v3, v225, v102
	s_waitcnt lgkmcnt(0)
	v_add_f32_e32 v3, v102, v3
	ds_bpermute_b32 v11, v221, v3
	s_waitcnt lgkmcnt(0)
	v_add_f32_e32 v3, v3, v11
	ds_bpermute_b32 v11, v222, v3
	s_waitcnt lgkmcnt(0)
	v_add_f32_e32 v3, v3, v11
	ds_bpermute_b32 v11, v252, v3
	s_waitcnt lgkmcnt(0)
	v_add_f32_e32 v3, v3, v11
	ds_bpermute_b32 v11, v253, v3
	s_waitcnt lgkmcnt(0)
	v_add_f32_e32 v68, v3, v11
	ds_bpermute_b32 v3, v225, v101
	s_waitcnt lgkmcnt(0)
	v_add_f32_e32 v3, v101, v3
	ds_bpermute_b32 v11, v221, v3
	s_waitcnt lgkmcnt(0)
	v_add_f32_e32 v3, v3, v11
	ds_bpermute_b32 v11, v222, v3
	s_waitcnt lgkmcnt(0)
	v_add_f32_e32 v3, v3, v11
	ds_bpermute_b32 v11, v252, v3
	s_waitcnt lgkmcnt(0)
	v_add_f32_e32 v3, v3, v11
	ds_bpermute_b32 v11, v253, v3
	s_waitcnt lgkmcnt(0)
	v_add_f32_e32 v69, v3, v11
	ds_bpermute_b32 v3, v225, v99
	s_waitcnt lgkmcnt(0)
	v_add_f32_e32 v3, v99, v3
	ds_bpermute_b32 v11, v221, v3
	s_waitcnt lgkmcnt(0)
	v_add_f32_e32 v3, v3, v11
	ds_bpermute_b32 v11, v222, v3
	s_waitcnt lgkmcnt(0)
	v_add_f32_e32 v3, v3, v11
	ds_bpermute_b32 v11, v252, v3
	s_waitcnt lgkmcnt(0)
	v_add_f32_e32 v3, v3, v11
	ds_bpermute_b32 v11, v253, v3
	s_waitcnt lgkmcnt(0)
	v_add_f32_e32 v70, v3, v11
	ds_bpermute_b32 v3, v225, v100
	s_waitcnt lgkmcnt(0)
	v_add_f32_e32 v3, v100, v3
	ds_bpermute_b32 v11, v221, v3
	s_waitcnt lgkmcnt(0)
	v_add_f32_e32 v3, v3, v11
	ds_bpermute_b32 v11, v222, v3
	s_waitcnt lgkmcnt(0)
	v_add_f32_e32 v3, v3, v11
	ds_bpermute_b32 v11, v252, v3
	s_waitcnt lgkmcnt(0)
	v_add_f32_e32 v3, v3, v11
	ds_bpermute_b32 v11, v253, v3
	s_waitcnt lgkmcnt(0)
	v_add_f32_e32 v72, v3, v11
	ds_bpermute_b32 v3, v225, v96
	s_waitcnt lgkmcnt(0)
	v_add_f32_e32 v3, v96, v3
	ds_bpermute_b32 v11, v221, v3
	s_waitcnt lgkmcnt(0)
	v_add_f32_e32 v3, v3, v11
	ds_bpermute_b32 v11, v222, v3
	s_waitcnt lgkmcnt(0)
	v_add_f32_e32 v3, v3, v11
	ds_bpermute_b32 v11, v252, v3
	s_waitcnt lgkmcnt(0)
	v_add_f32_e32 v3, v3, v11
	ds_bpermute_b32 v11, v253, v3
	s_waitcnt lgkmcnt(0)
	v_add_f32_e32 v73, v3, v11
	ds_bpermute_b32 v3, v225, v95
	s_waitcnt lgkmcnt(0)
	v_add_f32_e32 v3, v95, v3
	ds_bpermute_b32 v11, v221, v3
	s_waitcnt lgkmcnt(0)
	v_add_f32_e32 v3, v3, v11
	ds_bpermute_b32 v11, v222, v3
	s_waitcnt lgkmcnt(0)
	v_add_f32_e32 v3, v3, v11
	ds_bpermute_b32 v11, v252, v3
	s_waitcnt lgkmcnt(0)
	v_add_f32_e32 v3, v3, v11
	ds_bpermute_b32 v11, v253, v3
	s_waitcnt lgkmcnt(0)
	v_add_f32_e32 v75, v3, v11
	ds_bpermute_b32 v3, v225, v90
	s_waitcnt lgkmcnt(0)
	v_add_f32_e32 v3, v90, v3
	ds_bpermute_b32 v11, v221, v3
	s_waitcnt lgkmcnt(0)
	v_add_f32_e32 v3, v3, v11
	ds_bpermute_b32 v11, v222, v3
	s_waitcnt lgkmcnt(0)
; __device__ __forceinline__ unsigned f2bf(float f) { unsigned u = __builtin_bit_cast(unsigned, f); return (u + 0x7fffu + ((u >> 16) & 1u)) >> 16; }
; __device__ __forceinline__ float fast_rsq(float x) { return __builtin_amdgcn_rsqf(x); }
; __device__ __forceinline__ int crow(int r, int hi) { return (r & 3) + 8 * (r >> 2) + 4 * hi; }
; __device__ __forceinline__ void diff_unit(const Params& P, int l, int b, int h, int qb, float lam, float lam_init, LAS unsigned char* lds, bool dry = false) {
;     ...
;         for (int r = 0; r < 16; ++r) {
; #pragma unroll
;             for (int s = 1; s < 32; s <<= 1) ssq[r] += __shfl_xor(ssq[r], s);
;         }
;         const float post = 1.0f - lam_init;
;         float gsub[4];
; #pragma unroll
;         for (int d = 0; d < 4; ++d) gsub[d] = P.in[I_SUBG][l * 128 + 32 * d + r32] * post;
;         bf16_t* Ow = proj + O_DQ + (rowb + q0 + wq * 32) * QP + h * 128;
; #pragma unroll
;         for (int r = 0; r < 16; ++r) { const int q = crow(r, hi); const float rstd = fast_rsq(ssq[r] * (1.0f / 128.0f) + EPS);
; #pragma unroll
;             for (int d = 0; d < 4; ++d) if (!dry || o[d][r] == 1.2345e30f) Ow[(size_t)q * QP + 32 * d + r32] = (bf16_t)f2bf(o[d][r] * rstd * gsub[d]); }
	v_add_f32_e32 v3, v3, v11
	ds_bpermute_b32 v11, v252, v3
	s_waitcnt lgkmcnt(0)
	v_add_f32_e32 v3, v3, v11
	ds_bpermute_b32 v11, v253, v3
	s_waitcnt lgkmcnt(0)
	v_add_f32_e32 v74, v3, v11
	ds_bpermute_b32 v3, v225, v92
	s_waitcnt lgkmcnt(0)
	v_add_f32_e32 v3, v92, v3
	ds_bpermute_b32 v11, v221, v3
	s_waitcnt lgkmcnt(0)
	v_add_f32_e32 v3, v3, v11
	ds_bpermute_b32 v11, v222, v3
	s_waitcnt lgkmcnt(0)
	v_add_f32_e32 v3, v3, v11
	ds_bpermute_b32 v11, v252, v3
	s_waitcnt lgkmcnt(0)
	v_add_f32_e32 v3, v3, v11
	ds_bpermute_b32 v11, v253, v3
	s_waitcnt lgkmcnt(0)
	v_add_f32_e32 v71, v3, v11
	ds_bpermute_b32 v3, v225, v91
	s_waitcnt lgkmcnt(0)
	v_add_f32_e32 v3, v91, v3
	ds_bpermute_b32 v11, v221, v3
	s_waitcnt lgkmcnt(0)
	v_add_f32_e32 v3, v3, v11
	ds_bpermute_b32 v11, v222, v3
	s_waitcnt lgkmcnt(0)
	v_add_f32_e32 v3, v3, v11
	ds_bpermute_b32 v11, v252, v3
	s_waitcnt lgkmcnt(0)
	v_add_f32_e32 v3, v3, v11
	ds_bpermute_b32 v11, v253, v3
	s_waitcnt lgkmcnt(0)
	v_add_f32_e32 v17, v3, v11
	ds_bpermute_b32 v3, v225, v94
	s_waitcnt lgkmcnt(0)
	v_add_f32_e32 v3, v94, v3
	ds_bpermute_b32 v11, v221, v3
	s_waitcnt lgkmcnt(0)
	v_add_f32_e32 v3, v3, v11
	ds_bpermute_b32 v11, v222, v3
	s_waitcnt lgkmcnt(0)
	v_add_f32_e32 v3, v3, v11
	ds_bpermute_b32 v11, v252, v3
	s_waitcnt lgkmcnt(0)
	v_add_f32_e32 v3, v3, v11
	ds_bpermute_b32 v11, v253, v3
	s_waitcnt lgkmcnt(0)
	v_add_f32_e32 v14, v3, v11
	ds_bpermute_b32 v3, v225, v93
	s_waitcnt lgkmcnt(0)
	v_add_f32_e32 v3, v93, v3
	ds_bpermute_b32 v11, v221, v3
	s_waitcnt lgkmcnt(0)
	v_add_f32_e32 v3, v3, v11
	ds_bpermute_b32 v11, v222, v3
	s_waitcnt lgkmcnt(0)
	v_add_f32_e32 v3, v3, v11
	ds_bpermute_b32 v11, v252, v3
	s_waitcnt lgkmcnt(0)
	v_add_f32_e32 v3, v3, v11
	ds_bpermute_b32 v11, v253, v3
	s_waitcnt lgkmcnt(0)
	v_add_f32_e32 v13, v3, v11
	ds_bpermute_b32 v3, v225, v98
	s_waitcnt lgkmcnt(0)
	v_add_f32_e32 v3, v98, v3
	ds_bpermute_b32 v11, v221, v3
	s_waitcnt lgkmcnt(0)
	v_add_f32_e32 v3, v3, v11
	ds_bpermute_b32 v11, v222, v3
	s_waitcnt lgkmcnt(0)
	v_add_f32_e32 v3, v3, v11
	ds_bpermute_b32 v11, v252, v3
	s_waitcnt lgkmcnt(0)
	v_add_f32_e32 v3, v3, v11
	ds_bpermute_b32 v11, v253, v3
	s_waitcnt lgkmcnt(0)
	v_add_f32_e32 v12, v3, v11
	ds_bpermute_b32 v3, v225, v97
	s_waitcnt lgkmcnt(0)
	v_add_f32_e32 v3, v97, v3
	ds_bpermute_b32 v11, v221, v3
	s_waitcnt lgkmcnt(0)
	v_add_f32_e32 v3, v3, v11
	ds_bpermute_b32 v11, v222, v3
	s_waitcnt lgkmcnt(0)
	v_add_f32_e32 v3, v3, v11
	ds_bpermute_b32 v11, v252, v3
	s_waitcnt lgkmcnt(0)
	v_add_f32_e32 v3, v3, v11
	ds_bpermute_b32 v11, v253, v3
	s_waitcnt lgkmcnt(0)
	v_add_f32_e32 v11, v3, v11
	global_load_dword v3, v[80:81], off
	s_waitcnt vmcnt(0)
	v_mul_f32_e32 v76, v194, v3
	global_load_dword v3, v[80:81], off offset:128
	s_waitcnt vmcnt(0)
	v_mul_f32_e32 v77, v194, v3
	global_load_dword v3, v[80:81], off offset:256
	v_mul_f32_e32 v66, v66, v77
	s_waitcnt vmcnt(0)
	v_mul_f32_e32 v78, v194, v3
	global_load_dword v3, v[80:81], off offset:384
	v_lshlrev_b32_e32 v80, 1, v167
	v_mov_b32_e32 v81, v0
	v_lshl_add_u64 v[80:81], s[2:3], 0, v[80:81]
	v_mul_f32_e32 v51, v51, v78
	s_movk_i32 s2, 0x4000
	v_mul_f32_e32 v50, v50, v78
	s_waitcnt vmcnt(0)
	v_mul_f32_e32 v79, v194, v3
	v_mov_b32_e32 v3, v0
	v_lshl_add_u64 v[2:3], v[80:81], 0, v[2:3]
	v_mul_f32_e32 v80, v89, v82
	v_mul_f32_e32 v80, v80, v76
	v_bfe_u32 v81, v80, 16, 1
	v_add3_u32 v80, v80, v81, s60
	global_store_short_d16_hi v[2:3], v80, off
	v_bfe_u32 v80, v66, 16, 1
	v_add3_u32 v66, v66, v80, s60
	global_store_short_d16_hi v[2:3], v66, off offset:64
	v_bfe_u32 v66, v51, 16, 1
	v_add3_u32 v51, v51, v66, s60
	global_store_short_d16_hi v[2:3], v51, off offset:128
	v_mul_f32_e32 v51, v67, v82
	v_mul_f32_e32 v51, v51, v79
	v_bfe_u32 v66, v51, 16, 1
	v_add3_u32 v51, v51, v66, s60
	global_store_short_d16_hi v[2:3], v51, off offset:192
	v_mul_f32_e32 v51, v88, v15
	v_mul_f32_e32 v51, v51, v76
	v_bfe_u32 v66, v51, 16, 1
	v_add3_u32 v51, v51, v66, s60
	global_store_short_d16_hi v[2:3], v51, off offset:1024
	v_mul_f32_e32 v51, v65, v15
	v_mul_f32_e32 v15, v33, v15
	v_mul_f32_e32 v15, v15, v79
	v_bfe_u32 v33, v15, 16, 1
	v_add3_u32 v15, v15, v33, s60
	global_store_short_d16_hi v[2:3], v15, off offset:1216
	v_fmamk_f32 v15, v16, 0x3c000000, v216
	v_rsq_f32_e32 v15, v15
	v_mul_f32_e32 v51, v51, v77
	v_bfe_u32 v65, v51, 16, 1
	v_add3_u32 v51, v51, v65, s60
	v_mul_f32_e32 v16, v87, v15
	v_mul_f32_e32 v16, v16, v76
	v_bfe_u32 v33, v16, 16, 1
	v_add3_u32 v16, v16, v33, s60
	global_store_short_d16_hi v[2:3], v16, off offset:2048
	v_mul_f32_e32 v16, v64, v15
	v_mul_f32_e32 v16, v16, v77
	v_bfe_u32 v33, v16, 16, 1
	v_add3_u32 v16, v16, v33, s60
	global_store_short_d16_hi v[2:3], v16, off offset:2112
	v_mul_f32_e32 v16, v49, v15
	v_mul_f32_e32 v16, v16, v78
	v_bfe_u32 v33, v16, 16, 1
	v_mul_f32_e32 v15, v32, v15
	v_add3_u32 v16, v16, v33, s60
	v_mul_f32_e32 v15, v15, v79
	global_store_short_d16_hi v[2:3], v16, off offset:2176
	v_bfe_u32 v16, v15, 16, 1
	v_add3_u32 v15, v15, v16, s60
	global_store_short_d16_hi v[2:3], v15, off offset:2240
	v_fmamk_f32 v15, v68, 0x3c000000, v216
	v_rsq_f32_e32 v15, v15
	global_store_short_d16_hi v[2:3], v51, off offset:1088
	v_bfe_u32 v51, v50, 16, 1
	v_add3_u32 v50, v50, v51, s60
	v_mul_f32_e32 v16, v86, v15
	v_mul_f32_e32 v16, v16, v76
	v_bfe_u32 v32, v16, 16, 1
	v_add3_u32 v16, v16, v32, s60
	global_store_short_d16_hi v[2:3], v16, off offset:3072
	v_mul_f32_e32 v16, v63, v15
	v_mul_f32_e32 v16, v16, v77
	v_bfe_u32 v32, v16, 16, 1
	v_add3_u32 v16, v16, v32, s60
	global_store_short_d16_hi v[2:3], v16, off offset:3136
	v_mul_f32_e32 v16, v48, v15
	v_mul_f32_e32 v16, v16, v78
	v_bfe_u32 v32, v16, 16, 1
	v_mul_f32_e32 v15, v31, v15
; __device__ __forceinline__ unsigned f2bf(float f) { unsigned u = __builtin_bit_cast(unsigned, f); return (u + 0x7fffu + ((u >> 16) & 1u)) >> 16; }
; __device__ __forceinline__ float fast_rsq(float x) { return __builtin_amdgcn_rsqf(x); }
; __device__ __forceinline__ int crow(int r, int hi) { return (r & 3) + 8 * (r >> 2) + 4 * hi; }
; __device__ __forceinline__ void diff_unit(const Params& P, int l, int b, int h, int qb, float lam, float lam_init, LAS unsigned char* lds, bool dry = false) {
;     ...
;         for (int r = 0; r < 16; ++r) { const int q = crow(r, hi); const float rstd = fast_rsq(ssq[r] * (1.0f / 128.0f) + EPS);
; #pragma unroll
;             for (int d = 0; d < 4; ++d) if (!dry || o[d][r] == 1.2345e30f) Ow[(size_t)q * QP + 32 * d + r32] = (bf16_t)f2bf(o[d][r] * rstd * gsub[d]); }
	v_add3_u32 v16, v16, v32, s60
	v_mul_f32_e32 v15, v15, v79
	global_store_short_d16_hi v[2:3], v16, off offset:3200
	v_bfe_u32 v16, v15, 16, 1
	v_add3_u32 v15, v15, v16, s60
	global_store_short_d16_hi v[2:3], v15, off offset:3264
	v_fmamk_f32 v15, v69, 0x3c000000, v216
	v_rsq_f32_e32 v15, v15
	v_add_co_u32_e32 v32, vcc, s77, v2
	global_store_short_d16_hi v[2:3], v50, off offset:1152
	v_mul_f32_e32 v16, v85, v15
	v_mul_f32_e32 v16, v16, v76
	v_bfe_u32 v31, v16, 16, 1
	v_add3_u32 v16, v16, v31, s60
	v_addc_co_u32_e32 v33, vcc, 0, v3, vcc
	global_store_short_d16_hi v[32:33], v16, off
	v_mul_f32_e32 v16, v61, v15
	v_mul_f32_e32 v16, v16, v77
	v_bfe_u32 v31, v16, 16, 1
	v_add3_u32 v16, v16, v31, s60
	global_store_short_d16_hi v[32:33], v16, off offset:64
	v_mul_f32_e32 v16, v47, v15
	v_mul_f32_e32 v16, v16, v78
	v_bfe_u32 v31, v16, 16, 1
	v_mul_f32_e32 v15, v30, v15
	v_add3_u32 v16, v16, v31, s60
	v_mul_f32_e32 v15, v15, v79
	global_store_short_d16_hi v[32:33], v16, off offset:128
	v_bfe_u32 v16, v15, 16, 1
	v_add3_u32 v15, v15, v16, s60
	global_store_short_d16_hi v[32:33], v15, off offset:192
	v_fmamk_f32 v15, v70, 0x3c000000, v216
	v_rsq_f32_e32 v15, v15
	s_nop 0
	v_mul_f32_e32 v16, v84, v15
	v_mul_f32_e32 v16, v16, v76
	v_bfe_u32 v30, v16, 16, 1
	v_add3_u32 v16, v16, v30, s60
	global_store_short_d16_hi v[32:33], v16, off offset:1024
	v_mul_f32_e32 v16, v59, v15
	v_mul_f32_e32 v16, v16, v77
	v_bfe_u32 v30, v16, 16, 1
	v_add3_u32 v16, v16, v30, s60
	global_store_short_d16_hi v[32:33], v16, off offset:1088
	v_mul_f32_e32 v16, v45, v15
	v_mul_f32_e32 v16, v16, v78
	v_bfe_u32 v30, v16, 16, 1
	v_mul_f32_e32 v15, v28, v15
	v_add3_u32 v16, v16, v30, s60
	v_mul_f32_e32 v15, v15, v79
	global_store_short_d16_hi v[32:33], v16, off offset:1152
	v_bfe_u32 v16, v15, 16, 1
	v_add3_u32 v15, v15, v16, s60
	global_store_short_d16_hi v[32:33], v15, off offset:1216
	v_fmamk_f32 v15, v72, 0x3c000000, v216
	v_rsq_f32_e32 v15, v15
	s_nop 0
	v_mul_f32_e32 v16, v58, v15
	v_mul_f32_e32 v16, v16, v76
	v_bfe_u32 v28, v16, 16, 1
	v_add3_u32 v16, v16, v28, s60
	global_store_short_d16_hi v[32:33], v16, off offset:2048
	v_mul_f32_e32 v16, v62, v15
	v_mul_f32_e32 v16, v16, v77
	v_bfe_u32 v28, v16, 16, 1
	v_add3_u32 v16, v16, v28, s60
	global_store_short_d16_hi v[32:33], v16, off offset:2112
	v_mul_f32_e32 v16, v46, v15
	v_mul_f32_e32 v16, v16, v78
	v_bfe_u32 v28, v16, 16, 1
	v_mul_f32_e32 v15, v29, v15
	v_add3_u32 v16, v16, v28, s60
	v_mul_f32_e32 v15, v15, v79
	global_store_short_d16_hi v[32:33], v16, off offset:2176
	v_bfe_u32 v16, v15, 16, 1
	v_add3_u32 v15, v15, v16, s60
	global_store_short_d16_hi v[32:33], v15, off offset:2240
	v_fmamk_f32 v15, v73, 0x3c000000, v216
	v_rsq_f32_e32 v15, v15
	s_nop 0
	v_mul_f32_e32 v16, v57, v15
	v_mul_f32_e32 v16, v16, v76
	v_bfe_u32 v28, v16, 16, 1
	v_add3_u32 v16, v16, v28, s60
	global_store_short_d16_hi v[32:33], v16, off offset:3072
	v_mul_f32_e32 v16, v60, v15
	v_mul_f32_e32 v16, v16, v77
	v_bfe_u32 v28, v16, 16, 1
	v_add3_u32 v16, v16, v28, s60
	global_store_short_d16_hi v[32:33], v16, off offset:3136
	v_mul_f32_e32 v16, v44, v15
	v_mul_f32_e32 v16, v16, v78
	v_bfe_u32 v28, v16, 16, 1
	v_mul_f32_e32 v15, v27, v15
	v_add3_u32 v16, v16, v28, s60
	v_mul_f32_e32 v15, v15, v79
	global_store_short_d16_hi v[32:33], v16, off offset:3200
	v_bfe_u32 v16, v15, 16, 1
	v_add3_u32 v15, v15, v16, s60
	global_store_short_d16_hi v[32:33], v15, off offset:3264
	v_fmamk_f32 v15, v75, 0x3c000000, v216
	v_rsq_f32_e32 v15, v15
	v_add_co_u32_e32 v28, vcc, s2, v2
	s_movk_i32 s2, 0x6000
	v_mul_f32_e32 v16, v56, v15
	v_mul_f32_e32 v16, v16, v76
	v_bfe_u32 v27, v16, 16, 1
	v_add3_u32 v16, v16, v27, s60
	v_addc_co_u32_e32 v29, vcc, 0, v3, vcc
	global_store_short_d16_hi v[28:29], v16, off
	v_mul_f32_e32 v16, v43, v15
	v_mul_f32_e32 v16, v16, v77
	v_bfe_u32 v27, v16, 16, 1
	v_add3_u32 v16, v16, v27, s60
	global_store_short_d16_hi v[28:29], v16, off offset:64
	v_mul_f32_e32 v16, v25, v15
	v_mul_f32_e32 v16, v16, v78
	v_bfe_u32 v25, v16, 16, 1
	v_mul_f32_e32 v15, v26, v15
	v_add3_u32 v16, v16, v25, s60
	v_mul_f32_e32 v15, v15, v79
	global_store_short_d16_hi v[28:29], v16, off offset:128
	v_bfe_u32 v16, v15, 16, 1
	v_add3_u32 v15, v15, v16, s60
	global_store_short_d16_hi v[28:29], v15, off offset:192
	v_fmamk_f32 v15, v74, 0x3c000000, v216
	v_rsq_f32_e32 v15, v15
	v_add_co_u32_e32 v2, vcc, s2, v2
	v_mul_f32_e32 v16, v55, v15
	v_mul_f32_e32 v16, v16, v76
	v_bfe_u32 v25, v16, 16, 1
	v_add3_u32 v16, v16, v25, s60
	global_store_short_d16_hi v[28:29], v16, off offset:1024
	v_mul_f32_e32 v16, v42, v15
	v_mul_f32_e32 v16, v16, v77
	v_bfe_u32 v25, v16, 16, 1
	v_mul_f32_e32 v10, v10, v15
	v_add3_u32 v16, v16, v25, s60
	v_mul_f32_e32 v10, v10, v79
; __device__ __forceinline__ unsigned f2bf(float f) { unsigned u = __builtin_bit_cast(unsigned, f); return (u + 0x7fffu + ((u >> 16) & 1u)) >> 16; }
; __device__ __forceinline__ float fast_rsq(float x) { return __builtin_amdgcn_rsqf(x); }
; __device__ __forceinline__ int crow(int r, int hi) { return (r & 3) + 8 * (r >> 2) + 4 * hi; }
; __device__ __forceinline__ void diff_unit(const Params& P, int l, int b, int h, int qb, float lam, float lam_init, LAS unsigned char* lds, bool dry = false) {
;     ...
;         for (int r = 0; r < 16; ++r) { const int q = crow(r, hi); const float rstd = fast_rsq(ssq[r] * (1.0f / 128.0f) + EPS);
; #pragma unroll
;             for (int d = 0; d < 4; ++d) if (!dry || o[d][r] == 1.2345e30f) Ow[(size_t)q * QP + 32 * d + r32] = (bf16_t)f2bf(o[d][r] * rstd * gsub[d]); }
	global_store_short_d16_hi v[28:29], v16, off offset:1088
	v_mul_f32_e32 v16, v24, v15
	v_bfe_u32 v15, v10, 16, 1
	v_add3_u32 v10, v10, v15, s60
	global_store_short_d16_hi v[28:29], v10, off offset:1216
	v_fmamk_f32 v10, v71, 0x3c000000, v216
	v_rsq_f32_e32 v10, v10
	v_mul_f32_e32 v16, v16, v78
	v_bfe_u32 v24, v16, 16, 1
	v_add3_u32 v16, v16, v24, s60
	v_mul_f32_e32 v15, v54, v10
	v_mul_f32_e32 v15, v15, v76
	global_store_short_d16_hi v[28:29], v16, off offset:1152
	v_bfe_u32 v16, v15, 16, 1
	v_add3_u32 v15, v15, v16, s60
	global_store_short_d16_hi v[28:29], v15, off offset:2048
	v_mul_f32_e32 v15, v41, v10
	v_mul_f32_e32 v15, v15, v77
	v_bfe_u32 v16, v15, 16, 1
	v_mul_f32_e32 v9, v9, v10
	v_add3_u32 v15, v15, v16, s60
	v_mul_f32_e32 v9, v9, v79
	global_store_short_d16_hi v[28:29], v15, off offset:2112
	v_mul_f32_e32 v15, v23, v10
	v_bfe_u32 v10, v9, 16, 1
	v_add3_u32 v9, v9, v10, s60
	global_store_short_d16_hi v[28:29], v9, off offset:2240
	v_fmamk_f32 v9, v17, 0x3c000000, v216
	v_rsq_f32_e32 v9, v9
	v_mul_f32_e32 v15, v15, v78
	v_bfe_u32 v16, v15, 16, 1
	v_add3_u32 v15, v15, v16, s60
	v_mul_f32_e32 v10, v53, v9
	v_mul_f32_e32 v10, v10, v76
	global_store_short_d16_hi v[28:29], v15, off offset:2176
	v_bfe_u32 v15, v10, 16, 1
	v_add3_u32 v10, v10, v15, s60
	global_store_short_d16_hi v[28:29], v10, off offset:3072
	v_mul_f32_e32 v10, v40, v9
	v_mul_f32_e32 v10, v10, v77
	v_bfe_u32 v15, v10, 16, 1
	v_mul_f32_e32 v8, v8, v9
	v_add3_u32 v10, v10, v15, s60
	v_mul_f32_e32 v8, v8, v79
	global_store_short_d16_hi v[28:29], v10, off offset:3136
	v_mul_f32_e32 v10, v22, v9
	v_bfe_u32 v9, v8, 16, 1
	v_add3_u32 v8, v8, v9, s60
	global_store_short_d16_hi v[28:29], v8, off offset:3264
	v_fmamk_f32 v8, v14, 0x3c000000, v216
	v_rsq_f32_e32 v8, v8
	v_mul_f32_e32 v10, v10, v78
	v_bfe_u32 v15, v10, 16, 1
	v_add3_u32 v10, v10, v15, s60
	v_mul_f32_e32 v9, v52, v8
	v_mul_f32_e32 v9, v9, v76
	global_store_short_d16_hi v[28:29], v10, off offset:3200
	v_bfe_u32 v10, v9, 16, 1
	v_add3_u32 v9, v9, v10, s60
	v_addc_co_u32_e32 v3, vcc, 0, v3, vcc
	global_store_short_d16_hi v[2:3], v9, off
	v_mul_f32_e32 v9, v38, v8
	v_mul_f32_e32 v9, v9, v77
	v_bfe_u32 v10, v9, 16, 1
	v_mul_f32_e32 v7, v7, v8
	v_add3_u32 v9, v9, v10, s60
	v_mul_f32_e32 v7, v7, v79
	global_store_short_d16_hi v[2:3], v9, off offset:64
	v_mul_f32_e32 v9, v21, v8
	v_bfe_u32 v8, v7, 16, 1
	v_add3_u32 v7, v7, v8, s60
	global_store_short_d16_hi v[2:3], v7, off offset:192
	v_fmamk_f32 v7, v13, 0x3c000000, v216
	v_rsq_f32_e32 v7, v7
	v_mul_f32_e32 v9, v9, v78
	v_bfe_u32 v10, v9, 16, 1
	v_add3_u32 v9, v9, v10, s60
	v_mul_f32_e32 v8, v35, v7
	v_mul_f32_e32 v8, v8, v76
	global_store_short_d16_hi v[2:3], v9, off offset:128
	v_bfe_u32 v9, v8, 16, 1
	v_add3_u32 v8, v8, v9, s60
	global_store_short_d16_hi v[2:3], v8, off offset:1024
	v_mul_f32_e32 v8, v36, v7
	v_mul_f32_e32 v8, v8, v77
	v_bfe_u32 v9, v8, 16, 1
	v_mul_f32_e32 v6, v6, v7
	v_add3_u32 v8, v8, v9, s60
	v_mul_f32_e32 v6, v6, v79
	global_store_short_d16_hi v[2:3], v8, off offset:1088
	v_mul_f32_e32 v8, v19, v7
	v_bfe_u32 v7, v6, 16, 1
	v_add3_u32 v6, v6, v7, s60
	global_store_short_d16_hi v[2:3], v6, off offset:1216
	v_fmamk_f32 v6, v12, 0x3c000000, v216
	v_rsq_f32_e32 v6, v6
	v_mul_f32_e32 v8, v8, v78
	v_bfe_u32 v9, v8, 16, 1
	v_add3_u32 v8, v8, v9, s60
	v_mul_f32_e32 v7, v34, v6
	v_mul_f32_e32 v7, v7, v76
	global_store_short_d16_hi v[2:3], v8, off offset:1152
	v_bfe_u32 v8, v7, 16, 1
	v_add3_u32 v7, v7, v8, s60
	global_store_short_d16_hi v[2:3], v7, off offset:2048
	v_mul_f32_e32 v7, v39, v6
	v_mul_f32_e32 v7, v7, v77
	v_bfe_u32 v8, v7, 16, 1
	v_mul_f32_e32 v5, v5, v6
	v_add3_u32 v7, v7, v8, s60
	v_mul_f32_e32 v5, v5, v79
	global_store_short_d16_hi v[2:3], v7, off offset:2112
	v_mul_f32_e32 v7, v20, v6
	v_bfe_u32 v6, v5, 16, 1
	v_add3_u32 v5, v5, v6, s60
	global_store_short_d16_hi v[2:3], v5, off offset:2240
	v_fmamk_f32 v5, v11, 0x3c000000, v216
	v_rsq_f32_e32 v5, v5
	v_mul_f32_e32 v7, v7, v78
	v_bfe_u32 v8, v7, 16, 1
	v_add3_u32 v7, v7, v8, s60
	v_mul_f32_e32 v1, v1, v5
	v_mul_f32_e32 v1, v76, v1
	v_bfe_u32 v6, v1, 16, 1
	v_add3_u32 v1, v1, v6, s60
	global_store_short_d16_hi v[2:3], v1, off offset:3072
	v_mul_f32_e32 v1, v37, v5
	v_mul_f32_e32 v1, v77, v1
	v_bfe_u32 v6, v1, 16, 1
	v_add3_u32 v1, v1, v6, s60
	global_store_short_d16_hi v[2:3], v1, off offset:3136
	v_mul_f32_e32 v1, v18, v5
	v_mul_f32_e32 v1, v78, v1
	v_bfe_u32 v6, v1, 16, 1
	v_add3_u32 v1, v1, v6, s60
	global_store_short_d16_hi v[2:3], v1, off offset:3200
	v_mul_f32_e32 v1, v4, v5
	v_mul_f32_e32 v1, v79, v1
	v_bfe_u32 v4, v1, 16, 1
	v_add3_u32 v1, v1, v4, s60
	global_store_short_d16_hi v[2:3], v7, off offset:2176
	global_store_short_d16_hi v[2:3], v1, off offset:3264

; #define LAS __attribute__((address_space(3)))
; #define DIFF_QK(P0, P1, kt) do { bf16x8 qf[4]; _Pragma("unroll") for (int d0 = 0; d0 < 4; ++d0) qf[d0] = *(const LAS bf16x8*)(qlds + d0 * 32); attn_qk(P0, P1, kt, 272, qf, r32, hi); } while (0)
; #define DIFF_GLOADK(t) do { _Pragma("unroll") for (int i = 0; i < 2; ++i) kreg[i] = *(const u32x4*)(sbase + O_DK + (size_t)(64 * (t) + 32 * i) * QP); } while (0)
; #define DIFF_GLOADV(t) do { _Pragma("unroll") for (int i = 0; i < 2; ++i) vreg[i] = *(const u32x4*)(sbase + O_DV + (size_t)(64 * (t) + 32 * i) * QP); } while (0)
; __device__ __forceinline__ void attn_qk(f32x16& p0, f32x16& p1, const LAS unsigned char* Kt, int kstride, const bf16x8 (&qf)[4], int r32, int hi) {
; #pragma unroll
;     for (int d0 = 0; d0 < 4; ++d0) {
;         const bf16x8 k0 = *(const LAS bf16x8*)(Kt + r32 * kstride + d0 * 32 + hi * 16);
;         const bf16x8 k1 = *(const LAS bf16x8*)(Kt + (r32 + 32) * kstride + d0 * 32 + hi * 16);
;         p0 = __builtin_amdgcn_mfma_f32_32x32x16_bf16(k0, qf[d0], p0, 0, 0, 0);
;         p1 = __builtin_amdgcn_mfma_f32_32x32x16_bf16(k1, qf[d0], p1, 0, 0, 0);
;     }
; __device__ __forceinline__ void diff_unit(const Params& P, int l, int b, int h, int qb, float lam, float lam_init, LAS unsigned char* lds, bool dry = false) {
;     ...
;     if (tid < 128) bt[tid] = P.in[I_REL][T5_BUCKET[tid] * 4 + h] * LOG2E;
;     LAS unsigned char* qlds = lds + 79872 + wid * 4608 + r32 * 144 + hi * 16;
;     { const bf16_t* Qw = proj + O_DQ + (rowb + q0 + wq * 32 + r32) * QP + h * 128 + map * 64;
; #pragma unroll
;       for (int d0 = 0; d0 < 4; ++d0) *(LAS bf16x8*)(qlds + d0 * 32) = *(const bf16x8*)(Qw + d0 * 16 + hi * 8); }
;     ...
;     f32x16 o[4];
; #pragma unroll
;     for (int d = 0; d < 4; ++d) o[d] = f32x16{};
;     float mref = 0.f, lrun = 0.f;
;     const int NT = 2 * (qb + 1);
;     u32x4 kreg[2], vreg[2];
;     const int srow = tid >> 4, sch = tid & 15;
;     const bf16_t* sbase = proj + (rowb + srow) * QP + h * 128 + sch * 8;
;     ...
;     const int qme = q0 + wq * 32 + r32;
;     ...
;     DIFF_GLOADK(0); DIFF_GLOADV(0); DIFF_LSTOREK(0); DIFF_LSTOREV(0);
;     DIFF_GLOADK(1); DIFF_LSTOREK(1);
;     __syncthreads();
;     const float b31 = bt[127];
;     f32x16 s0, s1, n0 = {}, n1 = {};
;     DIFF_INIT(s0, s1, 0); DIFF_QK(s0, s1, lds + KOFF + map * 128);
.LBB0_495:
	s_or_b64 exec, exec, s[6:7]
	s_ashr_i32 s6, s52, 6
	s_and_b32 s7, s52, 0x3fffffc0
	s_and_b32 s53, s6, 3
	s_lshl_b32 s7, s7, 2
	s_mulk_i32 s6, 0x1200
	s_xor_b32 s9, s71, 15
	s_add_i32 s55, s7, 0
	s_add_i32 s6, s6, 0
	s_ashr_i32 s54, s52, 8
	s_lshl_b32 s8, s9, 7
	s_add_i32 s55, s55, 0x12800
	s_add_i32 s10, s6, 0x13800
	s_add_u32 s50, s2, 0xee00000
	s_addc_u32 s51, s3, 0
	s_lshl_b32 s71, s53, 5
	s_or_b32 s70, s71, s8
	v_and_b32_e32 v186, 31, v62
	s_or_b32 s90, s4, s70
	v_or_b32_e32 v2, s90, v186
	v_mov_b32_e32 v3, s5
	v_lshlrev_b64 v[2:3], 10, v[2:3]
	v_lshl_add_u64 v[2:3], s[50:51], 0, v[2:3]
	s_lshl_b32 s96, s82, 1
	s_lshl_b32 s6, s54, 6
	v_bfe_u32 v1, v62, 5, 1
	v_lshl_add_u64 v[2:3], v[2:3], 0, s[96:97]
	s_ashr_i32 s7, s6, 31
	v_lshlrev_b32_e32 v188, 4, v1
	v_lshl_add_u64 v[2:3], s[6:7], 1, v[2:3]
	v_mov_b32_e32 v189, v0
	v_lshl_add_u64 v[6:7], v[2:3], 0, v[188:189]
	global_load_dwordx4 v[2:5], v[6:7], off
	v_mov_b32_e32 v8, s10
	s_movk_i32 s6, 0x90
	v_mad_u32_u24 v8, v186, s6, v8
	v_add_u32_e32 v199, v8, v188
	v_ashrrev_i32_e32 v100, 4, v62
	v_ashrrev_i32_e32 v101, 31, v100
	v_mov_b32_e32 v157, v0
	s_movk_i32 s6, 0x110
	v_mul_lo_u32 v160, v100, s6
	s_lshl_b32 s74, s9, 1
	s_mov_b32 s9, 0x10e20000
	v_and_b32_e32 v189, 63, v62
	v_lshlrev_b32_e32 v195, 2, v1
	s_lshl_b64 s[12:13], s[48:49], 21
	s_mov_b32 s73, 2
	s_mov_b32 s10, 4
	s_mov_b32 s91, s5
	v_mul_u32_u24_e32 v176, 0x110, v186
	s_add_i32 s48, s70, 0xffffff00
	s_movk_i32 s49, 0x100
	s_waitcnt vmcnt(0) lgkmcnt(0)
	ds_write_b128 v199, v[2:5]
	global_load_dwordx4 v[2:5], v[6:7], off offset:32
	s_waitcnt vmcnt(0) lgkmcnt(0)
	ds_write_b128 v199, v[2:5] offset:32
	global_load_dwordx4 v[2:5], v[6:7], off offset:64
	s_waitcnt vmcnt(0) lgkmcnt(0)
	ds_write_b128 v199, v[2:5] offset:64
	global_load_dwordx4 v[2:5], v[6:7], off offset:96
	v_lshlrev_b32_e32 v6, 4, v62
	v_and_b32_e32 v156, 0xf0, v6
	v_lshl_add_u64 v[6:7], s[4:5], 0, v[100:101]
	v_lshlrev_b64 v[6:7], 10, v[6:7]
	v_lshl_add_u64 v[6:7], s[2:3], 0, v[6:7]
	v_lshl_add_u64 v[6:7], v[6:7], 0, s[96:97]
	v_lshl_add_u64 v[82:83], v[6:7], 0, v[156:157]
	s_mov_b32 s4, 0x10e00000
	v_add_co_u32_e32 v6, vcc, s4, v82
	s_mov_b32 s4, 0x10e08000
	s_nop 0
	v_addc_co_u32_e32 v7, vcc, 0, v83, vcc
	v_add_co_u32_e32 v8, vcc, s4, v82
	s_mov_b32 s4, 0x12e00000
	s_nop 0
	v_addc_co_u32_e32 v9, vcc, 0, v83, vcc
	v_add_co_u32_e32 v10, vcc, s4, v82
	s_mov_b32 s4, 0x12e08000
	s_nop 0
	v_addc_co_u32_e32 v11, vcc, 0, v83, vcc
	v_add_co_u32_e32 v14, vcc, s4, v82
	s_movk_i32 s4, 0x140
	s_nop 0
	v_addc_co_u32_e32 v15, vcc, 0, v83, vcc
	v_mul_lo_u32 v161, v100, s4
	v_add_u32_e32 v162, 0, v156
	v_add_u32_e32 v18, 0x2800, v161
	s_mov_b32 s4, 0x10e10000
	v_add_u32_e32 v173, v162, v18
	v_add_co_u32_e32 v18, vcc, s4, v82
	v_add_u32_e32 v163, v162, v160
	s_nop 0
	v_addc_co_u32_e32 v19, vcc, 0, v83, vcc
	s_mov_b32 s4, 0x10e18000
	v_add_u32_e32 v172, v162, v161
	v_add_co_u32_e32 v20, vcc, s4, v82
	v_readlane_b32 s4, v255, 8
	s_nop 0
	v_addc_co_u32_e32 v21, vcc, 0, v83, vcc
	s_add_i32 s5, s74, -4
	s_waitcnt vmcnt(0) lgkmcnt(0)
	ds_write_b128 v199, v[2:5] offset:96
	global_load_dwordx4 v[2:5], v[6:7], off
	s_nop 0
	global_load_dwordx4 v[6:9], v[8:9], off
	s_nop 0
	global_load_dwordx4 v[10:13], v[10:11], off
	s_nop 0
	global_load_dwordx4 v[14:17], v[14:15], off
	s_waitcnt vmcnt(0) lgkmcnt(0)
	ds_write_b128 v163, v[2:5]
	ds_write_b128 v163, v[6:9] offset:8704
	ds_write_b128 v172, v[10:13] offset:17408
	ds_write_b128 v173, v[14:17] offset:17408
	global_load_dwordx4 v[2:5], v[18:19], off
	global_load_dwordx4 v[6:9], v[20:21], off
	v_mov_b32_e32 v10, s4
	s_lshl_b32 s4, s54, 7
	s_add_i32 s4, s4, 0
	v_mov_b32_e32 v11, s4
	v_mad_u32_u24 v11, v186, s6, v11
	v_add_u32_e32 v174, v11, v188
	v_cmp_gt_u32_e64 s[6:7], 32, v189
	s_waitcnt vmcnt(0) lgkmcnt(0)
	ds_write_b128 v163, v[2:5] offset:37888
	ds_write_b128 v163, v[6:9] offset:46592
	s_waitcnt lgkmcnt(0)
	s_barrier
	ds_read_b32 v66, v10
	ds_read_b128 v[102:105], v199
	ds_read_b128 v[106:109], v199 offset:32
	ds_read_b128 v[2:5], v174 offset:37888
	ds_read_b128 v[6:9], v174
	ds_read_b128 v[50:53], v174 offset:46688
	s_waitcnt lgkmcnt(5)
	v_mov_b32_e32 v67, v66
	v_mov_b32_e32 v68, v66
	v_mov_b32_e32 v69, v66
	v_mov_b32_e32 v70, v66
	v_mov_b32_e32 v71, v66
	v_mov_b32_e32 v72, v66
	v_mov_b32_e32 v73, v66
	v_mov_b32_e32 v74, v66
	v_mov_b32_e32 v75, v66
	v_mov_b32_e32 v76, v66
	v_mov_b32_e32 v77, v66
	v_mov_b32_e32 v78, v66
	v_mov_b32_e32 v79, v66
	v_mov_b32_e32 v80, v66
	v_mov_b32_e32 v81, v66
	s_waitcnt lgkmcnt(1)
	s_nop 0
	v_mfma_f32_32x32x16_bf16 v[18:33], v[6:9], v[102:105], v[66:81]
	ds_read_b128 v[6:9], v174 offset:8704
	ds_read_b128 v[58:61], v174 offset:96
	ds_read_b128 v[110:113], v174 offset:46592
	ds_read_b128 v[54:57], v174 offset:37984
	s_waitcnt lgkmcnt(3)
	v_mfma_f32_32x32x16_bf16 v[34:49], v[6:9], v[102:105], v[66:81]
	v_mfma_f32_32x32x16_bf16 v[84:99], v[2:5], v[102:105], v[66:81]
	v_mov_b64_e32 v[2:3], v[66:67]
	v_mov_b64_e32 v[4:5], v[68:69]
	v_mov_b64_e32 v[6:7], v[70:71]
	v_mov_b64_e32 v[8:9], v[72:73]
	v_mov_b64_e32 v[10:11], v[74:75]
	v_mov_b64_e32 v[12:13], v[76:77]
	v_mov_b64_e32 v[14:15], v[78:79]
	v_mov_b64_e32 v[16:17], v[80:81]
	ds_read_b128 v[68:71], v174 offset:32
	ds_read_b128 v[76:79], v174 offset:64
	s_waitcnt lgkmcnt(3)
	v_mfma_f32_32x32x16_bf16 v[2:17], v[110:113], v[102:105], v[2:17]
	v_and_b32_e32 v80, 16, v62
	v_lshrrev_b32_e32 v67, 2, v62
	v_and_or_b32 v67, v67, 3, v195
	v_mul_u32_u24_e32 v177, 0x140, v67
	s_waitcnt lgkmcnt(1)
	v_mfma_f32_32x32x16_bf16 v[18:33], v[68:71], v[106:109], v[18:33]
	ds_read_b128 v[68:71], v174 offset:8736
	ds_read_b128 v[102:105], v174 offset:8768
	s_waitcnt lgkmcnt(1)
; #define LAS __attribute__((address_space(3)))
; __device__ __forceinline__ float fast_exp2(float x) { return __builtin_amdgcn_exp2f(x); }
; template <int NDT, int VSTR> ...
;     if (domask) {
; #pragma unroll
;         for (int r = 0; r < 16; ++r) { const int kv = crow(r, hi); if (kv > qrel) p0[r] = -INFINITY; if (kv + 32 > qrel) p1[r] = -INFINITY; }
;     }
;     float ra = fmaxf(fmaxf(p0[0], p0[1]), p1[0]), rb = fmaxf(fmaxf(p0[2], p0[3]), p1[1]);
;     ra = fmaxf(fmaxf(ra, p1[2]), p1[3]);
; #pragma unroll
;     for (int r = 4; r < 16; r += 4) { ra = fmaxf(fmaxf(ra, p0[r]), p0[r + 1]); rb = fmaxf(fmaxf(rb, p0[r + 2]), p0[r + 3]); ra = fmaxf(fmaxf(ra, p1[r]), p1[r + 1]); rb = fmaxf(fmaxf(rb, p1[r + 2]), p1[r + 3]); }
;     const float rm = half_max(fmaxf(ra, rb));
;     if (first || __any(rm > 8.0f)) {
;         const float dl = first ? rm : fmaxf(rm, 0.f);
;         mref += dl;
; #pragma unroll
;         for (int r = 0; r < 16; ++r) { p0[r] -= dl; p1[r] -= dl; }
;         if (has_next) {
; #pragma unroll
;             for (int r = 0; r < 16; ++r) { n0[r] -= dl; n1[r] -= dl; } }
;         if (!first) {
;             const float alpha = fast_exp2(-dl);
;             lrun *= alpha;
;             if (hi == 0) wsf[r32] = alpha;
;             asm volatile("s_waitcnt lgkmcnt(0)" ::: "memory");
; #pragma unroll
;             for (int jj = 0; jj < 4; ++jj) { const f32x4 al = *(const LAS f32x4*)(wsf + 8 * jj + 4 * hi);
; #pragma unroll
;                 for (int d = 0; d < NDT; ++d) { o[d][4 * jj + 0] *= al.x; o[d][4 * jj + 1] *= al.y; o[d][4 * jj + 2] *= al.z; o[d][4 * jj + 3] *= al.w; } }
;             asm volatile("s_waitcnt lgkmcnt(0)" ::: "memory");
;         }
;     }
;     constexpr int PRE = (NDT == 2) ? 4 : 1;
;     const int lane_ = hi * 32 + r32;
;     const LAS unsigned char* vb = Vt + (4 * hi + ((lane_ & 15) >> 2)) * VSTR + (16 * ((lane_ >> 4) & 1) + 4 * (lane_ & 3)) * 2;
;     ...
;     bf16x8 vpre[PRE][NDT];
; #pragma unroll
;     for (int s = 0; s < PRE; ++s)
; #pragma unroll
;         for (int d = 0; d < NDT; ++d) vpre[s][d] = VFRAG(s, d);
;     float rs0 = 0.f, rs1 = 0.f;
; #pragma unroll
;     for (int r = 0; r < 16; ++r) { p0[r] = fast_exp2(p0[r]); p1[r] = fast_exp2(p1[r]); rs0 += p0[r]; rs1 += p1[r]; }
;     lrun += rs0 + rs1;
;     bf16x8 pa[4];
; #pragma unroll
;     for (int s = 0; s < 2; ++s) {
;         u32x4 w0, w1;
	v_mfma_f32_32x32x16_bf16 v[34:49], v[68:71], v[106:109], v[34:49]
	ds_read_b128 v[68:71], v174 offset:37920
	ds_read_b128 v[110:113], v174 offset:37952
	ds_read_b128 v[72:75], v174 offset:46624
	ds_read_b128 v[62:65], v199 offset:96
	s_waitcnt lgkmcnt(3)
	v_mfma_f32_32x32x16_bf16 v[84:99], v[68:71], v[106:109], v[84:99]
	ds_read_b128 v[68:71], v174 offset:46656
	s_waitcnt lgkmcnt(2)
	v_mfma_f32_32x32x16_bf16 v[2:17], v[72:75], v[106:109], v[2:17]
	ds_read_b128 v[72:75], v199 offset:64
	s_waitcnt lgkmcnt(0)
	v_mfma_f32_32x32x16_bf16 v[18:33], v[76:79], v[72:75], v[18:33]
	v_lshlrev_b32_e32 v78, 2, v186
	v_and_or_b32 v79, v78, 12, v80
	v_add_u32_e32 v196, s55, v78
	v_add_co_u32_e32 v78, vcc, s9, v82
	v_lshlrev_b32_e32 v175, 1, v79
	s_nop 0
	v_addc_co_u32_e32 v79, vcc, 0, v83, vcc
	s_mov_b32 s9, 0x10e28000
	v_mfma_f32_32x32x16_bf16 v[34:49], v[102:105], v[72:75], v[34:49]
	v_add3_u32 v198, 0, v177, v175
	v_lshlrev_b64 v[76:77], 10, v[100:101]
	v_lshl_add_u64 v[76:77], s[12:13], 0, v[76:77]
	v_or_b32_e32 v76, s72, v76
	v_lshl_add_u64 v[100:101], v[76:77], 0, v[156:157]
	v_lshl_add_u64 v[100:101], s[2:3], 0, v[100:101]
	s_mov_b64 s[2:3], 0x12e38000
	v_mfma_f32_32x32x16_bf16 v[84:99], v[110:113], v[72:75], v[84:99]
	v_add_u32_e32 v197, 0xd800, v198
	v_mfma_f32_32x32x16_bf16 v[2:17], v[68:71], v[72:75], v[2:17]
	v_add_co_u32_e32 v72, vcc, s9, v82
	s_mov_b32 s9, 0x12e10000
	s_nop 0
	v_addc_co_u32_e32 v73, vcc, 0, v83, vcc
	v_add_co_u32_e32 v74, vcc, s9, v82
	s_mov_b32 s9, 0x12e18000
	s_nop 0
	v_addc_co_u32_e32 v75, vcc, 0, v83, vcc
	ds_read_b128 v[68:71], v174 offset:8800
	v_mfma_f32_32x32x16_bf16 v[18:33], v[58:61], v[62:65], v[18:33]
	v_add_co_u32_e32 v58, vcc, s9, v82
	s_mov_b32 s9, -1
	s_nop 0
	v_addc_co_u32_e32 v59, vcc, 0, v83, vcc
	global_load_dwordx4 v[104:107], v[78:79], off
	global_load_dwordx4 v[108:111], v[72:73], off
	global_load_dwordx4 v[112:115], v[74:75], off
	global_load_dwordx4 v[116:119], v[58:59], off
	s_waitcnt lgkmcnt(0)
	v_mfma_f32_32x32x16_bf16 v[34:49], v[68:71], v[62:65], v[34:49]
	ds_read_b64_tr_b16 v[58:59], v198 offset:17408
	ds_read_b64_tr_b16 v[68:69], v198 offset:17472
	ds_read_b64_tr_b16 v[72:73], v198 offset:17536
	ds_read_b64_tr_b16 v[120:121], v198 offset:17600
	ds_read_b64_tr_b16 v[60:61], v198 offset:19968
	ds_read_b64_tr_b16 v[70:71], v198 offset:20032
	ds_read_b64_tr_b16 v[74:75], v198 offset:20096
	ds_read_b64_tr_b16 v[122:123], v198 offset:20160
	ds_read_b64_tr_b16 v[76:77], v198 offset:22528
	ds_read_b64_tr_b16 v[124:125], v198 offset:22592
	ds_read_b64_tr_b16 v[128:129], v198 offset:22656
	ds_read_b64_tr_b16 v[132:133], v198 offset:22720
	ds_read_b64_tr_b16 v[78:79], v198 offset:25088
	ds_read_b64_tr_b16 v[126:127], v198 offset:25152
	ds_read_b64_tr_b16 v[130:131], v198 offset:25216
	ds_read_b64_tr_b16 v[134:135], v198 offset:25280
	v_mfma_f32_32x32x16_bf16 v[2:17], v[50:53], v[62:65], v[2:17]
	v_max_f32_e32 v50, v19, v19
	v_max_f32_e32 v51, v18, v18
	v_max_f32_e32 v50, v51, v50
	v_max3_f32 v52, v20, v21, v35
	v_max3_f32 v50, v50, v34, v36
	v_max3_f32 v51, v52, v24, v25
	v_max3_f32 v50, v50, v37, v22
	v_max3_f32 v51, v51, v40, v41
	v_max3_f32 v50, v50, v23, v38
	v_max3_f32 v51, v51, v28, v29
	v_max3_f32 v50, v50, v39, v26
	v_max3_f32 v51, v51, v44, v45
	v_max3_f32 v50, v50, v27, v42
	v_max3_f32 v51, v51, v32, v33
	v_max3_f32 v50, v50, v43, v30
	v_max3_f32 v51, v51, v48, v49
	v_max3_f32 v50, v50, v31, v46
	v_max3_f32 v50, v50, v47, v51
	v_mov_b32_e32 v51, v50
	s_nop 1
	v_permlane32_swap_b32_e32 v50, v51
	v_max_f32_e32 v51, v51, v51
	v_max_f32_e32 v50, v50, v50
	v_max_f32_e32 v158, v50, v51
	v_sub_f32_e32 v18, v18, v158
	v_sub_f32_e32 v19, v19, v158
	v_sub_f32_e32 v20, v20, v158
	v_sub_f32_e32 v21, v21, v158
	v_sub_f32_e32 v22, v22, v158
	v_sub_f32_e32 v23, v23, v158
	v_sub_f32_e32 v24, v24, v158
	v_sub_f32_e32 v25, v25, v158
	v_exp_f32_e32 v102, v18
	v_exp_f32_e32 v178, v19
	v_exp_f32_e32 v182, v20
	v_exp_f32_e32 v184, v21
	v_exp_f32_e32 v190, v22
	v_exp_f32_e32 v192, v23
	v_exp_f32_e32 v204, v24
	v_exp_f32_e32 v206, v25
	v_cvt_pk_bf16_f32 v136, v102, v178
	v_cvt_pk_bf16_f32 v137, v182, v184
	v_cvt_pk_bf16_f32 v138, v190, v192
	v_cvt_pk_bf16_f32 v139, v204, v206
	v_sub_f32_e32 v26, v26, v158
	v_sub_f32_e32 v27, v27, v158
	v_sub_f32_e32 v28, v28, v158
	v_sub_f32_e32 v29, v29, v158
	v_sub_f32_e32 v30, v30, v158
	v_sub_f32_e32 v31, v31, v158
	v_sub_f32_e32 v18, v32, v158
	v_sub_f32_e32 v19, v33, v158
	v_exp_f32_e32 v208, v26
	v_exp_f32_e32 v210, v27
	v_exp_f32_e32 v212, v28
	v_exp_f32_e32 v214, v29
	v_exp_f32_e32 v226, v30
	v_exp_f32_e32 v228, v31
	v_exp_f32_e32 v232, v18
	v_exp_f32_e32 v234, v19
	v_mfma_f32_32x32x16_bf16 v[84:99], v[54:57], v[62:65], v[84:99]
	v_cvt_pk_bf16_f32 v140, v208, v210
	v_cvt_pk_bf16_f32 v141, v212, v214
	v_cvt_pk_bf16_f32 v142, v226, v228
	v_cvt_pk_bf16_f32 v143, v232, v234
	v_sub_f32_e32 v159, v36, v158
	v_sub_f32_e32 v67, v34, v158
	v_sub_f32_e32 v157, v35, v158
	s_waitcnt lgkmcnt(0)
; template <int NDT, int VSTR> ...
;     ...
;         for (int r = 0; r < 16; ++r) { p0[r] -= dl; p1[r] -= dl; }
;         if (has_next) {
; #pragma unroll
;             for (int r = 0; r < 16; ++r) { n0[r] -= dl; n1[r] -= dl; } }
;         if (!first) {
;             const float alpha = fast_exp2(-dl);
;             lrun *= alpha;
;             if (hi == 0) wsf[r32] = alpha;
;             asm volatile("s_waitcnt lgkmcnt(0)" ::: "memory");
; #pragma unroll
;             for (int jj = 0; jj < 4; ++jj) { const f32x4 al = *(const LAS f32x4*)(wsf + 8 * jj + 4 * hi);
; #pragma unroll
;                 for (int d = 0; d < NDT; ++d) { o[d][4 * jj + 0] *= al.x; o[d][4 * jj + 1] *= al.y; o[d][4 * jj + 2] *= al.z; o[d][4 * jj + 3] *= al.w; } }
;             asm volatile("s_waitcnt lgkmcnt(0)" ::: "memory");
;         }
;     }
;     constexpr int PRE = (NDT == 2) ? 4 : 1;
;     const int lane_ = hi * 32 + r32;
;     const LAS unsigned char* vb = Vt + (4 * hi + ((lane_ & 15) >> 2)) * VSTR + (16 * ((lane_ >> 4) & 1) + 4 * (lane_ & 3)) * 2;
;     ...
;     bf16x8 vpre[PRE][NDT];
; #pragma unroll
;     for (int s = 0; s < PRE; ++s)
; #pragma unroll
;         for (int d = 0; d < NDT; ++d) vpre[s][d] = VFRAG(s, d);
;     float rs0 = 0.f, rs1 = 0.f;
; #pragma unroll
;     for (int r = 0; r < 16; ++r) { p0[r] = fast_exp2(p0[r]); p1[r] = fast_exp2(p1[r]); rs0 += p0[r]; rs1 += p1[r]; }
;     lrun += rs0 + rs1;
;     bf16x8 pa[4];
; #pragma unroll
;     for (int s = 0; s < 2; ++s) {
;         u32x4 w0, w1;
;         w0.x = cvt_pk_bf16(p0[8 * s + 0], p0[8 * s + 1]); w0.y = cvt_pk_bf16(p0[8 * s + 2], p0[8 * s + 3]); w0.z = cvt_pk_bf16(p0[8 * s + 4], p0[8 * s + 5]); w0.w = cvt_pk_bf16(p0[8 * s + 6], p0[8 * s + 7]);
;         w1.x = cvt_pk_bf16(p1[8 * s + 0], p1[8 * s + 1]); w1.y = cvt_pk_bf16(p1[8 * s + 2], p1[8 * s + 3]); w1.z = cvt_pk_bf16(p1[8 * s + 4], p1[8 * s + 5]); w1.w = cvt_pk_bf16(p1[8 * s + 6], p1[8 * s + 7]);
;         pa[s] = __builtin_bit_cast(bf16x8, w0); pa[2 + s] = __builtin_bit_cast(bf16x8, w1);
;     }
; #pragma unroll
;     for (int s = 0; s < 4; ++s) {
;         bf16x8 vw[NDT];
; #pragma unroll
;         for (int d = 0; d < NDT; ++d) { if (s < PRE) vw[d] = vpre[s < PRE ? s : 0][d]; else vw[d] = VFRAG(s, d); }
; #pragma unroll
;         for (int d = 0; d < NDT; ++d) o[d] = __builtin_amdgcn_mfma_f32_32x32x16_bf16(pa[s], vw[d], o[d], 0, 0, 0);
;     }
	v_mfma_f32_32x32x16_bf16 v[50:65], v[136:139], v[58:61], 0
	v_sub_f32_e32 v185, v37, v158
	v_sub_f32_e32 v191, v38, v158
	v_sub_f32_e32 v193, v39, v158
	v_sub_f32_e32 v205, v40, v158
	v_sub_f32_e32 v207, v41, v158
	v_sub_f32_e32 v209, v42, v158
	v_sub_f32_e32 v211, v43, v158
	v_sub_f32_e32 v213, v44, v158
	v_sub_f32_e32 v215, v45, v158
	v_sub_f32_e32 v227, v46, v158
	v_sub_f32_e32 v229, v47, v158
	v_sub_f32_e32 v231, v48, v158
	v_sub_f32_e32 v235, v49, v158
	v_mfma_f32_32x32x16_bf16 v[34:49], v[136:139], v[68:71], 0
	v_add_f32_e64 v68, v2, -v158
	v_add_f32_e64 v69, v3, -v158
	v_add_f32_e64 v70, v4, -v158
	v_add_f32_e64 v71, v5, -v158
	v_add_f32_e64 v80, v14, -v158
	v_add_f32_e64 v81, v15, -v158
	v_pk_add_f32 v[82:83], v[16:17], v[158:159] op_sel_hi:[1,0] neg_lo:[0,1] neg_hi:[0,1]
	v_exp_f32_e32 v103, v67
	v_exp_f32_e32 v179, v157
	v_exp_f32_e32 v183, v159
	v_mfma_f32_32x32x16_bf16 v[18:33], v[136:139], v[72:75], 0
	v_add_f32_e64 v72, v6, -v158
	v_add_f32_e64 v73, v7, -v158
	v_add_f32_e64 v74, v8, -v158
	v_add_f32_e64 v75, v9, -v158
	v_exp_f32_e32 v185, v185
	v_exp_f32_e32 v191, v191
	v_exp_f32_e32 v193, v193
	v_exp_f32_e32 v205, v205
	v_exp_f32_e32 v207, v207
	v_mfma_f32_32x32x16_bf16 v[50:65], v[140:143], v[76:79], v[50:65]
	v_add_f32_e64 v76, v10, -v158
	v_add_f32_e64 v77, v11, -v158
	v_add_f32_e64 v78, v12, -v158
	v_add_f32_e64 v79, v13, -v158
	v_add_f32_e64 v84, v84, -v158
	v_add_f32_e64 v85, v85, -v158
	v_pk_add_f32 v[86:87], v[86:87], v[158:159] op_sel_hi:[1,0] neg_lo:[0,1] neg_hi:[0,1]
	v_max_f32_e32 v67, v84, v85
	v_pk_add_f32 v[88:89], v[88:89], v[158:159] op_sel_hi:[1,0] neg_lo:[0,1] neg_hi:[0,1]
	v_pk_add_f32 v[90:91], v[90:91], v[158:159] op_sel_hi:[1,0] neg_lo:[0,1] neg_hi:[0,1]
	v_mfma_f32_32x32x16_bf16 v[2:17], v[136:139], v[120:123], 0
	v_cvt_pk_bf16_f32 v120, v103, v179
	v_cvt_pk_bf16_f32 v121, v183, v185
	v_cvt_pk_bf16_f32 v122, v191, v193
	v_cvt_pk_bf16_f32 v123, v205, v207
	v_max3_f32 v67, v67, v68, v70
	v_max3_f32 v67, v67, v71, v88
	v_pk_add_f32 v[92:93], v[92:93], v[158:159] op_sel_hi:[1,0] neg_lo:[0,1] neg_hi:[0,1]
	v_mfma_f32_32x32x16_bf16 v[34:49], v[140:143], v[124:127], v[34:49]
	ds_read_b64_tr_b16 v[124:125], v198 offset:27648
	ds_read_b64_tr_b16 v[144:145], v198 offset:27712
	ds_read_b64_tr_b16 v[148:149], v198 offset:27776
	ds_read_b64_tr_b16 v[152:153], v198 offset:27840
	ds_read_b64_tr_b16 v[126:127], v198 offset:30208
	ds_read_b64_tr_b16 v[146:147], v198 offset:30272
	ds_read_b64_tr_b16 v[150:151], v198 offset:30336
	ds_read_b64_tr_b16 v[154:155], v198 offset:30400
	v_pk_add_f32 v[94:95], v[94:95], v[158:159] op_sel_hi:[1,0] neg_lo:[0,1] neg_hi:[0,1]
	v_max3_f32 v67, v67, v89, v72
	v_pk_add_f32 v[102:103], v[102:103], 0 op_sel_hi:[1,0]
	v_max3_f32 v67, v67, v73, v92
	v_pk_add_f32 v[102:103], v[178:179], v[102:103]
	v_pk_add_f32 v[96:97], v[96:97], v[158:159] op_sel_hi:[1,0] neg_lo:[0,1] neg_hi:[0,1]
	v_mfma_f32_32x32x16_bf16 v[18:33], v[140:143], v[128:131], v[18:33]
	v_add_f32_e64 v98, v98, -v158
	v_add_f32_e64 v99, v99, -v158
	v_exp_f32_e32 v209, v209
	v_exp_f32_e32 v211, v211
	v_exp_f32_e32 v213, v213
	v_exp_f32_e32 v215, v215
	v_exp_f32_e32 v227, v227
	v_exp_f32_e32 v229, v229
	v_mfma_f32_32x32x16_bf16 v[2:17], v[140:143], v[132:135], v[2:17]
	v_max3_f32 v132, v86, v87, v69
	v_exp_f32_e32 v233, v231
	v_exp_f32_e32 v235, v235
	v_max3_f32 v67, v67, v93, v76
	v_pk_add_f32 v[102:103], v[182:183], v[102:103]
	v_max3_f32 v67, v67, v77, v96
	v_pk_add_f32 v[102:103], v[184:185], v[102:103]
	s_waitcnt lgkmcnt(0)
	v_mfma_f32_32x32x16_bf16 v[50:65], v[120:123], v[124:127], v[50:65]
	v_max3_f32 v124, v132, v90, v91
	v_max3_f32 v124, v124, v74, v75
	v_max3_f32 v132, v124, v94, v95
	v_max3_f32 v132, v132, v78, v79
	v_max3_f32 v132, v132, v98, v99
	v_max3_f32 v132, v132, v82, v83
	v_max3_f32 v67, v67, v97, v80
	v_mfma_f32_32x32x16_bf16 v[34:49], v[120:123], v[144:147], v[34:49]
	v_add_f32_e64 v102, v190, v102
	v_add_f32_e64 v103, v191, v103
	v_max3_f32 v67, v67, v81, v132
	v_add_f32_e64 v102, v192, v102
	v_add_f32_e64 v103, v193, v103
	ds_read_b64_tr_b16 v[128:129], v198 offset:32768
	ds_read_b64_tr_b16 v[164:165], v198 offset:32832
	ds_read_b64_tr_b16 v[168:169], v198 offset:32896
	ds_read_b64_tr_b16 v[200:201], v198 offset:32960
	ds_read_b64_tr_b16 v[130:131], v198 offset:35328
	ds_read_b64_tr_b16 v[166:167], v198 offset:35392
	ds_read_b64_tr_b16 v[170:171], v198 offset:35456
	ds_read_b64_tr_b16 v[202:203], v198 offset:35520
	v_cvt_pk_bf16_f32 v124, v209, v211
	v_cvt_pk_bf16_f32 v125, v213, v215
	v_cvt_pk_bf16_f32 v126, v227, v229
	v_mfma_f32_32x32x16_bf16 v[18:33], v[120:123], v[148:151], v[18:33]
	v_cvt_pk_bf16_f32 v127, v233, v235
	v_add_f32_e64 v102, v204, v102
	v_add_f32_e64 v103, v205, v103
	s_waitcnt vmcnt(0)
	ds_write_b128 v163, v[104:107]
	ds_write_b128 v163, v[108:111] offset:8704
	ds_write_b128 v172, v[112:115] offset:55296
	ds_write_b128 v173, v[116:119] offset:55296
	v_pk_add_f32 v[102:103], v[206:207], v[102:103]
	s_waitcnt lgkmcnt(0)
	s_barrier
	v_mfma_f32_32x32x16_bf16 v[2:17], v[120:123], v[152:155], v[2:17]
	v_mov_b32_e32 v120, v67
	s_nop 1
	v_permlane32_swap_b32_e32 v67, v120
	v_max_f32_e32 v122, v120, v120
	v_add_f32_e64 v120, v208, v102
	v_add_f32_e64 v121, v209, v103
	v_max_f32_e32 v67, v67, v67
	v_pk_add_f32 v[120:121], v[210:211], v[120:121]
	v_mfma_f32_32x32x16_bf16 v[50:65], v[124:127], v[128:131], v[50:65]
	v_add_f32_e64 v120, v212, v120
	v_add_f32_e64 v121, v213, v121
	v_max_f32_e32 v102, v67, v122
	v_add_f32_e64 v120, v214, v120
	v_add_f32_e64 v121, v215, v121
	v_sub_u32_e32 v67, s70, v195
	v_pk_add_f32 v[120:121], v[226:227], v[120:121]
	v_add_u32_e32 v67, 0xffffff80, v67
	v_pk_add_f32 v[120:121], v[228:229], v[120:121]
	v_mfma_f32_32x32x16_bf16 v[34:49], v[124:127], v[164:167], v[34:49]
	v_add_f32_e64 v120, v232, v120
	v_add_f32_e64 v121, v233, v121
	v_add_f32_e64 v120, v234, v120
	v_add_f32_e64 v121, v235, v121
	v_pk_add_f32 v[120:121], v[120:121], v[120:121] op_sel:[0,1] op_sel_hi:[1,0]
	s_nop 0
	v_mov_b32_e32 v121, v158
	v_mfma_f32_32x32x16_bf16 v[18:33], v[124:127], v[168:171], v[18:33]
	v_lshl_add_u64 v[158:159], v[100:101], 0, s[2:3]
	s_mov_b64 s[2:3], 0x10e50000
	v_add_f32_e64 v190, v120, 0
	v_add_f32_e64 v191, v121, 0
	v_lshl_add_u64 v[192:193], v[100:101], 0, s[2:3]
	v_mfma_f32_32x32x16_bf16 v[2:17], v[124:127], v[200:203], v[2:17]
; #define LAS __attribute__((address_space(3)))
; __device__ __forceinline__ unsigned cvt_pk_bf16(float lo, float hi) { const f32x2 v = {lo, hi}; const bf16x2_t b = __builtin_convertvector(v, bf16x2_t); return __builtin_bit_cast(unsigned, b); }
; __device__ __forceinline__ float fast_exp2(float x) { return __builtin_amdgcn_exp2f(x); }
; #define SBAR_() __builtin_amdgcn_sched_barrier(0)
; #define MF_(dst, a_, b_) dst = __builtin_amdgcn_mfma_f32_32x32x16_bf16(a_, b_, dst, 0, 0, 0)
; __device__ __forceinline__ void diff_steady_step(f32x16& s0, f32x16& s1, f32x16& n0, f32x16& n1, const LAS unsigned char* kb, const LAS unsigned char* Vt, const LAS unsigned char* qlds, ...
;     const float rm = rmc;
;     if (__any(rm > 8.0f)) {
;         const float dl = fmaxf(rm, 0.f);
;         mref += dl;
; #pragma unroll
;         for (int r = 0; r < 16; ++r) { s0[r] -= dl; s1[r] -= dl; }
;         const float alpha = fast_exp2(-dl);
;         lrun *= alpha;
;         if (hi == 0) wsf[r32] = alpha;
;         asm volatile("s_waitcnt lgkmcnt(0)" ::: "memory");
; #pragma unroll
;         for (int jj = 0; jj < 4; ++jj) { const f32x4 al = *(const LAS f32x4*)(wsf + 8 * jj + 4 * hi);
; #pragma unroll
;             for (int d = 0; d < 4; ++d) { o[d][4 * jj + 0] *= al.x; o[d][4 * jj + 1] *= al.y; o[d][4 * jj + 2] *= al.z; o[d][4 * jj + 3] *= al.w; } }
;         asm volatile("s_waitcnt lgkmcnt(0)" ::: "memory");
;     }
;     const int lane_ = hi * 32 + r32;
;     const LAS unsigned char* vb = Vt + (4 * hi + ((lane_ & 15) >> 2)) * 320 + (16 * ((lane_ >> 4) & 1) + 4 * (lane_ & 3)) * 2;
;     ...
;     bf16x8 ka[3], kc[3], va[4];
;     ...
;     DKF_(ka, 0); DKF_(kc, 1);
;     { const float v_ = b31 - mref;
; #pragma unroll
;       for (int r = 0; r < 16; ++r) { n0[r] = v_; n1[r] = v_; } }
;     SBAR_();
;     float rs = 0.f; u32x4 w0, w1, w2, w3;
;     ...
;     MF_(n0, ka[0], ka[2]); EXPN_(s0, 0, 2); SBAR_();
;     MF_(n1, ka[1], ka[2]); DKF_(ka, 2); EXPN_(s0, 2, 2); w0.x = cvt_pk_bf16(s0[0], s0[1]); SBAR_();
;     MF_(n0, kc[0], kc[2]); EXPN_(s0, 4, 2); w0.y = cvt_pk_bf16(s0[2], s0[3]); SBAR_();
;     MF_(n1, kc[1], kc[2]); DKF_(kc, 3); EXPN_(s0, 6, 2); w0.z = cvt_pk_bf16(s0[4], s0[5]); SBAR_();
;     MF_(n0, ka[0], ka[2]); EXPN_(s0, 8, 2); w0.w = cvt_pk_bf16(s0[6], s0[7]); SBAR_();
;     MF_(n1, ka[1], ka[2]); EXPN_(s0, 10, 2); w1.x = cvt_pk_bf16(s0[8], s0[9]); SBAR_();
.LBB0_496:
	v_add_co_u32_e32 v100, vcc, 0xfdff8000, v158
	s_nop 1
	v_addc_co_u32_e32 v101, vcc, -1, v159, vcc
	v_add_co_u32_e32 v104, vcc, 0xfe000000, v158
	s_nop 1
	v_addc_co_u32_e32 v105, vcc, -1, v159, vcc
	global_load_dwordx4 v[148:151], v[100:101], off
	global_load_dwordx4 v[152:155], v[104:105], off
	v_cmp_lt_f32_e32 vcc, s67, v102
	s_cbranch_vccz .LBB0_500
	v_max_f32_e32 v100, v102, v102
	v_max_f32_e32 v101, 0, v100
	v_exp_f32_e64 v100, -v101
	s_and_saveexec_b64 s[2:3], s[6:7]
	ds_write_b32 v196, v100
	s_or_b64 exec, exec, s[2:3]
	v_sub_f32_e32 v99, v99, v101
	v_sub_f32_e32 v98, v98, v101
	v_sub_f32_e32 v97, v97, v101
	v_sub_f32_e32 v96, v96, v101
	v_sub_f32_e32 v95, v95, v101
	v_sub_f32_e32 v94, v94, v101
	v_sub_f32_e32 v93, v93, v101
	v_sub_f32_e32 v92, v92, v101
	v_sub_f32_e32 v91, v91, v101
	v_sub_f32_e32 v90, v90, v101
	v_sub_f32_e32 v89, v89, v101
	v_sub_f32_e32 v88, v88, v101
	v_sub_f32_e32 v87, v87, v101
	v_sub_f32_e32 v86, v86, v101
	v_sub_f32_e32 v85, v85, v101
	v_sub_f32_e32 v84, v84, v101
	v_sub_f32_e32 v83, v83, v101
	v_sub_f32_e32 v82, v82, v101
	v_sub_f32_e32 v81, v81, v101
	v_sub_f32_e32 v80, v80, v101
	v_sub_f32_e32 v79, v79, v101
	v_sub_f32_e32 v78, v78, v101
	v_sub_f32_e32 v77, v77, v101
	v_sub_f32_e32 v76, v76, v101
	v_sub_f32_e32 v75, v75, v101
	v_sub_f32_e32 v74, v74, v101
	v_sub_f32_e32 v73, v73, v101
	v_sub_f32_e32 v72, v72, v101
	v_sub_f32_e32 v71, v71, v101
	v_sub_f32_e32 v70, v70, v101
	v_sub_f32_e32 v69, v69, v101
	v_sub_f32_e32 v68, v68, v101
	v_add_f32_e32 v191, v101, v191
	s_waitcnt lgkmcnt(0)
	v_add_u32_e32 v101, s55, v188
	ds_read_b128 v[102:105], v101
	ds_read_b128 v[106:109], v101 offset:32
	ds_read_b128 v[110:113], v101 offset:64
	ds_read_b128 v[114:117], v101 offset:96
	s_waitcnt lgkmcnt(0)
	s_waitcnt lgkmcnt(0)
	v_pk_mul_f32 v[52:53], v[52:53], v[104:105]
	v_pk_mul_f32 v[54:55], v[54:55], v[106:107]
	v_pk_mul_f32 v[58:59], v[58:59], v[110:111]
	v_pk_mul_f32 v[62:63], v[62:63], v[114:115]
	v_pk_mul_f32 v[64:65], v[64:65], v[116:117]
	v_pk_mul_f32 v[60:61], v[60:61], v[112:113]
	v_pk_mul_f32 v[56:57], v[56:57], v[108:109]
	v_pk_mul_f32 v[50:51], v[50:51], v[102:103]
	v_pk_mul_f32 v[46:47], v[46:47], v[114:115]
	v_pk_mul_f32 v[42:43], v[42:43], v[110:111]
	v_pk_mul_f32 v[38:39], v[38:39], v[106:107]
	v_pk_mul_f32 v[48:49], v[48:49], v[116:117]
	v_pk_mul_f32 v[44:45], v[44:45], v[112:113]
	v_pk_mul_f32 v[40:41], v[40:41], v[108:109]
	v_pk_mul_f32 v[36:37], v[36:37], v[104:105]
	v_pk_mul_f32 v[34:35], v[34:35], v[102:103]
	v_pk_mul_f32 v[30:31], v[30:31], v[114:115]
	v_pk_mul_f32 v[26:27], v[26:27], v[110:111]
	v_pk_mul_f32 v[22:23], v[22:23], v[106:107]
	v_pk_mul_f32 v[32:33], v[32:33], v[116:117]
	v_pk_mul_f32 v[28:29], v[28:29], v[112:113]
	v_pk_mul_f32 v[24:25], v[24:25], v[108:109]
	v_pk_mul_f32 v[20:21], v[20:21], v[104:105]
	v_pk_mul_f32 v[18:19], v[18:19], v[102:103]
	v_pk_mul_f32 v[14:15], v[14:15], v[114:115]
	v_pk_mul_f32 v[10:11], v[10:11], v[110:111]
	v_pk_mul_f32 v[6:7], v[6:7], v[106:107]
	v_pk_mul_f32 v[16:17], v[16:17], v[116:117]
	v_pk_mul_f32 v[12:13], v[12:13], v[112:113]
	v_pk_mul_f32 v[8:9], v[8:9], v[108:109]
	v_pk_mul_f32 v[4:5], v[4:5], v[104:105]
	v_pk_mul_f32 v[2:3], v[2:3], v[102:103]
	v_mul_f32_e32 v190, v100, v190
.LBB0_500:
	ds_read_b128 v[100:103], v174
	ds_read_b128 v[164:167], v174 offset:32
	ds_read_b128 v[168:171], v174 offset:8704
	ds_read_b128 v[200:203], v174 offset:8736
	ds_read_b128 v[204:207], v199
	ds_read_b128 v[208:211], v199 offset:32
	v_sub_f32_e32 v132, v66, v191
	v_mov_b32_e32 v133, v132
	v_mov_b32_e32 v134, v132
	v_mov_b32_e32 v135, v132
	v_mov_b32_e32 v136, v132
	v_mov_b32_e32 v137, v132
	v_mov_b32_e32 v138, v132
	v_mov_b32_e32 v139, v132
	v_mov_b32_e32 v140, v132
	v_mov_b32_e32 v141, v132
	v_mov_b32_e32 v142, v132
	v_mov_b32_e32 v143, v132
	v_mov_b32_e32 v144, v132
	v_mov_b32_e32 v145, v132
	v_mov_b32_e32 v146, v132
	v_mov_b32_e32 v147, v132
	s_waitcnt lgkmcnt(0)
	s_nop 0
	v_mfma_f32_32x32x16_bf16 v[116:131], v[100:103], v[204:207], v[132:147]
	v_exp_f32_e32 v84, v84
	v_exp_f32_e32 v85, v85
	v_add_f32_e32 v100, 0, v84
	v_add_f32_e32 v157, v85, v100
	v_mov_b64_e32 v[100:101], v[132:133]
	v_mov_b64_e32 v[102:103], v[134:135]
	v_mov_b64_e32 v[104:105], v[136:137]
	v_mov_b64_e32 v[106:107], v[138:139]
	v_mov_b64_e32 v[108:109], v[140:141]
	v_mov_b64_e32 v[110:111], v[142:143]
	v_mov_b64_e32 v[112:113], v[144:145]
	v_mov_b64_e32 v[114:115], v[146:147]
	ds_read_b128 v[134:137], v174 offset:64
	ds_read_b128 v[138:141], v174 offset:8768
	ds_read_b128 v[142:145], v199 offset:64
	v_mfma_f32_32x32x16_bf16 v[100:115], v[168:171], v[204:207], v[100:115]
	v_exp_f32_e32 v86, v86
	v_exp_f32_e32 v87, v87
	v_cvt_pk_bf16_f32 v168, v84, v85
	v_add_f32_e32 v133, v86, v157
	v_add_f32_e32 v133, v87, v133
	v_mfma_f32_32x32x16_bf16 v[116:131], v[164:167], v[208:211], v[116:131]
	v_exp_f32_e32 v88, v88
	v_exp_f32_e32 v89, v89
	v_cvt_pk_bf16_f32 v169, v86, v87
	v_add_f32_e32 v84, v88, v133
	v_add_f32_e32 v133, v89, v84
	v_mfma_f32_32x32x16_bf16 v[100:115], v[200:203], v[208:211], v[100:115]
	ds_read_b128 v[84:87], v174 offset:96
	ds_read_b128 v[164:167], v174 offset:8800
	ds_read_b128 v[200:203], v199 offset:96
	v_exp_f32_e32 v90, v90
	v_exp_f32_e32 v91, v91
	v_cvt_pk_bf16_f32 v170, v88, v89
	v_add_f32_e32 v133, v90, v133
	v_add_f32_e32 v133, v91, v133
	s_waitcnt lgkmcnt(0)
; #define SBAR_() __builtin_amdgcn_sched_barrier(0)
; __device__ __forceinline__ void diff_steady_step(f32x16& s0, f32x16& s1, f32x16& n0, f32x16& n1, const LAS unsigned char* kb, const LAS unsigned char* Vt, const LAS unsigned char* qlds, ...
;     ...
; #pragma unroll
;     for (int d = 0; d < 4; ++d) va[d] = DVF_(0, d);
;     MF_(n0, kc[0], kc[2]); EXPN_(s0, 12, 2); w1.y = cvt_pk_bf16(s0[10], s0[11]); SBAR_();
;     MF_(n1, kc[1], kc[2]); EXPN_(s0, 14, 2); w1.z = cvt_pk_bf16(s0[12], s0[13]); w1.w = cvt_pk_bf16(s0[14], s0[15]); SBAR_();
;     vreg[0] = *(const u32x4*)vsrc; vreg[1] = *(const u32x4*)(vsrc + vstep);
;     const bf16x8 pa0 = __builtin_bit_cast(bf16x8, w0), pa1 = __builtin_bit_cast(bf16x8, w1);
;     SBAR_();
;     MF_(o[0], pa0, va[0]); EXPN_(s1, 0, 2); SBAR_();
;     MF_(o[1], pa0, va[1]); va[0] = DVF_(1, 0); va[1] = DVF_(1, 1); EXPN_(s1, 2, 2); w2.x = cvt_pk_bf16(s1[0], s1[1]); SBAR_();
;     MF_(o[2], pa0, va[2]); va[2] = DVF_(1, 2); EXPN_(s1, 4, 2); w2.y = cvt_pk_bf16(s1[2], s1[3]); SBAR_();
;     MF_(o[3], pa0, va[3]); va[3] = DVF_(1, 3); EXPN_(s1, 6, 2); w2.z = cvt_pk_bf16(s1[4], s1[5]); w2.w = cvt_pk_bf16(s1[6], s1[7]); SBAR_();
;     MF_(o[0], pa1, va[0]); EXPN_(s1, 8, 2); SBAR_();
;     MF_(o[1], pa1, va[1]); va[0] = DVF_(2, 0); va[1] = DVF_(2, 1); EXPN_(s1, 10, 2); w3.x = cvt_pk_bf16(s1[8], s1[9]); SBAR_();
;     MF_(o[2], pa1, va[2]); va[2] = DVF_(2, 2); EXPN_(s1, 12, 2); w3.y = cvt_pk_bf16(s1[10], s1[11]); SBAR_();
;     MF_(o[3], pa1, va[3]); va[3] = DVF_(2, 3); EXPN_(s1, 14, 2); w3.z = cvt_pk_bf16(s1[12], s1[13]); w3.w = cvt_pk_bf16(s1[14], s1[15]); SBAR_();
;     lrun += rs;
;     const bf16x8 pa2 = __builtin_bit_cast(bf16x8, w2), pa3 = __builtin_bit_cast(bf16x8, w3);
;     float ra = fmaxf(fmaxf(n0[0], n0[1]), n1[0]), rb = fmaxf(fmaxf(n0[2], n0[3]), n1[1]);
;     MF_(o[0], pa2, va[0]); ra = fmaxf(fmaxf(ra, n1[2]), n1[3]); rb = fmaxf(fmaxf(rb, n0[4]), n0[5]); SBAR_();
;     MF_(o[1], pa2, va[1]); va[0] = DVF_(3, 0); va[1] = DVF_(3, 1); ra = fmaxf(fmaxf(ra, n0[6]), n0[7]); rb = fmaxf(fmaxf(rb, n1[4]), n1[5]); SBAR_();
;     MF_(o[2], pa2, va[2]); va[2] = DVF_(3, 2); ra = fmaxf(fmaxf(ra, n1[6]), n1[7]); rb = fmaxf(fmaxf(rb, n0[8]), n0[9]); SBAR_();
;     MF_(o[3], pa2, va[3]); va[3] = DVF_(3, 3); ra = fmaxf(fmaxf(ra, n0[10]), n0[11]); rb = fmaxf(fmaxf(rb, n1[8]), n1[9]); SBAR_();
	v_mfma_f32_32x32x16_bf16 v[116:131], v[134:137], v[142:145], v[116:131]
	v_exp_f32_e32 v88, v92
	v_exp_f32_e32 v92, v93
	v_cvt_pk_bf16_f32 v171, v90, v91
	v_add_f32_e32 v89, v88, v133
	v_add_f32_e32 v89, v92, v89
	v_mfma_f32_32x32x16_bf16 v[100:115], v[138:141], v[142:145], v[100:115]
	v_exp_f32_e32 v90, v94
	v_exp_f32_e32 v133, v95
	v_cvt_pk_bf16_f32 v92, v88, v92
	ds_read_b64_tr_b16 v[134:135], v198 offset:55296
	ds_read_b64_tr_b16 v[138:139], v198 offset:55360
	ds_read_b64_tr_b16 v[142:143], v198 offset:55424
	ds_read_b64_tr_b16 v[204:205], v198 offset:55488
	ds_read_b64_tr_b16 v[136:137], v198 offset:57856
	ds_read_b64_tr_b16 v[140:141], v198 offset:57920
	ds_read_b64_tr_b16 v[144:145], v198 offset:57984
	ds_read_b64_tr_b16 v[206:207], v198 offset:58048
	v_mfma_f32_32x32x16_bf16 v[116:131], v[84:87], v[200:203], v[116:131]
	v_add_f32_e32 v146, v90, v89
	v_exp_f32_e32 v147, v96
	v_exp_f32_e32 v157, v97
	v_cvt_pk_bf16_f32 v93, v90, v133
	v_mfma_f32_32x32x16_bf16 v[100:115], v[164:167], v[200:203], v[100:115]
	v_exp_f32_e32 v178, v98
	v_exp_f32_e32 v179, v99
	v_cvt_pk_bf16_f32 v94, v147, v157
	v_cvt_pk_bf16_f32 v95, v178, v179
	v_add_co_u32_e32 v84, vcc, s1, v158
	s_nop 1
	v_addc_co_u32_e32 v85, vcc, -1, v159, vcc
	v_add_co_u32_e32 v88, vcc, s61, v158
	s_nop 1
	v_addc_co_u32_e32 v89, vcc, -1, v159, vcc
	global_load_dwordx4 v[84:87], v[84:85], off
	s_nop 0
	global_load_dwordx4 v[88:91], v[88:89], off
	s_waitcnt lgkmcnt(0)
	v_mfma_f32_32x32x16_bf16 v[50:65], v[168:171], v[134:137], v[50:65]
	v_exp_f32_e32 v182, v68
	v_exp_f32_e32 v183, v69
	v_mfma_f32_32x32x16_bf16 v[34:49], v[168:171], v[138:141], v[34:49]
	ds_read_b64_tr_b16 v[96:97], v198 offset:60416
	ds_read_b64_tr_b16 v[98:99], v198 offset:62976
	ds_read_b64_tr_b16 v[134:135], v198 offset:60480
	ds_read_b64_tr_b16 v[136:137], v198 offset:63040
	v_exp_f32_e32 v184, v70
	v_exp_f32_e32 v185, v71
	v_mfma_f32_32x32x16_bf16 v[18:33], v[168:171], v[142:145], v[18:33]
	ds_read_b64_tr_b16 v[68:69], v198 offset:60544
	ds_read_b64_tr_b16 v[70:71], v198 offset:63104
	v_exp_f32_e32 v142, v72
	v_exp_f32_e32 v143, v73
	v_mfma_f32_32x32x16_bf16 v[2:17], v[168:171], v[204:207], v[2:17]
	ds_read_b64_tr_b16 v[138:139], v198 offset:60608
	ds_read_b64_tr_b16 v[140:141], v198 offset:63168
	v_exp_f32_e32 v144, v74
	v_exp_f32_e32 v145, v75
	s_waitcnt lgkmcnt(0)
	v_mfma_f32_32x32x16_bf16 v[50:65], v[92:95], v[96:99], v[50:65]
	v_exp_f32_e32 v200, v76
	v_exp_f32_e32 v201, v77
	v_mfma_f32_32x32x16_bf16 v[34:49], v[92:95], v[134:137], v[34:49]
	ds_read_b64_tr_b16 v[72:73], v197 offset:10240
	ds_read_b64_tr_b16 v[74:75], v197 offset:12800
	ds_read_b64_tr_b16 v[96:97], v197 offset:10304
	ds_read_b64_tr_b16 v[98:99], v197 offset:12864
	v_exp_f32_e32 v134, v78
	v_exp_f32_e32 v135, v79
	v_mfma_f32_32x32x16_bf16 v[18:33], v[92:95], v[68:71], v[18:33]
	ds_read_b64_tr_b16 v[68:69], v197 offset:10368
	ds_read_b64_tr_b16 v[70:71], v197 offset:12928
	v_exp_f32_e32 v136, v80
	v_exp_f32_e32 v137, v81
	v_mfma_f32_32x32x16_bf16 v[2:17], v[92:95], v[138:141], v[2:17]
	ds_read_b64_tr_b16 v[76:77], v197 offset:10432
	ds_read_b64_tr_b16 v[78:79], v197 offset:12992
	v_exp_f32_e32 v138, v82
	v_exp_f32_e32 v139, v83
	v_cvt_pk_bf16_f32 v81, v134, v135
	v_cvt_pk_bf16_f32 v80, v200, v201
	v_cvt_pk_bf16_f32 v95, v144, v145
	v_cvt_pk_bf16_f32 v94, v142, v143
	v_cvt_pk_bf16_f32 v93, v184, v185
	v_cvt_pk_bf16_f32 v92, v182, v183
	v_cvt_pk_bf16_f32 v82, v136, v137
	v_cvt_pk_bf16_f32 v83, v138, v139
	s_waitcnt lgkmcnt(0)
	v_mfma_f32_32x32x16_bf16 v[50:65], v[92:95], v[72:75], v[50:65]
	v_max_f32_e32 v140, v117, v117
	v_max_f32_e32 v141, v116, v116
	v_max_f32_e32 v140, v141, v140
	v_max3_f32 v141, v118, v119, v101
	v_max3_f32 v140, v140, v100, v102
	v_max3_f32 v141, v141, v120, v121
	v_mfma_f32_32x32x16_bf16 v[34:49], v[92:95], v[96:99], v[34:49]
	ds_read_b64_tr_b16 v[72:73], v197 offset:15360
	ds_read_b64_tr_b16 v[74:75], v197 offset:17920
	ds_read_b64_tr_b16 v[96:97], v197 offset:15424
	ds_read_b64_tr_b16 v[98:99], v197 offset:17984
	v_max3_f32 v140, v140, v103, v122
	v_max3_f32 v141, v141, v104, v105
	v_mfma_f32_32x32x16_bf16 v[18:33], v[92:95], v[68:71], v[18:33]
	ds_read_b64_tr_b16 v[68:69], v197 offset:15488
	ds_read_b64_tr_b16 v[70:71], v197 offset:18048
	v_max3_f32 v140, v140, v123, v106
	v_max3_f32 v141, v141, v124, v125
	v_mfma_f32_32x32x16_bf16 v[2:17], v[92:95], v[76:79], v[2:17]
	ds_read_b64_tr_b16 v[76:77], v197 offset:15552
	ds_read_b64_tr_b16 v[78:79], v197 offset:18112
	v_max3_f32 v92, v140, v107, v126
	v_max3_f32 v93, v141, v108, v109
	s_waitcnt lgkmcnt(0)
	v_mfma_f32_32x32x16_bf16 v[50:65], v[80:83], v[72:75], v[50:65]
	v_max3_f32 v72, v92, v127, v110
	v_max3_f32 v73, v93, v128, v129
	v_mfma_f32_32x32x16_bf16 v[34:49], v[80:83], v[96:99], v[34:49]
	v_max3_f32 v72, v72, v111, v130
	v_max3_f32 v73, v73, v112, v113
	v_mfma_f32_32x32x16_bf16 v[18:33], v[80:83], v[68:71], v[18:33]
	v_max3_f32 v72, v72, v131, v114
	v_add_co_u32_e32 v68, vcc, 0xfe008000, v158
	s_waitcnt vmcnt(0)
	ds_write_b128 v163, v[148:151] offset:37888
	ds_write_b128 v163, v[152:155] offset:46592
	ds_write_b128 v172, v[84:87] offset:17408
	ds_write_b128 v172, v[88:91] offset:27648
	v_addc_co_u32_e32 v69, vcc, -1, v159, vcc
	v_add_co_u32_e32 v70, vcc, 0xfe010000, v158
	s_waitcnt lgkmcnt(0)
	s_barrier
; #define LAS __attribute__((address_space(3)))
; __device__ __forceinline__ float fast_exp2(float x) { return __builtin_amdgcn_exp2f(x); }
; __device__ __forceinline__ float half_max(float v) { auto rr = __builtin_amdgcn_permlane32_swap(__float_as_uint(v), __float_as_uint(v), false, false); return fmaxf(__uint_as_float(rr[0]), __uint_as_float(rr[1])); }
; __device__ __forceinline__ void diff_steady_step(f32x16& s0, f32x16& s1, f32x16& n0, f32x16& n1, const LAS unsigned char* kb, const LAS unsigned char* Vt, const LAS unsigned char* qlds, ...
;     const float rm = rmc;
;     if (__any(rm > 8.0f)) {
;         const float dl = fmaxf(rm, 0.f);
;         mref += dl;
; #pragma unroll
;         for (int r = 0; r < 16; ++r) { s0[r] -= dl; s1[r] -= dl; }
;         const float alpha = fast_exp2(-dl);
;         lrun *= alpha;
;         if (hi == 0) wsf[r32] = alpha;
;         asm volatile("s_waitcnt lgkmcnt(0)" ::: "memory");
; #pragma unroll
;         for (int jj = 0; jj < 4; ++jj) { const f32x4 al = *(const LAS f32x4*)(wsf + 8 * jj + 4 * hi);
; #pragma unroll
;             for (int d = 0; d < 4; ++d) { o[d][4 * jj + 0] *= al.x; o[d][4 * jj + 1] *= al.y; o[d][4 * jj + 2] *= al.z; o[d][4 * jj + 3] *= al.w; } }
;         asm volatile("s_waitcnt lgkmcnt(0)" ::: "memory");
;     }
;     ...
;     lrun += rs;
;     const bf16x8 pa2 = __builtin_bit_cast(bf16x8, w2), pa3 = __builtin_bit_cast(bf16x8, w3);
;     float ra = fmaxf(fmaxf(n0[0], n0[1]), n1[0]), rb = fmaxf(fmaxf(n0[2], n0[3]), n1[1]);
;     MF_(o[0], pa2, va[0]); ra = fmaxf(fmaxf(ra, n1[2]), n1[3]); rb = fmaxf(fmaxf(rb, n0[4]), n0[5]); SBAR_();
;     MF_(o[1], pa2, va[1]); va[0] = DVF_(3, 0); va[1] = DVF_(3, 1); ra = fmaxf(fmaxf(ra, n0[6]), n0[7]); rb = fmaxf(fmaxf(rb, n1[4]), n1[5]); SBAR_();
;     MF_(o[2], pa2, va[2]); va[2] = DVF_(3, 2); ra = fmaxf(fmaxf(ra, n1[6]), n1[7]); rb = fmaxf(fmaxf(rb, n0[8]), n0[9]); SBAR_();
;     MF_(o[3], pa2, va[3]); va[3] = DVF_(3, 3); ra = fmaxf(fmaxf(ra, n0[10]), n0[11]); rb = fmaxf(fmaxf(rb, n1[8]), n1[9]); SBAR_();
;     MF_(o[0], pa3, va[0]); ra = fmaxf(fmaxf(ra, n1[10]), n1[11]); rb = fmaxf(fmaxf(rb, n0[12]), n0[13]); SBAR_();
;     MF_(o[1], pa3, va[1]); ra = fmaxf(fmaxf(ra, n0[14]), n0[15]); rb = fmaxf(fmaxf(rb, n1[12]), n1[13]); SBAR_();
;     MF_(o[2], pa3, va[2]); ra = fmaxf(fmaxf(ra, n1[14]), n1[15]); SBAR_();
;     MF_(o[3], pa3, va[3]);
;     ...
;     rmc = half_max(fmaxf(ra, rb));
	v_addc_co_u32_e32 v71, vcc, -1, v159, vcc
	global_load_dwordx4 v[164:167], v[68:69], off
	global_load_dwordx4 v[168:171], v[70:71], off
	v_add_f32_e32 v70, v133, v146
	v_add_f32_e32 v70, v147, v70
	v_add_f32_e32 v70, v157, v70
	v_add_f32_e32 v70, v178, v70
	v_add_f32_e32 v70, v179, v70
	v_add_f32_e32 v70, v182, v70
	v_add_f32_e32 v70, v183, v70
	v_add_f32_e32 v70, v184, v70
	v_add_f32_e32 v70, v185, v70
	v_add_f32_e32 v70, v142, v70
	v_add_f32_e32 v70, v143, v70
	v_add_f32_e32 v70, v144, v70
	v_add_f32_e32 v70, v145, v70
	v_add_f32_e32 v70, v200, v70
	v_mfma_f32_32x32x16_bf16 v[2:17], v[80:83], v[76:79], v[2:17]
	v_add_f32_e32 v70, v201, v70
	v_add_f32_e32 v70, v134, v70
	v_max3_f32 v68, v72, v115, v73
	v_add_f32_e32 v70, v135, v70
	v_mov_b32_e32 v69, v68
	v_add_f32_e32 v70, v136, v70
	s_nop 0
	v_permlane32_swap_b32_e32 v68, v69
	v_add_f32_e32 v70, v137, v70
	v_add_f32_e32 v70, v138, v70
	v_max_f32_e32 v69, v69, v69
	v_max_f32_e32 v68, v68, v68
	v_add_f32_e32 v70, v139, v70
	v_max_f32_e32 v68, v68, v69
	v_add_f32_e32 v148, v190, v70
	v_cmp_lt_f32_e32 vcc, s67, v68
	s_cbranch_vccz .LBB0_504
	v_max_f32_e32 v68, v68, v68
	v_max_f32_e32 v68, 0, v68
	v_exp_f32_e64 v69, -v68
	s_and_saveexec_b64 s[2:3], s[6:7]
	ds_write_b32 v196, v69
	s_or_b64 exec, exec, s[2:3]
	s_waitcnt lgkmcnt(0)
	v_add_u32_e32 v80, s55, v188
	v_add_f32_e32 v191, v191, v68
	v_pk_add_f32 v[116:117], v[116:117], v[68:69] op_sel_hi:[1,0] neg_lo:[0,1] neg_hi:[0,1]
	v_pk_add_f32 v[100:101], v[100:101], v[68:69] op_sel_hi:[1,0] neg_lo:[0,1] neg_hi:[0,1]
	v_pk_add_f32 v[118:119], v[118:119], v[68:69] op_sel_hi:[1,0] neg_lo:[0,1] neg_hi:[0,1]
	v_pk_add_f32 v[102:103], v[102:103], v[68:69] op_sel_hi:[1,0] neg_lo:[0,1] neg_hi:[0,1]
	v_pk_add_f32 v[120:121], v[120:121], v[68:69] op_sel_hi:[1,0] neg_lo:[0,1] neg_hi:[0,1]
	v_pk_add_f32 v[104:105], v[104:105], v[68:69] op_sel_hi:[1,0] neg_lo:[0,1] neg_hi:[0,1]
	v_pk_add_f32 v[122:123], v[122:123], v[68:69] op_sel_hi:[1,0] neg_lo:[0,1] neg_hi:[0,1]
	v_pk_add_f32 v[106:107], v[106:107], v[68:69] op_sel_hi:[1,0] neg_lo:[0,1] neg_hi:[0,1]
	v_pk_add_f32 v[124:125], v[124:125], v[68:69] op_sel_hi:[1,0] neg_lo:[0,1] neg_hi:[0,1]
	v_pk_add_f32 v[108:109], v[108:109], v[68:69] op_sel_hi:[1,0] neg_lo:[0,1] neg_hi:[0,1]
	v_pk_add_f32 v[126:127], v[126:127], v[68:69] op_sel_hi:[1,0] neg_lo:[0,1] neg_hi:[0,1]
	v_pk_add_f32 v[110:111], v[110:111], v[68:69] op_sel_hi:[1,0] neg_lo:[0,1] neg_hi:[0,1]
	v_pk_add_f32 v[128:129], v[128:129], v[68:69] op_sel_hi:[1,0] neg_lo:[0,1] neg_hi:[0,1]
	v_pk_add_f32 v[112:113], v[112:113], v[68:69] op_sel_hi:[1,0] neg_lo:[0,1] neg_hi:[0,1]
	v_pk_add_f32 v[130:131], v[130:131], v[68:69] op_sel_hi:[1,0] neg_lo:[0,1] neg_hi:[0,1]
	v_pk_add_f32 v[114:115], v[114:115], v[68:69] op_sel_hi:[1,0] neg_lo:[0,1] neg_hi:[0,1]
	v_mul_f32_e32 v148, v148, v69
	ds_read_b128 v[68:71], v80
	ds_read_b128 v[72:75], v80 offset:32
	ds_read_b128 v[76:79], v80 offset:64
	ds_read_b128 v[80:83], v80 offset:96
	s_waitcnt lgkmcnt(0)
	s_waitcnt lgkmcnt(0)
	v_pk_mul_f32 v[52:53], v[52:53], v[70:71]
	v_pk_mul_f32 v[54:55], v[54:55], v[72:73]
	v_pk_mul_f32 v[58:59], v[58:59], v[76:77]
	v_pk_mul_f32 v[62:63], v[62:63], v[80:81]
	v_pk_mul_f32 v[64:65], v[64:65], v[82:83]
	v_pk_mul_f32 v[60:61], v[60:61], v[78:79]
	v_pk_mul_f32 v[56:57], v[56:57], v[74:75]
	v_pk_mul_f32 v[50:51], v[50:51], v[68:69]
	v_pk_mul_f32 v[46:47], v[46:47], v[80:81]
	v_pk_mul_f32 v[42:43], v[42:43], v[76:77]
	v_pk_mul_f32 v[38:39], v[38:39], v[72:73]
	v_pk_mul_f32 v[48:49], v[48:49], v[82:83]
	v_pk_mul_f32 v[44:45], v[44:45], v[78:79]
	v_pk_mul_f32 v[40:41], v[40:41], v[74:75]
	v_pk_mul_f32 v[36:37], v[36:37], v[70:71]
	v_pk_mul_f32 v[34:35], v[34:35], v[68:69]
	v_pk_mul_f32 v[30:31], v[30:31], v[80:81]
	v_pk_mul_f32 v[26:27], v[26:27], v[76:77]
	v_pk_mul_f32 v[22:23], v[22:23], v[72:73]
	v_pk_mul_f32 v[32:33], v[32:33], v[82:83]
	v_pk_mul_f32 v[28:29], v[28:29], v[78:79]
	v_pk_mul_f32 v[24:25], v[24:25], v[74:75]
	v_pk_mul_f32 v[20:21], v[20:21], v[70:71]
	v_pk_mul_f32 v[18:19], v[18:19], v[68:69]
	v_pk_mul_f32 v[14:15], v[14:15], v[80:81]
	v_pk_mul_f32 v[10:11], v[10:11], v[76:77]
	v_pk_mul_f32 v[6:7], v[6:7], v[72:73]
	v_pk_mul_f32 v[16:17], v[16:17], v[82:83]
	v_pk_mul_f32 v[12:13], v[12:13], v[78:79]
	v_pk_mul_f32 v[8:9], v[8:9], v[74:75]
	v_pk_mul_f32 v[4:5], v[4:5], v[70:71]
	v_pk_mul_f32 v[2:3], v[2:3], v[68:69]
	v_sub_f32_e32 v132, v66, v191
; #define LAS __attribute__((address_space(3)))
; __device__ __forceinline__ unsigned cvt_pk_bf16(float lo, float hi) { const f32x2 v = {lo, hi}; const bf16x2_t b = __builtin_convertvector(v, bf16x2_t); return __builtin_bit_cast(unsigned, b); }
; #define SBAR_() __builtin_amdgcn_sched_barrier(0)
; __device__ __forceinline__ void diff_steady_step(f32x16& s0, f32x16& s1, f32x16& n0, f32x16& n1, const LAS unsigned char* kb, const LAS unsigned char* Vt, const LAS unsigned char* qlds, ...
;     ...
;     const int lane_ = hi * 32 + r32;
;     const LAS unsigned char* vb = Vt + (4 * hi + ((lane_ & 15) >> 2)) * 320 + (16 * ((lane_ >> 4) & 1) + 4 * (lane_ & 3)) * 2;
;     ...
;     bf16x8 ka[3], kc[3], va[4];
;     ...
;     DKF_(ka, 0); DKF_(kc, 1);
;     { const float v_ = b31 - mref;
; #pragma unroll
;       for (int r = 0; r < 16; ++r) { n0[r] = v_; n1[r] = v_; } }
;     SBAR_();
;     float rs = 0.f; u32x4 w0, w1, w2, w3;
;     ...
;     MF_(n0, ka[0], ka[2]); EXPN_(s0, 0, 2); SBAR_();
;     MF_(n1, ka[1], ka[2]); DKF_(ka, 2); EXPN_(s0, 2, 2); w0.x = cvt_pk_bf16(s0[0], s0[1]); SBAR_();
;     MF_(n0, kc[0], kc[2]); EXPN_(s0, 4, 2); w0.y = cvt_pk_bf16(s0[2], s0[3]); SBAR_();
;     MF_(n1, kc[1], kc[2]); DKF_(kc, 3); EXPN_(s0, 6, 2); w0.z = cvt_pk_bf16(s0[4], s0[5]); SBAR_();
;     MF_(n0, ka[0], ka[2]); EXPN_(s0, 8, 2); w0.w = cvt_pk_bf16(s0[6], s0[7]); SBAR_();
;     MF_(n1, ka[1], ka[2]); EXPN_(s0, 10, 2); w1.x = cvt_pk_bf16(s0[8], s0[9]); SBAR_();
; #pragma unroll
;     for (int d = 0; d < 4; ++d) va[d] = DVF_(0, d);
;     MF_(n0, kc[0], kc[2]); EXPN_(s0, 12, 2); w1.y = cvt_pk_bf16(s0[10], s0[11]); SBAR_();
;     MF_(n1, kc[1], kc[2]); EXPN_(s0, 14, 2); w1.z = cvt_pk_bf16(s0[12], s0[13]); w1.w = cvt_pk_bf16(s0[14], s0[15]); SBAR_();
;     vreg[0] = *(const u32x4*)vsrc; vreg[1] = *(const u32x4*)(vsrc + vstep);
;     const bf16x8 pa0 = __builtin_bit_cast(bf16x8, w0), pa1 = __builtin_bit_cast(bf16x8, w1);
;     SBAR_();
;     MF_(o[0], pa0, va[0]); EXPN_(s1, 0, 2); SBAR_();
;     MF_(o[1], pa0, va[1]); va[0] = DVF_(1, 0); va[1] = DVF_(1, 1); EXPN_(s1, 2, 2); w2.x = cvt_pk_bf16(s1[0], s1[1]); SBAR_();
;     MF_(o[2], pa0, va[2]); va[2] = DVF_(1, 2); EXPN_(s1, 4, 2); w2.y = cvt_pk_bf16(s1[2], s1[3]); SBAR_();
;     MF_(o[3], pa0, va[3]); va[3] = DVF_(1, 3); EXPN_(s1, 6, 2); w2.z = cvt_pk_bf16(s1[4], s1[5]); w2.w = cvt_pk_bf16(s1[6], s1[7]); SBAR_();
.LBB0_504:
	ds_read_b128 v[68:71], v174 offset:37888
	ds_read_b128 v[72:75], v174 offset:37920
	ds_read_b128 v[76:79], v174 offset:46592
	ds_read_b128 v[80:83], v174 offset:46624
	ds_read_b128 v[150:153], v199
	ds_read_b128 v[200:203], v199 offset:32
	v_mov_b32_e32 v133, v132
	v_mov_b32_e32 v134, v132
	v_mov_b32_e32 v135, v132
	v_mov_b32_e32 v136, v132
	v_mov_b32_e32 v137, v132
	v_mov_b32_e32 v138, v132
	v_mov_b32_e32 v139, v132
	v_mov_b32_e32 v140, v132
	v_mov_b32_e32 v141, v132
	v_mov_b32_e32 v142, v132
	v_mov_b32_e32 v143, v132
	v_mov_b32_e32 v144, v132
	v_mov_b32_e32 v145, v132
	v_mov_b32_e32 v146, v132
	v_mov_b32_e32 v147, v132
	s_waitcnt lgkmcnt(0)
	s_nop 0
	v_mfma_f32_32x32x16_bf16 v[84:99], v[68:71], v[150:153], v[132:147]
	v_exp_f32_e32 v116, v116
	v_exp_f32_e32 v117, v117
	v_add_f32_e32 v68, 0, v116
	v_add_f32_e32 v149, v117, v68
	v_mfma_f32_32x32x16_bf16 v[132:147], v[76:79], v[150:153], v[132:147]
	ds_read_b128 v[68:71], v174 offset:37952
	ds_read_b128 v[76:79], v174 offset:46656
	ds_read_b128 v[150:153], v199 offset:64
	v_exp_f32_e32 v118, v118
	v_exp_f32_e32 v119, v119
	v_cvt_pk_bf16_f32 v204, v116, v117
	v_add_f32_e32 v149, v118, v149
	v_add_f32_e32 v149, v119, v149
	v_mfma_f32_32x32x16_bf16 v[84:99], v[72:75], v[200:203], v[84:99]
	v_exp_f32_e32 v120, v120
	v_exp_f32_e32 v121, v121
	v_cvt_pk_bf16_f32 v205, v118, v119
	v_add_f32_e32 v72, v120, v149
	v_add_f32_e32 v149, v121, v72
	v_mfma_f32_32x32x16_bf16 v[132:147], v[80:83], v[200:203], v[132:147]
	ds_read_b128 v[72:75], v174 offset:37984
	ds_read_b128 v[116:119], v174 offset:46688
	ds_read_b128 v[200:203], v199 offset:96
	v_exp_f32_e32 v80, v122
	v_exp_f32_e32 v82, v123
	v_cvt_pk_bf16_f32 v206, v120, v121
	v_add_f32_e32 v81, v80, v149
	v_add_f32_e32 v81, v82, v81
	s_waitcnt lgkmcnt(0)
	v_mfma_f32_32x32x16_bf16 v[84:99], v[68:71], v[150:153], v[84:99]
	v_exp_f32_e32 v68, v124
	v_exp_f32_e32 v70, v125
	v_cvt_pk_bf16_f32 v207, v80, v82
	v_add_f32_e32 v69, v68, v81
	v_add_f32_e32 v69, v70, v69
	v_exp_f32_e32 v71, v126
	v_mfma_f32_32x32x16_bf16 v[132:147], v[76:79], v[150:153], v[132:147]
	v_exp_f32_e32 v149, v127
	v_cvt_pk_bf16_f32 v124, v68, v70
	ds_read_b64_tr_b16 v[150:151], v198 offset:17408
	ds_read_b64_tr_b16 v[208:209], v198 offset:17472
	ds_read_b64_tr_b16 v[212:213], v198 offset:17536
	ds_read_b64_tr_b16 v[232:233], v198 offset:17600
	ds_read_b64_tr_b16 v[152:153], v198 offset:19968
	ds_read_b64_tr_b16 v[210:211], v198 offset:20032
	ds_read_b64_tr_b16 v[214:215], v198 offset:20096
	ds_read_b64_tr_b16 v[234:235], v198 offset:20160
	v_mfma_f32_32x32x16_bf16 v[84:99], v[72:75], v[200:203], v[84:99]
	v_add_f32_e32 v154, v71, v69
	v_exp_f32_e32 v155, v128
	v_exp_f32_e32 v157, v129
	v_cvt_pk_bf16_f32 v125, v71, v149
	v_mov_b64_e32 v[68:69], v[132:133]
	v_mov_b64_e32 v[70:71], v[134:135]
	v_mov_b64_e32 v[72:73], v[136:137]
	v_mov_b64_e32 v[74:75], v[138:139]
	v_mov_b64_e32 v[76:77], v[140:141]
	v_mov_b64_e32 v[78:79], v[142:143]
	v_mov_b64_e32 v[80:81], v[144:145]
	v_mov_b64_e32 v[82:83], v[146:147]
	v_exp_f32_e32 v178, v130
	v_exp_f32_e32 v179, v131
	v_mfma_f32_32x32x16_bf16 v[68:83], v[116:119], v[200:203], v[68:83]
	v_cvt_pk_bf16_f32 v126, v155, v157
	v_cvt_pk_bf16_f32 v127, v178, v179
	v_add_co_u32_e32 v116, vcc, s40, v158
	s_nop 1
	v_addc_co_u32_e32 v117, vcc, -1, v159, vcc
	global_load_dwordx4 v[116:119], v[116:117], off
	s_nop 0
	global_load_dwordx4 v[120:123], v[158:159], off
	s_waitcnt lgkmcnt(0)
	v_mfma_f32_32x32x16_bf16 v[50:65], v[204:207], v[150:153], v[50:65]
	v_exp_f32_e32 v140, v100
	v_exp_f32_e32 v141, v101
	v_mfma_f32_32x32x16_bf16 v[34:49], v[204:207], v[208:211], v[34:49]
	ds_read_b64_tr_b16 v[128:129], v198 offset:22528
	ds_read_b64_tr_b16 v[130:131], v198 offset:25088
	ds_read_b64_tr_b16 v[132:133], v198 offset:22592
	ds_read_b64_tr_b16 v[134:135], v198 offset:25152
	v_exp_f32_e32 v142, v102
	v_exp_f32_e32 v143, v103
	v_mfma_f32_32x32x16_bf16 v[18:33], v[204:207], v[212:215], v[18:33]
	ds_read_b64_tr_b16 v[100:101], v198 offset:22656
	ds_read_b64_tr_b16 v[102:103], v198 offset:25216
	v_exp_f32_e32 v144, v104
	v_exp_f32_e32 v145, v105
	v_mfma_f32_32x32x16_bf16 v[2:17], v[204:207], v[232:235], v[2:17]
	ds_read_b64_tr_b16 v[136:137], v198 offset:22720
	ds_read_b64_tr_b16 v[138:139], v198 offset:25280
	v_exp_f32_e32 v146, v106
	v_exp_f32_e32 v147, v107
	s_waitcnt lgkmcnt(0)
; __device__ __forceinline__ unsigned cvt_pk_bf16(float lo, float hi) { const f32x2 v = {lo, hi}; const bf16x2_t b = __builtin_convertvector(v, bf16x2_t); return __builtin_bit_cast(unsigned, b); }
; #define SBAR_() __builtin_amdgcn_sched_barrier(0)
; __device__ __forceinline__ void diff_steady_step(f32x16& s0, f32x16& s1, f32x16& n0, f32x16& n1, const LAS unsigned char* kb, const LAS unsigned char* Vt, const LAS unsigned char* qlds, ...
;     ...
;     MF_(o[0], pa1, va[0]); EXPN_(s1, 8, 2); SBAR_();
;     MF_(o[1], pa1, va[1]); va[0] = DVF_(2, 0); va[1] = DVF_(2, 1); EXPN_(s1, 10, 2); w3.x = cvt_pk_bf16(s1[8], s1[9]); SBAR_();
;     MF_(o[2], pa1, va[2]); va[2] = DVF_(2, 2); EXPN_(s1, 12, 2); w3.y = cvt_pk_bf16(s1[10], s1[11]); SBAR_();
;     MF_(o[3], pa1, va[3]); va[3] = DVF_(2, 3); EXPN_(s1, 14, 2); w3.z = cvt_pk_bf16(s1[12], s1[13]); w3.w = cvt_pk_bf16(s1[14], s1[15]); SBAR_();
;     lrun += rs;
;     const bf16x8 pa2 = __builtin_bit_cast(bf16x8, w2), pa3 = __builtin_bit_cast(bf16x8, w3);
;     float ra = fmaxf(fmaxf(n0[0], n0[1]), n1[0]), rb = fmaxf(fmaxf(n0[2], n0[3]), n1[1]);
;     MF_(o[0], pa2, va[0]); ra = fmaxf(fmaxf(ra, n1[2]), n1[3]); rb = fmaxf(fmaxf(rb, n0[4]), n0[5]); SBAR_();
;     MF_(o[1], pa2, va[1]); va[0] = DVF_(3, 0); va[1] = DVF_(3, 1); ra = fmaxf(fmaxf(ra, n0[6]), n0[7]); rb = fmaxf(fmaxf(rb, n1[4]), n1[5]); SBAR_();
;     MF_(o[2], pa2, va[2]); va[2] = DVF_(3, 2); ra = fmaxf(fmaxf(ra, n1[6]), n1[7]); rb = fmaxf(fmaxf(rb, n0[8]), n0[9]); SBAR_();
;     MF_(o[3], pa2, va[3]); va[3] = DVF_(3, 3); ra = fmaxf(fmaxf(ra, n0[10]), n0[11]); rb = fmaxf(fmaxf(rb, n1[8]), n1[9]); SBAR_();
;     MF_(o[0], pa3, va[0]); ra = fmaxf(fmaxf(ra, n1[10]), n1[11]); rb = fmaxf(fmaxf(rb, n0[12]), n0[13]); SBAR_();
;     MF_(o[1], pa3, va[1]); ra = fmaxf(fmaxf(ra, n0[14]), n0[15]); rb = fmaxf(fmaxf(rb, n1[12]), n1[13]); SBAR_();
;     MF_(o[2], pa3, va[2]); ra = fmaxf(fmaxf(ra, n1[14]), n1[15]); SBAR_();
;     MF_(o[3], pa3, va[3]);
;     ...
;     rmc = half_max(fmaxf(ra, rb));
; __device__ __forceinline__ void diff_unit(const Params& P, int l, int b, int h, int qb, float lam, float lam_init, LAS unsigned char* lds, bool dry = false) {
;     ...
;     DIFF_ITER(0, s0, s1, n0, n1);
;     int t = 1;
;     float rmc = 0.f;
;     if (t + 1 <= NT - 6) rmc = rowmax32(n0, n1);
;     for (; t + 1 <= NT - 6; t += 2) { DIFF_STEADY(t, n0, n1, s0, s1); DIFF_STEADY(t + 1, s0, s1, n0, n1); }
	v_mfma_f32_32x32x16_bf16 v[50:65], v[124:127], v[128:131], v[50:65]
	v_exp_f32_e32 v150, v108
	v_exp_f32_e32 v151, v109
	v_mfma_f32_32x32x16_bf16 v[34:49], v[124:127], v[132:135], v[34:49]
	ds_read_b64_tr_b16 v[104:105], v198 offset:27648
	ds_read_b64_tr_b16 v[106:107], v198 offset:30208
	ds_read_b64_tr_b16 v[128:129], v198 offset:27712
	ds_read_b64_tr_b16 v[130:131], v198 offset:30272
	v_exp_f32_e32 v132, v110
	v_exp_f32_e32 v133, v111
	v_mfma_f32_32x32x16_bf16 v[18:33], v[124:127], v[100:103], v[18:33]
	ds_read_b64_tr_b16 v[100:101], v198 offset:27776
	ds_read_b64_tr_b16 v[102:103], v198 offset:30336
	v_exp_f32_e32 v134, v112
	v_exp_f32_e32 v135, v113
	v_mfma_f32_32x32x16_bf16 v[2:17], v[124:127], v[136:139], v[2:17]
	ds_read_b64_tr_b16 v[108:109], v198 offset:27840
	ds_read_b64_tr_b16 v[110:111], v198 offset:30400
	v_exp_f32_e32 v136, v114
	v_exp_f32_e32 v137, v115
	v_cvt_pk_bf16_f32 v113, v132, v133
	v_cvt_pk_bf16_f32 v112, v150, v151
	v_cvt_pk_bf16_f32 v127, v146, v147
	v_cvt_pk_bf16_f32 v126, v144, v145
	v_cvt_pk_bf16_f32 v125, v142, v143
	v_cvt_pk_bf16_f32 v124, v140, v141
	v_cvt_pk_bf16_f32 v114, v134, v135
	v_cvt_pk_bf16_f32 v115, v136, v137
	s_waitcnt lgkmcnt(0)
	v_mfma_f32_32x32x16_bf16 v[50:65], v[124:127], v[104:107], v[50:65]
	v_max_f32_e32 v138, v85, v85
	v_max_f32_e32 v139, v84, v84
	v_max_f32_e32 v138, v139, v138
	v_max3_f32 v139, v86, v87, v69
	v_max3_f32 v138, v138, v68, v70
	v_max3_f32 v139, v139, v88, v89
	v_mfma_f32_32x32x16_bf16 v[34:49], v[124:127], v[128:131], v[34:49]
	ds_read_b64_tr_b16 v[104:105], v198 offset:32768
	ds_read_b64_tr_b16 v[106:107], v198 offset:35328
	ds_read_b64_tr_b16 v[128:129], v198 offset:32832
	ds_read_b64_tr_b16 v[130:131], v198 offset:35392
	v_max3_f32 v138, v138, v71, v90
	v_max3_f32 v139, v139, v72, v73
	v_mfma_f32_32x32x16_bf16 v[18:33], v[124:127], v[100:103], v[18:33]
	ds_read_b64_tr_b16 v[100:101], v198 offset:32896
	ds_read_b64_tr_b16 v[102:103], v198 offset:35456
	v_max3_f32 v138, v138, v91, v74
	v_max3_f32 v139, v139, v92, v93
	v_mfma_f32_32x32x16_bf16 v[2:17], v[124:127], v[108:111], v[2:17]
	ds_read_b64_tr_b16 v[108:109], v198 offset:32960
	ds_read_b64_tr_b16 v[110:111], v198 offset:35520
	v_max3_f32 v124, v138, v75, v94
	v_max3_f32 v125, v139, v76, v77
	s_waitcnt lgkmcnt(0)
	v_mfma_f32_32x32x16_bf16 v[50:65], v[112:115], v[104:107], v[50:65]
	v_max3_f32 v104, v124, v95, v78
	v_max3_f32 v105, v125, v96, v97
	v_mfma_f32_32x32x16_bf16 v[34:49], v[112:115], v[128:131], v[34:49]
	v_max3_f32 v104, v104, v79, v98
	v_max3_f32 v105, v105, v80, v81
	v_mfma_f32_32x32x16_bf16 v[18:33], v[112:115], v[100:103], v[18:33]
	v_max3_f32 v100, v104, v99, v82
	v_add_f32_e32 v102, v149, v154
	v_add_f32_e32 v102, v155, v102
	v_add_f32_e32 v102, v157, v102
	v_add_f32_e32 v102, v178, v102
	v_add_f32_e32 v102, v179, v102
	v_add_f32_e32 v102, v140, v102
	v_add_f32_e32 v102, v141, v102
	v_add_f32_e32 v102, v142, v102
	v_add_f32_e32 v102, v143, v102
	v_add_f32_e32 v102, v144, v102
	v_add_f32_e32 v102, v145, v102
	v_add_f32_e32 v102, v146, v102
	v_add_f32_e32 v102, v147, v102
	v_add_f32_e32 v102, v150, v102
	v_mfma_f32_32x32x16_bf16 v[2:17], v[112:115], v[108:111], v[2:17]
	v_add_f32_e32 v102, v151, v102
	v_add_f32_e32 v102, v132, v102
	v_add_f32_e32 v102, v133, v102
	v_max3_f32 v100, v100, v83, v105
	v_add_f32_e32 v102, v134, v102
	v_mov_b32_e32 v101, v100
	v_add_f32_e32 v102, v135, v102
	s_nop 0
	v_permlane32_swap_b32_e32 v100, v101
	v_add_f32_e32 v102, v136, v102
	v_add_f32_e32 v102, v137, v102
	v_max_f32_e32 v101, v101, v101
	v_max_f32_e32 v100, v100, v100
	s_mov_b64 s[14:15], 0x20000
	s_add_i32 s2, s9, 2
	s_add_i32 s13, s9, 4
	s_add_i32 s3, s49, 0x80
	s_add_i32 s9, s10, 2
	s_add_i32 s11, s48, 0xffffff80
	s_add_i32 s12, s73, 2
	v_add_f32_e32 v190, v148, v102
	v_max_f32_e32 v102, v100, v101
	v_lshl_add_u64 v[158:159], v[158:159], 0, s[14:15]
	s_cmp_ge_u32 s13, s5
	v_add_u32_e32 v103, 0xffffff80, v67
	s_mov_b64 s[88:89], 0x20000
	v_lshl_add_u64 v[100:101], v[192:193], 0, s[14:15]
	s_waitcnt vmcnt(0)
	ds_write_b128 v163, v[164:167]
	ds_write_b128 v163, v[168:171] offset:8704
	ds_write_b128 v172, v[116:119] offset:55296
	ds_write_b128 v173, v[120:123] offset:55296
	s_waitcnt lgkmcnt(0)
	s_barrier
	s_cbranch_scc1 .LBB0_506
	s_mov_b32 s73, s12
	v_mov_b64_e32 v[192:193], v[100:101]
	s_mov_b32 s48, s11
	v_mov_b32_e32 v67, v103
	s_mov_b32 s10, s9
	s_mov_b32 s49, s3
	s_mov_b32 s9, s2
	s_branch .LBB0_496

; #define DIFF_QK(P0, P1, kt) do { bf16x8 qf[4]; _Pragma("unroll") for (int d0 = 0; d0 < 4; ++d0) qf[d0] = *(const LAS bf16x8*)(qlds + d0 * 32); attn_qk(P0, P1, kt, 272, qf, r32, hi); } while (0)
; #define DIFF_GLOADK(t) do { _Pragma("unroll") for (int i = 0; i < 2; ++i) kreg[i] = *(const u32x4*)(sbase + O_DK + (size_t)(64 * (t) + 32 * i) * QP); } while (0)
; #define DIFF_GLOADV(t) do { _Pragma("unroll") for (int i = 0; i < 2; ++i) vreg[i] = *(const u32x4*)(sbase + O_DV + (size_t)(64 * (t) + 32 * i) * QP); } while (0)
; #define DIFF_LSTOREK(buf) do { _Pragma("unroll") for (int i = 0; i < 2; ++i) *(LAS u32x4*)(lds + (buf) * BUFB + KOFF + (srow + 32 * i) * 272 + sch * 16) = kreg[i]; } while (0)
; #define DIFF_LSTOREV(buf) do { _Pragma("unroll") for (int i = 0; i < 2; ++i) *(LAS u32x4*)(lds + (buf) * BUFB + VOFF + (srow + 32 * i) * DVS + sch * 16) = vreg[i]; } while (0)
; __device__ __forceinline__ void diff_unit(const Params& P, int l, int b, int h, int qb, float lam, float lam_init, LAS unsigned char* lds, bool dry = false) {
;     ...
;     const int qme = q0 + wq * 32 + r32;
;     ...
;     DIFF_GLOADK(0); DIFF_GLOADV(0); DIFF_LSTOREK(0); DIFF_LSTOREV(0);
;     DIFF_GLOADK(1); DIFF_LSTOREK(1);
;     __syncthreads();
;     const float b31 = bt[127];
;     f32x16 s0, s1, n0 = {}, n1 = {};
;     DIFF_INIT(s0, s1, 0); DIFF_QK(s0, s1, lds + KOFF + map * 128);
.LBB0_508:
	s_add_i32 s2, s10, -1
	s_cmp_lt_u32 s2, s74
	s_cselect_b64 s[4:5], -1, 0
	s_cmp_ge_u32 s2, s74
	s_cbranch_scc1 .LBB0_510
	v_add_co_u32_e32 v100, vcc, 0x8000, v192
	s_nop 1
	v_addc_co_u32_e32 v101, vcc, 0, v193, vcc
	s_waitcnt vmcnt(0)
	global_load_dwordx4 v[164:167], v[192:193], off
	global_load_dwordx4 v[168:171], v[100:101], off
.LBB0_510:
	v_add_co_u32_e32 v100, vcc, 0x1ff0000, v192
	s_cmp_lt_u32 s49, s62
	s_nop 0
	v_addc_co_u32_e32 v101, vcc, 0, v193, vcc
	v_add_co_u32_e32 v102, vcc, 0x1ff8000, v192
	s_mov_b64 s[2:3], -1
	s_nop 0
	v_addc_co_u32_e32 v103, vcc, 0, v193, vcc
	s_waitcnt vmcnt(0)
	global_load_dwordx4 v[172:175], v[100:101], off
	global_load_dwordx4 v[176:179], v[102:103], off
	s_cbranch_scc1 .LBB0_512
	v_add_u32_e32 v100, v186, v67
	v_add_u32_e32 v101, 0xffffff80, v100
	v_add_u32_e32 v103, 0xffffff7f, v100
	v_add_u32_e32 v105, 0xffffff7e, v100
	v_add_u32_e32 v107, 0xffffff7d, v100
	v_med3_i32 v102, v101, 0, v223
	v_max_i32_e32 v101, 32, v101
	v_med3_i32 v104, v103, 0, v223
	v_max_i32_e32 v103, 32, v103
	v_med3_i32 v106, v105, 0, v223
	v_max_i32_e32 v105, 32, v105
	v_med3_i32 v108, v107, 0, v223
	v_max_i32_e32 v107, 32, v107
	v_subrev_u32_e32 v101, 32, v101
	v_subrev_u32_e32 v103, 32, v103
	v_subrev_u32_e32 v105, 32, v105
	v_subrev_u32_e32 v107, 32, v107
	s_add_i32 s2, 0, 0x13000
	v_min_u32_e32 v101, 0x7f, v101
	v_min_u32_e32 v103, 0x7f, v103
	v_min_u32_e32 v105, 0x7f, v105
	v_min_u32_e32 v107, 0x7f, v107
	v_lshl_add_u32 v102, v102, 2, s2
	v_lshl_add_u32 v101, v101, 2, s2
	v_lshl_add_u32 v104, v104, 2, s2
	v_lshl_add_u32 v103, v103, 2, s2
	v_lshl_add_u32 v106, v106, 2, s2
	v_lshl_add_u32 v105, v105, 2, s2
	v_lshl_add_u32 v108, v108, 2, s2
	v_lshl_add_u32 v107, v107, 2, s2
	ds_read_b32 v102, v102
	ds_read_b32 v132, v101
	ds_read_b32 v101, v104
	ds_read_b32 v103, v103
	ds_read_b32 v104, v106
	ds_read_b32 v105, v105
	ds_read_b32 v106, v108
	ds_read_b32 v107, v107
	v_add_u32_e32 v108, 0xffffff78, v100
	v_add_u32_e32 v110, 0xffffff77, v100
	v_add_u32_e32 v112, 0xffffff76, v100
	v_add_u32_e32 v114, 0xffffff75, v100
	v_add_u32_e32 v116, 0xffffff70, v100
	v_med3_i32 v109, v108, 0, v223
	v_max_i32_e32 v108, 32, v108
	v_med3_i32 v111, v110, 0, v223
	v_max_i32_e32 v110, 32, v110
	v_med3_i32 v113, v112, 0, v223
	v_max_i32_e32 v112, 32, v112
	v_med3_i32 v115, v114, 0, v223
	v_max_i32_e32 v114, 32, v114
	v_med3_i32 v117, v116, 0, v223
	v_max_i32_e32 v116, 32, v116
	v_add_u32_e32 v118, 0xffffff6f, v100
	v_add_u32_e32 v120, 0xffffff6e, v100
	v_add_u32_e32 v122, 0xffffff6d, v100
	v_subrev_u32_e32 v108, 32, v108
	v_subrev_u32_e32 v110, 32, v110
	v_subrev_u32_e32 v112, 32, v112
	v_subrev_u32_e32 v114, 32, v114
	v_subrev_u32_e32 v116, 32, v116
	v_med3_i32 v119, v118, 0, v223
	v_max_i32_e32 v118, 32, v118
	v_med3_i32 v121, v120, 0, v223
	v_max_i32_e32 v120, 32, v120
	v_med3_i32 v123, v122, 0, v223
	v_max_i32_e32 v122, 32, v122
	v_min_u32_e32 v108, 0x7f, v108
	v_min_u32_e32 v110, 0x7f, v110
	v_min_u32_e32 v112, 0x7f, v112
	v_min_u32_e32 v114, 0x7f, v114
	v_min_u32_e32 v116, 0x7f, v116
	v_subrev_u32_e32 v118, 32, v118
	v_subrev_u32_e32 v120, 32, v120
	v_subrev_u32_e32 v122, 32, v122
	v_lshl_add_u32 v109, v109, 2, s2
	v_lshl_add_u32 v108, v108, 2, s2
	v_lshl_add_u32 v111, v111, 2, s2
	v_lshl_add_u32 v110, v110, 2, s2
	v_lshl_add_u32 v113, v113, 2, s2
	v_lshl_add_u32 v112, v112, 2, s2
	v_lshl_add_u32 v115, v115, 2, s2
	v_lshl_add_u32 v114, v114, 2, s2
	v_lshl_add_u32 v117, v117, 2, s2
	v_lshl_add_u32 v116, v116, 2, s2
	v_min_u32_e32 v118, 0x7f, v118
	v_min_u32_e32 v120, 0x7f, v120
	v_min_u32_e32 v122, 0x7f, v122
	ds_read_b32 v109, v109
	ds_read_b32 v108, v108
	ds_read_b32 v111, v111
	ds_read_b32 v110, v110
	ds_read_b32 v113, v113
	ds_read_b32 v112, v112
	ds_read_b32 v115, v115
	ds_read_b32 v114, v114
	v_lshl_add_u32 v119, v119, 2, s2
	v_lshl_add_u32 v118, v118, 2, s2
	v_lshl_add_u32 v121, v121, 2, s2
	v_lshl_add_u32 v120, v120, 2, s2
	v_lshl_add_u32 v123, v123, 2, s2
	v_lshl_add_u32 v122, v122, 2, s2
	ds_read_b32 v124, v117
	ds_read_b32 v133, v116
	ds_read_b32 v116, v119
	ds_read_b32 v134, v118
	ds_read_b32 v126, v121
	ds_read_b32 v135, v120
	ds_read_b32 v127, v123
	ds_read_b32 v136, v122
	v_add_u32_e32 v117, 0xffffff68, v100
	v_med3_i32 v118, v117, 0, v223
	v_max_i32_e32 v117, 32, v117
	v_subrev_u32_e32 v117, 32, v117
	v_min_u32_e32 v117, 0x7f, v117
	v_lshl_add_u32 v129, v117, 2, s2
	v_add_u32_e32 v117, 0xffffff67, v100
	v_lshl_add_u32 v128, v118, 2, s2
	v_med3_i32 v118, v117, 0, v223
	v_max_i32_e32 v117, 32, v117
	v_subrev_u32_e32 v117, 32, v117
	v_min_u32_e32 v117, 0x7f, v117
	v_lshl_add_u32 v131, v117, 2, s2
	v_add_u32_e32 v117, 0xffffff66, v100
	v_lshl_add_u32 v130, v118, 2, s2
	v_med3_i32 v118, v117, 0, v223
	v_max_i32_e32 v117, 32, v117
	v_subrev_u32_e32 v117, 32, v117
	v_min_u32_e32 v117, 0x7f, v117
	v_add_u32_e32 v100, 0xffffff65, v100
	v_lshl_add_u32 v138, v117, 2, s2
	v_med3_i32 v117, v100, 0, v223
	v_max_i32_e32 v100, 32, v100
	v_subrev_u32_e32 v100, 32, v100
	v_min_u32_e32 v100, 0x7f, v100
	v_lshl_add_u32 v137, v118, 2, s2
	v_lshl_add_u32 v100, v100, 2, s2
	v_lshl_add_u32 v139, v117, 2, s2
	s_waitcnt lgkmcnt(0)
	v_sub_f32_e32 v117, v101, v191
	v_sub_f32_e32 v118, v104, v191
	v_sub_f32_e32 v119, v106, v191
	v_sub_f32_e32 v120, v109, v191
	v_sub_f32_e32 v122, v113, v191
	v_sub_f32_e32 v123, v115, v191
	ds_read_b32 v101, v128
	ds_read_b32 v113, v129
	ds_read_b32 v104, v130
	ds_read_b32 v115, v131
	ds_read_b32 v106, v137
	ds_read_b32 v137, v138
	ds_read_b32 v109, v139
	ds_read_b32 v100, v100
	v_sub_f32_e32 v121, v111, v191
	v_sub_f32_e32 v124, v124, v191
	v_sub_f32_e32 v125, v116, v191
	v_sub_f32_e32 v126, v126, v191
	v_sub_f32_e32 v127, v127, v191
	s_waitcnt lgkmcnt(0)
	v_sub_f32_e32 v128, v101, v191
	v_sub_f32_e32 v129, v104, v191
	v_sub_f32_e32 v130, v106, v191
	v_sub_f32_e32 v131, v109, v191
	v_sub_f32_e32 v116, v102, v191
	v_sub_f32_e32 v101, v103, v191
	v_sub_f32_e32 v102, v105, v191
	v_sub_f32_e32 v103, v107, v191
	v_sub_f32_e32 v104, v108, v191
	v_sub_f32_e32 v105, v110, v191
	v_sub_f32_e32 v106, v112, v191
	v_sub_f32_e32 v107, v114, v191
	v_sub_f32_e32 v108, v133, v191
	v_sub_f32_e32 v109, v134, v191
	v_sub_f32_e32 v110, v135, v191
	v_sub_f32_e32 v111, v136, v191
	v_sub_f32_e32 v112, v113, v191
	v_sub_f32_e32 v113, v115, v191
	v_sub_f32_e32 v114, v137, v191
	v_sub_f32_e32 v115, v100, v191
	v_sub_f32_e32 v100, v132, v191
	s_mov_b64 s[2:3], 0

.LBB0_520:
	s_add_i32 s72, s10, 2
	s_cmp_lt_u32 s72, s58
	s_cselect_b64 s[2:3], -1, 0
	s_cmp_ge_u32 s72, s58
	s_waitcnt vmcnt(0)
	ds_write_b128 v243, v[172:175] offset:17408
	ds_write_b128 v243, v[176:179] offset:27648
	s_waitcnt lgkmcnt(0)
	s_barrier
	s_cbranch_scc1 .LBB0_522
	v_add_co_u32_e32 v68, vcc, 0x10000, v192
	s_nop 1
	v_addc_co_u32_e32 v69, vcc, 0, v193, vcc
	v_add_co_u32_e32 v70, vcc, 0x18000, v192
	s_nop 1
	v_addc_co_u32_e32 v71, vcc, 0, v193, vcc
	global_load_dwordx4 v[164:167], v[68:69], off
	global_load_dwordx4 v[168:171], v[70:71], off
.LBB0_522:
	s_and_b64 vcc, exec, s[8:9]
	s_cbranch_vccnz .LBB0_524
	v_add_co_u32_e32 v68, vcc, 0x2000000, v192
	s_nop 1
	v_addc_co_u32_e32 v69, vcc, 0, v193, vcc
	v_add_co_u32_e32 v70, vcc, 0x2008000, v192
	s_nop 1
	v_addc_co_u32_e32 v71, vcc, 0, v193, vcc
	global_load_dwordx4 v[172:175], v[68:69], off
	global_load_dwordx4 v[176:179], v[70:71], off

; __device__ __forceinline__ void diff_unit(const Params& P, int l, int b, int h, int qb, float lam, float lam_init, LAS unsigned char* lds, bool dry = false) {
;     ...
;     if (map == 0) {
;         float ssq[16];
; #pragma unroll
;         for (int r = 0; r < 16; ++r) ssq[r] = 0.f;
; #pragma unroll
;         for (int d = 0; d < 4; ++d)
; #pragma unroll
;             for (int r = 0; r < 16; ++r) { const float v = o[d][r] * il[r] - xch[((wq * 4 + d) * 16 + r) * 64 + lane]; o[d][r] = v; ssq[r] += v * v; }
.LBB0_563:
	s_cmpk_gt_u32 s52, 0xff
	s_waitcnt lgkmcnt(0)
	s_barrier
	s_cbranch_scc1 .LBB0_389
	s_add_i32 s2, 0, 0x13800
	v_lshl_add_u32 v105, v189, 2, s2
	s_lshl_b32 s2, s52, 8
	s_and_b32 s3, s2, 0xc000
	v_add_u32_e32 v106, s3, v105
	ds_read2st64_b32 v[82:83], v106 offset1:1
	s_or_b32 s2, s2, 0x3f00
	v_readlane_b32 s4, v254, 29
	v_readlane_b32 s16, v254, 41
	v_readlane_b32 s17, v254, 42
	s_waitcnt lgkmcnt(0)
	v_fma_f32 v89, v50, v78, -v82
	v_fma_f32 v88, v51, v79, -v83
	ds_read2st64_b32 v[50:51], v106 offset0:2 offset1:3
	v_readlane_b32 s5, v254, 30
	v_readlane_b32 s6, v254, 31
	v_readlane_b32 s7, v254, 32
	v_readlane_b32 s8, v254, 33
	s_waitcnt lgkmcnt(0)
	v_fma_f32 v87, v52, v80, -v50
	v_fma_f32 v86, v53, v81, -v51
	ds_read2st64_b32 v[50:51], v106 offset0:4 offset1:5
	v_readlane_b32 s9, v254, 34
	v_readlane_b32 s10, v254, 35
	v_readlane_b32 s11, v254, 36
	v_readlane_b32 s12, v254, 37
	s_waitcnt lgkmcnt(0)
	v_fma_f32 v85, v54, v74, -v50
	v_fma_f32 v84, v55, v75, -v51
	ds_read2st64_b32 v[50:51], v106 offset0:6 offset1:7
	v_readlane_b32 s13, v254, 38
	v_readlane_b32 s14, v254, 39
	v_readlane_b32 s15, v254, 40
	v_readlane_b32 s18, v254, 43
	s_waitcnt lgkmcnt(0)
	v_fma_f32 v83, v56, v76, -v50
	v_fma_f32 v82, v57, v77, -v51
	ds_read2st64_b32 v[50:51], v106 offset0:8 offset1:9
	v_readlane_b32 s19, v254, 44
	s_waitcnt lgkmcnt(0)
	v_fma_f32 v57, v58, v70, -v50
	v_fma_f32 v56, v59, v71, -v51
	ds_read2st64_b32 v[50:51], v106 offset0:10 offset1:11
	ds_read2st64_b32 v[58:59], v106 offset0:14 offset1:15
	s_waitcnt lgkmcnt(0)
	v_fma_f32 v55, v60, v72, -v50
	v_fma_f32 v54, v61, v73, -v51
	ds_read2st64_b32 v[50:51], v106 offset0:12 offset1:13
	s_waitcnt lgkmcnt(0)
	v_fma_f32 v53, v62, v66, -v50
	v_fma_f32 v52, v63, v67, -v51
	v_fma_f32 v51, v64, v68, -v58
	v_fma_f32 v50, v65, v69, -v59
	ds_read2st64_b32 v[58:59], v106 offset0:16 offset1:17
	s_waitcnt lgkmcnt(0)
	v_fma_f32 v65, v34, v78, -v58
	v_fma_f32 v64, v35, v79, -v59
	ds_read2st64_b32 v[34:35], v106 offset0:18 offset1:19
	v_mul_f32_e32 v107, v65, v65
	v_fmac_f32_e32 v107, v89, v89
	v_mul_f32_e32 v104, v64, v64
	v_fmac_f32_e32 v104, v88, v88
	s_waitcnt lgkmcnt(0)
	v_fma_f32 v63, v36, v80, -v34
	v_fma_f32 v62, v37, v81, -v35
	ds_read2st64_b32 v[34:35], v106 offset0:20 offset1:21
	v_mul_f32_e32 v103, v63, v63
	v_fmac_f32_e32 v103, v87, v87
	v_mul_f32_e32 v102, v62, v62
	v_fmac_f32_e32 v102, v86, v86
	s_waitcnt lgkmcnt(0)
	v_fma_f32 v60, v38, v74, -v34
	v_fma_f32 v58, v39, v75, -v35
	ds_read2st64_b32 v[34:35], v106 offset0:22 offset1:23
	v_mul_f32_e32 v101, v60, v60
	v_fmac_f32_e32 v101, v85, v85
	v_mul_f32_e32 v99, v58, v58
	v_fmac_f32_e32 v99, v84, v84
	s_waitcnt lgkmcnt(0)
	v_fma_f32 v61, v40, v76, -v34
	v_fma_f32 v59, v41, v77, -v35
	ds_read2st64_b32 v[34:35], v106 offset0:24 offset1:25
	v_mul_f32_e32 v100, v61, v61
	v_fmac_f32_e32 v100, v83, v83
	v_mul_f32_e32 v96, v59, v59
	v_fmac_f32_e32 v96, v82, v82
	s_waitcnt lgkmcnt(0)
	v_fma_f32 v41, v42, v70, -v34
	v_fma_f32 v40, v43, v71, -v35
	ds_read2st64_b32 v[34:35], v106 offset0:26 offset1:27
	ds_read2st64_b32 v[42:43], v106 offset0:30 offset1:31
	v_mul_f32_e32 v95, v41, v41
	v_fmac_f32_e32 v95, v57, v57
	v_mul_f32_e32 v90, v40, v40
	s_waitcnt lgkmcnt(0)
	v_fma_f32 v39, v44, v72, -v34
	v_fma_f32 v38, v45, v73, -v35
	ds_read2st64_b32 v[34:35], v106 offset0:28 offset1:29
	v_fma_f32 v37, v48, v68, -v42
	v_fmac_f32_e32 v90, v56, v56
	v_mul_f32_e32 v92, v39, v39
	v_fmac_f32_e32 v92, v55, v55
	s_waitcnt lgkmcnt(0)
	v_fma_f32 v36, v46, v66, -v34
	v_fma_f32 v34, v47, v67, -v35
	v_fma_f32 v35, v49, v69, -v43
	ds_read2st64_b32 v[42:43], v106 offset0:32 offset1:33
	v_mul_f32_e32 v91, v38, v38
	v_fmac_f32_e32 v91, v54, v54
	v_mul_f32_e32 v94, v36, v36
	v_fmac_f32_e32 v94, v53, v53
	s_waitcnt lgkmcnt(0)
	v_fma_f32 v49, v18, v78, -v42
	v_fma_f32 v48, v19, v79, -v43
	ds_read2st64_b32 v[18:19], v106 offset0:34 offset1:35
	v_fmac_f32_e32 v107, v49, v49
	v_fmac_f32_e32 v104, v48, v48
	v_mul_f32_e32 v93, v34, v34
	v_fmac_f32_e32 v93, v52, v52
	s_waitcnt lgkmcnt(0)
	v_fma_f32 v47, v20, v80, -v18
	v_fma_f32 v46, v21, v81, -v19
	ds_read2st64_b32 v[18:19], v106 offset0:36 offset1:37
	v_fmac_f32_e32 v103, v47, v47
	v_fmac_f32_e32 v102, v46, v46
	v_mul_f32_e32 v98, v37, v37
	v_fmac_f32_e32 v98, v51, v51
	s_waitcnt lgkmcnt(0)
	v_fma_f32 v45, v22, v74, -v18
	v_fma_f32 v43, v23, v75, -v19
	ds_read2st64_b32 v[18:19], v106 offset0:38 offset1:39
	v_fmac_f32_e32 v101, v45, v45
	v_fmac_f32_e32 v99, v43, v43
	v_mul_f32_e32 v97, v35, v35
	v_fmac_f32_e32 v97, v50, v50
	s_waitcnt lgkmcnt(0)
	v_fma_f32 v44, v24, v76, -v18
	v_fma_f32 v42, v25, v77, -v19
	ds_read2st64_b32 v[18:19], v106 offset0:40 offset1:41
	v_fmac_f32_e32 v100, v44, v44
	v_fmac_f32_e32 v96, v42, v42
	s_waitcnt lgkmcnt(0)
	v_fma_f32 v25, v26, v70, -v18
	v_fma_f32 v24, v27, v71, -v19
	ds_read2st64_b32 v[18:19], v106 offset0:42 offset1:43
	ds_read2st64_b32 v[26:27], v106 offset0:46 offset1:47
	v_fmac_f32_e32 v95, v25, v25
	v_fmac_f32_e32 v90, v24, v24
	s_waitcnt lgkmcnt(0)
	v_fma_f32 v23, v28, v72, -v18
	v_fma_f32 v22, v29, v73, -v19
	ds_read2st64_b32 v[18:19], v106 offset0:44 offset1:45
	v_fma_f32 v20, v32, v68, -v26
	v_fmac_f32_e32 v92, v23, v23
	v_fmac_f32_e32 v91, v22, v22
	v_fmac_f32_e32 v98, v20, v20
	s_waitcnt lgkmcnt(0)
	v_fma_f32 v21, v30, v66, -v18
	v_fma_f32 v18, v33, v69, -v27
	ds_read2st64_b32 v[26:27], v106 offset0:48 offset1:49
	v_fma_f32 v19, v31, v67, -v19
	v_fmac_f32_e32 v94, v21, v21
	v_fmac_f32_e32 v93, v19, v19
	v_fmac_f32_e32 v97, v18, v18
	s_waitcnt lgkmcnt(0)
	v_fma_f32 v78, v2, v78, -v26
	v_fma_f32 v33, v3, v79, -v27
	ds_read2st64_b32 v[2:3], v106 offset0:50 offset1:51
	v_fmac_f32_e32 v107, v78, v78
	v_fmac_f32_e32 v104, v33, v33
	s_waitcnt lgkmcnt(0)
; __device__ __forceinline__ float fast_rsq(float x) { return __builtin_amdgcn_rsqf(x); }
; __device__ __forceinline__ int crow(int r, int hi) { return (r & 3) + 8 * (r >> 2) + 4 * hi; }
; __device__ __forceinline__ void diff_unit(const Params& P, int l, int b, int h, int qb, float lam, float lam_init, LAS unsigned char* lds, bool dry = false) {
;     ...
;             for (int r = 0; r < 16; ++r) { const float v = o[d][r] * il[r] - xch[((wq * 4 + d) * 16 + r) * 64 + lane]; o[d][r] = v; ssq[r] += v * v; }
; #pragma unroll
;         for (int r = 0; r < 16; ++r) {
; #pragma unroll
;             for (int s = 1; s < 32; s <<= 1) ssq[r] += __shfl_xor(ssq[r], s);
;         }
;         const float post = 1.0f - lam_init;
;         float gsub[4];
; #pragma unroll
;         for (int d = 0; d < 4; ++d) gsub[d] = P.in[I_SUBG][l * 128 + 32 * d + r32] * post;
;         bf16_t* Ow = proj + O_DQ + (rowb + q0 + wq * 32) * QP + h * 128;
; #pragma unroll
;         for (int r = 0; r < 16; ++r) { const int q = crow(r, hi); const float rstd = fast_rsq(ssq[r] * (1.0f / 128.0f) + EPS);
	v_fma_f32 v32, v4, v80, -v2
	v_fma_f32 v31, v5, v81, -v3
	ds_read2st64_b32 v[2:3], v106 offset0:52 offset1:53
	v_fmac_f32_e32 v103, v32, v32
	v_fmac_f32_e32 v102, v31, v31
	s_waitcnt lgkmcnt(0)
	v_fma_f32 v30, v6, v74, -v2
	v_fma_f32 v28, v7, v75, -v3
	ds_read2st64_b32 v[2:3], v106 offset0:54 offset1:55
	v_fmac_f32_e32 v101, v30, v30
	v_fmac_f32_e32 v99, v28, v28
	v_or_b32_e32 v74, s64, v186
	v_mov_b32_e32 v75, v0
	s_waitcnt lgkmcnt(0)
	v_fma_f32 v29, v8, v76, -v2
	v_fma_f32 v27, v9, v77, -v3
	ds_read2st64_b32 v[2:3], v106 offset0:56 offset1:57
	v_fmac_f32_e32 v100, v29, v29
	v_fmac_f32_e32 v96, v27, v27
	v_lshl_add_u64 v[80:81], v[74:75], 2, s[16:17]
	s_waitcnt lgkmcnt(0)
	v_fma_f32 v26, v10, v70, -v2
	v_fma_f32 v10, v11, v71, -v3
	ds_read2st64_b32 v[2:3], v106 offset0:58 offset1:59
	v_fmac_f32_e32 v95, v26, v26
	v_fmac_f32_e32 v90, v10, v10
	s_waitcnt lgkmcnt(0)
	v_fma_f32 v9, v12, v72, -v2
	v_fma_f32 v8, v13, v73, -v3
	ds_read2st64_b32 v[2:3], v106 offset0:60 offset1:61
	v_fmac_f32_e32 v92, v9, v9
	v_fmac_f32_e32 v91, v8, v8
	s_waitcnt lgkmcnt(0)
	v_fma_f32 v7, v14, v66, -v2
	ds_read_b32 v2, v106 offset:15872
	v_fma_f32 v6, v15, v67, -v3
	v_fmac_f32_e32 v94, v7, v7
	v_fmac_f32_e32 v93, v6, v6
	s_waitcnt lgkmcnt(0)
	v_fma_f32 v5, v16, v68, -v2
	v_add_u32_e32 v2, s2, v105
	ds_read_b32 v2, v2
	v_fmac_f32_e32 v98, v5, v5
	s_lshl_b64 s[2:3], s[90:91], 10
	s_add_u32 s2, s50, s2
	s_addc_u32 s3, s51, s3
	s_waitcnt lgkmcnt(0)
	v_fma_f32 v4, v17, v69, -v2
	ds_bpermute_b32 v2, v225, v107
	v_fmac_f32_e32 v97, v4, v4
	s_add_u32 s2, s2, s96
	s_addc_u32 s3, s3, 0
	s_waitcnt lgkmcnt(0)
	v_add_f32_e32 v2, v107, v2
	ds_bpermute_b32 v3, v221, v2
	s_waitcnt lgkmcnt(0)
	v_add_f32_e32 v2, v2, v3
	ds_bpermute_b32 v3, v222, v2
	s_waitcnt lgkmcnt(0)
	v_add_f32_e32 v2, v2, v3
	ds_bpermute_b32 v3, v252, v2
	s_waitcnt lgkmcnt(0)
	v_add_f32_e32 v2, v2, v3
	ds_bpermute_b32 v3, v253, v2
	s_waitcnt lgkmcnt(0)
	v_add_f32_e32 v2, v2, v3
	ds_bpermute_b32 v3, v225, v104
	v_fmamk_f32 v2, v2, 0x3c000000, v216
	v_rsq_f32_e32 v79, v2
	v_lshlrev_b32_e32 v2, 12, v1
	s_waitcnt lgkmcnt(0)
	v_add_f32_e32 v3, v104, v3
	ds_bpermute_b32 v11, v221, v3
	v_mul_f32_e32 v1, v89, v79
	s_waitcnt lgkmcnt(0)
	v_add_f32_e32 v3, v3, v11
	ds_bpermute_b32 v11, v222, v3
	s_waitcnt lgkmcnt(0)
	v_add_f32_e32 v3, v3, v11
	ds_bpermute_b32 v11, v252, v3
	s_waitcnt lgkmcnt(0)
	v_add_f32_e32 v3, v3, v11
	ds_bpermute_b32 v11, v253, v3
	s_waitcnt lgkmcnt(0)
	v_add_f32_e32 v15, v3, v11
	ds_bpermute_b32 v3, v225, v103
	s_waitcnt lgkmcnt(0)
	v_add_f32_e32 v3, v103, v3
	ds_bpermute_b32 v11, v221, v3
	s_waitcnt lgkmcnt(0)
	v_add_f32_e32 v3, v3, v11
	ds_bpermute_b32 v11, v222, v3
	s_waitcnt lgkmcnt(0)
	v_add_f32_e32 v3, v3, v11
	ds_bpermute_b32 v11, v252, v3
	s_waitcnt lgkmcnt(0)
	v_add_f32_e32 v3, v3, v11
	ds_bpermute_b32 v11, v253, v3
	s_waitcnt lgkmcnt(0)
	v_add_f32_e32 v16, v3, v11
	ds_bpermute_b32 v3, v225, v102
	s_waitcnt lgkmcnt(0)
	v_add_f32_e32 v3, v102, v3
	ds_bpermute_b32 v11, v221, v3
	s_waitcnt lgkmcnt(0)
	v_add_f32_e32 v3, v3, v11
	ds_bpermute_b32 v11, v222, v3
	s_waitcnt lgkmcnt(0)
	v_add_f32_e32 v3, v3, v11
	ds_bpermute_b32 v11, v252, v3
	s_waitcnt lgkmcnt(0)
	v_add_f32_e32 v3, v3, v11
	ds_bpermute_b32 v11, v253, v3
	s_waitcnt lgkmcnt(0)
	v_add_f32_e32 v66, v3, v11
	ds_bpermute_b32 v3, v225, v101
	s_waitcnt lgkmcnt(0)
	v_add_f32_e32 v3, v101, v3
	ds_bpermute_b32 v11, v221, v3
	s_waitcnt lgkmcnt(0)
	v_add_f32_e32 v3, v3, v11
	ds_bpermute_b32 v11, v222, v3
	s_waitcnt lgkmcnt(0)
	v_add_f32_e32 v3, v3, v11
	ds_bpermute_b32 v11, v252, v3
	s_waitcnt lgkmcnt(0)
	v_add_f32_e32 v3, v3, v11
	ds_bpermute_b32 v11, v253, v3
	s_waitcnt lgkmcnt(0)
	v_add_f32_e32 v67, v3, v11
	ds_bpermute_b32 v3, v225, v99
	s_waitcnt lgkmcnt(0)
	v_add_f32_e32 v3, v99, v3
	ds_bpermute_b32 v11, v221, v3
	s_waitcnt lgkmcnt(0)
	v_add_f32_e32 v3, v3, v11
	ds_bpermute_b32 v11, v222, v3
	s_waitcnt lgkmcnt(0)
	v_add_f32_e32 v3, v3, v11
	ds_bpermute_b32 v11, v252, v3
	s_waitcnt lgkmcnt(0)
	v_add_f32_e32 v3, v3, v11
	ds_bpermute_b32 v11, v253, v3
	s_waitcnt lgkmcnt(0)
	v_add_f32_e32 v68, v3, v11
	ds_bpermute_b32 v3, v225, v100
	s_waitcnt lgkmcnt(0)
	v_add_f32_e32 v3, v100, v3
	ds_bpermute_b32 v11, v221, v3
	s_waitcnt lgkmcnt(0)
	v_add_f32_e32 v3, v3, v11
	ds_bpermute_b32 v11, v222, v3
	s_waitcnt lgkmcnt(0)
	v_add_f32_e32 v3, v3, v11
	ds_bpermute_b32 v11, v252, v3
	s_waitcnt lgkmcnt(0)
	v_add_f32_e32 v3, v3, v11
	ds_bpermute_b32 v11, v253, v3
	s_waitcnt lgkmcnt(0)
	v_add_f32_e32 v70, v3, v11
	ds_bpermute_b32 v3, v225, v96
	s_waitcnt lgkmcnt(0)
	v_add_f32_e32 v3, v96, v3
	ds_bpermute_b32 v11, v221, v3
	s_waitcnt lgkmcnt(0)
	v_add_f32_e32 v3, v3, v11
	ds_bpermute_b32 v11, v222, v3
	s_waitcnt lgkmcnt(0)
	v_add_f32_e32 v3, v3, v11
	ds_bpermute_b32 v11, v252, v3
	s_waitcnt lgkmcnt(0)
	v_add_f32_e32 v3, v3, v11
	ds_bpermute_b32 v11, v253, v3
	s_waitcnt lgkmcnt(0)
	v_add_f32_e32 v71, v3, v11
	ds_bpermute_b32 v3, v225, v95
	s_waitcnt lgkmcnt(0)
	v_add_f32_e32 v3, v95, v3
	ds_bpermute_b32 v11, v221, v3
	s_waitcnt lgkmcnt(0)
	v_add_f32_e32 v3, v3, v11
	ds_bpermute_b32 v11, v222, v3
	s_waitcnt lgkmcnt(0)
	v_add_f32_e32 v3, v3, v11
	ds_bpermute_b32 v11, v252, v3
	s_waitcnt lgkmcnt(0)
	v_add_f32_e32 v3, v3, v11
	ds_bpermute_b32 v11, v253, v3
	s_waitcnt lgkmcnt(0)
	v_add_f32_e32 v73, v3, v11
	ds_bpermute_b32 v3, v225, v90
	s_waitcnt lgkmcnt(0)
	v_add_f32_e32 v3, v90, v3
	ds_bpermute_b32 v11, v221, v3
	s_waitcnt lgkmcnt(0)
	v_add_f32_e32 v3, v3, v11
	ds_bpermute_b32 v11, v222, v3
	s_waitcnt lgkmcnt(0)
	v_add_f32_e32 v3, v3, v11
	ds_bpermute_b32 v11, v252, v3
	s_waitcnt lgkmcnt(0)
	v_add_f32_e32 v3, v3, v11
	ds_bpermute_b32 v11, v253, v3
	s_waitcnt lgkmcnt(0)
; __device__ __forceinline__ unsigned f2bf(float f) { unsigned u = __builtin_bit_cast(unsigned, f); return (u + 0x7fffu + ((u >> 16) & 1u)) >> 16; }
; __device__ __forceinline__ float fast_rsq(float x) { return __builtin_amdgcn_rsqf(x); }
; __device__ __forceinline__ int crow(int r, int hi) { return (r & 3) + 8 * (r >> 2) + 4 * hi; }
; __device__ __forceinline__ void diff_unit(const Params& P, int l, int b, int h, int qb, float lam, float lam_init, LAS unsigned char* lds, bool dry = false) {
;     ...
;         for (int r = 0; r < 16; ++r) {
; #pragma unroll
;             for (int s = 1; s < 32; s <<= 1) ssq[r] += __shfl_xor(ssq[r], s);
;         }
;         const float post = 1.0f - lam_init;
;         float gsub[4];
; #pragma unroll
;         for (int d = 0; d < 4; ++d) gsub[d] = P.in[I_SUBG][l * 128 + 32 * d + r32] * post;
;         bf16_t* Ow = proj + O_DQ + (rowb + q0 + wq * 32) * QP + h * 128;
; #pragma unroll
;         for (int r = 0; r < 16; ++r) { const int q = crow(r, hi); const float rstd = fast_rsq(ssq[r] * (1.0f / 128.0f) + EPS);
; #pragma unroll
;             for (int d = 0; d < 4; ++d) if (!dry || o[d][r] == 1.2345e30f) Ow[(size_t)q * QP + 32 * d + r32] = (bf16_t)f2bf(o[d][r] * rstd * gsub[d]); }
	v_add_f32_e32 v72, v3, v11
	ds_bpermute_b32 v3, v225, v92
	s_waitcnt lgkmcnt(0)
	v_add_f32_e32 v3, v92, v3
	ds_bpermute_b32 v11, v221, v3
	s_waitcnt lgkmcnt(0)
	v_add_f32_e32 v3, v3, v11
	ds_bpermute_b32 v11, v222, v3
	s_waitcnt lgkmcnt(0)
	v_add_f32_e32 v3, v3, v11
	ds_bpermute_b32 v11, v252, v3
	s_waitcnt lgkmcnt(0)
	v_add_f32_e32 v3, v3, v11
	ds_bpermute_b32 v11, v253, v3
	s_waitcnt lgkmcnt(0)
	v_add_f32_e32 v69, v3, v11
	ds_bpermute_b32 v3, v225, v91
	s_waitcnt lgkmcnt(0)
	v_add_f32_e32 v3, v91, v3
	ds_bpermute_b32 v11, v221, v3
	s_waitcnt lgkmcnt(0)
	v_add_f32_e32 v3, v3, v11
	ds_bpermute_b32 v11, v222, v3
	s_waitcnt lgkmcnt(0)
	v_add_f32_e32 v3, v3, v11
	ds_bpermute_b32 v11, v252, v3
	s_waitcnt lgkmcnt(0)
	v_add_f32_e32 v3, v3, v11
	ds_bpermute_b32 v11, v253, v3
	s_waitcnt lgkmcnt(0)
	v_add_f32_e32 v17, v3, v11
	ds_bpermute_b32 v3, v225, v94
	s_waitcnt lgkmcnt(0)
	v_add_f32_e32 v3, v94, v3
	ds_bpermute_b32 v11, v221, v3
	s_waitcnt lgkmcnt(0)
	v_add_f32_e32 v3, v3, v11
	ds_bpermute_b32 v11, v222, v3
	s_waitcnt lgkmcnt(0)
	v_add_f32_e32 v3, v3, v11
	ds_bpermute_b32 v11, v252, v3
	s_waitcnt lgkmcnt(0)
	v_add_f32_e32 v3, v3, v11
	ds_bpermute_b32 v11, v253, v3
	s_waitcnt lgkmcnt(0)
	v_add_f32_e32 v14, v3, v11
	ds_bpermute_b32 v3, v225, v93
	s_waitcnt lgkmcnt(0)
	v_add_f32_e32 v3, v93, v3
	ds_bpermute_b32 v11, v221, v3
	s_waitcnt lgkmcnt(0)
	v_add_f32_e32 v3, v3, v11
	ds_bpermute_b32 v11, v222, v3
	s_waitcnt lgkmcnt(0)
	v_add_f32_e32 v3, v3, v11
	ds_bpermute_b32 v11, v252, v3
	s_waitcnt lgkmcnt(0)
	v_add_f32_e32 v3, v3, v11
	ds_bpermute_b32 v11, v253, v3
	s_waitcnt lgkmcnt(0)
	v_add_f32_e32 v13, v3, v11
	ds_bpermute_b32 v3, v225, v98
	s_waitcnt lgkmcnt(0)
	v_add_f32_e32 v3, v98, v3
	ds_bpermute_b32 v11, v221, v3
	s_waitcnt lgkmcnt(0)
	v_add_f32_e32 v3, v3, v11
	ds_bpermute_b32 v11, v222, v3
	s_waitcnt lgkmcnt(0)
	v_add_f32_e32 v3, v3, v11
	ds_bpermute_b32 v11, v252, v3
	s_waitcnt lgkmcnt(0)
	v_add_f32_e32 v3, v3, v11
	ds_bpermute_b32 v11, v253, v3
	s_waitcnt lgkmcnt(0)
	v_add_f32_e32 v12, v3, v11
	ds_bpermute_b32 v3, v225, v97
	s_waitcnt lgkmcnt(0)
	v_add_f32_e32 v3, v97, v3
	ds_bpermute_b32 v11, v221, v3
	s_waitcnt lgkmcnt(0)
	v_add_f32_e32 v3, v3, v11
	ds_bpermute_b32 v11, v222, v3
	s_waitcnt lgkmcnt(0)
	v_add_f32_e32 v3, v3, v11
	ds_bpermute_b32 v11, v252, v3
	s_waitcnt lgkmcnt(0)
	v_add_f32_e32 v3, v3, v11
	ds_bpermute_b32 v11, v253, v3
	s_waitcnt lgkmcnt(0)
	v_add_f32_e32 v11, v3, v11
	global_load_dword v3, v[80:81], off
	s_waitcnt vmcnt(0)
	v_mul_f32_e32 v74, v194, v3
	global_load_dword v3, v[80:81], off offset:128
	v_mul_f32_e32 v1, v1, v74
	s_waitcnt vmcnt(0)
	v_mul_f32_e32 v75, v194, v3
	global_load_dword v3, v[80:81], off offset:256
	s_waitcnt vmcnt(0)
	v_mul_f32_e32 v76, v194, v3
	global_load_dword v3, v[80:81], off offset:384
	v_lshlrev_b32_e32 v80, 1, v186
	v_mov_b32_e32 v81, v0
	v_lshl_add_u64 v[80:81], s[2:3], 0, v[80:81]
	s_movk_i32 s2, 0x4000
	s_waitcnt vmcnt(0)
	v_mul_f32_e32 v77, v194, v3
	v_mov_b32_e32 v3, v0
	v_lshl_add_u64 v[2:3], v[80:81], 0, v[2:3]
	v_bfe_u32 v80, v1, 16, 1
	v_add3_u32 v1, v1, v80, s60
	global_store_short_d16_hi v[2:3], v1, off
	v_mul_f32_e32 v1, v65, v79
	v_mul_f32_e32 v1, v1, v75
	v_bfe_u32 v65, v1, 16, 1
	v_add3_u32 v1, v1, v65, s60
	global_store_short_d16_hi v[2:3], v1, off offset:64
	v_mul_f32_e32 v1, v49, v79
	v_mul_f32_e32 v1, v1, v76
	v_bfe_u32 v49, v1, 16, 1
	v_add3_u32 v1, v1, v49, s60
	global_store_short_d16_hi v[2:3], v1, off offset:128
	v_mul_f32_e32 v1, v78, v79
	v_mul_f32_e32 v1, v1, v77
	v_bfe_u32 v49, v1, 16, 1
	v_add3_u32 v1, v1, v49, s60
	global_store_short_d16_hi v[2:3], v1, off offset:192
	v_fmamk_f32 v1, v15, 0x3c000000, v216
	v_rsq_f32_e32 v1, v1
	s_nop 0
	v_mul_f32_e32 v15, v88, v1
	v_mul_f32_e32 v15, v15, v74
	v_bfe_u32 v49, v15, 16, 1
	v_add3_u32 v15, v15, v49, s60
	global_store_short_d16_hi v[2:3], v15, off offset:1024
	v_mul_f32_e32 v15, v64, v1
	v_mul_f32_e32 v15, v15, v75
	v_bfe_u32 v49, v15, 16, 1
	v_add3_u32 v15, v15, v49, s60
	global_store_short_d16_hi v[2:3], v15, off offset:1088
	v_mul_f32_e32 v15, v48, v1
	v_mul_f32_e32 v15, v15, v76
	v_bfe_u32 v48, v15, 16, 1
	v_mul_f32_e32 v1, v33, v1
	v_add3_u32 v15, v15, v48, s60
	v_mul_f32_e32 v1, v1, v77
	global_store_short_d16_hi v[2:3], v15, off offset:1152
	v_bfe_u32 v15, v1, 16, 1
	v_add3_u32 v1, v1, v15, s60
	global_store_short_d16_hi v[2:3], v1, off offset:1216
	v_fmamk_f32 v1, v16, 0x3c000000, v216
	v_rsq_f32_e32 v1, v1
	s_nop 0
	v_mul_f32_e32 v15, v87, v1
	v_mul_f32_e32 v15, v15, v74
	v_bfe_u32 v16, v15, 16, 1
	v_add3_u32 v15, v15, v16, s60
	global_store_short_d16_hi v[2:3], v15, off offset:2048
	v_mul_f32_e32 v15, v63, v1
	v_mul_f32_e32 v15, v15, v75
	v_bfe_u32 v16, v15, 16, 1
	v_add3_u32 v15, v15, v16, s60
	global_store_short_d16_hi v[2:3], v15, off offset:2112
	v_mul_f32_e32 v15, v47, v1
	v_mul_f32_e32 v15, v15, v76
	v_bfe_u32 v16, v15, 16, 1
	v_mul_f32_e32 v1, v32, v1
	v_add3_u32 v15, v15, v16, s60
	v_mul_f32_e32 v1, v1, v77
	global_store_short_d16_hi v[2:3], v15, off offset:2176
	v_bfe_u32 v15, v1, 16, 1
	v_add3_u32 v1, v1, v15, s60
	global_store_short_d16_hi v[2:3], v1, off offset:2240
	v_fmamk_f32 v1, v66, 0x3c000000, v216
	v_rsq_f32_e32 v1, v1
	v_add_co_u32_e32 v32, vcc, s77, v2
	v_mul_f32_e32 v15, v86, v1
	v_mul_f32_e32 v15, v15, v74
	v_bfe_u32 v16, v15, 16, 1
	v_add3_u32 v15, v15, v16, s60
	global_store_short_d16_hi v[2:3], v15, off offset:3072
	v_mul_f32_e32 v15, v62, v1
	v_mul_f32_e32 v15, v15, v75
	v_bfe_u32 v16, v15, 16, 1
	v_add3_u32 v15, v15, v16, s60
	global_store_short_d16_hi v[2:3], v15, off offset:3136
	v_mul_f32_e32 v15, v46, v1
	v_mul_f32_e32 v15, v15, v76
	v_bfe_u32 v16, v15, 16, 1
; __device__ __forceinline__ unsigned f2bf(float f) { unsigned u = __builtin_bit_cast(unsigned, f); return (u + 0x7fffu + ((u >> 16) & 1u)) >> 16; }
; __device__ __forceinline__ float fast_rsq(float x) { return __builtin_amdgcn_rsqf(x); }
; __device__ __forceinline__ int crow(int r, int hi) { return (r & 3) + 8 * (r >> 2) + 4 * hi; }
; __device__ __forceinline__ void diff_unit(const Params& P, int l, int b, int h, int qb, float lam, float lam_init, LAS unsigned char* lds, bool dry = false) {
;     ...
;         for (int r = 0; r < 16; ++r) { const int q = crow(r, hi); const float rstd = fast_rsq(ssq[r] * (1.0f / 128.0f) + EPS);
; #pragma unroll
;             for (int d = 0; d < 4; ++d) if (!dry || o[d][r] == 1.2345e30f) Ow[(size_t)q * QP + 32 * d + r32] = (bf16_t)f2bf(o[d][r] * rstd * gsub[d]); }
	v_mul_f32_e32 v1, v31, v1
	v_add3_u32 v15, v15, v16, s60
	v_mul_f32_e32 v1, v1, v77
	global_store_short_d16_hi v[2:3], v15, off offset:3200
	v_bfe_u32 v15, v1, 16, 1
	v_add3_u32 v1, v1, v15, s60
	global_store_short_d16_hi v[2:3], v1, off offset:3264
	v_fmamk_f32 v1, v67, 0x3c000000, v216
	v_rsq_f32_e32 v1, v1
	v_addc_co_u32_e32 v33, vcc, 0, v3, vcc
	v_mul_f32_e32 v15, v85, v1
	v_mul_f32_e32 v15, v15, v74
	v_bfe_u32 v16, v15, 16, 1
	v_add3_u32 v15, v15, v16, s60
	global_store_short_d16_hi v[32:33], v15, off
	v_mul_f32_e32 v15, v60, v1
	v_mul_f32_e32 v15, v15, v75
	v_bfe_u32 v16, v15, 16, 1
	v_add3_u32 v15, v15, v16, s60
	global_store_short_d16_hi v[32:33], v15, off offset:64
	v_mul_f32_e32 v15, v45, v1
	v_mul_f32_e32 v15, v15, v76
	v_bfe_u32 v16, v15, 16, 1
	v_mul_f32_e32 v1, v30, v1
	v_add3_u32 v15, v15, v16, s60
	v_mul_f32_e32 v1, v1, v77
	global_store_short_d16_hi v[32:33], v15, off offset:128
	v_bfe_u32 v15, v1, 16, 1
	v_add3_u32 v1, v1, v15, s60
	global_store_short_d16_hi v[32:33], v1, off offset:192
	v_fmamk_f32 v1, v68, 0x3c000000, v216
	v_rsq_f32_e32 v1, v1
	s_nop 0
	v_mul_f32_e32 v15, v84, v1
	v_mul_f32_e32 v15, v15, v74
	v_bfe_u32 v16, v15, 16, 1
	v_add3_u32 v15, v15, v16, s60
	global_store_short_d16_hi v[32:33], v15, off offset:1024
	v_mul_f32_e32 v15, v58, v1
	v_mul_f32_e32 v15, v15, v75
	v_bfe_u32 v16, v15, 16, 1
	v_add3_u32 v15, v15, v16, s60
	global_store_short_d16_hi v[32:33], v15, off offset:1088
	v_mul_f32_e32 v15, v43, v1
	v_mul_f32_e32 v15, v15, v76
	v_bfe_u32 v16, v15, 16, 1
	v_mul_f32_e32 v1, v28, v1
	v_add3_u32 v15, v15, v16, s60
	v_mul_f32_e32 v1, v1, v77
	global_store_short_d16_hi v[32:33], v15, off offset:1152
	v_bfe_u32 v15, v1, 16, 1
	v_add3_u32 v1, v1, v15, s60
	global_store_short_d16_hi v[32:33], v1, off offset:1216
	v_fmamk_f32 v1, v70, 0x3c000000, v216
	v_rsq_f32_e32 v1, v1
	v_add_co_u32_e32 v28, vcc, s2, v2
	s_movk_i32 s2, 0x6000
	v_mul_f32_e32 v15, v83, v1
	v_mul_f32_e32 v15, v15, v74
	v_bfe_u32 v16, v15, 16, 1
	v_add3_u32 v15, v15, v16, s60
	global_store_short_d16_hi v[32:33], v15, off offset:2048
	v_mul_f32_e32 v15, v61, v1
	v_mul_f32_e32 v15, v15, v75
	v_bfe_u32 v16, v15, 16, 1
	v_add3_u32 v15, v15, v16, s60
	global_store_short_d16_hi v[32:33], v15, off offset:2112
	v_mul_f32_e32 v15, v44, v1
	v_mul_f32_e32 v15, v15, v76
	v_bfe_u32 v16, v15, 16, 1
	v_mul_f32_e32 v1, v29, v1
	v_add3_u32 v15, v15, v16, s60
	v_mul_f32_e32 v1, v1, v77
	global_store_short_d16_hi v[32:33], v15, off offset:2176
	v_bfe_u32 v15, v1, 16, 1
	v_add3_u32 v1, v1, v15, s60
	global_store_short_d16_hi v[32:33], v1, off offset:2240
	v_fmamk_f32 v1, v71, 0x3c000000, v216
	v_rsq_f32_e32 v1, v1
	v_addc_co_u32_e32 v29, vcc, 0, v3, vcc
	v_add_co_u32_e32 v2, vcc, s2, v2
	v_mul_f32_e32 v15, v82, v1
	v_mul_f32_e32 v15, v15, v74
	v_bfe_u32 v16, v15, 16, 1
	v_add3_u32 v15, v15, v16, s60
	global_store_short_d16_hi v[32:33], v15, off offset:3072
	v_mul_f32_e32 v15, v59, v1
	v_mul_f32_e32 v15, v15, v75
	v_bfe_u32 v16, v15, 16, 1
	v_add3_u32 v15, v15, v16, s60
	global_store_short_d16_hi v[32:33], v15, off offset:3136
	v_mul_f32_e32 v15, v42, v1
	v_mul_f32_e32 v15, v15, v76
	v_bfe_u32 v16, v15, 16, 1
	v_mul_f32_e32 v1, v27, v1
	v_add3_u32 v15, v15, v16, s60
	v_mul_f32_e32 v1, v1, v77
	global_store_short_d16_hi v[32:33], v15, off offset:3200
	v_bfe_u32 v15, v1, 16, 1
	v_add3_u32 v1, v1, v15, s60
	global_store_short_d16_hi v[32:33], v1, off offset:3264
	v_fmamk_f32 v1, v73, 0x3c000000, v216
	v_rsq_f32_e32 v1, v1
	v_addc_co_u32_e32 v3, vcc, 0, v3, vcc
	v_mul_f32_e32 v15, v57, v1
	v_mul_f32_e32 v15, v15, v74
	v_bfe_u32 v16, v15, 16, 1
	v_add3_u32 v15, v15, v16, s60
	global_store_short_d16_hi v[28:29], v15, off
	v_mul_f32_e32 v15, v41, v1
	v_mul_f32_e32 v15, v15, v75
	v_bfe_u32 v16, v15, 16, 1
	v_add3_u32 v15, v15, v16, s60
	global_store_short_d16_hi v[28:29], v15, off offset:64
	v_mul_f32_e32 v15, v25, v1
	v_mul_f32_e32 v15, v15, v76
	v_bfe_u32 v16, v15, 16, 1
	v_mul_f32_e32 v1, v26, v1
	v_add3_u32 v15, v15, v16, s60
	v_mul_f32_e32 v1, v1, v77
	global_store_short_d16_hi v[28:29], v15, off offset:128
	v_bfe_u32 v15, v1, 16, 1
	v_add3_u32 v1, v1, v15, s60
	global_store_short_d16_hi v[28:29], v1, off offset:192
	v_fmamk_f32 v1, v72, 0x3c000000, v216
	v_rsq_f32_e32 v1, v1
	s_nop 0
	v_mul_f32_e32 v15, v56, v1
	v_mul_f32_e32 v15, v15, v74
	v_bfe_u32 v16, v15, 16, 1
	v_add3_u32 v15, v15, v16, s60
	global_store_short_d16_hi v[28:29], v15, off offset:1024
	v_mul_f32_e32 v15, v40, v1
	v_mul_f32_e32 v15, v15, v75
	v_bfe_u32 v16, v15, 16, 1
	v_add3_u32 v15, v15, v16, s60
	global_store_short_d16_hi v[28:29], v15, off offset:1088
	v_mul_f32_e32 v15, v24, v1
; __device__ __forceinline__ unsigned f2bf(float f) { unsigned u = __builtin_bit_cast(unsigned, f); return (u + 0x7fffu + ((u >> 16) & 1u)) >> 16; }
; __device__ __forceinline__ float fast_rsq(float x) { return __builtin_amdgcn_rsqf(x); }
; __device__ __forceinline__ int crow(int r, int hi) { return (r & 3) + 8 * (r >> 2) + 4 * hi; }
; __device__ __forceinline__ void diff_unit(const Params& P, int l, int b, int h, int qb, float lam, float lam_init, LAS unsigned char* lds, bool dry = false) {
;     ...
;         for (int r = 0; r < 16; ++r) { const int q = crow(r, hi); const float rstd = fast_rsq(ssq[r] * (1.0f / 128.0f) + EPS);
; #pragma unroll
;             for (int d = 0; d < 4; ++d) if (!dry || o[d][r] == 1.2345e30f) Ow[(size_t)q * QP + 32 * d + r32] = (bf16_t)f2bf(o[d][r] * rstd * gsub[d]); }
	v_mul_f32_e32 v1, v10, v1
	v_mul_f32_e32 v1, v1, v77
	v_bfe_u32 v10, v1, 16, 1
	v_add3_u32 v1, v1, v10, s60
	global_store_short_d16_hi v[28:29], v1, off offset:1216
	v_fmamk_f32 v1, v69, 0x3c000000, v216
	v_rsq_f32_e32 v1, v1
	v_mul_f32_e32 v15, v15, v76
	v_bfe_u32 v16, v15, 16, 1
	v_add3_u32 v15, v15, v16, s60
	v_mul_f32_e32 v10, v55, v1
	v_mul_f32_e32 v10, v10, v74
	global_store_short_d16_hi v[28:29], v15, off offset:1152
	v_bfe_u32 v15, v10, 16, 1
	v_add3_u32 v10, v10, v15, s60
	global_store_short_d16_hi v[28:29], v10, off offset:2048
	v_mul_f32_e32 v10, v39, v1
	v_mul_f32_e32 v10, v10, v75
	v_bfe_u32 v15, v10, 16, 1
	v_add3_u32 v10, v10, v15, s60
	global_store_short_d16_hi v[28:29], v10, off offset:2112
	v_mul_f32_e32 v10, v23, v1
	v_mul_f32_e32 v1, v9, v1
	v_mul_f32_e32 v1, v1, v77
	v_bfe_u32 v9, v1, 16, 1
	v_add3_u32 v1, v1, v9, s60
	global_store_short_d16_hi v[28:29], v1, off offset:2240
	v_fmamk_f32 v1, v17, 0x3c000000, v216
	v_rsq_f32_e32 v1, v1
	v_mul_f32_e32 v10, v10, v76
	v_bfe_u32 v15, v10, 16, 1
	v_add3_u32 v10, v10, v15, s60
	v_mul_f32_e32 v9, v54, v1
	v_mul_f32_e32 v9, v9, v74
	global_store_short_d16_hi v[28:29], v10, off offset:2176
	v_bfe_u32 v10, v9, 16, 1
	v_add3_u32 v9, v9, v10, s60
	global_store_short_d16_hi v[28:29], v9, off offset:3072
	v_mul_f32_e32 v9, v38, v1
	v_mul_f32_e32 v9, v9, v75
	v_bfe_u32 v10, v9, 16, 1
	v_add3_u32 v9, v9, v10, s60
	global_store_short_d16_hi v[28:29], v9, off offset:3136
	v_mul_f32_e32 v9, v22, v1
	v_mul_f32_e32 v1, v8, v1
	v_mul_f32_e32 v1, v1, v77
	v_bfe_u32 v8, v1, 16, 1
	v_add3_u32 v1, v1, v8, s60
	global_store_short_d16_hi v[28:29], v1, off offset:3264
	v_fmamk_f32 v1, v14, 0x3c000000, v216
	v_rsq_f32_e32 v1, v1
	v_mul_f32_e32 v9, v9, v76
	v_bfe_u32 v10, v9, 16, 1
	v_add3_u32 v9, v9, v10, s60
	v_mul_f32_e32 v8, v53, v1
	v_mul_f32_e32 v8, v8, v74
	global_store_short_d16_hi v[28:29], v9, off offset:3200
	v_bfe_u32 v9, v8, 16, 1
	v_add3_u32 v8, v8, v9, s60
	global_store_short_d16_hi v[2:3], v8, off
	v_mul_f32_e32 v8, v36, v1
	v_mul_f32_e32 v8, v8, v75
	v_bfe_u32 v9, v8, 16, 1
	v_add3_u32 v8, v8, v9, s60
	global_store_short_d16_hi v[2:3], v8, off offset:64
	v_mul_f32_e32 v8, v21, v1
	v_mul_f32_e32 v1, v7, v1
	v_mul_f32_e32 v1, v1, v77
	v_bfe_u32 v7, v1, 16, 1
	v_add3_u32 v1, v1, v7, s60
	global_store_short_d16_hi v[2:3], v1, off offset:192
	v_fmamk_f32 v1, v13, 0x3c000000, v216
	v_rsq_f32_e32 v1, v1
	v_mul_f32_e32 v8, v8, v76
	v_bfe_u32 v9, v8, 16, 1
	v_add3_u32 v8, v8, v9, s60
	v_mul_f32_e32 v7, v52, v1
	v_mul_f32_e32 v7, v7, v74
	global_store_short_d16_hi v[2:3], v8, off offset:128
	v_bfe_u32 v8, v7, 16, 1
	v_add3_u32 v7, v7, v8, s60
	global_store_short_d16_hi v[2:3], v7, off offset:1024
	v_mul_f32_e32 v7, v34, v1
	v_mul_f32_e32 v7, v7, v75
	v_bfe_u32 v8, v7, 16, 1
	v_add3_u32 v7, v7, v8, s60
	global_store_short_d16_hi v[2:3], v7, off offset:1088
	v_mul_f32_e32 v7, v19, v1
	v_mul_f32_e32 v1, v6, v1
	v_mul_f32_e32 v1, v1, v77
	v_bfe_u32 v6, v1, 16, 1
	v_add3_u32 v1, v1, v6, s60
	global_store_short_d16_hi v[2:3], v1, off offset:1216
	v_fmamk_f32 v1, v12, 0x3c000000, v216
	v_rsq_f32_e32 v1, v1
	v_mul_f32_e32 v7, v7, v76
	v_bfe_u32 v8, v7, 16, 1
	v_add3_u32 v7, v7, v8, s60
	v_mul_f32_e32 v6, v51, v1
	v_mul_f32_e32 v6, v6, v74
	global_store_short_d16_hi v[2:3], v7, off offset:1152
	v_bfe_u32 v7, v6, 16, 1
	v_add3_u32 v6, v6, v7, s60
	global_store_short_d16_hi v[2:3], v6, off offset:2048
	v_mul_f32_e32 v6, v37, v1
	v_mul_f32_e32 v6, v6, v75
	v_bfe_u32 v7, v6, 16, 1
	v_add3_u32 v6, v6, v7, s60
	global_store_short_d16_hi v[2:3], v6, off offset:2112
	v_mul_f32_e32 v6, v20, v1
	v_mul_f32_e32 v1, v5, v1
	v_mul_f32_e32 v1, v1, v77
	v_bfe_u32 v5, v1, 16, 1
	v_add3_u32 v1, v1, v5, s60
	global_store_short_d16_hi v[2:3], v1, off offset:2240
	v_fmamk_f32 v1, v11, 0x3c000000, v216
	v_rsq_f32_e32 v1, v1
	v_mul_f32_e32 v6, v6, v76
	v_bfe_u32 v7, v6, 16, 1
	v_add3_u32 v6, v6, v7, s60
	v_mul_f32_e32 v5, v50, v1
	v_mul_f32_e32 v5, v74, v5
	global_store_short_d16_hi v[2:3], v6, off offset:2176
	v_bfe_u32 v6, v5, 16, 1
	v_add3_u32 v5, v5, v6, s60
	global_store_short_d16_hi v[2:3], v5, off offset:3072
	v_mul_f32_e32 v5, v35, v1
	v_mul_f32_e32 v5, v75, v5
	v_bfe_u32 v6, v5, 16, 1
	v_add3_u32 v5, v5, v6, s60
	global_store_short_d16_hi v[2:3], v5, off offset:3136
	v_mul_f32_e32 v5, v18, v1
	v_mul_f32_e32 v1, v4, v1
	v_mul_f32_e32 v5, v76, v5
	v_mul_f32_e32 v1, v77, v1
	v_bfe_u32 v6, v5, 16, 1
	v_bfe_u32 v4, v1, 16, 1
	v_add3_u32 v5, v5, v6, s60
	v_add3_u32 v1, v1, v4, s60
	global_store_short_d16_hi v[2:3], v5, off offset:3200
	global_store_short_d16_hi v[2:3], v1, off offset:3264
	s_branch .LBB0_389

; __device__ __forceinline__ unsigned f2bf(float f) { unsigned u = __builtin_bit_cast(unsigned, f); return (u + 0x7fffu + ((u >> 16) & 1u)) >> 16; }
; __device__ __forceinline__ float fast_rcp(float x) { return __builtin_amdgcn_rcpf(x); }
; __device__ __forceinline__ int crow(int r, int hi) { return (r & 3) + 8 * (r >> 2) + 4 * hi; }
; __device__ __forceinline__ float half_sum(float v) { auto rr = __builtin_amdgcn_permlane32_swap(__float_as_uint(v), __float_as_uint(v), false, false); return __uint_as_float(rr[0]) + __uint_as_float(rr[1]); }
; __device__ __forceinline__ void fox_unit(const Params& P, int b, int h, int qb, LAS unsigned char* lds, bool dry = false) {
;     ...
;     const float lt = half_sum(lrun);
;     if (hi == 0) wsf[r32] = fast_rcp(lt);
;     asm volatile("s_waitcnt lgkmcnt(0)" ::: "memory");
;     bf16_t* Ow = proj + O_FQ + (rowb + q0 + wid * 32) * QP + h * 64;
; #pragma unroll
;     for (int r = 0; r < 16; ++r) { const int q = crow(r, hi); const float il = wsf[q];
; #pragma unroll
;         for (int d = 0; d < 2; ++d) if (!dry || o[d][r] == 1.2345e30f) Ow[(size_t)q * QP + 32 * d + r32] = (bf16_t)f2bf(o[d][r] * il); }
;     __syncthreads();
.LBB0_571:
	s_or_b64 exec, exec, s[4:5]
	s_lshl_b64 s[4:5], s[90:91], 10
	s_add_u32 s4, s84, s4
	s_addc_u32 s5, s85, s5
	s_add_u32 s4, s4, s2
	s_waitcnt lgkmcnt(0)
	s_addc_u32 s5, s5, 0
	v_lshlrev_b32_e32 v34, 1, v162
	v_mov_b32_e32 v35, v0
	v_lshl_add_u32 v46, v147, 2, s3
	v_lshl_add_u64 v[42:43], s[4:5], 0, v[34:35]
	ds_read_b128 v[34:37], v46 offset:43520
	ds_read_b128 v[38:41], v46 offset:43552
	v_lshlrev_b32_e32 v44, 12, v1
	v_mov_b32_e32 v45, v0
	v_lshl_add_u64 v[44:45], v[42:43], 0, v[44:45]
	s_waitcnt lgkmcnt(0)
	v_mul_f32_e32 v1, v2, v34
	v_bfe_u32 v2, v1, 16, 1
	v_add3_u32 v1, v1, v2, s60
	global_store_short_d16_hi v[44:45], v1, off
	v_mul_f32_e32 v1, v18, v34
	v_bfe_u32 v2, v1, 16, 1
	v_add3_u32 v1, v1, v2, s60
	global_store_short_d16_hi v[44:45], v1, off offset:64
	v_lshlrev_b32_e32 v1, 10, v147
	v_mul_f32_e32 v2, v3, v35
	v_or_b32_e32 v44, 0x400, v1
	v_mov_b32_e32 v45, v0
	v_bfe_u32 v3, v2, 16, 1
	v_lshl_add_u64 v[44:45], v[42:43], 0, v[44:45]
	v_add3_u32 v2, v2, v3, s60
	global_store_short_d16_hi v[44:45], v2, off
	v_mul_f32_e32 v2, v19, v35
	v_bfe_u32 v3, v2, 16, 1
	v_add3_u32 v2, v2, v3, s60
	v_mul_f32_e32 v4, v4, v36
	global_store_short_d16_hi v[44:45], v2, off offset:64
	v_or_b32_e32 v2, 0x800, v1
	v_mov_b32_e32 v3, v0
	v_bfe_u32 v18, v4, 16, 1
	v_lshl_add_u64 v[2:3], v[42:43], 0, v[2:3]
	v_add3_u32 v4, v4, v18, s60
	global_store_short_d16_hi v[2:3], v4, off
	v_mul_f32_e32 v4, v20, v36
	v_bfe_u32 v18, v4, 16, 1
	v_add3_u32 v4, v4, v18, s60
	global_store_short_d16_hi v[2:3], v4, off offset:64
	v_mul_f32_e32 v4, v5, v37
	v_or_b32_e32 v2, 0xc00, v1
	v_mov_b32_e32 v3, v0
	v_bfe_u32 v5, v4, 16, 1
	v_lshl_add_u64 v[2:3], v[42:43], 0, v[2:3]
	v_add3_u32 v4, v4, v5, s60
	global_store_short_d16_hi v[2:3], v4, off
	v_mul_f32_e32 v4, v21, v37
	v_bfe_u32 v5, v4, 16, 1
	v_add3_u32 v4, v4, v5, s60
	global_store_short_d16_hi v[2:3], v4, off offset:64
	v_mul_f32_e32 v4, v6, v38
	v_or_b32_e32 v2, 0x2000, v1
	v_mov_b32_e32 v3, v0
	v_bfe_u32 v5, v4, 16, 1
	v_lshl_add_u64 v[2:3], v[42:43], 0, v[2:3]
	v_add3_u32 v4, v4, v5, s60
	global_store_short_d16_hi v[2:3], v4, off
	v_mul_f32_e32 v4, v22, v38
	v_bfe_u32 v5, v4, 16, 1
	v_add3_u32 v4, v4, v5, s60
	global_store_short_d16_hi v[2:3], v4, off offset:64
	v_mul_f32_e32 v4, v7, v39
	v_or_b32_e32 v2, 0x2400, v1
	v_mov_b32_e32 v3, v0
	v_bfe_u32 v5, v4, 16, 1
	v_lshl_add_u64 v[2:3], v[42:43], 0, v[2:3]
	v_add3_u32 v4, v4, v5, s60
	global_store_short_d16_hi v[2:3], v4, off
	v_mul_f32_e32 v4, v23, v39
	v_bfe_u32 v5, v4, 16, 1
	v_add3_u32 v4, v4, v5, s60
	global_store_short_d16_hi v[2:3], v4, off offset:64
	v_mul_f32_e32 v4, v8, v40
	v_or_b32_e32 v2, 0x2800, v1
	v_mov_b32_e32 v3, v0
	v_bfe_u32 v5, v4, 16, 1
	v_lshl_add_u64 v[2:3], v[42:43], 0, v[2:3]
	v_add3_u32 v4, v4, v5, s60
	global_store_short_d16_hi v[2:3], v4, off
	v_mul_f32_e32 v4, v24, v40
	v_bfe_u32 v5, v4, 16, 1
	v_add3_u32 v4, v4, v5, s60
	global_store_short_d16_hi v[2:3], v4, off offset:64
	v_mul_f32_e32 v4, v9, v41
	v_or_b32_e32 v2, 0x2c00, v1
	v_mov_b32_e32 v3, v0
	v_bfe_u32 v5, v4, 16, 1
	v_lshl_add_u64 v[2:3], v[42:43], 0, v[2:3]
	v_add3_u32 v4, v4, v5, s60
	global_store_short_d16_hi v[2:3], v4, off
	v_mul_f32_e32 v4, v25, v41
	v_bfe_u32 v5, v4, 16, 1
	v_add3_u32 v4, v4, v5, s60
	global_store_short_d16_hi v[2:3], v4, off offset:64
	ds_read_b128 v[2:5], v46 offset:43584
	ds_read_b128 v[6:9], v46 offset:43616
	v_or_b32_e32 v18, 0x4000, v1
	v_mov_b32_e32 v19, v0
	v_lshl_add_u64 v[18:19], v[42:43], 0, v[18:19]
	s_waitcnt lgkmcnt(0)
	v_mul_f32_e32 v10, v10, v2
	v_bfe_u32 v20, v10, 16, 1
	v_add3_u32 v10, v10, v20, s60
	v_mul_f32_e32 v2, v26, v2
	global_store_short_d16_hi v[18:19], v10, off
	v_bfe_u32 v10, v2, 16, 1
	v_add3_u32 v2, v2, v10, s60
	global_store_short_d16_hi v[18:19], v2, off offset:64
	v_mul_f32_e32 v2, v11, v3
	v_or_b32_e32 v18, 0x4400, v1
	v_mov_b32_e32 v19, v0
	v_bfe_u32 v10, v2, 16, 1
	v_lshl_add_u64 v[18:19], v[42:43], 0, v[18:19]
	v_add3_u32 v2, v2, v10, s60
	global_store_short_d16_hi v[18:19], v2, off
	v_mul_f32_e32 v2, v27, v3
	v_bfe_u32 v3, v2, 16, 1
	v_add3_u32 v2, v2, v3, s60
	v_mul_f32_e32 v10, v12, v4
	global_store_short_d16_hi v[18:19], v2, off offset:64
	v_or_b32_e32 v2, 0x4800, v1
	v_mov_b32_e32 v3, v0
	v_bfe_u32 v11, v10, 16, 1
	v_lshl_add_u64 v[2:3], v[42:43], 0, v[2:3]
	v_add3_u32 v10, v10, v11, s60
	v_mul_f32_e32 v4, v28, v4
	global_store_short_d16_hi v[2:3], v10, off
	v_bfe_u32 v10, v4, 16, 1
	v_add3_u32 v4, v4, v10, s60
	global_store_short_d16_hi v[2:3], v4, off offset:64
	v_mul_f32_e32 v4, v13, v5
	v_or_b32_e32 v2, 0x4c00, v1
	v_mov_b32_e32 v3, v0
	v_bfe_u32 v10, v4, 16, 1
	v_lshl_add_u64 v[2:3], v[42:43], 0, v[2:3]
	v_add3_u32 v4, v4, v10, s60
	global_store_short_d16_hi v[2:3], v4, off
	v_mul_f32_e32 v4, v29, v5
	v_bfe_u32 v5, v4, 16, 1
	v_add3_u32 v4, v4, v5, s60
	global_store_short_d16_hi v[2:3], v4, off offset:64
	v_mul_f32_e32 v4, v14, v6
	v_or_b32_e32 v2, 0x6000, v1
	v_mov_b32_e32 v3, v0
	v_bfe_u32 v5, v4, 16, 1
	v_lshl_add_u64 v[2:3], v[42:43], 0, v[2:3]
	v_add3_u32 v4, v4, v5, s60
	global_store_short_d16_hi v[2:3], v4, off
	v_mul_f32_e32 v4, v30, v6
	v_bfe_u32 v5, v4, 16, 1
	v_add3_u32 v4, v4, v5, s60
	global_store_short_d16_hi v[2:3], v4, off offset:64
	v_mul_f32_e32 v4, v15, v7
	v_or_b32_e32 v2, 0x6400, v1
	v_mov_b32_e32 v3, v0
	v_bfe_u32 v5, v4, 16, 1
	v_lshl_add_u64 v[2:3], v[42:43], 0, v[2:3]
	v_add3_u32 v4, v4, v5, s60
	global_store_short_d16_hi v[2:3], v4, off
	v_mul_f32_e32 v4, v31, v7
	v_bfe_u32 v5, v4, 16, 1
	v_add3_u32 v4, v4, v5, s60
	global_store_short_d16_hi v[2:3], v4, off offset:64
	v_mul_f32_e32 v4, v16, v8
	v_or_b32_e32 v2, 0x6800, v1
	v_mov_b32_e32 v3, v0
	v_bfe_u32 v5, v4, 16, 1
	v_lshl_add_u64 v[2:3], v[42:43], 0, v[2:3]
	v_add3_u32 v4, v4, v5, s60
	global_store_short_d16_hi v[2:3], v4, off
	v_mul_f32_e32 v4, v32, v8
	v_bfe_u32 v5, v4, 16, 1
	v_add3_u32 v4, v4, v5, s60
	global_store_short_d16_hi v[2:3], v4, off offset:64
	v_or_b32_e32 v2, 0x6c00, v1
	v_mul_f32_e32 v1, v17, v9
	v_mov_b32_e32 v3, v0
	v_bfe_u32 v4, v1, 16, 1
	v_lshl_add_u64 v[2:3], v[42:43], 0, v[2:3]
	v_add3_u32 v1, v1, v4, s60
	global_store_short_d16_hi v[2:3], v1, off
	v_mul_f32_e32 v1, v33, v9
	v_bfe_u32 v4, v1, 16, 1
	s_add_i32 s70, s70, s82
	s_add_i32 s71, s71, s82
	v_add3_u32 v1, v1, v4, s60
	s_cmpk_gt_i32 s70, 0x1ff
	global_store_short_d16_hi v[2:3], v1, off offset:64
	s_waitcnt lgkmcnt(0)
	s_barrier
	s_cbranch_scc1 .LBB0_776
; #define LAS __attribute__((address_space(3)))
; __device__ __forceinline__ int launder_tid() { int t = threadIdx.x; asm volatile("" : "+v"(t)); return t; }
; template <class T> __device__ __forceinline__ T* launder_ptr(T* p) { asm volatile("" : "+s"(p)); return p; }
; #define FOX_GLOADK(t) do { kreg = *(const u32x4*)(sbase + O_FK + (size_t)(64 * (t)) * QP); if (tid < 64) creg = cbuf[(rowb + 64 * (t) + tid) * 8 + h]; } while (0)
; #define FOX_GLOADV(t) do { vreg = *(const u32x4*)(sbase + O_FV + (size_t)(64 * (t)) * QP); } while (0)
; #define FOX_LSTOREK(buf) do { LAS unsigned char* bb_ = lds + (buf) * BUFB; *(LAS u32x4*)(bb_ + KOFF + srow * 144 + sch * 16) = kreg; if (tid < 64) *(LAS float*)(bb_ + COFF + tid * 4) = creg; } while (0)
; __device__ __forceinline__ void fox_unit(const Params& P, int b, int h, int qb, LAS unsigned char* lds, bool dry = false) {
;     unsigned char* ws_ = launder_ptr(P.ws);
;     const int tid = launder_tid(), lane = tid & 63, wid = __builtin_amdgcn_readfirstlane(tid >> 6), r32 = lane & 31, hi = lane >> 5;
;     bf16_t* proj = (bf16_t*)(ws_ + WS_P);
;     const float* cbuf = (const float*)(ws_ + WS_C);
;     const size_t rowb = (size_t)b * SEQ; const int q0 = qb * 256;
;     constexpr int BUFB = 21760, KOFF = 0, VOFF = 9216, COFF = 21504, FVS = 192;
;     LAS float* wsf = (LAS float*)(lds + 2 * BUFB) + wid * 64;
;     bf16x8 qf[4];
;     { const bf16_t* Qw = proj + O_FQ + (rowb + q0 + wid * 32 + r32) * QP + h * 64;
; #pragma unroll
;       for (int d0 = 0; d0 < 4; ++d0) qf[d0] = *(const bf16x8*)(Qw + d0 * 16 + hi * 8); }
;     const float cq = cbuf[(rowb + q0 + wid * 32 + r32) * 8 + h];
;     f32x16 o[2]; o[0] = f32x16{}; o[1] = f32x16{};
;     float mref = 0.f, lrun = 0.f;
;     const int NT = 4 * (qb + 1);
;     const int srow = tid >> 3, sch = tid & 7;
;     u32x4 kreg, vreg; float creg = 0.f;
;     const bf16_t* sbase = proj + (rowb + srow) * QP + h * 64 + sch * 8;
;     ...
;     FOX_GLOADK(0); FOX_GLOADV(0); FOX_LSTOREK(0); FOX_LSTOREV(0);
;     FOX_GLOADK(1); FOX_LSTOREK(1);
.LBB0_572:
	s_ashr_i32 s4, s70, 5
	s_and_b32 s72, s70, 3
	s_ashr_i32 s5, s4, 31
	s_bfe_u32 s53, s70, 0x30002
	s_mov_b64 s[84:85], s[94:95]
	v_mov_b32_e32 v158, v180
	s_lshl_b64 s[50:51], s[4:5], 11
	s_lshl_b32 s75, s72, 8
	s_add_u32 s90, s84, 0x14e00000
	v_readfirstlane_b32 s52, v158
	s_addc_u32 s91, s85, 0
	s_ashr_i32 s78, s52, 1
	s_andn2_b32 s78, s78, 31
	s_or_b32 s2, s50, s75
	s_ashr_i32 s3, s78, 31
	s_add_u32 s2, s2, s78
	s_waitcnt vmcnt(0)
	v_and_b32_e32 v165, 31, v158
	s_addc_u32 s3, s51, s3
	s_waitcnt lgkmcnt(1)
	v_or_b32_e32 v2, s2, v165
	v_mov_b32_e32 v3, s3
	s_waitcnt lgkmcnt(0)
	v_lshlrev_b64 v[4:5], 10, v[2:3]
	v_bfe_u32 v164, v158, 5, 1
	v_lshl_add_u64 v[4:5], s[90:91], 0, v[4:5]
	s_lshl_b32 s6, s53, 7
	s_mov_b32 s7, s97
	v_lshl_add_u64 v[4:5], v[4:5], 0, s[6:7]
	v_lshlrev_b32_e32 v156, 4, v164
	v_mov_b32_e32 v157, v0
	v_ashrrev_i32_e32 v162, 3, v158
	v_lshl_add_u64 v[4:5], v[4:5], 0, v[156:157]
	v_ashrrev_i32_e32 v163, 31, v162
	global_load_dwordx4 v[112:115], v[4:5], off
	global_load_dwordx4 v[116:119], v[4:5], off offset:32
	global_load_dwordx4 v[120:123], v[4:5], off offset:64
	global_load_dwordx4 v[124:127], v[4:5], off offset:96
	v_lshl_add_u64 v[4:5], s[50:51], 0, v[162:163]
	v_lshlrev_b64 v[4:5], 10, v[4:5]
	v_and_b32_e32 v1, 7, v158
	v_lshl_add_u64 v[4:5], s[84:85], 0, v[4:5]
	s_add_u32 s8, s84, 0x2c00000
	v_lshl_add_u64 v[4:5], v[4:5], 0, s[6:7]
	v_lshlrev_b32_e32 v160, 4, v1
	v_mov_b32_e32 v161, v0
	s_addc_u32 s9, s85, 0
	v_lshlrev_b64 v[2:3], 5, v[2:3]
	v_lshl_add_u64 v[6:7], v[4:5], 0, v[160:161]
	v_lshl_add_u64 v[2:3], s[8:9], 0, v[2:3]
	s_lshl_b32 s96, s53, 2
	v_add_co_u32_e32 v4, vcc, 0x16e00000, v6
	v_lshl_add_u64 v[2:3], v[2:3], 0, s[96:97]
	s_nop 0
	v_addc_co_u32_e32 v5, vcc, 0, v7, vcc
	global_load_dword v157, v[2:3], off
	s_nop 0
	global_load_dwordx4 v[2:5], v[4:5], off
	v_cmp_gt_i32_e64 s[6:7], 64, v158
	v_mov_b32_e32 v166, 0
	v_ashrrev_i32_e32 v159, 31, v158
	s_and_saveexec_b64 s[10:11], s[6:7]
	s_cbranch_execz .LBB0_574
	v_lshl_add_u64 v[8:9], s[50:51], 0, v[158:159]
	v_lshlrev_b64 v[8:9], 5, v[8:9]
	v_lshl_add_u64 v[8:9], s[8:9], 0, v[8:9]
	v_lshl_add_u64 v[8:9], v[8:9], 0, s[96:97]
	global_load_dword v166, v[8:9], off
.LBB0_574:
	s_or_b64 exec, exec, s[10:11]
	s_mov_b64 s[10:11], 0x6e00000
	v_lshl_add_u64 v[10:11], v[6:7], 0, s[10:11]
	v_add_co_u32_e32 v6, vcc, 0x12000000, v10
	s_movk_i32 s10, 0x90
	s_nop 0
	v_addc_co_u32_e32 v7, vcc, 0, v11, vcc
	global_load_dwordx4 v[6:9], v[6:7], off
	v_mul_lo_u32 v170, v162, s10
	v_add_u32_e32 v12, 0, v170
	v_add_u32_e32 v171, v12, v160
	v_lshl_add_u32 v161, v158, 2, 0
	s_waitcnt vmcnt(0) lgkmcnt(0)
	ds_write_b128 v171, v[2:5]
	s_and_saveexec_b64 s[10:11], s[6:7]
	ds_write_b32 v161, v166 offset:21504
	s_or_b64 exec, exec, s[10:11]
	v_mad_u64_u32 v[12:13], s[10:11], v162, 48, v[12:13]
	v_add_u32_e32 v172, v12, v160
	v_add_co_u32_e32 v2, vcc, 0x10010000, v10
	ds_write_b128 v172, v[6:9] offset:9216
	s_nop 0
	v_addc_co_u32_e32 v3, vcc, 0, v11, vcc
	global_load_dwordx4 v[2:5], v[2:3], off
	s_and_saveexec_b64 s[10:11], s[6:7]
	s_cbranch_execz .LBB0_578
	v_lshl_add_u64 v[6:7], v[158:159], 0, s[50:51]
	v_lshlrev_b64 v[6:7], 5, v[6:7]
	v_lshl_add_u64 v[6:7], s[8:9], 0, v[6:7]
	v_lshl_add_u64 v[6:7], v[6:7], 0, s[96:97]
	global_load_dword v166, v[6:7], off offset:2048
; #define FOX_GLOADK(t) do { kreg = *(const u32x4*)(sbase + O_FK + (size_t)(64 * (t)) * QP); if (tid < 64) creg = cbuf[(rowb + 64 * (t) + tid) * 8 + h]; } while (0)
; #define FOX_GLOADV(t) do { vreg = *(const u32x4*)(sbase + O_FV + (size_t)(64 * (t)) * QP); } while (0)
; #define FOX_LSTOREK(buf) do { LAS unsigned char* bb_ = lds + (buf) * BUFB; *(LAS u32x4*)(bb_ + KOFF + srow * 144 + sch * 16) = kreg; if (tid < 64) *(LAS float*)(bb_ + COFF + tid * 4) = creg; } while (0)
; __device__ __forceinline__ void fox_unit(const Params& P, int b, int h, int qb, LAS unsigned char* lds, bool dry = false) {
;     ...
;     FOX_GLOADK(0); FOX_GLOADV(0); FOX_LSTOREK(0); FOX_LSTOREV(0);
;     FOX_GLOADK(1); FOX_LSTOREK(1);
;     __syncthreads();
;     f32x16 s0, s1, n0 = {}, n1 = {};
;     FOX_INIT(s0, s1, 0); attn_qk(s0, s1, lds + KOFF, 144, qf, r32, hi);
.LBB0_578:
	s_or_b64 exec, exec, s[10:11]
	s_movk_i32 s10, 0xffd0
	v_mad_u64_u32 v[6:7], s[10:11], v162, s10, v[12:13]
	v_add_u32_e32 v173, v6, v160
	s_waitcnt vmcnt(0) lgkmcnt(0)
	ds_write_b128 v173, v[2:5] offset:21760
	s_and_saveexec_b64 s[10:11], s[6:7]
	ds_write_b32 v161, v166 offset:43264
	s_or_b64 exec, exec, s[10:11]
	s_movk_i32 s10, 0x90
	v_add_u32_e32 v174, 0, v156
	v_mad_u32_u24 v1, v165, s10, 0
	s_waitcnt lgkmcnt(0)
	s_barrier
	ds_read_b128 v[2:5], v174 offset:21632
	ds_read_b128 v[6:9], v174 offset:21504
	ds_read_b128 v[12:15], v174 offset:21536
	ds_read_b128 v[16:19], v174 offset:21664
	ds_read_b128 v[20:23], v174 offset:21568
	ds_read_b128 v[24:27], v174 offset:21696
	ds_read_b128 v[28:31], v174 offset:21600
	ds_read_b128 v[32:35], v174 offset:21728
	v_add_u32_e32 v175, v1, v156
	s_waitcnt lgkmcnt(5)
	v_sub_f32_e32 v87, v157, v15
	v_sub_f32_e32 v86, v157, v14
	v_sub_f32_e32 v85, v157, v13
	v_sub_f32_e32 v84, v157, v12
	v_sub_f32_e32 v83, v157, v9
	v_sub_f32_e32 v82, v157, v8
	v_sub_f32_e32 v81, v157, v7
	v_sub_f32_e32 v80, v157, v6
	v_sub_f32_e32 v99, v157, v5
	v_sub_f32_e32 v98, v157, v4
	v_sub_f32_e32 v97, v157, v3
	v_sub_f32_e32 v96, v157, v2
	ds_read_b128 v[2:5], v175 offset:4608
	ds_read_b128 v[6:9], v175
	ds_read_b128 v[12:15], v175 offset:32
	s_waitcnt lgkmcnt(4)
	v_sub_f32_e32 v95, v157, v31
	v_sub_f32_e32 v94, v157, v30
	v_sub_f32_e32 v93, v157, v29
	v_sub_f32_e32 v92, v157, v28
	v_sub_f32_e32 v91, v157, v23
	v_sub_f32_e32 v90, v157, v22
	v_sub_f32_e32 v89, v157, v21
	v_sub_f32_e32 v88, v157, v20
	s_waitcnt lgkmcnt(3)
	v_sub_f32_e32 v111, v157, v35
	v_sub_f32_e32 v110, v157, v34
	s_waitcnt lgkmcnt(1)
	v_mfma_f32_32x32x16_bf16 v[80:95], v[6:9], v[112:115], v[80:95]
	v_sub_f32_e32 v109, v157, v33
	v_sub_f32_e32 v108, v157, v32
	v_sub_f32_e32 v107, v157, v27
	v_sub_f32_e32 v106, v157, v26
	v_sub_f32_e32 v105, v157, v25
	v_sub_f32_e32 v104, v157, v24
	v_sub_f32_e32 v103, v157, v19
	v_sub_f32_e32 v102, v157, v18
	v_sub_f32_e32 v101, v157, v17
	v_sub_f32_e32 v100, v157, v16
	s_waitcnt lgkmcnt(0)
	v_mfma_f32_32x32x16_bf16 v[80:95], v[12:15], v[116:119], v[80:95]
	v_mfma_f32_32x32x16_bf16 v[96:111], v[2:5], v[112:115], v[96:111]
	ds_read_b128 v[2:5], v175 offset:4640
	s_waitcnt lgkmcnt(0)
	v_mfma_f32_32x32x16_bf16 v[96:111], v[2:5], v[116:119], v[96:111]
	ds_read_b128 v[2:5], v175 offset:64
	ds_read_b128 v[6:9], v175 offset:4672
	s_waitcnt lgkmcnt(1)
	v_mfma_f32_32x32x16_bf16 v[80:95], v[2:5], v[120:123], v[80:95]
	s_waitcnt lgkmcnt(0)
	v_mfma_f32_32x32x16_bf16 v[96:111], v[6:9], v[120:123], v[96:111]
	ds_read_b128 v[2:5], v175 offset:96
	ds_read_b128 v[6:9], v175 offset:4704
	s_waitcnt lgkmcnt(1)
	v_mfma_f32_32x32x16_bf16 v[80:95], v[2:5], v[124:127], v[80:95]
	v_add_co_u32_e32 v2, vcc, 0x10020000, v10
	s_nop 1
	v_addc_co_u32_e32 v3, vcc, 0, v11, vcc
	global_load_dwordx4 v[128:131], v[2:3], off
	s_waitcnt lgkmcnt(0)
	v_mfma_f32_32x32x16_bf16 v[96:111], v[6:9], v[124:127], v[96:111]
	s_and_saveexec_b64 s[10:11], s[6:7]
	s_cbranch_execz .LBB0_582
	v_lshl_add_u64 v[2:3], v[158:159], 0, s[50:51]
	v_lshlrev_b64 v[2:3], 5, v[2:3]
	v_lshl_add_u64 v[2:3], s[8:9], 0, v[2:3]
	v_lshl_add_u64 v[2:3], v[2:3], 0, s[96:97]
	v_add_co_u32_e32 v2, vcc, 0x1000, v2
	s_nop 1
	v_addc_co_u32_e32 v3, vcc, 0, v3, vcc
	global_load_dword v166, v[2:3], off
.LBB0_582:
	s_or_b64 exec, exec, s[10:11]
	v_add_co_u32_e32 v2, vcc, 0x12010000, v10
	s_lshl_b32 s80, s72, 2
	s_nop 0
	v_addc_co_u32_e32 v3, vcc, 0, v11, vcc
	global_load_dwordx4 v[132:135], v[2:3], off
	s_ashr_i32 s81, s52, 7
	s_cmp_eq_u32 s72, 0
	s_cselect_b64 s[8:9], -1, 0
	s_cmp_lg_u32 s72, 0
	s_cselect_b64 s[42:43], -1, 0
	s_sub_i32 s10, 1, s80
	s_cmp_gt_i32 s10, s81
	s_cselect_b64 s[10:11], -1, 0
	s_and_b64 s[44:45], s[8:9], s[10:11]
	s_and_b64 vcc, exec, s[44:45]
	s_cbranch_vccnz .LBB0_584
	ds_read_b128 v[2:5], v174 offset:43392
	ds_read_b128 v[6:9], v174 offset:43264
	ds_read_b128 v[10:13], v174 offset:43296
	ds_read_b128 v[14:17], v174 offset:43424
	ds_read_b128 v[18:21], v174 offset:43328
	ds_read_b128 v[22:25], v174 offset:43456
	ds_read_b128 v[26:29], v174 offset:43360
	ds_read_b128 v[30:33], v174 offset:43488
	s_waitcnt lgkmcnt(0)
	v_sub_f32_e32 v71, v157, v13
	v_sub_f32_e32 v70, v157, v12
	v_sub_f32_e32 v69, v157, v11
	v_sub_f32_e32 v68, v157, v10
	v_sub_f32_e32 v67, v157, v9
	v_sub_f32_e32 v66, v157, v8
	v_sub_f32_e32 v65, v157, v7
	v_sub_f32_e32 v64, v157, v6
	v_sub_f32_e32 v51, v157, v5
	v_sub_f32_e32 v50, v157, v4
	v_sub_f32_e32 v49, v157, v3
	v_sub_f32_e32 v48, v157, v2
	ds_read_b128 v[2:5], v175 offset:26368
	ds_read_b128 v[6:9], v175 offset:21760
	ds_read_b128 v[10:13], v175 offset:21792
	v_sub_f32_e32 v63, v157, v33
	v_sub_f32_e32 v62, v157, v32
	v_sub_f32_e32 v61, v157, v31
	v_sub_f32_e32 v60, v157, v30
	v_sub_f32_e32 v59, v157, v25
	v_sub_f32_e32 v58, v157, v24
	v_sub_f32_e32 v57, v157, v23
	v_sub_f32_e32 v56, v157, v22
	v_sub_f32_e32 v55, v157, v17
	v_sub_f32_e32 v54, v157, v16
	v_sub_f32_e32 v53, v157, v15
	v_sub_f32_e32 v52, v157, v14
	v_sub_f32_e32 v79, v157, v29
	v_sub_f32_e32 v78, v157, v28
	v_sub_f32_e32 v77, v157, v27
	v_sub_f32_e32 v76, v157, v26
	v_sub_f32_e32 v75, v157, v21
	v_sub_f32_e32 v74, v157, v20
	v_sub_f32_e32 v73, v157, v19
	v_sub_f32_e32 v72, v157, v18
	s_waitcnt lgkmcnt(0)
	v_mfma_f32_32x32x16_bf16 v[48:63], v[2:5], v[112:115], v[48:63]
	ds_read_b128 v[2:5], v175 offset:26400
	v_mfma_f32_32x32x16_bf16 v[64:79], v[6:9], v[112:115], v[64:79]
	v_mfma_f32_32x32x16_bf16 v[64:79], v[10:13], v[116:119], v[64:79]
	s_waitcnt lgkmcnt(0)
	v_mfma_f32_32x32x16_bf16 v[48:63], v[2:5], v[116:119], v[48:63]
	ds_read_b128 v[2:5], v175 offset:21824
	ds_read_b128 v[6:9], v175 offset:26432
	s_waitcnt lgkmcnt(0)
	v_mfma_f32_32x32x16_bf16 v[64:79], v[2:5], v[120:123], v[64:79]
	v_mfma_f32_32x32x16_bf16 v[48:63], v[6:9], v[120:123], v[48:63]
	ds_read_b128 v[2:5], v175 offset:21856
	ds_read_b128 v[6:9], v175 offset:26464
	s_waitcnt lgkmcnt(0)
	v_mfma_f32_32x32x16_bf16 v[64:79], v[2:5], v[124:127], v[64:79]
	v_mfma_f32_32x32x16_bf16 v[48:63], v[6:9], v[124:127], v[48:63]
	s_branch .LBB0_585

; #define LAS __attribute__((address_space(3)))
; __device__ __forceinline__ float fast_exp2(float x) { return __builtin_amdgcn_exp2f(x); }
; __device__ __forceinline__ void fox_steady_step(f32x16& s0, f32x16& s1, f32x16& n0, f32x16& n1, const LAS unsigned char* kb, int coff, const LAS unsigned char* Vt, ...
;     const float rm = rmc;
;     if (__any(rm > 8.0f)) {
;         const float dl = fmaxf(rm, 0.f);
;         mref += dl;
; #pragma unroll
;         for (int r = 0; r < 16; ++r) { s0[r] -= dl; s1[r] -= dl; }
;         const float alpha = fast_exp2(-dl);
;         lrun *= alpha;
;         if (hi == 0) wsf[r32] = alpha;
;         asm volatile("s_waitcnt lgkmcnt(0)" ::: "memory");
; #pragma unroll
;         for (int jj = 0; jj < 4; ++jj) { const f32x4 al = *(const LAS f32x4*)(wsf + 8 * jj + 4 * hi);
; #pragma unroll
;             for (int d = 0; d < 2; ++d) { o[d][4 * jj + 0] *= al.x; o[d][4 * jj + 1] *= al.y; o[d][4 * jj + 2] *= al.z; o[d][4 * jj + 3] *= al.w; } }
;         asm volatile("s_waitcnt lgkmcnt(0)" ::: "memory");
;     }
;     bf16x8 kf[8]; f32x4 ck4[8]; bf16x8 vf[4][2];
; #pragma unroll
;     for (int d0 = 0; d0 < 4; ++d0) { kf[2 * d0] = *(const LAS bf16x8*)(kb + r32 * 144 + d0 * 32 + hi * 16); kf[2 * d0 + 1] = *(const LAS bf16x8*)(kb + (r32 + 32) * 144 + d0 * 32 + hi * 16); }
; #pragma unroll
;     for (int jj = 0; jj < 4; ++jj) { ck4[jj] = *(const LAS f32x4*)(kb + coff + (8 * jj + 4 * hi) * 4); ck4[4 + jj] = *(const LAS f32x4*)(kb + coff + (32 + 8 * jj + 4 * hi) * 4); }
;     { const int lane_ = hi * 32 + r32;
;       const LAS unsigned char* vb = Vt + (4 * hi + ((lane_ & 15) >> 2)) * 192 + (16 * ((lane_ >> 4) & 1) + 4 * (lane_ & 3)) * 2;
; #pragma unroll
;       for (int s = 0; s < 4; ++s)
; #pragma unroll
;           for (int d = 0; d < 2; ++d) {
;               const s16x4 lo_ = __builtin_bit_cast(s16x4, __builtin_amdgcn_ds_read_tr16_b64_v4i16((LAS s16x4*)(vb + (16 * s) * 192 + 64 * d)));
;               const s16x4 hh_ = __builtin_bit_cast(s16x4, __builtin_amdgcn_ds_read_tr16_b64_v4i16((LAS s16x4*)(vb + (16 * s + 8) * 192 + 64 * d)));
;               vf[s][d] = (bf16x8){lo_[0], lo_[1], lo_[2], lo_[3], hh_[0], hh_[1], hh_[2], hh_[3]}; } }
.LBB0_601:
	v_lshl_add_u64 v[152:153], s[84:85], 0, v[148:149]
	v_add_co_u32_e32 v2, vcc, 0x16e30000, v152
	v_lshl_add_u64 v[154:155], s[84:85], 0, v[150:151]
	s_nop 0
	v_addc_co_u32_e32 v3, vcc, 0, v153, vcc
	global_load_dwordx4 v[2:5], v[2:3], off
	s_and_saveexec_b64 s[12:13], s[6:7]
	s_cbranch_execz .LBB0_603
	v_add_co_u32_e32 v6, vcc, 0x2c01000, v154
	s_nop 1
	v_addc_co_u32_e32 v7, vcc, 0, v155, vcc
	global_load_dword v166, v[6:7], off offset:2048
.LBB0_603:
	s_or_b64 exec, exec, s[12:13]
	v_add_co_u32_e32 v6, vcc, 0x18e20000, v152
	s_nop 1
	v_addc_co_u32_e32 v7, vcc, 0, v153, vcc
	global_load_dwordx4 v[6:9], v[6:7], off
	v_cmp_lt_f32_e32 vcc, s67, v10
	s_cbranch_vccz .LBB0_607
	v_max_f32_e32 v10, v10, v10
	v_max_f32_e32 v10, 0, v10
	v_exp_f32_e64 v11, -v10
	s_and_saveexec_b64 s[12:13], s[8:9]
	ds_write_b32 v177, v11 offset:43520
	s_or_b64 exec, exec, s[12:13]
	s_waitcnt lgkmcnt(0)
	v_add_u32_e32 v88, s58, v156
	v_add_f32_e32 v167, v10, v167
	v_sub_f32_e32 v79, v79, v10
	v_sub_f32_e32 v78, v78, v10
	v_sub_f32_e32 v77, v77, v10
	v_sub_f32_e32 v76, v76, v10
	v_sub_f32_e32 v75, v75, v10
	v_sub_f32_e32 v74, v74, v10
	v_sub_f32_e32 v73, v73, v10
	v_sub_f32_e32 v72, v72, v10
	v_sub_f32_e32 v71, v71, v10
	v_sub_f32_e32 v70, v70, v10
	v_sub_f32_e32 v69, v69, v10
	v_sub_f32_e32 v68, v68, v10
	v_sub_f32_e32 v67, v67, v10
	v_sub_f32_e32 v66, v66, v10
	v_sub_f32_e32 v65, v65, v10
	v_sub_f32_e32 v64, v64, v10
	v_sub_f32_e32 v63, v63, v10
	v_sub_f32_e32 v62, v62, v10
	v_sub_f32_e32 v61, v61, v10
	v_sub_f32_e32 v60, v60, v10
	v_sub_f32_e32 v59, v59, v10
	v_sub_f32_e32 v58, v58, v10
	v_sub_f32_e32 v57, v57, v10
	v_sub_f32_e32 v56, v56, v10
	v_sub_f32_e32 v55, v55, v10
	v_sub_f32_e32 v54, v54, v10
	v_sub_f32_e32 v53, v53, v10
	v_sub_f32_e32 v52, v52, v10
	v_sub_f32_e32 v51, v51, v10
	v_sub_f32_e32 v50, v50, v10
	v_sub_f32_e32 v49, v49, v10
	v_sub_f32_e32 v48, v48, v10
	v_mul_f32_e32 v168, v11, v168
	ds_read_b128 v[10:13], v88 offset:43520
	ds_read_b128 v[80:83], v88 offset:43552
	ds_read_b128 v[84:87], v88 offset:43584
	ds_read_b128 v[88:91], v88 offset:43616
	s_waitcnt lgkmcnt(0)
	s_waitcnt lgkmcnt(0)
	v_pk_mul_f32 v[18:19], v[18:19], v[12:13]
	v_pk_mul_f32 v[20:21], v[20:21], v[80:81]
	v_pk_mul_f32 v[24:25], v[24:25], v[84:85]
	v_pk_mul_f32 v[28:29], v[28:29], v[88:89]
	v_pk_mul_f32 v[30:31], v[30:31], v[90:91]
	v_pk_mul_f32 v[26:27], v[26:27], v[86:87]
	v_pk_mul_f32 v[22:23], v[22:23], v[82:83]
	v_pk_mul_f32 v[16:17], v[16:17], v[10:11]
	v_pk_mul_f32 v[44:45], v[44:45], v[88:89]
	v_pk_mul_f32 v[40:41], v[40:41], v[84:85]
	v_pk_mul_f32 v[36:37], v[36:37], v[80:81]
	v_pk_mul_f32 v[46:47], v[46:47], v[90:91]
	v_pk_mul_f32 v[42:43], v[42:43], v[86:87]
	v_pk_mul_f32 v[38:39], v[38:39], v[82:83]
	v_pk_mul_f32 v[34:35], v[34:35], v[12:13]
	v_pk_mul_f32 v[32:33], v[32:33], v[10:11]
.LBB0_607:
	ds_read_b128 v[182:185], v175
	ds_read_b128 v[188:191], v175 offset:32
	ds_read_b128 v[192:195], v175 offset:4608
	ds_read_b128 v[196:199], v175 offset:4640
	ds_read_b128 v[200:203], v175 offset:64
	ds_read_b128 v[204:207], v175 offset:96
	ds_read_b128 v[208:211], v175 offset:4672
	ds_read_b128 v[212:215], v175 offset:4704
	ds_read_b128 v[80:83], v174 offset:21504
	ds_read_b128 v[84:87], v174 offset:21536
	ds_read_b128 v[96:99], v174 offset:21632
	ds_read_b128 v[100:103], v174 offset:21664
	ds_read_b128 v[88:91], v174 offset:21568
	ds_read_b128 v[92:95], v174 offset:21600
	ds_read_b128 v[104:107], v174 offset:21696
	ds_read_b128 v[108:111], v174 offset:21728
	ds_read_b64_tr_b16 v[232:233], v161 offset:30976
	ds_read_b64_tr_b16 v[234:235], v161 offset:32512
	ds_read_b64_tr_b16 v[238:239], v161 offset:32576
	ds_read_b64_tr_b16 v[236:237], v161 offset:31040
	ds_read_b64_tr_b16 v[144:145], v161 offset:34048
	ds_read_b64_tr_b16 v[146:147], v161 offset:35584
	ds_read_b64_tr_b16 v[142:143], v161 offset:35648
	ds_read_b64_tr_b16 v[140:141], v161 offset:34112
	ds_read_b64_tr_b16 v[136:137], v161 offset:37120
	ds_read_b64_tr_b16 v[138:139], v161 offset:38656
	ds_read_b64_tr_b16 v[134:135], v161 offset:38720
	ds_read_b64_tr_b16 v[132:133], v161 offset:37184
	ds_read_b64_tr_b16 v[128:129], v161 offset:40192
	ds_read_b64_tr_b16 v[130:131], v161 offset:41728
	ds_read_b64_tr_b16 v[12:13], v161 offset:41792
	ds_read_b64_tr_b16 v[10:11], v161 offset:40256
	v_sub_f32_e32 v187, v157, v167
	s_waitcnt lgkmcnt(0)
; #define SBAR_() __builtin_amdgcn_sched_barrier(0)
; __device__ __forceinline__ void fox_steady_step(f32x16& s0, f32x16& s1, f32x16& n0, f32x16& n1, const LAS unsigned char* kb, int coff, const LAS unsigned char* Vt, ...
;     ...
;     { const float cqm = cq - mref;
; #pragma unroll
;       for (int jj = 0; jj < 4; ++jj)
; #pragma unroll
;           for (int e = 0; e < 4; ++e) { n0[4 * jj + e] = cqm - ck4[jj][e]; n1[4 * jj + e] = cqm - ck4[4 + jj][e]; } }
;     SBAR_();
;     float rs = 0.f; u32x4 w0, w1, w2, w3;
;     ...
;     n0 = __builtin_amdgcn_mfma_f32_32x32x16_bf16(kf[0], qf[0], n0, 0, 0, 0); EXPN_(s0, 0, 3); SBAR_();
;     n1 = __builtin_amdgcn_mfma_f32_32x32x16_bf16(kf[1], qf[0], n1, 0, 0, 0); EXPN_(s0, 3, 3); w0.x = cvt_pk_bf16(s0[0], s0[1]); w0.y = cvt_pk_bf16(s0[2], s0[3]); SBAR_();
;     n0 = __builtin_amdgcn_mfma_f32_32x32x16_bf16(kf[2], qf[1], n0, 0, 0, 0); EXPN_(s0, 6, 3); w0.z = cvt_pk_bf16(s0[4], s0[5]); w0.w = cvt_pk_bf16(s0[6], s0[7]); SBAR_();
;     n1 = __builtin_amdgcn_mfma_f32_32x32x16_bf16(kf[3], qf[1], n1, 0, 0, 0); EXPN_(s0, 9, 3); w1.x = cvt_pk_bf16(s0[8], s0[9]); w1.y = cvt_pk_bf16(s0[10], s0[11]); SBAR_();
;     n0 = __builtin_amdgcn_mfma_f32_32x32x16_bf16(kf[4], qf[2], n0, 0, 0, 0); EXPN_(s0, 12, 4); w1.z = cvt_pk_bf16(s0[12], s0[13]); w1.w = cvt_pk_bf16(s0[14], s0[15]); SBAR_();
;     n1 = __builtin_amdgcn_mfma_f32_32x32x16_bf16(kf[5], qf[2], n1, 0, 0, 0); EXPN_(s1, 0, 3); SBAR_();
;     n0 = __builtin_amdgcn_mfma_f32_32x32x16_bf16(kf[6], qf[3], n0, 0, 0, 0); EXPN_(s1, 3, 3); w2.x = cvt_pk_bf16(s1[0], s1[1]); w2.y = cvt_pk_bf16(s1[2], s1[3]); SBAR_();
;     n1 = __builtin_amdgcn_mfma_f32_32x32x16_bf16(kf[7], qf[3], n1, 0, 0, 0); EXPN_(s1, 6, 2); w2.z = cvt_pk_bf16(s1[4], s1[5]); w2.w = cvt_pk_bf16(s1[6], s1[7]); SBAR_();
;     const bf16x8 pa0 = __builtin_bit_cast(bf16x8, w0), pa1 = __builtin_bit_cast(bf16x8, w1), pa2 = __builtin_bit_cast(bf16x8, w2);
;     float ra = fmaxf(fmaxf(n0[0], n0[1]), n1[0]), rb = fmaxf(fmaxf(n0[2], n0[3]), n1[1]);
;     o[0] = __builtin_amdgcn_mfma_f32_32x32x16_bf16(pa0, vf[0][0], o[0], 0, 0, 0); EXPN_(s1, 8, 2); ra = fmaxf(fmaxf(ra, n1[2]), n1[3]); SBAR_();
;     o[1] = __builtin_amdgcn_mfma_f32_32x32x16_bf16(pa0, vf[0][1], o[1], 0, 0, 0); EXPN_(s1, 10, 2); w3.x = cvt_pk_bf16(s1[8], s1[9]); rb = fmaxf(fmaxf(rb, n0[4]), n0[5]); SBAR_();
	v_sub_f32_e32 v95, v187, v95
	v_sub_f32_e32 v94, v187, v94
	v_sub_f32_e32 v93, v187, v93
	v_sub_f32_e32 v92, v187, v92
	v_sub_f32_e32 v91, v187, v91
	v_sub_f32_e32 v90, v187, v90
	v_sub_f32_e32 v89, v187, v89
	v_sub_f32_e32 v88, v187, v88
	v_sub_f32_e32 v87, v187, v87
	v_sub_f32_e32 v86, v187, v86
	v_sub_f32_e32 v85, v187, v85
	v_sub_f32_e32 v84, v187, v84
	v_sub_f32_e32 v83, v187, v83
	v_sub_f32_e32 v82, v187, v82
	v_sub_f32_e32 v81, v187, v81
	v_sub_f32_e32 v80, v187, v80
	v_sub_f32_e32 v111, v187, v111
	v_sub_f32_e32 v110, v187, v110
	v_sub_f32_e32 v109, v187, v109
	v_sub_f32_e32 v108, v187, v108
	v_sub_f32_e32 v107, v187, v107
	v_sub_f32_e32 v106, v187, v106
	v_sub_f32_e32 v105, v187, v105
	v_sub_f32_e32 v104, v187, v104
	v_sub_f32_e32 v103, v187, v103
	v_sub_f32_e32 v102, v187, v102
	v_sub_f32_e32 v101, v187, v101
	v_sub_f32_e32 v100, v187, v100
	v_sub_f32_e32 v99, v187, v99
	v_sub_f32_e32 v98, v187, v98
	v_sub_f32_e32 v97, v187, v97
	v_sub_f32_e32 v96, v187, v96
	v_mfma_f32_32x32x16_bf16 v[80:95], v[182:185], v[112:115], v[80:95]
	v_exp_f32_e32 v64, v64
	v_exp_f32_e32 v65, v65
	v_exp_f32_e32 v66, v66
	v_mfma_f32_32x32x16_bf16 v[96:111], v[192:195], v[112:115], v[96:111]
	v_exp_f32_e32 v67, v67
	v_exp_f32_e32 v68, v68
	v_exp_f32_e32 v69, v69
	v_cvt_pk_bf16_f32 v182, v64, v65
	v_cvt_pk_bf16_f32 v183, v66, v67
	v_mfma_f32_32x32x16_bf16 v[80:95], v[188:191], v[116:119], v[80:95]
	v_exp_f32_e32 v70, v70
	v_exp_f32_e32 v71, v71
	v_exp_f32_e32 v72, v72
	v_cvt_pk_bf16_f32 v184, v68, v69
	v_cvt_pk_bf16_f32 v185, v70, v71
	v_mfma_f32_32x32x16_bf16 v[96:111], v[196:199], v[116:119], v[96:111]
	v_exp_f32_e32 v73, v73
	v_exp_f32_e32 v74, v74
	v_exp_f32_e32 v75, v75
	v_cvt_pk_bf16_f32 v188, v72, v73
	v_cvt_pk_bf16_f32 v189, v74, v75
	v_mfma_f32_32x32x16_bf16 v[80:95], v[200:203], v[120:123], v[80:95]
	v_exp_f32_e32 v76, v76
	v_exp_f32_e32 v77, v77
	v_exp_f32_e32 v78, v78
	v_exp_f32_e32 v79, v79
	v_cvt_pk_bf16_f32 v190, v76, v77
	v_cvt_pk_bf16_f32 v191, v78, v79
	v_mfma_f32_32x32x16_bf16 v[96:111], v[208:211], v[120:123], v[96:111]
	v_exp_f32_e32 v48, v48
	v_exp_f32_e32 v49, v49
	v_exp_f32_e32 v50, v50
	v_mfma_f32_32x32x16_bf16 v[80:95], v[204:207], v[124:127], v[80:95]
	v_exp_f32_e32 v51, v51
	v_exp_f32_e32 v52, v52
	v_exp_f32_e32 v53, v53
	v_mfma_f32_32x32x16_bf16 v[96:111], v[212:215], v[124:127], v[96:111]
	v_exp_f32_e32 v54, v54
	v_exp_f32_e32 v55, v55
	v_mfma_f32_32x32x16_bf16 v[16:31], v[182:185], v[232:235], v[16:31]
	v_exp_f32_e32 v56, v56
	v_exp_f32_e32 v57, v57
	v_mfma_f32_32x32x16_bf16 v[32:47], v[182:185], v[236:239], v[32:47]
	v_exp_f32_e32 v58, v58
	v_exp_f32_e32 v59, v59
	v_mfma_f32_32x32x16_bf16 v[16:31], v[188:191], v[144:147], v[16:31]
	v_exp_f32_e32 v60, v60
	v_exp_f32_e32 v61, v61
	v_mfma_f32_32x32x16_bf16 v[32:47], v[188:191], v[140:143], v[32:47]
	v_max_f32_e32 v140, v81, v81
	v_max_f32_e32 v141, v80, v80
	v_exp_f32_e32 v62, v62
	v_exp_f32_e32 v63, v63
	v_max_f32_e32 v140, v141, v140
	v_max3_f32 v140, v140, v96, v98
	v_max3_f32 v182, v140, v99, v86
	v_max3_f32 v140, v82, v83, v97
	v_max3_f32 v143, v140, v84, v85
	v_cvt_pk_bf16_f32 v141, v58, v59
	v_cvt_pk_bf16_f32 v140, v56, v57
	v_cvt_pk_bf16_f32 v147, v54, v55
	v_cvt_pk_bf16_f32 v146, v52, v53
	v_cvt_pk_bf16_f32 v145, v50, v51
	v_cvt_pk_bf16_f32 v144, v48, v49
	v_cvt_pk_bf16_f32 v142, v60, v61
	v_max3_f32 v183, v143, v100, v101
	v_mfma_f32_32x32x16_bf16 v[16:31], v[144:147], v[136:139], v[16:31]
	v_cvt_pk_bf16_f32 v143, v62, v63
	v_max3_f32 v136, v182, v87, v102
	v_max3_f32 v137, v183, v88, v89
	v_mfma_f32_32x32x16_bf16 v[32:47], v[144:147], v[132:135], v[32:47]
	v_max3_f32 v132, v136, v103, v90
	v_max3_f32 v133, v137, v104, v105
	v_max3_f32 v132, v132, v91, v106
	v_max3_f32 v133, v133, v92, v93
	v_mfma_f32_32x32x16_bf16 v[16:31], v[140:143], v[128:131], v[16:31]
	v_max3_f32 v128, v132, v107, v94
	v_max3_f32 v129, v133, v108, v109
	v_max3_f32 v128, v128, v95, v110
	v_mfma_f32_32x32x16_bf16 v[32:47], v[140:143], v[10:13], v[32:47]
	v_max3_f32 v10, v128, v111, v129
	v_mov_b32_e32 v11, v10
	s_nop 1
	v_permlane32_swap_b32_e32 v10, v11
	v_add_u32_e32 v186, 0, v169
	s_waitcnt vmcnt(0)
	ds_write_b128 v173, v[2:5] offset:21760
	s_and_saveexec_b64 s[12:13], s[6:7]
	ds_write_b32 v186, v166 offset:43264
	s_or_b64 exec, exec, s[12:13]
	v_add_co_u32_e32 v2, vcc, 0x16e40000, v152
	ds_write_b128 v172, v[6:9] offset:9216
	s_nop 0
	v_addc_co_u32_e32 v3, vcc, 0, v153, vcc
	s_waitcnt lgkmcnt(0)
	s_barrier
	global_load_dwordx4 v[128:131], v[2:3], off
	s_and_saveexec_b64 s[12:13], s[6:7]
	s_cbranch_execz .LBB0_611
	v_add_co_u32_e32 v2, vcc, 0x2c02000, v154
	s_nop 1
	v_addc_co_u32_e32 v3, vcc, 0, v155, vcc
	global_load_dword v166, v[2:3], off
; #define LAS __attribute__((address_space(3)))
; __device__ __forceinline__ float fast_exp2(float x) { return __builtin_amdgcn_exp2f(x); }
; __device__ __forceinline__ float half_max(float v) { auto rr = __builtin_amdgcn_permlane32_swap(__float_as_uint(v), __float_as_uint(v), false, false); return fmaxf(__uint_as_float(rr[0]), __uint_as_float(rr[1])); }
; #define SBAR_() __builtin_amdgcn_sched_barrier(0)
; __device__ __forceinline__ void fox_steady_step(f32x16& s0, f32x16& s1, f32x16& n0, f32x16& n1, const LAS unsigned char* kb, int coff, const LAS unsigned char* Vt, ...
;     const float rm = rmc;
;     if (__any(rm > 8.0f)) {
;         const float dl = fmaxf(rm, 0.f);
;         mref += dl;
; #pragma unroll
;         for (int r = 0; r < 16; ++r) { s0[r] -= dl; s1[r] -= dl; }
;         const float alpha = fast_exp2(-dl);
;         lrun *= alpha;
;         if (hi == 0) wsf[r32] = alpha;
;         asm volatile("s_waitcnt lgkmcnt(0)" ::: "memory");
; #pragma unroll
;         for (int jj = 0; jj < 4; ++jj) { const f32x4 al = *(const LAS f32x4*)(wsf + 8 * jj + 4 * hi);
; #pragma unroll
;             for (int d = 0; d < 2; ++d) { o[d][4 * jj + 0] *= al.x; o[d][4 * jj + 1] *= al.y; o[d][4 * jj + 2] *= al.z; o[d][4 * jj + 3] *= al.w; } }
;         asm volatile("s_waitcnt lgkmcnt(0)" ::: "memory");
;     ...
;     lrun += rs;
;     o[0] = __builtin_amdgcn_mfma_f32_32x32x16_bf16(pa3, vf[3][0], o[0], 0, 0, 0); ra = fmaxf(fmaxf(ra, n0[14]), n0[15]); rb = fmaxf(fmaxf(rb, n1[12]), n1[13]); ra = fmaxf(fmaxf(ra, n1[14]), n1[15]); SBAR_();
;     o[1] = __builtin_amdgcn_mfma_f32_32x32x16_bf16(pa3, vf[3][1], o[1], 0, 0, 0);
;     ...
;     rmc = half_max(fmaxf(ra, rb));
.LBB0_611:
	s_or_b64 exec, exec, s[12:13]
	v_add_f32_e32 v2, 0, v64
	v_add_f32_e32 v2, v65, v2
	v_add_f32_e32 v2, v66, v2
	v_add_f32_e32 v2, v67, v2
	v_add_f32_e32 v2, v68, v2
	v_add_f32_e32 v2, v69, v2
	v_add_f32_e32 v2, v70, v2
	v_add_f32_e32 v2, v71, v2
	v_add_f32_e32 v2, v72, v2
	v_add_f32_e32 v2, v73, v2
	v_add_f32_e32 v2, v74, v2
	v_add_f32_e32 v2, v75, v2
	v_add_f32_e32 v2, v76, v2
	v_add_f32_e32 v2, v77, v2
	v_add_f32_e32 v2, v78, v2
	v_add_f32_e32 v2, v79, v2
	v_add_f32_e32 v2, v48, v2
	v_add_f32_e32 v2, v49, v2
	v_add_f32_e32 v2, v50, v2
	v_add_f32_e32 v2, v51, v2
	v_add_f32_e32 v2, v52, v2
	v_add_f32_e32 v2, v53, v2
	v_add_f32_e32 v2, v54, v2
	v_add_f32_e32 v2, v55, v2
	v_add_f32_e32 v2, v56, v2
	v_add_f32_e32 v2, v57, v2
	v_add_f32_e32 v2, v58, v2
	v_add_f32_e32 v2, v59, v2
	v_add_f32_e32 v2, v60, v2
	v_add_f32_e32 v2, v61, v2
	v_add_f32_e32 v2, v62, v2
	v_add_f32_e32 v2, v63, v2
	v_add_f32_e32 v154, v168, v2
	v_max_f32_e32 v2, v10, v10
	v_max_f32_e32 v3, v11, v11
	v_max_f32_e32 v6, v2, v3
	v_add_co_u32_e32 v2, vcc, s66, v152
	s_nop 1
	v_addc_co_u32_e32 v3, vcc, 0, v153, vcc
	global_load_dwordx4 v[2:5], v[2:3], off
	v_cmp_lt_f32_e32 vcc, s67, v6
	s_cbranch_vccz .LBB0_615
	v_max_f32_e32 v6, v6, v6
	v_max_f32_e32 v6, 0, v6
	v_exp_f32_e64 v7, -v6
	s_and_saveexec_b64 s[12:13], s[8:9]
	ds_write_b32 v177, v7 offset:43520
	s_or_b64 exec, exec, s[12:13]
	s_waitcnt lgkmcnt(0)
	v_add_u32_e32 v52, s58, v156
	v_add_f32_e32 v167, v167, v6
	v_pk_add_f32 v[80:81], v[80:81], v[6:7] op_sel_hi:[1,0] neg_lo:[0,1] neg_hi:[0,1]
	v_pk_add_f32 v[96:97], v[96:97], v[6:7] op_sel_hi:[1,0] neg_lo:[0,1] neg_hi:[0,1]
	v_pk_add_f32 v[82:83], v[82:83], v[6:7] op_sel_hi:[1,0] neg_lo:[0,1] neg_hi:[0,1]
	v_pk_add_f32 v[98:99], v[98:99], v[6:7] op_sel_hi:[1,0] neg_lo:[0,1] neg_hi:[0,1]
	v_pk_add_f32 v[84:85], v[84:85], v[6:7] op_sel_hi:[1,0] neg_lo:[0,1] neg_hi:[0,1]
	v_pk_add_f32 v[100:101], v[100:101], v[6:7] op_sel_hi:[1,0] neg_lo:[0,1] neg_hi:[0,1]
	v_pk_add_f32 v[86:87], v[86:87], v[6:7] op_sel_hi:[1,0] neg_lo:[0,1] neg_hi:[0,1]
	v_pk_add_f32 v[102:103], v[102:103], v[6:7] op_sel_hi:[1,0] neg_lo:[0,1] neg_hi:[0,1]
	v_pk_add_f32 v[88:89], v[88:89], v[6:7] op_sel_hi:[1,0] neg_lo:[0,1] neg_hi:[0,1]
	v_pk_add_f32 v[104:105], v[104:105], v[6:7] op_sel_hi:[1,0] neg_lo:[0,1] neg_hi:[0,1]
	v_pk_add_f32 v[90:91], v[90:91], v[6:7] op_sel_hi:[1,0] neg_lo:[0,1] neg_hi:[0,1]
	v_pk_add_f32 v[106:107], v[106:107], v[6:7] op_sel_hi:[1,0] neg_lo:[0,1] neg_hi:[0,1]
	v_pk_add_f32 v[92:93], v[92:93], v[6:7] op_sel_hi:[1,0] neg_lo:[0,1] neg_hi:[0,1]
	v_pk_add_f32 v[108:109], v[108:109], v[6:7] op_sel_hi:[1,0] neg_lo:[0,1] neg_hi:[0,1]
	v_pk_add_f32 v[94:95], v[94:95], v[6:7] op_sel_hi:[1,0] neg_lo:[0,1] neg_hi:[0,1]
	v_pk_add_f32 v[110:111], v[110:111], v[6:7] op_sel_hi:[1,0] neg_lo:[0,1] neg_hi:[0,1]
	v_mul_f32_e32 v154, v154, v7
	ds_read_b128 v[6:9], v52 offset:43520
	ds_read_b128 v[10:13], v52 offset:43552
	ds_read_b128 v[48:51], v52 offset:43584
	ds_read_b128 v[52:55], v52 offset:43616
	s_waitcnt lgkmcnt(0)
	s_waitcnt lgkmcnt(0)
	v_pk_mul_f32 v[18:19], v[18:19], v[8:9]
	v_pk_mul_f32 v[20:21], v[20:21], v[10:11]
	v_pk_mul_f32 v[24:25], v[24:25], v[48:49]
	v_pk_mul_f32 v[28:29], v[28:29], v[52:53]
	v_pk_mul_f32 v[30:31], v[30:31], v[54:55]
	v_pk_mul_f32 v[26:27], v[26:27], v[50:51]
	v_pk_mul_f32 v[22:23], v[22:23], v[12:13]
	v_pk_mul_f32 v[16:17], v[16:17], v[6:7]
	v_pk_mul_f32 v[44:45], v[44:45], v[52:53]
	v_pk_mul_f32 v[40:41], v[40:41], v[48:49]
	v_pk_mul_f32 v[36:37], v[36:37], v[10:11]
	v_pk_mul_f32 v[46:47], v[46:47], v[54:55]
	v_pk_mul_f32 v[42:43], v[42:43], v[50:51]
	v_pk_mul_f32 v[38:39], v[38:39], v[12:13]
	v_pk_mul_f32 v[34:35], v[34:35], v[8:9]
	v_pk_mul_f32 v[32:33], v[32:33], v[6:7]
	v_sub_f32_e32 v187, v157, v167

.LBB0_620:
	s_add_i32 s10, s95, -1
	s_cmp_lt_u32 s10, s62
	s_cselect_b64 s[44:45], -1, 0
	s_cmp_ge_u32 s10, s62
	v_lshl_add_u64 v[10:11], s[84:85], 0, v[6:7]
	s_cbranch_scc1 .LBB0_624
	s_waitcnt vmcnt(0)
	v_add_co_u32_e32 v2, vcc, 0x16e20000, v10
	s_nop 1
	v_addc_co_u32_e32 v3, vcc, 0, v11, vcc
	global_load_dwordx4 v[128:131], v[2:3], off
	s_and_saveexec_b64 s[10:11], s[6:7]
	s_cbranch_execz .LBB0_623
	v_lshl_add_u64 v[2:3], s[84:85], 0, v[8:9]
	v_add_co_u32_e32 v2, vcc, 0x2c01000, v2
	s_nop 1
	v_addc_co_u32_e32 v3, vcc, 0, v3, vcc
	global_load_dword v166, v[2:3], off

.LBB0_624:
	s_waitcnt vmcnt(0)
	v_add_co_u32_e32 v2, vcc, 0x18e10000, v10
	s_add_i32 s56, s76, s95
	s_nop 0
	v_addc_co_u32_e32 v3, vcc, 0, v11, vcc
	global_load_dwordx4 v[2:5], v[2:3], off
	s_add_i32 s10, s56, -3
	s_cmp_lt_i32 s10, s66
	s_cselect_b64 s[48:49], -1, 0
	s_cmp_ge_i32 s10, s66
	s_cbranch_scc1 .LBB0_627
	v_add_u32_e32 v108, s92, v156
	ds_read_b128 v[96:99], v108 offset:21632
	ds_read_b128 v[80:83], v108 offset:21504
	ds_read_b128 v[84:87], v108 offset:21536
	ds_read_b128 v[100:103], v108 offset:21664
	ds_read_b128 v[88:91], v108 offset:21568
	ds_read_b128 v[104:107], v108 offset:21696
	ds_read_b128 v[92:95], v108 offset:21600
	ds_read_b128 v[108:111], v108 offset:21728
	ds_read_b128 v[182:185], v14 offset:4608
	ds_read_b128 v[186:189], v14
	ds_read_b128 v[190:193], v14 offset:32
	v_sub_f32_e32 v12, v157, v167
	s_waitcnt lgkmcnt(0)
	v_sub_f32_e32 v107, v12, v107
	v_sub_f32_e32 v106, v12, v106
	v_sub_f32_e32 v111, v12, v111
	v_sub_f32_e32 v110, v12, v110
	v_sub_f32_e32 v109, v12, v109
	v_sub_f32_e32 v108, v12, v108
	v_sub_f32_e32 v105, v12, v105
	v_sub_f32_e32 v104, v12, v104
	v_sub_f32_e32 v103, v12, v103
	v_sub_f32_e32 v102, v12, v102
	v_sub_f32_e32 v101, v12, v101
	v_sub_f32_e32 v100, v12, v100
	v_sub_f32_e32 v99, v12, v99
	v_sub_f32_e32 v98, v12, v98
	v_sub_f32_e32 v97, v12, v97
	v_sub_f32_e32 v96, v12, v96
	v_sub_f32_e32 v95, v12, v95
	v_sub_f32_e32 v94, v12, v94
	v_sub_f32_e32 v93, v12, v93
	v_sub_f32_e32 v92, v12, v92
	v_sub_f32_e32 v91, v12, v91
	v_sub_f32_e32 v90, v12, v90
	v_sub_f32_e32 v89, v12, v89
	v_sub_f32_e32 v88, v12, v88
	v_sub_f32_e32 v87, v12, v87
	v_sub_f32_e32 v86, v12, v86
	v_sub_f32_e32 v85, v12, v85
	v_sub_f32_e32 v84, v12, v84
	v_sub_f32_e32 v83, v12, v83
	v_sub_f32_e32 v82, v12, v82
	v_sub_f32_e32 v81, v12, v81
	v_sub_f32_e32 v80, v12, v80
	v_mfma_f32_32x32x16_bf16 v[96:111], v[182:185], v[112:115], v[96:111]
	ds_read_b128 v[182:185], v14 offset:4640
	v_mfma_f32_32x32x16_bf16 v[80:95], v[186:189], v[112:115], v[80:95]
	v_mfma_f32_32x32x16_bf16 v[80:95], v[190:193], v[116:119], v[80:95]
	s_waitcnt lgkmcnt(0)
	v_mfma_f32_32x32x16_bf16 v[96:111], v[182:185], v[116:119], v[96:111]
	ds_read_b128 v[182:185], v14 offset:64
	ds_read_b128 v[186:189], v14 offset:4672
	s_waitcnt lgkmcnt(0)
	v_mfma_f32_32x32x16_bf16 v[80:95], v[182:185], v[120:123], v[80:95]
	v_mfma_f32_32x32x16_bf16 v[96:111], v[186:189], v[120:123], v[96:111]
	ds_read_b128 v[182:185], v14 offset:96
	ds_read_b128 v[186:189], v14 offset:4704
	s_waitcnt lgkmcnt(0)
	v_mfma_f32_32x32x16_bf16 v[80:95], v[182:185], v[124:127], v[80:95]
	v_mfma_f32_32x32x16_bf16 v[96:111], v[186:189], v[124:127], v[96:111]
	s_cmp_lt_i32 s66, s10
	s_cbranch_scc0 .LBB0_628

.LBB0_642:
	s_cmp_lt_u32 s95, s62
	s_cselect_b64 s[54:55], -1, 0
	s_cmp_ge_u32 s95, s62
	s_cselect_b64 s[52:53], -1, 0
	s_and_b64 vcc, exec, s[52:53]
	s_waitcnt vmcnt(0) lgkmcnt(0)
	ds_write_b128 v159, v[2:5] offset:9216
	s_waitcnt lgkmcnt(0)
	s_barrier
	s_cbranch_vccnz .LBB0_646
	v_add_co_u32_e32 v128, vcc, 0x16e30000, v10
	s_nop 1
	v_addc_co_u32_e32 v129, vcc, 0, v11, vcc
	global_load_dwordx4 v[128:131], v[128:129], off
	s_and_saveexec_b64 s[12:13], s[6:7]
	s_cbranch_execz .LBB0_645
	v_lshl_add_u64 v[182:183], s[84:85], 0, v[8:9]
	v_add_co_u32_e32 v182, vcc, 0x2c01000, v182
	s_nop 1
	v_addc_co_u32_e32 v183, vcc, 0, v183, vcc
	global_load_dword v166, v[182:183], off offset:2048

.LBB0_646:
	s_and_b64 vcc, exec, s[10:11]
	s_cbranch_vccnz .LBB0_648
	v_add_co_u32_e32 v2, vcc, 0x18e20000, v10
	s_nop 1
	v_addc_co_u32_e32 v3, vcc, 0, v11, vcc
	global_load_dwordx4 v[2:5], v[2:3], off

; __device__ __forceinline__ unsigned f2bf(float f) { unsigned u = __builtin_bit_cast(unsigned, f); return (u + 0x7fffu + ((u >> 16) & 1u)) >> 16; }
; __device__ __forceinline__ float fast_rcp(float x) { return __builtin_amdgcn_rcpf(x); }
; __device__ __forceinline__ int crow(int r, int hi) { return (r & 3) + 8 * (r >> 2) + 4 * hi; }
; __device__ __forceinline__ float half_sum(float v) { auto rr = __builtin_amdgcn_permlane32_swap(__float_as_uint(v), __float_as_uint(v), false, false); return __uint_as_float(rr[0]) + __uint_as_float(rr[1]); }
; __device__ __forceinline__ void fox_unit(const Params& P, int b, int h, int qb, LAS unsigned char* lds, bool dry = false) {
;     ...
;     const float lt = half_sum(lrun);
;     if (hi == 0) wsf[r32] = fast_rcp(lt);
;     asm volatile("s_waitcnt lgkmcnt(0)" ::: "memory");
;     bf16_t* Ow = proj + O_FQ + (rowb + q0 + wid * 32) * QP + h * 64;
; #pragma unroll
;     for (int r = 0; r < 16; ++r) { const int q = crow(r, hi); const float il = wsf[q];
; #pragma unroll
;         for (int d = 0; d < 2; ++d) if (!dry || o[d][r] == 1.2345e30f) Ow[(size_t)q * QP + 32 * d + r32] = (bf16_t)f2bf(o[d][r] * il); }
;     __syncthreads();
.LBB0_681:
	s_or_b64 exec, exec, s[6:7]
	s_lshl_b64 s[2:3], s[2:3], 10
	s_add_u32 s6, s90, s2
	s_addc_u32 s7, s91, s3
	s_lshl_b32 s2, s83, 1
	s_add_u32 s6, s6, s2
	s_waitcnt lgkmcnt(0)
	s_addc_u32 s7, s7, 0
	s_waitcnt vmcnt(0)
	v_lshlrev_b32_e32 v2, 1, v165
	v_mov_b32_e32 v3, v0
	v_lshl_add_u32 v1, v164, 4, s58
	v_lshl_add_u64 v[10:11], s[6:7], 0, v[2:3]
	ds_read_b128 v[2:5], v1 offset:43520
	ds_read_b128 v[6:9], v1 offset:43552
	v_lshlrev_b32_e32 v12, 12, v164
	v_mov_b32_e32 v13, v0
	v_lshl_add_u64 v[14:15], v[10:11], 0, v[12:13]
	s_waitcnt lgkmcnt(1)
	v_mul_f32_e32 v13, v16, v2
	v_bfe_u32 v16, v13, 16, 1
	v_add3_u32 v13, v13, v16, s60
	v_mul_f32_e32 v2, v32, v2
	global_store_short_d16_hi v[14:15], v13, off
	v_bfe_u32 v13, v2, 16, 1
	v_add3_u32 v2, v2, v13, s60
	global_store_short_d16_hi v[14:15], v2, off offset:64
	v_mul_f32_e32 v2, v17, v3
	v_or_b32_e32 v14, 0x400, v12
	v_mov_b32_e32 v15, v0
	v_bfe_u32 v13, v2, 16, 1
	v_lshl_add_u64 v[14:15], v[10:11], 0, v[14:15]
	v_add3_u32 v2, v2, v13, s60
	global_store_short_d16_hi v[14:15], v2, off
	v_mul_f32_e32 v2, v33, v3
	v_bfe_u32 v3, v2, 16, 1
	v_add3_u32 v2, v2, v3, s60
	v_mul_f32_e32 v13, v18, v4
	global_store_short_d16_hi v[14:15], v2, off offset:64
	v_or_b32_e32 v2, 0x800, v12
	v_mov_b32_e32 v3, v0
	v_bfe_u32 v14, v13, 16, 1
	v_lshl_add_u64 v[2:3], v[10:11], 0, v[2:3]
	v_add3_u32 v13, v13, v14, s60
	v_mul_f32_e32 v4, v34, v4
	global_store_short_d16_hi v[2:3], v13, off
	v_bfe_u32 v13, v4, 16, 1
	v_add3_u32 v4, v4, v13, s60
	global_store_short_d16_hi v[2:3], v4, off offset:64
	v_mul_f32_e32 v4, v19, v5
	v_or_b32_e32 v2, 0xc00, v12
	v_mov_b32_e32 v3, v0
	v_bfe_u32 v13, v4, 16, 1
	v_lshl_add_u64 v[2:3], v[10:11], 0, v[2:3]
	v_add3_u32 v4, v4, v13, s60
	global_store_short_d16_hi v[2:3], v4, off
	v_mul_f32_e32 v4, v35, v5
	v_bfe_u32 v5, v4, 16, 1
	v_add3_u32 v4, v4, v5, s60
	global_store_short_d16_hi v[2:3], v4, off offset:64
	s_waitcnt lgkmcnt(0)
	v_mul_f32_e32 v4, v20, v6
	v_or_b32_e32 v2, 0x2000, v12
	v_mov_b32_e32 v3, v0
	v_bfe_u32 v5, v4, 16, 1
	v_lshl_add_u64 v[2:3], v[10:11], 0, v[2:3]
	v_add3_u32 v4, v4, v5, s60
	global_store_short_d16_hi v[2:3], v4, off
	v_mul_f32_e32 v4, v36, v6
	v_bfe_u32 v5, v4, 16, 1
	v_add3_u32 v4, v4, v5, s60
	global_store_short_d16_hi v[2:3], v4, off offset:64
	v_mul_f32_e32 v4, v21, v7
	v_or_b32_e32 v2, 0x2400, v12
	v_mov_b32_e32 v3, v0
	v_bfe_u32 v5, v4, 16, 1
	v_lshl_add_u64 v[2:3], v[10:11], 0, v[2:3]
	v_add3_u32 v4, v4, v5, s60
	global_store_short_d16_hi v[2:3], v4, off
	v_mul_f32_e32 v4, v37, v7
	v_bfe_u32 v5, v4, 16, 1
	v_add3_u32 v4, v4, v5, s60
	global_store_short_d16_hi v[2:3], v4, off offset:64
	v_mul_f32_e32 v4, v22, v8
	v_or_b32_e32 v2, 0x2800, v12
	v_mov_b32_e32 v3, v0
	v_bfe_u32 v5, v4, 16, 1
	v_lshl_add_u64 v[2:3], v[10:11], 0, v[2:3]
	v_add3_u32 v4, v4, v5, s60
	global_store_short_d16_hi v[2:3], v4, off
	v_mul_f32_e32 v4, v38, v8
	v_bfe_u32 v5, v4, 16, 1
	v_add3_u32 v4, v4, v5, s60
	global_store_short_d16_hi v[2:3], v4, off offset:64
	v_mul_f32_e32 v4, v23, v9
	v_or_b32_e32 v2, 0x2c00, v12
	v_mov_b32_e32 v3, v0
	v_bfe_u32 v5, v4, 16, 1
	v_lshl_add_u64 v[2:3], v[10:11], 0, v[2:3]
	v_add3_u32 v4, v4, v5, s60
	global_store_short_d16_hi v[2:3], v4, off
	v_mul_f32_e32 v4, v39, v9
	v_bfe_u32 v5, v4, 16, 1
	v_add3_u32 v4, v4, v5, s60
	global_store_short_d16_hi v[2:3], v4, off offset:64
	ds_read_b128 v[2:5], v1 offset:43584
	ds_read_b128 v[6:9], v1 offset:43616
	v_or_b32_e32 v14, 0x4000, v12
	v_mov_b32_e32 v15, v0
	v_lshl_add_u64 v[14:15], v[10:11], 0, v[14:15]
	s_waitcnt lgkmcnt(0)
	v_mul_f32_e32 v1, v24, v2
	v_bfe_u32 v13, v1, 16, 1
	v_add3_u32 v1, v1, v13, s60
	global_store_short_d16_hi v[14:15], v1, off
	v_mul_f32_e32 v1, v40, v2
	v_bfe_u32 v2, v1, 16, 1
	v_add3_u32 v1, v1, v2, s60
	global_store_short_d16_hi v[14:15], v1, off offset:64
	v_mul_f32_e32 v1, v25, v3
	v_or_b32_e32 v14, 0x4400, v12
	v_mov_b32_e32 v15, v0
	v_bfe_u32 v2, v1, 16, 1
	v_lshl_add_u64 v[14:15], v[10:11], 0, v[14:15]
	v_add3_u32 v1, v1, v2, s60
	global_store_short_d16_hi v[14:15], v1, off
	v_mul_f32_e32 v1, v41, v3
	v_bfe_u32 v2, v1, 16, 1
	v_add3_u32 v1, v1, v2, s60
	global_store_short_d16_hi v[14:15], v1, off offset:64
	v_mul_f32_e32 v1, v26, v4
	v_or_b32_e32 v2, 0x4800, v12
	v_mov_b32_e32 v3, v0
	v_bfe_u32 v13, v1, 16, 1
	v_lshl_add_u64 v[2:3], v[10:11], 0, v[2:3]
	v_add3_u32 v1, v1, v13, s60
	global_store_short_d16_hi v[2:3], v1, off
	v_mul_f32_e32 v1, v42, v4
	v_bfe_u32 v4, v1, 16, 1
	v_add3_u32 v1, v1, v4, s60
	global_store_short_d16_hi v[2:3], v1, off offset:64
	v_mul_f32_e32 v1, v27, v5
	v_or_b32_e32 v2, 0x4c00, v12
	v_mov_b32_e32 v3, v0
	v_bfe_u32 v4, v1, 16, 1
	v_lshl_add_u64 v[2:3], v[10:11], 0, v[2:3]
	v_add3_u32 v1, v1, v4, s60
	global_store_short_d16_hi v[2:3], v1, off
	v_mul_f32_e32 v1, v43, v5
	v_bfe_u32 v4, v1, 16, 1
	v_add3_u32 v1, v1, v4, s60
	global_store_short_d16_hi v[2:3], v1, off offset:64
	v_mul_f32_e32 v1, v28, v6
	v_or_b32_e32 v2, 0x6000, v12
	v_mov_b32_e32 v3, v0
	v_bfe_u32 v4, v1, 16, 1
	v_lshl_add_u64 v[2:3], v[10:11], 0, v[2:3]
	v_add3_u32 v1, v1, v4, s60
	global_store_short_d16_hi v[2:3], v1, off
	v_mul_f32_e32 v1, v44, v6
	v_bfe_u32 v4, v1, 16, 1
	v_add3_u32 v1, v1, v4, s60
	global_store_short_d16_hi v[2:3], v1, off offset:64
	v_mul_f32_e32 v1, v29, v7
	v_or_b32_e32 v2, 0x6400, v12
	v_mov_b32_e32 v3, v0
	v_bfe_u32 v4, v1, 16, 1
	v_lshl_add_u64 v[2:3], v[10:11], 0, v[2:3]
	v_add3_u32 v1, v1, v4, s60
	global_store_short_d16_hi v[2:3], v1, off
	v_mul_f32_e32 v1, v45, v7
	v_bfe_u32 v4, v1, 16, 1
	v_add3_u32 v1, v1, v4, s60
	global_store_short_d16_hi v[2:3], v1, off offset:64
	v_mul_f32_e32 v1, v30, v8
	v_or_b32_e32 v2, 0x6800, v12
	v_mov_b32_e32 v3, v0
	v_bfe_u32 v4, v1, 16, 1
	v_lshl_add_u64 v[2:3], v[10:11], 0, v[2:3]
	v_add3_u32 v1, v1, v4, s60
	global_store_short_d16_hi v[2:3], v1, off
	v_mul_f32_e32 v1, v46, v8
	v_bfe_u32 v4, v1, 16, 1
	v_add3_u32 v1, v1, v4, s60
	global_store_short_d16_hi v[2:3], v1, off offset:64
	v_mul_f32_e32 v1, v31, v9
	v_or_b32_e32 v2, 0x6c00, v12
	v_mov_b32_e32 v3, v0
	v_bfe_u32 v4, v1, 16, 1
	v_lshl_add_u64 v[2:3], v[10:11], 0, v[2:3]
	v_add3_u32 v1, v1, v4, s60
	global_store_short_d16_hi v[2:3], v1, off
	v_mul_f32_e32 v1, v47, v9
	v_bfe_u32 v4, v1, 16, 1
	s_xor_b32 s13, s72, 7
	v_add3_u32 v1, v1, v4, s60
	s_mov_b64 s[52:53], s[94:95]
	v_mov_b32_e32 v76, v180
	s_lshl_b32 s56, s13, 8
	global_store_short_d16_hi v[2:3], v1, off offset:64
	s_waitcnt lgkmcnt(0)
	s_barrier
; #define FOX_GLOADK(t) do { kreg = *(const u32x4*)(sbase + O_FK + (size_t)(64 * (t)) * QP); if (tid < 64) creg = cbuf[(rowb + 64 * (t) + tid) * 8 + h]; } while (0)
; #define FOX_GLOADV(t) do { vreg = *(const u32x4*)(sbase + O_FV + (size_t)(64 * (t)) * QP); } while (0)
; #define FOX_LSTOREK(buf) do { LAS unsigned char* bb_ = lds + (buf) * BUFB; *(LAS u32x4*)(bb_ + KOFF + srow * 144 + sch * 16) = kreg; if (tid < 64) *(LAS float*)(bb_ + COFF + tid * 4) = creg; } while (0)
; __device__ __forceinline__ void fox_unit(const Params& P, int b, int h, int qb, LAS unsigned char* lds, bool dry = false) {
;     ...
;     bf16x8 qf[4];
;     { const bf16_t* Qw = proj + O_FQ + (rowb + q0 + wid * 32 + r32) * QP + h * 64;
; #pragma unroll
;       for (int d0 = 0; d0 < 4; ++d0) qf[d0] = *(const bf16x8*)(Qw + d0 * 16 + hi * 8); }
;     const float cq = cbuf[(rowb + q0 + wid * 32 + r32) * 8 + h];
;     f32x16 o[2]; o[0] = f32x16{}; o[1] = f32x16{};
;     float mref = 0.f, lrun = 0.f;
;     const int NT = 4 * (qb + 1);
;     const int srow = tid >> 3, sch = tid & 7;
;     u32x4 kreg, vreg; float creg = 0.f;
;     const bf16_t* sbase = proj + (rowb + srow) * QP + h * 64 + sch * 8;
;     ...
;     FOX_GLOADK(0); FOX_GLOADV(0); FOX_LSTOREK(0); FOX_LSTOREV(0);
;     FOX_GLOADK(1); FOX_LSTOREK(1);
;     __syncthreads();
;     f32x16 s0, s1, n0 = {}, n1 = {};
;     FOX_INIT(s0, s1, 0); attn_qk(s0, s1, lds + KOFF, 144, qf, r32, hi);
	s_add_u32 s84, s52, 0x14e00000
	v_readfirstlane_b32 s12, v76
	s_addc_u32 s85, s53, 0
	s_ashr_i32 s57, s12, 1
	s_andn2_b32 s57, s57, 31
	s_or_b32 s6, s50, s56
	s_ashr_i32 s7, s57, 31
	s_add_u32 s90, s6, s57
	v_and_b32_e32 v162, 31, v76
	s_addc_u32 s91, s51, s7
	v_or_b32_e32 v2, s90, v162
	v_mov_b32_e32 v3, s91
	v_lshlrev_b64 v[4:5], 10, v[2:3]
	s_mov_b32 s3, s97
	v_bfe_u32 v1, v76, 5, 1
	v_lshl_add_u64 v[4:5], s[84:85], 0, v[4:5]
	v_lshl_add_u64 v[4:5], v[4:5], 0, s[2:3]
	v_lshlrev_b32_e32 v146, 4, v1
	v_mov_b32_e32 v147, v0
	v_ashrrev_i32_e32 v78, 3, v76
	v_lshl_add_u64 v[4:5], v[4:5], 0, v[146:147]
	v_ashrrev_i32_e32 v79, 31, v78
	global_load_dwordx4 v[98:101], v[4:5], off
	global_load_dwordx4 v[102:105], v[4:5], off offset:32
	global_load_dwordx4 v[106:109], v[4:5], off offset:64
	global_load_dwordx4 v[110:113], v[4:5], off offset:96
	v_lshl_add_u64 v[4:5], s[50:51], 0, v[78:79]
	v_lshlrev_b64 v[4:5], 10, v[4:5]
	v_and_b32_e32 v6, 7, v76
	v_lshl_add_u64 v[4:5], s[52:53], 0, v[4:5]
	s_add_u32 s8, s52, 0x2c00000
	v_lshl_add_u64 v[4:5], v[4:5], 0, s[2:3]
	v_lshlrev_b32_e32 v152, 4, v6
	v_mov_b32_e32 v153, v0
	s_addc_u32 s9, s53, 0
	v_lshlrev_b64 v[2:3], 5, v[2:3]
	v_lshl_add_u64 v[6:7], v[4:5], 0, v[152:153]
	v_lshl_add_u64 v[2:3], s[8:9], 0, v[2:3]
	v_add_co_u32_e32 v4, vcc, 0x16e00000, v6
	v_lshl_add_u64 v[2:3], v[2:3], 0, s[96:97]
	s_nop 0
	v_addc_co_u32_e32 v5, vcc, 0, v7, vcc
	global_load_dword v163, v[2:3], off
	s_nop 0
	global_load_dwordx4 v[2:5], v[4:5], off
	v_cmp_gt_i32_e64 s[6:7], 64, v76
	v_mov_b32_e32 v165, 0
	v_ashrrev_i32_e32 v77, 31, v76
	s_and_saveexec_b64 s[10:11], s[6:7]
	s_cbranch_execz .LBB0_683
	v_lshl_add_u64 v[8:9], s[50:51], 0, v[76:77]
	v_lshlrev_b64 v[8:9], 5, v[8:9]
	v_lshl_add_u64 v[8:9], s[8:9], 0, v[8:9]
	v_lshl_add_u64 v[8:9], v[8:9], 0, s[96:97]
	global_load_dword v165, v[8:9], off
.LBB0_683:
	s_or_b64 exec, exec, s[10:11]
	s_mov_b64 s[10:11], 0x6e00000
	v_lshl_add_u64 v[50:51], v[6:7], 0, s[10:11]
	v_add_co_u32_e32 v6, vcc, 0x12000000, v50
	s_movk_i32 s3, 0x90
	s_nop 0
	v_addc_co_u32_e32 v7, vcc, 0, v51, vcc
	global_load_dwordx4 v[6:9], v[6:7], off
	v_mul_lo_u32 v168, v78, s3
	v_add_u32_e32 v10, 0, v168
	v_add_u32_e32 v169, v10, v152
	v_lshl_add_u32 v12, v76, 2, 0
	s_waitcnt vmcnt(0) lgkmcnt(0)
	ds_write_b128 v169, v[2:5]
	s_and_saveexec_b64 s[10:11], s[6:7]
	ds_write_b32 v12, v165 offset:21504
	s_or_b64 exec, exec, s[10:11]
	v_mad_u64_u32 v[10:11], s[10:11], v78, 48, v[10:11]
	v_add_u32_e32 v170, v10, v152
	v_add_co_u32_e32 v2, vcc, 0x10010000, v50
	ds_write_b128 v170, v[6:9] offset:9216
	s_nop 0
	v_addc_co_u32_e32 v3, vcc, 0, v51, vcc
	global_load_dwordx4 v[2:5], v[2:3], off
	s_and_saveexec_b64 s[10:11], s[6:7]
	s_cbranch_execz .LBB0_687
	v_lshl_add_u64 v[6:7], v[76:77], 0, s[50:51]
	v_lshlrev_b64 v[6:7], 5, v[6:7]
	v_lshl_add_u64 v[6:7], s[8:9], 0, v[6:7]
	v_lshl_add_u64 v[6:7], v[6:7], 0, s[96:97]
	global_load_dword v165, v[6:7], off offset:2048
.LBB0_687:
	s_or_b64 exec, exec, s[10:11]
	s_movk_i32 s3, 0xffd0
	v_mad_u64_u32 v[6:7], s[10:11], v78, s3, v[10:11]
	v_add_u32_e32 v171, v6, v152
	s_waitcnt vmcnt(0) lgkmcnt(0)
	ds_write_b128 v171, v[2:5] offset:21760
	s_and_saveexec_b64 s[10:11], s[6:7]
	ds_write_b32 v12, v165 offset:43264
	s_or_b64 exec, exec, s[10:11]
	s_movk_i32 s3, 0x90
	v_add_u32_e32 v172, 0, v146
	v_mad_u32_u24 v34, v162, s3, 0
	s_waitcnt lgkmcnt(0)
	s_barrier
	ds_read_b128 v[18:21], v172 offset:21632
	ds_read_b128 v[2:5], v172 offset:21504
	ds_read_b128 v[6:9], v172 offset:21536
	ds_read_b128 v[22:25], v172 offset:21664
	ds_read_b128 v[10:13], v172 offset:21568
	ds_read_b128 v[26:29], v172 offset:21696
	ds_read_b128 v[14:17], v172 offset:21600
	ds_read_b128 v[30:33], v172 offset:21728
	v_add_u32_e32 v173, v34, v146
	ds_read_b128 v[34:37], v173 offset:4608
	ds_read_b128 v[38:41], v173
	ds_read_b128 v[42:45], v173 offset:32
	s_waitcnt lgkmcnt(6)
	v_sub_f32_e32 v13, v163, v13
	s_waitcnt lgkmcnt(4)
	v_sub_f32_e32 v17, v163, v17
	v_sub_f32_e32 v16, v163, v16
	v_sub_f32_e32 v15, v163, v15
	v_sub_f32_e32 v14, v163, v14
	v_sub_f32_e32 v12, v163, v12
	v_sub_f32_e32 v11, v163, v11
	v_sub_f32_e32 v10, v163, v10
	v_sub_f32_e32 v9, v163, v9
	v_sub_f32_e32 v8, v163, v8
	v_sub_f32_e32 v7, v163, v7
	v_sub_f32_e32 v6, v163, v6
	v_sub_f32_e32 v5, v163, v5
	v_sub_f32_e32 v4, v163, v4
	v_sub_f32_e32 v3, v163, v3
	v_sub_f32_e32 v2, v163, v2
	s_waitcnt lgkmcnt(3)
	v_sub_f32_e32 v33, v163, v33
	v_sub_f32_e32 v32, v163, v32
	s_waitcnt lgkmcnt(1)
	v_mfma_f32_32x32x16_bf16 v[2:17], v[38:41], v[98:101], v[2:17]
	v_sub_f32_e32 v31, v163, v31
	v_sub_f32_e32 v30, v163, v30
	v_sub_f32_e32 v29, v163, v29
	v_sub_f32_e32 v28, v163, v28
	v_sub_f32_e32 v27, v163, v27
	v_sub_f32_e32 v26, v163, v26
	v_sub_f32_e32 v25, v163, v25
	v_sub_f32_e32 v24, v163, v24
	v_sub_f32_e32 v23, v163, v23
	v_sub_f32_e32 v22, v163, v22
	v_sub_f32_e32 v21, v163, v21
	v_sub_f32_e32 v20, v163, v20
	v_sub_f32_e32 v19, v163, v19
	v_sub_f32_e32 v18, v163, v18
	s_waitcnt lgkmcnt(0)
	v_mfma_f32_32x32x16_bf16 v[2:17], v[42:45], v[102:105], v[2:17]
	v_mfma_f32_32x32x16_bf16 v[18:33], v[34:37], v[98:101], v[18:33]
	ds_read_b128 v[34:37], v173 offset:4640
	s_waitcnt lgkmcnt(0)
	v_mfma_f32_32x32x16_bf16 v[18:33], v[34:37], v[102:105], v[18:33]
	ds_read_b128 v[34:37], v173 offset:64
	ds_read_b128 v[38:41], v173 offset:4672
	s_waitcnt lgkmcnt(1)
	v_mfma_f32_32x32x16_bf16 v[2:17], v[34:37], v[106:109], v[2:17]
	s_waitcnt lgkmcnt(0)
	v_mfma_f32_32x32x16_bf16 v[18:33], v[38:41], v[106:109], v[18:33]
	ds_read_b128 v[34:37], v173 offset:96
	ds_read_b128 v[38:41], v173 offset:4704
	s_waitcnt lgkmcnt(1)
	v_mfma_f32_32x32x16_bf16 v[2:17], v[34:37], v[110:113], v[2:17]
	v_add_co_u32_e32 v34, vcc, 0x10020000, v50
	s_nop 1
	v_addc_co_u32_e32 v35, vcc, 0, v51, vcc
	global_load_dwordx4 v[68:71], v[34:35], off
	s_waitcnt lgkmcnt(0)
	v_mfma_f32_32x32x16_bf16 v[18:33], v[38:41], v[110:113], v[18:33]
	s_and_saveexec_b64 s[10:11], s[6:7]
	s_cbranch_execz .LBB0_691
	v_lshl_add_u64 v[34:35], v[76:77], 0, s[50:51]
	v_lshlrev_b64 v[34:35], 5, v[34:35]
	v_lshl_add_u64 v[34:35], s[8:9], 0, v[34:35]
	v_lshl_add_u64 v[34:35], v[34:35], 0, s[96:97]
	v_add_co_u32_e32 v34, vcc, 0x1000, v34
	s_nop 1
	v_addc_co_u32_e32 v35, vcc, 0, v35, vcc
	global_load_dword v165, v[34:35], off
; #define LAS __attribute__((address_space(3)))
; __device__ __forceinline__ float fast_exp2(float x) { return __builtin_amdgcn_exp2f(x); }
; __device__ __forceinline__ int crow(int r, int hi) { return (r & 3) + 8 * (r >> 2) + 4 * hi; }
; template <int NDT, int VSTR> ...
;     if (domask) {
; #pragma unroll
;         for (int r = 0; r < 16; ++r) { const int kv = crow(r, hi); if (kv > qrel) p0[r] = -INFINITY; if (kv + 32 > qrel) p1[r] = -INFINITY; }
;     }
;     float ra = fmaxf(fmaxf(p0[0], p0[1]), p1[0]), rb = fmaxf(fmaxf(p0[2], p0[3]), p1[1]);
;     ra = fmaxf(fmaxf(ra, p1[2]), p1[3]);
; #pragma unroll
;     for (int r = 4; r < 16; r += 4) { ra = fmaxf(fmaxf(ra, p0[r]), p0[r + 1]); rb = fmaxf(fmaxf(rb, p0[r + 2]), p0[r + 3]); ra = fmaxf(fmaxf(ra, p1[r]), p1[r + 1]); rb = fmaxf(fmaxf(rb, p1[r + 2]), p1[r + 3]); }
;     const float rm = half_max(fmaxf(ra, rb));
;     if (first || __any(rm > 8.0f)) {
;         const float dl = first ? rm : fmaxf(rm, 0.f);
;         mref += dl;
; #pragma unroll
;         for (int r = 0; r < 16; ++r) { p0[r] -= dl; p1[r] -= dl; }
;         if (has_next) {
; #pragma unroll
;             for (int r = 0; r < 16; ++r) { n0[r] -= dl; n1[r] -= dl; } }
;         if (!first) {
;             const float alpha = fast_exp2(-dl);
;             lrun *= alpha;
;             if (hi == 0) wsf[r32] = alpha;
;             asm volatile("s_waitcnt lgkmcnt(0)" ::: "memory");
; #pragma unroll
;             for (int jj = 0; jj < 4; ++jj) { const f32x4 al = *(const LAS f32x4*)(wsf + 8 * jj + 4 * hi);
; #pragma unroll
;                 for (int d = 0; d < NDT; ++d) { o[d][4 * jj + 0] *= al.x; o[d][4 * jj + 1] *= al.y; o[d][4 * jj + 2] *= al.z; o[d][4 * jj + 3] *= al.w; } }
;             asm volatile("s_waitcnt lgkmcnt(0)" ::: "memory");
;         }
;     }
;     constexpr int PRE = (NDT == 2) ? 4 : 1;
;     const int lane_ = hi * 32 + r32;
;     const LAS unsigned char* vb = Vt + (4 * hi + ((lane_ & 15) >> 2)) * VSTR + (16 * ((lane_ >> 4) & 1) + 4 * (lane_ & 3)) * 2;
;     ...
;     bf16x8 vpre[PRE][NDT];
; #pragma unroll
;     for (int s = 0; s < PRE; ++s)
; #pragma unroll
;         for (int d = 0; d < NDT; ++d) vpre[s][d] = VFRAG(s, d);
;     float rs0 = 0.f, rs1 = 0.f;
; #pragma unroll
;     for (int r = 0; r < 16; ++r) { p0[r] = fast_exp2(p0[r]); p1[r] = fast_exp2(p1[r]); rs0 += p0[r]; rs1 += p1[r]; }
.LBB0_691:
	s_or_b64 exec, exec, s[10:11]
	ds_read_b128 v[34:37], v172 offset:43264
	ds_read_b128 v[38:41], v172 offset:43296
	ds_read_b128 v[42:45], v172 offset:43328
	ds_read_b128 v[46:49], v172 offset:43360
	ds_read_b128 v[52:55], v172 offset:43392
	ds_read_b128 v[56:59], v172 offset:43424
	ds_read_b128 v[60:63], v172 offset:43456
	ds_read_b128 v[64:67], v172 offset:43488
	ds_read_b128 v[72:75], v173 offset:21760
	s_waitcnt lgkmcnt(0)
	v_sub_f32_e32 v49, v163, v49
	v_sub_f32_e32 v48, v163, v48
	v_sub_f32_e32 v47, v163, v47
	v_sub_f32_e32 v46, v163, v46
	v_sub_f32_e32 v45, v163, v45
	v_sub_f32_e32 v44, v163, v44
	v_sub_f32_e32 v43, v163, v43
	v_sub_f32_e32 v42, v163, v42
	v_sub_f32_e32 v41, v163, v41
	v_sub_f32_e32 v40, v163, v40
	v_sub_f32_e32 v39, v163, v39
	v_sub_f32_e32 v38, v163, v38
	v_sub_f32_e32 v37, v163, v37
	v_sub_f32_e32 v36, v163, v36
	v_sub_f32_e32 v35, v163, v35
	v_sub_f32_e32 v34, v163, v34
	ds_read_b128 v[80:83], v173 offset:26368
	ds_read_b128 v[84:87], v173 offset:21792
	v_mfma_f32_32x32x16_bf16 v[34:49], v[72:75], v[98:101], v[34:49]
	v_sub_f32_e32 v67, v163, v67
	v_sub_f32_e32 v66, v163, v66
	v_sub_f32_e32 v65, v163, v65
	v_sub_f32_e32 v64, v163, v64
	v_sub_f32_e32 v63, v163, v63
	v_sub_f32_e32 v62, v163, v62
	v_sub_f32_e32 v61, v163, v61
	v_sub_f32_e32 v60, v163, v60
	v_sub_f32_e32 v59, v163, v59
	v_sub_f32_e32 v58, v163, v58
	v_sub_f32_e32 v57, v163, v57
	v_sub_f32_e32 v56, v163, v56
	v_sub_f32_e32 v55, v163, v55
	v_sub_f32_e32 v54, v163, v54
	v_sub_f32_e32 v53, v163, v53
	v_sub_f32_e32 v52, v163, v52
	ds_read_b128 v[72:75], v173 offset:26400
	s_waitcnt lgkmcnt(0)
	v_mfma_f32_32x32x16_bf16 v[34:49], v[84:87], v[102:105], v[34:49]
	v_lshlrev_b32_e32 v147, 2, v1
	s_movk_i32 s3, 0xc0
	v_add_co_u32_e32 v50, vcc, 0x12010000, v50
	v_lshlrev_b32_e32 v167, 2, v76
	s_nop 0
	v_addc_co_u32_e32 v51, vcc, 0, v51, vcc
	v_mfma_f32_32x32x16_bf16 v[52:67], v[80:83], v[98:101], v[52:67]
	v_add_u32_e32 v177, 0, v167
	v_mfma_f32_32x32x16_bf16 v[52:67], v[72:75], v[102:105], v[52:67]
	ds_read_b128 v[72:75], v173 offset:21824
	ds_read_b128 v[80:83], v173 offset:21856
	s_waitcnt lgkmcnt(0)
	v_mfma_f32_32x32x16_bf16 v[34:49], v[72:75], v[106:109], v[34:49]
	ds_read_b128 v[72:75], v173 offset:26432
	ds_read_b128 v[84:87], v173 offset:26464
	s_waitcnt lgkmcnt(0)
	v_mfma_f32_32x32x16_bf16 v[52:67], v[72:75], v[106:109], v[52:67]
	v_max_f32_e32 v72, v3, v3
	v_max_f32_e32 v73, v2, v2
	v_max_f32_e32 v72, v73, v72
	v_max3_f32 v73, v4, v5, v19
	v_max3_f32 v72, v72, v18, v20
	v_max3_f32 v72, v72, v21, v6
	v_max3_f32 v73, v73, v8, v9
	v_max3_f32 v72, v72, v7, v22
	v_max3_f32 v73, v73, v24, v25
	v_max3_f32 v72, v72, v23, v10
	v_max3_f32 v73, v73, v12, v13
	v_max3_f32 v72, v72, v11, v26
	v_max3_f32 v73, v73, v28, v29
	v_max3_f32 v72, v72, v27, v14
	v_max3_f32 v73, v73, v16, v17
	v_max3_f32 v72, v72, v15, v30
	v_max3_f32 v73, v73, v32, v33
	v_max3_f32 v72, v72, v31, v73
	v_mov_b32_e32 v73, v72
	s_nop 1
	v_permlane32_swap_b32_e32 v72, v73
	v_max_f32_e32 v73, v73, v73
	v_max_f32_e32 v72, v72, v72
	v_mfma_f32_32x32x16_bf16 v[34:49], v[80:83], v[110:113], v[34:49]
	v_max_f32_e32 v80, v72, v73
	v_sub_f32_e32 v82, v2, v80
	v_sub_f32_e32 v88, v5, v80
	v_sub_f32_e32 v6, v6, v80
	v_sub_f32_e32 v7, v7, v80
	v_sub_f32_e32 v8, v8, v80
	v_sub_f32_e32 v9, v9, v80
	v_mfma_f32_32x32x16_bf16 v[52:67], v[84:87], v[110:113], v[52:67]
	v_sub_f32_e32 v84, v3, v80
	v_sub_f32_e32 v86, v4, v80
	v_exp_f32_e32 v114, v82
	v_exp_f32_e32 v96, v84
	v_exp_f32_e32 v94, v86
	v_exp_f32_e32 v92, v88
	v_exp_f32_e32 v90, v6
	v_exp_f32_e32 v88, v7
	v_exp_f32_e32 v86, v8
	v_exp_f32_e32 v84, v9
	v_sub_f32_e32 v91, v22, v80
	v_sub_f32_e32 v117, v23, v80
	v_sub_f32_e32 v119, v24, v80
	v_sub_f32_e32 v121, v25, v80
	v_lshrrev_b32_e32 v2, 2, v76
	v_and_b32_e32 v3, 16, v76
	v_lshlrev_b32_e32 v4, 2, v162
	v_cvt_pk_bf16_f32 v22, v114, v96
	v_cvt_pk_bf16_f32 v23, v94, v92
	v_cvt_pk_bf16_f32 v24, v90, v88
	v_cvt_pk_bf16_f32 v25, v86, v84
	v_and_or_b32 v81, v2, 3, v147
	v_and_or_b32 v3, v4, 12, v3
	v_mad_u32_u24 v2, v81, s3, 0
	v_lshlrev_b32_e32 v176, 1, v3
	v_sub_f32_e32 v10, v10, v80
	v_sub_f32_e32 v123, v26, v80
	v_sub_f32_e32 v11, v11, v80
	v_sub_f32_e32 v125, v27, v80
	v_sub_f32_e32 v12, v12, v80
	v_sub_f32_e32 v127, v28, v80
	v_sub_f32_e32 v13, v13, v80
	v_sub_f32_e32 v14, v14, v80
	v_sub_f32_e32 v26, v15, v80
	v_sub_f32_e32 v27, v16, v80
	v_sub_f32_e32 v28, v17, v80
	v_add_u32_e32 v164, v2, v176
	v_sub_f32_e32 v83, v18, v80
	v_sub_f32_e32 v85, v19, v80
	v_sub_f32_e32 v87, v20, v80
	v_sub_f32_e32 v89, v21, v80
	ds_read_b64_tr_b16 v[2:3], v164 offset:9216
	ds_read_b64_tr_b16 v[4:5], v164 offset:10752
	ds_read_b64_tr_b16 v[20:21], v164 offset:10816
	ds_read_b64_tr_b16 v[18:19], v164 offset:9280
	ds_read_b64_tr_b16 v[72:73], v164 offset:12288
	ds_read_b64_tr_b16 v[74:75], v164 offset:13824
	ds_read_b64_tr_b16 v[132:133], v164 offset:13888
	ds_read_b64_tr_b16 v[130:131], v164 offset:12352
	v_exp_f32_e32 v82, v10
	v_exp_f32_e32 v122, v11
	v_exp_f32_e32 v120, v12
	v_exp_f32_e32 v118, v13
	v_exp_f32_e32 v116, v14
	v_exp_f32_e32 v128, v26
	v_exp_f32_e32 v126, v27
	v_exp_f32_e32 v124, v28
	v_sub_f32_e32 v129, v29, v80
	v_sub_f32_e32 v148, v30, v80
	v_sub_f32_e32 v149, v31, v80
	v_sub_f32_e32 v150, v32, v80
	v_sub_f32_e32 v151, v33, v80
	s_waitcnt lgkmcnt(0)
; __device__ __forceinline__ unsigned cvt_pk_bf16(float lo, float hi) { const f32x2 v = {lo, hi}; const bf16x2_t b = __builtin_convertvector(v, bf16x2_t); return __builtin_bit_cast(unsigned, b); }
; __device__ __forceinline__ float fast_exp2(float x) { return __builtin_amdgcn_exp2f(x); }
; template <int NDT, int VSTR> ...
;     ...
;     for (int r = 0; r < 16; ++r) { p0[r] = fast_exp2(p0[r]); p1[r] = fast_exp2(p1[r]); rs0 += p0[r]; rs1 += p1[r]; }
;     lrun += rs0 + rs1;
;     bf16x8 pa[4];
; #pragma unroll
;     for (int s = 0; s < 2; ++s) {
;         u32x4 w0, w1;
;         w0.x = cvt_pk_bf16(p0[8 * s + 0], p0[8 * s + 1]); w0.y = cvt_pk_bf16(p0[8 * s + 2], p0[8 * s + 3]); w0.z = cvt_pk_bf16(p0[8 * s + 4], p0[8 * s + 5]); w0.w = cvt_pk_bf16(p0[8 * s + 6], p0[8 * s + 7]);
;         w1.x = cvt_pk_bf16(p1[8 * s + 0], p1[8 * s + 1]); w1.y = cvt_pk_bf16(p1[8 * s + 2], p1[8 * s + 3]); w1.z = cvt_pk_bf16(p1[8 * s + 4], p1[8 * s + 5]); w1.w = cvt_pk_bf16(p1[8 * s + 6], p1[8 * s + 7]);
;         pa[s] = __builtin_bit_cast(bf16x8, w0); pa[2 + s] = __builtin_bit_cast(bf16x8, w1);
;     }
; #pragma unroll
;     for (int s = 0; s < 4; ++s) {
;         bf16x8 vw[NDT];
; #pragma unroll
;         for (int d = 0; d < NDT; ++d) { if (s < PRE) vw[d] = vpre[s < PRE ? s : 0][d]; else vw[d] = VFRAG(s, d); }
; #pragma unroll
;         for (int d = 0; d < NDT; ++d) o[d] = __builtin_amdgcn_mfma_f32_32x32x16_bf16(pa[s], vw[d], o[d], 0, 0, 0);
; __device__ __forceinline__ void fox_unit(const Params& P, int b, int h, int qb, LAS unsigned char* lds, bool dry = false) {
;     ...
;     if (t + 1 <= NT - 6) rmc = rowmax32(n0, n1);
	v_mfma_f32_32x32x16_bf16 v[2:17], v[22:25], v[2:5], 0
	v_cvt_pk_bf16_f32 v134, v82, v122
	v_cvt_pk_bf16_f32 v135, v120, v118
	v_cvt_pk_bf16_f32 v136, v116, v128
	v_cvt_pk_bf16_f32 v137, v126, v124
	v_exp_f32_e32 v115, v83
	v_exp_f32_e32 v97, v85
	v_exp_f32_e32 v95, v87
	v_mfma_f32_32x32x16_bf16 v[18:33], v[22:25], v[18:21], 0
	v_exp_f32_e32 v93, v89
	v_exp_f32_e32 v91, v91
	v_exp_f32_e32 v89, v117
	v_exp_f32_e32 v87, v119
	v_exp_f32_e32 v85, v121
	ds_read_b64_tr_b16 v[138:139], v164 offset:15360
	ds_read_b64_tr_b16 v[140:141], v164 offset:16896
	ds_read_b64_tr_b16 v[144:145], v164 offset:16960
	ds_read_b64_tr_b16 v[142:143], v164 offset:15424
	v_exp_f32_e32 v83, v123
	v_mfma_f32_32x32x16_bf16 v[2:17], v[134:137], v[72:75], v[2:17]
	v_cvt_pk_bf16_f32 v72, v115, v97
	v_cvt_pk_bf16_f32 v73, v95, v93
	v_cvt_pk_bf16_f32 v74, v91, v89
	v_cvt_pk_bf16_f32 v75, v87, v85
	v_exp_f32_e32 v123, v125
	v_exp_f32_e32 v121, v127
	v_exp_f32_e32 v119, v129
	v_mfma_f32_32x32x16_bf16 v[18:33], v[134:137], v[130:133], v[18:33]
	ds_read_b64_tr_b16 v[130:131], v164 offset:18432
	ds_read_b64_tr_b16 v[132:133], v164 offset:19968
	v_exp_f32_e32 v117, v148
	v_exp_f32_e32 v129, v149
	v_exp_f32_e32 v127, v150
	v_exp_f32_e32 v125, v151
	v_cvt_pk_bf16_f32 v134, v83, v123
	v_cvt_pk_bf16_f32 v135, v121, v119
	s_waitcnt lgkmcnt(0)
	v_mfma_f32_32x32x16_bf16 v[2:17], v[72:75], v[138:141], v[2:17]
	ds_read_b64_tr_b16 v[140:141], v164 offset:20032
	ds_read_b64_tr_b16 v[138:139], v164 offset:18496
	v_cvt_pk_bf16_f32 v136, v117, v129
	v_cvt_pk_bf16_f32 v137, v127, v125
	v_mfma_f32_32x32x16_bf16 v[18:33], v[72:75], v[142:145], v[18:33]
	global_load_dwordx4 v[72:75], v[50:51], off
	s_waitcnt vmcnt(0)
	ds_write_b128 v169, v[68:71]
	v_mfma_f32_32x32x16_bf16 v[2:17], v[134:137], v[130:133], v[2:17]
	s_waitcnt lgkmcnt(0)
	v_mfma_f32_32x32x16_bf16 v[18:33], v[134:137], v[138:141], v[18:33]
	s_and_saveexec_b64 s[8:9], s[6:7]
	ds_write_b32 v177, v165 offset:21504
	s_or_b64 exec, exec, s[8:9]
	v_pk_add_f32 v[50:51], v[34:35], v[80:81] op_sel_hi:[1,0] neg_lo:[0,1] neg_hi:[0,1]
	v_pk_add_f32 v[34:35], v[52:53], v[80:81] op_sel_hi:[1,0] neg_lo:[0,1] neg_hi:[0,1]
	v_pk_add_f32 v[52:53], v[36:37], v[80:81] op_sel_hi:[1,0] neg_lo:[0,1] neg_hi:[0,1]
	v_pk_add_f32 v[36:37], v[54:55], v[80:81] op_sel_hi:[1,0] neg_lo:[0,1] neg_hi:[0,1]
	v_pk_add_f32 v[54:55], v[38:39], v[80:81] op_sel_hi:[1,0] neg_lo:[0,1] neg_hi:[0,1]
	v_pk_add_f32 v[38:39], v[56:57], v[80:81] op_sel_hi:[1,0] neg_lo:[0,1] neg_hi:[0,1]
	v_pk_add_f32 v[56:57], v[40:41], v[80:81] op_sel_hi:[1,0] neg_lo:[0,1] neg_hi:[0,1]
	v_pk_add_f32 v[40:41], v[58:59], v[80:81] op_sel_hi:[1,0] neg_lo:[0,1] neg_hi:[0,1]
	v_pk_add_f32 v[58:59], v[42:43], v[80:81] op_sel_hi:[1,0] neg_lo:[0,1] neg_hi:[0,1]
	v_pk_add_f32 v[42:43], v[60:61], v[80:81] op_sel_hi:[1,0] neg_lo:[0,1] neg_hi:[0,1]
	v_pk_add_f32 v[60:61], v[44:45], v[80:81] op_sel_hi:[1,0] neg_lo:[0,1] neg_hi:[0,1]
	v_pk_add_f32 v[44:45], v[62:63], v[80:81] op_sel_hi:[1,0] neg_lo:[0,1] neg_hi:[0,1]
	v_pk_add_f32 v[62:63], v[46:47], v[80:81] op_sel_hi:[1,0] neg_lo:[0,1] neg_hi:[0,1]
	v_pk_add_f32 v[46:47], v[64:65], v[80:81] op_sel_hi:[1,0] neg_lo:[0,1] neg_hi:[0,1]
	v_pk_add_f32 v[64:65], v[48:49], v[80:81] op_sel_hi:[1,0] neg_lo:[0,1] neg_hi:[0,1]
	v_pk_add_f32 v[48:49], v[66:67], v[80:81] op_sel_hi:[1,0] neg_lo:[0,1] neg_hi:[0,1]
	v_pk_add_f32 v[66:67], v[114:115], 0 op_sel_hi:[1,0]
	v_mul_lo_u32 v178, v78, s3
	v_pk_add_f32 v[66:67], v[96:97], v[66:67]
	s_lshl_b64 s[14:15], s[4:5], 21
	v_pk_add_f32 v[66:67], v[94:95], v[66:67]
	v_mov_b32_e32 v153, v0
	v_pk_add_f32 v[66:67], v[92:93], v[66:67]
	s_lshl_b64 s[4:5], s[4:5], 16
	v_pk_add_f32 v[66:67], v[90:91], v[66:67]
	s_and_b32 s3, s12, 0x3fffffc0
	v_pk_add_f32 v[66:67], v[88:89], v[66:67]
	s_lshl_b32 s3, s3, 2
	v_pk_add_f32 v[66:67], v[86:87], v[66:67]
	s_add_i32 s3, s3, 0
	v_pk_add_f32 v[66:67], v[84:85], v[66:67]
	s_lshl_b32 s46, s13, 2
	v_pk_add_f32 v[66:67], v[82:83], v[66:67]
	v_mul_u32_u24_e32 v174, 0x90, v162
	v_pk_add_f32 v[66:67], v[122:123], v[66:67]
	v_mul_u32_u24_e32 v175, 0xc0, v81
	v_pk_add_f32 v[66:67], v[120:121], v[66:67]
	s_add_i32 s10, s46, -2
	v_pk_add_f32 v[66:67], v[118:119], v[66:67]
	v_cmp_eq_u32_e64 s[8:9], 0, v1
	v_pk_add_f32 v[66:67], v[116:117], v[66:67]
	v_lshl_add_u32 v166, v162, 2, s3
	v_pk_add_f32 v[66:67], v[128:129], v[66:67]
	s_mov_b32 s58, 4
	v_pk_add_f32 v[66:67], v[126:127], v[66:67]
	s_sub_i32 s72, 0x100, s56
	v_pk_add_f32 v[66:67], v[124:125], v[66:67]
	s_mov_b32 s11, -1
	v_pk_add_f32 v[66:67], v[66:67], v[66:67] op_sel:[0,1] op_sel_hi:[1,0]
	s_nop 0
	v_mov_b32_e32 v67, v80
	v_pk_add_f32 v[148:149], v[66:67], 0 op_sel_hi:[1,0]
	v_add_u32_e32 v66, 0, v178
	v_add_u32_e32 v179, v66, v152
	v_max_f32_e32 v66, v50, v51
	v_max3_f32 v67, v52, v53, v35
	v_max3_f32 v66, v66, v34, v36
	v_max3_f32 v66, v66, v37, v54
	v_max3_f32 v67, v67, v56, v57
	v_max3_f32 v66, v66, v55, v38
	v_max3_f32 v67, v67, v40, v41
	v_max3_f32 v66, v66, v39, v58
	v_max3_f32 v67, v67, v60, v61
	v_max3_f32 v66, v66, v59, v42
	v_max3_f32 v67, v67, v44, v45
	v_max3_f32 v66, v66, v43, v62
	v_max3_f32 v67, v67, v64, v65
	v_max3_f32 v66, v66, v63, v46
	v_max3_f32 v67, v67, v48, v49
	v_max3_f32 v66, v66, v47, v67
	v_mov_b32_e32 v67, v66
	s_nop 1
	v_permlane32_swap_b32_e32 v66, v67
	v_max_f32_e32 v67, v67, v67
	v_max_f32_e32 v66, v66, v66
	v_max_f32_e32 v122, v66, v67
	v_lshlrev_b64 v[66:67], 10, v[78:79]
	v_lshl_add_u64 v[66:67], s[14:15], 0, v[66:67]
	v_or_b32_e32 v66, s74, v66
	v_lshl_add_u64 v[154:155], v[66:67], 0, v[152:153]
	v_lshlrev_b64 v[66:67], 5, v[76:77]
	v_lshl_add_u64 v[156:157], s[4:5], 0, v[66:67]
	s_add_i32 s4, s56, s57
	s_addk_i32 s4, 0xff00
	v_or_b32_e32 v156, s73, v156
	v_add_u32_e32 v153, s4, v162
	s_mov_b64 s[4:5], 0x1000
	v_lshl_add_u64 v[150:151], v[156:157], 0, s[4:5]
	s_mov_b32 s73, 6
	ds_write_b128 v179, v[72:75] offset:30976
	s_waitcnt lgkmcnt(0)
	s_barrier
; #define LAS __attribute__((address_space(3)))
; __device__ __forceinline__ float fast_exp2(float x) { return __builtin_amdgcn_exp2f(x); }
; __device__ __forceinline__ void fox_steady_step(f32x16& s0, f32x16& s1, f32x16& n0, f32x16& n1, const LAS unsigned char* kb, int coff, const LAS unsigned char* Vt, ...
;     const float rm = rmc;
;     if (__any(rm > 8.0f)) {
;         const float dl = fmaxf(rm, 0.f);
;         mref += dl;
; #pragma unroll
;         for (int r = 0; r < 16; ++r) { s0[r] -= dl; s1[r] -= dl; }
;         const float alpha = fast_exp2(-dl);
;         lrun *= alpha;
;         if (hi == 0) wsf[r32] = alpha;
;         asm volatile("s_waitcnt lgkmcnt(0)" ::: "memory");
; #pragma unroll
;         for (int jj = 0; jj < 4; ++jj) { const f32x4 al = *(const LAS f32x4*)(wsf + 8 * jj + 4 * hi);
; #pragma unroll
;             for (int d = 0; d < 2; ++d) { o[d][4 * jj + 0] *= al.x; o[d][4 * jj + 1] *= al.y; o[d][4 * jj + 2] *= al.z; o[d][4 * jj + 3] *= al.w; } }
;         asm volatile("s_waitcnt lgkmcnt(0)" ::: "memory");
;     }
;     bf16x8 kf[8]; f32x4 ck4[8]; bf16x8 vf[4][2];
; #pragma unroll
;     for (int d0 = 0; d0 < 4; ++d0) { kf[2 * d0] = *(const LAS bf16x8*)(kb + r32 * 144 + d0 * 32 + hi * 16); kf[2 * d0 + 1] = *(const LAS bf16x8*)(kb + (r32 + 32) * 144 + d0 * 32 + hi * 16); }
; #pragma unroll
;     for (int jj = 0; jj < 4; ++jj) { ck4[jj] = *(const LAS f32x4*)(kb + coff + (8 * jj + 4 * hi) * 4); ck4[4 + jj] = *(const LAS f32x4*)(kb + coff + (32 + 8 * jj + 4 * hi) * 4); }
;     { const int lane_ = hi * 32 + r32;
;       const LAS unsigned char* vb = Vt + (4 * hi + ((lane_ & 15) >> 2)) * 192 + (16 * ((lane_ >> 4) & 1) + 4 * (lane_ & 3)) * 2;
; #pragma unroll
;       for (int s = 0; s < 4; ++s)
; #pragma unroll
;           for (int d = 0; d < 2; ++d) {
;               const s16x4 lo_ = __builtin_bit_cast(s16x4, __builtin_amdgcn_ds_read_tr16_b64_v4i16((LAS s16x4*)(vb + (16 * s) * 192 + 64 * d)));
;               const s16x4 hh_ = __builtin_bit_cast(s16x4, __builtin_amdgcn_ds_read_tr16_b64_v4i16((LAS s16x4*)(vb + (16 * s + 8) * 192 + 64 * d)));
;               vf[s][d] = (bf16x8){lo_[0], lo_[1], lo_[2], lo_[3], hh_[0], hh_[1], hh_[2], hh_[3]}; } }
.LBB0_694:
	v_lshl_add_u64 v[158:159], s[52:53], 0, v[154:155]
	v_add_co_u32_e32 v66, vcc, 0x16e30000, v158
	v_lshl_add_u64 v[160:161], s[52:53], 0, v[156:157]
	s_nop 0
	v_addc_co_u32_e32 v67, vcc, 0, v159, vcc
	global_load_dwordx4 v[114:117], v[66:67], off
	s_and_saveexec_b64 s[4:5], s[6:7]
	s_cbranch_execz .LBB0_696
	v_add_co_u32_e32 v66, vcc, 0x2c01000, v160
	s_nop 1
	v_addc_co_u32_e32 v67, vcc, 0, v161, vcc
	global_load_dword v165, v[66:67], off offset:2048
.LBB0_696:
	s_or_b64 exec, exec, s[4:5]
	v_add_co_u32_e32 v66, vcc, 0x18e20000, v158
	s_nop 1
	v_addc_co_u32_e32 v67, vcc, 0, v159, vcc
	global_load_dwordx4 v[118:121], v[66:67], off
	v_cmp_lt_f32_e32 vcc, s67, v122
	s_cbranch_vccz .LBB0_700
	v_max_f32_e32 v66, v122, v122
	v_max_f32_e32 v67, 0, v66
	v_exp_f32_e64 v66, -v67
	s_and_saveexec_b64 s[4:5], s[8:9]
	ds_write_b32 v166, v66 offset:43520
	s_or_b64 exec, exec, s[4:5]
	v_sub_f32_e32 v65, v65, v67
	v_sub_f32_e32 v64, v64, v67
	v_sub_f32_e32 v63, v63, v67
	v_sub_f32_e32 v62, v62, v67
	v_sub_f32_e32 v61, v61, v67
	v_sub_f32_e32 v60, v60, v67
	v_sub_f32_e32 v59, v59, v67
	v_sub_f32_e32 v58, v58, v67
	v_sub_f32_e32 v57, v57, v67
	v_sub_f32_e32 v56, v56, v67
	v_sub_f32_e32 v55, v55, v67
	v_sub_f32_e32 v54, v54, v67
	v_sub_f32_e32 v53, v53, v67
	v_sub_f32_e32 v52, v52, v67
	v_sub_f32_e32 v51, v51, v67
	v_sub_f32_e32 v50, v50, v67
	v_sub_f32_e32 v49, v49, v67
	v_sub_f32_e32 v48, v48, v67
	v_sub_f32_e32 v47, v47, v67
	v_sub_f32_e32 v46, v46, v67
	v_sub_f32_e32 v45, v45, v67
	v_sub_f32_e32 v44, v44, v67
	v_sub_f32_e32 v43, v43, v67
	v_sub_f32_e32 v42, v42, v67
	v_sub_f32_e32 v41, v41, v67
	v_sub_f32_e32 v40, v40, v67
	v_sub_f32_e32 v39, v39, v67
	v_sub_f32_e32 v38, v38, v67
	v_sub_f32_e32 v37, v37, v67
	v_sub_f32_e32 v36, v36, v67
	v_sub_f32_e32 v35, v35, v67
	v_sub_f32_e32 v34, v34, v67
	v_add_f32_e32 v149, v67, v149
	s_waitcnt lgkmcnt(0)
	v_add_u32_e32 v67, s3, v146
	ds_read_b128 v[68:71], v67 offset:43520
	ds_read_b128 v[72:75], v67 offset:43552
	ds_read_b128 v[76:79], v67 offset:43584
	ds_read_b128 v[80:83], v67 offset:43616
	s_waitcnt lgkmcnt(0)
	s_waitcnt lgkmcnt(0)
	v_pk_mul_f32 v[4:5], v[4:5], v[70:71]
	v_pk_mul_f32 v[6:7], v[6:7], v[72:73]
	v_pk_mul_f32 v[10:11], v[10:11], v[76:77]
	v_pk_mul_f32 v[14:15], v[14:15], v[80:81]
	v_pk_mul_f32 v[16:17], v[16:17], v[82:83]
	v_pk_mul_f32 v[12:13], v[12:13], v[78:79]
	v_pk_mul_f32 v[8:9], v[8:9], v[74:75]
	v_pk_mul_f32 v[2:3], v[2:3], v[68:69]
	v_pk_mul_f32 v[30:31], v[30:31], v[80:81]
	v_pk_mul_f32 v[26:27], v[26:27], v[76:77]
	v_pk_mul_f32 v[22:23], v[22:23], v[72:73]
	v_pk_mul_f32 v[32:33], v[32:33], v[82:83]
	v_pk_mul_f32 v[28:29], v[28:29], v[78:79]
	v_pk_mul_f32 v[24:25], v[24:25], v[74:75]
	v_pk_mul_f32 v[20:21], v[20:21], v[70:71]
	v_pk_mul_f32 v[18:19], v[18:19], v[68:69]
	v_mul_f32_e32 v148, v66, v148
.LBB0_700:
	ds_read_b128 v[182:185], v173
	ds_read_b128 v[188:191], v173 offset:32
	ds_read_b128 v[192:195], v173 offset:4608
	ds_read_b128 v[196:199], v173 offset:4640
	ds_read_b128 v[200:203], v173 offset:64
	ds_read_b128 v[204:207], v173 offset:96
	ds_read_b128 v[208:211], v173 offset:4672
	ds_read_b128 v[212:215], v173 offset:4704
	ds_read_b128 v[66:69], v172 offset:21504
	ds_read_b128 v[70:73], v172 offset:21536
	ds_read_b128 v[82:85], v172 offset:21632
	ds_read_b128 v[86:89], v172 offset:21664
	ds_read_b128 v[74:77], v172 offset:21568
	ds_read_b128 v[78:81], v172 offset:21600
	ds_read_b128 v[90:93], v172 offset:21696
	ds_read_b128 v[94:97], v172 offset:21728
	ds_read_b64_tr_b16 v[226:227], v164 offset:30976
	ds_read_b64_tr_b16 v[228:229], v164 offset:32512
	ds_read_b64_tr_b16 v[234:235], v164 offset:32576
	ds_read_b64_tr_b16 v[232:233], v164 offset:31040
	ds_read_b64_tr_b16 v[142:143], v164 offset:34048
	ds_read_b64_tr_b16 v[144:145], v164 offset:35584
	ds_read_b64_tr_b16 v[140:141], v164 offset:35648
	ds_read_b64_tr_b16 v[138:139], v164 offset:34112
	ds_read_b64_tr_b16 v[134:135], v164 offset:37120
	ds_read_b64_tr_b16 v[136:137], v164 offset:38656
	ds_read_b64_tr_b16 v[132:133], v164 offset:38720
	ds_read_b64_tr_b16 v[130:131], v164 offset:37184
	ds_read_b64_tr_b16 v[126:127], v164 offset:40192
	ds_read_b64_tr_b16 v[128:129], v164 offset:41728
	ds_read_b64_tr_b16 v[124:125], v164 offset:41792
	ds_read_b64_tr_b16 v[122:123], v164 offset:40256
	v_sub_f32_e32 v186, v163, v149
	s_waitcnt lgkmcnt(0)
; #define SBAR_() __builtin_amdgcn_sched_barrier(0)
; __device__ __forceinline__ void fox_steady_step(f32x16& s0, f32x16& s1, f32x16& n0, f32x16& n1, const LAS unsigned char* kb, int coff, const LAS unsigned char* Vt, ...
;     ...
;     { const float cqm = cq - mref;
; #pragma unroll
;       for (int jj = 0; jj < 4; ++jj)
; #pragma unroll
;           for (int e = 0; e < 4; ++e) { n0[4 * jj + e] = cqm - ck4[jj][e]; n1[4 * jj + e] = cqm - ck4[4 + jj][e]; } }
;     SBAR_();
;     float rs = 0.f; u32x4 w0, w1, w2, w3;
;     ...
;     n0 = __builtin_amdgcn_mfma_f32_32x32x16_bf16(kf[0], qf[0], n0, 0, 0, 0); EXPN_(s0, 0, 3); SBAR_();
;     n1 = __builtin_amdgcn_mfma_f32_32x32x16_bf16(kf[1], qf[0], n1, 0, 0, 0); EXPN_(s0, 3, 3); w0.x = cvt_pk_bf16(s0[0], s0[1]); w0.y = cvt_pk_bf16(s0[2], s0[3]); SBAR_();
;     n0 = __builtin_amdgcn_mfma_f32_32x32x16_bf16(kf[2], qf[1], n0, 0, 0, 0); EXPN_(s0, 6, 3); w0.z = cvt_pk_bf16(s0[4], s0[5]); w0.w = cvt_pk_bf16(s0[6], s0[7]); SBAR_();
;     n1 = __builtin_amdgcn_mfma_f32_32x32x16_bf16(kf[3], qf[1], n1, 0, 0, 0); EXPN_(s0, 9, 3); w1.x = cvt_pk_bf16(s0[8], s0[9]); w1.y = cvt_pk_bf16(s0[10], s0[11]); SBAR_();
;     n0 = __builtin_amdgcn_mfma_f32_32x32x16_bf16(kf[4], qf[2], n0, 0, 0, 0); EXPN_(s0, 12, 4); w1.z = cvt_pk_bf16(s0[12], s0[13]); w1.w = cvt_pk_bf16(s0[14], s0[15]); SBAR_();
;     n1 = __builtin_amdgcn_mfma_f32_32x32x16_bf16(kf[5], qf[2], n1, 0, 0, 0); EXPN_(s1, 0, 3); SBAR_();
;     n0 = __builtin_amdgcn_mfma_f32_32x32x16_bf16(kf[6], qf[3], n0, 0, 0, 0); EXPN_(s1, 3, 3); w2.x = cvt_pk_bf16(s1[0], s1[1]); w2.y = cvt_pk_bf16(s1[2], s1[3]); SBAR_();
;     n1 = __builtin_amdgcn_mfma_f32_32x32x16_bf16(kf[7], qf[3], n1, 0, 0, 0); EXPN_(s1, 6, 2); w2.z = cvt_pk_bf16(s1[4], s1[5]); w2.w = cvt_pk_bf16(s1[6], s1[7]); SBAR_();
;     const bf16x8 pa0 = __builtin_bit_cast(bf16x8, w0), pa1 = __builtin_bit_cast(bf16x8, w1), pa2 = __builtin_bit_cast(bf16x8, w2);
;     float ra = fmaxf(fmaxf(n0[0], n0[1]), n1[0]), rb = fmaxf(fmaxf(n0[2], n0[3]), n1[1]);
;     o[0] = __builtin_amdgcn_mfma_f32_32x32x16_bf16(pa0, vf[0][0], o[0], 0, 0, 0); EXPN_(s1, 8, 2); ra = fmaxf(fmaxf(ra, n1[2]), n1[3]); SBAR_();
;     o[1] = __builtin_amdgcn_mfma_f32_32x32x16_bf16(pa0, vf[0][1], o[1], 0, 0, 0); EXPN_(s1, 10, 2); w3.x = cvt_pk_bf16(s1[8], s1[9]); rb = fmaxf(fmaxf(rb, n0[4]), n0[5]); SBAR_();
	v_sub_f32_e32 v81, v186, v81
	v_sub_f32_e32 v80, v186, v80
	v_sub_f32_e32 v79, v186, v79
	v_sub_f32_e32 v78, v186, v78
	v_sub_f32_e32 v77, v186, v77
	v_sub_f32_e32 v76, v186, v76
	v_sub_f32_e32 v75, v186, v75
	v_sub_f32_e32 v74, v186, v74
	v_sub_f32_e32 v73, v186, v73
	v_sub_f32_e32 v72, v186, v72
	v_sub_f32_e32 v71, v186, v71
	v_sub_f32_e32 v70, v186, v70
	v_sub_f32_e32 v69, v186, v69
	v_sub_f32_e32 v68, v186, v68
	v_sub_f32_e32 v67, v186, v67
	v_sub_f32_e32 v66, v186, v66
	v_sub_f32_e32 v97, v186, v97
	v_sub_f32_e32 v96, v186, v96
	v_sub_f32_e32 v95, v186, v95
	v_sub_f32_e32 v94, v186, v94
	v_sub_f32_e32 v93, v186, v93
	v_sub_f32_e32 v92, v186, v92
	v_sub_f32_e32 v91, v186, v91
	v_sub_f32_e32 v90, v186, v90
	v_sub_f32_e32 v89, v186, v89
	v_sub_f32_e32 v88, v186, v88
	v_sub_f32_e32 v87, v186, v87
	v_sub_f32_e32 v86, v186, v86
	v_sub_f32_e32 v85, v186, v85
	v_sub_f32_e32 v84, v186, v84
	v_sub_f32_e32 v83, v186, v83
	v_sub_f32_e32 v82, v186, v82
	v_mfma_f32_32x32x16_bf16 v[66:81], v[182:185], v[98:101], v[66:81]
	v_exp_f32_e32 v50, v50
	v_exp_f32_e32 v51, v51
	v_exp_f32_e32 v52, v52
	v_mfma_f32_32x32x16_bf16 v[82:97], v[192:195], v[98:101], v[82:97]
	v_exp_f32_e32 v53, v53
	v_exp_f32_e32 v54, v54
	v_exp_f32_e32 v55, v55
	v_cvt_pk_bf16_f32 v182, v50, v51
	v_cvt_pk_bf16_f32 v183, v52, v53
	v_mfma_f32_32x32x16_bf16 v[66:81], v[188:191], v[102:105], v[66:81]
	v_exp_f32_e32 v56, v56
	v_exp_f32_e32 v57, v57
	v_exp_f32_e32 v58, v58
	v_cvt_pk_bf16_f32 v184, v54, v55
	v_cvt_pk_bf16_f32 v185, v56, v57
	v_mfma_f32_32x32x16_bf16 v[82:97], v[196:199], v[102:105], v[82:97]
	v_exp_f32_e32 v59, v59
	v_exp_f32_e32 v60, v60
	v_exp_f32_e32 v61, v61
	v_cvt_pk_bf16_f32 v188, v58, v59
	v_cvt_pk_bf16_f32 v189, v60, v61
	v_mfma_f32_32x32x16_bf16 v[66:81], v[200:203], v[106:109], v[66:81]
	v_exp_f32_e32 v62, v62
	v_exp_f32_e32 v63, v63
	v_exp_f32_e32 v64, v64
	v_exp_f32_e32 v65, v65
	v_cvt_pk_bf16_f32 v190, v62, v63
	v_cvt_pk_bf16_f32 v191, v64, v65
	v_mfma_f32_32x32x16_bf16 v[82:97], v[208:211], v[106:109], v[82:97]
	v_exp_f32_e32 v34, v34
	v_exp_f32_e32 v35, v35
	v_exp_f32_e32 v36, v36
	v_mfma_f32_32x32x16_bf16 v[66:81], v[204:207], v[110:113], v[66:81]
	v_exp_f32_e32 v37, v37
	v_exp_f32_e32 v38, v38
	v_exp_f32_e32 v39, v39
	v_mfma_f32_32x32x16_bf16 v[82:97], v[212:215], v[110:113], v[82:97]
	v_exp_f32_e32 v40, v40
	v_exp_f32_e32 v41, v41
	v_mfma_f32_32x32x16_bf16 v[2:17], v[182:185], v[226:229], v[2:17]
	v_exp_f32_e32 v42, v42
	v_exp_f32_e32 v43, v43
	v_mfma_f32_32x32x16_bf16 v[18:33], v[182:185], v[232:235], v[18:33]
	v_exp_f32_e32 v44, v44
	v_exp_f32_e32 v45, v45
	v_mfma_f32_32x32x16_bf16 v[2:17], v[188:191], v[142:145], v[2:17]
	v_exp_f32_e32 v46, v46
	v_exp_f32_e32 v47, v47
	v_mfma_f32_32x32x16_bf16 v[18:33], v[188:191], v[138:141], v[18:33]
	v_max_f32_e32 v138, v67, v67
	v_max_f32_e32 v139, v66, v66
	v_exp_f32_e32 v48, v48
	v_exp_f32_e32 v49, v49
	v_max_f32_e32 v138, v139, v138
	v_max3_f32 v138, v138, v82, v84
	v_max3_f32 v182, v138, v85, v72
	v_max3_f32 v138, v68, v69, v83
	v_max3_f32 v141, v138, v70, v71
	v_cvt_pk_bf16_f32 v139, v44, v45
	v_cvt_pk_bf16_f32 v138, v42, v43
	v_cvt_pk_bf16_f32 v145, v40, v41
	v_cvt_pk_bf16_f32 v144, v38, v39
	v_cvt_pk_bf16_f32 v143, v36, v37
	v_cvt_pk_bf16_f32 v142, v34, v35
	v_cvt_pk_bf16_f32 v140, v46, v47
	v_max3_f32 v183, v141, v86, v87
	v_mfma_f32_32x32x16_bf16 v[2:17], v[142:145], v[134:137], v[2:17]
	v_cvt_pk_bf16_f32 v141, v48, v49
	v_max3_f32 v134, v182, v73, v88
	v_max3_f32 v135, v183, v74, v75
	v_mfma_f32_32x32x16_bf16 v[18:33], v[142:145], v[130:133], v[18:33]
	v_max3_f32 v130, v134, v89, v76
	v_max3_f32 v131, v135, v90, v91
	v_max3_f32 v130, v130, v77, v92
	v_max3_f32 v131, v131, v78, v79
	v_mfma_f32_32x32x16_bf16 v[2:17], v[138:141], v[126:129], v[2:17]
	v_max3_f32 v126, v130, v93, v80
	v_max3_f32 v127, v131, v94, v95
	v_max3_f32 v126, v126, v81, v96
	v_mfma_f32_32x32x16_bf16 v[18:33], v[138:141], v[122:125], v[18:33]
	v_max3_f32 v122, v126, v97, v127
	v_mov_b32_e32 v123, v122
	s_nop 1
	v_permlane32_swap_b32_e32 v122, v123
	s_waitcnt vmcnt(0)
	ds_write_b128 v171, v[114:117] offset:21760
	s_and_saveexec_b64 s[4:5], s[6:7]
	ds_write_b32 v177, v165 offset:43264
	s_or_b64 exec, exec, s[4:5]
	v_add_co_u32_e32 v114, vcc, 0x16e40000, v158
	ds_write_b128 v170, v[118:121] offset:9216
	s_nop 0
	v_addc_co_u32_e32 v115, vcc, 0, v159, vcc
	s_waitcnt lgkmcnt(0)
	s_barrier
	global_load_dwordx4 v[114:117], v[114:115], off
	s_and_saveexec_b64 s[4:5], s[6:7]
	s_cbranch_execz .LBB0_704
	v_add_co_u32_e32 v118, vcc, 0x2c02000, v160
	s_nop 1
	v_addc_co_u32_e32 v119, vcc, 0, v161, vcc
	global_load_dword v165, v[118:119], off
; #define LAS __attribute__((address_space(3)))
; __device__ __forceinline__ float fast_exp2(float x) { return __builtin_amdgcn_exp2f(x); }
; __device__ __forceinline__ float half_max(float v) { auto rr = __builtin_amdgcn_permlane32_swap(__float_as_uint(v), __float_as_uint(v), false, false); return fmaxf(__uint_as_float(rr[0]), __uint_as_float(rr[1])); }
; #define SBAR_() __builtin_amdgcn_sched_barrier(0)
; __device__ __forceinline__ void fox_steady_step(f32x16& s0, f32x16& s1, f32x16& n0, f32x16& n1, const LAS unsigned char* kb, int coff, const LAS unsigned char* Vt, ...
;     const float rm = rmc;
;     if (__any(rm > 8.0f)) {
;         const float dl = fmaxf(rm, 0.f);
;         mref += dl;
; #pragma unroll
;         for (int r = 0; r < 16; ++r) { s0[r] -= dl; s1[r] -= dl; }
;         const float alpha = fast_exp2(-dl);
;         lrun *= alpha;
;         if (hi == 0) wsf[r32] = alpha;
;         asm volatile("s_waitcnt lgkmcnt(0)" ::: "memory");
; #pragma unroll
;         for (int jj = 0; jj < 4; ++jj) { const f32x4 al = *(const LAS f32x4*)(wsf + 8 * jj + 4 * hi);
; #pragma unroll
;             for (int d = 0; d < 2; ++d) { o[d][4 * jj + 0] *= al.x; o[d][4 * jj + 1] *= al.y; o[d][4 * jj + 2] *= al.z; o[d][4 * jj + 3] *= al.w; } }
;         asm volatile("s_waitcnt lgkmcnt(0)" ::: "memory");
;     ...
;     lrun += rs;
;     o[0] = __builtin_amdgcn_mfma_f32_32x32x16_bf16(pa3, vf[3][0], o[0], 0, 0, 0); ra = fmaxf(fmaxf(ra, n0[14]), n0[15]); rb = fmaxf(fmaxf(rb, n1[12]), n1[13]); ra = fmaxf(fmaxf(ra, n1[14]), n1[15]); SBAR_();
;     o[1] = __builtin_amdgcn_mfma_f32_32x32x16_bf16(pa3, vf[3][1], o[1], 0, 0, 0);
;     ...
;     rmc = half_max(fmaxf(ra, rb));
.LBB0_704:
	s_or_b64 exec, exec, s[4:5]
	v_add_f32_e32 v50, 0, v50
	v_add_f32_e32 v50, v51, v50
	v_add_f32_e32 v50, v52, v50
	v_add_f32_e32 v50, v53, v50
	v_add_f32_e32 v50, v54, v50
	v_add_f32_e32 v50, v55, v50
	v_add_f32_e32 v50, v56, v50
	v_add_f32_e32 v50, v57, v50
	v_add_f32_e32 v50, v58, v50
	v_add_f32_e32 v50, v59, v50
	v_add_f32_e32 v50, v60, v50
	v_add_f32_e32 v50, v61, v50
	v_add_f32_e32 v50, v62, v50
	v_add_f32_e32 v50, v63, v50
	v_add_f32_e32 v50, v64, v50
	v_add_f32_e32 v50, v65, v50
	v_add_f32_e32 v34, v34, v50
	v_add_f32_e32 v34, v35, v34
	v_add_f32_e32 v34, v36, v34
	v_add_co_u32_e32 v36, vcc, s66, v158
	v_add_f32_e32 v34, v37, v34
	s_nop 0
	v_addc_co_u32_e32 v37, vcc, 0, v159, vcc
	global_load_dwordx4 v[118:121], v[36:37], off
	v_add_f32_e32 v34, v38, v34
	v_add_f32_e32 v34, v39, v34
	v_add_f32_e32 v34, v40, v34
	v_add_f32_e32 v34, v41, v34
	v_add_f32_e32 v34, v42, v34
	v_add_f32_e32 v34, v43, v34
	v_add_f32_e32 v34, v44, v34
	v_add_f32_e32 v34, v45, v34
	v_add_f32_e32 v34, v46, v34
	v_add_f32_e32 v34, v47, v34
	v_add_f32_e32 v34, v48, v34
	v_add_f32_e32 v34, v49, v34
	v_add_f32_e32 v148, v148, v34
	v_max_f32_e32 v34, v122, v122
	v_max_f32_e32 v35, v123, v123
	v_max_f32_e32 v34, v34, v35
	v_cmp_lt_f32_e32 vcc, s67, v34
	s_cbranch_vccz .LBB0_708
	v_max_f32_e32 v34, v34, v34
	v_max_f32_e32 v34, 0, v34
	v_exp_f32_e64 v35, -v34
	s_and_saveexec_b64 s[4:5], s[8:9]
	ds_write_b32 v166, v35 offset:43520
	s_or_b64 exec, exec, s[4:5]
	s_waitcnt lgkmcnt(0)
	v_add_u32_e32 v46, s3, v146
	v_add_f32_e32 v149, v149, v34
	v_pk_add_f32 v[66:67], v[66:67], v[34:35] op_sel_hi:[1,0] neg_lo:[0,1] neg_hi:[0,1]
	v_pk_add_f32 v[82:83], v[82:83], v[34:35] op_sel_hi:[1,0] neg_lo:[0,1] neg_hi:[0,1]
	v_pk_add_f32 v[68:69], v[68:69], v[34:35] op_sel_hi:[1,0] neg_lo:[0,1] neg_hi:[0,1]
	v_pk_add_f32 v[84:85], v[84:85], v[34:35] op_sel_hi:[1,0] neg_lo:[0,1] neg_hi:[0,1]
	v_pk_add_f32 v[70:71], v[70:71], v[34:35] op_sel_hi:[1,0] neg_lo:[0,1] neg_hi:[0,1]
	v_pk_add_f32 v[86:87], v[86:87], v[34:35] op_sel_hi:[1,0] neg_lo:[0,1] neg_hi:[0,1]
	v_pk_add_f32 v[72:73], v[72:73], v[34:35] op_sel_hi:[1,0] neg_lo:[0,1] neg_hi:[0,1]
	v_pk_add_f32 v[88:89], v[88:89], v[34:35] op_sel_hi:[1,0] neg_lo:[0,1] neg_hi:[0,1]
	v_pk_add_f32 v[74:75], v[74:75], v[34:35] op_sel_hi:[1,0] neg_lo:[0,1] neg_hi:[0,1]
	v_pk_add_f32 v[90:91], v[90:91], v[34:35] op_sel_hi:[1,0] neg_lo:[0,1] neg_hi:[0,1]
	v_pk_add_f32 v[76:77], v[76:77], v[34:35] op_sel_hi:[1,0] neg_lo:[0,1] neg_hi:[0,1]
	v_pk_add_f32 v[92:93], v[92:93], v[34:35] op_sel_hi:[1,0] neg_lo:[0,1] neg_hi:[0,1]
	v_pk_add_f32 v[78:79], v[78:79], v[34:35] op_sel_hi:[1,0] neg_lo:[0,1] neg_hi:[0,1]
	v_pk_add_f32 v[94:95], v[94:95], v[34:35] op_sel_hi:[1,0] neg_lo:[0,1] neg_hi:[0,1]
	v_pk_add_f32 v[80:81], v[80:81], v[34:35] op_sel_hi:[1,0] neg_lo:[0,1] neg_hi:[0,1]
	v_pk_add_f32 v[96:97], v[96:97], v[34:35] op_sel_hi:[1,0] neg_lo:[0,1] neg_hi:[0,1]
	v_mul_f32_e32 v148, v148, v35
	ds_read_b128 v[34:37], v46 offset:43520
	ds_read_b128 v[38:41], v46 offset:43552
	ds_read_b128 v[42:45], v46 offset:43584
	ds_read_b128 v[46:49], v46 offset:43616
	s_waitcnt lgkmcnt(0)
	s_waitcnt lgkmcnt(0)
	v_pk_mul_f32 v[4:5], v[4:5], v[36:37]
	v_pk_mul_f32 v[6:7], v[6:7], v[38:39]
	v_pk_mul_f32 v[10:11], v[10:11], v[42:43]
	v_pk_mul_f32 v[14:15], v[14:15], v[46:47]
	v_pk_mul_f32 v[16:17], v[16:17], v[48:49]
	v_pk_mul_f32 v[12:13], v[12:13], v[44:45]
	v_pk_mul_f32 v[8:9], v[8:9], v[40:41]
	v_pk_mul_f32 v[2:3], v[2:3], v[34:35]
	v_pk_mul_f32 v[30:31], v[30:31], v[46:47]
	v_pk_mul_f32 v[26:27], v[26:27], v[42:43]
	v_pk_mul_f32 v[22:23], v[22:23], v[38:39]
	v_pk_mul_f32 v[32:33], v[32:33], v[48:49]
	v_pk_mul_f32 v[28:29], v[28:29], v[44:45]
	v_pk_mul_f32 v[24:25], v[24:25], v[40:41]
	v_pk_mul_f32 v[20:21], v[20:21], v[36:37]
	v_pk_mul_f32 v[18:19], v[18:19], v[34:35]
	v_sub_f32_e32 v186, v163, v149

.LBB0_715:
	s_add_i32 s10, s73, -1
	s_cmp_lt_u32 s10, s66
	s_cselect_b64 s[44:45], -1, 0
	s_cmp_ge_u32 s10, s66
	v_lshl_add_u64 v[124:125], v[122:123], 0, s[4:5]
	s_cbranch_scc1 .LBB0_719
	s_waitcnt vmcnt(0)
	v_add_co_u32_e32 v114, vcc, 0x16e30000, v124
	s_nop 1
	v_addc_co_u32_e32 v115, vcc, 0, v125, vcc
	global_load_dwordx4 v[114:117], v[114:115], off
	s_and_saveexec_b64 s[10:11], s[6:7]
	s_cbranch_execz .LBB0_718
	v_lshl_add_u64 v[118:119], s[52:53], 0, v[150:151]
	v_add_co_u32_e32 v118, vcc, 0x2c01000, v118
	s_nop 1
	v_addc_co_u32_e32 v119, vcc, 0, v119, vcc
	global_load_dword v165, v[118:119], off offset:2048

.LBB0_719:
	s_waitcnt vmcnt(0)
	v_add_co_u32_e32 v118, vcc, 0x18e20000, v124
	s_add_i32 s54, s78, s73
	s_nop 0
	v_addc_co_u32_e32 v119, vcc, 0, v125, vcc
	global_load_dwordx4 v[118:121], v[118:119], off
	s_add_i32 s10, s54, -3
	s_cmp_lt_i32 s10, s67
	s_cselect_b64 s[48:49], -1, 0
	s_cmp_ge_i32 s10, s67
	s_cbranch_scc1 .LBB0_722
	v_add_u32_e32 v94, s75, v146
	ds_read_b128 v[82:85], v94 offset:21632
	ds_read_b128 v[66:69], v94 offset:21504
	ds_read_b128 v[70:73], v94 offset:21536
	ds_read_b128 v[86:89], v94 offset:21664
	ds_read_b128 v[74:77], v94 offset:21568
	ds_read_b128 v[90:93], v94 offset:21696
	ds_read_b128 v[78:81], v94 offset:21600
	ds_read_b128 v[94:97], v94 offset:21728
	ds_read_b128 v[182:185], v154 offset:4608
	ds_read_b128 v[186:189], v154
	ds_read_b128 v[190:193], v154 offset:32
	v_sub_f32_e32 v126, v163, v149
	s_waitcnt lgkmcnt(0)
	v_sub_f32_e32 v93, v126, v93
	v_sub_f32_e32 v92, v126, v92
	v_sub_f32_e32 v97, v126, v97
	v_sub_f32_e32 v96, v126, v96
	v_sub_f32_e32 v95, v126, v95
	v_sub_f32_e32 v94, v126, v94
	v_sub_f32_e32 v91, v126, v91
	v_sub_f32_e32 v90, v126, v90
	v_sub_f32_e32 v89, v126, v89
	v_sub_f32_e32 v88, v126, v88
	v_sub_f32_e32 v87, v126, v87
	v_sub_f32_e32 v86, v126, v86
	v_sub_f32_e32 v85, v126, v85
	v_sub_f32_e32 v84, v126, v84
	v_sub_f32_e32 v83, v126, v83
	v_sub_f32_e32 v82, v126, v82
	v_sub_f32_e32 v81, v126, v81
	v_sub_f32_e32 v80, v126, v80
	v_sub_f32_e32 v79, v126, v79
	v_sub_f32_e32 v78, v126, v78
	v_sub_f32_e32 v77, v126, v77
	v_sub_f32_e32 v76, v126, v76
	v_sub_f32_e32 v75, v126, v75
	v_sub_f32_e32 v74, v126, v74
	v_sub_f32_e32 v73, v126, v73
	v_sub_f32_e32 v72, v126, v72
	v_sub_f32_e32 v71, v126, v71
	v_sub_f32_e32 v70, v126, v70
	v_sub_f32_e32 v69, v126, v69
	v_sub_f32_e32 v68, v126, v68
	v_sub_f32_e32 v67, v126, v67
	v_sub_f32_e32 v66, v126, v66
	v_mfma_f32_32x32x16_bf16 v[82:97], v[182:185], v[98:101], v[82:97]
	ds_read_b128 v[182:185], v154 offset:4640
	v_mfma_f32_32x32x16_bf16 v[66:81], v[186:189], v[98:101], v[66:81]
	v_mfma_f32_32x32x16_bf16 v[66:81], v[190:193], v[102:105], v[66:81]
	s_waitcnt lgkmcnt(0)
	v_mfma_f32_32x32x16_bf16 v[82:97], v[182:185], v[102:105], v[82:97]
	ds_read_b128 v[182:185], v154 offset:64
	ds_read_b128 v[186:189], v154 offset:4672
	s_waitcnt lgkmcnt(0)
	v_mfma_f32_32x32x16_bf16 v[66:81], v[182:185], v[106:109], v[66:81]
	v_mfma_f32_32x32x16_bf16 v[82:97], v[186:189], v[106:109], v[82:97]
	ds_read_b128 v[182:185], v154 offset:96
	ds_read_b128 v[186:189], v154 offset:4704
	s_waitcnt lgkmcnt(0)
	v_mfma_f32_32x32x16_bf16 v[66:81], v[182:185], v[110:113], v[66:81]
	v_mfma_f32_32x32x16_bf16 v[82:97], v[186:189], v[110:113], v[82:97]
	s_cmp_lt_i32 s67, s10
	s_cbranch_scc0 .LBB0_723

.LBB0_737:
	s_cmp_lt_u32 s73, s66
	s_cselect_b64 s[50:51], -1, 0
	s_cmp_ge_u32 s73, s66
	s_waitcnt vmcnt(0) lgkmcnt(0)
	ds_write_b128 v174, v[118:121] offset:9216
	s_waitcnt lgkmcnt(0)
	s_barrier
	s_cbranch_scc1 .LBB0_741
	v_add_co_u32_e32 v114, vcc, 0x16e40000, v124
	s_nop 1
	v_addc_co_u32_e32 v115, vcc, 0, v125, vcc
	global_load_dwordx4 v[114:117], v[114:115], off
	s_and_saveexec_b64 s[12:13], s[6:7]
	s_cbranch_execz .LBB0_740
	v_lshl_add_u64 v[178:179], s[52:53], 0, v[150:151]
	v_add_co_u32_e32 v178, vcc, 0x2c02000, v178
	s_nop 1
	v_addc_co_u32_e32 v179, vcc, 0, v179, vcc
	global_load_dword v165, v[178:179], off

.LBB0_741:
	s_and_b64 vcc, exec, s[10:11]
	s_cbranch_vccnz .LBB0_743
	v_add_co_u32_e32 v118, vcc, 0x18e30000, v124
	s_nop 1
	v_addc_co_u32_e32 v119, vcc, 0, v125, vcc
	global_load_dwordx4 v[118:121], v[118:119], off

; __device__ __forceinline__ unsigned xb_ld(unsigned* p)              { return __hip_atomic_load(p, __ATOMIC_RELAXED, __HIP_MEMORY_SCOPE_AGENT); }
; __device__ __forceinline__ void xcd_barrier_complete(unsigned* bar, unsigned x, unsigned& nloc, unsigned& nx) {
;     const unsigned G = gridDim.x * gridDim.y * gridDim.z;
;     unsigned sum, cnt, mine, sp = 0u;
;     for (;;) {
;         sum = 0u; cnt = 0u; mine = 0u;
; #pragma unroll
;         for (unsigned j = 0; j < 16; ++j) { const unsigned c = xb_ld(&bar[XB_XCNT(j)]); sum += c; cnt += (c > 0u) ? 1u : 0u; mine = (j == x) ? c : mine; }
;         if (sum == G) break;
;         __builtin_amdgcn_s_sleep(1);
;         if ((++sp & 255u) == 0u) { if (xb_ld(&bar[XB_TMO])) break; if (sp > XB_SPIN_CAP) { atomicAdd(&bar[XB_TMO], 1u); break; } }
;     }
;     nloc = mine > 0u ? mine : 1u; nx = cnt > 0u ? cnt : 1u;
.LBB0_781:
	v_mov_b64_e32 v[12:13], s[4:5]
	s_waitcnt lgkmcnt(0)
	global_load_dword v2, v[12:13], off offset:1024 sc1
	global_load_dword v1, v[12:13], off offset:1280 sc1
	global_load_dword v3, v[12:13], off offset:1536 sc1
	s_or_b64 s[20:21], s[20:21], exec
	s_or_b64 s[18:19], s[18:19], exec
	s_waitcnt vmcnt(0) lgkmcnt(0)
	v_add_u32_e32 v4, v1, v2
	v_add_u32_e32 v5, v4, v3
	global_load_dword v4, v[12:13], off offset:1792 sc1
	s_waitcnt vmcnt(0) lgkmcnt(0)
	v_add_u32_e32 v6, v5, v4
	global_load_dword v5, v[12:13], off offset:2048 sc1
	s_waitcnt vmcnt(0) lgkmcnt(0)
	v_add_u32_e32 v7, v6, v5
	global_load_dword v6, v[12:13], off offset:2304 sc1
	s_waitcnt vmcnt(0) lgkmcnt(0)
	v_add_u32_e32 v8, v7, v6
	global_load_dword v7, v[12:13], off offset:2560 sc1
	s_waitcnt vmcnt(0) lgkmcnt(0)
	v_add_u32_e32 v9, v8, v7
	global_load_dword v8, v[12:13], off offset:2816 sc1
	s_waitcnt vmcnt(0) lgkmcnt(0)
	v_add_u32_e32 v10, v9, v8
	global_load_dword v9, v[12:13], off offset:3072 sc1
	s_waitcnt vmcnt(0) lgkmcnt(0)
	v_add_u32_e32 v11, v10, v9
	global_load_dword v10, v[12:13], off offset:3328 sc1
	s_waitcnt vmcnt(0) lgkmcnt(0)
	v_add_u32_e32 v14, v11, v10
	global_load_dword v11, v[12:13], off offset:3584 sc1
	s_waitcnt vmcnt(0) lgkmcnt(0)
	v_add_u32_e32 v14, v14, v11
	global_load_dword v12, v[12:13], off offset:3840 sc1
	s_waitcnt vmcnt(0) lgkmcnt(0)
	v_add_u32_e32 v16, v14, v12
	v_mov_b64_e32 v[14:15], s[6:7]
	global_load_dword v13, v[14:15], off sc1
	v_mov_b64_e32 v[14:15], s[8:9]
	global_load_dword v14, v[14:15], off sc1
	s_waitcnt vmcnt(0) lgkmcnt(0)
	v_add_u32_e32 v16, v16, v13
	v_add_u32_e32 v18, v16, v14
	v_mov_b64_e32 v[16:17], s[10:11]
	global_load_dword v15, v[16:17], off sc1
	v_mov_b64_e32 v[16:17], s[12:13]
	global_load_dword v16, v[16:17], off sc1
	s_waitcnt vmcnt(0) lgkmcnt(0)
	v_add_u32_e32 v18, v18, v15
	v_add_u32_e32 v17, v18, v16
	v_cmp_ne_u32_e32 vcc, s59, v17
	s_and_saveexec_b64 s[22:23], vcc
	s_cbranch_execz .LBB0_780
	s_and_b32 s26, s34, 0xff
	s_mov_b64 s[24:25], -1
	s_cmp_eq_u32 s26, 0
	s_mov_b64 s[28:29], -1
	s_mov_b64 s[26:27], -1
	s_sleep 1
	s_cbranch_scc1 .LBB0_784
	s_and_saveexec_b64 s[30:31], s[28:29]
	s_cbranch_execz .LBB0_779
	s_branch .LBB0_787
.LBB0_784:
	v_mov_b64_e32 v[18:19], s[4:5]
	global_load_dword v17, v[18:19], off offset:512 sc1
	s_mov_b64 s[28:29], 0
	s_waitcnt vmcnt(0) lgkmcnt(0)
	v_cmp_eq_u32_e32 vcc, 0, v17
	s_and_saveexec_b64 s[30:31], vcc
	s_cmp_lt_u32 s34, 0x400001
	s_cselect_b64 s[28:29], -1, 0
	s_xor_b64 s[26:27], exec, -1
	s_and_b64 s[28:29], s[28:29], exec
	s_or_b64 exec, exec, s[30:31]
	s_and_saveexec_b64 s[30:31], s[28:29]
	s_cbranch_execz .LBB0_779

; __device__ __forceinline__ unsigned xb_ld(unsigned* p)              { return __hip_atomic_load(p, __ATOMIC_RELAXED, __HIP_MEMORY_SCOPE_AGENT); }
; __device__ __forceinline__ unsigned xb_add(unsigned* p, unsigned v) { return __hip_atomic_fetch_add(p, v, __ATOMIC_RELAXED, __HIP_MEMORY_SCOPE_AGENT); }
; #define XB_SPIN(cond, bar) do { unsigned _sp = 0; while (cond) { __builtin_amdgcn_s_sleep(1); \
;     if ((++_sp & 255u) == 0u) { if (xb_ld(&(bar)[XB_TMO])) break; if (_sp > XB_SPIN_CAP) { atomicAdd(&(bar)[XB_TMO], 1u); break; } } } } while (0)
; __device__ __forceinline__ void xcd_barrier(const XcdBarrier& b) {
;     ...
;     if (threadIdx.x == 0) {
;         unsigned* bar = b.bar;
;         __builtin_amdgcn_s_waitcnt(0);
;         unsigned nloc = b.st[0], nx = b.st[1];
;         if (nloc == 0u) { xcd_barrier_complete(bar, b.x, nloc, nx); b.st[0] = nloc; b.st[1] = nx; }
;         const unsigned old = xb_add(&bar[XB_XSUB(b.x)], 1u);
;         const unsigned gen = old / nloc;
;         if (old + 1u == (gen + 1u) * nloc) {
;             __builtin_amdgcn_fence(__ATOMIC_RELEASE, "agent");
;             asm volatile("s_waitcnt vmcnt(0)" ::: "memory");
;             const unsigned og = xb_add(&bar[XB_TOP], 1u);
;             const unsigned tg = og / nx;
;             if (og + 1u == (tg + 1u) * nx) xb_add(&bar[XB_TOPGEN], 1u);
;             else XB_SPIN(xb_ld(&bar[XB_TOPGEN]) == tg, bar);
;             __builtin_amdgcn_fence(__ATOMIC_ACQUIRE, "agent");
;             xb_add(&bar[XB_XGEN(b.x)], 1u);
;             asm volatile("s_waitcnt vmcnt(0)" ::: "memory");
;         } else {
;             XB_SPIN(xb_ld(&bar[XB_XGEN(b.x)]) == gen, bar);
.LBB0_791:
	s_lshl_b32 s6, s38, 8
	s_add_u32 s27, s4, s6
	s_addc_u32 s26, s5, 0
	v_mov_b32_e32 v1, s27
	v_add_co_u32_e32 v6, vcc, 0x1000, v1
	v_mov_b32_e32 v1, s26
	s_nop 0
	v_addc_co_u32_e32 v7, vcc, 0, v1, vcc
	flat_atomic_add v3, v[6:7], v217 offset:1024 sc0
	v_cvt_f32_u32_e32 v1, v4
	v_sub_u32_e32 v5, 0, v4
	v_rcp_iflag_f32_e32 v1, v1
	s_nop 0
	v_mul_f32_e32 v1, 0x4f7ffffe, v1
	v_cvt_u32_f32_e32 v1, v1
	v_mul_lo_u32 v5, v5, v1
	v_mul_hi_u32 v5, v1, v5
	v_add_u32_e32 v1, v1, v5
	s_waitcnt vmcnt(0) lgkmcnt(0)
	v_mul_hi_u32 v1, v3, v1
	v_mul_lo_u32 v5, v1, v4
	v_sub_u32_e32 v5, v3, v5
	v_cmp_ge_u32_e32 vcc, v5, v4
	v_add_u32_e32 v6, 1, v1
	v_add_u32_e32 v3, 1, v3
	v_cndmask_b32_e32 v1, v1, v6, vcc
	v_sub_u32_e32 v6, v5, v4
	v_cndmask_b32_e32 v5, v5, v6, vcc
	v_cmp_ge_u32_e32 vcc, v5, v4
	v_add_u32_e32 v5, 1, v1
	s_nop 0
	v_cndmask_b32_e32 v1, v1, v5, vcc
	v_mad_u64_u32 v[4:5], s[6:7], v4, v1, v[4:5]
	v_cmp_ne_u32_e32 vcc, v3, v4
	s_and_saveexec_b64 s[6:7], vcc
	s_xor_b64 s[6:7], exec, s[6:7]
	s_cbranch_execz .LBB0_804
	v_mov_b32_e32 v2, s27
	v_add_co_u32_e32 v2, vcc, 0x2000, v2
	v_mov_b32_e32 v3, s26
	s_nop 0
	v_addc_co_u32_e32 v3, vcc, 0, v3, vcc
	global_load_dword v2, v[2:3], off offset:1024 sc1
	s_add_u32 s10, s27, 0x2400
	s_addc_u32 s11, s26, 0
	s_waitcnt vmcnt(0) lgkmcnt(0)
	v_cmp_eq_u32_e32 vcc, v2, v1
	s_and_saveexec_b64 s[8:9], vcc
	s_cbranch_execz .LBB0_803
	s_mov_b32 s28, 1
	s_mov_b64 s[12:13], 0
	s_branch .LBB0_795

.LBB0_795:
	s_and_b32 s20, s28, 0xff
	s_mov_b64 s[18:19], -1
	s_cmp_lg_u32 s20, 0
	s_mov_b64 s[20:21], -1
	s_sleep 1
	s_cbranch_scc1 .LBB0_799
	v_mov_b64_e32 v[2:3], s[4:5]
	global_load_dword v2, v[2:3], off offset:512 sc1
	s_mov_b64 s[20:21], 0
	s_mov_b64 s[22:23], -1
	s_waitcnt vmcnt(0) lgkmcnt(0)
	v_cmp_eq_u32_e32 vcc, 0, v2
	s_and_saveexec_b64 s[24:25], vcc
	s_cmp_lt_u32 s28, 0x400001
	s_cselect_b64 s[20:21], -1, 0
	s_xor_b64 s[22:23], exec, -1
	s_and_b64 s[20:21], s[20:21], exec
	s_or_b64 exec, exec, s[24:25]
.LBB0_799:
	s_andn2_b64 s[16:17], s[16:17], exec
	s_and_b64 s[22:23], s[22:23], exec
	s_or_b64 s[16:17], s[16:17], s[22:23]
	s_and_saveexec_b64 s[22:23], s[20:21]
	s_cbranch_execz .LBB0_794
	v_mov_b64_e32 v[2:3], s[10:11]
	global_load_dword v2, v[2:3], off sc1
	s_add_i32 s28, s28, 1
	s_or_b64 s[16:17], s[16:17], exec
	s_waitcnt vmcnt(0) lgkmcnt(0)
	v_cmp_ne_u32_e32 vcc, v2, v1
	s_orn2_b64 s[18:19], vcc, exec
	s_branch .LBB0_794

; __device__ __forceinline__ unsigned xb_ld(unsigned* p)              { return __hip_atomic_load(p, __ATOMIC_RELAXED, __HIP_MEMORY_SCOPE_AGENT); }
; __device__ __forceinline__ unsigned xb_add(unsigned* p, unsigned v) { return __hip_atomic_fetch_add(p, v, __ATOMIC_RELAXED, __HIP_MEMORY_SCOPE_AGENT); }
; #define XB_SPIN(cond, bar) do { unsigned _sp = 0; while (cond) { __builtin_amdgcn_s_sleep(1); \
;     if ((++_sp & 255u) == 0u) { if (xb_ld(&(bar)[XB_TMO])) break; if (_sp > XB_SPIN_CAP) { atomicAdd(&(bar)[XB_TMO], 1u); break; } } } } while (0)
; __device__ __forceinline__ void xcd_barrier(const XcdBarrier& b) {
;     ...
;         const unsigned old = xb_add(&bar[XB_XSUB(b.x)], 1u);
;         const unsigned gen = old / nloc;
;         if (old + 1u == (gen + 1u) * nloc) {
;             __builtin_amdgcn_fence(__ATOMIC_RELEASE, "agent");
;             asm volatile("s_waitcnt vmcnt(0)" ::: "memory");
;             const unsigned og = xb_add(&bar[XB_TOP], 1u);
;             const unsigned tg = og / nx;
;             if (og + 1u == (tg + 1u) * nx) xb_add(&bar[XB_TOPGEN], 1u);
;             else XB_SPIN(xb_ld(&bar[XB_TOPGEN]) == tg, bar);
;             __builtin_amdgcn_fence(__ATOMIC_ACQUIRE, "agent");
.LBB0_804:
	s_andn2_saveexec_b64 s[6:7], s[6:7]
	s_cbranch_execz .LBB0_820
	v_mov_b32_e32 v1, s4
	v_add_co_u32_e32 v4, vcc, 0x3000, v1
	v_mov_b32_e32 v1, s5
	buffer_wbl2 sc1
	s_waitcnt vmcnt(0)
	v_addc_co_u32_e32 v5, vcc, 0, v1, vcc
	flat_atomic_add v3, v[4:5], v217 offset:1024 sc0
	v_cvt_f32_u32_e32 v1, v2
	v_sub_u32_e32 v4, 0, v2
	s_mov_b64 s[10:11], -1
	v_rcp_iflag_f32_e32 v1, v1
	s_nop 0
	v_mul_f32_e32 v1, 0x4f7ffffe, v1
	v_cvt_u32_f32_e32 v1, v1
	v_mul_lo_u32 v4, v4, v1
	v_mul_hi_u32 v4, v1, v4
	v_add_u32_e32 v1, v1, v4
	s_waitcnt vmcnt(0) lgkmcnt(0)
	v_mul_hi_u32 v1, v3, v1
	v_mul_lo_u32 v4, v1, v2
	v_sub_u32_e32 v4, v3, v4
	v_cmp_ge_u32_e32 vcc, v4, v2
	v_add_u32_e32 v5, 1, v1
	s_nop 0
	v_cndmask_b32_e32 v1, v1, v5, vcc
	v_sub_u32_e32 v5, v4, v2
	v_cndmask_b32_e32 v4, v4, v5, vcc
	v_cmp_ge_u32_e32 vcc, v4, v2
	v_add_u32_e32 v4, 1, v1
	s_nop 0
	v_cndmask_b32_e32 v1, v1, v4, vcc
	v_add_u32_e32 v4, 1, v3
	v_mad_u64_u32 v[2:3], s[6:7], v2, v1, v[2:3]
	s_add_u32 s6, s4, 0x3500
	s_addc_u32 s7, s5, 0
	v_cmp_ne_u32_e32 vcc, v4, v2
	v_mov_b64_e32 v[2:3], s[6:7]
	s_and_saveexec_b64 s[8:9], vcc
	s_cbranch_execz .LBB0_817
	v_mov_b64_e32 v[2:3], s[6:7]
	global_load_dword v2, v[2:3], off sc1
	s_mov_b64 s[14:15], 0
	s_waitcnt vmcnt(0) lgkmcnt(0)
	v_cmp_eq_u32_e32 vcc, v2, v1
	s_and_saveexec_b64 s[12:13], vcc
	s_cbranch_execz .LBB0_816
	s_add_u32 s10, s4, 0x200
	s_addc_u32 s11, s5, 0
	s_mov_b32 s24, 1
	s_mov_b64 s[4:5], 0
	s_branch .LBB0_809

; __device__ __forceinline__ unsigned xb_ld(unsigned* p)              { return __hip_atomic_load(p, __ATOMIC_RELAXED, __HIP_MEMORY_SCOPE_AGENT); }
; #define XB_SPIN(cond, bar) do { unsigned _sp = 0; while (cond) { __builtin_amdgcn_s_sleep(1); \
;     if ((++_sp & 255u) == 0u) { if (xb_ld(&(bar)[XB_TMO])) break; if (_sp > XB_SPIN_CAP) { atomicAdd(&(bar)[XB_TMO], 1u); break; } } } } while (0)
; __device__ __forceinline__ void xcd_barrier(const XcdBarrier& b) {
;     ...
;             else XB_SPIN(xb_ld(&bar[XB_TOPGEN]) == tg, bar);
.LBB0_811:
	v_mov_b64_e32 v[2:3], s[10:11]
	global_load_dword v2, v[2:3], off sc1
	s_mov_b64 s[20:21], 0
	s_mov_b64 s[18:19], -1
	s_waitcnt vmcnt(0) lgkmcnt(0)
	v_cmp_eq_u32_e32 vcc, 0, v2
	s_and_saveexec_b64 s[22:23], vcc
	s_cmp_lt_u32 s24, 0x400001
	s_cselect_b64 s[20:21], -1, 0
	s_xor_b64 s[18:19], exec, -1
	s_and_b64 s[20:21], s[20:21], exec
	s_or_b64 exec, exec, s[22:23]
	s_and_saveexec_b64 s[22:23], s[20:21]
	s_cbranch_execz .LBB0_808
.LBB0_814:
	v_mov_b64_e32 v[2:3], s[6:7]
	global_load_dword v2, v[2:3], off sc1
	s_add_i32 s24, s24, 1
	s_or_b64 s[18:19], s[18:19], exec
	s_waitcnt vmcnt(0) lgkmcnt(0)
	v_cmp_ne_u32_e32 vcc, v2, v1
	s_orn2_b64 s[16:17], vcc, exec
	s_branch .LBB0_808

; __device__ __forceinline__ u32x4 pack8(f32x4 v0, f32x4 v1) { u32x4 w; w.x = cvt_pk_bf16(v0[0], v0[1]); w.y = cvt_pk_bf16(v0[2], v0[3]); w.z = cvt_pk_bf16(v1[0], v1[1]); w.w = cvt_pk_bf16(v1[2], v1[3]); return w; }
;     __device__ __forceinline__ void operator()(f32x4 (&acc)[2][2][4][2], const Unit& u, int wr, int wc, int fr, int fq) const {
;         const int row0 = u.pm * BM + wr * 64 + fr; const int colt = u.pn * BM + wc * 32 + 8 * fq;
; #pragma unroll
;         for (int ai = 0; ai < 2; ++ai)
; #pragma unroll
;             for (int m = 0; m < 4; ++m) { const int row = row0 + ai * HALF + m * 16; float ss = 0.f;
; #pragma unroll
;                 for (int bj = 0; bj < 2; ++bj) { const int col = colt + bj * HALF; const size_t off = (size_t)row * DM + col;
;                     const f32x4 x0 = *(const f32x4*)(in + off) + acc[ai][bj][m][0], x1 = *(const f32x4*)(in + off + 4) + acc[ai][bj][m][1];
;                     *(f32x4*)(out + off) = x0; *(f32x4*)(out + off + 4) = x1;
;                     const f32x4 g0 = *(const f32x4*)(g + col), g1 = *(const f32x4*)(g + col + 4);
;                     *(u32x4*)(xg + off) = pack8(x0 * g0, x1 * g1);
;                     ss += (x0[0] * x0[0] + x0[1] * x0[1]) + (x0[2] * x0[2] + x0[3] * x0[3]) + (x1[0] * x1[0] + x1[1] * x1[1]) + (x1[2] * x1[2] + x1[3] * x1[3]); }
;                 ss += __shfl_xor(ss, 16); ss += __shfl_xor(ss, 32);
;                 if (fq == 0) atomicAdd(sumsq + row, ss);
;                 if (m == 3) asm volatile("" ::: "memory"); }
.LBB0_1054:
	v_lshl_add_u32 v146, s28, 8, v1
	v_lshl_or_b32 v144, s30, 8, v149
	v_ashrrev_i32_e32 v147, 31, v146
	v_lshlrev_b64 v[164:165], 10, v[146:147]
	v_ashrrev_i32_e32 v145, 31, v144
	v_lshl_add_u64 v[160:161], v[164:165], 0, v[144:145]
	v_lshlrev_b64 v[162:163], 2, v[160:161]
	v_lshl_add_u64 v[166:167], s[4:5], 0, v[162:163]
	global_load_dwordx4 v[152:155], v[166:167], off
	global_load_dwordx4 v[156:159], v[166:167], off offset:16
	v_lshl_add_u64 v[162:163], s[2:3], 0, v[162:163]
	v_lshl_add_u64 v[142:143], v[144:145], 2, s[14:15]
	v_lshl_add_u64 v[160:161], v[160:161], 1, s[12:13]
	s_waitcnt vmcnt(0) lgkmcnt(0)
	v_pk_add_f32 v[128:129], v[128:129], v[154:155]
	v_pk_add_f32 v[126:127], v[126:127], v[152:153]
	v_pk_add_f32 v[124:125], v[124:125], v[158:159]
	v_pk_add_f32 v[122:123], v[122:123], v[156:157]
	global_store_dwordx4 v[162:163], v[126:129], off
	global_store_dwordx4 v[162:163], v[122:125], off offset:16
	global_load_dwordx4 v[152:155], v[142:143], off
	global_load_dwordx4 v[156:159], v[142:143], off offset:16
	s_waitcnt vmcnt(0)
	v_pk_mul_f32 v[154:155], v[128:129], v[154:155]
	v_pk_mul_f32 v[152:153], v[126:127], v[152:153]
	v_pk_mul_f32 v[158:159], v[124:125], v[158:159]
	v_pk_mul_f32 v[156:157], v[122:123], v[156:157]
	v_cvt_pk_bf16_f32 v152, v152, v153
	v_cvt_pk_bf16_f32 v153, v154, v155
	v_cvt_pk_bf16_f32 v154, v156, v157
	v_cvt_pk_bf16_f32 v155, v158, v159
	global_store_dwordx4 v[160:161], v[152:155], off
	global_load_dwordx4 v[152:155], v[166:167], off offset:512
	s_nop 0
	global_load_dwordx4 v[156:159], v[166:167], off offset:528
	s_waitcnt vmcnt(0) lgkmcnt(0)
	v_pk_add_f32 v[120:121], v[120:121], v[154:155]
	v_pk_add_f32 v[118:119], v[118:119], v[152:153]
	v_pk_add_f32 v[154:155], v[116:117], v[158:159]
	v_pk_add_f32 v[152:153], v[114:115], v[156:157]
	global_store_dwordx4 v[162:163], v[118:121], off offset:512
	global_store_dwordx4 v[162:163], v[152:155], off offset:528
	global_load_dwordx4 v[156:159], v[142:143], off offset:512
	s_nop 0
	global_load_dwordx4 v[160:163], v[142:143], off offset:528
	v_mul_f32_e32 v114, v127, v127
	v_mul_f32_e32 v115, v129, v129
	v_mul_f32_e32 v116, v123, v123
	v_fmac_f32_e32 v114, v126, v126
	v_fmac_f32_e32 v115, v128, v128
	v_mul_f32_e32 v117, v125, v125
	v_fmac_f32_e32 v116, v122, v122
	v_add_f32_e32 v114, v114, v115
	v_fmac_f32_e32 v117, v124, v124
	v_add_f32_e32 v114, v114, v116
	v_mul_f32_e32 v115, v119, v119
	v_mul_f32_e32 v116, v121, v121
	v_add_f32_e32 v114, v117, v114
	v_mul_f32_e32 v117, v153, v153
	v_fmac_f32_e32 v115, v118, v118
	v_fmac_f32_e32 v116, v120, v120
	v_mul_f32_e32 v122, v155, v155
	v_fmac_f32_e32 v117, v152, v152
	v_add_f32_e32 v115, v115, v116
	v_fmac_f32_e32 v122, v154, v154
	v_add_f32_e32 v115, v115, v117
	v_add_f32_e32 v115, v122, v115
	v_add_f32_e32 v116, v114, v115
	ds_bpermute_b32 v117, v253, v116
	v_or_b32_e32 v114, 0x80, v144
	v_ashrrev_i32_e32 v115, 31, v114
	v_lshl_add_u64 v[122:123], v[164:165], 0, v[114:115]
	v_lshl_add_u64 v[122:123], v[122:123], 1, s[12:13]
	s_waitcnt lgkmcnt(0)
	v_add_f32_e32 v116, v116, v117
	ds_bpermute_b32 v117, v230, v116
	s_waitcnt vmcnt(0)
	v_pk_mul_f32 v[120:121], v[120:121], v[158:159]
	v_pk_mul_f32 v[118:119], v[118:119], v[156:157]
	v_pk_mul_f32 v[124:125], v[154:155], v[162:163]
	v_pk_mul_f32 v[126:127], v[152:153], v[160:161]
	v_cvt_pk_bf16_f32 v118, v118, v119
	v_cvt_pk_bf16_f32 v119, v120, v121
	v_cvt_pk_bf16_f32 v120, v126, v127
	v_cvt_pk_bf16_f32 v121, v124, v125
	global_store_dwordx4 v[122:123], v[118:121], off
	s_and_saveexec_b64 s[28:29], s[6:7]
	s_cbranch_execz .LBB0_1056
	v_lshl_add_u64 v[118:119], v[146:147], 2, s[16:17]
	s_waitcnt lgkmcnt(0)
	v_add_f32_e32 v116, v116, v117
	flat_atomic_add_f32 v[118:119], v116
.LBB0_1056:
	s_or_b64 exec, exec, s[28:29]
	v_or_b32_e32 v116, 16, v146
	s_waitcnt lgkmcnt(0)
	v_ashrrev_i32_e32 v117, 31, v116
	v_lshlrev_b64 v[152:153], 10, v[116:117]
	v_lshl_add_u64 v[126:127], v[152:153], 0, v[144:145]
	v_lshlrev_b64 v[128:129], 2, v[126:127]
	v_lshl_add_u64 v[154:155], s[4:5], 0, v[128:129]
	global_load_dwordx4 v[118:121], v[154:155], off
	global_load_dwordx4 v[122:125], v[154:155], off offset:16
	v_lshl_add_u64 v[128:129], s[2:3], 0, v[128:129]
	v_lshl_add_u64 v[126:127], v[126:127], 1, s[12:13]
	s_waitcnt vmcnt(0) lgkmcnt(0)
	v_pk_add_f32 v[112:113], v[112:113], v[120:121]
	v_pk_add_f32 v[110:111], v[110:111], v[118:119]
	v_pk_add_f32 v[108:109], v[108:109], v[124:125]
	v_pk_add_f32 v[106:107], v[106:107], v[122:123]
	global_store_dwordx4 v[128:129], v[110:113], off
	global_store_dwordx4 v[128:129], v[106:109], off offset:16
	global_load_dwordx4 v[118:121], v[142:143], off
	global_load_dwordx4 v[122:125], v[142:143], off offset:16
	s_waitcnt vmcnt(0)
	v_pk_mul_f32 v[120:121], v[112:113], v[120:121]
	v_pk_mul_f32 v[118:119], v[110:111], v[118:119]
	v_pk_mul_f32 v[124:125], v[108:109], v[124:125]
	v_pk_mul_f32 v[122:123], v[106:107], v[122:123]
	v_cvt_pk_bf16_f32 v118, v118, v119
	v_cvt_pk_bf16_f32 v119, v120, v121
	v_cvt_pk_bf16_f32 v120, v122, v123
	v_cvt_pk_bf16_f32 v121, v124, v125
	global_store_dwordx4 v[126:127], v[118:121], off
	global_load_dwordx4 v[118:121], v[154:155], off offset:512
	s_nop 0
	global_load_dwordx4 v[122:125], v[154:155], off offset:528
	s_waitcnt vmcnt(0) lgkmcnt(0)
; __device__ __forceinline__ u32x4 pack8(f32x4 v0, f32x4 v1) { u32x4 w; w.x = cvt_pk_bf16(v0[0], v0[1]); w.y = cvt_pk_bf16(v0[2], v0[3]); w.z = cvt_pk_bf16(v1[0], v1[1]); w.w = cvt_pk_bf16(v1[2], v1[3]); return w; }
;     __device__ __forceinline__ void operator()(f32x4 (&acc)[2][2][4][2], const Unit& u, int wr, int wc, int fr, int fq) const {
;         const int row0 = u.pm * BM + wr * 64 + fr; const int colt = u.pn * BM + wc * 32 + 8 * fq;
; #pragma unroll
;         for (int ai = 0; ai < 2; ++ai)
; #pragma unroll
;             for (int m = 0; m < 4; ++m) { const int row = row0 + ai * HALF + m * 16; float ss = 0.f;
; #pragma unroll
;                 for (int bj = 0; bj < 2; ++bj) { const int col = colt + bj * HALF; const size_t off = (size_t)row * DM + col;
;                     const f32x4 x0 = *(const f32x4*)(in + off) + acc[ai][bj][m][0], x1 = *(const f32x4*)(in + off + 4) + acc[ai][bj][m][1];
;                     *(f32x4*)(out + off) = x0; *(f32x4*)(out + off + 4) = x1;
;                     const f32x4 g0 = *(const f32x4*)(g + col), g1 = *(const f32x4*)(g + col + 4);
;                     *(u32x4*)(xg + off) = pack8(x0 * g0, x1 * g1);
;                     ss += (x0[0] * x0[0] + x0[1] * x0[1]) + (x0[2] * x0[2] + x0[3] * x0[3]) + (x1[0] * x1[0] + x1[1] * x1[1]) + (x1[2] * x1[2] + x1[3] * x1[3]); }
;                 ss += __shfl_xor(ss, 16); ss += __shfl_xor(ss, 32);
;                 if (fq == 0) atomicAdd(sumsq + row, ss);
;                 if (m == 3) asm volatile("" ::: "memory"); }
	v_pk_add_f32 v[104:105], v[104:105], v[120:121]
	v_pk_add_f32 v[102:103], v[102:103], v[118:119]
	v_pk_add_f32 v[120:121], v[100:101], v[124:125]
	v_pk_add_f32 v[118:119], v[98:99], v[122:123]
	global_store_dwordx4 v[128:129], v[102:105], off offset:512
	global_store_dwordx4 v[128:129], v[118:121], off offset:528
	global_load_dwordx4 v[122:125], v[142:143], off offset:512
	s_nop 0
	global_load_dwordx4 v[126:129], v[142:143], off offset:528
	v_mul_f32_e32 v98, v111, v111
	v_mul_f32_e32 v99, v113, v113
	v_mul_f32_e32 v100, v107, v107
	v_fmac_f32_e32 v98, v110, v110
	v_fmac_f32_e32 v99, v112, v112
	v_mul_f32_e32 v101, v109, v109
	v_fmac_f32_e32 v100, v106, v106
	v_add_f32_e32 v98, v98, v99
	v_fmac_f32_e32 v101, v108, v108
	v_add_f32_e32 v98, v98, v100
	v_mul_f32_e32 v99, v103, v103
	v_mul_f32_e32 v100, v105, v105
	v_add_f32_e32 v98, v101, v98
	v_mul_f32_e32 v101, v119, v119
	v_fmac_f32_e32 v99, v102, v102
	v_fmac_f32_e32 v100, v104, v104
	v_mul_f32_e32 v106, v121, v121
	v_fmac_f32_e32 v101, v118, v118
	v_add_f32_e32 v99, v99, v100
	v_fmac_f32_e32 v106, v120, v120
	v_add_f32_e32 v99, v99, v101
	v_add_f32_e32 v99, v106, v99
	v_add_f32_e32 v98, v98, v99
	ds_bpermute_b32 v99, v253, v98
	v_lshl_add_u64 v[106:107], v[152:153], 0, v[114:115]
	s_waitcnt lgkmcnt(0)
	v_add_f32_e32 v98, v98, v99
	ds_bpermute_b32 v99, v230, v98
	s_waitcnt vmcnt(0)
	v_pk_mul_f32 v[104:105], v[104:105], v[124:125]
	v_pk_mul_f32 v[100:101], v[102:103], v[122:123]
	v_pk_mul_f32 v[108:109], v[120:121], v[128:129]
	v_pk_mul_f32 v[102:103], v[118:119], v[126:127]
	v_cvt_pk_bf16_f32 v100, v100, v101
	v_cvt_pk_bf16_f32 v101, v104, v105
	v_cvt_pk_bf16_f32 v102, v102, v103
	v_cvt_pk_bf16_f32 v103, v108, v109
	v_lshl_add_u64 v[104:105], v[106:107], 1, s[12:13]
	global_store_dwordx4 v[104:105], v[100:103], off
	s_and_saveexec_b64 s[28:29], s[6:7]
	s_cbranch_execz .LBB0_1058
	v_lshl_add_u64 v[100:101], v[116:117], 2, s[16:17]
	s_waitcnt lgkmcnt(0)
	v_add_f32_e32 v98, v98, v99
	flat_atomic_add_f32 v[100:101], v98
.LBB0_1058:
	s_or_b64 exec, exec, s[28:29]
	v_or_b32_e32 v98, 32, v146
	s_waitcnt lgkmcnt(0)
	v_ashrrev_i32_e32 v99, 31, v98
	v_lshlrev_b64 v[112:113], 10, v[98:99]
	v_lshl_add_u64 v[108:109], v[112:113], 0, v[144:145]
	v_lshlrev_b64 v[110:111], 2, v[108:109]
	v_lshl_add_u64 v[116:117], s[4:5], 0, v[110:111]
	global_load_dwordx4 v[100:103], v[116:117], off
	global_load_dwordx4 v[104:107], v[116:117], off offset:16
	v_lshl_add_u64 v[110:111], s[2:3], 0, v[110:111]
	v_lshl_add_u64 v[108:109], v[108:109], 1, s[12:13]
	s_waitcnt vmcnt(0) lgkmcnt(0)
	v_pk_add_f32 v[96:97], v[96:97], v[102:103]
	v_pk_add_f32 v[94:95], v[94:95], v[100:101]
	v_pk_add_f32 v[92:93], v[92:93], v[106:107]
	v_pk_add_f32 v[90:91], v[90:91], v[104:105]
	global_store_dwordx4 v[110:111], v[94:97], off
	global_store_dwordx4 v[110:111], v[90:93], off offset:16
	global_load_dwordx4 v[100:103], v[142:143], off
	global_load_dwordx4 v[104:107], v[142:143], off offset:16
	s_waitcnt vmcnt(0)
	v_pk_mul_f32 v[102:103], v[96:97], v[102:103]
	v_pk_mul_f32 v[100:101], v[94:95], v[100:101]
	v_pk_mul_f32 v[106:107], v[92:93], v[106:107]
	v_pk_mul_f32 v[104:105], v[90:91], v[104:105]
	v_cvt_pk_bf16_f32 v100, v100, v101
	v_cvt_pk_bf16_f32 v101, v102, v103
	v_cvt_pk_bf16_f32 v102, v104, v105
	v_cvt_pk_bf16_f32 v103, v106, v107
	global_store_dwordx4 v[108:109], v[100:103], off
	global_load_dwordx4 v[100:103], v[116:117], off offset:512
	s_nop 0
	global_load_dwordx4 v[104:107], v[116:117], off offset:528
	s_waitcnt vmcnt(0) lgkmcnt(0)
	v_pk_add_f32 v[88:89], v[88:89], v[102:103]
	v_pk_add_f32 v[86:87], v[86:87], v[100:101]
	v_pk_add_f32 v[102:103], v[84:85], v[106:107]
	v_pk_add_f32 v[100:101], v[82:83], v[104:105]
	global_store_dwordx4 v[110:111], v[86:89], off offset:512
	global_store_dwordx4 v[110:111], v[100:103], off offset:528
	global_load_dwordx4 v[104:107], v[142:143], off offset:512
	s_nop 0
	global_load_dwordx4 v[108:111], v[142:143], off offset:528
	v_mul_f32_e32 v82, v95, v95
	v_mul_f32_e32 v83, v97, v97
	v_mul_f32_e32 v84, v91, v91
	v_fmac_f32_e32 v82, v94, v94
	v_fmac_f32_e32 v83, v96, v96
	v_mul_f32_e32 v85, v93, v93
	v_fmac_f32_e32 v84, v90, v90
	v_add_f32_e32 v82, v82, v83
	v_fmac_f32_e32 v85, v92, v92
	v_add_f32_e32 v82, v82, v84
	v_mul_f32_e32 v83, v87, v87
	v_mul_f32_e32 v84, v89, v89
	v_add_f32_e32 v82, v85, v82
	v_mul_f32_e32 v85, v101, v101
	v_fmac_f32_e32 v83, v86, v86
	v_fmac_f32_e32 v84, v88, v88
	v_mul_f32_e32 v90, v103, v103
	v_fmac_f32_e32 v85, v100, v100
	v_add_f32_e32 v83, v83, v84
	v_fmac_f32_e32 v90, v102, v102
	v_add_f32_e32 v83, v83, v85
	v_add_f32_e32 v83, v90, v83
	v_add_f32_e32 v82, v82, v83
	ds_bpermute_b32 v83, v253, v82
	v_lshl_add_u64 v[90:91], v[112:113], 0, v[114:115]
	s_waitcnt lgkmcnt(0)
	v_add_f32_e32 v82, v82, v83
	ds_bpermute_b32 v83, v230, v82
	s_waitcnt vmcnt(0)
	v_pk_mul_f32 v[88:89], v[88:89], v[106:107]
	v_pk_mul_f32 v[84:85], v[86:87], v[104:105]
	v_pk_mul_f32 v[92:93], v[102:103], v[110:111]
	v_pk_mul_f32 v[86:87], v[100:101], v[108:109]
	v_cvt_pk_bf16_f32 v84, v84, v85
	v_cvt_pk_bf16_f32 v85, v88, v89
	v_cvt_pk_bf16_f32 v86, v86, v87
	v_cvt_pk_bf16_f32 v87, v92, v93
	v_lshl_add_u64 v[88:89], v[90:91], 1, s[12:13]
	global_store_dwordx4 v[88:89], v[84:87], off
	s_and_saveexec_b64 s[28:29], s[6:7]
	s_mov_b32 s66, 0x18e30000
	s_mov_b32 s67, 0x41000000
	s_cbranch_execz .LBB0_1060
	v_lshl_add_u64 v[84:85], v[98:99], 2, s[16:17]
	s_waitcnt lgkmcnt(0)
	v_add_f32_e32 v82, v82, v83
	flat_atomic_add_f32 v[84:85], v82
; __device__ __forceinline__ u32x4 pack8(f32x4 v0, f32x4 v1) { u32x4 w; w.x = cvt_pk_bf16(v0[0], v0[1]); w.y = cvt_pk_bf16(v0[2], v0[3]); w.z = cvt_pk_bf16(v1[0], v1[1]); w.w = cvt_pk_bf16(v1[2], v1[3]); return w; }
;     __device__ __forceinline__ void operator()(f32x4 (&acc)[2][2][4][2], const Unit& u, int wr, int wc, int fr, int fq) const {
;         const int row0 = u.pm * BM + wr * 64 + fr; const int colt = u.pn * BM + wc * 32 + 8 * fq;
; #pragma unroll
;         for (int ai = 0; ai < 2; ++ai)
; #pragma unroll
;             for (int m = 0; m < 4; ++m) { const int row = row0 + ai * HALF + m * 16; float ss = 0.f;
; #pragma unroll
;                 for (int bj = 0; bj < 2; ++bj) { const int col = colt + bj * HALF; const size_t off = (size_t)row * DM + col;
;                     const f32x4 x0 = *(const f32x4*)(in + off) + acc[ai][bj][m][0], x1 = *(const f32x4*)(in + off + 4) + acc[ai][bj][m][1];
;                     *(f32x4*)(out + off) = x0; *(f32x4*)(out + off + 4) = x1;
;                     const f32x4 g0 = *(const f32x4*)(g + col), g1 = *(const f32x4*)(g + col + 4);
;                     *(u32x4*)(xg + off) = pack8(x0 * g0, x1 * g1);
;                     ss += (x0[0] * x0[0] + x0[1] * x0[1]) + (x0[2] * x0[2] + x0[3] * x0[3]) + (x1[0] * x1[0] + x1[1] * x1[1]) + (x1[2] * x1[2] + x1[3] * x1[3]); }
;                 ss += __shfl_xor(ss, 16); ss += __shfl_xor(ss, 32);
;                 if (fq == 0) atomicAdd(sumsq + row, ss);
;                 if (m == 3) asm volatile("" ::: "memory"); }
.LBB0_1060:
	s_or_b64 exec, exec, s[28:29]
	v_or_b32_e32 v82, 48, v146
	s_waitcnt lgkmcnt(0)
	v_ashrrev_i32_e32 v83, 31, v82
	v_lshlrev_b64 v[96:97], 10, v[82:83]
	v_lshl_add_u64 v[92:93], v[96:97], 0, v[144:145]
	v_lshlrev_b64 v[94:95], 2, v[92:93]
	v_lshl_add_u64 v[98:99], s[4:5], 0, v[94:95]
	global_load_dwordx4 v[84:87], v[98:99], off
	global_load_dwordx4 v[88:91], v[98:99], off offset:16
	v_lshl_add_u64 v[94:95], s[2:3], 0, v[94:95]
	v_lshl_add_u64 v[92:93], v[92:93], 1, s[12:13]
	s_waitcnt vmcnt(0) lgkmcnt(0)
	v_pk_add_f32 v[80:81], v[80:81], v[86:87]
	v_pk_add_f32 v[78:79], v[78:79], v[84:85]
	v_pk_add_f32 v[76:77], v[76:77], v[90:91]
	v_pk_add_f32 v[74:75], v[74:75], v[88:89]
	global_store_dwordx4 v[94:95], v[78:81], off
	global_store_dwordx4 v[94:95], v[74:77], off offset:16
	global_load_dwordx4 v[84:87], v[142:143], off
	global_load_dwordx4 v[88:91], v[142:143], off offset:16
	s_waitcnt vmcnt(0)
	v_pk_mul_f32 v[86:87], v[80:81], v[86:87]
	v_pk_mul_f32 v[84:85], v[78:79], v[84:85]
	v_pk_mul_f32 v[90:91], v[76:77], v[90:91]
	v_pk_mul_f32 v[88:89], v[74:75], v[88:89]
	v_cvt_pk_bf16_f32 v84, v84, v85
	v_cvt_pk_bf16_f32 v85, v86, v87
	v_cvt_pk_bf16_f32 v86, v88, v89
	v_cvt_pk_bf16_f32 v87, v90, v91
	global_store_dwordx4 v[92:93], v[84:87], off
	global_load_dwordx4 v[84:87], v[98:99], off offset:512
	s_nop 0
	global_load_dwordx4 v[88:91], v[98:99], off offset:528
	s_waitcnt vmcnt(0) lgkmcnt(0)
	v_pk_add_f32 v[72:73], v[72:73], v[86:87]
	v_pk_add_f32 v[70:71], v[70:71], v[84:85]
	v_pk_add_f32 v[86:87], v[68:69], v[90:91]
	v_pk_add_f32 v[84:85], v[66:67], v[88:89]
	global_store_dwordx4 v[94:95], v[70:73], off offset:512
	global_store_dwordx4 v[94:95], v[84:87], off offset:528
	global_load_dwordx4 v[88:91], v[142:143], off offset:512
	s_nop 0
	global_load_dwordx4 v[92:95], v[142:143], off offset:528
	v_mul_f32_e32 v66, v79, v79
	v_mul_f32_e32 v67, v81, v81
	v_mul_f32_e32 v68, v75, v75
	v_fmac_f32_e32 v66, v78, v78
	v_fmac_f32_e32 v67, v80, v80
	v_mul_f32_e32 v69, v77, v77
	v_fmac_f32_e32 v68, v74, v74
	v_add_f32_e32 v66, v66, v67
	v_fmac_f32_e32 v69, v76, v76
	v_add_f32_e32 v66, v66, v68
	v_mul_f32_e32 v67, v71, v71
	v_mul_f32_e32 v68, v73, v73
	v_add_f32_e32 v66, v69, v66
	v_mul_f32_e32 v69, v85, v85
	v_fmac_f32_e32 v67, v70, v70
	v_fmac_f32_e32 v68, v72, v72
	v_mul_f32_e32 v74, v87, v87
	v_fmac_f32_e32 v69, v84, v84
	v_add_f32_e32 v67, v67, v68
	v_fmac_f32_e32 v74, v86, v86
	v_add_f32_e32 v67, v67, v69
	v_add_f32_e32 v67, v74, v67
	v_add_f32_e32 v66, v66, v67
	ds_bpermute_b32 v67, v253, v66
	v_lshl_add_u64 v[74:75], v[96:97], 0, v[114:115]
	s_waitcnt lgkmcnt(0)
	v_add_f32_e32 v66, v66, v67
	ds_bpermute_b32 v67, v230, v66
	s_waitcnt vmcnt(0)
	v_pk_mul_f32 v[72:73], v[72:73], v[90:91]
	v_pk_mul_f32 v[68:69], v[70:71], v[88:89]
	v_pk_mul_f32 v[76:77], v[86:87], v[94:95]
	v_pk_mul_f32 v[70:71], v[84:85], v[92:93]
	v_cvt_pk_bf16_f32 v68, v68, v69
	v_cvt_pk_bf16_f32 v69, v72, v73
	v_cvt_pk_bf16_f32 v70, v70, v71
	v_cvt_pk_bf16_f32 v71, v76, v77
	v_lshl_add_u64 v[72:73], v[74:75], 1, s[12:13]
	global_store_dwordx4 v[72:73], v[68:71], off
	s_and_saveexec_b64 s[28:29], s[6:7]
	s_cbranch_execz .LBB0_1062
	v_lshl_add_u64 v[68:69], v[82:83], 2, s[16:17]
	s_waitcnt lgkmcnt(0)
	v_add_f32_e32 v66, v66, v67
	flat_atomic_add_f32 v[68:69], v66
.LBB0_1062:
	s_or_b64 exec, exec, s[28:29]
	v_add_u32_e32 v66, 0x80, v146
	s_waitcnt lgkmcnt(0)
	v_ashrrev_i32_e32 v67, 31, v66
	v_lshlrev_b64 v[80:81], 10, v[66:67]
	v_lshl_add_u64 v[76:77], v[80:81], 0, v[144:145]
	v_lshlrev_b64 v[78:79], 2, v[76:77]
	v_lshl_add_u64 v[82:83], s[4:5], 0, v[78:79]
	global_load_dwordx4 v[68:71], v[82:83], off
	global_load_dwordx4 v[72:75], v[82:83], off offset:16
	v_lshl_add_u64 v[78:79], s[2:3], 0, v[78:79]
	v_lshl_add_u64 v[76:77], v[76:77], 1, s[12:13]
	s_waitcnt vmcnt(0) lgkmcnt(0)
	v_pk_add_f32 v[64:65], v[64:65], v[70:71]
	v_pk_add_f32 v[62:63], v[62:63], v[68:69]
	v_pk_add_f32 v[60:61], v[60:61], v[74:75]
	v_pk_add_f32 v[58:59], v[58:59], v[72:73]
	global_store_dwordx4 v[78:79], v[62:65], off
	global_store_dwordx4 v[78:79], v[58:61], off offset:16
	global_load_dwordx4 v[68:71], v[142:143], off
	global_load_dwordx4 v[72:75], v[142:143], off offset:16
	s_waitcnt vmcnt(0)
	v_pk_mul_f32 v[70:71], v[64:65], v[70:71]
	v_pk_mul_f32 v[68:69], v[62:63], v[68:69]
	v_pk_mul_f32 v[74:75], v[60:61], v[74:75]
	v_pk_mul_f32 v[72:73], v[58:59], v[72:73]
	v_cvt_pk_bf16_f32 v68, v68, v69
	v_cvt_pk_bf16_f32 v69, v70, v71
	v_cvt_pk_bf16_f32 v70, v72, v73
	v_cvt_pk_bf16_f32 v71, v74, v75
	global_store_dwordx4 v[76:77], v[68:71], off
	global_load_dwordx4 v[68:71], v[82:83], off offset:512
	s_nop 0
	global_load_dwordx4 v[72:75], v[82:83], off offset:528
	s_waitcnt vmcnt(0) lgkmcnt(0)
	v_pk_add_f32 v[56:57], v[56:57], v[70:71]
	v_pk_add_f32 v[54:55], v[54:55], v[68:69]
	v_pk_add_f32 v[70:71], v[52:53], v[74:75]
	v_pk_add_f32 v[68:69], v[50:51], v[72:73]
	global_store_dwordx4 v[78:79], v[54:57], off offset:512
	global_store_dwordx4 v[78:79], v[68:71], off offset:528
	global_load_dwordx4 v[72:75], v[142:143], off offset:512
	s_nop 0
	global_load_dwordx4 v[76:79], v[142:143], off offset:528
	v_mul_f32_e32 v50, v63, v63
	v_mul_f32_e32 v51, v65, v65
	v_mul_f32_e32 v52, v59, v59
	v_fmac_f32_e32 v50, v62, v62
	v_fmac_f32_e32 v51, v64, v64
	v_mul_f32_e32 v53, v61, v61
	v_fmac_f32_e32 v52, v58, v58
	v_add_f32_e32 v50, v50, v51
	v_fmac_f32_e32 v53, v60, v60
	v_add_f32_e32 v50, v50, v52
	v_mul_f32_e32 v51, v55, v55
	v_mul_f32_e32 v52, v57, v57
	v_add_f32_e32 v50, v53, v50
	v_mul_f32_e32 v53, v69, v69
	v_fmac_f32_e32 v51, v54, v54
	v_fmac_f32_e32 v52, v56, v56
	v_mul_f32_e32 v58, v71, v71
	v_fmac_f32_e32 v53, v68, v68
	v_add_f32_e32 v51, v51, v52
	v_fmac_f32_e32 v58, v70, v70
	v_add_f32_e32 v51, v51, v53
	v_add_f32_e32 v51, v58, v51
	v_add_f32_e32 v50, v50, v51
	ds_bpermute_b32 v51, v253, v50
	v_lshl_add_u64 v[58:59], v[80:81], 0, v[114:115]
	s_waitcnt lgkmcnt(0)
	v_add_f32_e32 v50, v50, v51
	ds_bpermute_b32 v51, v230, v50
	s_waitcnt vmcnt(0)
	v_pk_mul_f32 v[56:57], v[56:57], v[74:75]
	v_pk_mul_f32 v[52:53], v[54:55], v[72:73]
	v_pk_mul_f32 v[60:61], v[70:71], v[78:79]
	v_pk_mul_f32 v[54:55], v[68:69], v[76:77]
	v_cvt_pk_bf16_f32 v52, v52, v53
	v_cvt_pk_bf16_f32 v53, v56, v57
	v_cvt_pk_bf16_f32 v54, v54, v55
	v_cvt_pk_bf16_f32 v55, v60, v61
	v_lshl_add_u64 v[56:57], v[58:59], 1, s[12:13]
	global_store_dwordx4 v[56:57], v[52:55], off
	s_and_saveexec_b64 s[28:29], s[6:7]
	s_cbranch_execz .LBB0_1064
	v_lshl_add_u64 v[52:53], v[66:67], 2, s[16:17]
	s_waitcnt lgkmcnt(0)
	v_add_f32_e32 v50, v50, v51
	flat_atomic_add_f32 v[52:53], v50
; __device__ __forceinline__ u32x4 pack8(f32x4 v0, f32x4 v1) { u32x4 w; w.x = cvt_pk_bf16(v0[0], v0[1]); w.y = cvt_pk_bf16(v0[2], v0[3]); w.z = cvt_pk_bf16(v1[0], v1[1]); w.w = cvt_pk_bf16(v1[2], v1[3]); return w; }
;     __device__ __forceinline__ void operator()(f32x4 (&acc)[2][2][4][2], const Unit& u, int wr, int wc, int fr, int fq) const {
;         const int row0 = u.pm * BM + wr * 64 + fr; const int colt = u.pn * BM + wc * 32 + 8 * fq;
; #pragma unroll
;         for (int ai = 0; ai < 2; ++ai)
; #pragma unroll
;             for (int m = 0; m < 4; ++m) { const int row = row0 + ai * HALF + m * 16; float ss = 0.f;
; #pragma unroll
;                 for (int bj = 0; bj < 2; ++bj) { const int col = colt + bj * HALF; const size_t off = (size_t)row * DM + col;
;                     const f32x4 x0 = *(const f32x4*)(in + off) + acc[ai][bj][m][0], x1 = *(const f32x4*)(in + off + 4) + acc[ai][bj][m][1];
;                     *(f32x4*)(out + off) = x0; *(f32x4*)(out + off + 4) = x1;
;                     const f32x4 g0 = *(const f32x4*)(g + col), g1 = *(const f32x4*)(g + col + 4);
;                     *(u32x4*)(xg + off) = pack8(x0 * g0, x1 * g1);
;                     ss += (x0[0] * x0[0] + x0[1] * x0[1]) + (x0[2] * x0[2] + x0[3] * x0[3]) + (x1[0] * x1[0] + x1[1] * x1[1]) + (x1[2] * x1[2] + x1[3] * x1[3]); }
;                 ss += __shfl_xor(ss, 16); ss += __shfl_xor(ss, 32);
;                 if (fq == 0) atomicAdd(sumsq + row, ss);
;                 if (m == 3) asm volatile("" ::: "memory"); }
.LBB0_1064:
	s_or_b64 exec, exec, s[28:29]
	v_add_u32_e32 v50, 0x90, v146
	s_waitcnt lgkmcnt(0)
	v_ashrrev_i32_e32 v51, 31, v50
	v_lshlrev_b64 v[64:65], 10, v[50:51]
	v_lshl_add_u64 v[60:61], v[64:65], 0, v[144:145]
	v_lshlrev_b64 v[62:63], 2, v[60:61]
	v_lshl_add_u64 v[66:67], s[4:5], 0, v[62:63]
	global_load_dwordx4 v[52:55], v[66:67], off
	global_load_dwordx4 v[56:59], v[66:67], off offset:16
	v_lshl_add_u64 v[62:63], s[2:3], 0, v[62:63]
	v_lshl_add_u64 v[60:61], v[60:61], 1, s[12:13]
	s_waitcnt vmcnt(0) lgkmcnt(0)
	v_pk_add_f32 v[48:49], v[48:49], v[54:55]
	v_pk_add_f32 v[46:47], v[46:47], v[52:53]
	v_pk_add_f32 v[44:45], v[44:45], v[58:59]
	v_pk_add_f32 v[42:43], v[42:43], v[56:57]
	global_store_dwordx4 v[62:63], v[46:49], off
	global_store_dwordx4 v[62:63], v[42:45], off offset:16
	global_load_dwordx4 v[52:55], v[142:143], off
	global_load_dwordx4 v[56:59], v[142:143], off offset:16
	s_waitcnt vmcnt(0)
	v_pk_mul_f32 v[54:55], v[48:49], v[54:55]
	v_pk_mul_f32 v[52:53], v[46:47], v[52:53]
	v_pk_mul_f32 v[58:59], v[44:45], v[58:59]
	v_pk_mul_f32 v[56:57], v[42:43], v[56:57]
	v_cvt_pk_bf16_f32 v52, v52, v53
	v_cvt_pk_bf16_f32 v53, v54, v55
	v_cvt_pk_bf16_f32 v54, v56, v57
	v_cvt_pk_bf16_f32 v55, v58, v59
	global_store_dwordx4 v[60:61], v[52:55], off
	global_load_dwordx4 v[52:55], v[66:67], off offset:512
	s_nop 0
	global_load_dwordx4 v[56:59], v[66:67], off offset:528
	s_waitcnt vmcnt(0) lgkmcnt(0)
	v_pk_add_f32 v[40:41], v[40:41], v[54:55]
	v_pk_add_f32 v[38:39], v[38:39], v[52:53]
	v_pk_add_f32 v[54:55], v[36:37], v[58:59]
	v_pk_add_f32 v[52:53], v[34:35], v[56:57]
	global_store_dwordx4 v[62:63], v[38:41], off offset:512
	global_store_dwordx4 v[62:63], v[52:55], off offset:528
	global_load_dwordx4 v[56:59], v[142:143], off offset:512
	s_nop 0
	global_load_dwordx4 v[60:63], v[142:143], off offset:528
	v_mul_f32_e32 v34, v47, v47
	v_mul_f32_e32 v35, v49, v49
	v_mul_f32_e32 v36, v43, v43
	v_fmac_f32_e32 v34, v46, v46
	v_fmac_f32_e32 v35, v48, v48
	v_mul_f32_e32 v37, v45, v45
	v_fmac_f32_e32 v36, v42, v42
	v_add_f32_e32 v34, v34, v35
	v_fmac_f32_e32 v37, v44, v44
	v_add_f32_e32 v34, v34, v36
	v_mul_f32_e32 v35, v39, v39
	v_mul_f32_e32 v36, v41, v41
	v_add_f32_e32 v34, v37, v34
	v_mul_f32_e32 v37, v53, v53
	v_fmac_f32_e32 v35, v38, v38
	v_fmac_f32_e32 v36, v40, v40
	v_mul_f32_e32 v42, v55, v55
	v_fmac_f32_e32 v37, v52, v52
	v_add_f32_e32 v35, v35, v36
	v_fmac_f32_e32 v42, v54, v54
	v_add_f32_e32 v35, v35, v37
	v_add_f32_e32 v35, v42, v35
	v_add_f32_e32 v34, v34, v35
	ds_bpermute_b32 v35, v253, v34
	v_lshl_add_u64 v[42:43], v[64:65], 0, v[114:115]
	s_waitcnt lgkmcnt(0)
	v_add_f32_e32 v34, v34, v35
	ds_bpermute_b32 v35, v230, v34
	s_waitcnt vmcnt(0)
	v_pk_mul_f32 v[40:41], v[40:41], v[58:59]
	v_pk_mul_f32 v[36:37], v[38:39], v[56:57]
	v_pk_mul_f32 v[44:45], v[54:55], v[62:63]
	v_pk_mul_f32 v[38:39], v[52:53], v[60:61]
	v_cvt_pk_bf16_f32 v36, v36, v37
	v_cvt_pk_bf16_f32 v37, v40, v41
	v_cvt_pk_bf16_f32 v38, v38, v39
	v_cvt_pk_bf16_f32 v39, v44, v45
	v_lshl_add_u64 v[40:41], v[42:43], 1, s[12:13]
	global_store_dwordx4 v[40:41], v[36:39], off
	s_and_saveexec_b64 s[28:29], s[6:7]
	s_cbranch_execz .LBB0_1066
	v_lshl_add_u64 v[36:37], v[50:51], 2, s[16:17]
	s_waitcnt lgkmcnt(0)
	v_add_f32_e32 v34, v34, v35
	flat_atomic_add_f32 v[36:37], v34
; __device__ __forceinline__ u32x4 pack8(f32x4 v0, f32x4 v1) { u32x4 w; w.x = cvt_pk_bf16(v0[0], v0[1]); w.y = cvt_pk_bf16(v0[2], v0[3]); w.z = cvt_pk_bf16(v1[0], v1[1]); w.w = cvt_pk_bf16(v1[2], v1[3]); return w; }
;     __device__ __forceinline__ void operator()(f32x4 (&acc)[2][2][4][2], const Unit& u, int wr, int wc, int fr, int fq) const {
;     ...
;             for (int m = 0; m < 4; ++m) { const int row = row0 + ai * HALF + m * 16; float ss = 0.f;
; #pragma unroll
;                 for (int bj = 0; bj < 2; ++bj) { const int col = colt + bj * HALF; const size_t off = (size_t)row * DM + col;
;                     const f32x4 x0 = *(const f32x4*)(in + off) + acc[ai][bj][m][0], x1 = *(const f32x4*)(in + off + 4) + acc[ai][bj][m][1];
;                     *(f32x4*)(out + off) = x0; *(f32x4*)(out + off + 4) = x1;
;                     const f32x4 g0 = *(const f32x4*)(g + col), g1 = *(const f32x4*)(g + col + 4);
;                     *(u32x4*)(xg + off) = pack8(x0 * g0, x1 * g1);
;                     ss += (x0[0] * x0[0] + x0[1] * x0[1]) + (x0[2] * x0[2] + x0[3] * x0[3]) + (x1[0] * x1[0] + x1[1] * x1[1]) + (x1[2] * x1[2] + x1[3] * x1[3]); }
;                 ss += __shfl_xor(ss, 16); ss += __shfl_xor(ss, 32);
;                 if (fq == 0) atomicAdd(sumsq + row, ss);
.LBB0_1066:
	s_or_b64 exec, exec, s[28:29]
	v_add_u32_e32 v34, 0xa0, v146
	s_waitcnt lgkmcnt(0)
	v_ashrrev_i32_e32 v35, 31, v34
	v_lshlrev_b64 v[48:49], 10, v[34:35]
	v_lshl_add_u64 v[44:45], v[48:49], 0, v[144:145]
	v_lshlrev_b64 v[46:47], 2, v[44:45]
	v_lshl_add_u64 v[50:51], s[4:5], 0, v[46:47]
	global_load_dwordx4 v[36:39], v[50:51], off
	global_load_dwordx4 v[40:43], v[50:51], off offset:16
	v_lshl_add_u64 v[46:47], s[2:3], 0, v[46:47]
	v_lshl_add_u64 v[44:45], v[44:45], 1, s[12:13]
	s_waitcnt vmcnt(0) lgkmcnt(0)
	v_pk_add_f32 v[32:33], v[32:33], v[38:39]
	v_pk_add_f32 v[30:31], v[30:31], v[36:37]
	v_pk_add_f32 v[28:29], v[28:29], v[42:43]
	v_pk_add_f32 v[26:27], v[26:27], v[40:41]
	global_store_dwordx4 v[46:47], v[30:33], off
	global_store_dwordx4 v[46:47], v[26:29], off offset:16
	global_load_dwordx4 v[36:39], v[142:143], off
	global_load_dwordx4 v[40:43], v[142:143], off offset:16
	s_waitcnt vmcnt(0)
	v_pk_mul_f32 v[38:39], v[32:33], v[38:39]
	v_pk_mul_f32 v[36:37], v[30:31], v[36:37]
	v_pk_mul_f32 v[42:43], v[28:29], v[42:43]
	v_pk_mul_f32 v[40:41], v[26:27], v[40:41]
	v_cvt_pk_bf16_f32 v36, v36, v37
	v_cvt_pk_bf16_f32 v37, v38, v39
	v_cvt_pk_bf16_f32 v38, v40, v41
	v_cvt_pk_bf16_f32 v39, v42, v43
	global_store_dwordx4 v[44:45], v[36:39], off
	global_load_dwordx4 v[36:39], v[50:51], off offset:512
	s_nop 0
	global_load_dwordx4 v[40:43], v[50:51], off offset:528
	s_waitcnt vmcnt(0) lgkmcnt(0)
	v_pk_add_f32 v[24:25], v[24:25], v[38:39]
	v_pk_add_f32 v[22:23], v[22:23], v[36:37]
	v_pk_add_f32 v[38:39], v[20:21], v[42:43]
	v_pk_add_f32 v[36:37], v[18:19], v[40:41]
	global_store_dwordx4 v[46:47], v[22:25], off offset:512
	global_store_dwordx4 v[46:47], v[36:39], off offset:528
	global_load_dwordx4 v[40:43], v[142:143], off offset:512
	s_nop 0
	global_load_dwordx4 v[44:47], v[142:143], off offset:528
	v_mul_f32_e32 v18, v31, v31
	v_mul_f32_e32 v19, v33, v33
	v_mul_f32_e32 v20, v27, v27
	v_fmac_f32_e32 v18, v30, v30
	v_fmac_f32_e32 v19, v32, v32
	v_mul_f32_e32 v21, v29, v29
	v_fmac_f32_e32 v20, v26, v26
	v_add_f32_e32 v18, v18, v19
	v_fmac_f32_e32 v21, v28, v28
	v_add_f32_e32 v18, v18, v20
	v_mul_f32_e32 v19, v23, v23
	v_mul_f32_e32 v20, v25, v25
	v_add_f32_e32 v18, v21, v18
	v_mul_f32_e32 v21, v37, v37
	v_fmac_f32_e32 v19, v22, v22
	v_fmac_f32_e32 v20, v24, v24
	v_mul_f32_e32 v26, v39, v39
	v_fmac_f32_e32 v21, v36, v36
	v_add_f32_e32 v19, v19, v20
	v_fmac_f32_e32 v26, v38, v38
	v_add_f32_e32 v19, v19, v21
	v_add_f32_e32 v19, v26, v19
	v_add_f32_e32 v18, v18, v19
	ds_bpermute_b32 v19, v253, v18
	v_lshl_add_u64 v[26:27], v[48:49], 0, v[114:115]
	s_waitcnt lgkmcnt(0)
	v_add_f32_e32 v18, v18, v19
	ds_bpermute_b32 v19, v230, v18
	s_waitcnt vmcnt(0)
	v_pk_mul_f32 v[24:25], v[24:25], v[42:43]
	v_pk_mul_f32 v[20:21], v[22:23], v[40:41]
	v_pk_mul_f32 v[28:29], v[38:39], v[46:47]
	v_pk_mul_f32 v[22:23], v[36:37], v[44:45]
	v_cvt_pk_bf16_f32 v20, v20, v21
	v_cvt_pk_bf16_f32 v21, v24, v25
	v_cvt_pk_bf16_f32 v22, v22, v23
	v_cvt_pk_bf16_f32 v23, v28, v29
	v_lshl_add_u64 v[24:25], v[26:27], 1, s[12:13]
	global_store_dwordx4 v[24:25], v[20:23], off
	s_and_saveexec_b64 s[28:29], s[6:7]
	s_cbranch_execz .LBB0_1068
	v_lshl_add_u64 v[20:21], v[34:35], 2, s[16:17]
	s_waitcnt lgkmcnt(0)
	v_add_f32_e32 v18, v18, v19
	flat_atomic_add_f32 v[20:21], v18
.LBB0_1068:
	s_or_b64 exec, exec, s[28:29]
	v_add_u32_e32 v18, 0xb0, v146
	s_waitcnt lgkmcnt(0)
	v_ashrrev_i32_e32 v19, 31, v18
	v_lshlrev_b64 v[32:33], 10, v[18:19]
	v_lshl_add_u64 v[28:29], v[32:33], 0, v[144:145]
	v_lshlrev_b64 v[30:31], 2, v[28:29]
	v_lshl_add_u64 v[34:35], s[4:5], 0, v[30:31]
	global_load_dwordx4 v[20:23], v[34:35], off
	global_load_dwordx4 v[24:27], v[34:35], off offset:16
	v_lshl_add_u64 v[30:31], s[2:3], 0, v[30:31]
	v_lshl_add_u64 v[28:29], v[28:29], 1, s[12:13]
	s_waitcnt vmcnt(0) lgkmcnt(0)
	v_pk_add_f32 v[16:17], v[16:17], v[22:23]
	v_pk_add_f32 v[14:15], v[14:15], v[20:21]
	v_pk_add_f32 v[12:13], v[12:13], v[26:27]
	v_pk_add_f32 v[10:11], v[10:11], v[24:25]
	global_store_dwordx4 v[30:31], v[14:17], off
	global_store_dwordx4 v[30:31], v[10:13], off offset:16
	global_load_dwordx4 v[20:23], v[142:143], off
	global_load_dwordx4 v[24:27], v[142:143], off offset:16
	s_waitcnt vmcnt(0)
	v_pk_mul_f32 v[22:23], v[16:17], v[22:23]
	v_pk_mul_f32 v[20:21], v[14:15], v[20:21]
	v_pk_mul_f32 v[26:27], v[12:13], v[26:27]
	v_pk_mul_f32 v[24:25], v[10:11], v[24:25]
	v_cvt_pk_bf16_f32 v20, v20, v21
	v_cvt_pk_bf16_f32 v21, v22, v23
	v_cvt_pk_bf16_f32 v22, v24, v25
	v_cvt_pk_bf16_f32 v23, v26, v27
	global_store_dwordx4 v[28:29], v[20:23], off
	global_load_dwordx4 v[20:23], v[34:35], off offset:512
	s_nop 0
	global_load_dwordx4 v[24:27], v[34:35], off offset:528
	s_waitcnt vmcnt(0) lgkmcnt(0)
	v_pk_add_f32 v[8:9], v[8:9], v[22:23]
	v_pk_add_f32 v[6:7], v[6:7], v[20:21]
	v_pk_add_f32 v[22:23], v[4:5], v[26:27]
	v_pk_add_f32 v[20:21], v[2:3], v[24:25]
	global_store_dwordx4 v[30:31], v[6:9], off offset:512
	global_store_dwordx4 v[30:31], v[20:23], off offset:528
	global_load_dwordx4 v[24:27], v[142:143], off offset:512
	s_nop 0
	global_load_dwordx4 v[28:31], v[142:143], off offset:528
	v_mul_f32_e32 v2, v15, v15
	v_mul_f32_e32 v3, v17, v17
	v_mul_f32_e32 v4, v11, v11
	v_fmac_f32_e32 v2, v14, v14
	v_fmac_f32_e32 v3, v16, v16
	v_mul_f32_e32 v5, v13, v13
	v_fmac_f32_e32 v4, v10, v10
	v_add_f32_e32 v2, v2, v3
	v_fmac_f32_e32 v5, v12, v12
	v_add_f32_e32 v2, v2, v4
	v_mul_f32_e32 v3, v7, v7
	v_mul_f32_e32 v4, v9, v9
	v_add_f32_e32 v2, v5, v2
	v_mul_f32_e32 v5, v21, v21
	v_fmac_f32_e32 v3, v6, v6
	v_fmac_f32_e32 v4, v8, v8
	v_mul_f32_e32 v10, v23, v23
	v_fmac_f32_e32 v5, v20, v20
	v_add_f32_e32 v3, v3, v4
	v_fmac_f32_e32 v10, v22, v22
	v_add_f32_e32 v3, v3, v5
	v_add_f32_e32 v3, v10, v3
	v_add_f32_e32 v2, v2, v3
	ds_bpermute_b32 v3, v253, v2
	v_lshl_add_u64 v[10:11], v[32:33], 0, v[114:115]
	s_waitcnt lgkmcnt(0)
	v_add_f32_e32 v2, v2, v3
	ds_bpermute_b32 v3, v230, v2
	s_waitcnt vmcnt(0)
	v_pk_mul_f32 v[8:9], v[8:9], v[26:27]
	v_pk_mul_f32 v[4:5], v[6:7], v[24:25]
	v_pk_mul_f32 v[12:13], v[22:23], v[30:31]
	v_pk_mul_f32 v[6:7], v[20:21], v[28:29]
	v_cvt_pk_bf16_f32 v4, v4, v5
	v_cvt_pk_bf16_f32 v5, v8, v9
	v_cvt_pk_bf16_f32 v6, v6, v7
	v_cvt_pk_bf16_f32 v7, v12, v13
	v_lshl_add_u64 v[8:9], v[10:11], 1, s[12:13]
	global_store_dwordx4 v[8:9], v[4:7], off
	s_and_saveexec_b64 s[28:29], s[6:7]
	s_cbranch_execz .LBB0_1070
	v_lshl_add_u64 v[4:5], v[18:19], 2, s[16:17]
	s_waitcnt lgkmcnt(0)
	v_add_f32_e32 v2, v2, v3
	flat_atomic_add_f32 v[4:5], v2

; __device__ __forceinline__ unsigned cvt_pk_bf16(float lo, float hi) { const f32x2 v = {lo, hi}; const bf16x2_t b = __builtin_convertvector(v, bf16x2_t); return __builtin_bit_cast(unsigned, b); }
; __device__ __forceinline__ float fast_rsq(float x) { return __builtin_amdgcn_rsqf(x); }
;     __device__ __forceinline__ void operator()(f32x4 (&acc)[2][2][4][2], const Unit& u, int wr, int wc, int fr, int fq) const {
;         float rs[2][4];
; #pragma unroll
;         for (int ai = 0; ai < 2; ++ai)
; #pragma unroll
;             for (int m = 0; m < 4; ++m) rs[ai][m] = fast_rsq(sumsq[u.pm * BM + ai * HALF + wr * 64 + m * 16 + fr] * (1.0f / DM) + EPS);
; #pragma unroll
;         for (int n = 0; n < 2; ++n) {
;             const int ch0 = u.pn * 128 + wc * 32 + 8 * fq + 4 * n;
;             const f32x4 wg0 = *(const f32x4*)(cw + ch0), wg1 = *(const f32x4*)(cw + DFF2 + ch0), wg2 = *(const f32x4*)(cw + 2 * DFF2 + ch0), bg = *(const f32x4*)(cb + ch0);
;             const f32x4 wv0 = *(const f32x4*)(cw + DFF + ch0), wv1 = *(const f32x4*)(cw + DFF2 + DFF + ch0), wv2 = *(const f32x4*)(cw + 2 * DFF2 + DFF + ch0), bv = *(const f32x4*)(cb + DFF + ch0);
; #pragma unroll
;             for (int ai = 0; ai < 2; ++ai) {
;                 const int blk = u.pm * 4 + ai * 2 + wr;
;                 f32x4 pg = {0.f, 0.f, 0.f, 0.f}, pv = {0.f, 0.f, 0.f, 0.f};
; #pragma unroll
;                 for (int m = 0; m < 4; ++m) {
;                     const int row = u.pm * BM + ai * HALF + wr * 64 + m * 16 + fr;
;                     const f32x4 gq = acc[ai][0][m][n] * rs[ai][m], vq = acc[ai][1][m][n] * rs[ai][m];
;                     f32x4 g1, g2, v1, v2;
; #pragma unroll
;                     for (int e = 0; e < 4; ++e) {
;                         g1[e] = dpp_ror1(fr == 15 ? pg[e] : gq[e]); g2[e] = dpp_ror2(fr >= 14 ? pg[e] : gq[e]); v1[e] = dpp_ror1(fr == 15 ? pv[e] : vq[e]); v2[e] = dpp_ror2(fr >= 14 ? pv[e] : vq[e]); }
;                     const f32x4 cg = bg + wg0 * g2 + wg1 * g1 + wg2 * gq, cv = bv + wv0 * v2 + wv1 * v1 + wv2 * vq;
;                     {
;                         u32x2 w; w.x = cvt_pk_bf16(gelu_tanh(cg[0]) * cv[0], gelu_tanh(cg[1]) * cv[1]); w.y = cvt_pk_bf16(gelu_tanh(cg[2]) * cv[2], gelu_tanh(cg[3]) * cv[3]);
;                         *(u32x2*)(act + (size_t)row * DFF + ch0) = w; }
.LBB0_1134:
	v_lshl_add_u32 v176, s48, 8, v1
	v_ashrrev_i32_e32 v177, 31, v176
	v_lshl_add_u64 v[114:115], v[176:177], 2, s[18:19]
	global_load_dword v177, v[114:115], off
	v_lshl_or_b32 v188, s50, 7, v232
	v_ashrrev_i32_e32 v189, 31, v188
	v_lshlrev_b64 v[114:115], 2, v[188:189]
	v_or_b32_e32 v214, 16, v176
	v_lshl_add_u64 v[190:191], s[2:3], 0, v[114:115]
	v_lshl_add_u64 v[116:117], s[22:23], 0, v[114:115]
	v_or_b32_e32 v212, 32, v176
	v_or_b32_e32 v210, 48, v176
	v_lshl_add_u64 v[118:119], s[24:25], 0, v[114:115]
	v_lshl_add_u64 v[192:193], s[38:39], 0, v[114:115]
	global_load_dwordx4 v[134:137], v[190:191], off
	global_load_dwordx4 v[138:141], v[192:193], off
	global_load_dwordx4 v[122:125], v[116:117], off
	v_lshl_add_u64 v[116:117], s[34:35], 0, v[114:115]
	v_add_u32_e32 v208, 0x80, v176
	v_add_u32_e32 v206, 0x90, v176
	v_add_u32_e32 v204, 0xa0, v176
	v_add_u32_e32 v202, 0xb0, v176
	v_ashrrev_i32_e32 v215, 31, v214
	v_lshl_add_u64 v[120:121], s[26:27], 0, v[114:115]
	global_load_dwordx4 v[142:145], v[118:119], off
	global_load_dwordx4 v[126:129], v[120:121], off
	global_load_dwordx4 v[130:133], v[116:117], off
	v_lshl_add_u64 v[116:117], s[28:29], 0, v[114:115]
	v_lshl_add_u64 v[114:115], s[30:31], 0, v[114:115]
	v_ashrrev_i32_e32 v213, 31, v212
	v_ashrrev_i32_e32 v211, 31, v210
	v_ashrrev_i32_e32 v209, 31, v208
	v_ashrrev_i32_e32 v207, 31, v206
	v_ashrrev_i32_e32 v205, 31, v204
	v_ashrrev_i32_e32 v203, 31, v202
	v_lshl_add_u64 v[178:179], v[214:215], 2, s[18:19]
	global_load_dwordx4 v[118:121], v[116:117], off
	v_lshl_add_u64 v[182:183], v[212:213], 2, s[18:19]
	global_load_dwordx4 v[114:117], v[114:115], off
	v_lshl_add_u64 v[184:185], v[210:211], 2, s[18:19]
	v_lshl_add_u64 v[194:195], v[208:209], 2, s[18:19]
	v_lshl_add_u64 v[198:199], v[206:207], 2, s[18:19]
	v_lshl_add_u64 v[226:227], v[204:205], 2, s[18:19]
	v_lshl_add_u64 v[228:229], v[202:203], 2, s[18:19]
	global_load_dword v196, v[178:179], off
	global_load_dword v186, v[182:183], off
	s_nop 0
	global_load_dword v178, v[184:185], off
	global_load_dword v201, v[194:195], off
	global_load_dword v197, v[198:199], off
	global_load_dword v187, v[226:227], off
	global_load_dword v179, v[228:229], off
	s_lshl_b32 s37, s48, 2
	s_add_i32 s48, s37, s74
	s_ashr_i32 s49, s48, 31
	v_lshl_add_u64 v[234:235], s[48:49], 2, v[170:171]
	s_movk_i32 s37, 0x5800
	v_mad_u64_u32 v[182:183], s[50:51], v234, s37, 0
	v_mad_i32_i24 v183, v235, s37, v183
	s_movk_i32 s41, 0x1600
	s_waitcnt vmcnt(0) lgkmcnt(0)
	v_fmamk_f32 v177, v177, 0x3a800000, v216
	v_rsq_f32_e32 v200, v177
	s_nop 0
	v_pk_mul_f32 v[158:159], v[158:159], v[200:201] op_sel_hi:[1,0]
	v_pk_mul_f32 v[154:155], v[154:155], v[200:201] op_sel_hi:[1,0]
	v_cndmask_b32_e64 v185, v158, 0, s[8:9]
	v_cndmask_b32_e64 v195, v154, 0, s[6:7]
	v_cndmask_b32_e64 v205, v159, 0, s[8:9]
	v_cndmask_b32_e64 v177, v158, 0, s[6:7]
	v_cndmask_b32_e64 v203, v159, 0, s[6:7]
	v_mov_b32_dpp v194, v185 row_ror:2 row_mask:0xf bank_mask:0xf bound_ctrl:1
	v_mov_b32_dpp v198, v195 row_ror:1 row_mask:0xf bank_mask:0xf bound_ctrl:1
	v_mov_b32_dpp v195, v205 row_ror:2 row_mask:0xf bank_mask:0xf bound_ctrl:1
	v_pk_mul_f32 v[160:161], v[160:161], v[200:201] op_sel_hi:[1,0]
	v_pk_mul_f32 v[156:157], v[156:157], v[200:201] op_sel_hi:[1,0]
	v_mov_b32_dpp v184, v177 row_ror:1 row_mask:0xf bank_mask:0xf bound_ctrl:1
	v_mov_b32_dpp v185, v203 row_ror:1 row_mask:0xf bank_mask:0xf bound_ctrl:1
	v_pk_fma_f32 v[194:195], v[134:135], v[194:195], v[138:139]
	v_cndmask_b32_e64 v229, v156, 0, s[8:9]
	v_cndmask_b32_e64 v235, v161, 0, s[6:7]
	v_cndmask_b32_e64 v237, v161, 0, s[8:9]
	v_cndmask_b32_e64 v177, v157, 0, s[6:7]
	v_pk_fma_f32 v[184:185], v[122:123], v[184:185], v[194:195]
	v_mov_b32_dpp v238, v229 row_ror:2 row_mask:0xf bank_mask:0xf bound_ctrl:1
	v_mov_b32_dpp v229, v235 row_ror:1 row_mask:0xf bank_mask:0xf bound_ctrl:1
	v_mov_b32_dpp v235, v237 row_ror:2 row_mask:0xf bank_mask:0xf bound_ctrl:1
	v_mov_b32_dpp v237, v177 row_ror:1 row_mask:0xf bank_mask:0xf bound_ctrl:1
	v_cndmask_b32_e64 v177, v157, 0, s[8:9]
	v_pk_fma_f32 v[184:185], v[158:159], v[142:143], v[184:185]
	v_cndmask_b32_e64 v213, v160, 0, s[8:9]
	v_mov_b32_dpp v239, v177 row_ror:2 row_mask:0xf bank_mask:0xf bound_ctrl:1
	v_mul_f32_e32 v177, 0x3d372713, v184
	v_mul_f32_e32 v177, v184, v177
	v_mul_f32_e32 v203, 0x3d372713, v185
	v_fma_f32 v177, v184, v177, v184
	v_mul_f32_e32 v203, v185, v203
	v_mul_f32_e32 v177, 0xc0135761, v177
	v_fma_f32 v203, v185, v203, v185
	v_cndmask_b32_e64 v211, v160, 0, s[6:7]
	v_mov_b32_dpp v234, v213 row_ror:2 row_mask:0xf bank_mask:0xf bound_ctrl:1
	v_exp_f32_e32 v177, v177
	v_mul_f32_e32 v203, 0xc0135761, v203
	v_mov_b32_dpp v228, v211 row_ror:1 row_mask:0xf bank_mask:0xf bound_ctrl:1
	v_pk_fma_f32 v[234:235], v[136:137], v[234:235], v[140:141]
	v_exp_f32_e32 v203, v203
	v_cndmask_b32_e64 v199, v154, 0, s[8:9]
	v_cndmask_b32_e64 v209, v155, 0, s[8:9]
	v_cndmask_b32_e64 v215, v156, 0, s[6:7]
	v_pk_fma_f32 v[228:229], v[124:125], v[228:229], v[234:235]
	v_cndmask_b32_e64 v207, v155, 0, s[6:7]
	v_mov_b32_dpp v226, v199 row_ror:2 row_mask:0xf bank_mask:0xf bound_ctrl:1
	v_mov_b32_dpp v227, v209 row_ror:2 row_mask:0xf bank_mask:0xf bound_ctrl:1
	v_mov_b32_dpp v236, v215 row_ror:1 row_mask:0xf bank_mask:0xf bound_ctrl:1
	v_pk_fma_f32 v[194:195], v[160:161], v[144:145], v[228:229]
	v_pk_fma_f32 v[228:229], v[128:129], v[238:239], v[132:133]
	v_mov_b32_dpp v199, v207 row_ror:1 row_mask:0xf bank_mask:0xf bound_ctrl:1
	v_pk_fma_f32 v[226:227], v[126:127], v[226:227], v[130:131]
	v_pk_fma_f32 v[228:229], v[120:121], v[236:237], v[228:229]
	v_add_f32_e32 v177, 1.0, v177
	v_pk_fma_f32 v[198:199], v[118:119], v[198:199], v[226:227]
	v_pk_fma_f32 v[226:227], v[156:157], v[116:117], v[228:229]
	v_rcp_f32_e32 v228, v177
	v_add_f32_e32 v177, 1.0, v203
	v_mul_f32_e32 v203, 0x3d372713, v194
	v_mul_f32_e32 v203, v194, v203
	v_mul_f32_e32 v205, 0x3d372713, v195
	v_fma_f32 v203, v194, v203, v194
	v_mul_f32_e32 v205, v195, v205
	v_mul_f32_e32 v203, 0xc0135761, v203
	v_fma_f32 v205, v195, v205, v195
	v_exp_f32_e32 v203, v203
	v_mul_f32_e32 v205, 0xc0135761, v205
	v_exp_f32_e32 v205, v205
	v_rcp_f32_e32 v229, v177
	v_add_f32_e32 v177, 1.0, v203
	v_rcp_f32_e32 v234, v177
	v_add_f32_e32 v177, 1.0, v205
	v_rcp_f32_e32 v235, v177
	v_pk_fma_f32 v[198:199], v[154:155], v[114:115], v[198:199]
	v_pk_mul_f32 v[184:185], v[184:185], v[228:229]
	v_pk_mul_f32 v[194:195], v[194:195], v[234:235]
	v_pk_mul_f32 v[184:185], v[198:199], v[184:185]
	v_pk_mul_f32 v[194:195], v[226:227], v[194:195]
	v_cvt_pk_bf16_f32 v184, v184, v185
	v_cvt_pk_bf16_f32 v185, v194, v195
	v_mov_b64_e32 v[194:195], s[14:15]
	v_mad_i64_i32 v[176:177], s[50:51], v176, s41, v[194:195]
	v_lshl_add_u64 v[198:199], v[188:189], 1, v[176:177]
	v_lshl_add_u64 v[176:177], s[16:17], 0, v[182:183]
	v_lshl_add_u64 v[194:195], v[188:189], 2, v[176:177]
	global_store_dwordx2 v[198:199], v[184:185], off
	s_and_saveexec_b64 s[50:51], s[10:11]
	s_mov_b32 s76, 0x16000
	s_mov_b32 s67, 0x41000000
	s_cbranch_execz .LBB0_1136
; __device__ __forceinline__ unsigned cvt_pk_bf16(float lo, float hi) { const f32x2 v = {lo, hi}; const bf16x2_t b = __builtin_convertvector(v, bf16x2_t); return __builtin_bit_cast(unsigned, b); }
; __device__ __forceinline__ float gelu_tanh(float x) { const float t = x + 0.044715f * x * x * x; return x * fast_rcp(1.0f + fast_exp2(-2.3022082f * t)); }
; __device__ __forceinline__ float dpp_ror1(float x) { return __builtin_bit_cast(float, __builtin_amdgcn_mov_dpp(__builtin_bit_cast(int, x), 0x121, 0xf, 0xf, true)); }
; __device__ __forceinline__ float dpp_ror2(float x) { return __builtin_bit_cast(float, __builtin_amdgcn_mov_dpp(__builtin_bit_cast(int, x), 0x122, 0xf, 0xf, true)); }
;     __device__ __forceinline__ void operator()(f32x4 (&acc)[2][2][4][2], const Unit& u, int wr, int wc, int fr, int fq) const {
;     ...
;                     const f32x4 gq = acc[ai][0][m][n] * rs[ai][m], vq = acc[ai][1][m][n] * rs[ai][m];
;                     f32x4 g1, g2, v1, v2;
; #pragma unroll
;                     for (int e = 0; e < 4; ++e) {
;                         g1[e] = dpp_ror1(fr == 15 ? pg[e] : gq[e]); g2[e] = dpp_ror2(fr >= 14 ? pg[e] : gq[e]); v1[e] = dpp_ror1(fr == 15 ? pv[e] : vq[e]); v2[e] = dpp_ror2(fr >= 14 ? pv[e] : vq[e]); }
;                     const f32x4 cg = bg + wg0 * g2 + wg1 * g1 + wg2 * gq, cv = bv + wv0 * v2 + wv1 * v1 + wv2 * vq;
;                     {
;                         u32x2 w; w.x = cvt_pk_bf16(gelu_tanh(cg[0]) * cv[0], gelu_tanh(cg[1]) * cv[1]); w.y = cvt_pk_bf16(gelu_tanh(cg[2]) * cv[2], gelu_tanh(cg[3]) * cv[3]);
;                         *(u32x2*)(act + (size_t)row * DFF + ch0) = w; }
;                     if (m == 0 && fr < 2) { float* hp = halo + ((size_t)blk * 4 + fr) * DFF2 + ch0; *(f32x4*)hp = gq; *(f32x4*)(hp + DFF) = vq; }
;                     if (m == 3 && fr >= 14) { float* hp = halo + ((size_t)blk * 4 + fr - 12) * DFF2 + ch0; *(f32x4*)hp = gq; *(f32x4*)(hp + DFF) = vq; }
	v_add_co_u32_e32 v182, vcc, 0x2000, v194
	global_store_dwordx4 v[194:195], v[158:161], off
	s_nop 0
	v_addc_co_u32_e32 v183, vcc, 0, v195, vcc
	global_store_dwordx4 v[182:183], v[154:157], off offset:3072
.LBB0_1136:
	s_or_b64 exec, exec, s[50:51]
	v_fmamk_f32 v182, v196, 0x3a800000, v216
	v_rsq_f32_e32 v196, v182
	v_fmamk_f32 v182, v186, 0x3a800000, v216
	v_rsq_f32_e32 v186, v182
	v_fmamk_f32 v178, v178, 0x3a800000, v216
	v_pk_mul_f32 v[150:151], v[150:151], v[196:197] op_sel_hi:[1,0]
	v_pk_mul_f32 v[182:183], v[146:147], v[196:197] op_sel_hi:[1,0]
	v_cndmask_b32_e64 v147, v150, v158, s[8:9]
	v_cndmask_b32_e64 v146, v150, v158, s[6:7]
	v_pk_mul_f32 v[152:153], v[152:153], v[196:197] op_sel_hi:[1,0]
	v_mov_b32_dpp v158, v147 row_ror:2 row_mask:0xf bank_mask:0xf bound_ctrl:1
	v_cndmask_b32_e64 v147, v182, v154, s[6:7]
	v_pk_mul_f32 v[148:149], v[148:149], v[196:197] op_sel_hi:[1,0]
	v_cndmask_b32_e64 v203, v152, v160, s[6:7]
	v_mov_b32_dpp v184, v147 row_ror:1 row_mask:0xf bank_mask:0xf bound_ctrl:1
	v_cndmask_b32_e64 v147, v182, v154, s[8:9]
	v_mov_b32_dpp v226, v203 row_ror:1 row_mask:0xf bank_mask:0xf bound_ctrl:1
	v_cndmask_b32_e64 v203, v148, v156, s[6:7]
	v_mov_b32_dpp v154, v147 row_ror:2 row_mask:0xf bank_mask:0xf bound_ctrl:1
	v_cndmask_b32_e64 v147, v151, v159, s[6:7]
	v_cndmask_b32_e64 v159, v151, v159, s[8:9]
	v_mov_b32_dpp v146, v146 row_ror:1 row_mask:0xf bank_mask:0xf bound_ctrl:1
	v_mov_b32_dpp v147, v147 row_ror:1 row_mask:0xf bank_mask:0xf bound_ctrl:1
	v_mov_b32_dpp v159, v159 row_ror:2 row_mask:0xf bank_mask:0xf bound_ctrl:1
	v_cndmask_b32_e64 v160, v152, v160, s[8:9]
	v_mov_b32_dpp v228, v203 row_ror:1 row_mask:0xf bank_mask:0xf bound_ctrl:1
	v_cndmask_b32_e64 v203, v153, v161, s[6:7]
	v_cndmask_b32_e64 v161, v153, v161, s[8:9]
	v_pk_fma_f32 v[158:159], v[134:135], v[158:159], v[138:139]
	v_mov_b32_dpp v160, v160 row_ror:2 row_mask:0xf bank_mask:0xf bound_ctrl:1
	v_mov_b32_dpp v161, v161 row_ror:2 row_mask:0xf bank_mask:0xf bound_ctrl:1
	v_pk_fma_f32 v[146:147], v[122:123], v[146:147], v[158:159]
	v_cndmask_b32_e64 v185, v183, v155, s[6:7]
	v_cndmask_b32_e64 v155, v183, v155, s[8:9]
	v_mov_b32_dpp v227, v203 row_ror:1 row_mask:0xf bank_mask:0xf bound_ctrl:1
	v_pk_fma_f32 v[160:161], v[136:137], v[160:161], v[140:141]
	v_pk_fma_f32 v[146:147], v[150:151], v[142:143], v[146:147]
	v_mov_b32_dpp v155, v155 row_ror:2 row_mask:0xf bank_mask:0xf bound_ctrl:1
	v_pk_fma_f32 v[158:159], v[124:125], v[226:227], v[160:161]
	v_mul_f32_e32 v160, 0x3d372713, v146
	v_mul_f32_e32 v161, 0x3d372713, v147
	v_mov_b32_dpp v185, v185 row_ror:1 row_mask:0xf bank_mask:0xf bound_ctrl:1
	v_pk_fma_f32 v[158:159], v[152:153], v[144:145], v[158:159]
	v_pk_fma_f32 v[154:155], v[126:127], v[154:155], v[130:131]
	v_mul_f32_e32 v160, v146, v160
	v_mul_f32_e32 v161, v147, v161
	v_pk_fma_f32 v[154:155], v[118:119], v[184:185], v[154:155]
	v_fma_f32 v160, v146, v160, v146
	v_fma_f32 v161, v147, v161, v147
	v_mul_f32_e32 v184, 0x3d372713, v158
	v_mul_f32_e32 v185, 0x3d372713, v159
	v_mul_f32_e32 v160, 0xc0135761, v160
	v_mul_f32_e32 v161, 0xc0135761, v161
	v_mul_f32_e32 v184, v158, v184
	v_mul_f32_e32 v185, v159, v185
	v_exp_f32_e32 v160, v160
	v_exp_f32_e32 v161, v161
	v_fma_f32 v184, v158, v184, v158
	v_fma_f32 v185, v159, v185, v159
	v_mul_f32_e32 v184, 0xc0135761, v184
	v_mul_f32_e32 v185, 0xc0135761, v185
	v_exp_f32_e32 v184, v184
	v_exp_f32_e32 v185, v185
	v_add_f32_e32 v160, 1.0, v160
	v_add_f32_e32 v161, 1.0, v161
	v_rcp_f32_e32 v160, v160
	v_rcp_f32_e32 v161, v161
	v_add_f32_e32 v184, 1.0, v184
	v_add_f32_e32 v185, 1.0, v185
	v_cndmask_b32_e64 v156, v148, v156, s[8:9]
	v_cndmask_b32_e64 v203, v149, v157, s[6:7]
	v_cndmask_b32_e64 v157, v149, v157, s[8:9]
	v_rcp_f32_e32 v184, v184
	v_rcp_f32_e32 v185, v185
	v_mov_b32_dpp v156, v156 row_ror:2 row_mask:0xf bank_mask:0xf bound_ctrl:1
	v_mov_b32_dpp v157, v157 row_ror:2 row_mask:0xf bank_mask:0xf bound_ctrl:1
	v_mov_b32_dpp v229, v203 row_ror:1 row_mask:0xf bank_mask:0xf bound_ctrl:1
	v_pk_fma_f32 v[156:157], v[128:129], v[156:157], v[132:133]
	v_pk_fma_f32 v[154:155], v[182:183], v[114:115], v[154:155]
	v_pk_mul_f32 v[146:147], v[146:147], v[160:161]
	v_pk_fma_f32 v[156:157], v[120:121], v[228:229], v[156:157]
	v_pk_mul_f32 v[146:147], v[154:155], v[146:147]
	v_pk_fma_f32 v[156:157], v[148:149], v[116:117], v[156:157]
	v_cvt_pk_bf16_f32 v160, v146, v147
	v_pk_mul_f32 v[146:147], v[158:159], v[184:185]
	v_pk_mul_f32 v[110:111], v[110:111], v[186:187] op_sel_hi:[1,0]
	v_pk_mul_f32 v[146:147], v[156:157], v[146:147]
	v_mov_b64_e32 v[156:157], s[14:15]
	v_cvt_pk_bf16_f32 v161, v146, v147
	v_mad_i64_i32 v[146:147], s[50:51], v214, s41, v[156:157]
	v_lshlrev_b64 v[154:155], 1, v[188:189]
	v_pk_mul_f32 v[158:159], v[108:109], v[186:187] op_sel_hi:[1,0]
	v_pk_mul_f32 v[106:107], v[106:107], v[186:187] op_sel_hi:[1,0]
	v_cndmask_b32_e64 v109, v110, v150, s[8:9]
	v_lshl_add_u64 v[146:147], v[146:147], 0, v[154:155]
	v_cndmask_b32_e64 v108, v110, v150, s[6:7]
	v_mov_b32_dpp v150, v109 row_ror:2 row_mask:0xf bank_mask:0xf bound_ctrl:1
	v_cndmask_b32_e64 v109, v106, v182, s[6:7]
	global_store_dwordx2 v[146:147], v[160:161], off
	v_pk_mul_f32 v[112:113], v[112:113], v[186:187] op_sel_hi:[1,0]
	v_mov_b32_dpp v160, v109 row_ror:1 row_mask:0xf bank_mask:0xf bound_ctrl:1
	v_cndmask_b32_e64 v109, v106, v182, s[8:9]
	v_cndmask_b32_e64 v185, v158, v148, s[6:7]
	v_cndmask_b32_e64 v184, v112, v152, s[6:7]
	v_mov_b32_dpp v182, v109 row_ror:2 row_mask:0xf bank_mask:0xf bound_ctrl:1
	v_cndmask_b32_e64 v109, v111, v151, s[6:7]
	v_cndmask_b32_e64 v151, v111, v151, s[8:9]
	v_cndmask_b32_e64 v152, v112, v152, s[8:9]
; __device__ __forceinline__ unsigned cvt_pk_bf16(float lo, float hi) { const f32x2 v = {lo, hi}; const bf16x2_t b = __builtin_convertvector(v, bf16x2_t); return __builtin_bit_cast(unsigned, b); }
; __device__ __forceinline__ float gelu_tanh(float x) { const float t = x + 0.044715f * x * x * x; return x * fast_rcp(1.0f + fast_exp2(-2.3022082f * t)); }
; __device__ __forceinline__ float dpp_ror1(float x) { return __builtin_bit_cast(float, __builtin_amdgcn_mov_dpp(__builtin_bit_cast(int, x), 0x121, 0xf, 0xf, true)); }
; __device__ __forceinline__ float dpp_ror2(float x) { return __builtin_bit_cast(float, __builtin_amdgcn_mov_dpp(__builtin_bit_cast(int, x), 0x122, 0xf, 0xf, true)); }
;     __device__ __forceinline__ void operator()(f32x4 (&acc)[2][2][4][2], const Unit& u, int wr, int wc, int fr, int fq) const {
;     ...
;                     const f32x4 gq = acc[ai][0][m][n] * rs[ai][m], vq = acc[ai][1][m][n] * rs[ai][m];
;                     f32x4 g1, g2, v1, v2;
; #pragma unroll
;                     for (int e = 0; e < 4; ++e) {
;                         g1[e] = dpp_ror1(fr == 15 ? pg[e] : gq[e]); g2[e] = dpp_ror2(fr >= 14 ? pg[e] : gq[e]); v1[e] = dpp_ror1(fr == 15 ? pv[e] : vq[e]); v2[e] = dpp_ror2(fr >= 14 ? pv[e] : vq[e]); }
;                     const f32x4 cg = bg + wg0 * g2 + wg1 * g1 + wg2 * gq, cv = bv + wv0 * v2 + wv1 * v1 + wv2 * vq;
;                     {
;                         u32x2 w; w.x = cvt_pk_bf16(gelu_tanh(cg[0]) * cv[0], gelu_tanh(cg[1]) * cv[1]); w.y = cvt_pk_bf16(gelu_tanh(cg[2]) * cv[2], gelu_tanh(cg[3]) * cv[3]);
;                         *(u32x2*)(act + (size_t)row * DFF + ch0) = w; }
	v_mov_b32_dpp v214, v185 row_ror:1 row_mask:0xf bank_mask:0xf bound_ctrl:1
	v_mov_b32_dpp v151, v151 row_ror:2 row_mask:0xf bank_mask:0xf bound_ctrl:1
	v_cndmask_b32_e64 v185, v113, v153, s[6:7]
	v_cndmask_b32_e64 v153, v113, v153, s[8:9]
	v_mov_b32_dpp v108, v108 row_ror:1 row_mask:0xf bank_mask:0xf bound_ctrl:1
	v_mov_b32_dpp v109, v109 row_ror:1 row_mask:0xf bank_mask:0xf bound_ctrl:1
	v_cndmask_b32_e64 v161, v107, v183, s[6:7]
	v_cndmask_b32_e64 v183, v107, v183, s[8:9]
	v_mov_b32_dpp v152, v152 row_ror:2 row_mask:0xf bank_mask:0xf bound_ctrl:1
	v_mov_b32_dpp v153, v153 row_ror:2 row_mask:0xf bank_mask:0xf bound_ctrl:1
	v_pk_fma_f32 v[150:151], v[134:135], v[150:151], v[138:139]
	v_mov_b32_dpp v183, v183 row_ror:2 row_mask:0xf bank_mask:0xf bound_ctrl:1
	v_mov_b32_dpp v184, v184 row_ror:1 row_mask:0xf bank_mask:0xf bound_ctrl:1
	v_mov_b32_dpp v185, v185 row_ror:1 row_mask:0xf bank_mask:0xf bound_ctrl:1
	v_pk_fma_f32 v[152:153], v[136:137], v[152:153], v[140:141]
	v_pk_fma_f32 v[108:109], v[122:123], v[108:109], v[150:151]
	v_mov_b32_dpp v161, v161 row_ror:1 row_mask:0xf bank_mask:0xf bound_ctrl:1
	v_pk_fma_f32 v[150:151], v[124:125], v[184:185], v[152:153]
	v_pk_fma_f32 v[108:109], v[110:111], v[142:143], v[108:109]
	v_pk_fma_f32 v[152:153], v[126:127], v[182:183], v[130:131]
	v_pk_fma_f32 v[150:151], v[112:113], v[144:145], v[150:151]
	v_pk_fma_f32 v[152:153], v[118:119], v[160:161], v[152:153]
	v_mul_f32_e32 v160, 0x3d372713, v108
	v_mul_f32_e32 v161, 0x3d372713, v109
	v_mul_f32_e32 v160, v108, v160
	v_mul_f32_e32 v161, v109, v161
	v_fma_f32 v160, v108, v160, v108
	v_fma_f32 v161, v109, v161, v109
	v_mul_f32_e32 v182, 0x3d372713, v150
	v_mul_f32_e32 v183, 0x3d372713, v151
	v_mul_f32_e32 v160, 0xc0135761, v160
	v_mul_f32_e32 v161, 0xc0135761, v161
	v_mul_f32_e32 v182, v150, v182
	v_mul_f32_e32 v183, v151, v183
	v_exp_f32_e32 v160, v160
	v_exp_f32_e32 v161, v161
	v_fma_f32 v182, v150, v182, v150
	v_fma_f32 v183, v151, v183, v151
	v_mul_f32_e32 v182, 0xc0135761, v182
	v_mul_f32_e32 v183, 0xc0135761, v183
	v_exp_f32_e32 v182, v182
	v_exp_f32_e32 v183, v183
	v_add_f32_e32 v160, 1.0, v160
	v_add_f32_e32 v161, 1.0, v161
	v_rcp_f32_e32 v160, v160
	v_rcp_f32_e32 v161, v161
	v_add_f32_e32 v182, 1.0, v182
	v_add_f32_e32 v183, 1.0, v183
	v_cndmask_b32_e64 v148, v158, v148, s[8:9]
	v_cndmask_b32_e64 v203, v159, v149, s[6:7]
	v_cndmask_b32_e64 v149, v159, v149, s[8:9]
	v_rcp_f32_e32 v182, v182
	v_rcp_f32_e32 v183, v183
	v_mov_b32_dpp v148, v148 row_ror:2 row_mask:0xf bank_mask:0xf bound_ctrl:1
	v_mov_b32_dpp v149, v149 row_ror:2 row_mask:0xf bank_mask:0xf bound_ctrl:1
	v_mov_b32_dpp v215, v203 row_ror:1 row_mask:0xf bank_mask:0xf bound_ctrl:1
	v_pk_fma_f32 v[148:149], v[128:129], v[148:149], v[132:133]
	v_pk_fma_f32 v[152:153], v[106:107], v[114:115], v[152:153]
	v_pk_mul_f32 v[108:109], v[108:109], v[160:161]
	v_rsq_f32_e32 v178, v178
	v_pk_fma_f32 v[148:149], v[120:121], v[214:215], v[148:149]
	v_pk_mul_f32 v[108:109], v[152:153], v[108:109]
	v_pk_fma_f32 v[148:149], v[158:159], v[116:117], v[148:149]
	v_cvt_pk_bf16_f32 v152, v108, v109
	v_pk_mul_f32 v[108:109], v[150:151], v[182:183]
	v_pk_mul_f32 v[100:101], v[100:101], v[178:179] op_sel_hi:[1,0]
	v_pk_mul_f32 v[108:109], v[148:149], v[108:109]
	v_pk_mul_f32 v[98:99], v[98:99], v[178:179] op_sel_hi:[1,0]
	v_cvt_pk_bf16_f32 v153, v108, v109
	v_mad_i64_i32 v[108:109], s[50:51], v212, s41, v[156:157]
	v_lshl_add_u64 v[108:109], v[108:109], 0, v[154:155]
	global_store_dwordx2 v[108:109], v[152:153], off
	v_pk_mul_f32 v[102:103], v[102:103], v[178:179] op_sel_hi:[1,0]
	v_cndmask_b32_e64 v149, v98, v106, s[6:7]
	v_cndmask_b32_e64 v153, v100, v158, s[6:7]
	v_pk_mul_f32 v[104:105], v[104:105], v[178:179] op_sel_hi:[1,0]
	v_cndmask_b32_e64 v148, v102, v110, s[6:7]
	v_cndmask_b32_e64 v110, v102, v110, s[8:9]
	v_mov_b32_dpp v150, v149 row_ror:1 row_mask:0xf bank_mask:0xf bound_ctrl:1
	v_cndmask_b32_e64 v149, v103, v111, s[6:7]
	v_cndmask_b32_e64 v111, v103, v111, s[8:9]
	v_mov_b32_dpp v160, v153 row_ror:1 row_mask:0xf bank_mask:0xf bound_ctrl:1
	v_cndmask_b32_e64 v153, v100, v158, s[8:9]
	v_mov_b32_dpp v110, v110 row_ror:2 row_mask:0xf bank_mask:0xf bound_ctrl:1
	v_mov_b32_dpp v111, v111 row_ror:2 row_mask:0xf bank_mask:0xf bound_ctrl:1
	v_cndmask_b32_e64 v152, v104, v112, s[6:7]
	v_cndmask_b32_e64 v112, v104, v112, s[8:9]
	v_mov_b32_dpp v158, v153 row_ror:2 row_mask:0xf bank_mask:0xf bound_ctrl:1
	v_cndmask_b32_e64 v153, v105, v113, s[6:7]
	v_cndmask_b32_e64 v113, v105, v113, s[8:9]
	v_mov_b32_dpp v148, v148 row_ror:1 row_mask:0xf bank_mask:0xf bound_ctrl:1
	v_cndmask_b32_e64 v106, v98, v106, s[8:9]
	v_mov_b32_dpp v149, v149 row_ror:1 row_mask:0xf bank_mask:0xf bound_ctrl:1
	v_cndmask_b32_e64 v151, v99, v107, s[6:7]
	v_cndmask_b32_e64 v107, v99, v107, s[8:9]
	v_mov_b32_dpp v112, v112 row_ror:2 row_mask:0xf bank_mask:0xf bound_ctrl:1
	v_mov_b32_dpp v113, v113 row_ror:2 row_mask:0xf bank_mask:0xf bound_ctrl:1
	v_pk_fma_f32 v[110:111], v[134:135], v[110:111], v[138:139]
	v_mov_b32_dpp v106, v106 row_ror:2 row_mask:0xf bank_mask:0xf bound_ctrl:1
	v_mov_b32_dpp v107, v107 row_ror:2 row_mask:0xf bank_mask:0xf bound_ctrl:1
	v_mov_b32_dpp v152, v152 row_ror:1 row_mask:0xf bank_mask:0xf bound_ctrl:1
	v_mov_b32_dpp v153, v153 row_ror:1 row_mask:0xf bank_mask:0xf bound_ctrl:1
	v_pk_fma_f32 v[112:113], v[136:137], v[112:113], v[140:141]
	v_pk_fma_f32 v[110:111], v[122:123], v[148:149], v[110:111]
	v_mov_b32_dpp v151, v151 row_ror:1 row_mask:0xf bank_mask:0xf bound_ctrl:1
	v_pk_fma_f32 v[112:113], v[124:125], v[152:153], v[112:113]
	v_pk_fma_f32 v[110:111], v[102:103], v[142:143], v[110:111]
; __device__ __forceinline__ unsigned cvt_pk_bf16(float lo, float hi) { const f32x2 v = {lo, hi}; const bf16x2_t b = __builtin_convertvector(v, bf16x2_t); return __builtin_bit_cast(unsigned, b); }
; __device__ __forceinline__ float gelu_tanh(float x) { const float t = x + 0.044715f * x * x * x; return x * fast_rcp(1.0f + fast_exp2(-2.3022082f * t)); }
; __device__ __forceinline__ float dpp_ror1(float x) { return __builtin_bit_cast(float, __builtin_amdgcn_mov_dpp(__builtin_bit_cast(int, x), 0x121, 0xf, 0xf, true)); }
; __device__ __forceinline__ float dpp_ror2(float x) { return __builtin_bit_cast(float, __builtin_amdgcn_mov_dpp(__builtin_bit_cast(int, x), 0x122, 0xf, 0xf, true)); }
;     __device__ __forceinline__ void operator()(f32x4 (&acc)[2][2][4][2], const Unit& u, int wr, int wc, int fr, int fq) const {
;     ...
;                     const f32x4 gq = acc[ai][0][m][n] * rs[ai][m], vq = acc[ai][1][m][n] * rs[ai][m];
;                     f32x4 g1, g2, v1, v2;
; #pragma unroll
;                     for (int e = 0; e < 4; ++e) {
;                         g1[e] = dpp_ror1(fr == 15 ? pg[e] : gq[e]); g2[e] = dpp_ror2(fr >= 14 ? pg[e] : gq[e]); v1[e] = dpp_ror1(fr == 15 ? pv[e] : vq[e]); v2[e] = dpp_ror2(fr >= 14 ? pv[e] : vq[e]); }
;                     const f32x4 cg = bg + wg0 * g2 + wg1 * g1 + wg2 * gq, cv = bv + wv0 * v2 + wv1 * v1 + wv2 * vq;
;                     {
;                         u32x2 w; w.x = cvt_pk_bf16(gelu_tanh(cg[0]) * cv[0], gelu_tanh(cg[1]) * cv[1]); w.y = cvt_pk_bf16(gelu_tanh(cg[2]) * cv[2], gelu_tanh(cg[3]) * cv[3]);
;                         *(u32x2*)(act + (size_t)row * DFF + ch0) = w; }
;                     if (m == 0 && fr < 2) { float* hp = halo + ((size_t)blk * 4 + fr) * DFF2 + ch0; *(f32x4*)hp = gq; *(f32x4*)(hp + DFF) = vq; }
;                     if (m == 3 && fr >= 14) { float* hp = halo + ((size_t)blk * 4 + fr - 12) * DFF2 + ch0; *(f32x4*)hp = gq; *(f32x4*)(hp + DFF) = vq; }
	v_pk_fma_f32 v[106:107], v[126:127], v[106:107], v[130:131]
	v_pk_fma_f32 v[112:113], v[104:105], v[144:145], v[112:113]
	v_pk_fma_f32 v[106:107], v[118:119], v[150:151], v[106:107]
	v_mul_f32_e32 v150, 0x3d372713, v110
	v_mul_f32_e32 v151, 0x3d372713, v111
	v_mul_f32_e32 v150, v110, v150
	v_mul_f32_e32 v151, v111, v151
	v_mul_f32_e32 v152, 0x3d372713, v112
	v_mul_f32_e32 v153, 0x3d372713, v113
	v_fma_f32 v150, v110, v150, v110
	v_fma_f32 v151, v111, v151, v111
	v_mul_f32_e32 v152, v112, v152
	v_mul_f32_e32 v153, v113, v153
	v_mul_f32_e32 v150, 0xc0135761, v150
	v_mul_f32_e32 v151, 0xc0135761, v151
	v_fma_f32 v152, v112, v152, v112
	v_fma_f32 v153, v113, v153, v113
	v_exp_f32_e32 v150, v150
	v_exp_f32_e32 v151, v151
	v_mul_f32_e32 v152, 0xc0135761, v152
	v_mul_f32_e32 v153, 0xc0135761, v153
	v_exp_f32_e32 v152, v152
	v_exp_f32_e32 v153, v153
	v_add_f32_e32 v150, 1.0, v150
	v_add_f32_e32 v151, 1.0, v151
	v_rcp_f32_e32 v150, v150
	v_rcp_f32_e32 v151, v151
	v_add_f32_e32 v152, 1.0, v152
	v_add_f32_e32 v153, 1.0, v153
	v_cndmask_b32_e64 v161, v101, v159, s[6:7]
	v_cndmask_b32_e64 v159, v101, v159, s[8:9]
	v_rcp_f32_e32 v152, v152
	v_rcp_f32_e32 v153, v153
	v_mov_b32_dpp v159, v159 row_ror:2 row_mask:0xf bank_mask:0xf bound_ctrl:1
	v_mov_b32_dpp v161, v161 row_ror:1 row_mask:0xf bank_mask:0xf bound_ctrl:1
	v_pk_fma_f32 v[148:149], v[128:129], v[158:159], v[132:133]
	v_pk_fma_f32 v[106:107], v[98:99], v[114:115], v[106:107]
	v_pk_fma_f32 v[148:149], v[120:121], v[160:161], v[148:149]
	v_pk_mul_f32 v[110:111], v[110:111], v[150:151]
	v_pk_fma_f32 v[148:149], v[100:101], v[116:117], v[148:149]
	v_pk_mul_f32 v[106:107], v[106:107], v[110:111]
	v_pk_mul_f32 v[110:111], v[112:113], v[152:153]
	v_cvt_pk_bf16_f32 v106, v106, v107
	v_pk_mul_f32 v[110:111], v[148:149], v[110:111]
	s_nop 0
	v_cvt_pk_bf16_f32 v107, v110, v111
	v_mad_i64_i32 v[110:111], s[50:51], v210, s41, v[156:157]
	v_lshl_add_u64 v[110:111], v[110:111], 0, v[154:155]
	global_store_dwordx2 v[110:111], v[106:107], off
	s_and_saveexec_b64 s[50:51], s[8:9]
	s_cbranch_execz .LBB0_1138
	v_add_co_u32_e32 v106, vcc, 0xfffbe000, v194
	s_nop 1
	v_addc_co_u32_e32 v107, vcc, -1, v195, vcc
	global_store_dwordx4 v[106:107], v[102:105], off
	s_nop 1
	v_add_co_u32_e32 v102, vcc, 0xfffc0c00, v194
	s_nop 1
	v_addc_co_u32_e32 v103, vcc, -1, v195, vcc
	global_store_dwordx4 v[102:103], v[98:101], off
.LBB0_1138:
	s_or_b64 exec, exec, s[50:51]
	s_nop 0
	v_fmamk_f32 v98, v201, 0x3a800000, v216
	v_rsq_f32_e32 v104, v98
	s_add_i32 s48, s48, 2
	s_ashr_i32 s49, s48, 31
	v_lshl_add_u64 v[98:99], s[48:49], 2, v[170:171]
	v_pk_mul_f32 v[90:91], v[90:91], v[104:105] op_sel_hi:[1,0]
	v_pk_mul_f32 v[96:97], v[96:97], v[104:105] op_sel_hi:[1,0]
	v_pk_mul_f32 v[94:95], v[94:95], v[104:105] op_sel_hi:[1,0]
	v_pk_mul_f32 v[92:93], v[92:93], v[104:105] op_sel_hi:[1,0]
	v_cndmask_b32_e64 v105, v91, 0, s[6:7]
	v_mad_u64_u32 v[100:101], s[48:49], v98, s37, 0
	s_nop 0
	v_mov_b32_dpp v107, v105 row_ror:1 row_mask:0xf bank_mask:0xf bound_ctrl:1
	v_cndmask_b32_e64 v105, v91, 0, s[8:9]
	v_mad_i32_i24 v101, v99, s37, v101
	v_cndmask_b32_e64 v99, v94, 0, s[8:9]
	v_mov_b32_dpp v113, v105 row_ror:2 row_mask:0xf bank_mask:0xf bound_ctrl:1
	v_cndmask_b32_e64 v105, v96, 0, s[6:7]
	v_mov_b32_dpp v102, v99 row_ror:2 row_mask:0xf bank_mask:0xf bound_ctrl:1
	v_cndmask_b32_e64 v99, v90, 0, s[6:7]
	v_mov_b32_dpp v148, v105 row_ror:1 row_mask:0xf bank_mask:0xf bound_ctrl:1
	v_cndmask_b32_e64 v105, v96, 0, s[8:9]
	v_mov_b32_dpp v106, v99 row_ror:1 row_mask:0xf bank_mask:0xf bound_ctrl:1
	v_cndmask_b32_e64 v99, v90, 0, s[8:9]
	v_mov_b32_dpp v150, v105 row_ror:2 row_mask:0xf bank_mask:0xf bound_ctrl:1
	v_cndmask_b32_e64 v105, v92, 0, s[6:7]
	v_cndmask_b32_e64 v103, v95, 0, s[8:9]
	v_cndmask_b32_e64 v98, v94, 0, s[6:7]
	v_mov_b32_dpp v152, v105 row_ror:1 row_mask:0xf bank_mask:0xf bound_ctrl:1
	v_cndmask_b32_e64 v105, v92, 0, s[8:9]
	v_mov_b32_dpp v112, v99 row_ror:2 row_mask:0xf bank_mask:0xf bound_ctrl:1
	v_cndmask_b32_e64 v99, v95, 0, s[6:7]
	v_mov_b32_dpp v156, v105 row_ror:2 row_mask:0xf bank_mask:0xf bound_ctrl:1
	v_cndmask_b32_e64 v105, v97, 0, s[6:7]
	v_mov_b32_dpp v103, v103 row_ror:2 row_mask:0xf bank_mask:0xf bound_ctrl:1
	v_mov_b32_dpp v98, v98 row_ror:1 row_mask:0xf bank_mask:0xf bound_ctrl:1
	v_mov_b32_dpp v149, v105 row_ror:1 row_mask:0xf bank_mask:0xf bound_ctrl:1
	v_cndmask_b32_e64 v105, v97, 0, s[8:9]
	v_mov_b32_dpp v99, v99 row_ror:1 row_mask:0xf bank_mask:0xf bound_ctrl:1
	v_pk_fma_f32 v[102:103], v[134:135], v[102:103], v[138:139]
	v_mov_b32_dpp v151, v105 row_ror:2 row_mask:0xf bank_mask:0xf bound_ctrl:1
	v_cndmask_b32_e64 v105, v93, 0, s[6:7]
	v_pk_fma_f32 v[98:99], v[122:123], v[98:99], v[102:103]
	v_pk_fma_f32 v[150:151], v[136:137], v[150:151], v[140:141]
	v_mov_b32_dpp v153, v105 row_ror:1 row_mask:0xf bank_mask:0xf bound_ctrl:1
	v_cndmask_b32_e64 v105, v93, 0, s[8:9]
	v_pk_fma_f32 v[98:99], v[142:143], v[94:95], v[98:99]
	v_pk_fma_f32 v[102:103], v[124:125], v[148:149], v[150:151]
	v_mov_b32_dpp v157, v105 row_ror:2 row_mask:0xf bank_mask:0xf bound_ctrl:1
	v_pk_fma_f32 v[148:149], v[128:129], v[156:157], v[132:133]
	v_pk_fma_f32 v[112:113], v[126:127], v[112:113], v[130:131]
	v_mul_f32_e32 v105, 0x3d372713, v98
	v_pk_fma_f32 v[106:107], v[118:119], v[106:107], v[112:113]
	v_pk_fma_f32 v[112:113], v[120:121], v[152:153], v[148:149]
	v_mul_f32_e32 v105, v98, v105
	v_mul_f32_e32 v148, 0x3d372713, v99
	v_fma_f32 v105, v98, v105, v98
	v_mul_f32_e32 v148, v99, v148
	v_mul_f32_e32 v105, 0xc0135761, v105
	v_fma_f32 v148, v99, v148, v99
	v_exp_f32_e32 v105, v105
	v_mul_f32_e32 v148, 0xc0135761, v148
	v_exp_f32_e32 v149, v148
; __device__ __forceinline__ unsigned cvt_pk_bf16(float lo, float hi) { const f32x2 v = {lo, hi}; const bf16x2_t b = __builtin_convertvector(v, bf16x2_t); return __builtin_bit_cast(unsigned, b); }
; __device__ __forceinline__ float gelu_tanh(float x) { const float t = x + 0.044715f * x * x * x; return x * fast_rcp(1.0f + fast_exp2(-2.3022082f * t)); }
; __device__ __forceinline__ float dpp_ror1(float x) { return __builtin_bit_cast(float, __builtin_amdgcn_mov_dpp(__builtin_bit_cast(int, x), 0x121, 0xf, 0xf, true)); }
; __device__ __forceinline__ float dpp_ror2(float x) { return __builtin_bit_cast(float, __builtin_amdgcn_mov_dpp(__builtin_bit_cast(int, x), 0x122, 0xf, 0xf, true)); }
;     __device__ __forceinline__ void operator()(f32x4 (&acc)[2][2][4][2], const Unit& u, int wr, int wc, int fr, int fq) const {
;     ...
;                     const f32x4 gq = acc[ai][0][m][n] * rs[ai][m], vq = acc[ai][1][m][n] * rs[ai][m];
;                     f32x4 g1, g2, v1, v2;
; #pragma unroll
;                     for (int e = 0; e < 4; ++e) {
;                         g1[e] = dpp_ror1(fr == 15 ? pg[e] : gq[e]); g2[e] = dpp_ror2(fr >= 14 ? pg[e] : gq[e]); v1[e] = dpp_ror1(fr == 15 ? pv[e] : vq[e]); v2[e] = dpp_ror2(fr >= 14 ? pv[e] : vq[e]); }
;                     const f32x4 cg = bg + wg0 * g2 + wg1 * g1 + wg2 * gq, cv = bv + wv0 * v2 + wv1 * v1 + wv2 * vq;
;                     {
;                         u32x2 w; w.x = cvt_pk_bf16(gelu_tanh(cg[0]) * cv[0], gelu_tanh(cg[1]) * cv[1]); w.y = cvt_pk_bf16(gelu_tanh(cg[2]) * cv[2], gelu_tanh(cg[3]) * cv[3]);
;                         *(u32x2*)(act + (size_t)row * DFF + ch0) = w; }
;                     if (m == 0 && fr < 2) { float* hp = halo + ((size_t)blk * 4 + fr) * DFF2 + ch0; *(f32x4*)hp = gq; *(f32x4*)(hp + DFF) = vq; }
;                     if (m == 3 && fr >= 14) { float* hp = halo + ((size_t)blk * 4 + fr - 12) * DFF2 + ch0; *(f32x4*)hp = gq; *(f32x4*)(hp + DFF) = vq; }
	v_pk_fma_f32 v[102:103], v[144:145], v[96:97], v[102:103]
	v_add_f32_e32 v105, 1.0, v105
	v_rcp_f32_e32 v148, v105
	v_add_f32_e32 v105, 1.0, v149
	v_mul_f32_e32 v149, 0x3d372713, v102
	v_mul_f32_e32 v149, v102, v149
	v_fma_f32 v149, v102, v149, v102
	v_mul_f32_e32 v149, 0xc0135761, v149
	v_exp_f32_e32 v150, v149
	v_mul_f32_e32 v149, 0x3d372713, v103
	v_mul_f32_e32 v149, v103, v149
	v_fma_f32 v149, v103, v149, v103
	v_mul_f32_e32 v149, 0xc0135761, v149
	v_exp_f32_e32 v151, v149
	v_rcp_f32_e32 v149, v105
	v_add_f32_e32 v105, 1.0, v150
	v_rcp_f32_e32 v150, v105
	v_add_f32_e32 v105, 1.0, v151
	v_rcp_f32_e32 v151, v105
	v_pk_fma_f32 v[112:113], v[92:93], v[116:117], v[112:113]
	v_pk_fma_f32 v[106:107], v[90:91], v[114:115], v[106:107]
	v_pk_mul_f32 v[98:99], v[98:99], v[148:149]
	v_pk_mul_f32 v[102:103], v[102:103], v[150:151]
	v_pk_mul_f32 v[98:99], v[106:107], v[98:99]
	v_pk_mul_f32 v[102:103], v[112:113], v[102:103]
	v_cvt_pk_bf16_f32 v98, v98, v99
	v_cvt_pk_bf16_f32 v99, v102, v103
	v_mov_b64_e32 v[102:103], s[14:15]
	v_mad_i64_i32 v[102:103], s[48:49], v208, s41, v[102:103]
	v_lshl_add_u64 v[148:149], v[188:189], 1, v[102:103]
	global_store_dwordx2 v[148:149], v[98:99], off
	v_lshl_add_u64 v[98:99], s[16:17], 0, v[100:101]
	v_lshl_add_u64 v[106:107], v[188:189], 2, v[98:99]
	s_and_saveexec_b64 s[48:49], s[10:11]
	v_readlane_b32 s92, v255, 10
	v_readlane_b32 s93, v255, 11
	v_readlane_b32 s94, v255, 12
	v_readlane_b32 s95, v255, 13
	s_cbranch_execz .LBB0_1140
	v_add_co_u32_e32 v100, vcc, 0x2000, v106
	global_store_dwordx4 v[106:107], v[94:97], off
	s_nop 0
	v_addc_co_u32_e32 v101, vcc, 0, v107, vcc
	global_store_dwordx4 v[100:101], v[90:93], off offset:3072
.LBB0_1140:
	s_or_b64 exec, exec, s[48:49]
	v_fmamk_f32 v100, v197, 0x3a800000, v216
	v_rsq_f32_e32 v112, v100
	v_fmamk_f32 v100, v187, 0x3a800000, v216
	v_rsq_f32_e32 v102, v100
	s_movk_i32 s37, 0x1600
	v_pk_mul_f32 v[86:87], v[86:87], v[112:113] op_sel_hi:[1,0]
	v_pk_mul_f32 v[82:83], v[82:83], v[112:113] op_sel_hi:[1,0]
	v_cndmask_b32_e64 v101, v86, v94, s[6:7]
	v_pk_mul_f32 v[88:89], v[88:89], v[112:113] op_sel_hi:[1,0]
	v_cndmask_b32_e64 v94, v86, v94, s[8:9]
	v_mov_b32_dpp v150, v101 row_ror:1 row_mask:0xf bank_mask:0xf bound_ctrl:1
	v_cndmask_b32_e64 v101, v82, v90, s[6:7]
	v_pk_mul_f32 v[84:85], v[84:85], v[112:113] op_sel_hi:[1,0]
	v_mov_b32_dpp v94, v94 row_ror:2 row_mask:0xf bank_mask:0xf bound_ctrl:1
	v_mov_b32_dpp v152, v101 row_ror:1 row_mask:0xf bank_mask:0xf bound_ctrl:1
	v_cndmask_b32_e64 v101, v87, v95, s[6:7]
	v_cndmask_b32_e64 v95, v87, v95, s[8:9]
	v_cndmask_b32_e64 v90, v82, v90, s[8:9]
	v_mov_b32_dpp v151, v101 row_ror:1 row_mask:0xf bank_mask:0xf bound_ctrl:1
	v_cndmask_b32_e64 v101, v83, v91, s[6:7]
	v_mov_b32_dpp v95, v95 row_ror:2 row_mask:0xf bank_mask:0xf bound_ctrl:1
	v_pk_fma_f32 v[94:95], v[134:135], v[94:95], v[138:139]
	v_mov_b32_dpp v153, v101 row_ror:1 row_mask:0xf bank_mask:0xf bound_ctrl:1
	v_cndmask_b32_e64 v101, v88, v96, s[6:7]
	v_pk_fma_f32 v[94:95], v[122:123], v[150:151], v[94:95]
	v_cndmask_b32_e64 v96, v88, v96, s[8:9]
	v_mov_b32_dpp v156, v101 row_ror:1 row_mask:0xf bank_mask:0xf bound_ctrl:1
	v_cndmask_b32_e64 v101, v84, v92, s[6:7]
	v_pk_fma_f32 v[94:95], v[142:143], v[86:87], v[94:95]
	v_mov_b32_dpp v96, v96 row_ror:2 row_mask:0xf bank_mask:0xf bound_ctrl:1
	v_mov_b32_dpp v158, v101 row_ror:1 row_mask:0xf bank_mask:0xf bound_ctrl:1
	v_cndmask_b32_e64 v101, v89, v97, s[6:7]
	v_mul_f32_e32 v103, 0x3d372713, v95
	v_mul_f32_e32 v103, v95, v103
	v_mov_b32_dpp v157, v101 row_ror:1 row_mask:0xf bank_mask:0xf bound_ctrl:1
	v_cndmask_b32_e64 v101, v85, v93, s[6:7]
	v_fma_f32 v103, v95, v103, v95
	v_cndmask_b32_e64 v97, v89, v97, s[8:9]
	v_mov_b32_dpp v159, v101 row_ror:1 row_mask:0xf bank_mask:0xf bound_ctrl:1
	v_mul_f32_e32 v101, 0x3d372713, v94
	v_mul_f32_e32 v101, v94, v101
	v_fma_f32 v101, v94, v101, v94
	v_mul_f32_e32 v101, 0xc0135761, v101
	v_exp_f32_e32 v101, v101
	v_mul_f32_e32 v103, 0xc0135761, v103
	v_mov_b32_dpp v97, v97 row_ror:2 row_mask:0xf bank_mask:0xf bound_ctrl:1
	v_exp_f32_e32 v103, v103
	v_pk_fma_f32 v[96:97], v[136:137], v[96:97], v[140:141]
	v_add_f32_e32 v101, 1.0, v101
	v_pk_fma_f32 v[96:97], v[124:125], v[156:157], v[96:97]
	v_rcp_f32_e32 v150, v101
	v_pk_fma_f32 v[96:97], v[144:145], v[88:89], v[96:97]
	v_add_f32_e32 v101, 1.0, v103
	v_mul_f32_e32 v103, 0x3d372713, v96
	v_mul_f32_e32 v103, v96, v103
	v_mul_f32_e32 v105, 0x3d372713, v97
	v_fma_f32 v103, v96, v103, v96
	v_mul_f32_e32 v105, v97, v105
	v_mul_f32_e32 v103, 0xc0135761, v103
	v_fma_f32 v105, v97, v105, v97
	v_exp_f32_e32 v103, v103
	v_mul_f32_e32 v105, 0xc0135761, v105
	v_exp_f32_e32 v105, v105
	v_cndmask_b32_e64 v91, v83, v91, s[8:9]
	v_mov_b32_dpp v90, v90 row_ror:2 row_mask:0xf bank_mask:0xf bound_ctrl:1
	v_rcp_f32_e32 v151, v101
	v_mov_b32_dpp v91, v91 row_ror:2 row_mask:0xf bank_mask:0xf bound_ctrl:1
	v_pk_fma_f32 v[90:91], v[126:127], v[90:91], v[130:131]
	v_add_f32_e32 v101, 1.0, v103
	v_pk_fma_f32 v[90:91], v[118:119], v[152:153], v[90:91]
	v_rcp_f32_e32 v152, v101
	v_add_f32_e32 v101, 1.0, v105
	v_cndmask_b32_e64 v92, v84, v92, s[8:9]
	v_cndmask_b32_e64 v93, v85, v93, s[8:9]
	v_rcp_f32_e32 v153, v101
	v_mov_b32_dpp v92, v92 row_ror:2 row_mask:0xf bank_mask:0xf bound_ctrl:1
	v_mov_b32_dpp v93, v93 row_ror:2 row_mask:0xf bank_mask:0xf bound_ctrl:1
	v_pk_fma_f32 v[92:93], v[128:129], v[92:93], v[132:133]
	v_pk_fma_f32 v[90:91], v[82:83], v[114:115], v[90:91]
	v_pk_fma_f32 v[92:93], v[120:121], v[158:159], v[92:93]
	v_pk_mul_f32 v[94:95], v[94:95], v[150:151]
	v_pk_fma_f32 v[92:93], v[84:85], v[116:117], v[92:93]
	v_pk_mul_f32 v[90:91], v[90:91], v[94:95]
; __device__ __forceinline__ unsigned cvt_pk_bf16(float lo, float hi) { const f32x2 v = {lo, hi}; const bf16x2_t b = __builtin_convertvector(v, bf16x2_t); return __builtin_bit_cast(unsigned, b); }
; __device__ __forceinline__ float gelu_tanh(float x) { const float t = x + 0.044715f * x * x * x; return x * fast_rcp(1.0f + fast_exp2(-2.3022082f * t)); }
; __device__ __forceinline__ float dpp_ror1(float x) { return __builtin_bit_cast(float, __builtin_amdgcn_mov_dpp(__builtin_bit_cast(int, x), 0x121, 0xf, 0xf, true)); }
; __device__ __forceinline__ float dpp_ror2(float x) { return __builtin_bit_cast(float, __builtin_amdgcn_mov_dpp(__builtin_bit_cast(int, x), 0x122, 0xf, 0xf, true)); }
;     __device__ __forceinline__ void operator()(f32x4 (&acc)[2][2][4][2], const Unit& u, int wr, int wc, int fr, int fq) const {
;     ...
;                     const f32x4 gq = acc[ai][0][m][n] * rs[ai][m], vq = acc[ai][1][m][n] * rs[ai][m];
;                     f32x4 g1, g2, v1, v2;
; #pragma unroll
;                     for (int e = 0; e < 4; ++e) {
;                         g1[e] = dpp_ror1(fr == 15 ? pg[e] : gq[e]); g2[e] = dpp_ror2(fr >= 14 ? pg[e] : gq[e]); v1[e] = dpp_ror1(fr == 15 ? pv[e] : vq[e]); v2[e] = dpp_ror2(fr >= 14 ? pv[e] : vq[e]); }
;                     const f32x4 cg = bg + wg0 * g2 + wg1 * g1 + wg2 * gq, cv = bv + wv0 * v2 + wv1 * v1 + wv2 * vq;
;                     {
;                         u32x2 w; w.x = cvt_pk_bf16(gelu_tanh(cg[0]) * cv[0], gelu_tanh(cg[1]) * cv[1]); w.y = cvt_pk_bf16(gelu_tanh(cg[2]) * cv[2], gelu_tanh(cg[3]) * cv[3]);
;                         *(u32x2*)(act + (size_t)row * DFF + ch0) = w; }
	v_pk_mul_f32 v[94:95], v[96:97], v[152:153]
	v_cvt_pk_bf16_f32 v90, v90, v91
	v_pk_mul_f32 v[92:93], v[92:93], v[94:95]
	v_pk_mul_f32 v[74:75], v[74:75], v[102:103] op_sel_hi:[1,0]
	v_cvt_pk_bf16_f32 v91, v92, v93
	v_mov_b64_e32 v[92:93], s[14:15]
	v_mad_i64_i32 v[94:95], s[48:49], v206, s37, v[92:93]
	v_lshl_add_u64 v[150:151], v[94:95], 0, v[154:155]
	global_store_dwordx2 v[150:151], v[90:91], off
	v_pk_mul_f32 v[78:79], v[78:79], v[102:103] op_sel_hi:[1,0]
	v_pk_mul_f32 v[76:77], v[76:77], v[102:103] op_sel_hi:[1,0]
	v_cndmask_b32_e64 v91, v74, v82, s[6:7]
	v_pk_mul_f32 v[80:81], v[80:81], v[102:103] op_sel_hi:[1,0]
	v_cndmask_b32_e64 v90, v78, v86, s[6:7]
	v_cndmask_b32_e64 v86, v78, v86, s[8:9]
	v_mov_b32_dpp v94, v91 row_ror:1 row_mask:0xf bank_mask:0xf bound_ctrl:1
	v_cndmask_b32_e64 v91, v79, v87, s[6:7]
	v_cndmask_b32_e64 v87, v79, v87, s[8:9]
	v_cndmask_b32_e64 v97, v76, v84, s[6:7]
	v_mov_b32_dpp v86, v86 row_ror:2 row_mask:0xf bank_mask:0xf bound_ctrl:1
	v_mov_b32_dpp v87, v87 row_ror:2 row_mask:0xf bank_mask:0xf bound_ctrl:1
	v_cndmask_b32_e64 v96, v80, v88, s[6:7]
	v_cndmask_b32_e64 v88, v80, v88, s[8:9]
	v_mov_b32_dpp v152, v97 row_ror:1 row_mask:0xf bank_mask:0xf bound_ctrl:1
	v_cndmask_b32_e64 v97, v81, v89, s[6:7]
	v_cndmask_b32_e64 v89, v81, v89, s[8:9]
	v_mov_b32_dpp v90, v90 row_ror:1 row_mask:0xf bank_mask:0xf bound_ctrl:1
	v_mov_b32_dpp v91, v91 row_ror:1 row_mask:0xf bank_mask:0xf bound_ctrl:1
	v_mov_b32_dpp v88, v88 row_ror:2 row_mask:0xf bank_mask:0xf bound_ctrl:1
	v_mov_b32_dpp v89, v89 row_ror:2 row_mask:0xf bank_mask:0xf bound_ctrl:1
	v_pk_fma_f32 v[86:87], v[134:135], v[86:87], v[138:139]
	v_cndmask_b32_e64 v82, v74, v82, s[8:9]
	v_cndmask_b32_e64 v95, v75, v83, s[6:7]
	v_cndmask_b32_e64 v83, v75, v83, s[8:9]
	v_mov_b32_dpp v96, v96 row_ror:1 row_mask:0xf bank_mask:0xf bound_ctrl:1
	v_mov_b32_dpp v97, v97 row_ror:1 row_mask:0xf bank_mask:0xf bound_ctrl:1
	v_pk_fma_f32 v[88:89], v[136:137], v[88:89], v[140:141]
	v_pk_fma_f32 v[86:87], v[122:123], v[90:91], v[86:87]
	v_mov_b32_dpp v82, v82 row_ror:2 row_mask:0xf bank_mask:0xf bound_ctrl:1
	v_mov_b32_dpp v83, v83 row_ror:2 row_mask:0xf bank_mask:0xf bound_ctrl:1
	v_pk_fma_f32 v[88:89], v[124:125], v[96:97], v[88:89]
	v_pk_fma_f32 v[86:87], v[142:143], v[78:79], v[86:87]
	v_mov_b32_dpp v95, v95 row_ror:1 row_mask:0xf bank_mask:0xf bound_ctrl:1
	v_pk_fma_f32 v[88:89], v[144:145], v[80:81], v[88:89]
	v_pk_fma_f32 v[82:83], v[126:127], v[82:83], v[130:131]
	v_mul_f32_e32 v90, 0x3d372713, v86
	v_mul_f32_e32 v91, 0x3d372713, v87
	v_pk_fma_f32 v[82:83], v[118:119], v[94:95], v[82:83]
	v_mul_f32_e32 v90, v86, v90
	v_mul_f32_e32 v91, v87, v91
	v_mul_f32_e32 v94, 0x3d372713, v88
	v_mul_f32_e32 v95, 0x3d372713, v89
	v_fma_f32 v90, v86, v90, v86
	v_fma_f32 v91, v87, v91, v87
	v_mul_f32_e32 v94, v88, v94
	v_mul_f32_e32 v95, v89, v95
	v_mul_f32_e32 v90, 0xc0135761, v90
	v_mul_f32_e32 v91, 0xc0135761, v91
	v_fma_f32 v94, v88, v94, v88
	v_fma_f32 v95, v89, v95, v89
	v_exp_f32_e32 v90, v90
	v_exp_f32_e32 v91, v91
	v_mul_f32_e32 v94, 0xc0135761, v94
	v_mul_f32_e32 v95, 0xc0135761, v95
	v_exp_f32_e32 v94, v94
	v_exp_f32_e32 v95, v95
	v_add_f32_e32 v90, 1.0, v90
	v_add_f32_e32 v91, 1.0, v91
	v_rcp_f32_e32 v90, v90
	v_rcp_f32_e32 v91, v91
	v_add_f32_e32 v94, 1.0, v94
	v_add_f32_e32 v95, 1.0, v95
	v_cndmask_b32_e64 v84, v76, v84, s[8:9]
	v_cndmask_b32_e64 v101, v77, v85, s[6:7]
	v_cndmask_b32_e64 v85, v77, v85, s[8:9]
	v_rcp_f32_e32 v94, v94
	v_rcp_f32_e32 v95, v95
	v_mov_b32_dpp v84, v84 row_ror:2 row_mask:0xf bank_mask:0xf bound_ctrl:1
	v_mov_b32_dpp v85, v85 row_ror:2 row_mask:0xf bank_mask:0xf bound_ctrl:1
	v_fmamk_f32 v100, v179, 0x3a800000, v216
	v_mov_b32_dpp v153, v101 row_ror:1 row_mask:0xf bank_mask:0xf bound_ctrl:1
	v_pk_fma_f32 v[84:85], v[128:129], v[84:85], v[132:133]
	v_rsq_f32_e32 v100, v100
	v_pk_fma_f32 v[84:85], v[120:121], v[152:153], v[84:85]
	v_pk_fma_f32 v[82:83], v[74:75], v[114:115], v[82:83]
	v_pk_mul_f32 v[86:87], v[86:87], v[90:91]
	v_pk_fma_f32 v[84:85], v[76:77], v[116:117], v[84:85]
	v_pk_mul_f32 v[82:83], v[82:83], v[86:87]
	v_pk_mul_f32 v[86:87], v[88:89], v[94:95]
	v_cvt_pk_bf16_f32 v82, v82, v83
	v_pk_mul_f32 v[84:85], v[84:85], v[86:87]
	v_pk_mul_f32 v[66:67], v[66:67], v[100:101] op_sel_hi:[1,0]
	v_cvt_pk_bf16_f32 v83, v84, v85
	v_mad_i64_i32 v[84:85], s[48:49], v204, s37, v[92:93]
	v_lshl_add_u64 v[152:153], v[84:85], 0, v[154:155]
	global_store_dwordx2 v[152:153], v[82:83], off
	v_pk_mul_f32 v[70:71], v[70:71], v[100:101] op_sel_hi:[1,0]
	v_pk_mul_f32 v[68:69], v[68:69], v[100:101] op_sel_hi:[1,0]
	v_cndmask_b32_e64 v83, v66, v74, s[6:7]
	v_pk_mul_f32 v[72:73], v[72:73], v[100:101] op_sel_hi:[1,0]
	v_cndmask_b32_e64 v82, v70, v78, s[6:7]
	v_cndmask_b32_e64 v78, v70, v78, s[8:9]
	v_mov_b32_dpp v84, v83 row_ror:1 row_mask:0xf bank_mask:0xf bound_ctrl:1
	v_cndmask_b32_e64 v83, v71, v79, s[6:7]
	v_cndmask_b32_e64 v79, v71, v79, s[8:9]
	v_cndmask_b32_e64 v87, v68, v76, s[6:7]
	v_mov_b32_dpp v78, v78 row_ror:2 row_mask:0xf bank_mask:0xf bound_ctrl:1
	v_mov_b32_dpp v79, v79 row_ror:2 row_mask:0xf bank_mask:0xf bound_ctrl:1
	v_cndmask_b32_e64 v86, v72, v80, s[6:7]
	v_cndmask_b32_e64 v80, v72, v80, s[8:9]
	v_mov_b32_dpp v88, v87 row_ror:1 row_mask:0xf bank_mask:0xf bound_ctrl:1
	v_cndmask_b32_e64 v87, v73, v81, s[6:7]
	v_cndmask_b32_e64 v81, v73, v81, s[8:9]
	v_mov_b32_dpp v82, v82 row_ror:1 row_mask:0xf bank_mask:0xf bound_ctrl:1
	v_mov_b32_dpp v83, v83 row_ror:1 row_mask:0xf bank_mask:0xf bound_ctrl:1
	v_mov_b32_dpp v80, v80 row_ror:2 row_mask:0xf bank_mask:0xf bound_ctrl:1
	v_mov_b32_dpp v81, v81 row_ror:2 row_mask:0xf bank_mask:0xf bound_ctrl:1
; __device__ __forceinline__ unsigned cvt_pk_bf16(float lo, float hi) { const f32x2 v = {lo, hi}; const bf16x2_t b = __builtin_convertvector(v, bf16x2_t); return __builtin_bit_cast(unsigned, b); }
; __device__ __forceinline__ float gelu_tanh(float x) { const float t = x + 0.044715f * x * x * x; return x * fast_rcp(1.0f + fast_exp2(-2.3022082f * t)); }
; __device__ __forceinline__ float dpp_ror1(float x) { return __builtin_bit_cast(float, __builtin_amdgcn_mov_dpp(__builtin_bit_cast(int, x), 0x121, 0xf, 0xf, true)); }
; __device__ __forceinline__ float dpp_ror2(float x) { return __builtin_bit_cast(float, __builtin_amdgcn_mov_dpp(__builtin_bit_cast(int, x), 0x122, 0xf, 0xf, true)); }
;     __device__ __forceinline__ void operator()(f32x4 (&acc)[2][2][4][2], const Unit& u, int wr, int wc, int fr, int fq) const {
;     ...
;             const int ch0 = u.pn * 128 + wc * 32 + 8 * fq + 4 * n;
;             const f32x4 wg0 = *(const f32x4*)(cw + ch0), wg1 = *(const f32x4*)(cw + DFF2 + ch0), wg2 = *(const f32x4*)(cw + 2 * DFF2 + ch0), bg = *(const f32x4*)(cb + ch0);
;             const f32x4 wv0 = *(const f32x4*)(cw + DFF + ch0), wv1 = *(const f32x4*)(cw + DFF2 + DFF + ch0), wv2 = *(const f32x4*)(cw + 2 * DFF2 + DFF + ch0), bv = *(const f32x4*)(cb + DFF + ch0);
;     ...
;                     const f32x4 gq = acc[ai][0][m][n] * rs[ai][m], vq = acc[ai][1][m][n] * rs[ai][m];
;                     f32x4 g1, g2, v1, v2;
; #pragma unroll
;                     for (int e = 0; e < 4; ++e) {
;                         g1[e] = dpp_ror1(fr == 15 ? pg[e] : gq[e]); g2[e] = dpp_ror2(fr >= 14 ? pg[e] : gq[e]); v1[e] = dpp_ror1(fr == 15 ? pv[e] : vq[e]); v2[e] = dpp_ror2(fr >= 14 ? pv[e] : vq[e]); }
;                     const f32x4 cg = bg + wg0 * g2 + wg1 * g1 + wg2 * gq, cv = bv + wv0 * v2 + wv1 * v1 + wv2 * vq;
;                     {
;                         u32x2 w; w.x = cvt_pk_bf16(gelu_tanh(cg[0]) * cv[0], gelu_tanh(cg[1]) * cv[1]); w.y = cvt_pk_bf16(gelu_tanh(cg[2]) * cv[2], gelu_tanh(cg[3]) * cv[3]);
;                         *(u32x2*)(act + (size_t)row * DFF + ch0) = w; }
;                     if (m == 0 && fr < 2) { float* hp = halo + ((size_t)blk * 4 + fr) * DFF2 + ch0; *(f32x4*)hp = gq; *(f32x4*)(hp + DFF) = vq; }
;                     if (m == 3 && fr >= 14) { float* hp = halo + ((size_t)blk * 4 + fr - 12) * DFF2 + ch0; *(f32x4*)hp = gq; *(f32x4*)(hp + DFF) = vq; }
	v_pk_fma_f32 v[78:79], v[134:135], v[78:79], v[138:139]
	v_cndmask_b32_e64 v74, v66, v74, s[8:9]
	v_cndmask_b32_e64 v85, v67, v75, s[6:7]
	v_cndmask_b32_e64 v75, v67, v75, s[8:9]
	v_mov_b32_dpp v86, v86 row_ror:1 row_mask:0xf bank_mask:0xf bound_ctrl:1
	v_mov_b32_dpp v87, v87 row_ror:1 row_mask:0xf bank_mask:0xf bound_ctrl:1
	v_pk_fma_f32 v[80:81], v[136:137], v[80:81], v[140:141]
	v_pk_fma_f32 v[78:79], v[122:123], v[82:83], v[78:79]
	v_mov_b32_dpp v74, v74 row_ror:2 row_mask:0xf bank_mask:0xf bound_ctrl:1
	v_mov_b32_dpp v75, v75 row_ror:2 row_mask:0xf bank_mask:0xf bound_ctrl:1
	v_pk_fma_f32 v[80:81], v[124:125], v[86:87], v[80:81]
	v_pk_fma_f32 v[78:79], v[142:143], v[70:71], v[78:79]
	v_mov_b32_dpp v85, v85 row_ror:1 row_mask:0xf bank_mask:0xf bound_ctrl:1
	v_pk_fma_f32 v[80:81], v[144:145], v[72:73], v[80:81]
	v_pk_fma_f32 v[74:75], v[126:127], v[74:75], v[130:131]
	v_mul_f32_e32 v82, 0x3d372713, v78
	v_mul_f32_e32 v83, 0x3d372713, v79
	v_pk_fma_f32 v[74:75], v[118:119], v[84:85], v[74:75]
	v_mul_f32_e32 v82, v78, v82
	v_mul_f32_e32 v83, v79, v83
	v_mul_f32_e32 v84, 0x3d372713, v80
	v_mul_f32_e32 v85, 0x3d372713, v81
	v_fma_f32 v82, v78, v82, v78
	v_fma_f32 v83, v79, v83, v79
	v_mul_f32_e32 v84, v80, v84
	v_mul_f32_e32 v85, v81, v85
	v_mul_f32_e32 v82, 0xc0135761, v82
	v_mul_f32_e32 v83, 0xc0135761, v83
	v_fma_f32 v84, v80, v84, v80
	v_fma_f32 v85, v81, v85, v81
	v_exp_f32_e32 v82, v82
	v_exp_f32_e32 v83, v83
	v_mul_f32_e32 v84, 0xc0135761, v84
	v_mul_f32_e32 v85, 0xc0135761, v85
	v_exp_f32_e32 v84, v84
	v_exp_f32_e32 v85, v85
	v_add_f32_e32 v82, 1.0, v82
	v_add_f32_e32 v83, 1.0, v83
	v_rcp_f32_e32 v82, v82
	v_rcp_f32_e32 v83, v83
	v_add_f32_e32 v84, 1.0, v84
	v_add_f32_e32 v85, 1.0, v85
	v_cndmask_b32_e64 v76, v68, v76, s[8:9]
	v_cndmask_b32_e64 v89, v69, v77, s[6:7]
	v_cndmask_b32_e64 v77, v69, v77, s[8:9]
	v_rcp_f32_e32 v84, v84
	v_rcp_f32_e32 v85, v85
	v_mov_b32_dpp v76, v76 row_ror:2 row_mask:0xf bank_mask:0xf bound_ctrl:1
	v_mov_b32_dpp v77, v77 row_ror:2 row_mask:0xf bank_mask:0xf bound_ctrl:1
	v_mov_b32_dpp v89, v89 row_ror:1 row_mask:0xf bank_mask:0xf bound_ctrl:1
	v_pk_fma_f32 v[76:77], v[128:129], v[76:77], v[132:133]
	v_pk_fma_f32 v[74:75], v[66:67], v[114:115], v[74:75]
	v_pk_fma_f32 v[76:77], v[120:121], v[88:89], v[76:77]
	v_pk_mul_f32 v[78:79], v[78:79], v[82:83]
	v_pk_fma_f32 v[76:77], v[68:69], v[116:117], v[76:77]
	v_pk_mul_f32 v[74:75], v[74:75], v[78:79]
	v_pk_mul_f32 v[78:79], v[80:81], v[84:85]
	v_cvt_pk_bf16_f32 v74, v74, v75
	v_pk_mul_f32 v[76:77], v[76:77], v[78:79]
	s_nop 0
	v_cvt_pk_bf16_f32 v75, v76, v77
	v_mad_i64_i32 v[76:77], s[48:49], v202, s37, v[92:93]
	v_lshl_add_u64 v[114:115], v[76:77], 0, v[154:155]
	global_store_dwordx2 v[114:115], v[74:75], off
	s_and_saveexec_b64 s[48:49], s[8:9]
	s_cbranch_execz .LBB0_1142
	v_add_co_u32_e32 v74, vcc, 0xfffbe000, v106
	s_nop 1
	v_addc_co_u32_e32 v75, vcc, -1, v107, vcc
	global_store_dwordx4 v[74:75], v[70:73], off
	s_nop 1
	v_add_co_u32_e32 v70, vcc, 0xfffc0c00, v106
	s_nop 1
	v_addc_co_u32_e32 v71, vcc, -1, v107, vcc
	global_store_dwordx4 v[70:71], v[66:69], off
.LBB0_1142:
	s_or_b64 exec, exec, s[48:49]
	v_or_b32_e32 v116, 4, v188
	v_ashrrev_i32_e32 v117, 31, v116
	v_lshlrev_b64 v[66:67], 2, v[116:117]
	v_lshl_add_u64 v[68:69], s[22:23], 0, v[66:67]
	global_load_dwordx4 v[82:85], v[190:191], off offset:16
	global_load_dwordx4 v[74:77], v[68:69], off
	global_load_dwordx4 v[90:93], v[192:193], off offset:16
	v_lshl_add_u64 v[68:69], s[26:27], 0, v[66:67]
	global_load_dwordx4 v[70:73], v[68:69], off
	v_lshl_add_u64 v[68:69], s[34:35], 0, v[66:67]
	global_load_dwordx4 v[86:89], v[68:69], off
	v_lshl_add_u64 v[68:69], s[24:25], 0, v[66:67]
	global_load_dwordx4 v[94:97], v[68:69], off
	v_lshl_add_u64 v[68:69], s[28:29], 0, v[66:67]
	global_load_dwordx4 v[78:81], v[68:69], off
	v_lshl_add_u64 v[66:67], s[30:31], 0, v[66:67]
	global_load_dwordx4 v[66:69], v[66:67], off
	v_mov_b32_e32 v201, v200
	v_mov_b32_e32 v118, v200
	v_mov_b32_e32 v119, v200
	v_pk_mul_f32 v[64:65], v[64:65], v[118:119]
	v_pk_mul_f32 v[62:63], v[62:63], v[200:201]
	v_pk_mul_f32 v[60:61], v[60:61], v[118:119]
	v_cndmask_b32_e64 v103, v62, 0, s[8:9]
	v_cndmask_b32_e64 v121, v63, 0, s[8:9]
	v_cndmask_b32_e64 v127, v64, 0, s[8:9]
	v_cndmask_b32_e64 v129, v60, 0, s[6:7]
	v_cndmask_b32_e64 v134, v65, 0, s[8:9]
	v_cndmask_b32_e64 v101, v62, 0, s[6:7]
	v_cndmask_b32_e64 v119, v63, 0, s[6:7]
	v_cndmask_b32_e64 v126, v64, 0, s[6:7]
	v_cndmask_b32_e64 v133, v65, 0, s[6:7]
	v_mov_b32_dpp v120, v103 row_ror:2 row_mask:0xf bank_mask:0xf bound_ctrl:1
	v_mov_b32_dpp v121, v121 row_ror:2 row_mask:0xf bank_mask:0xf bound_ctrl:1
	v_mov_b32_dpp v128, v127 row_ror:2 row_mask:0xf bank_mask:0xf bound_ctrl:1
	v_mov_b32_dpp v130, v129 row_ror:1 row_mask:0xf bank_mask:0xf bound_ctrl:1
	v_mov_b32_dpp v129, v134 row_ror:2 row_mask:0xf bank_mask:0xf bound_ctrl:1
	v_mov_b32_dpp v118, v101 row_ror:1 row_mask:0xf bank_mask:0xf bound_ctrl:1
	v_mov_b32_dpp v119, v119 row_ror:1 row_mask:0xf bank_mask:0xf bound_ctrl:1
	v_mov_b32_dpp v126, v126 row_ror:1 row_mask:0xf bank_mask:0xf bound_ctrl:1
	v_mov_b32_dpp v127, v133 row_ror:1 row_mask:0xf bank_mask:0xf bound_ctrl:1
	v_pk_mul_f32 v[58:59], v[58:59], v[200:201]
	v_cndmask_b32_e64 v131, v60, 0, s[8:9]
	v_cndmask_b32_e64 v105, v58, 0, s[6:7]
	v_cndmask_b32_e64 v113, v58, 0, s[8:9]
	v_cndmask_b32_e64 v125, v59, 0, s[8:9]
	v_mov_b32_dpp v122, v105 row_ror:1 row_mask:0xf bank_mask:0xf bound_ctrl:1
	v_mov_b32_dpp v124, v113 row_ror:2 row_mask:0xf bank_mask:0xf bound_ctrl:1
	v_cndmask_b32_e64 v123, v59, 0, s[6:7]
	v_mov_b32_dpp v125, v125 row_ror:2 row_mask:0xf bank_mask:0xf bound_ctrl:1
	v_cndmask_b32_e64 v136, v61, 0, s[8:9]
	v_mov_b32_dpp v123, v123 row_ror:1 row_mask:0xf bank_mask:0xf bound_ctrl:1
	v_cndmask_b32_e64 v135, v61, 0, s[6:7]
	v_mov_b32_dpp v132, v131 row_ror:2 row_mask:0xf bank_mask:0xf bound_ctrl:1
	v_mov_b32_dpp v133, v136 row_ror:2 row_mask:0xf bank_mask:0xf bound_ctrl:1
	v_mov_b32_dpp v131, v135 row_ror:1 row_mask:0xf bank_mask:0xf bound_ctrl:1
	s_waitcnt vmcnt(0)
; __device__ __forceinline__ unsigned cvt_pk_bf16(float lo, float hi) { const f32x2 v = {lo, hi}; const bf16x2_t b = __builtin_convertvector(v, bf16x2_t); return __builtin_bit_cast(unsigned, b); }
; __device__ __forceinline__ float gelu_tanh(float x) { const float t = x + 0.044715f * x * x * x; return x * fast_rcp(1.0f + fast_exp2(-2.3022082f * t)); }
; __device__ __forceinline__ float dpp_ror1(float x) { return __builtin_bit_cast(float, __builtin_amdgcn_mov_dpp(__builtin_bit_cast(int, x), 0x121, 0xf, 0xf, true)); }
; __device__ __forceinline__ float dpp_ror2(float x) { return __builtin_bit_cast(float, __builtin_amdgcn_mov_dpp(__builtin_bit_cast(int, x), 0x122, 0xf, 0xf, true)); }
;     __device__ __forceinline__ void operator()(f32x4 (&acc)[2][2][4][2], const Unit& u, int wr, int wc, int fr, int fq) const {
;     ...
;                     const f32x4 gq = acc[ai][0][m][n] * rs[ai][m], vq = acc[ai][1][m][n] * rs[ai][m];
;                     f32x4 g1, g2, v1, v2;
; #pragma unroll
;                     for (int e = 0; e < 4; ++e) {
;                         g1[e] = dpp_ror1(fr == 15 ? pg[e] : gq[e]); g2[e] = dpp_ror2(fr >= 14 ? pg[e] : gq[e]); v1[e] = dpp_ror1(fr == 15 ? pv[e] : vq[e]); v2[e] = dpp_ror2(fr >= 14 ? pv[e] : vq[e]); }
;                     const f32x4 cg = bg + wg0 * g2 + wg1 * g1 + wg2 * gq, cv = bv + wv0 * v2 + wv1 * v1 + wv2 * vq;
;                     {
;                         u32x2 w; w.x = cvt_pk_bf16(gelu_tanh(cg[0]) * cv[0], gelu_tanh(cg[1]) * cv[1]); w.y = cvt_pk_bf16(gelu_tanh(cg[2]) * cv[2], gelu_tanh(cg[3]) * cv[3]);
;                         *(u32x2*)(act + (size_t)row * DFF + ch0) = w; }
;                     if (m == 0 && fr < 2) { float* hp = halo + ((size_t)blk * 4 + fr) * DFF2 + ch0; *(f32x4*)hp = gq; *(f32x4*)(hp + DFF) = vq; }
;                     if (m == 3 && fr >= 14) { float* hp = halo + ((size_t)blk * 4 + fr - 12) * DFF2 + ch0; *(f32x4*)hp = gq; *(f32x4*)(hp + DFF) = vq; }
	v_pk_fma_f32 v[128:129], v[84:85], v[128:129], v[92:93]
	v_pk_fma_f32 v[120:121], v[82:83], v[120:121], v[90:91]
	v_pk_fma_f32 v[126:127], v[76:77], v[126:127], v[128:129]
	v_pk_fma_f32 v[118:119], v[74:75], v[118:119], v[120:121]
	v_pk_fma_f32 v[124:125], v[70:71], v[124:125], v[86:87]
	v_pk_fma_f32 v[120:121], v[72:73], v[132:133], v[88:89]
	v_pk_fma_f32 v[126:127], v[64:65], v[96:97], v[126:127]
	v_pk_fma_f32 v[118:119], v[62:63], v[94:95], v[118:119]
	v_mul_f32_e32 v105, 0x3d372713, v126
	v_mul_f32_e32 v101, 0x3d372713, v118
	v_mul_f32_e32 v103, 0x3d372713, v119
	v_mul_f32_e32 v113, 0x3d372713, v127
	v_mul_f32_e32 v101, v118, v101
	v_mul_f32_e32 v103, v119, v103
	v_mul_f32_e32 v105, v126, v105
	v_mul_f32_e32 v113, v127, v113
	v_fma_f32 v101, v118, v101, v118
	v_fma_f32 v103, v119, v103, v119
	v_fma_f32 v105, v126, v105, v126
	v_fma_f32 v113, v127, v113, v127
	v_mul_f32_e32 v101, 0xc0135761, v101
	v_mul_f32_e32 v103, 0xc0135761, v103
	v_mul_f32_e32 v105, 0xc0135761, v105
	v_mul_f32_e32 v113, 0xc0135761, v113
	v_exp_f32_e32 v101, v101
	v_exp_f32_e32 v103, v103
	v_exp_f32_e32 v105, v105
	v_exp_f32_e32 v113, v113
	v_add_f32_e32 v101, 1.0, v101
	v_add_f32_e32 v103, 1.0, v103
	v_add_f32_e32 v105, 1.0, v105
	v_add_f32_e32 v113, 1.0, v113
	v_pk_fma_f32 v[122:123], v[78:79], v[122:123], v[124:125]
	v_rcp_f32_e32 v124, v101
	v_rcp_f32_e32 v125, v103
	v_rcp_f32_e32 v128, v105
	v_rcp_f32_e32 v129, v113
	v_pk_fma_f32 v[120:121], v[80:81], v[130:131], v[120:121]
	v_pk_fma_f32 v[122:123], v[58:59], v[66:67], v[122:123]
	v_pk_fma_f32 v[120:121], v[60:61], v[68:69], v[120:121]
	v_pk_mul_f32 v[118:119], v[118:119], v[124:125]
	v_pk_mul_f32 v[124:125], v[126:127], v[128:129]
	v_pk_mul_f32 v[118:119], v[122:123], v[118:119]
	v_pk_mul_f32 v[120:121], v[120:121], v[124:125]
	v_cvt_pk_bf16_f32 v118, v118, v119
	v_cvt_pk_bf16_f32 v119, v120, v121
	global_store_dwordx2 v[198:199], v[118:119], off offset:8
	s_and_saveexec_b64 s[48:49], s[10:11]
	s_cbranch_execz .LBB0_1144
	v_add_co_u32_e32 v118, vcc, 0x2000, v194
	global_store_dwordx4 v[194:195], v[62:65], off offset:16
	s_nop 0
	v_addc_co_u32_e32 v119, vcc, 0, v195, vcc
	global_store_dwordx4 v[118:119], v[58:61], off offset:3088
.LBB0_1144:
	s_or_b64 exec, exec, s[48:49]
	v_mov_b32_e32 v197, v196
	v_pk_mul_f32 v[54:55], v[54:55], v[196:197]
	v_mov_b32_e32 v118, v196
	v_mov_b32_e32 v119, v196
	v_pk_mul_f32 v[50:51], v[50:51], v[196:197]
	v_cndmask_b32_e64 v101, v54, v62, s[6:7]
	v_pk_mul_f32 v[56:57], v[56:57], v[118:119]
	v_pk_mul_f32 v[52:53], v[52:53], v[118:119]
	v_mov_b32_dpp v118, v101 row_ror:1 row_mask:0xf bank_mask:0xf bound_ctrl:1
	v_cndmask_b32_e64 v101, v50, v58, s[6:7]
	v_cndmask_b32_e64 v62, v54, v62, s[8:9]
	v_cndmask_b32_e64 v58, v50, v58, s[8:9]
	v_mov_b32_dpp v120, v101 row_ror:1 row_mask:0xf bank_mask:0xf bound_ctrl:1
	v_cndmask_b32_e64 v101, v55, v63, s[6:7]
	v_cndmask_b32_e64 v63, v55, v63, s[8:9]
	v_mov_b32_dpp v62, v62 row_ror:2 row_mask:0xf bank_mask:0xf bound_ctrl:1
	v_mov_b32_dpp v119, v101 row_ror:1 row_mask:0xf bank_mask:0xf bound_ctrl:1
	v_cndmask_b32_e64 v101, v51, v59, s[6:7]
	v_mov_b32_dpp v63, v63 row_ror:2 row_mask:0xf bank_mask:0xf bound_ctrl:1
	v_pk_fma_f32 v[62:63], v[82:83], v[62:63], v[90:91]
	v_mov_b32_dpp v121, v101 row_ror:1 row_mask:0xf bank_mask:0xf bound_ctrl:1
	v_cndmask_b32_e64 v101, v56, v64, s[6:7]
	v_pk_fma_f32 v[62:63], v[74:75], v[118:119], v[62:63]
	v_cndmask_b32_e64 v64, v56, v64, s[8:9]
	v_mov_b32_dpp v122, v101 row_ror:1 row_mask:0xf bank_mask:0xf bound_ctrl:1
	v_cndmask_b32_e64 v101, v52, v60, s[6:7]
	v_pk_fma_f32 v[62:63], v[54:55], v[94:95], v[62:63]
	v_mov_b32_dpp v64, v64 row_ror:2 row_mask:0xf bank_mask:0xf bound_ctrl:1
	v_mov_b32_dpp v124, v101 row_ror:1 row_mask:0xf bank_mask:0xf bound_ctrl:1
	v_cndmask_b32_e64 v101, v57, v65, s[6:7]
	v_mul_f32_e32 v103, 0x3d372713, v63
	v_mul_f32_e32 v103, v63, v103
	v_mov_b32_dpp v123, v101 row_ror:1 row_mask:0xf bank_mask:0xf bound_ctrl:1
	v_cndmask_b32_e64 v101, v53, v61, s[6:7]
	v_fma_f32 v103, v63, v103, v63
	v_cndmask_b32_e64 v65, v57, v65, s[8:9]
	v_mov_b32_dpp v125, v101 row_ror:1 row_mask:0xf bank_mask:0xf bound_ctrl:1
	v_mul_f32_e32 v101, 0x3d372713, v62
	v_mul_f32_e32 v101, v62, v101
	v_fma_f32 v101, v62, v101, v62
	v_mul_f32_e32 v101, 0xc0135761, v101
	v_exp_f32_e32 v101, v101
	v_mul_f32_e32 v103, 0xc0135761, v103
	v_mov_b32_dpp v65, v65 row_ror:2 row_mask:0xf bank_mask:0xf bound_ctrl:1
	v_exp_f32_e32 v103, v103
	v_pk_fma_f32 v[64:65], v[84:85], v[64:65], v[92:93]
	v_add_f32_e32 v101, 1.0, v101
	v_pk_fma_f32 v[64:65], v[76:77], v[122:123], v[64:65]
	v_rcp_f32_e32 v118, v101
	v_pk_fma_f32 v[64:65], v[56:57], v[96:97], v[64:65]
	v_add_f32_e32 v101, 1.0, v103
	v_mul_f32_e32 v103, 0x3d372713, v64
	v_mul_f32_e32 v103, v64, v103
	v_mul_f32_e32 v105, 0x3d372713, v65
	v_fma_f32 v103, v64, v103, v64
	v_mul_f32_e32 v105, v65, v105
	v_mul_f32_e32 v103, 0xc0135761, v103
	v_fma_f32 v105, v65, v105, v65
	v_exp_f32_e32 v103, v103
	v_mul_f32_e32 v105, 0xc0135761, v105
	v_exp_f32_e32 v105, v105
	v_cndmask_b32_e64 v59, v51, v59, s[8:9]
	v_mov_b32_dpp v58, v58 row_ror:2 row_mask:0xf bank_mask:0xf bound_ctrl:1
	v_rcp_f32_e32 v119, v101
	v_mov_b32_dpp v59, v59 row_ror:2 row_mask:0xf bank_mask:0xf bound_ctrl:1
	v_pk_fma_f32 v[58:59], v[70:71], v[58:59], v[86:87]
	v_add_f32_e32 v101, 1.0, v103
	v_pk_fma_f32 v[58:59], v[78:79], v[120:121], v[58:59]
	v_rcp_f32_e32 v120, v101
	v_add_f32_e32 v101, 1.0, v105
	v_cndmask_b32_e64 v60, v52, v60, s[8:9]
	v_cndmask_b32_e64 v61, v53, v61, s[8:9]
	v_rcp_f32_e32 v121, v101
	v_mov_b32_dpp v60, v60 row_ror:2 row_mask:0xf bank_mask:0xf bound_ctrl:1
; __device__ __forceinline__ unsigned cvt_pk_bf16(float lo, float hi) { const f32x2 v = {lo, hi}; const bf16x2_t b = __builtin_convertvector(v, bf16x2_t); return __builtin_bit_cast(unsigned, b); }
; __device__ __forceinline__ float gelu_tanh(float x) { const float t = x + 0.044715f * x * x * x; return x * fast_rcp(1.0f + fast_exp2(-2.3022082f * t)); }
; __device__ __forceinline__ float dpp_ror1(float x) { return __builtin_bit_cast(float, __builtin_amdgcn_mov_dpp(__builtin_bit_cast(int, x), 0x121, 0xf, 0xf, true)); }
; __device__ __forceinline__ float dpp_ror2(float x) { return __builtin_bit_cast(float, __builtin_amdgcn_mov_dpp(__builtin_bit_cast(int, x), 0x122, 0xf, 0xf, true)); }
;     __device__ __forceinline__ void operator()(f32x4 (&acc)[2][2][4][2], const Unit& u, int wr, int wc, int fr, int fq) const {
;     ...
;                     const f32x4 gq = acc[ai][0][m][n] * rs[ai][m], vq = acc[ai][1][m][n] * rs[ai][m];
;                     f32x4 g1, g2, v1, v2;
; #pragma unroll
;                     for (int e = 0; e < 4; ++e) {
;                         g1[e] = dpp_ror1(fr == 15 ? pg[e] : gq[e]); g2[e] = dpp_ror2(fr >= 14 ? pg[e] : gq[e]); v1[e] = dpp_ror1(fr == 15 ? pv[e] : vq[e]); v2[e] = dpp_ror2(fr >= 14 ? pv[e] : vq[e]); }
;                     const f32x4 cg = bg + wg0 * g2 + wg1 * g1 + wg2 * gq, cv = bv + wv0 * v2 + wv1 * v1 + wv2 * vq;
;                     {
;                         u32x2 w; w.x = cvt_pk_bf16(gelu_tanh(cg[0]) * cv[0], gelu_tanh(cg[1]) * cv[1]); w.y = cvt_pk_bf16(gelu_tanh(cg[2]) * cv[2], gelu_tanh(cg[3]) * cv[3]);
;                         *(u32x2*)(act + (size_t)row * DFF + ch0) = w; }
	v_mov_b32_dpp v61, v61 row_ror:2 row_mask:0xf bank_mask:0xf bound_ctrl:1
	v_pk_fma_f32 v[60:61], v[72:73], v[60:61], v[88:89]
	v_pk_fma_f32 v[58:59], v[50:51], v[66:67], v[58:59]
	v_pk_fma_f32 v[60:61], v[80:81], v[124:125], v[60:61]
	v_pk_mul_f32 v[62:63], v[62:63], v[118:119]
	v_pk_fma_f32 v[60:61], v[52:53], v[68:69], v[60:61]
	v_pk_mul_f32 v[58:59], v[58:59], v[62:63]
	v_pk_mul_f32 v[62:63], v[64:65], v[120:121]
	v_mov_b32_e32 v187, v186
	v_pk_mul_f32 v[60:61], v[60:61], v[62:63]
	v_cvt_pk_bf16_f32 v58, v58, v59
	v_cvt_pk_bf16_f32 v59, v60, v61
	global_store_dwordx2 v[146:147], v[58:59], off offset:8
	v_mov_b32_e32 v58, v186
	v_mov_b32_e32 v59, v186
	v_pk_mul_f32 v[42:43], v[42:43], v[186:187]
	v_pk_mul_f32 v[48:49], v[48:49], v[58:59]
	v_pk_mul_f32 v[46:47], v[46:47], v[186:187]
	v_pk_mul_f32 v[44:45], v[44:45], v[58:59]
	v_cndmask_b32_e64 v59, v42, v50, s[6:7]
	v_cndmask_b32_e64 v58, v46, v54, s[6:7]
	v_cndmask_b32_e64 v54, v46, v54, s[8:9]
	v_mov_b32_dpp v60, v59 row_ror:1 row_mask:0xf bank_mask:0xf bound_ctrl:1
	v_cndmask_b32_e64 v59, v47, v55, s[6:7]
	v_cndmask_b32_e64 v55, v47, v55, s[8:9]
	v_cndmask_b32_e64 v63, v44, v52, s[6:7]
	v_mov_b32_dpp v54, v54 row_ror:2 row_mask:0xf bank_mask:0xf bound_ctrl:1
	v_mov_b32_dpp v55, v55 row_ror:2 row_mask:0xf bank_mask:0xf bound_ctrl:1
	v_cndmask_b32_e64 v62, v48, v56, s[6:7]
	v_cndmask_b32_e64 v56, v48, v56, s[8:9]
	v_mov_b32_dpp v64, v63 row_ror:1 row_mask:0xf bank_mask:0xf bound_ctrl:1
	v_cndmask_b32_e64 v63, v49, v57, s[6:7]
	v_cndmask_b32_e64 v57, v49, v57, s[8:9]
	v_mov_b32_dpp v58, v58 row_ror:1 row_mask:0xf bank_mask:0xf bound_ctrl:1
	v_mov_b32_dpp v59, v59 row_ror:1 row_mask:0xf bank_mask:0xf bound_ctrl:1
	v_mov_b32_dpp v56, v56 row_ror:2 row_mask:0xf bank_mask:0xf bound_ctrl:1
	v_mov_b32_dpp v57, v57 row_ror:2 row_mask:0xf bank_mask:0xf bound_ctrl:1
	v_pk_fma_f32 v[54:55], v[82:83], v[54:55], v[90:91]
	v_cndmask_b32_e64 v50, v42, v50, s[8:9]
	v_cndmask_b32_e64 v61, v43, v51, s[6:7]
	v_cndmask_b32_e64 v51, v43, v51, s[8:9]
	v_mov_b32_dpp v62, v62 row_ror:1 row_mask:0xf bank_mask:0xf bound_ctrl:1
	v_mov_b32_dpp v63, v63 row_ror:1 row_mask:0xf bank_mask:0xf bound_ctrl:1
	v_pk_fma_f32 v[56:57], v[84:85], v[56:57], v[92:93]
	v_pk_fma_f32 v[54:55], v[74:75], v[58:59], v[54:55]
	v_mov_b32_dpp v50, v50 row_ror:2 row_mask:0xf bank_mask:0xf bound_ctrl:1
	v_mov_b32_dpp v51, v51 row_ror:2 row_mask:0xf bank_mask:0xf bound_ctrl:1
	v_pk_fma_f32 v[56:57], v[76:77], v[62:63], v[56:57]
	v_pk_fma_f32 v[54:55], v[46:47], v[94:95], v[54:55]
	v_mov_b32_dpp v61, v61 row_ror:1 row_mask:0xf bank_mask:0xf bound_ctrl:1
	v_pk_fma_f32 v[56:57], v[48:49], v[96:97], v[56:57]
	v_pk_fma_f32 v[50:51], v[70:71], v[50:51], v[86:87]
	v_mul_f32_e32 v58, 0x3d372713, v54
	v_mul_f32_e32 v59, 0x3d372713, v55
	v_pk_fma_f32 v[50:51], v[78:79], v[60:61], v[50:51]
	v_mul_f32_e32 v58, v54, v58
	v_mul_f32_e32 v59, v55, v59
	v_mul_f32_e32 v60, 0x3d372713, v56
	v_mul_f32_e32 v61, 0x3d372713, v57
	v_fma_f32 v58, v54, v58, v54
	v_fma_f32 v59, v55, v59, v55
	v_mul_f32_e32 v60, v56, v60
	v_mul_f32_e32 v61, v57, v61
	v_mul_f32_e32 v58, 0xc0135761, v58
	v_mul_f32_e32 v59, 0xc0135761, v59
	v_fma_f32 v60, v56, v60, v56
	v_fma_f32 v61, v57, v61, v57
	v_exp_f32_e32 v58, v58
	v_exp_f32_e32 v59, v59
	v_mul_f32_e32 v60, 0xc0135761, v60
	v_mul_f32_e32 v61, 0xc0135761, v61
	v_exp_f32_e32 v60, v60
	v_exp_f32_e32 v61, v61
	v_add_f32_e32 v58, 1.0, v58
	v_add_f32_e32 v59, 1.0, v59
	v_rcp_f32_e32 v58, v58
	v_rcp_f32_e32 v59, v59
	v_add_f32_e32 v60, 1.0, v60
	v_add_f32_e32 v61, 1.0, v61
	v_cndmask_b32_e64 v52, v44, v52, s[8:9]
	v_cndmask_b32_e64 v65, v45, v53, s[6:7]
	v_cndmask_b32_e64 v53, v45, v53, s[8:9]
	v_rcp_f32_e32 v60, v60
	v_rcp_f32_e32 v61, v61
	v_mov_b32_dpp v52, v52 row_ror:2 row_mask:0xf bank_mask:0xf bound_ctrl:1
	v_mov_b32_dpp v53, v53 row_ror:2 row_mask:0xf bank_mask:0xf bound_ctrl:1
	v_mov_b32_dpp v65, v65 row_ror:1 row_mask:0xf bank_mask:0xf bound_ctrl:1
	v_pk_fma_f32 v[52:53], v[72:73], v[52:53], v[88:89]
	v_pk_fma_f32 v[50:51], v[42:43], v[66:67], v[50:51]
	v_pk_fma_f32 v[52:53], v[80:81], v[64:65], v[52:53]
	v_pk_mul_f32 v[54:55], v[54:55], v[58:59]
	v_pk_fma_f32 v[52:53], v[44:45], v[68:69], v[52:53]
	v_pk_mul_f32 v[50:51], v[50:51], v[54:55]
	v_pk_mul_f32 v[54:55], v[56:57], v[60:61]
	v_mov_b32_e32 v179, v178
	v_pk_mul_f32 v[52:53], v[52:53], v[54:55]
	v_cvt_pk_bf16_f32 v50, v50, v51
	v_cvt_pk_bf16_f32 v51, v52, v53
	global_store_dwordx2 v[108:109], v[50:51], off offset:8
	v_mov_b32_e32 v50, v178
	v_mov_b32_e32 v51, v178
	v_pk_mul_f32 v[34:35], v[34:35], v[178:179]
	v_pk_mul_f32 v[40:41], v[40:41], v[50:51]
	v_pk_mul_f32 v[38:39], v[38:39], v[178:179]
	v_pk_mul_f32 v[36:37], v[36:37], v[50:51]
	v_cndmask_b32_e64 v51, v34, v42, s[6:7]
	v_cndmask_b32_e64 v50, v38, v46, s[6:7]
	v_cndmask_b32_e64 v46, v38, v46, s[8:9]
	v_mov_b32_dpp v52, v51 row_ror:1 row_mask:0xf bank_mask:0xf bound_ctrl:1
	v_cndmask_b32_e64 v51, v39, v47, s[6:7]
	v_cndmask_b32_e64 v47, v39, v47, s[8:9]
	v_cndmask_b32_e64 v55, v36, v44, s[6:7]
	v_mov_b32_dpp v46, v46 row_ror:2 row_mask:0xf bank_mask:0xf bound_ctrl:1
	v_mov_b32_dpp v47, v47 row_ror:2 row_mask:0xf bank_mask:0xf bound_ctrl:1
	v_cndmask_b32_e64 v54, v40, v48, s[6:7]
	v_cndmask_b32_e64 v48, v40, v48, s[8:9]
	v_mov_b32_dpp v56, v55 row_ror:1 row_mask:0xf bank_mask:0xf bound_ctrl:1
	v_cndmask_b32_e64 v55, v41, v49, s[6:7]
	v_cndmask_b32_e64 v49, v41, v49, s[8:9]
	v_mov_b32_dpp v50, v50 row_ror:1 row_mask:0xf bank_mask:0xf bound_ctrl:1
	v_mov_b32_dpp v51, v51 row_ror:1 row_mask:0xf bank_mask:0xf bound_ctrl:1
	v_mov_b32_dpp v48, v48 row_ror:2 row_mask:0xf bank_mask:0xf bound_ctrl:1
; __device__ __forceinline__ unsigned cvt_pk_bf16(float lo, float hi) { const f32x2 v = {lo, hi}; const bf16x2_t b = __builtin_convertvector(v, bf16x2_t); return __builtin_bit_cast(unsigned, b); }
; __device__ __forceinline__ float gelu_tanh(float x) { const float t = x + 0.044715f * x * x * x; return x * fast_rcp(1.0f + fast_exp2(-2.3022082f * t)); }
; __device__ __forceinline__ float dpp_ror1(float x) { return __builtin_bit_cast(float, __builtin_amdgcn_mov_dpp(__builtin_bit_cast(int, x), 0x121, 0xf, 0xf, true)); }
; __device__ __forceinline__ float dpp_ror2(float x) { return __builtin_bit_cast(float, __builtin_amdgcn_mov_dpp(__builtin_bit_cast(int, x), 0x122, 0xf, 0xf, true)); }
;     __device__ __forceinline__ void operator()(f32x4 (&acc)[2][2][4][2], const Unit& u, int wr, int wc, int fr, int fq) const {
;     ...
;                     const f32x4 gq = acc[ai][0][m][n] * rs[ai][m], vq = acc[ai][1][m][n] * rs[ai][m];
;                     f32x4 g1, g2, v1, v2;
; #pragma unroll
;                     for (int e = 0; e < 4; ++e) {
;                         g1[e] = dpp_ror1(fr == 15 ? pg[e] : gq[e]); g2[e] = dpp_ror2(fr >= 14 ? pg[e] : gq[e]); v1[e] = dpp_ror1(fr == 15 ? pv[e] : vq[e]); v2[e] = dpp_ror2(fr >= 14 ? pv[e] : vq[e]); }
;                     const f32x4 cg = bg + wg0 * g2 + wg1 * g1 + wg2 * gq, cv = bv + wv0 * v2 + wv1 * v1 + wv2 * vq;
;                     {
;                         u32x2 w; w.x = cvt_pk_bf16(gelu_tanh(cg[0]) * cv[0], gelu_tanh(cg[1]) * cv[1]); w.y = cvt_pk_bf16(gelu_tanh(cg[2]) * cv[2], gelu_tanh(cg[3]) * cv[3]);
;                         *(u32x2*)(act + (size_t)row * DFF + ch0) = w; }
;                     if (m == 0 && fr < 2) { float* hp = halo + ((size_t)blk * 4 + fr) * DFF2 + ch0; *(f32x4*)hp = gq; *(f32x4*)(hp + DFF) = vq; }
;                     if (m == 3 && fr >= 14) { float* hp = halo + ((size_t)blk * 4 + fr - 12) * DFF2 + ch0; *(f32x4*)hp = gq; *(f32x4*)(hp + DFF) = vq; }
	v_mov_b32_dpp v49, v49 row_ror:2 row_mask:0xf bank_mask:0xf bound_ctrl:1
	v_pk_fma_f32 v[46:47], v[82:83], v[46:47], v[90:91]
	v_cndmask_b32_e64 v42, v34, v42, s[8:9]
	v_cndmask_b32_e64 v53, v35, v43, s[6:7]
	v_cndmask_b32_e64 v43, v35, v43, s[8:9]
	v_mov_b32_dpp v54, v54 row_ror:1 row_mask:0xf bank_mask:0xf bound_ctrl:1
	v_mov_b32_dpp v55, v55 row_ror:1 row_mask:0xf bank_mask:0xf bound_ctrl:1
	v_pk_fma_f32 v[48:49], v[84:85], v[48:49], v[92:93]
	v_pk_fma_f32 v[46:47], v[74:75], v[50:51], v[46:47]
	v_mov_b32_dpp v42, v42 row_ror:2 row_mask:0xf bank_mask:0xf bound_ctrl:1
	v_mov_b32_dpp v43, v43 row_ror:2 row_mask:0xf bank_mask:0xf bound_ctrl:1
	v_pk_fma_f32 v[48:49], v[76:77], v[54:55], v[48:49]
	v_pk_fma_f32 v[46:47], v[38:39], v[94:95], v[46:47]
	v_mov_b32_dpp v53, v53 row_ror:1 row_mask:0xf bank_mask:0xf bound_ctrl:1
	v_pk_fma_f32 v[48:49], v[40:41], v[96:97], v[48:49]
	v_pk_fma_f32 v[42:43], v[70:71], v[42:43], v[86:87]
	v_mul_f32_e32 v50, 0x3d372713, v46
	v_mul_f32_e32 v51, 0x3d372713, v47
	v_pk_fma_f32 v[42:43], v[78:79], v[52:53], v[42:43]
	v_mul_f32_e32 v50, v46, v50
	v_mul_f32_e32 v51, v47, v51
	v_mul_f32_e32 v52, 0x3d372713, v48
	v_mul_f32_e32 v53, 0x3d372713, v49
	v_fma_f32 v50, v46, v50, v46
	v_fma_f32 v51, v47, v51, v47
	v_mul_f32_e32 v52, v48, v52
	v_mul_f32_e32 v53, v49, v53
	v_mul_f32_e32 v50, 0xc0135761, v50
	v_mul_f32_e32 v51, 0xc0135761, v51
	v_fma_f32 v52, v48, v52, v48
	v_fma_f32 v53, v49, v53, v49
	v_exp_f32_e32 v50, v50
	v_exp_f32_e32 v51, v51
	v_mul_f32_e32 v52, 0xc0135761, v52
	v_mul_f32_e32 v53, 0xc0135761, v53
	v_exp_f32_e32 v52, v52
	v_exp_f32_e32 v53, v53
	v_add_f32_e32 v50, 1.0, v50
	v_add_f32_e32 v51, 1.0, v51
	v_rcp_f32_e32 v50, v50
	v_rcp_f32_e32 v51, v51
	v_add_f32_e32 v52, 1.0, v52
	v_add_f32_e32 v53, 1.0, v53
	v_cndmask_b32_e64 v44, v36, v44, s[8:9]
	v_cndmask_b32_e64 v57, v37, v45, s[6:7]
	v_cndmask_b32_e64 v45, v37, v45, s[8:9]
	v_rcp_f32_e32 v52, v52
	v_rcp_f32_e32 v53, v53
	v_mov_b32_dpp v44, v44 row_ror:2 row_mask:0xf bank_mask:0xf bound_ctrl:1
	v_mov_b32_dpp v45, v45 row_ror:2 row_mask:0xf bank_mask:0xf bound_ctrl:1
	v_mov_b32_dpp v57, v57 row_ror:1 row_mask:0xf bank_mask:0xf bound_ctrl:1
	v_pk_fma_f32 v[44:45], v[72:73], v[44:45], v[88:89]
	v_pk_fma_f32 v[42:43], v[34:35], v[66:67], v[42:43]
	v_pk_fma_f32 v[44:45], v[80:81], v[56:57], v[44:45]
	v_pk_mul_f32 v[46:47], v[46:47], v[50:51]
	v_pk_fma_f32 v[44:45], v[36:37], v[68:69], v[44:45]
	v_pk_mul_f32 v[42:43], v[42:43], v[46:47]
	v_pk_mul_f32 v[46:47], v[48:49], v[52:53]
	v_cvt_pk_bf16_f32 v42, v42, v43
	v_pk_mul_f32 v[44:45], v[44:45], v[46:47]
	s_nop 0
	v_cvt_pk_bf16_f32 v43, v44, v45
	global_store_dwordx2 v[110:111], v[42:43], off offset:8
	s_and_saveexec_b64 s[48:49], s[8:9]
	s_cbranch_execz .LBB0_1146
	v_lshl_add_u64 v[42:43], v[116:117], 2, v[176:177]
	v_add_co_u32_e32 v44, vcc, 0xfffbe000, v42
	s_nop 1
	v_addc_co_u32_e32 v45, vcc, -1, v43, vcc
	global_store_dwordx4 v[44:45], v[38:41], off
	s_nop 1
	v_add_co_u32_e32 v38, vcc, 0xfffc0c00, v42
	s_nop 1
	v_addc_co_u32_e32 v39, vcc, -1, v43, vcc
	global_store_dwordx4 v[38:39], v[34:37], off
.LBB0_1146:
	s_or_b64 exec, exec, s[48:49]
	s_nop 0
	v_mov_b32_e32 v34, v104
	v_mov_b32_e32 v35, v104
	v_mov_b32_e32 v105, v104
	v_pk_mul_f32 v[32:33], v[32:33], v[34:35]
	v_pk_mul_f32 v[30:31], v[30:31], v[104:105]
	v_pk_mul_f32 v[28:29], v[28:29], v[34:35]
	v_cndmask_b32_e64 v43, v32, 0, s[8:9]
	v_pk_mul_f32 v[26:27], v[26:27], v[104:105]
	v_cndmask_b32_e64 v35, v30, 0, s[8:9]
	v_mov_b32_dpp v44, v43 row_ror:2 row_mask:0xf bank_mask:0xf bound_ctrl:1
	v_cndmask_b32_e64 v43, v28, 0, s[6:7]
	v_mov_b32_dpp v36, v35 row_ror:2 row_mask:0xf bank_mask:0xf bound_ctrl:1
	v_cndmask_b32_e64 v35, v26, 0, s[6:7]
	v_mov_b32_dpp v46, v43 row_ror:1 row_mask:0xf bank_mask:0xf bound_ctrl:1
	v_cndmask_b32_e64 v43, v28, 0, s[8:9]
	v_cndmask_b32_e64 v45, v33, 0, s[8:9]
	v_mov_b32_dpp v38, v35 row_ror:1 row_mask:0xf bank_mask:0xf bound_ctrl:1
	v_cndmask_b32_e64 v35, v26, 0, s[8:9]
	v_cndmask_b32_e64 v37, v31, 0, s[8:9]
	v_cndmask_b32_e64 v42, v32, 0, s[6:7]
	v_mov_b32_dpp v48, v43 row_ror:2 row_mask:0xf bank_mask:0xf bound_ctrl:1
	v_cndmask_b32_e64 v43, v33, 0, s[6:7]
	v_mov_b32_dpp v45, v45 row_ror:2 row_mask:0xf bank_mask:0xf bound_ctrl:1
	v_cndmask_b32_e64 v34, v30, 0, s[6:7]
	v_mov_b32_dpp v40, v35 row_ror:2 row_mask:0xf bank_mask:0xf bound_ctrl:1
	v_cndmask_b32_e64 v35, v31, 0, s[6:7]
	v_mov_b32_dpp v37, v37 row_ror:2 row_mask:0xf bank_mask:0xf bound_ctrl:1
	v_mov_b32_dpp v42, v42 row_ror:1 row_mask:0xf bank_mask:0xf bound_ctrl:1
	v_mov_b32_dpp v43, v43 row_ror:1 row_mask:0xf bank_mask:0xf bound_ctrl:1
	v_cndmask_b32_e64 v49, v29, 0, s[8:9]
	v_pk_fma_f32 v[44:45], v[84:85], v[44:45], v[92:93]
	v_mov_b32_dpp v34, v34 row_ror:1 row_mask:0xf bank_mask:0xf bound_ctrl:1
	v_mov_b32_dpp v35, v35 row_ror:1 row_mask:0xf bank_mask:0xf bound_ctrl:1
	v_cndmask_b32_e64 v41, v27, 0, s[8:9]
	v_cndmask_b32_e64 v47, v29, 0, s[6:7]
	v_mov_b32_dpp v49, v49 row_ror:2 row_mask:0xf bank_mask:0xf bound_ctrl:1
	v_pk_fma_f32 v[36:37], v[82:83], v[36:37], v[90:91]
	v_pk_fma_f32 v[42:43], v[76:77], v[42:43], v[44:45]
	v_cndmask_b32_e64 v39, v27, 0, s[6:7]
	v_mov_b32_dpp v41, v41 row_ror:2 row_mask:0xf bank_mask:0xf bound_ctrl:1
	v_mov_b32_dpp v47, v47 row_ror:1 row_mask:0xf bank_mask:0xf bound_ctrl:1
	v_pk_fma_f32 v[34:35], v[74:75], v[34:35], v[36:37]
	v_pk_fma_f32 v[36:37], v[32:33], v[96:97], v[42:43]
	v_pk_fma_f32 v[42:43], v[72:73], v[48:49], v[88:89]
	v_mov_b32_dpp v39, v39 row_ror:1 row_mask:0xf bank_mask:0xf bound_ctrl:1
	v_pk_fma_f32 v[34:35], v[30:31], v[94:95], v[34:35]
	v_pk_fma_f32 v[40:41], v[70:71], v[40:41], v[86:87]
	v_pk_fma_f32 v[42:43], v[80:81], v[46:47], v[42:43]
	v_pk_fma_f32 v[38:39], v[78:79], v[38:39], v[40:41]
	v_pk_fma_f32 v[40:41], v[28:29], v[68:69], v[42:43]
	v_mul_f32_e32 v42, 0x3d372713, v34
	v_mul_f32_e32 v43, 0x3d372713, v35
	v_mul_f32_e32 v44, 0x3d372713, v36
	v_mul_f32_e32 v45, 0x3d372713, v37
	v_mul_f32_e32 v42, v34, v42
	v_mul_f32_e32 v43, v35, v43
	v_mul_f32_e32 v44, v36, v44
	v_mul_f32_e32 v45, v37, v45
	v_fma_f32 v42, v34, v42, v34
	v_fma_f32 v43, v35, v43, v35
	v_fma_f32 v44, v36, v44, v36
	v_fma_f32 v45, v37, v45, v37
	v_mul_f32_e32 v42, 0xc0135761, v42
	v_mul_f32_e32 v43, 0xc0135761, v43
	v_mul_f32_e32 v44, 0xc0135761, v44
	v_mul_f32_e32 v45, 0xc0135761, v45
	v_exp_f32_e32 v42, v42
	v_exp_f32_e32 v43, v43
	v_exp_f32_e32 v44, v44
	v_exp_f32_e32 v45, v45
	v_add_f32_e32 v42, 1.0, v42
	v_add_f32_e32 v43, 1.0, v43
	v_add_f32_e32 v44, 1.0, v44
	v_add_f32_e32 v45, 1.0, v45
	v_rcp_f32_e32 v42, v42
	v_rcp_f32_e32 v43, v43
	v_rcp_f32_e32 v44, v44
	v_rcp_f32_e32 v45, v45
	v_pk_fma_f32 v[38:39], v[26:27], v[66:67], v[38:39]
	v_pk_mul_f32 v[34:35], v[34:35], v[42:43]
	v_pk_mul_f32 v[36:37], v[36:37], v[44:45]
	v_pk_mul_f32 v[34:35], v[38:39], v[34:35]
	v_pk_mul_f32 v[36:37], v[40:41], v[36:37]
	v_cvt_pk_bf16_f32 v34, v34, v35
	v_cvt_pk_bf16_f32 v35, v36, v37
	global_store_dwordx2 v[148:149], v[34:35], off offset:8
	s_and_saveexec_b64 s[48:49], s[10:11]
	s_cbranch_execz .LBB0_1148
; __device__ __forceinline__ unsigned cvt_pk_bf16(float lo, float hi) { const f32x2 v = {lo, hi}; const bf16x2_t b = __builtin_convertvector(v, bf16x2_t); return __builtin_bit_cast(unsigned, b); }
; __device__ __forceinline__ float gelu_tanh(float x) { const float t = x + 0.044715f * x * x * x; return x * fast_rcp(1.0f + fast_exp2(-2.3022082f * t)); }
; __device__ __forceinline__ float dpp_ror1(float x) { return __builtin_bit_cast(float, __builtin_amdgcn_mov_dpp(__builtin_bit_cast(int, x), 0x121, 0xf, 0xf, true)); }
; __device__ __forceinline__ float dpp_ror2(float x) { return __builtin_bit_cast(float, __builtin_amdgcn_mov_dpp(__builtin_bit_cast(int, x), 0x122, 0xf, 0xf, true)); }
;     __device__ __forceinline__ void operator()(f32x4 (&acc)[2][2][4][2], const Unit& u, int wr, int wc, int fr, int fq) const {
;     ...
;                     const f32x4 gq = acc[ai][0][m][n] * rs[ai][m], vq = acc[ai][1][m][n] * rs[ai][m];
;                     f32x4 g1, g2, v1, v2;
; #pragma unroll
;                     for (int e = 0; e < 4; ++e) {
;                         g1[e] = dpp_ror1(fr == 15 ? pg[e] : gq[e]); g2[e] = dpp_ror2(fr >= 14 ? pg[e] : gq[e]); v1[e] = dpp_ror1(fr == 15 ? pv[e] : vq[e]); v2[e] = dpp_ror2(fr >= 14 ? pv[e] : vq[e]); }
;                     const f32x4 cg = bg + wg0 * g2 + wg1 * g1 + wg2 * gq, cv = bv + wv0 * v2 + wv1 * v1 + wv2 * vq;
;                     {
;                         u32x2 w; w.x = cvt_pk_bf16(gelu_tanh(cg[0]) * cv[0], gelu_tanh(cg[1]) * cv[1]); w.y = cvt_pk_bf16(gelu_tanh(cg[2]) * cv[2], gelu_tanh(cg[3]) * cv[3]);
;                         *(u32x2*)(act + (size_t)row * DFF + ch0) = w; }
;                     if (m == 0 && fr < 2) { float* hp = halo + ((size_t)blk * 4 + fr) * DFF2 + ch0; *(f32x4*)hp = gq; *(f32x4*)(hp + DFF) = vq; }
;                     if (m == 3 && fr >= 14) { float* hp = halo + ((size_t)blk * 4 + fr - 12) * DFF2 + ch0; *(f32x4*)hp = gq; *(f32x4*)(hp + DFF) = vq; }
	v_add_co_u32_e32 v34, vcc, 0x2000, v106
	global_store_dwordx4 v[106:107], v[30:33], off offset:16
	s_nop 0
	v_addc_co_u32_e32 v35, vcc, 0, v107, vcc
	global_store_dwordx4 v[34:35], v[26:29], off offset:3088
.LBB0_1148:
	s_or_b64 exec, exec, s[48:49]
	v_mov_b32_e32 v113, v112
	v_mov_b32_e32 v34, v112
	v_mov_b32_e32 v35, v112
	v_pk_mul_f32 v[18:19], v[18:19], v[112:113]
	v_pk_mul_f32 v[24:25], v[24:25], v[34:35]
	v_pk_mul_f32 v[22:23], v[22:23], v[112:113]
	v_pk_mul_f32 v[20:21], v[20:21], v[34:35]
	v_cndmask_b32_e64 v35, v18, v26, s[6:7]
	v_cndmask_b32_e64 v34, v22, v30, s[6:7]
	v_cndmask_b32_e64 v30, v22, v30, s[8:9]
	v_mov_b32_dpp v36, v35 row_ror:1 row_mask:0xf bank_mask:0xf bound_ctrl:1
	v_cndmask_b32_e64 v35, v23, v31, s[6:7]
	v_cndmask_b32_e64 v31, v23, v31, s[8:9]
	v_cndmask_b32_e64 v39, v20, v28, s[6:7]
	v_mov_b32_dpp v30, v30 row_ror:2 row_mask:0xf bank_mask:0xf bound_ctrl:1
	v_mov_b32_dpp v31, v31 row_ror:2 row_mask:0xf bank_mask:0xf bound_ctrl:1
	v_cndmask_b32_e64 v38, v24, v32, s[6:7]
	v_cndmask_b32_e64 v32, v24, v32, s[8:9]
	v_mov_b32_dpp v40, v39 row_ror:1 row_mask:0xf bank_mask:0xf bound_ctrl:1
	v_cndmask_b32_e64 v39, v25, v33, s[6:7]
	v_cndmask_b32_e64 v33, v25, v33, s[8:9]
	v_mov_b32_dpp v34, v34 row_ror:1 row_mask:0xf bank_mask:0xf bound_ctrl:1
	v_mov_b32_dpp v35, v35 row_ror:1 row_mask:0xf bank_mask:0xf bound_ctrl:1
	v_mov_b32_dpp v32, v32 row_ror:2 row_mask:0xf bank_mask:0xf bound_ctrl:1
	v_mov_b32_dpp v33, v33 row_ror:2 row_mask:0xf bank_mask:0xf bound_ctrl:1
	v_pk_fma_f32 v[30:31], v[82:83], v[30:31], v[90:91]
	v_cndmask_b32_e64 v26, v18, v26, s[8:9]
	v_cndmask_b32_e64 v37, v19, v27, s[6:7]
	v_cndmask_b32_e64 v27, v19, v27, s[8:9]
	v_mov_b32_dpp v38, v38 row_ror:1 row_mask:0xf bank_mask:0xf bound_ctrl:1
	v_mov_b32_dpp v39, v39 row_ror:1 row_mask:0xf bank_mask:0xf bound_ctrl:1
	v_pk_fma_f32 v[32:33], v[84:85], v[32:33], v[92:93]
	v_pk_fma_f32 v[30:31], v[74:75], v[34:35], v[30:31]
	v_mov_b32_dpp v26, v26 row_ror:2 row_mask:0xf bank_mask:0xf bound_ctrl:1
	v_mov_b32_dpp v27, v27 row_ror:2 row_mask:0xf bank_mask:0xf bound_ctrl:1
	v_pk_fma_f32 v[32:33], v[76:77], v[38:39], v[32:33]
	v_pk_fma_f32 v[30:31], v[22:23], v[94:95], v[30:31]
	v_mov_b32_dpp v37, v37 row_ror:1 row_mask:0xf bank_mask:0xf bound_ctrl:1
	v_pk_fma_f32 v[32:33], v[24:25], v[96:97], v[32:33]
	v_pk_fma_f32 v[26:27], v[70:71], v[26:27], v[86:87]
	v_mul_f32_e32 v34, 0x3d372713, v30
	v_mul_f32_e32 v35, 0x3d372713, v31
	v_pk_fma_f32 v[26:27], v[78:79], v[36:37], v[26:27]
	v_mul_f32_e32 v34, v30, v34
	v_mul_f32_e32 v35, v31, v35
	v_mul_f32_e32 v36, 0x3d372713, v32
	v_mul_f32_e32 v37, 0x3d372713, v33
	v_fma_f32 v34, v30, v34, v30
	v_fma_f32 v35, v31, v35, v31
	v_mul_f32_e32 v36, v32, v36
	v_mul_f32_e32 v37, v33, v37
	v_mul_f32_e32 v34, 0xc0135761, v34
	v_mul_f32_e32 v35, 0xc0135761, v35
	v_fma_f32 v36, v32, v36, v32
	v_fma_f32 v37, v33, v37, v33
	v_exp_f32_e32 v34, v34
	v_exp_f32_e32 v35, v35
	v_mul_f32_e32 v36, 0xc0135761, v36
	v_mul_f32_e32 v37, 0xc0135761, v37
	v_exp_f32_e32 v36, v36
	v_exp_f32_e32 v37, v37
	v_add_f32_e32 v34, 1.0, v34
	v_add_f32_e32 v35, 1.0, v35
	v_rcp_f32_e32 v34, v34
	v_rcp_f32_e32 v35, v35
	v_add_f32_e32 v36, 1.0, v36
	v_add_f32_e32 v37, 1.0, v37
	v_cndmask_b32_e64 v28, v20, v28, s[8:9]
	v_cndmask_b32_e64 v41, v21, v29, s[6:7]
	v_cndmask_b32_e64 v29, v21, v29, s[8:9]
	v_rcp_f32_e32 v36, v36
	v_rcp_f32_e32 v37, v37
	v_mov_b32_dpp v28, v28 row_ror:2 row_mask:0xf bank_mask:0xf bound_ctrl:1
	v_mov_b32_dpp v29, v29 row_ror:2 row_mask:0xf bank_mask:0xf bound_ctrl:1
	v_mov_b32_dpp v41, v41 row_ror:1 row_mask:0xf bank_mask:0xf bound_ctrl:1
	v_pk_fma_f32 v[28:29], v[72:73], v[28:29], v[88:89]
	v_pk_fma_f32 v[26:27], v[18:19], v[66:67], v[26:27]
	v_pk_fma_f32 v[28:29], v[80:81], v[40:41], v[28:29]
	v_pk_mul_f32 v[30:31], v[30:31], v[34:35]
	v_pk_fma_f32 v[28:29], v[20:21], v[68:69], v[28:29]
	v_pk_mul_f32 v[26:27], v[26:27], v[30:31]
	v_pk_mul_f32 v[30:31], v[32:33], v[36:37]
	v_mov_b32_e32 v103, v102
	v_pk_mul_f32 v[28:29], v[28:29], v[30:31]
	v_cvt_pk_bf16_f32 v26, v26, v27
	v_cvt_pk_bf16_f32 v27, v28, v29
	global_store_dwordx2 v[150:151], v[26:27], off offset:8
	v_mov_b32_e32 v26, v102
	v_mov_b32_e32 v27, v102
	v_pk_mul_f32 v[10:11], v[10:11], v[102:103]
	v_pk_mul_f32 v[16:17], v[16:17], v[26:27]
	v_pk_mul_f32 v[14:15], v[14:15], v[102:103]
	v_pk_mul_f32 v[12:13], v[12:13], v[26:27]
	v_cndmask_b32_e64 v27, v10, v18, s[6:7]
	v_cndmask_b32_e64 v26, v14, v22, s[6:7]
	v_cndmask_b32_e64 v22, v14, v22, s[8:9]
	v_mov_b32_dpp v28, v27 row_ror:1 row_mask:0xf bank_mask:0xf bound_ctrl:1
	v_cndmask_b32_e64 v27, v15, v23, s[6:7]
	v_cndmask_b32_e64 v23, v15, v23, s[8:9]
	v_cndmask_b32_e64 v31, v12, v20, s[6:7]
	v_mov_b32_dpp v22, v22 row_ror:2 row_mask:0xf bank_mask:0xf bound_ctrl:1
	v_mov_b32_dpp v23, v23 row_ror:2 row_mask:0xf bank_mask:0xf bound_ctrl:1
	v_cndmask_b32_e64 v30, v16, v24, s[6:7]
	v_cndmask_b32_e64 v24, v16, v24, s[8:9]
	v_mov_b32_dpp v32, v31 row_ror:1 row_mask:0xf bank_mask:0xf bound_ctrl:1
	v_cndmask_b32_e64 v31, v17, v25, s[6:7]
	v_cndmask_b32_e64 v25, v17, v25, s[8:9]
	v_mov_b32_dpp v26, v26 row_ror:1 row_mask:0xf bank_mask:0xf bound_ctrl:1
	v_mov_b32_dpp v27, v27 row_ror:1 row_mask:0xf bank_mask:0xf bound_ctrl:1
	v_mov_b32_dpp v24, v24 row_ror:2 row_mask:0xf bank_mask:0xf bound_ctrl:1
	v_mov_b32_dpp v25, v25 row_ror:2 row_mask:0xf bank_mask:0xf bound_ctrl:1
	v_pk_fma_f32 v[22:23], v[82:83], v[22:23], v[90:91]
	v_cndmask_b32_e64 v18, v10, v18, s[8:9]
	v_cndmask_b32_e64 v29, v11, v19, s[6:7]
	v_cndmask_b32_e64 v19, v11, v19, s[8:9]
	v_mov_b32_dpp v30, v30 row_ror:1 row_mask:0xf bank_mask:0xf bound_ctrl:1
; __device__ __forceinline__ unsigned cvt_pk_bf16(float lo, float hi) { const f32x2 v = {lo, hi}; const bf16x2_t b = __builtin_convertvector(v, bf16x2_t); return __builtin_bit_cast(unsigned, b); }
; __device__ __forceinline__ float gelu_tanh(float x) { const float t = x + 0.044715f * x * x * x; return x * fast_rcp(1.0f + fast_exp2(-2.3022082f * t)); }
; __device__ __forceinline__ float dpp_ror1(float x) { return __builtin_bit_cast(float, __builtin_amdgcn_mov_dpp(__builtin_bit_cast(int, x), 0x121, 0xf, 0xf, true)); }
; __device__ __forceinline__ float dpp_ror2(float x) { return __builtin_bit_cast(float, __builtin_amdgcn_mov_dpp(__builtin_bit_cast(int, x), 0x122, 0xf, 0xf, true)); }
;     __device__ __forceinline__ void operator()(f32x4 (&acc)[2][2][4][2], const Unit& u, int wr, int wc, int fr, int fq) const {
;     ...
;                     const f32x4 gq = acc[ai][0][m][n] * rs[ai][m], vq = acc[ai][1][m][n] * rs[ai][m];
;                     f32x4 g1, g2, v1, v2;
; #pragma unroll
;                     for (int e = 0; e < 4; ++e) {
;                         g1[e] = dpp_ror1(fr == 15 ? pg[e] : gq[e]); g2[e] = dpp_ror2(fr >= 14 ? pg[e] : gq[e]); v1[e] = dpp_ror1(fr == 15 ? pv[e] : vq[e]); v2[e] = dpp_ror2(fr >= 14 ? pv[e] : vq[e]); }
;                     const f32x4 cg = bg + wg0 * g2 + wg1 * g1 + wg2 * gq, cv = bv + wv0 * v2 + wv1 * v1 + wv2 * vq;
;                     {
;                         u32x2 w; w.x = cvt_pk_bf16(gelu_tanh(cg[0]) * cv[0], gelu_tanh(cg[1]) * cv[1]); w.y = cvt_pk_bf16(gelu_tanh(cg[2]) * cv[2], gelu_tanh(cg[3]) * cv[3]);
;                         *(u32x2*)(act + (size_t)row * DFF + ch0) = w; }
;                     if (m == 0 && fr < 2) { float* hp = halo + ((size_t)blk * 4 + fr) * DFF2 + ch0; *(f32x4*)hp = gq; *(f32x4*)(hp + DFF) = vq; }
;                     if (m == 3 && fr >= 14) { float* hp = halo + ((size_t)blk * 4 + fr - 12) * DFF2 + ch0; *(f32x4*)hp = gq; *(f32x4*)(hp + DFF) = vq; }
	v_mov_b32_dpp v31, v31 row_ror:1 row_mask:0xf bank_mask:0xf bound_ctrl:1
	v_pk_fma_f32 v[24:25], v[84:85], v[24:25], v[92:93]
	v_pk_fma_f32 v[22:23], v[74:75], v[26:27], v[22:23]
	v_mov_b32_dpp v18, v18 row_ror:2 row_mask:0xf bank_mask:0xf bound_ctrl:1
	v_mov_b32_dpp v19, v19 row_ror:2 row_mask:0xf bank_mask:0xf bound_ctrl:1
	v_pk_fma_f32 v[24:25], v[76:77], v[30:31], v[24:25]
	v_pk_fma_f32 v[22:23], v[14:15], v[94:95], v[22:23]
	v_mov_b32_dpp v29, v29 row_ror:1 row_mask:0xf bank_mask:0xf bound_ctrl:1
	v_pk_fma_f32 v[24:25], v[16:17], v[96:97], v[24:25]
	v_pk_fma_f32 v[18:19], v[70:71], v[18:19], v[86:87]
	v_mul_f32_e32 v26, 0x3d372713, v22
	v_mul_f32_e32 v27, 0x3d372713, v23
	v_pk_fma_f32 v[18:19], v[78:79], v[28:29], v[18:19]
	v_mul_f32_e32 v26, v22, v26
	v_mul_f32_e32 v27, v23, v27
	v_mul_f32_e32 v28, 0x3d372713, v24
	v_mul_f32_e32 v29, 0x3d372713, v25
	v_fma_f32 v26, v22, v26, v22
	v_fma_f32 v27, v23, v27, v23
	v_mul_f32_e32 v28, v24, v28
	v_mul_f32_e32 v29, v25, v29
	v_mul_f32_e32 v26, 0xc0135761, v26
	v_mul_f32_e32 v27, 0xc0135761, v27
	v_fma_f32 v28, v24, v28, v24
	v_fma_f32 v29, v25, v29, v25
	v_exp_f32_e32 v26, v26
	v_exp_f32_e32 v27, v27
	v_mul_f32_e32 v28, 0xc0135761, v28
	v_mul_f32_e32 v29, 0xc0135761, v29
	v_exp_f32_e32 v28, v28
	v_exp_f32_e32 v29, v29
	v_add_f32_e32 v26, 1.0, v26
	v_add_f32_e32 v27, 1.0, v27
	v_rcp_f32_e32 v26, v26
	v_rcp_f32_e32 v27, v27
	v_add_f32_e32 v28, 1.0, v28
	v_add_f32_e32 v29, 1.0, v29
	v_cndmask_b32_e64 v20, v12, v20, s[8:9]
	v_cndmask_b32_e64 v33, v13, v21, s[6:7]
	v_cndmask_b32_e64 v21, v13, v21, s[8:9]
	v_rcp_f32_e32 v28, v28
	v_rcp_f32_e32 v29, v29
	v_mov_b32_dpp v20, v20 row_ror:2 row_mask:0xf bank_mask:0xf bound_ctrl:1
	v_mov_b32_dpp v21, v21 row_ror:2 row_mask:0xf bank_mask:0xf bound_ctrl:1
	v_mov_b32_dpp v33, v33 row_ror:1 row_mask:0xf bank_mask:0xf bound_ctrl:1
	v_pk_fma_f32 v[20:21], v[72:73], v[20:21], v[88:89]
	v_pk_fma_f32 v[18:19], v[10:11], v[66:67], v[18:19]
	v_pk_fma_f32 v[20:21], v[80:81], v[32:33], v[20:21]
	v_pk_mul_f32 v[22:23], v[22:23], v[26:27]
	v_pk_fma_f32 v[20:21], v[12:13], v[68:69], v[20:21]
	v_pk_mul_f32 v[18:19], v[18:19], v[22:23]
	v_pk_mul_f32 v[22:23], v[24:25], v[28:29]
	v_mov_b32_e32 v101, v100
	v_pk_mul_f32 v[20:21], v[20:21], v[22:23]
	v_cvt_pk_bf16_f32 v18, v18, v19
	v_cvt_pk_bf16_f32 v19, v20, v21
	global_store_dwordx2 v[152:153], v[18:19], off offset:8
	v_mov_b32_e32 v18, v100
	v_mov_b32_e32 v19, v100
	v_pk_mul_f32 v[2:3], v[2:3], v[100:101]
	v_pk_mul_f32 v[8:9], v[8:9], v[18:19]
	v_pk_mul_f32 v[6:7], v[6:7], v[100:101]
	v_pk_mul_f32 v[4:5], v[4:5], v[18:19]
	v_cndmask_b32_e64 v19, v2, v10, s[6:7]
	v_cndmask_b32_e64 v18, v6, v14, s[6:7]
	v_cndmask_b32_e64 v14, v6, v14, s[8:9]
	v_mov_b32_dpp v20, v19 row_ror:1 row_mask:0xf bank_mask:0xf bound_ctrl:1
	v_cndmask_b32_e64 v19, v7, v15, s[6:7]
	v_cndmask_b32_e64 v15, v7, v15, s[8:9]
	v_cndmask_b32_e64 v23, v4, v12, s[6:7]
	v_mov_b32_dpp v14, v14 row_ror:2 row_mask:0xf bank_mask:0xf bound_ctrl:1
	v_mov_b32_dpp v15, v15 row_ror:2 row_mask:0xf bank_mask:0xf bound_ctrl:1
	v_cndmask_b32_e64 v22, v8, v16, s[6:7]
	v_cndmask_b32_e64 v16, v8, v16, s[8:9]
	v_mov_b32_dpp v24, v23 row_ror:1 row_mask:0xf bank_mask:0xf bound_ctrl:1
	v_cndmask_b32_e64 v23, v9, v17, s[6:7]
	v_cndmask_b32_e64 v17, v9, v17, s[8:9]
	v_mov_b32_dpp v18, v18 row_ror:1 row_mask:0xf bank_mask:0xf bound_ctrl:1
	v_mov_b32_dpp v19, v19 row_ror:1 row_mask:0xf bank_mask:0xf bound_ctrl:1
	v_mov_b32_dpp v16, v16 row_ror:2 row_mask:0xf bank_mask:0xf bound_ctrl:1
	v_mov_b32_dpp v17, v17 row_ror:2 row_mask:0xf bank_mask:0xf bound_ctrl:1
	v_pk_fma_f32 v[14:15], v[82:83], v[14:15], v[90:91]
	v_cndmask_b32_e64 v10, v2, v10, s[8:9]
	v_cndmask_b32_e64 v21, v3, v11, s[6:7]
	v_cndmask_b32_e64 v11, v3, v11, s[8:9]
	v_mov_b32_dpp v22, v22 row_ror:1 row_mask:0xf bank_mask:0xf bound_ctrl:1
	v_mov_b32_dpp v23, v23 row_ror:1 row_mask:0xf bank_mask:0xf bound_ctrl:1
	v_pk_fma_f32 v[16:17], v[84:85], v[16:17], v[92:93]
	v_pk_fma_f32 v[14:15], v[74:75], v[18:19], v[14:15]
	v_mov_b32_dpp v10, v10 row_ror:2 row_mask:0xf bank_mask:0xf bound_ctrl:1
	v_mov_b32_dpp v11, v11 row_ror:2 row_mask:0xf bank_mask:0xf bound_ctrl:1
	v_pk_fma_f32 v[16:17], v[76:77], v[22:23], v[16:17]
	v_pk_fma_f32 v[14:15], v[6:7], v[94:95], v[14:15]
	v_mov_b32_dpp v21, v21 row_ror:1 row_mask:0xf bank_mask:0xf bound_ctrl:1
	v_pk_fma_f32 v[16:17], v[8:9], v[96:97], v[16:17]
	v_pk_fma_f32 v[10:11], v[70:71], v[10:11], v[86:87]
	v_mul_f32_e32 v18, 0x3d372713, v14
	v_mul_f32_e32 v19, 0x3d372713, v15
	v_pk_fma_f32 v[10:11], v[78:79], v[20:21], v[10:11]
	v_mul_f32_e32 v18, v14, v18
	v_mul_f32_e32 v19, v15, v19
	v_mul_f32_e32 v20, 0x3d372713, v16
	v_mul_f32_e32 v21, 0x3d372713, v17
	v_fma_f32 v18, v14, v18, v14
	v_fma_f32 v19, v15, v19, v15
	v_mul_f32_e32 v20, v16, v20
	v_mul_f32_e32 v21, v17, v21
	v_mul_f32_e32 v18, 0xc0135761, v18
	v_mul_f32_e32 v19, 0xc0135761, v19
	v_fma_f32 v20, v16, v20, v16
	v_fma_f32 v21, v17, v21, v17
	v_exp_f32_e32 v18, v18
	v_exp_f32_e32 v19, v19
	v_mul_f32_e32 v20, 0xc0135761, v20
	v_mul_f32_e32 v21, 0xc0135761, v21
	v_exp_f32_e32 v20, v20
	v_exp_f32_e32 v21, v21
	v_add_f32_e32 v18, 1.0, v18
	v_add_f32_e32 v19, 1.0, v19
	v_rcp_f32_e32 v18, v18
	v_rcp_f32_e32 v19, v19
	v_add_f32_e32 v20, 1.0, v20
	v_add_f32_e32 v21, 1.0, v21
	v_cndmask_b32_e64 v12, v4, v12, s[8:9]
	v_cndmask_b32_e64 v25, v5, v13, s[6:7]
	v_cndmask_b32_e64 v13, v5, v13, s[8:9]
	v_rcp_f32_e32 v20, v20
	v_rcp_f32_e32 v21, v21
	v_mov_b32_dpp v12, v12 row_ror:2 row_mask:0xf bank_mask:0xf bound_ctrl:1
	v_mov_b32_dpp v13, v13 row_ror:2 row_mask:0xf bank_mask:0xf bound_ctrl:1
	v_mov_b32_dpp v25, v25 row_ror:1 row_mask:0xf bank_mask:0xf bound_ctrl:1
	v_pk_fma_f32 v[12:13], v[72:73], v[12:13], v[88:89]
	v_pk_fma_f32 v[10:11], v[2:3], v[66:67], v[10:11]
	v_pk_fma_f32 v[12:13], v[80:81], v[24:25], v[12:13]
	v_pk_mul_f32 v[14:15], v[14:15], v[18:19]
	v_pk_fma_f32 v[12:13], v[4:5], v[68:69], v[12:13]
	v_pk_mul_f32 v[10:11], v[10:11], v[14:15]
	v_pk_mul_f32 v[14:15], v[16:17], v[20:21]
	v_cvt_pk_bf16_f32 v10, v10, v11
	v_pk_mul_f32 v[12:13], v[12:13], v[14:15]
	s_nop 0
	v_cvt_pk_bf16_f32 v11, v12, v13
	global_store_dwordx2 v[114:115], v[10:11], off offset:8
	s_and_saveexec_b64 s[48:49], s[8:9]
	s_cbranch_execz .LBB0_1150
	v_lshl_add_u64 v[10:11], v[116:117], 2, v[98:99]
	v_add_co_u32_e32 v12, vcc, 0xfffbe000, v10
	s_nop 1
	v_addc_co_u32_e32 v13, vcc, -1, v11, vcc
	global_store_dwordx4 v[12:13], v[6:9], off
	s_nop 1
	v_add_co_u32_e32 v6, vcc, 0xfffc0c00, v10
	s_nop 1
	v_addc_co_u32_e32 v7, vcc, -1, v11, vcc
	global_store_dwordx4 v[6:7], v[2:5], off

; __device__ __forceinline__ unsigned xb_ld(unsigned* p)              { return __hip_atomic_load(p, __ATOMIC_RELAXED, __HIP_MEMORY_SCOPE_AGENT); }
; __device__ __forceinline__ void xcd_barrier_complete(unsigned* bar, unsigned x, unsigned& nloc, unsigned& nx) {
;     const unsigned G = gridDim.x * gridDim.y * gridDim.z;
;     unsigned sum, cnt, mine, sp = 0u;
;     for (;;) {
;         sum = 0u; cnt = 0u; mine = 0u;
; #pragma unroll
;         for (unsigned j = 0; j < 16; ++j) { const unsigned c = xb_ld(&bar[XB_XCNT(j)]); sum += c; cnt += (c > 0u) ? 1u : 0u; mine = (j == x) ? c : mine; }
;         if (sum == G) break;
;         __builtin_amdgcn_s_sleep(1);
;         if ((++sp & 255u) == 0u) { if (xb_ld(&bar[XB_TMO])) break; if (sp > XB_SPIN_CAP) { atomicAdd(&bar[XB_TMO], 1u); break; } }
;     }
;     nloc = mine > 0u ? mine : 1u; nx = cnt > 0u ? cnt : 1u;
; }
.LBB0_1159:
	v_mov_b64_e32 v[12:13], s[40:41]
	s_waitcnt lgkmcnt(0)
	global_load_dword v2, v[12:13], off offset:1024 sc1
	global_load_dword v1, v[12:13], off offset:1280 sc1
	global_load_dword v3, v[12:13], off offset:1536 sc1
	s_or_b64 s[20:21], s[20:21], exec
	s_or_b64 s[18:19], s[18:19], exec
	s_waitcnt vmcnt(0) lgkmcnt(0)
	v_add_u32_e32 v4, v1, v2
	v_add_u32_e32 v5, v4, v3
	global_load_dword v4, v[12:13], off offset:1792 sc1
	s_waitcnt vmcnt(0) lgkmcnt(0)
	v_add_u32_e32 v6, v5, v4
	global_load_dword v5, v[12:13], off offset:2048 sc1
	s_waitcnt vmcnt(0) lgkmcnt(0)
	v_add_u32_e32 v7, v6, v5
	global_load_dword v6, v[12:13], off offset:2304 sc1
	s_waitcnt vmcnt(0) lgkmcnt(0)
	v_add_u32_e32 v8, v7, v6
	global_load_dword v7, v[12:13], off offset:2560 sc1
	s_waitcnt vmcnt(0) lgkmcnt(0)
	v_add_u32_e32 v9, v8, v7
	global_load_dword v8, v[12:13], off offset:2816 sc1
	s_waitcnt vmcnt(0) lgkmcnt(0)
	v_add_u32_e32 v10, v9, v8
	global_load_dword v9, v[12:13], off offset:3072 sc1
	s_waitcnt vmcnt(0) lgkmcnt(0)
	v_add_u32_e32 v11, v10, v9
	global_load_dword v10, v[12:13], off offset:3328 sc1
	s_waitcnt vmcnt(0) lgkmcnt(0)
	v_add_u32_e32 v14, v11, v10
	global_load_dword v11, v[12:13], off offset:3584 sc1
	s_waitcnt vmcnt(0) lgkmcnt(0)
	v_add_u32_e32 v14, v14, v11
	global_load_dword v12, v[12:13], off offset:3840 sc1
	s_waitcnt vmcnt(0) lgkmcnt(0)
	v_add_u32_e32 v16, v14, v12
	v_mov_b64_e32 v[14:15], s[6:7]
	global_load_dword v13, v[14:15], off sc1
	v_mov_b64_e32 v[14:15], s[8:9]
	global_load_dword v14, v[14:15], off sc1
	s_waitcnt vmcnt(0) lgkmcnt(0)
	v_add_u32_e32 v16, v16, v13
	v_add_u32_e32 v18, v16, v14
	v_mov_b64_e32 v[16:17], s[10:11]
	global_load_dword v15, v[16:17], off sc1
	v_mov_b64_e32 v[16:17], s[12:13]
	global_load_dword v16, v[16:17], off sc1
	s_waitcnt vmcnt(0) lgkmcnt(0)
	v_add_u32_e32 v18, v18, v15
	v_add_u32_e32 v17, v18, v16
	v_cmp_ne_u32_e32 vcc, s59, v17
	s_and_saveexec_b64 s[22:23], vcc
	s_cbranch_execz .LBB0_1158
	s_and_b32 s26, s34, 0xff
	s_mov_b64 s[24:25], -1
	s_cmp_eq_u32 s26, 0
	s_mov_b64 s[28:29], -1
	s_mov_b64 s[26:27], -1
	s_sleep 1
	s_cbranch_scc1 .LBB0_1162
	s_and_saveexec_b64 s[30:31], s[28:29]
	s_cbranch_execz .LBB0_1157
	s_branch .LBB0_1165
.LBB0_1162:
	v_mov_b64_e32 v[18:19], s[40:41]
	global_load_dword v17, v[18:19], off offset:512 sc1
	s_mov_b64 s[28:29], 0
	s_waitcnt vmcnt(0) lgkmcnt(0)
	v_cmp_eq_u32_e32 vcc, 0, v17
	s_and_saveexec_b64 s[30:31], vcc
	s_cmp_lt_u32 s34, 0x400001
	s_cselect_b64 s[28:29], -1, 0
	s_xor_b64 s[26:27], exec, -1
	s_and_b64 s[28:29], s[28:29], exec
	s_or_b64 exec, exec, s[30:31]
	s_and_saveexec_b64 s[30:31], s[28:29]
	s_cbranch_execz .LBB0_1157

; __device__ __forceinline__ unsigned xb_ld(unsigned* p)              { return __hip_atomic_load(p, __ATOMIC_RELAXED, __HIP_MEMORY_SCOPE_AGENT); }
; __device__ __forceinline__ unsigned xb_add(unsigned* p, unsigned v) { return __hip_atomic_fetch_add(p, v, __ATOMIC_RELAXED, __HIP_MEMORY_SCOPE_AGENT); }
; #define XB_SPIN(cond, bar) do { unsigned _sp = 0; while (cond) { __builtin_amdgcn_s_sleep(1); \
;     if ((++_sp & 255u) == 0u) { if (xb_ld(&(bar)[XB_TMO])) break; if (_sp > XB_SPIN_CAP) { atomicAdd(&(bar)[XB_TMO], 1u); break; } } } } while (0)
; __device__ __forceinline__ void xcd_barrier(const XcdBarrier& b) {
;     ...
;         unsigned nloc = b.st[0], nx = b.st[1];
;         if (nloc == 0u) { xcd_barrier_complete(bar, b.x, nloc, nx); b.st[0] = nloc; b.st[1] = nx; }
;         const unsigned old = xb_add(&bar[XB_XSUB(b.x)], 1u);
;         const unsigned gen = old / nloc;
;         if (old + 1u == (gen + 1u) * nloc) {
;             __builtin_amdgcn_fence(__ATOMIC_RELEASE, "agent");
;             asm volatile("s_waitcnt vmcnt(0)" ::: "memory");
;             const unsigned og = xb_add(&bar[XB_TOP], 1u);
;             const unsigned tg = og / nx;
;             if (og + 1u == (tg + 1u) * nx) xb_add(&bar[XB_TOPGEN], 1u);
;             else XB_SPIN(xb_ld(&bar[XB_TOPGEN]) == tg, bar);
;             __builtin_amdgcn_fence(__ATOMIC_ACQUIRE, "agent");
;             xb_add(&bar[XB_XGEN(b.x)], 1u);
;             asm volatile("s_waitcnt vmcnt(0)" ::: "memory");
;         } else {
;             XB_SPIN(xb_ld(&bar[XB_XGEN(b.x)]) == gen, bar);
.LBB0_1169:
	s_lshl_b32 s6, s42, 8
	s_add_u32 s27, s40, s6
	s_addc_u32 s26, s41, 0
	v_mov_b32_e32 v1, s27
	v_add_co_u32_e32 v6, vcc, 0x1000, v1
	v_mov_b32_e32 v1, s26
	s_nop 0
	v_addc_co_u32_e32 v7, vcc, 0, v1, vcc
	flat_atomic_add v3, v[6:7], v217 offset:1024 sc0
	v_cvt_f32_u32_e32 v1, v4
	v_sub_u32_e32 v5, 0, v4
	v_rcp_iflag_f32_e32 v1, v1
	s_nop 0
	v_mul_f32_e32 v1, 0x4f7ffffe, v1
	v_cvt_u32_f32_e32 v1, v1
	v_mul_lo_u32 v5, v5, v1
	v_mul_hi_u32 v5, v1, v5
	v_add_u32_e32 v1, v1, v5
	s_waitcnt vmcnt(0) lgkmcnt(0)
	v_mul_hi_u32 v1, v3, v1
	v_mul_lo_u32 v5, v1, v4
	v_sub_u32_e32 v5, v3, v5
	v_cmp_ge_u32_e32 vcc, v5, v4
	v_add_u32_e32 v6, 1, v1
	v_add_u32_e32 v3, 1, v3
	v_cndmask_b32_e32 v1, v1, v6, vcc
	v_sub_u32_e32 v6, v5, v4
	v_cndmask_b32_e32 v5, v5, v6, vcc
	v_cmp_ge_u32_e32 vcc, v5, v4
	v_add_u32_e32 v5, 1, v1
	s_nop 0
	v_cndmask_b32_e32 v1, v1, v5, vcc
	v_mad_u64_u32 v[4:5], s[6:7], v4, v1, v[4:5]
	v_cmp_ne_u32_e32 vcc, v3, v4
	s_and_saveexec_b64 s[6:7], vcc
	s_xor_b64 s[6:7], exec, s[6:7]
	s_cbranch_execz .LBB0_1182
	v_mov_b32_e32 v2, s27
	v_add_co_u32_e32 v2, vcc, 0x2000, v2
	v_mov_b32_e32 v3, s26
	s_nop 0
	v_addc_co_u32_e32 v3, vcc, 0, v3, vcc
	global_load_dword v2, v[2:3], off offset:1024 sc1
	s_add_u32 s10, s27, 0x2400
	s_addc_u32 s11, s26, 0
	s_waitcnt vmcnt(0) lgkmcnt(0)
	v_cmp_eq_u32_e32 vcc, v2, v1
	s_and_saveexec_b64 s[8:9], vcc
	s_cbranch_execz .LBB0_1181
	s_mov_b32 s28, 1
	s_mov_b64 s[12:13], 0
	s_branch .LBB0_1173

.LBB0_1173:
	s_and_b32 s20, s28, 0xff
	s_mov_b64 s[18:19], -1
	s_cmp_lg_u32 s20, 0
	s_mov_b64 s[20:21], -1
	s_sleep 1
	s_cbranch_scc1 .LBB0_1177
	v_mov_b64_e32 v[2:3], s[40:41]
	global_load_dword v2, v[2:3], off offset:512 sc1
	s_mov_b64 s[20:21], 0
	s_mov_b64 s[22:23], -1
	s_waitcnt vmcnt(0) lgkmcnt(0)
	v_cmp_eq_u32_e32 vcc, 0, v2
	s_and_saveexec_b64 s[24:25], vcc
	s_cmp_lt_u32 s28, 0x400001
	s_cselect_b64 s[20:21], -1, 0
	s_xor_b64 s[22:23], exec, -1
	s_and_b64 s[20:21], s[20:21], exec
	s_or_b64 exec, exec, s[24:25]

; __device__ __forceinline__ unsigned xb_ld(unsigned* p)              { return __hip_atomic_load(p, __ATOMIC_RELAXED, __HIP_MEMORY_SCOPE_AGENT); }
; __device__ __forceinline__ unsigned xb_add(unsigned* p, unsigned v) { return __hip_atomic_fetch_add(p, v, __ATOMIC_RELAXED, __HIP_MEMORY_SCOPE_AGENT); }
; #define XB_SPIN(cond, bar) do { unsigned _sp = 0; while (cond) { __builtin_amdgcn_s_sleep(1); \
;     if ((++_sp & 255u) == 0u) { if (xb_ld(&(bar)[XB_TMO])) break; if (_sp > XB_SPIN_CAP) { atomicAdd(&(bar)[XB_TMO], 1u); break; } } } } while (0)
; __device__ __forceinline__ void xcd_barrier(const XcdBarrier& b) {
;     ...
;         if (old + 1u == (gen + 1u) * nloc) {
;             __builtin_amdgcn_fence(__ATOMIC_RELEASE, "agent");
;             asm volatile("s_waitcnt vmcnt(0)" ::: "memory");
;             const unsigned og = xb_add(&bar[XB_TOP], 1u);
;             const unsigned tg = og / nx;
;             if (og + 1u == (tg + 1u) * nx) xb_add(&bar[XB_TOPGEN], 1u);
;             else XB_SPIN(xb_ld(&bar[XB_TOPGEN]) == tg, bar);
.LBB0_1182:
	s_andn2_saveexec_b64 s[6:7], s[6:7]
	s_cbranch_execz .LBB0_1198
	v_mov_b32_e32 v1, s40
	v_add_co_u32_e32 v4, vcc, 0x3000, v1
	v_mov_b32_e32 v1, s41
	buffer_wbl2 sc1
	s_waitcnt vmcnt(0)
	v_addc_co_u32_e32 v5, vcc, 0, v1, vcc
	flat_atomic_add v3, v[4:5], v217 offset:1024 sc0
	v_cvt_f32_u32_e32 v1, v2
	v_sub_u32_e32 v4, 0, v2
	s_mov_b64 s[10:11], -1
	v_rcp_iflag_f32_e32 v1, v1
	s_nop 0
	v_mul_f32_e32 v1, 0x4f7ffffe, v1
	v_cvt_u32_f32_e32 v1, v1
	v_mul_lo_u32 v4, v4, v1
	v_mul_hi_u32 v4, v1, v4
	v_add_u32_e32 v1, v1, v4
	s_waitcnt vmcnt(0) lgkmcnt(0)
	v_mul_hi_u32 v1, v3, v1
	v_mul_lo_u32 v4, v1, v2
	v_sub_u32_e32 v4, v3, v4
	v_cmp_ge_u32_e32 vcc, v4, v2
	v_add_u32_e32 v5, 1, v1
	s_nop 0
	v_cndmask_b32_e32 v1, v1, v5, vcc
	v_sub_u32_e32 v5, v4, v2
	v_cndmask_b32_e32 v4, v4, v5, vcc
	v_cmp_ge_u32_e32 vcc, v4, v2
	v_add_u32_e32 v4, 1, v1
	s_nop 0
	v_cndmask_b32_e32 v1, v1, v4, vcc
	v_add_u32_e32 v4, 1, v3
	v_mad_u64_u32 v[2:3], s[6:7], v2, v1, v[2:3]
	s_add_u32 s6, s40, 0x3500
	s_addc_u32 s7, s41, 0
	v_cmp_ne_u32_e32 vcc, v4, v2
	v_mov_b64_e32 v[2:3], s[6:7]
	s_and_saveexec_b64 s[8:9], vcc
	s_cbranch_execz .LBB0_1195
	v_mov_b64_e32 v[2:3], s[6:7]
	global_load_dword v2, v[2:3], off sc1
	s_mov_b64 s[14:15], 0
	s_waitcnt vmcnt(0) lgkmcnt(0)
	v_cmp_eq_u32_e32 vcc, v2, v1
	s_and_saveexec_b64 s[12:13], vcc
	s_cbranch_execz .LBB0_1194
	s_add_u32 s10, s40, 0x200
	s_addc_u32 s11, s41, 0
	s_mov_b32 s28, 1
	s_branch .LBB0_1187

; __device__ __forceinline__ unsigned xb_ld(unsigned* p)              { return __hip_atomic_load(p, __ATOMIC_RELAXED, __HIP_MEMORY_SCOPE_AGENT); }
; #define XB_SPIN(cond, bar) do { unsigned _sp = 0; while (cond) { __builtin_amdgcn_s_sleep(1); \
;     if ((++_sp & 255u) == 0u) { if (xb_ld(&(bar)[XB_TMO])) break; if (_sp > XB_SPIN_CAP) { atomicAdd(&(bar)[XB_TMO], 1u); break; } } } } while (0)
; __device__ __forceinline__ void xcd_barrier(const XcdBarrier& b) {
;     ...
;             else XB_SPIN(xb_ld(&bar[XB_TOPGEN]) == tg, bar);
.LBB0_1189:
	v_mov_b64_e32 v[2:3], s[10:11]
	global_load_dword v2, v[2:3], off sc1
	s_mov_b64 s[22:23], 0
	s_mov_b64 s[20:21], -1
	s_waitcnt vmcnt(0) lgkmcnt(0)
	v_cmp_eq_u32_e32 vcc, 0, v2
	s_and_saveexec_b64 s[24:25], vcc
	s_cmp_lt_u32 s28, 0x400001
	s_cselect_b64 s[22:23], -1, 0
	s_xor_b64 s[20:21], exec, -1
	s_and_b64 s[22:23], s[22:23], exec
	s_or_b64 exec, exec, s[24:25]
	s_and_saveexec_b64 s[24:25], s[22:23]
	s_cbranch_execz .LBB0_1186
.LBB0_1192:
	v_mov_b64_e32 v[2:3], s[6:7]
	global_load_dword v2, v[2:3], off sc1
	s_add_i32 s28, s28, 1
	s_or_b64 s[20:21], s[20:21], exec
	s_waitcnt vmcnt(0) lgkmcnt(0)
	v_cmp_ne_u32_e32 vcc, v2, v1
	s_orn2_b64 s[18:19], vcc, exec
	s_branch .LBB0_1186

; __device__ __forceinline__ void ffn_fixup(const Params& P, int l, int pm, int tid) {
;     ...
;         if ((blk & 31) != 0) { const float* hp = halo + ((size_t)(blk - 1) * 4 + 2) * DFF2 + ch0;
;             gm2 = *(const f32x4*)hp; vm2 = *(const f32x4*)(hp + DFF); gm1 = *(const f32x4*)(hp + DFF2); vm1 = *(const f32x4*)(hp + DFF2 + DFF); }
;         const float* hc = halo + ((size_t)blk * 4) * DFF2 + ch0;
;         const f32x4 g0 = *(const f32x4*)hc, v0 = *(const f32x4*)(hc + DFF), g1 = *(const f32x4*)(hc + DFF2), v1 = *(const f32x4*)(hc + DFF2 + DFF);
;         const f32x4 wg0 = *(const f32x4*)(cw + ch0), wg1 = *(const f32x4*)(cw + DFF2 + ch0), wg2 = *(const f32x4*)(cw + 2 * DFF2 + ch0), bg = *(const f32x4*)(cb + ch0);
;         const f32x4 wv0 = *(const f32x4*)(cw + DFF + ch0), wv1 = *(const f32x4*)(cw + DFF2 + DFF + ch0), wv2 = *(const f32x4*)(cw + 2 * DFF2 + DFF + ch0), bv = *(const f32x4*)(cb + DFF + ch0);
.LBB0_1212:
	s_or_b64 exec, exec, s[30:31]
	v_mov_b64_e32 v[10:11], s[24:25]
	v_mad_i64_i32 v[10:11], s[30:31], v71, s76, v[10:11]
	v_lshlrev_b64 v[54:55], 2, v[66:67]
	v_lshl_add_u64 v[14:15], v[10:11], 0, v[54:55]
	v_lshl_add_u64 v[38:39], s[38:39], 0, v[54:55]
	v_add_co_u32_e32 v10, vcc, s77, v14
	v_lshl_add_u64 v[26:27], s[2:3], 0, v[54:55]
	global_load_dwordx4 v[50:53], v[38:39], off
	v_lshl_add_u64 v[38:39], s[14:15], 0, v[54:55]
	v_addc_co_u32_e32 v11, vcc, 0, v15, vcc
	global_load_dwordx4 v[30:33], v[26:27], off
	v_lshl_add_u64 v[26:27], s[10:11], 0, v[54:55]
	global_load_dwordx4 v[42:45], v[38:39], off
	v_lshl_add_u64 v[38:39], s[16:17], 0, v[54:55]
	v_add_co_u32_e32 v16, vcc, s79, v14
	global_load_dwordx4 v[34:37], v[26:27], off
	v_lshl_add_u64 v[26:27], s[12:13], 0, v[54:55]
	global_load_dwordx4 v[46:49], v[38:39], off
	v_lshl_add_u64 v[38:39], s[18:19], 0, v[54:55]
	v_lshl_add_u64 v[54:55], s[20:21], 0, v[54:55]
	global_load_dwordx4 v[18:21], v[14:15], off
	v_addc_co_u32_e32 v17, vcc, 0, v15, vcc
	global_load_dwordx4 v[54:57], v[54:55], off
	v_lshlrev_b32_e32 v71, 6, v71
	global_load_dwordx4 v[22:25], v[16:17], off offset:2048
	s_movk_i32 s42, 0x1600
	global_load_dwordx4 v[26:29], v[26:27], off
	v_add_u32_e32 v69, 0x800, v69
	global_load_dwordx4 v[10:13], v[10:11], off offset:3072
	v_add_co_u32_e32 v14, vcc, s73, v14
	global_load_dwordx4 v[38:41], v[38:39], off
	s_nop 0
	v_addc_co_u32_e32 v15, vcc, 0, v15, vcc
	global_load_dwordx4 v[14:17], v[14:15], off offset:1024
	s_waitcnt vmcnt(0) lgkmcnt(0)
; __device__ __forceinline__ unsigned pk2(float lo, float hi) { return f2bf(lo) | (f2bf(hi) << 16); }
; __device__ __forceinline__ float gelu_tanh(float x) { const float t = x + 0.044715f * x * x * x; return x * fast_rcp(1.0f + fast_exp2(-2.3022082f * t)); }
; __device__ __forceinline__ void ffn_fixup(const Params& P, int l, int pm, int tid) {
;     ...
;     for (int it = tid; it < 4 * (DFF / 4); it += 512) {
;         const int bi = it / (DFF / 4), ch0 = 4 * (it % (DFF / 4)); const int blk = pm * 4 + bi;
;         const f32x4 z = {0.f, 0.f, 0.f, 0.f};
;         f32x4 gm2 = z, gm1 = z, vm2 = z, vm1 = z;
;         if ((blk & 31) != 0) { const float* hp = halo + ((size_t)(blk - 1) * 4 + 2) * DFF2 + ch0;
;             gm2 = *(const f32x4*)hp; vm2 = *(const f32x4*)(hp + DFF); gm1 = *(const f32x4*)(hp + DFF2); vm1 = *(const f32x4*)(hp + DFF2 + DFF); }
;     ...
;         { const f32x4 cg = bg + wg0 * gm2 + wg1 * gm1 + wg2 * g0, cv = bv + wv0 * vm2 + wv1 * vm1 + wv2 * v0;
;           u32x2 w; w.x = pk2(gelu_tanh(cg[0]) * cv[0], gelu_tanh(cg[1]) * cv[1]); w.y = pk2(gelu_tanh(cg[2]) * cv[2], gelu_tanh(cg[3]) * cv[3]);
;           *(u32x2*)(act + (size_t)(blk * 64) * DFF + ch0) = w; }
;         { const f32x4 cg = bg + wg0 * gm1 + wg1 * g0 + wg2 * g1, cv = bv + wv0 * vm1 + wv1 * v0 + wv2 * v1;
;           u32x2 w; w.x = pk2(gelu_tanh(cg[0]) * cv[0], gelu_tanh(cg[1]) * cv[1]); w.y = pk2(gelu_tanh(cg[2]) * cv[2], gelu_tanh(cg[3]) * cv[3]);
;           *(u32x2*)(act + (size_t)(blk * 64 + 1) * DFF + ch0) = w; }
	v_pk_fma_f32 v[62:63], v[62:63], v[30:31], v[50:51]
	v_pk_fma_f32 v[64:65], v[64:65], v[32:33], v[52:53]
	v_pk_fma_f32 v[62:63], v[6:7], v[34:35], v[62:63]
	v_pk_fma_f32 v[6:7], v[6:7], v[30:31], v[50:51]
	v_pk_fma_f32 v[64:65], v[8:9], v[36:37], v[64:65]
	v_pk_fma_f32 v[8:9], v[8:9], v[32:33], v[52:53]
	v_pk_fma_f32 v[6:7], v[18:19], v[34:35], v[6:7]
	v_pk_fma_f32 v[8:9], v[20:21], v[36:37], v[8:9]
	v_pk_fma_f32 v[58:59], v[58:59], v[42:43], v[54:55]
	s_nop 0
	v_pk_fma_f32 v[58:59], v[2:3], v[46:47], v[58:59]
	v_pk_fma_f32 v[2:3], v[2:3], v[42:43], v[54:55]
	v_pk_fma_f32 v[60:61], v[60:61], v[44:45], v[56:57]
	v_pk_fma_f32 v[62:63], v[18:19], v[26:27], v[62:63]
	v_pk_fma_f32 v[6:7], v[22:23], v[26:27], v[6:7]
	v_mul_f32_e32 v73, 0x3d372713, v63
	v_pk_fma_f32 v[2:3], v[10:11], v[46:47], v[2:3]
	v_mul_f32_e32 v73, v63, v73
	v_pk_fma_f32 v[58:59], v[10:11], v[38:39], v[58:59]
	v_mul_f32_e32 v11, 0x3d372713, v7
	v_mul_f32_e32 v11, v7, v11
	v_fma_f32 v73, v63, v73, v63
	v_fma_f32 v11, v7, v11, v7
	v_mul_f32_e32 v73, 0xc0135761, v73
	v_mul_f32_e32 v11, 0xc0135761, v11
	v_exp_f32_e32 v73, v73
	v_exp_f32_e32 v11, v11
	v_pk_fma_f32 v[64:65], v[20:21], v[28:29], v[64:65]
	v_pk_fma_f32 v[60:61], v[4:5], v[48:49], v[60:61]
	v_add_f32_e32 v73, 1.0, v73
	v_pk_fma_f32 v[8:9], v[24:25], v[28:29], v[8:9]
	v_pk_fma_f32 v[4:5], v[4:5], v[44:45], v[56:57]
	v_add_f32_e32 v11, 1.0, v11
	v_pk_fma_f32 v[60:61], v[12:13], v[40:41], v[60:61]
	v_mul_f32_e32 v72, 0x3d372713, v62
	v_rcp_f32_e32 v74, v73
	v_mul_f32_e32 v73, 0x3d372713, v64
	v_mul_f32_e32 v75, 0x3d372713, v65
	v_pk_fma_f32 v[4:5], v[12:13], v[48:49], v[4:5]
	v_mul_f32_e32 v10, 0x3d372713, v6
	v_rcp_f32_e32 v12, v11
	v_mul_f32_e32 v11, 0x3d372713, v8
	v_mul_f32_e32 v13, 0x3d372713, v9
	v_mul_f32_e32 v72, v62, v72
	v_mul_f32_e32 v73, v64, v73
	v_mul_f32_e32 v75, v65, v75
	v_mul_f32_e32 v10, v6, v10
	v_mul_f32_e32 v11, v8, v11
	v_mul_f32_e32 v13, v9, v13
	v_fma_f32 v72, v62, v72, v62
	v_fma_f32 v73, v64, v73, v64
	v_fma_f32 v75, v65, v75, v65
	v_fma_f32 v10, v6, v10, v6
	v_fma_f32 v11, v8, v11, v8
	v_fma_f32 v13, v9, v13, v9
	v_mul_f32_e32 v72, 0xc0135761, v72
	v_mul_f32_e32 v73, 0xc0135761, v73
	v_mul_f32_e32 v75, 0xc0135761, v75
	v_mul_f32_e32 v10, 0xc0135761, v10
	v_mul_f32_e32 v11, 0xc0135761, v11
	v_mul_f32_e32 v13, 0xc0135761, v13
	v_exp_f32_e32 v72, v72
	v_exp_f32_e32 v73, v73
	v_exp_f32_e32 v75, v75
	v_exp_f32_e32 v10, v10
	v_exp_f32_e32 v11, v11
	v_exp_f32_e32 v13, v13
	v_add_f32_e32 v72, 1.0, v72
	v_add_f32_e32 v73, 1.0, v73
	v_add_f32_e32 v75, 1.0, v75
	v_add_f32_e32 v10, 1.0, v10
	v_add_f32_e32 v11, 1.0, v11
	v_add_f32_e32 v13, 1.0, v13
	v_rcp_f32_e32 v72, v72
	v_rcp_f32_e32 v73, v73
	v_rcp_f32_e32 v75, v75
	v_rcp_f32_e32 v10, v10
	v_rcp_f32_e32 v11, v11
	v_rcp_f32_e32 v13, v13
	v_mov_b32_e32 v76, v62
	v_mov_b32_e32 v77, v64
	v_mov_b32_e32 v64, v63
	v_pk_fma_f32 v[4:5], v[16:17], v[40:41], v[4:5]
	v_pk_fma_f32 v[2:3], v[14:15], v[38:39], v[2:3]
	v_mov_b32_e32 v14, v6
	v_mov_b32_e32 v15, v8
	v_mov_b32_e32 v8, v7
	v_pk_mul_f32 v[72:73], v[76:77], v[72:73]
	v_mov_b32_e32 v77, v60
	v_pk_mul_f32 v[62:63], v[64:65], v[74:75]
	v_mov_b32_e32 v60, v59
	v_pk_mul_f32 v[10:11], v[14:15], v[10:11]
	v_mov_b32_e32 v15, v4
	v_pk_mul_f32 v[6:7], v[8:9], v[12:13]
	v_mov_b32_e32 v4, v3
	v_mov_b32_e32 v76, v58
	v_pk_mul_f32 v[58:59], v[60:61], v[62:63]
	v_mov_b32_e32 v14, v2
	v_pk_mul_f32 v[2:3], v[4:5], v[6:7]
	v_pk_mul_f32 v[72:73], v[76:77], v[72:73]
	v_and_b32_sdwa v62, v59, v217 dst_sel:DWORD dst_unused:UNUSED_PAD src0_sel:WORD_1 src1_sel:DWORD
	v_and_b32_sdwa v63, v58, v217 dst_sel:DWORD dst_unused:UNUSED_PAD src0_sel:WORD_1 src1_sel:DWORD
	v_pk_mul_f32 v[10:11], v[14:15], v[10:11]
	v_and_b32_sdwa v6, v3, v217 dst_sel:DWORD dst_unused:UNUSED_PAD src0_sel:WORD_1 src1_sel:DWORD
	v_and_b32_sdwa v60, v73, v217 dst_sel:DWORD dst_unused:UNUSED_PAD src0_sel:WORD_1 src1_sel:DWORD
	v_and_b32_sdwa v61, v72, v217 dst_sel:DWORD dst_unused:UNUSED_PAD src0_sel:WORD_1 src1_sel:DWORD
	v_add3_u32 v59, v59, v62, s60
	v_add3_u32 v58, v58, v63, s60
	v_and_b32_sdwa v4, v11, v217 dst_sel:DWORD dst_unused:UNUSED_PAD src0_sel:WORD_1 src1_sel:DWORD
	v_and_b32_sdwa v7, v2, v217 dst_sel:DWORD dst_unused:UNUSED_PAD src0_sel:WORD_1 src1_sel:DWORD
	v_add3_u32 v3, v3, v6, s60
	v_add3_u32 v61, v72, v61, s60
	v_add3_u32 v60, v73, v60, s60
	v_and_b32_e32 v59, 0xffff0000, v59
	v_and_b32_e32 v58, 0xffff0000, v58
	v_and_b32_sdwa v5, v10, v217 dst_sel:DWORD dst_unused:UNUSED_PAD src0_sel:WORD_1 src1_sel:DWORD
	v_add3_u32 v4, v11, v4, s60
	v_add3_u32 v2, v2, v7, s60
	v_and_b32_e32 v3, 0xffff0000, v3
	v_or_b32_sdwa v59, v59, v60 dst_sel:DWORD dst_unused:UNUSED_PAD src0_sel:DWORD src1_sel:WORD_1
	v_or_b32_sdwa v58, v58, v61 dst_sel:DWORD dst_unused:UNUSED_PAD src0_sel:DWORD src1_sel:WORD_1
	v_mov_b64_e32 v[60:61], s[26:27]
	v_add3_u32 v5, v10, v5, s60
	v_and_b32_e32 v2, 0xffff0000, v2
	v_or_b32_sdwa v3, v3, v4 dst_sel:DWORD dst_unused:UNUSED_PAD src0_sel:DWORD src1_sel:WORD_1
	v_or_b32_e32 v4, 1, v71
	v_mad_i64_i32 v[64:65], s[30:31], v71, s42, v[60:61]
	v_lshlrev_b64 v[62:63], 1, v[66:67]
	v_or_b32_sdwa v2, v2, v5 dst_sel:DWORD dst_unused:UNUSED_PAD src0_sel:DWORD src1_sel:WORD_1
	v_mad_i64_i32 v[4:5], s[30:31], v4, s42, v[60:61]
	v_lshl_add_u64 v[4:5], v[4:5], 0, v[62:63]
	s_movk_i32 s30, 0x8ff
	global_store_dwordx2 v[4:5], v[2:3], off
	v_add_u32_e32 v2, 0x200, v70
	v_cmp_lt_i32_e32 vcc, s30, v70
	v_lshl_add_u64 v[64:65], v[64:65], 0, v[62:63]
	s_or_b64 s[28:29], vcc, s[28:29]
	v_mov_b32_e32 v70, v2
	global_store_dwordx2 v[64:65], v[58:59], off
	s_andn2_b64 exec, exec, s[28:29]
	s_cbranch_execz .LBB0_1201
.LBB0_1213:
	s_mov_b32 s30, 0x2e8ba2e9
	v_mul_hi_i32 v2, v70, s30
	v_lshrrev_b32_e32 v3, 31, v2
	v_ashrrev_i32_e32 v2, 7, v2
	v_add_u32_e32 v2, v2, v3
	v_mul_i32_i24_e32 v3, 0x2c0, v2
	v_lshlrev_b32_e32 v3, 2, v3
	v_add_u32_e32 v71, s41, v2
	v_sub_u32_e32 v66, v69, v3
	v_and_b32_e32 v2, 31, v71
	v_cmp_ne_u32_e32 vcc, 0, v2
	v_ashrrev_i32_e32 v67, 31, v66
	s_and_saveexec_b64 s[30:31], vcc
	s_xor_b64 s[30:31], exec, s[30:31]
	s_cbranch_execz .LBB0_1215
	v_add_u32_e32 v4, -1, v71
	v_mov_b64_e32 v[2:3], s[24:25]
	v_mad_i64_i32 v[2:3], s[42:43], v4, s76, v[2:3]
	v_lshl_add_u64 v[2:3], v[66:67], 2, v[2:3]
	v_add_co_u32_e32 v4, vcc, 0xb000, v2
	s_mov_b32 s42, 0x10000
	s_nop 0
	v_addc_co_u32_e32 v5, vcc, 0, v3, vcc
	v_add_co_u32_e32 v6, vcc, 0xd000, v2
	s_nop 1
	v_addc_co_u32_e32 v7, vcc, 0, v3, vcc
	global_load_dwordx4 v[62:65], v[4:5], off
	global_load_dwordx4 v[58:61], v[6:7], off offset:3072
	v_add_co_u32_e32 v4, vcc, s42, v2
	s_mov_b32 s42, 0x13000
	s_nop 0
	v_addc_co_u32_e32 v5, vcc, 0, v3, vcc
	v_add_co_u32_e32 v2, vcc, s42, v2
	s_nop 1
	v_addc_co_u32_e32 v3, vcc, 0, v3, vcc
	global_load_dwordx4 v[6:9], v[4:5], off offset:2048
	s_nop 0
	global_load_dwordx4 v[2:5], v[2:3], off offset:1024

.LBB0_1241:
	v_lshl_add_u32 v144, s42, 8, v1
	v_lshl_or_b32 v142, s43, 8, v149
	v_ashrrev_i32_e32 v145, 31, v144
	v_ashrrev_i32_e32 v143, 31, v142
	v_lshlrev_b64 v[146:147], 12, v[144:145]
	v_lshl_add_u64 v[152:153], s[8:9], 0, v[146:147]
	v_lshlrev_b64 v[146:147], 2, v[142:143]
	v_lshl_add_u64 v[142:143], v[152:153], 0, v[146:147]
	global_load_dwordx4 v[152:155], v[142:143], off
	global_load_dwordx4 v[156:159], v[142:143], off offset:16
	s_mov_b64 s[14:15], 0x80000
	s_waitcnt vmcnt(0) lgkmcnt(0)
	v_pk_add_f32 v[128:129], v[128:129], v[154:155]
	v_pk_add_f32 v[126:127], v[126:127], v[152:153]
	v_pk_add_f32 v[124:125], v[124:125], v[158:159]
	v_pk_add_f32 v[122:123], v[122:123], v[156:157]
	global_store_dwordx4 v[142:143], v[126:129], off
	global_store_dwordx4 v[142:143], v[122:125], off offset:16
	global_load_dwordx4 v[122:125], v[142:143], off offset:512
	s_nop 0
	global_load_dwordx4 v[126:129], v[142:143], off offset:528
	s_waitcnt vmcnt(0) lgkmcnt(0)
	v_pk_add_f32 v[120:121], v[120:121], v[124:125]
	v_pk_add_f32 v[116:117], v[116:117], v[128:129]
	v_pk_add_f32 v[114:115], v[114:115], v[126:127]
	global_store_dwordx4 v[142:143], v[114:117], off offset:528
	v_pk_add_f32 v[118:119], v[118:119], v[122:123]
	global_store_dwordx4 v[142:143], v[118:121], off offset:512
	v_or_b32_e32 v114, 16, v144
	v_ashrrev_i32_e32 v115, 31, v114
	v_lshlrev_b64 v[114:115], 12, v[114:115]
	v_lshl_add_u64 v[114:115], s[8:9], 0, v[114:115]
	v_lshl_add_u64 v[122:123], v[114:115], 0, v[146:147]
	global_load_dwordx4 v[114:117], v[122:123], off
	global_load_dwordx4 v[118:121], v[122:123], off offset:16
	s_waitcnt vmcnt(0) lgkmcnt(0)
	v_pk_add_f32 v[112:113], v[112:113], v[116:117]
	v_pk_add_f32 v[110:111], v[110:111], v[114:115]
	v_pk_add_f32 v[108:109], v[108:109], v[120:121]
	v_pk_add_f32 v[106:107], v[106:107], v[118:119]
	global_store_dwordx4 v[122:123], v[110:113], off
	global_store_dwordx4 v[122:123], v[106:109], off offset:16
	global_load_dwordx4 v[106:109], v[122:123], off offset:512
	s_nop 0
	global_load_dwordx4 v[110:113], v[122:123], off offset:528
	s_waitcnt vmcnt(0) lgkmcnt(0)
	v_pk_add_f32 v[104:105], v[104:105], v[108:109]
	v_pk_add_f32 v[100:101], v[100:101], v[112:113]
	v_pk_add_f32 v[98:99], v[98:99], v[110:111]
	global_store_dwordx4 v[122:123], v[98:101], off offset:528
	v_pk_add_f32 v[102:103], v[102:103], v[106:107]
	global_store_dwordx4 v[122:123], v[102:105], off offset:512
	v_or_b32_e32 v98, 32, v144
	v_ashrrev_i32_e32 v99, 31, v98
	v_lshlrev_b64 v[98:99], 12, v[98:99]
	v_lshl_add_u64 v[98:99], s[8:9], 0, v[98:99]
	v_lshl_add_u64 v[106:107], v[98:99], 0, v[146:147]
	global_load_dwordx4 v[98:101], v[106:107], off
	global_load_dwordx4 v[102:105], v[106:107], off offset:16
	s_waitcnt vmcnt(0) lgkmcnt(0)
	v_pk_add_f32 v[96:97], v[96:97], v[100:101]
	v_pk_add_f32 v[94:95], v[94:95], v[98:99]
	v_pk_add_f32 v[92:93], v[92:93], v[104:105]
	v_pk_add_f32 v[90:91], v[90:91], v[102:103]
	global_store_dwordx4 v[106:107], v[94:97], off
	global_store_dwordx4 v[106:107], v[90:93], off offset:16
	global_load_dwordx4 v[90:93], v[106:107], off offset:512
	s_nop 0
	global_load_dwordx4 v[94:97], v[106:107], off offset:528
	s_waitcnt vmcnt(0) lgkmcnt(0)
	v_pk_add_f32 v[88:89], v[88:89], v[92:93]
	v_pk_add_f32 v[84:85], v[84:85], v[96:97]
	v_pk_add_f32 v[82:83], v[82:83], v[94:95]
	global_store_dwordx4 v[106:107], v[82:85], off offset:528
	v_pk_add_f32 v[86:87], v[86:87], v[90:91]
	global_store_dwordx4 v[106:107], v[86:89], off offset:512
	v_or_b32_e32 v82, 48, v144
	v_ashrrev_i32_e32 v83, 31, v82
	v_lshlrev_b64 v[82:83], 12, v[82:83]
	v_lshl_add_u64 v[82:83], s[8:9], 0, v[82:83]
	v_lshl_add_u64 v[90:91], v[82:83], 0, v[146:147]
	global_load_dwordx4 v[82:85], v[90:91], off
	global_load_dwordx4 v[86:89], v[90:91], off offset:16
	s_waitcnt vmcnt(0) lgkmcnt(0)
	v_pk_add_f32 v[80:81], v[80:81], v[84:85]
	v_pk_add_f32 v[78:79], v[78:79], v[82:83]
	v_pk_add_f32 v[76:77], v[76:77], v[88:89]
	v_pk_add_f32 v[74:75], v[74:75], v[86:87]
	global_store_dwordx4 v[90:91], v[78:81], off
	global_store_dwordx4 v[90:91], v[74:77], off offset:16
	global_load_dwordx4 v[74:77], v[90:91], off offset:512
	s_nop 0
	global_load_dwordx4 v[78:81], v[90:91], off offset:528
	s_waitcnt vmcnt(0) lgkmcnt(0)
; #define PG8_BAR __builtin_amdgcn_s_barrier()
; #define PG8_BAR __builtin_amdgcn_s_barrier()
; template <class Epi, class Sched>
; __device__ __forceinline__ void gemm_phase(LAS unsigned char* lds, const Gemm g, const Sched& S, const Epi& E) {
;     ...
;         cur = nxt; cA = nA; cB = nB; ++ui;
;         if (wr == 1) PG8_BAR;
	v_pk_add_f32 v[72:73], v[72:73], v[76:77]
	v_pk_add_f32 v[70:71], v[70:71], v[74:75]
	v_pk_add_f32 v[68:69], v[68:69], v[80:81]
	v_pk_add_f32 v[66:67], v[66:67], v[78:79]
	v_lshl_add_u64 v[74:75], v[142:143], 0, s[14:15]
	s_mov_b32 s14, 0x80000
	global_store_dwordx4 v[90:91], v[70:73], off offset:512
	global_store_dwordx4 v[90:91], v[66:69], off offset:528
	v_add_co_u32_e32 v76, vcc, s14, v142
	s_mov_b64 s[14:15], 0x90000
	s_nop 0
	v_addc_co_u32_e32 v77, vcc, 0, v143, vcc
	global_load_dwordx4 v[66:69], v[76:77], off
	global_load_dwordx4 v[70:73], v[74:75], off offset:16
	s_waitcnt vmcnt(0) lgkmcnt(0)
	v_pk_add_f32 v[64:65], v[64:65], v[68:69]
	v_pk_add_f32 v[62:63], v[62:63], v[66:67]
	v_pk_add_f32 v[60:61], v[60:61], v[72:73]
	v_pk_add_f32 v[58:59], v[58:59], v[70:71]
	global_store_dwordx4 v[76:77], v[62:65], off
	global_store_dwordx4 v[74:75], v[58:61], off offset:16
	global_load_dwordx4 v[58:61], v[74:75], off offset:512
	s_nop 0
	global_load_dwordx4 v[62:65], v[74:75], off offset:528
	s_waitcnt vmcnt(0) lgkmcnt(0)
	v_pk_add_f32 v[54:55], v[54:55], v[58:59]
	v_lshl_add_u64 v[58:59], v[142:143], 0, s[14:15]
	s_mov_b32 s14, 0x90000
	v_pk_add_f32 v[56:57], v[56:57], v[60:61]
	v_pk_add_f32 v[52:53], v[52:53], v[64:65]
	v_pk_add_f32 v[50:51], v[50:51], v[62:63]
	v_add_co_u32_e32 v60, vcc, s14, v142
	global_store_dwordx4 v[74:75], v[54:57], off offset:512
	global_store_dwordx4 v[74:75], v[50:53], off offset:528
	v_addc_co_u32_e32 v61, vcc, 0, v143, vcc
	global_load_dwordx4 v[50:53], v[60:61], off
	global_load_dwordx4 v[54:57], v[58:59], off offset:16
	s_mov_b64 s[14:15], 0xa0000
	s_waitcnt vmcnt(0) lgkmcnt(0)
	v_pk_add_f32 v[48:49], v[48:49], v[52:53]
	v_pk_add_f32 v[46:47], v[46:47], v[50:51]
	v_pk_add_f32 v[44:45], v[44:45], v[56:57]
	v_pk_add_f32 v[42:43], v[42:43], v[54:55]
	global_store_dwordx4 v[60:61], v[46:49], off
	global_store_dwordx4 v[58:59], v[42:45], off offset:16
	global_load_dwordx4 v[42:45], v[58:59], off offset:512
	s_nop 0
	global_load_dwordx4 v[46:49], v[58:59], off offset:528
	s_waitcnt vmcnt(0) lgkmcnt(0)
	v_pk_add_f32 v[38:39], v[38:39], v[42:43]
	v_lshl_add_u64 v[42:43], v[142:143], 0, s[14:15]
	s_mov_b32 s14, 0xa0000
	v_pk_add_f32 v[40:41], v[40:41], v[44:45]
	v_pk_add_f32 v[36:37], v[36:37], v[48:49]
	v_pk_add_f32 v[34:35], v[34:35], v[46:47]
	v_add_co_u32_e32 v44, vcc, s14, v142
	global_store_dwordx4 v[58:59], v[38:41], off offset:512
	global_store_dwordx4 v[58:59], v[34:37], off offset:528
	v_addc_co_u32_e32 v45, vcc, 0, v143, vcc
	global_load_dwordx4 v[34:37], v[44:45], off
	global_load_dwordx4 v[38:41], v[42:43], off offset:16
	s_mov_b64 s[14:15], 0xb0000
	s_waitcnt vmcnt(0) lgkmcnt(0)
	v_pk_add_f32 v[32:33], v[32:33], v[36:37]
	v_pk_add_f32 v[30:31], v[30:31], v[34:35]
	v_pk_add_f32 v[28:29], v[28:29], v[40:41]
	v_pk_add_f32 v[26:27], v[26:27], v[38:39]
	global_store_dwordx4 v[44:45], v[30:33], off
	global_store_dwordx4 v[42:43], v[26:29], off offset:16
	global_load_dwordx4 v[26:29], v[42:43], off offset:512
	s_nop 0
	global_load_dwordx4 v[30:33], v[42:43], off offset:528
	s_waitcnt vmcnt(0) lgkmcnt(0)
	v_pk_add_f32 v[24:25], v[24:25], v[28:29]
	v_pk_add_f32 v[20:21], v[20:21], v[32:33]
	v_pk_add_f32 v[18:19], v[18:19], v[30:31]
	global_store_dwordx4 v[42:43], v[18:21], off offset:528
	v_pk_add_f32 v[22:23], v[22:23], v[26:27]
	global_store_dwordx4 v[42:43], v[22:25], off offset:512
	v_lshl_add_u64 v[18:19], v[142:143], 0, s[14:15]
	s_mov_b32 s14, 0xb0000
	v_add_co_u32_e32 v28, vcc, s14, v142
	s_mov_b64 s[14:15], -1
	s_nop 0
	v_addc_co_u32_e32 v29, vcc, 0, v143, vcc
	global_load_dwordx4 v[20:23], v[28:29], off
	global_load_dwordx4 v[24:27], v[18:19], off offset:16
	s_and_b64 vcc, exec, s[4:5]
	s_waitcnt vmcnt(0) lgkmcnt(0)
	v_pk_add_f32 v[16:17], v[16:17], v[22:23]
	v_pk_add_f32 v[14:15], v[14:15], v[20:21]
	v_pk_add_f32 v[12:13], v[12:13], v[26:27]
	v_pk_add_f32 v[10:11], v[10:11], v[24:25]
	global_store_dwordx4 v[28:29], v[14:17], off
	global_store_dwordx4 v[18:19], v[10:13], off offset:16
	global_load_dwordx4 v[10:13], v[18:19], off offset:512
	s_nop 0
	global_load_dwordx4 v[14:17], v[18:19], off offset:528
	s_waitcnt vmcnt(0) lgkmcnt(0)
	v_pk_add_f32 v[8:9], v[8:9], v[12:13]
	v_pk_add_f32 v[6:7], v[6:7], v[10:11]
	v_pk_add_f32 v[4:5], v[4:5], v[16:17]
	v_pk_add_f32 v[2:3], v[2:3], v[14:15]
	global_store_dwordx4 v[18:19], v[6:9], off offset:512
	global_store_dwordx4 v[18:19], v[2:5], off offset:528
	s_cbranch_vccnz .LBB0_1226
	s_andn2_b64 vcc, exec, s[2:3]
	s_cbranch_vccnz .LBB0_1225
	s_barrier
	s_branch .LBB0_1225

; __device__ __forceinline__ unsigned xb_ld(unsigned* p)              { return __hip_atomic_load(p, __ATOMIC_RELAXED, __HIP_MEMORY_SCOPE_AGENT); }
; __device__ __forceinline__ void xcd_barrier_complete(unsigned* bar, unsigned x, unsigned& nloc, unsigned& nx) {
;     const unsigned G = gridDim.x * gridDim.y * gridDim.z;
;     unsigned sum, cnt, mine, sp = 0u;
;     for (;;) {
;         sum = 0u; cnt = 0u; mine = 0u;
; #pragma unroll
;         for (unsigned j = 0; j < 16; ++j) { const unsigned c = xb_ld(&bar[XB_XCNT(j)]); sum += c; cnt += (c > 0u) ? 1u : 0u; mine = (j == x) ? c : mine; }
;         if (sum == G) break;
;         __builtin_amdgcn_s_sleep(1);
;         if ((++sp & 255u) == 0u) { if (xb_ld(&bar[XB_TMO])) break; if (sp > XB_SPIN_CAP) { atomicAdd(&bar[XB_TMO], 1u); break; } }
;     }
;     nloc = mine > 0u ? mine : 1u; nx = cnt > 0u ? cnt : 1u;
; }
.LBB0_1250:
	v_mov_b64_e32 v[12:13], s[36:37]
	s_waitcnt lgkmcnt(0)
	global_load_dword v2, v[12:13], off offset:1024 sc1
	global_load_dword v1, v[12:13], off offset:1280 sc1
	global_load_dword v3, v[12:13], off offset:1536 sc1
	s_or_b64 s[18:19], s[18:19], exec
	s_or_b64 s[16:17], s[16:17], exec
	s_waitcnt vmcnt(0) lgkmcnt(0)
	v_add_u32_e32 v4, v1, v2
	v_add_u32_e32 v5, v4, v3
	global_load_dword v4, v[12:13], off offset:1792 sc1
	s_waitcnt vmcnt(0) lgkmcnt(0)
	v_add_u32_e32 v6, v5, v4
	global_load_dword v5, v[12:13], off offset:2048 sc1
	s_waitcnt vmcnt(0) lgkmcnt(0)
	v_add_u32_e32 v7, v6, v5
	global_load_dword v6, v[12:13], off offset:2304 sc1
	s_waitcnt vmcnt(0) lgkmcnt(0)
	v_add_u32_e32 v8, v7, v6
	global_load_dword v7, v[12:13], off offset:2560 sc1
	s_waitcnt vmcnt(0) lgkmcnt(0)
	v_add_u32_e32 v9, v8, v7
	global_load_dword v8, v[12:13], off offset:2816 sc1
	s_waitcnt vmcnt(0) lgkmcnt(0)
	v_add_u32_e32 v10, v9, v8
	global_load_dword v9, v[12:13], off offset:3072 sc1
	s_waitcnt vmcnt(0) lgkmcnt(0)
	v_add_u32_e32 v11, v10, v9
	global_load_dword v10, v[12:13], off offset:3328 sc1
	s_waitcnt vmcnt(0) lgkmcnt(0)
	v_add_u32_e32 v14, v11, v10
	global_load_dword v11, v[12:13], off offset:3584 sc1
	s_waitcnt vmcnt(0) lgkmcnt(0)
	v_add_u32_e32 v14, v14, v11
	global_load_dword v12, v[12:13], off offset:3840 sc1
	s_waitcnt vmcnt(0) lgkmcnt(0)
	v_add_u32_e32 v16, v14, v12
	v_mov_b64_e32 v[14:15], s[4:5]
	global_load_dword v13, v[14:15], off sc1
	v_mov_b64_e32 v[14:15], s[6:7]
	global_load_dword v14, v[14:15], off sc1
	s_waitcnt vmcnt(0) lgkmcnt(0)
	v_add_u32_e32 v16, v16, v13
	v_add_u32_e32 v18, v16, v14
	v_mov_b64_e32 v[16:17], s[8:9]
	global_load_dword v15, v[16:17], off sc1
	v_mov_b64_e32 v[16:17], s[10:11]
	global_load_dword v16, v[16:17], off sc1
	s_waitcnt vmcnt(0) lgkmcnt(0)
	v_add_u32_e32 v18, v18, v15
	v_add_u32_e32 v17, v18, v16
	v_cmp_ne_u32_e32 vcc, s59, v17
	s_and_saveexec_b64 s[20:21], vcc
	s_cbranch_execz .LBB0_1249
	s_and_b32 s24, s30, 0xff
	s_mov_b64 s[22:23], -1
	s_cmp_eq_u32 s24, 0
	s_mov_b64 s[26:27], -1
	s_mov_b64 s[24:25], -1
	s_sleep 1
	s_cbranch_scc1 .LBB0_1253
	s_and_saveexec_b64 s[28:29], s[26:27]
	s_cbranch_execz .LBB0_1248
	s_branch .LBB0_1256
.LBB0_1253:
	v_mov_b64_e32 v[18:19], s[36:37]
	global_load_dword v17, v[18:19], off offset:512 sc1
	s_mov_b64 s[26:27], 0
	s_waitcnt vmcnt(0) lgkmcnt(0)
	v_cmp_eq_u32_e32 vcc, 0, v17
	s_and_saveexec_b64 s[28:29], vcc
	s_cmp_lt_u32 s30, 0x400001
	s_cselect_b64 s[26:27], -1, 0
	s_xor_b64 s[24:25], exec, -1
	s_and_b64 s[26:27], s[26:27], exec
	s_or_b64 exec, exec, s[28:29]
	s_and_saveexec_b64 s[28:29], s[26:27]
	s_cbranch_execz .LBB0_1248

; __device__ __forceinline__ unsigned xb_ld(unsigned* p)              { return __hip_atomic_load(p, __ATOMIC_RELAXED, __HIP_MEMORY_SCOPE_AGENT); }
; __device__ __forceinline__ unsigned xb_add(unsigned* p, unsigned v) { return __hip_atomic_fetch_add(p, v, __ATOMIC_RELAXED, __HIP_MEMORY_SCOPE_AGENT); }
; #define XB_SPIN(cond, bar) do { unsigned _sp = 0; while (cond) { __builtin_amdgcn_s_sleep(1); \
;     if ((++_sp & 255u) == 0u) { if (xb_ld(&(bar)[XB_TMO])) break; if (_sp > XB_SPIN_CAP) { atomicAdd(&(bar)[XB_TMO], 1u); break; } } } } while (0)
; __device__ __forceinline__ void xcd_barrier(const XcdBarrier& b) {
;     ...
;         unsigned nloc = b.st[0], nx = b.st[1];
;         if (nloc == 0u) { xcd_barrier_complete(bar, b.x, nloc, nx); b.st[0] = nloc; b.st[1] = nx; }
;         const unsigned old = xb_add(&bar[XB_XSUB(b.x)], 1u);
;         const unsigned gen = old / nloc;
;         if (old + 1u == (gen + 1u) * nloc) {
;             __builtin_amdgcn_fence(__ATOMIC_RELEASE, "agent");
;             asm volatile("s_waitcnt vmcnt(0)" ::: "memory");
;             const unsigned og = xb_add(&bar[XB_TOP], 1u);
;             const unsigned tg = og / nx;
;             if (og + 1u == (tg + 1u) * nx) xb_add(&bar[XB_TOPGEN], 1u);
;             else XB_SPIN(xb_ld(&bar[XB_TOPGEN]) == tg, bar);
;             __builtin_amdgcn_fence(__ATOMIC_ACQUIRE, "agent");
;             xb_add(&bar[XB_XGEN(b.x)], 1u);
;             asm volatile("s_waitcnt vmcnt(0)" ::: "memory");
;         } else {
;             XB_SPIN(xb_ld(&bar[XB_XGEN(b.x)]) == gen, bar);
.LBB0_1260:
	s_lshl_b32 s4, s38, 8
	s_add_u32 s25, s36, s4
	s_addc_u32 s24, s37, 0
	v_mov_b32_e32 v1, s25
	v_add_co_u32_e32 v6, vcc, 0x1000, v1
	v_mov_b32_e32 v1, s24
	s_nop 0
	v_addc_co_u32_e32 v7, vcc, 0, v1, vcc
	flat_atomic_add v3, v[6:7], v217 offset:1024 sc0
	v_cvt_f32_u32_e32 v1, v4
	v_sub_u32_e32 v5, 0, v4
	v_rcp_iflag_f32_e32 v1, v1
	s_nop 0
	v_mul_f32_e32 v1, 0x4f7ffffe, v1
	v_cvt_u32_f32_e32 v1, v1
	v_mul_lo_u32 v5, v5, v1
	v_mul_hi_u32 v5, v1, v5
	v_add_u32_e32 v1, v1, v5
	s_waitcnt vmcnt(0) lgkmcnt(0)
	v_mul_hi_u32 v1, v3, v1
	v_mul_lo_u32 v5, v1, v4
	v_sub_u32_e32 v5, v3, v5
	v_cmp_ge_u32_e32 vcc, v5, v4
	v_add_u32_e32 v6, 1, v1
	v_add_u32_e32 v3, 1, v3
	v_cndmask_b32_e32 v1, v1, v6, vcc
	v_sub_u32_e32 v6, v5, v4
	v_cndmask_b32_e32 v5, v5, v6, vcc
	v_cmp_ge_u32_e32 vcc, v5, v4
	v_add_u32_e32 v5, 1, v1
	s_nop 0
	v_cndmask_b32_e32 v1, v1, v5, vcc
	v_mad_u64_u32 v[4:5], s[4:5], v4, v1, v[4:5]
	v_cmp_ne_u32_e32 vcc, v3, v4
	s_and_saveexec_b64 s[4:5], vcc
	s_xor_b64 s[4:5], exec, s[4:5]
	s_cbranch_execz .LBB0_1273
	v_mov_b32_e32 v2, s25
	v_add_co_u32_e32 v2, vcc, 0x2000, v2
	v_mov_b32_e32 v3, s24
	s_nop 0
	v_addc_co_u32_e32 v3, vcc, 0, v3, vcc
	global_load_dword v2, v[2:3], off offset:1024 sc1
	s_add_u32 s8, s25, 0x2400
	s_addc_u32 s9, s24, 0
	s_waitcnt vmcnt(0) lgkmcnt(0)
	v_cmp_eq_u32_e32 vcc, v2, v1
	s_and_saveexec_b64 s[6:7], vcc
	s_cbranch_execz .LBB0_1272
	s_mov_b32 s26, 1
	s_mov_b64 s[10:11], 0
	s_branch .LBB0_1264

; __device__ __forceinline__ unsigned xb_ld(unsigned* p)              { return __hip_atomic_load(p, __ATOMIC_RELAXED, __HIP_MEMORY_SCOPE_AGENT); }
; #define XB_SPIN(cond, bar) do { unsigned _sp = 0; while (cond) { __builtin_amdgcn_s_sleep(1); \
;     if ((++_sp & 255u) == 0u) { if (xb_ld(&(bar)[XB_TMO])) break; if (_sp > XB_SPIN_CAP) { atomicAdd(&(bar)[XB_TMO], 1u); break; } } } } while (0)
; __device__ __forceinline__ void xcd_barrier(const XcdBarrier& b) {
;     ...
;             XB_SPIN(xb_ld(&bar[XB_XGEN(b.x)]) == gen, bar);
.LBB0_1264:
	s_and_b32 s18, s26, 0xff
	s_mov_b64 s[16:17], -1
	s_cmp_lg_u32 s18, 0
	s_mov_b64 s[18:19], -1
	s_sleep 1
	s_cbranch_scc1 .LBB0_1268
	v_mov_b64_e32 v[2:3], s[36:37]
	global_load_dword v2, v[2:3], off offset:512 sc1
	s_mov_b64 s[18:19], 0
	s_mov_b64 s[20:21], -1
	s_waitcnt vmcnt(0) lgkmcnt(0)
	v_cmp_eq_u32_e32 vcc, 0, v2
	s_and_saveexec_b64 s[22:23], vcc
	s_cmp_lt_u32 s26, 0x400001
	s_cselect_b64 s[18:19], -1, 0
	s_xor_b64 s[20:21], exec, -1
	s_and_b64 s[18:19], s[18:19], exec
	s_or_b64 exec, exec, s[22:23]
.LBB0_1268:
	s_andn2_b64 s[14:15], s[14:15], exec
	s_and_b64 s[20:21], s[20:21], exec
	s_or_b64 s[14:15], s[14:15], s[20:21]
	s_and_saveexec_b64 s[20:21], s[18:19]
	s_cbranch_execz .LBB0_1263
	v_mov_b64_e32 v[2:3], s[8:9]
	global_load_dword v2, v[2:3], off sc1
	s_add_i32 s26, s26, 1
	s_or_b64 s[14:15], s[14:15], exec
	s_waitcnt vmcnt(0) lgkmcnt(0)
	v_cmp_ne_u32_e32 vcc, v2, v1
	s_orn2_b64 s[16:17], vcc, exec
	s_branch .LBB0_1263

; __device__ __forceinline__ unsigned xb_ld(unsigned* p)              { return __hip_atomic_load(p, __ATOMIC_RELAXED, __HIP_MEMORY_SCOPE_AGENT); }
; __device__ __forceinline__ unsigned xb_add(unsigned* p, unsigned v) { return __hip_atomic_fetch_add(p, v, __ATOMIC_RELAXED, __HIP_MEMORY_SCOPE_AGENT); }
; #define XB_SPIN(cond, bar) do { unsigned _sp = 0; while (cond) { __builtin_amdgcn_s_sleep(1); \
;     if ((++_sp & 255u) == 0u) { if (xb_ld(&(bar)[XB_TMO])) break; if (_sp > XB_SPIN_CAP) { atomicAdd(&(bar)[XB_TMO], 1u); break; } } } } while (0)
; __device__ __forceinline__ void xcd_barrier(const XcdBarrier& b) {
;     ...
;         if (old + 1u == (gen + 1u) * nloc) {
;             __builtin_amdgcn_fence(__ATOMIC_RELEASE, "agent");
;             asm volatile("s_waitcnt vmcnt(0)" ::: "memory");
;             const unsigned og = xb_add(&bar[XB_TOP], 1u);
;             const unsigned tg = og / nx;
;             if (og + 1u == (tg + 1u) * nx) xb_add(&bar[XB_TOPGEN], 1u);
;             else XB_SPIN(xb_ld(&bar[XB_TOPGEN]) == tg, bar);
.LBB0_1274:
	v_mov_b32_e32 v1, s36
	v_add_co_u32_e32 v4, vcc, 0x3000, v1
	v_mov_b32_e32 v1, s37
	buffer_wbl2 sc1
	s_waitcnt vmcnt(0)
	v_addc_co_u32_e32 v5, vcc, 0, v1, vcc
	flat_atomic_add v3, v[4:5], v217 offset:1024 sc0
	v_cvt_f32_u32_e32 v1, v2
	v_sub_u32_e32 v4, 0, v2
	s_mov_b64 s[8:9], -1
	v_rcp_iflag_f32_e32 v1, v1
	s_nop 0
	v_mul_f32_e32 v1, 0x4f7ffffe, v1
	v_cvt_u32_f32_e32 v1, v1
	v_mul_lo_u32 v4, v4, v1
	v_mul_hi_u32 v4, v1, v4
	v_add_u32_e32 v1, v1, v4
	s_waitcnt vmcnt(0) lgkmcnt(0)
	v_mul_hi_u32 v1, v3, v1
	v_mul_lo_u32 v4, v1, v2
	v_sub_u32_e32 v4, v3, v4
	v_cmp_ge_u32_e32 vcc, v4, v2
	v_add_u32_e32 v5, 1, v1
	s_nop 0
	v_cndmask_b32_e32 v1, v1, v5, vcc
	v_sub_u32_e32 v5, v4, v2
	v_cndmask_b32_e32 v4, v4, v5, vcc
	v_cmp_ge_u32_e32 vcc, v4, v2
	v_add_u32_e32 v4, 1, v1
	s_nop 0
	v_cndmask_b32_e32 v1, v1, v4, vcc
	v_add_u32_e32 v4, 1, v3
	v_mad_u64_u32 v[2:3], s[4:5], v2, v1, v[2:3]
	s_add_u32 s4, s36, 0x3500
	s_addc_u32 s5, s37, 0
	v_cmp_ne_u32_e32 vcc, v4, v2
	v_mov_b64_e32 v[2:3], s[4:5]
	s_and_saveexec_b64 s[6:7], vcc
	s_cbranch_execz .LBB0_1286
	v_mov_b64_e32 v[2:3], s[4:5]
	global_load_dword v2, v[2:3], off sc1
	s_mov_b64 s[12:13], 0
	s_waitcnt vmcnt(0) lgkmcnt(0)
	v_cmp_eq_u32_e32 vcc, v2, v1
	s_and_saveexec_b64 s[10:11], vcc
	s_cbranch_execz .LBB0_1285
	s_add_u32 s8, s36, 0x200
	s_addc_u32 s9, s37, 0
	s_mov_b32 s26, 1
	s_branch .LBB0_1278

; __device__ __forceinline__ unsigned xb_ld(unsigned* p)              { return __hip_atomic_load(p, __ATOMIC_RELAXED, __HIP_MEMORY_SCOPE_AGENT); }
; #define XB_SPIN(cond, bar) do { unsigned _sp = 0; while (cond) { __builtin_amdgcn_s_sleep(1); \
;     if ((++_sp & 255u) == 0u) { if (xb_ld(&(bar)[XB_TMO])) break; if (_sp > XB_SPIN_CAP) { atomicAdd(&(bar)[XB_TMO], 1u); break; } } } } while (0)
; __device__ __forceinline__ void xcd_barrier(const XcdBarrier& b) {
;     ...
;             else XB_SPIN(xb_ld(&bar[XB_TOPGEN]) == tg, bar);
.LBB0_1280:
	v_mov_b64_e32 v[2:3], s[8:9]
	global_load_dword v2, v[2:3], off sc1
	s_mov_b64 s[20:21], 0
	s_mov_b64 s[18:19], -1
	s_waitcnt vmcnt(0) lgkmcnt(0)
	v_cmp_eq_u32_e32 vcc, 0, v2
	s_and_saveexec_b64 s[22:23], vcc
	s_cmp_lt_u32 s26, 0x400001
	s_cselect_b64 s[20:21], -1, 0
	s_xor_b64 s[18:19], exec, -1
	s_and_b64 s[20:21], s[20:21], exec
	s_or_b64 exec, exec, s[22:23]
	s_and_saveexec_b64 s[22:23], s[20:21]
	s_cbranch_execz .LBB0_1277
.LBB0_1283:
	v_mov_b64_e32 v[2:3], s[4:5]
	global_load_dword v2, v[2:3], off sc1
	s_add_i32 s26, s26, 1
	s_or_b64 s[18:19], s[18:19], exec
	s_waitcnt vmcnt(0) lgkmcnt(0)
	v_cmp_ne_u32_e32 vcc, v2, v1
	s_orn2_b64 s[16:17], vcc, exec
	s_branch .LBB0_1277

; __device__ __forceinline__ float fast_rsq(float x) { return __builtin_amdgcn_rsqf(x); }
; __device__ __forceinline__ void final_norm(float* x, const float* g, int gw, int NGW, int lane) {
;     ...
;     for (int m = gw; m < MTOK; m += NGW) {
;         f32x4* xr = (f32x4*)(x + (size_t)m * DM) + lane;
;         f32x4 v[4]; float ss = 0.f;
; #pragma unroll
;         for (int j = 0; j < 4; ++j) { v[j] = xr[64 * j]; ss += (v[j].x * v[j].x + v[j].y * v[j].y) + (v[j].z * v[j].z + v[j].w * v[j].w); }
;         const float rstd = fast_rsq(wave_sum(ss) * (1.0f / DM) + EPS);
; #pragma unroll
;         for (int j = 0; j < 4; ++j) xr[64 * j] = v[j] * rstd * gv[j];
;     }
.LBB0_1292:
	global_load_dwordx4 v[20:23], v[16:17], off
	global_load_dwordx4 v[24:27], v[16:17], off offset:1024
	global_load_dwordx4 v[28:31], v[16:17], off offset:3072
	global_load_dwordx4 v[32:35], v[16:17], off offset:2048
	s_add_i32 s0, s0, s2
	s_cmp_lt_i32 s0, 0x8000
	s_waitcnt vmcnt(0) lgkmcnt(0)
	v_pk_mul_f32 v[36:37], v[22:23], v[22:23]
	v_pk_mul_f32 v[38:39], v[20:21], v[20:21]
	v_pk_mul_f32 v[40:41], v[26:27], v[26:27]
	v_pk_mul_f32 v[42:43], v[24:25], v[24:25]
	v_pk_mov_b32 v[48:49], v[38:39], v[36:37] op_sel:[1,0]
	v_mov_b32_e32 v39, v37
	v_pk_mov_b32 v[36:37], v[42:43], v[40:41] op_sel:[1,0]
	v_mov_b32_e32 v43, v41
	v_mul_f32_e32 v47, v29, v29
	v_mul_f32_e32 v44, v33, v33
	v_mul_f32_e32 v46, v35, v35
	v_pk_add_f32 v[38:39], v[48:49], v[38:39]
	v_pk_add_f32 v[36:37], v[36:37], v[42:43]
	v_mul_f32_e32 v19, v28, v28
	v_mul_f32_e32 v50, v30, v30
	v_mul_f32_e32 v51, v31, v31
	v_pk_fma_f32 v[40:41], v[32:33], v[32:33], v[44:45] op_sel_hi:[1,1,0]
	v_pk_fma_f32 v[44:45], v[34:35], v[34:35], v[46:47] op_sel_hi:[1,1,0]
	v_pk_add_f32 v[38:39], v[38:39], v[38:39] op_sel:[0,1] op_sel_hi:[1,0]
	v_pk_add_f32 v[36:37], v[36:37], v[36:37] op_sel:[0,1] op_sel_hi:[1,0]
	v_mov_b32_e32 v41, v50
	v_mov_b32_e32 v45, v51
	v_mov_b32_e32 v39, v19
	v_mov_b32_e32 v37, v47
	v_pk_add_f32 v[40:41], v[40:41], v[44:45]
	v_pk_add_f32 v[36:37], v[38:39], v[36:37]
	s_nop 0
	v_pk_add_f32 v[36:37], v[36:37], v[40:41]
	s_nop 0
	v_add_f32_e32 v19, v36, v37
	ds_bpermute_b32 v36, v225, v19
	s_waitcnt lgkmcnt(0)
	v_add_f32_e32 v19, v19, v36
	ds_bpermute_b32 v36, v221, v19
	s_waitcnt lgkmcnt(0)
	v_add_f32_e32 v19, v19, v36
	ds_bpermute_b32 v36, v222, v19
	s_waitcnt lgkmcnt(0)
	v_add_f32_e32 v19, v19, v36
	ds_bpermute_b32 v36, v252, v19
	s_waitcnt lgkmcnt(0)
	v_add_f32_e32 v19, v19, v36
	ds_bpermute_b32 v36, v253, v19
	s_waitcnt lgkmcnt(0)
	v_add_f32_e32 v19, v19, v36
	ds_bpermute_b32 v36, v230, v19
	s_waitcnt lgkmcnt(0)
	v_add_f32_e32 v19, v19, v36
	v_fmamk_f32 v19, v19, 0x3a800000, v18
	v_rsq_f32_e32 v36, v19
	s_nop 0
	v_pk_mul_f32 v[20:21], v[20:21], v[36:37] op_sel_hi:[1,0]
	v_pk_mul_f32 v[22:23], v[22:23], v[36:37] op_sel_hi:[1,0]
	v_pk_mul_f32 v[24:25], v[24:25], v[36:37] op_sel_hi:[1,0]
	v_pk_mul_f32 v[26:27], v[26:27], v[36:37] op_sel_hi:[1,0]
	v_pk_mul_f32 v[32:33], v[32:33], v[36:37] op_sel_hi:[1,0]
	v_pk_mul_f32 v[34:35], v[34:35], v[36:37] op_sel_hi:[1,0]
	v_pk_mul_f32 v[38:39], v[28:29], v[36:37] op_sel_hi:[1,0]
	v_pk_mul_f32 v[36:37], v[30:31], v[36:37] op_sel_hi:[1,0]
	v_pk_mul_f32 v[22:23], v[2:3], v[22:23]
	v_pk_mul_f32 v[20:21], v[0:1], v[20:21]
	v_pk_mul_f32 v[26:27], v[6:7], v[26:27]
	v_pk_mul_f32 v[24:25], v[4:5], v[24:25]
	v_pk_mul_f32 v[30:31], v[10:11], v[34:35]
	v_pk_mul_f32 v[28:29], v[8:9], v[32:33]
	v_pk_mul_f32 v[34:35], v[14:15], v[36:37]
	v_pk_mul_f32 v[32:33], v[12:13], v[38:39]
	global_store_dwordx4 v[16:17], v[20:23], off
	global_store_dwordx4 v[16:17], v[24:27], off offset:1024
	global_store_dwordx4 v[16:17], v[28:31], off offset:2048
	global_store_dwordx4 v[16:17], v[32:35], off offset:3072
	v_lshl_add_u64 v[16:17], v[16:17], 0, s[4:5]
	s_cbranch_scc1 .LBB0_1292
